# conv loads all up front; flat to global ops; attention and pass3 epilogue loads hoisted; attention pk ops split
# baseline (speedup 1.0000x reference)
; __device__ __forceinline__ void p0_transpose_item(const float* W, int K, int N, bf16* WT, float* scr, int item, int lane, const float* scale, const float* cb, float* c1, float* c2) {
;     const int nblk = N / 64, kb = item / nblk, nb = item % nblk, k0 = 64 * kb, n0 = 64 * nb;
;     const int lr = lane >> 4, lc = (lane & 15) * 4;
;     f32x4 v[16];
; #pragma unroll
;     for (int i = 0; i < 16; ++i) v[i] = *(const f32x4*)(W + (size_t)(k0 + 4 * i + lr) * N + n0 + lc);
; #pragma unroll
;     for (int i = 0; i < 16; ++i) { const int kk = 4 * i + lr; f32x4 w = v[i]; if (scale) w = w * scale[k0 + kk]; float* d = scr + kk * 65 + lc; d[0] = w[0]; d[1] = w[1]; d[2] = w[2]; d[3] = w[3]; }
.LBB0_23:
	s_cmpk_gt_u32 s61, 0x12ff
	s_cbranch_scc0 .LBB0_55
	s_ashr_i32 s7, s6, 31
	s_cmpk_gt_u32 s61, 0x16ff
	s_cbranch_scc0 .LBB0_26
	v_readlane_b32 s64, v253, 18
	s_lshl_b64 s[4:5], s[6:7], 21
	v_readlane_b32 s78, v253, 32
	v_readlane_b32 s79, v253, 33
	s_add_u32 s8, s78, s4
	s_addc_u32 s9, s79, s5
	s_lshl_b64 s[4:5], s[6:7], 20
	s_add_u32 s10, s34, s4
	s_addc_u32 s5, s35, s5
	s_lshl_b32 s4, s61, 1
	s_and_b32 s11, s4, 0x1c0
	s_lshl_b32 s4, s61, 6
	s_and_b32 s4, s4, 0x7c0
	s_lshl_b32 s12, s4, 2
	s_add_u32 s8, s8, s12
	v_or_b32_e32 v2, s11, v80
	s_addc_u32 s9, s9, 0
	v_lshl_add_u64 v[0:1], s[8:9], 0, v[68:69]
	v_lshlrev_b32_e32 v2, 13, v2
	v_mov_b32_e32 v3, v69
	v_lshl_add_u64 v[60:61], v[0:1], 0, v[2:3]
	v_add_co_u32_e32 v4, vcc, s41, v60
	s_lshl_b32 s8, s11, 1
	s_nop 0
	v_addc_co_u32_e32 v5, vcc, 0, v61, vcc
	v_add_co_u32_e32 v8, vcc, s42, v60
	global_load_dwordx4 v[0:3], v[60:61], off
	s_nop 0
	global_load_dwordx4 v[4:7], v[4:5], off
	v_addc_co_u32_e32 v9, vcc, 0, v61, vcc
	v_add_co_u32_e32 v12, vcc, s43, v60
	s_add_u32 s8, s10, s8
	s_nop 0
	v_addc_co_u32_e32 v13, vcc, 0, v61, vcc
	v_add_co_u32_e32 v16, vcc, s44, v60
	global_load_dwordx4 v[8:11], v[8:9], off
	s_nop 0
	global_load_dwordx4 v[12:15], v[12:13], off
	v_addc_co_u32_e32 v17, vcc, 0, v61, vcc
	v_add_co_u32_e32 v20, vcc, s45, v60
	s_addc_u32 s9, s5, 0
	s_nop 0
	v_addc_co_u32_e32 v21, vcc, 0, v61, vcc
	v_add_co_u32_e32 v24, vcc, s46, v60
	global_load_dwordx4 v[16:19], v[16:17], off
	s_nop 0
	global_load_dwordx4 v[20:23], v[20:21], off
	v_addc_co_u32_e32 v25, vcc, 0, v61, vcc
	v_add_co_u32_e32 v28, vcc, s47, v60
	v_mov_b32_e32 v75, v69
	s_nop 0
	v_addc_co_u32_e32 v29, vcc, 0, v61, vcc
	v_add_co_u32_e32 v32, vcc, s48, v60
	global_load_dwordx4 v[24:27], v[24:25], off
	s_nop 0
	global_load_dwordx4 v[28:31], v[28:29], off
	v_addc_co_u32_e32 v33, vcc, 0, v61, vcc
	v_add_co_u32_e32 v36, vcc, s49, v60
	v_readlane_b32 s65, v253, 19
	s_nop 0
	v_addc_co_u32_e32 v37, vcc, 0, v61, vcc
	v_add_co_u32_e32 v40, vcc, s50, v60
	global_load_dwordx4 v[32:35], v[32:33], off
	s_nop 0
	global_load_dwordx4 v[36:39], v[36:37], off
	v_addc_co_u32_e32 v41, vcc, 0, v61, vcc
	v_add_co_u32_e32 v44, vcc, s51, v60
	v_readlane_b32 s66, v253, 20
	s_nop 0
	v_addc_co_u32_e32 v45, vcc, 0, v61, vcc
	v_add_co_u32_e32 v48, vcc, s52, v60
	global_load_dwordx4 v[40:43], v[40:41], off
	s_nop 0
	global_load_dwordx4 v[44:47], v[44:45], off
	v_addc_co_u32_e32 v49, vcc, 0, v61, vcc
	v_add_co_u32_e32 v52, vcc, s53, v60
	v_readlane_b32 s67, v253, 21
	s_nop 0
	v_addc_co_u32_e32 v53, vcc, 0, v61, vcc
	global_load_dwordx4 v[48:51], v[48:49], off
	s_nop 0
	global_load_dwordx4 v[52:55], v[52:53], off
	v_add_co_u32_e32 v56, vcc, s54, v60
	v_readlane_b32 s68, v253, 22
	s_nop 0
	v_addc_co_u32_e32 v57, vcc, 0, v61, vcc
	global_load_dwordx4 v[56:59], v[56:57], off
	v_add_co_u32_e32 v60, vcc, s55, v60
	v_readlane_b32 s69, v253, 23
	s_nop 0
	v_addc_co_u32_e32 v61, vcc, 0, v61, vcc
	global_load_dwordx4 v[60:63], v[60:61], off
	v_readlane_b32 s70, v253, 24
	v_readlane_b32 s71, v253, 25
	v_readlane_b32 s72, v253, 26
	v_readlane_b32 s73, v253, 27
	v_readlane_b32 s74, v253, 28
	v_readlane_b32 s75, v253, 29
	v_readlane_b32 s76, v253, 30
	v_readlane_b32 s77, v253, 31
	s_waitcnt vmcnt(0)
	ds_write2_b32 v81, v0, v1 offset1:1
	ds_write2_b32 v81, v2, v3 offset0:2 offset1:3
	s_waitcnt vmcnt(14)
	ds_write2_b32 v92, v4, v5 offset1:1
	ds_write2_b32 v93, v6, v7 offset1:1
	s_waitcnt vmcnt(13)
	ds_write2_b32 v94, v8, v9 offset1:1
	ds_write2_b32 v95, v10, v11 offset1:1
	s_waitcnt vmcnt(12)
	ds_write2_b32 v96, v12, v13 offset1:1
	ds_write2_b32 v97, v14, v15 offset1:1
	s_waitcnt vmcnt(11)
	ds_write2_b32 v98, v16, v17 offset1:1
	ds_write2_b32 v99, v18, v19 offset1:1
	s_waitcnt vmcnt(10)
	ds_write2_b32 v100, v20, v21 offset1:1
	ds_write2_b32 v101, v22, v23 offset1:1
	s_waitcnt vmcnt(9)
	ds_write2_b32 v102, v24, v25 offset1:1
	ds_write2_b32 v103, v26, v27 offset1:1
	s_waitcnt vmcnt(8)
	ds_write2_b32 v104, v28, v29 offset1:1
	ds_write2_b32 v105, v30, v31 offset1:1
	s_waitcnt vmcnt(7)
	ds_write2_b32 v106, v32, v33 offset1:1
	ds_write2_b32 v107, v34, v35 offset1:1
	s_waitcnt vmcnt(6)
	ds_write2_b32 v108, v36, v37 offset1:1
	ds_write2_b32 v109, v38, v39 offset1:1
	s_waitcnt vmcnt(5)
	ds_write2_b32 v110, v40, v41 offset1:1
	ds_write2_b32 v111, v42, v43 offset1:1
	s_waitcnt vmcnt(4)
	ds_write2_b32 v112, v44, v45 offset1:1
	ds_write2_b32 v113, v46, v47 offset1:1
	s_waitcnt vmcnt(3)
	ds_write2_b32 v114, v48, v49 offset1:1
	ds_write2_b32 v115, v50, v51 offset1:1
	s_waitcnt vmcnt(2)
	ds_write2_b32 v116, v52, v53 offset1:1
	ds_write2_b32 v117, v54, v55 offset1:1
	s_waitcnt vmcnt(1)
	ds_write2_b32 v118, v56, v57 offset1:1
	ds_write2_b32 v119, v58, v59 offset1:1
	s_waitcnt vmcnt(0)
; #define LDS_WAIT() asm volatile("s_waitcnt lgkmcnt(0)" ::: "memory")
; __device__ __forceinline__ unsigned pk2(float lo, float hi) { unsigned r; asm("v_cvt_pk_bf16_f32 %0, %1, %2" : "=v"(r) : "v"(lo), "v"(hi)); return r; }
; __device__ __forceinline__ void p0_transpose_item(const float* W, int K, int N, bf16* WT, float* scr, int item, int lane, const float* scale, const float* cb, float* c1, float* c2) {
;     ...
;     LDS_WAIT(); asm volatile("" ::: "memory");
;     const int c = lane & 7;
; #pragma unroll
;     for (int j = 0; j < 8; ++j) { const int n = (lane >> 3) + 8 * j; const float* sp = scr + (8 * c) * 65 + n;
;         v4u o; o.x = pk2(sp[0 * 65], sp[1 * 65]); o.y = pk2(sp[2 * 65], sp[3 * 65]); o.z = pk2(sp[4 * 65], sp[5 * 65]); o.w = pk2(sp[6 * 65], sp[7 * 65]);
;         *(v4u*)(WT + (size_t)(n0 + n) * K + k0 + 8 * c) = o; }
	ds_write2_b32 v120, v60, v61 offset1:1
	ds_write2_b32 v121, v62, v63 offset1:1
	s_waitcnt lgkmcnt(0)
	ds_read_b32 v0, v83
	ds_read_b32 v1, v83 offset:260
	ds_read_b32 v2, v83 offset:520
	ds_read_b32 v3, v83 offset:780
	ds_read_b32 v6, v83 offset:1040
	ds_read_b32 v7, v83 offset:1300
	ds_read_b32 v8, v83 offset:1560
	ds_read_b32 v9, v83 offset:1820
	s_waitcnt lgkmcnt(6)
	v_cvt_pk_bf16_f32 v0, v0, v1
	s_waitcnt lgkmcnt(4)
	v_cvt_pk_bf16_f32 v1, v2, v3
	s_waitcnt lgkmcnt(2)
	v_cvt_pk_bf16_f32 v2, v6, v7
	v_or_b32_e32 v6, s4, v82
	v_lshl_add_u64 v[4:5], s[8:9], 0, v[74:75]
	v_lshlrev_b32_e32 v6, 9, v6
	v_mov_b32_e32 v7, v69
	v_lshl_add_u64 v[6:7], v[4:5], 0, v[6:7]
	s_waitcnt lgkmcnt(0)
	v_cvt_pk_bf16_f32 v3, v8, v9
	global_store_dwordx4 v[6:7], v[0:3], off
	ds_read_b32 v0, v83 offset:32
	ds_read_b32 v1, v83 offset:292
	ds_read_b32 v2, v83 offset:552
	ds_read_b32 v3, v83 offset:812
	ds_read_b32 v6, v83 offset:1072
	ds_read_b32 v7, v83 offset:1332
	ds_read_b32 v8, v83 offset:1592
	ds_read_b32 v9, v83 offset:1852
	s_waitcnt lgkmcnt(0)
	v_cvt_pk_bf16_f32 v0, v0, v1
	v_cvt_pk_bf16_f32 v1, v2, v3
	v_cvt_pk_bf16_f32 v2, v6, v7
	v_or_b32_e32 v6, s4, v84
	v_lshlrev_b32_e32 v6, 9, v6
	v_mov_b32_e32 v7, v69
	v_lshl_add_u64 v[6:7], v[4:5], 0, v[6:7]
	v_cvt_pk_bf16_f32 v3, v8, v9
	global_store_dwordx4 v[6:7], v[0:3], off
	ds_read_b32 v0, v83 offset:64
	ds_read_b32 v1, v83 offset:324
	ds_read_b32 v2, v83 offset:584
	ds_read_b32 v3, v83 offset:844
	ds_read_b32 v6, v83 offset:1104
	ds_read_b32 v7, v83 offset:1364
	ds_read_b32 v8, v83 offset:1624
	ds_read_b32 v9, v83 offset:1884
	s_waitcnt lgkmcnt(0)
	v_cvt_pk_bf16_f32 v0, v0, v1
	v_cvt_pk_bf16_f32 v1, v2, v3
	v_cvt_pk_bf16_f32 v2, v6, v7
	v_or_b32_e32 v6, s4, v85
	v_lshlrev_b32_e32 v6, 9, v6
	v_mov_b32_e32 v7, v69
	v_lshl_add_u64 v[6:7], v[4:5], 0, v[6:7]
	v_cvt_pk_bf16_f32 v3, v8, v9
	global_store_dwordx4 v[6:7], v[0:3], off
	ds_read_b32 v0, v83 offset:96
	ds_read_b32 v1, v83 offset:356
	ds_read_b32 v2, v83 offset:616
	ds_read_b32 v3, v83 offset:876
	ds_read_b32 v6, v83 offset:1136
	ds_read_b32 v7, v83 offset:1396
	ds_read_b32 v8, v83 offset:1656
	ds_read_b32 v9, v83 offset:1916
	s_waitcnt lgkmcnt(0)
	v_cvt_pk_bf16_f32 v0, v0, v1
	v_cvt_pk_bf16_f32 v1, v2, v3
	v_cvt_pk_bf16_f32 v2, v6, v7
	v_or_b32_e32 v6, s4, v86
	v_lshlrev_b32_e32 v6, 9, v6
	v_mov_b32_e32 v7, v69
	v_lshl_add_u64 v[6:7], v[4:5], 0, v[6:7]
	v_cvt_pk_bf16_f32 v3, v8, v9
	global_store_dwordx4 v[6:7], v[0:3], off
	ds_read_b32 v0, v83 offset:128
	ds_read_b32 v1, v83 offset:388
	ds_read_b32 v2, v83 offset:648
	ds_read_b32 v3, v83 offset:908
	ds_read_b32 v6, v83 offset:1168
	ds_read_b32 v7, v83 offset:1428
	ds_read_b32 v8, v83 offset:1688
	ds_read_b32 v9, v83 offset:1948
	s_waitcnt lgkmcnt(0)
	v_cvt_pk_bf16_f32 v0, v0, v1
	v_cvt_pk_bf16_f32 v1, v2, v3
	v_cvt_pk_bf16_f32 v2, v6, v7
	v_or_b32_e32 v6, s4, v87
	v_lshlrev_b32_e32 v6, 9, v6
	v_mov_b32_e32 v7, v69
	v_lshl_add_u64 v[6:7], v[4:5], 0, v[6:7]
	v_cvt_pk_bf16_f32 v3, v8, v9
	global_store_dwordx4 v[6:7], v[0:3], off
	ds_read_b32 v0, v83 offset:160
	ds_read_b32 v1, v83 offset:420
	ds_read_b32 v2, v83 offset:680
	ds_read_b32 v3, v83 offset:940
	ds_read_b32 v6, v83 offset:1200
	ds_read_b32 v7, v83 offset:1460
	ds_read_b32 v8, v83 offset:1720
	ds_read_b32 v9, v83 offset:1980
	s_waitcnt lgkmcnt(0)
	v_cvt_pk_bf16_f32 v0, v0, v1
	v_cvt_pk_bf16_f32 v1, v2, v3
	v_cvt_pk_bf16_f32 v2, v6, v7
	v_or_b32_e32 v6, s4, v88
	v_lshlrev_b32_e32 v6, 9, v6
	v_mov_b32_e32 v7, v69
	v_lshl_add_u64 v[6:7], v[4:5], 0, v[6:7]
	v_cvt_pk_bf16_f32 v3, v8, v9
	global_store_dwordx4 v[6:7], v[0:3], off
	ds_read_b32 v0, v83 offset:192
	ds_read_b32 v1, v83 offset:452
	ds_read_b32 v2, v83 offset:712
	ds_read_b32 v3, v83 offset:972
	ds_read_b32 v6, v83 offset:1232
	ds_read_b32 v7, v83 offset:1492
	ds_read_b32 v8, v83 offset:1752
	ds_read_b32 v9, v83 offset:2012
	s_waitcnt lgkmcnt(0)
	v_cvt_pk_bf16_f32 v0, v0, v1
	v_cvt_pk_bf16_f32 v1, v2, v3
	v_cvt_pk_bf16_f32 v2, v6, v7
	v_or_b32_e32 v6, s4, v89
	v_lshlrev_b32_e32 v6, 9, v6
	v_mov_b32_e32 v7, v69
	v_lshl_add_u64 v[6:7], v[4:5], 0, v[6:7]
	v_cvt_pk_bf16_f32 v3, v8, v9
	global_store_dwordx4 v[6:7], v[0:3], off
	ds_read_b32 v0, v83 offset:224
	ds_read_b32 v1, v83 offset:484
	ds_read_b32 v2, v83 offset:744
	ds_read_b32 v3, v83 offset:1004
	ds_read_b32 v6, v83 offset:1264
	ds_read_b32 v7, v83 offset:1524
	ds_read_b32 v8, v83 offset:1784
	ds_read_b32 v9, v83 offset:2044
	s_waitcnt lgkmcnt(0)
	v_cvt_pk_bf16_f32 v0, v0, v1
	v_cvt_pk_bf16_f32 v1, v2, v3
	v_cvt_pk_bf16_f32 v2, v6, v7
	v_or_b32_e32 v6, s4, v90
	v_lshlrev_b32_e32 v6, 9, v6
	v_mov_b32_e32 v7, v69
	v_lshl_add_u64 v[4:5], v[4:5], 0, v[6:7]
	v_cvt_pk_bf16_f32 v3, v8, v9
	global_store_dwordx4 v[4:5], v[0:3], off
	s_waitcnt lgkmcnt(0)
	s_mov_b64 s[4:5], 0

; #define LDS_WAIT() asm volatile("s_waitcnt lgkmcnt(0)" ::: "memory")
; __device__ __forceinline__ unsigned pk2(float lo, float hi) { unsigned r; asm("v_cvt_pk_bf16_f32 %0, %1, %2" : "=v"(r) : "v"(lo), "v"(hi)); return r; }
; __device__ __forceinline__ unsigned f2bf(float f) { return pk2(f, 0.f) & 0xffffu; }
; __device__ __forceinline__ void p0_transpose_item(const float* W, int K, int N, bf16* WT, float* scr, int item, int lane, const float* scale, const float* cb, float* c1, float* c2) {
;     ...
;     for (int i = 0; i < 16; ++i) { const int kk = 4 * i + lr; f32x4 w = v[i]; if (scale) w = w * scale[k0 + kk]; float* d = scr + kk * 65 + lc; d[0] = w[0]; d[1] = w[1]; d[2] = w[2]; d[3] = w[3]; }
;     LDS_WAIT(); asm volatile("" ::: "memory");
;     const int c = lane & 7;
; #pragma unroll
;     for (int j = 0; j < 8; ++j) { const int n = (lane >> 3) + 8 * j; const float* sp = scr + (8 * c) * 65 + n;
;         v4u o; o.x = pk2(sp[0 * 65], sp[1 * 65]); o.y = pk2(sp[2 * 65], sp[3 * 65]); o.z = pk2(sp[4 * 65], sp[5 * 65]); o.w = pk2(sp[6 * 65], sp[7 * 65]);
;         *(v4u*)(WT + (size_t)(n0 + n) * K + k0 + 8 * c) = o; }
;     if (c1) { float a1 = 0.f, a2 = 0.f;
;         for (int kk = 0; kk < 64; ++kk) { a1 += __uint_as_float(f2bf(scr[kk * 65 + lane]) << 16); a2 += cb[k0 + kk] * W[(size_t)(k0 + kk) * N + n0 + lane]; }
.LBB0_51:
	v_add_u32_e32 v0, 0x34d0, v122
	ds_write2_b32 v0, v14, v15 offset1:1
	v_add_u32_e32 v0, 0x34d8, v122
	ds_write2_b32 v0, v12, v13 offset1:1
	v_add_u32_e32 v0, 0x38e0, v122
	ds_write2_b32 v0, v8, v9 offset1:1
	v_add_u32_e32 v0, 0x38e8, v122
	ds_write2_b32 v0, v10, v11 offset1:1
	s_lshl_b64 s[4:5], s[6:7], 22
	s_waitcnt lgkmcnt(0)
	s_lshl_b64 s[4:5], s[4:5], 1
	s_add_u32 s4, s30, s4
	ds_read_b32 v0, v83
	ds_read_b32 v1, v83 offset:260
	ds_read_b32 v2, v83 offset:520
	ds_read_b32 v3, v83 offset:780
	ds_read_b32 v6, v83 offset:1040
	ds_read_b32 v7, v83 offset:1300
	ds_read_b32 v8, v83 offset:1560
	ds_read_b32 v9, v83 offset:1820
	s_addc_u32 s5, s31, s5
	s_lshl_b32 s7, s64, 1
	s_add_u32 s4, s4, s7
	s_addc_u32 s5, s5, 0
	v_mov_b32_e32 v75, v69
	s_waitcnt lgkmcnt(0)
	v_cvt_pk_bf16_f32 v0, v0, v1
	v_cvt_pk_bf16_f32 v1, v2, v3
	v_cvt_pk_bf16_f32 v2, v6, v7
	v_or_b32_e32 v6, s65, v82
	v_lshl_add_u64 v[4:5], s[4:5], 0, v[74:75]
	v_lshlrev_b32_e32 v6, 12, v6
	v_mov_b32_e32 v7, v69
	v_lshl_add_u64 v[6:7], v[4:5], 0, v[6:7]
	v_cvt_pk_bf16_f32 v3, v8, v9
	global_store_dwordx4 v[6:7], v[0:3], off
	ds_read_b32 v0, v83 offset:32
	ds_read_b32 v1, v83 offset:292
	ds_read_b32 v2, v83 offset:552
	ds_read_b32 v3, v83 offset:812
	ds_read_b32 v6, v83 offset:1072
	ds_read_b32 v7, v83 offset:1332
	ds_read_b32 v8, v83 offset:1592
	ds_read_b32 v9, v83 offset:1852
	s_waitcnt lgkmcnt(0)
	v_cvt_pk_bf16_f32 v0, v0, v1
	v_cvt_pk_bf16_f32 v1, v2, v3
	v_cvt_pk_bf16_f32 v2, v6, v7
	v_or_b32_e32 v6, s65, v84
	v_lshlrev_b32_e32 v6, 12, v6
	v_mov_b32_e32 v7, v69
	v_lshl_add_u64 v[6:7], v[4:5], 0, v[6:7]
	v_cvt_pk_bf16_f32 v3, v8, v9
	global_store_dwordx4 v[6:7], v[0:3], off
	ds_read_b32 v0, v83 offset:64
	ds_read_b32 v1, v83 offset:324
	ds_read_b32 v2, v83 offset:584
	ds_read_b32 v3, v83 offset:844
	ds_read_b32 v6, v83 offset:1104
	ds_read_b32 v7, v83 offset:1364
	ds_read_b32 v8, v83 offset:1624
	ds_read_b32 v9, v83 offset:1884
	s_waitcnt lgkmcnt(0)
	v_cvt_pk_bf16_f32 v0, v0, v1
	v_cvt_pk_bf16_f32 v1, v2, v3
	v_cvt_pk_bf16_f32 v2, v6, v7
	v_or_b32_e32 v6, s65, v85
	v_lshlrev_b32_e32 v6, 12, v6
	v_mov_b32_e32 v7, v69
	v_lshl_add_u64 v[6:7], v[4:5], 0, v[6:7]
	v_cvt_pk_bf16_f32 v3, v8, v9
	global_store_dwordx4 v[6:7], v[0:3], off
	ds_read_b32 v0, v83 offset:96
	ds_read_b32 v1, v83 offset:356
	ds_read_b32 v2, v83 offset:616
	ds_read_b32 v3, v83 offset:876
	ds_read_b32 v6, v83 offset:1136
	ds_read_b32 v7, v83 offset:1396
	ds_read_b32 v8, v83 offset:1656
	ds_read_b32 v9, v83 offset:1916
	s_waitcnt lgkmcnt(0)
	v_cvt_pk_bf16_f32 v0, v0, v1
	v_cvt_pk_bf16_f32 v1, v2, v3
	v_cvt_pk_bf16_f32 v2, v6, v7
	v_or_b32_e32 v6, s65, v86
	v_lshlrev_b32_e32 v6, 12, v6
	v_mov_b32_e32 v7, v69
	v_lshl_add_u64 v[6:7], v[4:5], 0, v[6:7]
	v_cvt_pk_bf16_f32 v3, v8, v9
	global_store_dwordx4 v[6:7], v[0:3], off
	ds_read_b32 v0, v83 offset:128
	ds_read_b32 v1, v83 offset:388
	ds_read_b32 v2, v83 offset:648
	ds_read_b32 v3, v83 offset:908
	ds_read_b32 v6, v83 offset:1168
	ds_read_b32 v7, v83 offset:1428
	ds_read_b32 v8, v83 offset:1688
	ds_read_b32 v9, v83 offset:1948
	s_waitcnt lgkmcnt(0)
	v_cvt_pk_bf16_f32 v0, v0, v1
	v_cvt_pk_bf16_f32 v1, v2, v3
	v_cvt_pk_bf16_f32 v2, v6, v7
	v_or_b32_e32 v6, s65, v87
	v_lshlrev_b32_e32 v6, 12, v6
	v_mov_b32_e32 v7, v69
	v_lshl_add_u64 v[6:7], v[4:5], 0, v[6:7]
	v_cvt_pk_bf16_f32 v3, v8, v9
	global_store_dwordx4 v[6:7], v[0:3], off
	ds_read_b32 v0, v83 offset:160
	ds_read_b32 v1, v83 offset:420
	ds_read_b32 v2, v83 offset:680
	ds_read_b32 v3, v83 offset:940
	ds_read_b32 v6, v83 offset:1200
	ds_read_b32 v7, v83 offset:1460
	ds_read_b32 v8, v83 offset:1720
	ds_read_b32 v9, v83 offset:1980
	s_waitcnt lgkmcnt(0)
	v_cvt_pk_bf16_f32 v0, v0, v1
	v_cvt_pk_bf16_f32 v1, v2, v3
	v_cvt_pk_bf16_f32 v2, v6, v7
	v_or_b32_e32 v6, s65, v88
	v_lshlrev_b32_e32 v6, 12, v6
	v_mov_b32_e32 v7, v69
	v_lshl_add_u64 v[6:7], v[4:5], 0, v[6:7]
	v_cvt_pk_bf16_f32 v3, v8, v9
	global_store_dwordx4 v[6:7], v[0:3], off
	ds_read_b32 v0, v83 offset:192
	ds_read_b32 v1, v83 offset:452
	ds_read_b32 v2, v83 offset:712
	ds_read_b32 v3, v83 offset:972
	ds_read_b32 v6, v83 offset:1232
	ds_read_b32 v7, v83 offset:1492
	ds_read_b32 v8, v83 offset:1752
	ds_read_b32 v9, v83 offset:2012
	s_waitcnt lgkmcnt(0)
	v_cvt_pk_bf16_f32 v0, v0, v1
	v_cvt_pk_bf16_f32 v1, v2, v3
	v_cvt_pk_bf16_f32 v2, v6, v7
	v_or_b32_e32 v6, s65, v89
	v_lshlrev_b32_e32 v6, 12, v6
	v_mov_b32_e32 v7, v69
	v_lshl_add_u64 v[6:7], v[4:5], 0, v[6:7]
	v_cvt_pk_bf16_f32 v3, v8, v9
	global_store_dwordx4 v[6:7], v[0:3], off
	ds_read_b32 v0, v83 offset:224
	ds_read_b32 v1, v83 offset:484
	ds_read_b32 v2, v83 offset:744
	ds_read_b32 v3, v83 offset:1004
	ds_read_b32 v6, v83 offset:1264
	ds_read_b32 v7, v83 offset:1524
	ds_read_b32 v8, v83 offset:1784
	ds_read_b32 v9, v83 offset:2044
	s_lshl_b32 s4, s63, 13
	s_and_b32 s4, s4, 0x3ff80000
	s_add_u32 s4, s10, s4
	s_waitcnt lgkmcnt(0)
	v_cvt_pk_bf16_f32 v0, v0, v1
	v_cvt_pk_bf16_f32 v1, v2, v3
	v_cvt_pk_bf16_f32 v2, v6, v7
	v_or_b32_e32 v6, s65, v90
	s_addc_u32 s5, s11, 0
	s_and_b32 s7, s61, 31
	v_lshlrev_b32_e32 v6, 12, v6
	v_mov_b32_e32 v7, v69
	s_lshl_b32 s7, s7, 8
	v_lshl_add_u64 v[4:5], v[4:5], 0, v[6:7]
	s_or_b32 s4, s4, s7
	v_cvt_pk_bf16_f32 v3, v8, v9
	global_store_dwordx4 v[4:5], v[0:3], off
	v_mov_b32_e32 v4, v91
	s_nop 0
	v_lshl_add_u64 v[0:1], v[70:71], 0, s[4:5]
	s_lshl_b32 s4, s64, 2
	v_readlane_b32 s64, v253, 18
	v_readlane_b32 s76, v253, 30
	v_readlane_b32 s77, v253, 31
	s_add_u32 s7, s76, s4
	s_addc_u32 s12, s77, 0
	s_lshl_b32 s4, s63, 2
	s_and_b32 s4, s4, 0x7ff00
	s_add_u32 s13, s76, s4
	v_mov_b32_e32 v2, 0
	s_addc_u32 s14, s77, 0
	s_mov_b64 s[4:5], 0
	v_mov_b32_e32 v3, v2
	v_readlane_b32 s65, v253, 19
	v_readlane_b32 s66, v253, 20
	v_readlane_b32 s67, v253, 21
	v_readlane_b32 s68, v253, 22
	v_readlane_b32 s69, v253, 23
	v_readlane_b32 s70, v253, 24
	v_readlane_b32 s71, v253, 25
	v_readlane_b32 s72, v253, 26
	v_readlane_b32 s73, v253, 27
	v_readlane_b32 s74, v253, 28
	v_readlane_b32 s75, v253, 29
	v_readlane_b32 s78, v253, 32
	v_readlane_b32 s79, v253, 33
; #define LDS_WAIT() asm volatile("s_waitcnt lgkmcnt(0)" ::: "memory")
; __device__ __forceinline__ unsigned f2bf(float f) { return pk2(f, 0.f) & 0xffffu; }
; __device__ __forceinline__ void p0_transpose_item(const float* W, int K, int N, bf16* WT, float* scr, int item, int lane, const float* scale, const float* cb, float* c1, float* c2) {
;     ...
;     if (c1) { float a1 = 0.f, a2 = 0.f;
;         for (int kk = 0; kk < 64; ++kk) { a1 += __uint_as_float(f2bf(scr[kk * 65 + lane]) << 16); a2 += cb[k0 + kk] * W[(size_t)(k0 + kk) * N + n0 + lane]; }
;         atomicAdd(c1 + n0 + lane, a1); atomicAdd(c2 + n0 + lane, a2); }
;     LDS_WAIT(); asm volatile("" ::: "memory");
.LBB0_52:
	v_lshl_add_u64 v[6:7], v[0:1], 0, s[4:5]
	s_movk_i32 s15, 0x2000
	v_add_co_u32_e32 v8, vcc, s15, v6
	s_movk_i32 s15, 0x4000
	s_nop 0
	v_addc_co_u32_e32 v9, vcc, 0, v7, vcc
	v_add_co_u32_e32 v10, vcc, s15, v6
	s_movk_i32 s15, 0x6000
	s_nop 0
	v_addc_co_u32_e32 v11, vcc, 0, v7, vcc
	v_add_co_u32_e32 v12, vcc, s15, v6
	s_mov_b32 s15, 0xa000
	s_nop 0
	v_addc_co_u32_e32 v13, vcc, 0, v7, vcc
	v_add_co_u32_e32 v14, vcc, s41, v6
	s_add_u32 s10, s13, s8
	s_nop 0
	v_addc_co_u32_e32 v15, vcc, 0, v7, vcc
	v_add_co_u32_e32 v16, vcc, s15, v6
	s_addc_u32 s11, s14, s9
	s_nop 0
	v_addc_co_u32_e32 v17, vcc, 0, v7, vcc
	s_mov_b32 s15, 0xc000
	global_load_dword v5, v[6:7], off
	v_add_co_u32_e32 v18, vcc, s15, v6
	global_load_dword v22, v69, s[10:11]
	s_nop 0
	v_addc_co_u32_e32 v19, vcc, 0, v7, vcc
	s_mov_b32 s15, 0xe000
	s_add_u32 s10, s7, s8
	v_add_co_u32_e32 v20, vcc, s15, v6
	s_addc_u32 s11, s12, s9
	s_nop 0
	v_addc_co_u32_e32 v21, vcc, 0, v7, vcc
	global_load_dword v24, v[8:9], off
	global_load_dword v26, v[10:11], off
	global_load_dword v28, v[12:13], off
	global_load_dword v29, v[14:15], off
	global_load_dword v30, v[16:17], off
	global_load_dword v31, v[18:19], off
	global_load_dwordx4 v[6:9], v69, s[10:11] offset:4
	s_nop 0
	global_load_dwordx3 v[10:12], v69, s[10:11] offset:20
	global_load_dword v32, v[20:21], off
	ds_read2_b32 v[14:15], v4 offset1:65
	ds_read2_b32 v[16:17], v4 offset0:130 offset1:195
	v_add_u32_e32 v13, 0x400, v4
	ds_read2_b32 v[18:19], v13 offset0:4 offset1:69
	ds_read2_b32 v[20:21], v13 offset0:134 offset1:199
	s_waitcnt lgkmcnt(0)
	v_cvt_pk_bf16_f32 v13, v14, v69
	v_cvt_pk_bf16_f32 v14, v15, v69
	v_cvt_pk_bf16_f32 v16, v16, v69
	v_cvt_pk_bf16_f32 v25, v17, v69
	s_nop 0
	v_lshlrev_b32_e32 v15, 16, v13
	v_lshlrev_b32_e32 v17, 16, v14
	v_cvt_pk_bf16_f32 v14, v19, v69
	v_lshlrev_b32_e32 v23, 16, v16
	v_cvt_pk_bf16_f32 v13, v18, v69
	v_cvt_pk_bf16_f32 v16, v20, v69
	v_cvt_pk_bf16_f32 v18, v21, v69
	v_lshlrev_b32_e32 v21, 16, v14
	v_lshlrev_b32_e32 v27, 16, v16
	s_add_u32 s4, s4, 0x10000
	s_addc_u32 s5, s5, 0
	v_lshlrev_b32_e32 v25, 16, v25
	s_add_u32 s7, s7, 32
	v_lshlrev_b32_e32 v19, 16, v13
	v_lshlrev_b32_e32 v13, 16, v18
	s_addc_u32 s12, s12, 0
	s_add_u32 s13, s13, 32
	s_addc_u32 s14, s14, 0
	v_add_u32_e32 v4, 0x820, v4
	s_cmp_lg_u32 s4, 0x80000
	s_waitcnt vmcnt(0)
	v_mul_f32_e32 v14, v22, v5
	v_pk_add_f32 v[2:3], v[2:3], v[14:15]
	v_mul_f32_e32 v16, v6, v24
	v_mul_f32_e32 v22, v7, v26
	v_pk_add_f32 v[2:3], v[2:3], v[16:17]
	v_mul_f32_e32 v24, v8, v28
	v_pk_add_f32 v[2:3], v[2:3], v[22:23]
	v_mul_f32_e32 v18, v9, v29
	v_pk_add_f32 v[2:3], v[2:3], v[24:25]
	v_mul_f32_e32 v20, v10, v30
	v_pk_add_f32 v[2:3], v[2:3], v[18:19]
	v_mul_f32_e32 v26, v11, v31
	v_pk_add_f32 v[2:3], v[2:3], v[20:21]
	v_mul_f32_e32 v12, v12, v32
	v_pk_add_f32 v[2:3], v[2:3], v[26:27]
	s_nop 0
	v_pk_add_f32 v[2:3], v[2:3], v[12:13]
	s_cbranch_scc1 .LBB0_52
	s_add_u32 s4, s37, s8
	s_addc_u32 s5, s38, s9
	s_add_u32 s7, s39, s8
	s_addc_u32 s8, s40, s9
	s_add_u32 s4, s4, s62
	s_addc_u32 s5, s5, 0
	v_mov_b32_e32 v73, v69
	v_lshl_add_u64 v[0:1], s[4:5], 0, v[72:73]
	s_add_u32 s4, s7, s62
	s_addc_u32 s5, s8, 0
	global_atomic_add_f32 v[0:1], v3, off
	v_lshl_add_u64 v[0:1], s[4:5], 0, v[72:73]
	global_atomic_add_f32 v[0:1], v2, off
	s_waitcnt lgkmcnt(0)

; __device__ __forceinline__ void p0_transpose_item(const float* W, int K, int N, bf16* WT, float* scr, int item, int lane, const float* scale, const float* cb, float* c1, float* c2) {
;     const int nblk = N / 64, kb = item / nblk, nb = item % nblk, k0 = 64 * kb, n0 = 64 * nb;
;     const int lr = lane >> 4, lc = (lane & 15) * 4;
;     f32x4 v[16];
; #pragma unroll
;     for (int i = 0; i < 16; ++i) v[i] = *(const f32x4*)(W + (size_t)(k0 + 4 * i + lr) * N + n0 + lc);
; #pragma unroll
;     for (int i = 0; i < 16; ++i) { const int kk = 4 * i + lr; f32x4 w = v[i]; if (scale) w = w * scale[k0 + kk]; float* d = scr + kk * 65 + lc; d[0] = w[0]; d[1] = w[1]; d[2] = w[2]; d[3] = w[3]; }
.LBB0_55:
	s_andn2_b64 vcc, exec, s[4:5]
	s_cbranch_vccnz .LBB0_57
	s_ashr_i32 s7, s6, 31
	v_readlane_b32 s64, v253, 18
	s_lshl_b64 s[4:5], s[6:7], 24
	v_readlane_b32 s72, v253, 26
	v_readlane_b32 s73, v253, 27
	s_add_u32 s10, s72, s4
	s_addc_u32 s11, s73, s5
	s_lshl_b64 s[8:9], s[6:7], 23
	s_add_u32 s5, s28, s8
	s_addc_u32 s7, s29, s9
	s_lshl_b32 s4, s61, 1
	s_add_i32 s4, s4, 0x1e200
	s_and_b32 s8, s4, 0x1ffc0
	s_lshl_b32 s4, s61, 6
	s_and_b32 s4, s4, 0x7c0
	s_lshl_b32 s9, s4, 2
	s_add_u32 s10, s10, s9
	v_or_b32_e32 v2, s8, v80
	s_addc_u32 s11, s11, 0
	v_lshl_add_u64 v[0:1], s[10:11], 0, v[68:69]
	v_lshlrev_b32_e32 v2, 13, v2
	v_mov_b32_e32 v3, v69
	v_lshl_add_u64 v[60:61], v[0:1], 0, v[2:3]
	v_add_co_u32_e32 v4, vcc, s41, v60
	s_lshl_b32 s8, s8, 1
	s_nop 0
	v_addc_co_u32_e32 v5, vcc, 0, v61, vcc
	v_add_co_u32_e32 v8, vcc, s42, v60
	global_load_dwordx4 v[0:3], v[60:61], off
	s_nop 0
	global_load_dwordx4 v[4:7], v[4:5], off
	v_addc_co_u32_e32 v9, vcc, 0, v61, vcc
	v_add_co_u32_e32 v12, vcc, s43, v60
	s_add_u32 s8, s5, s8
	s_nop 0
	v_addc_co_u32_e32 v13, vcc, 0, v61, vcc
	v_add_co_u32_e32 v16, vcc, s44, v60
	global_load_dwordx4 v[8:11], v[8:9], off
	s_nop 0
	global_load_dwordx4 v[12:15], v[12:13], off
	v_addc_co_u32_e32 v17, vcc, 0, v61, vcc
	v_add_co_u32_e32 v20, vcc, s45, v60
	s_addc_u32 s9, s7, 0
	s_nop 0
	v_addc_co_u32_e32 v21, vcc, 0, v61, vcc
	v_add_co_u32_e32 v24, vcc, s46, v60
	global_load_dwordx4 v[16:19], v[16:17], off
	s_nop 0
	global_load_dwordx4 v[20:23], v[20:21], off
	v_addc_co_u32_e32 v25, vcc, 0, v61, vcc
	v_add_co_u32_e32 v28, vcc, s47, v60
	v_mov_b32_e32 v75, v69
	s_nop 0
	v_addc_co_u32_e32 v29, vcc, 0, v61, vcc
	v_add_co_u32_e32 v32, vcc, s48, v60
	global_load_dwordx4 v[24:27], v[24:25], off
	s_nop 0
	global_load_dwordx4 v[28:31], v[28:29], off
	v_addc_co_u32_e32 v33, vcc, 0, v61, vcc
	v_add_co_u32_e32 v36, vcc, s49, v60
	v_readlane_b32 s65, v253, 19
	s_nop 0
	v_addc_co_u32_e32 v37, vcc, 0, v61, vcc
	v_add_co_u32_e32 v40, vcc, s50, v60
	v_readlane_b32 s66, v253, 20
	s_nop 0
	v_addc_co_u32_e32 v41, vcc, 0, v61, vcc
	v_add_co_u32_e32 v44, vcc, s51, v60
	v_readlane_b32 s67, v253, 21
	s_nop 0
	v_addc_co_u32_e32 v45, vcc, 0, v61, vcc
	v_add_co_u32_e32 v48, vcc, s52, v60
	global_load_dwordx4 v[32:35], v[32:33], off
	s_nop 0
	global_load_dwordx4 v[36:39], v[36:37], off
	s_nop 0
	global_load_dwordx4 v[40:43], v[40:41], off
	s_nop 0
	global_load_dwordx4 v[44:47], v[44:45], off
	v_addc_co_u32_e32 v49, vcc, 0, v61, vcc
	v_add_co_u32_e32 v52, vcc, s53, v60
	v_readlane_b32 s68, v253, 22
	s_nop 0
	v_addc_co_u32_e32 v53, vcc, 0, v61, vcc
	global_load_dwordx4 v[48:51], v[48:49], off
	s_nop 0
	global_load_dwordx4 v[52:55], v[52:53], off
	v_add_co_u32_e32 v56, vcc, s54, v60
	v_readlane_b32 s69, v253, 23
	s_nop 0
	v_addc_co_u32_e32 v57, vcc, 0, v61, vcc
	global_load_dwordx4 v[56:59], v[56:57], off
	v_add_co_u32_e32 v60, vcc, s55, v60
	v_readlane_b32 s70, v253, 24
	s_nop 0
	v_addc_co_u32_e32 v61, vcc, 0, v61, vcc
	global_load_dwordx4 v[60:63], v[60:61], off
	v_readlane_b32 s71, v253, 25
	v_readlane_b32 s74, v253, 28
	v_readlane_b32 s75, v253, 29
	v_readlane_b32 s76, v253, 30
	v_readlane_b32 s77, v253, 31
	v_readlane_b32 s78, v253, 32
	v_readlane_b32 s79, v253, 33
	s_waitcnt vmcnt(0)
	ds_write2_b32 v81, v0, v1 offset1:1
	ds_write2_b32 v81, v2, v3 offset0:2 offset1:3
	ds_write2_b32 v92, v4, v5 offset1:1
	ds_write2_b32 v93, v6, v7 offset1:1
	ds_write2_b32 v94, v8, v9 offset1:1
	ds_write2_b32 v95, v10, v11 offset1:1
	ds_write2_b32 v96, v12, v13 offset1:1
	ds_write2_b32 v97, v14, v15 offset1:1
	ds_write2_b32 v98, v16, v17 offset1:1
	ds_write2_b32 v99, v18, v19 offset1:1
	ds_write2_b32 v100, v20, v21 offset1:1
	ds_write2_b32 v101, v22, v23 offset1:1
	ds_write2_b32 v102, v24, v25 offset1:1
	ds_write2_b32 v103, v26, v27 offset1:1
	ds_write2_b32 v104, v28, v29 offset1:1
	ds_write2_b32 v105, v30, v31 offset1:1
	ds_write2_b32 v106, v32, v33 offset1:1
	ds_write2_b32 v107, v34, v35 offset1:1
	ds_write2_b32 v108, v36, v37 offset1:1
	ds_write2_b32 v109, v38, v39 offset1:1
	ds_write2_b32 v110, v40, v41 offset1:1
	ds_write2_b32 v111, v42, v43 offset1:1
	ds_write2_b32 v112, v44, v45 offset1:1
	ds_write2_b32 v113, v46, v47 offset1:1
	ds_write2_b32 v114, v48, v49 offset1:1
	ds_write2_b32 v115, v50, v51 offset1:1
	ds_write2_b32 v116, v52, v53 offset1:1
	ds_write2_b32 v117, v54, v55 offset1:1
	ds_write2_b32 v118, v56, v57 offset1:1
	ds_write2_b32 v119, v58, v59 offset1:1
	ds_write2_b32 v120, v60, v61 offset1:1
	ds_write2_b32 v121, v62, v63 offset1:1
	s_waitcnt lgkmcnt(0)
; #define LDS_WAIT() asm volatile("s_waitcnt lgkmcnt(0)" ::: "memory")
; __device__ __forceinline__ unsigned pk2(float lo, float hi) { unsigned r; asm("v_cvt_pk_bf16_f32 %0, %1, %2" : "=v"(r) : "v"(lo), "v"(hi)); return r; }
; __device__ __forceinline__ void p0_transpose_item(const float* W, int K, int N, bf16* WT, float* scr, int item, int lane, const float* scale, const float* cb, float* c1, float* c2) {
;     ...
;     LDS_WAIT(); asm volatile("" ::: "memory");
;     const int c = lane & 7;
; #pragma unroll
;     for (int j = 0; j < 8; ++j) { const int n = (lane >> 3) + 8 * j; const float* sp = scr + (8 * c) * 65 + n;
;         v4u o; o.x = pk2(sp[0 * 65], sp[1 * 65]); o.y = pk2(sp[2 * 65], sp[3 * 65]); o.z = pk2(sp[4 * 65], sp[5 * 65]); o.w = pk2(sp[6 * 65], sp[7 * 65]);
;         *(v4u*)(WT + (size_t)(n0 + n) * K + k0 + 8 * c) = o; }
	ds_read_b32 v0, v83
	ds_read_b32 v1, v83 offset:260
	ds_read_b32 v2, v83 offset:520
	ds_read_b32 v3, v83 offset:780
	ds_read_b32 v6, v83 offset:1040
	ds_read_b32 v7, v83 offset:1300
	ds_read_b32 v8, v83 offset:1560
	ds_read_b32 v9, v83 offset:1820
	s_waitcnt lgkmcnt(0)
	v_cvt_pk_bf16_f32 v0, v0, v1
	v_cvt_pk_bf16_f32 v1, v2, v3
	v_cvt_pk_bf16_f32 v2, v6, v7
	v_or_b32_e32 v6, s4, v82
	v_lshl_add_u64 v[4:5], s[8:9], 0, v[74:75]
	v_lshlrev_b32_e32 v6, 12, v6
	v_mov_b32_e32 v7, v69
	v_lshl_add_u64 v[6:7], v[4:5], 0, v[6:7]
	v_cvt_pk_bf16_f32 v3, v8, v9
	global_store_dwordx4 v[6:7], v[0:3], off
	ds_read_b32 v0, v83 offset:32
	ds_read_b32 v1, v83 offset:292
	ds_read_b32 v2, v83 offset:552
	ds_read_b32 v3, v83 offset:812
	ds_read_b32 v6, v83 offset:1072
	ds_read_b32 v7, v83 offset:1332
	ds_read_b32 v8, v83 offset:1592
	ds_read_b32 v9, v83 offset:1852
	s_waitcnt lgkmcnt(0)
	v_cvt_pk_bf16_f32 v0, v0, v1
	v_cvt_pk_bf16_f32 v1, v2, v3
	v_cvt_pk_bf16_f32 v2, v6, v7
	v_or_b32_e32 v6, s4, v84
	v_lshlrev_b32_e32 v6, 12, v6
	v_mov_b32_e32 v7, v69
	v_lshl_add_u64 v[6:7], v[4:5], 0, v[6:7]
	v_cvt_pk_bf16_f32 v3, v8, v9
	global_store_dwordx4 v[6:7], v[0:3], off
	ds_read_b32 v0, v83 offset:64
	ds_read_b32 v1, v83 offset:324
	ds_read_b32 v2, v83 offset:584
	ds_read_b32 v3, v83 offset:844
	ds_read_b32 v6, v83 offset:1104
	ds_read_b32 v7, v83 offset:1364
	ds_read_b32 v8, v83 offset:1624
	ds_read_b32 v9, v83 offset:1884
	s_waitcnt lgkmcnt(0)
	v_cvt_pk_bf16_f32 v0, v0, v1
	v_cvt_pk_bf16_f32 v1, v2, v3
	v_cvt_pk_bf16_f32 v2, v6, v7
	v_or_b32_e32 v6, s4, v85
	v_lshlrev_b32_e32 v6, 12, v6
	v_mov_b32_e32 v7, v69
	v_lshl_add_u64 v[6:7], v[4:5], 0, v[6:7]
	v_cvt_pk_bf16_f32 v3, v8, v9
	global_store_dwordx4 v[6:7], v[0:3], off
	ds_read_b32 v0, v83 offset:96
	ds_read_b32 v1, v83 offset:356
	ds_read_b32 v2, v83 offset:616
	ds_read_b32 v3, v83 offset:876
	ds_read_b32 v6, v83 offset:1136
	ds_read_b32 v7, v83 offset:1396
	ds_read_b32 v8, v83 offset:1656
	ds_read_b32 v9, v83 offset:1916
	s_waitcnt lgkmcnt(0)
	v_cvt_pk_bf16_f32 v0, v0, v1
	v_cvt_pk_bf16_f32 v1, v2, v3
	v_cvt_pk_bf16_f32 v2, v6, v7
	v_or_b32_e32 v6, s4, v86
	v_lshlrev_b32_e32 v6, 12, v6
	v_mov_b32_e32 v7, v69
	v_lshl_add_u64 v[6:7], v[4:5], 0, v[6:7]
	v_cvt_pk_bf16_f32 v3, v8, v9
	global_store_dwordx4 v[6:7], v[0:3], off
	ds_read_b32 v0, v83 offset:128
	ds_read_b32 v1, v83 offset:388
	ds_read_b32 v2, v83 offset:648
	ds_read_b32 v3, v83 offset:908
	ds_read_b32 v6, v83 offset:1168
	ds_read_b32 v7, v83 offset:1428
	ds_read_b32 v8, v83 offset:1688
	ds_read_b32 v9, v83 offset:1948
	s_waitcnt lgkmcnt(0)
	v_cvt_pk_bf16_f32 v0, v0, v1
	v_cvt_pk_bf16_f32 v1, v2, v3
	v_cvt_pk_bf16_f32 v2, v6, v7
	v_or_b32_e32 v6, s4, v87
	v_lshlrev_b32_e32 v6, 12, v6
	v_mov_b32_e32 v7, v69
	v_lshl_add_u64 v[6:7], v[4:5], 0, v[6:7]
	v_cvt_pk_bf16_f32 v3, v8, v9
	global_store_dwordx4 v[6:7], v[0:3], off
	ds_read_b32 v0, v83 offset:160
	ds_read_b32 v1, v83 offset:420
	ds_read_b32 v2, v83 offset:680
	ds_read_b32 v3, v83 offset:940
	ds_read_b32 v6, v83 offset:1200
	ds_read_b32 v7, v83 offset:1460
	ds_read_b32 v8, v83 offset:1720
	ds_read_b32 v9, v83 offset:1980
	s_waitcnt lgkmcnt(0)
	v_cvt_pk_bf16_f32 v0, v0, v1
	v_cvt_pk_bf16_f32 v1, v2, v3
	v_cvt_pk_bf16_f32 v2, v6, v7
	v_or_b32_e32 v6, s4, v88
	v_lshlrev_b32_e32 v6, 12, v6
	v_mov_b32_e32 v7, v69
	v_lshl_add_u64 v[6:7], v[4:5], 0, v[6:7]
	v_cvt_pk_bf16_f32 v3, v8, v9
	global_store_dwordx4 v[6:7], v[0:3], off
	ds_read_b32 v0, v83 offset:192
	ds_read_b32 v1, v83 offset:452
	ds_read_b32 v2, v83 offset:712
	ds_read_b32 v3, v83 offset:972
	ds_read_b32 v6, v83 offset:1232
	ds_read_b32 v7, v83 offset:1492
	ds_read_b32 v8, v83 offset:1752
	ds_read_b32 v9, v83 offset:2012
	s_waitcnt lgkmcnt(0)
	v_cvt_pk_bf16_f32 v0, v0, v1
	v_cvt_pk_bf16_f32 v1, v2, v3
	v_cvt_pk_bf16_f32 v2, v6, v7
	v_or_b32_e32 v6, s4, v89
	v_lshlrev_b32_e32 v6, 12, v6
	v_mov_b32_e32 v7, v69
	v_lshl_add_u64 v[6:7], v[4:5], 0, v[6:7]
	v_cvt_pk_bf16_f32 v3, v8, v9
	global_store_dwordx4 v[6:7], v[0:3], off
	ds_read_b32 v0, v83 offset:224
	ds_read_b32 v1, v83 offset:484
	ds_read_b32 v2, v83 offset:744
	ds_read_b32 v3, v83 offset:1004
	ds_read_b32 v6, v83 offset:1264
	ds_read_b32 v7, v83 offset:1524
	ds_read_b32 v8, v83 offset:1784
	ds_read_b32 v9, v83 offset:2044
	s_waitcnt lgkmcnt(0)
	v_cvt_pk_bf16_f32 v0, v0, v1
	v_cvt_pk_bf16_f32 v1, v2, v3
	v_cvt_pk_bf16_f32 v2, v6, v7
	v_or_b32_e32 v6, s4, v90
	v_lshlrev_b32_e32 v6, 12, v6
	v_mov_b32_e32 v7, v69
	v_lshl_add_u64 v[4:5], v[4:5], 0, v[6:7]
	v_cvt_pk_bf16_f32 v3, v8, v9
	global_store_dwordx4 v[4:5], v[0:3], off
	s_waitcnt lgkmcnt(0)

; __device__ __forceinline__ void p0_transpose_item(const float* W, int K, int N, bf16* WT, float* scr, int item, int lane, const float* scale, const float* cb, float* c1, float* c2) {
;     const int nblk = N / 64, kb = item / nblk, nb = item % nblk, k0 = 64 * kb, n0 = 64 * nb;
;     const int lr = lane >> 4, lc = (lane & 15) * 4;
;     f32x4 v[16];
; #pragma unroll
;     for (int i = 0; i < 16; ++i) v[i] = *(const f32x4*)(W + (size_t)(k0 + 4 * i + lr) * N + n0 + lc);
; #pragma unroll
;     for (int i = 0; i < 16; ++i) { const int kk = 4 * i + lr; f32x4 w = v[i]; if (scale) w = w * scale[k0 + kk]; float* d = scr + kk * 65 + lc; d[0] = w[0]; d[1] = w[1]; d[2] = w[2]; d[3] = w[3]; }
.LBB0_58:
	v_readlane_b32 s64, v253, 2
	s_mul_i32 s5, s6, 0x3c00000
	v_readlane_b32 s68, v253, 6
	s_mul_hi_i32 s4, s6, 0x3c00000
	v_readlane_b32 s69, v253, 7
	s_add_u32 s7, s68, s5
	s_addc_u32 s12, s69, s4
	s_mul_i32 s5, s6, 0x1e00000
	s_mul_hi_i32 s4, s6, 0x1e00000
	s_add_u32 s8, s26, s5
	s_addc_u32 s9, s27, s4
	s_mul_i32 s4, s61, 0xffff8889
	s_lshr_b32 s4, s4, 16
	s_add_i32 s4, s4, s61
	s_sext_i32_i16 s5, s4
	s_ashr_i32 s5, s5, 6
	s_bfe_u32 s4, s4, 0x1000f
	s_add_i32 s4, s5, s4
	s_sext_i32_i16 s5, s4
	s_mulk_i32 s4, 0x78
	s_sub_i32 s4, s61, s4
	s_sext_i32_i16 s4, s4
	s_lshl_b32 s4, s4, 6
	s_lshl_b32 s6, s5, 6
	s_ashr_i32 s5, s4, 31
	s_lshl_b64 s[10:11], s[4:5], 2
	v_or_b32_e32 v2, s6, v80
	s_add_u32 s10, s7, s10
	s_addc_u32 s11, s12, s11
	v_mul_i32_i24_e32 v2, 0x1e00, v2
	v_lshl_add_u64 v[0:1], s[10:11], 0, v[68:69]
	v_ashrrev_i32_e32 v3, 31, v2
	v_lshl_add_u64 v[60:61], v[2:3], 2, v[0:1]
	s_mov_b32 s5, 0x1e000
	v_add_co_u32_e32 v4, vcc, s5, v60
	s_mov_b32 s5, 0x3c000
	s_nop 0
	v_addc_co_u32_e32 v5, vcc, 0, v61, vcc
	v_add_co_u32_e32 v8, vcc, s5, v60
	s_mov_b32 s5, 0x5a000
	s_nop 0
	v_addc_co_u32_e32 v9, vcc, 0, v61, vcc
	v_add_co_u32_e32 v12, vcc, s5, v60
	s_mov_b32 s5, 0x96000
	s_nop 0
	v_addc_co_u32_e32 v13, vcc, 0, v61, vcc
	v_add_co_u32_e32 v16, vcc, s55, v60
	global_load_dwordx4 v[0:3], v[60:61], off
	s_nop 0
	global_load_dwordx4 v[4:7], v[4:5], off
	v_addc_co_u32_e32 v17, vcc, 0, v61, vcc
	v_add_co_u32_e32 v20, vcc, s5, v60
	s_mov_b32 s5, 0xb4000
	s_nop 0
	v_addc_co_u32_e32 v21, vcc, 0, v61, vcc
	v_add_co_u32_e32 v24, vcc, s5, v60
	s_mov_b32 s5, 0xd2000
	s_nop 0
	v_addc_co_u32_e32 v25, vcc, 0, v61, vcc
	v_add_co_u32_e32 v28, vcc, s5, v60
	s_mov_b32 s5, 0xf0000
	s_nop 0
	v_addc_co_u32_e32 v29, vcc, 0, v61, vcc
	v_add_co_u32_e32 v32, vcc, s5, v60
	s_mov_b32 s5, 0x10e000
	s_nop 0
	v_addc_co_u32_e32 v33, vcc, 0, v61, vcc
	v_add_co_u32_e32 v36, vcc, s5, v60
	s_mov_b32 s5, 0x12c000
	s_nop 0
	v_addc_co_u32_e32 v37, vcc, 0, v61, vcc
	v_add_co_u32_e32 v40, vcc, s5, v60
	global_load_dwordx4 v[8:11], v[8:9], off
	s_nop 0
	global_load_dwordx4 v[12:15], v[12:13], off
	v_addc_co_u32_e32 v41, vcc, 0, v61, vcc
	v_add_co_u32_e32 v44, vcc, s56, v60
	global_load_dwordx4 v[16:19], v[16:17], off
	s_nop 0
	global_load_dwordx4 v[20:23], v[20:21], off
	v_addc_co_u32_e32 v45, vcc, 0, v61, vcc
	v_add_co_u32_e32 v48, vcc, s57, v60
	global_load_dwordx4 v[24:27], v[24:25], off
	s_nop 0
	global_load_dwordx4 v[28:31], v[28:29], off
	v_addc_co_u32_e32 v49, vcc, 0, v61, vcc
	v_add_co_u32_e32 v52, vcc, s58, v60
	global_load_dwordx4 v[32:35], v[32:33], off
	s_nop 0
	global_load_dwordx4 v[36:39], v[36:37], off
	v_addc_co_u32_e32 v53, vcc, 0, v61, vcc
	global_load_dwordx4 v[40:43], v[40:41], off
	s_nop 0
	global_load_dwordx4 v[44:47], v[44:45], off
	s_nop 0
	global_load_dwordx4 v[48:51], v[48:49], off
	s_nop 0
	global_load_dwordx4 v[52:55], v[52:53], off
	v_add_co_u32_e32 v56, vcc, s59, v60
	s_ashr_i32 s7, s6, 31
	s_nop 0
	v_addc_co_u32_e32 v57, vcc, 0, v61, vcc
	global_load_dwordx4 v[56:59], v[56:57], off
	v_add_co_u32_e32 v60, vcc, s60, v60
	s_lshl_b64 s[6:7], s[6:7], 1
	s_nop 0
	v_addc_co_u32_e32 v61, vcc, 0, v61, vcc
	global_load_dwordx4 v[60:63], v[60:61], off
	s_add_u32 s6, s8, s6
	s_addc_u32 s7, s9, s7
	v_mov_b32_e32 v75, v69
	v_readlane_b32 s65, v253, 3
	v_readlane_b32 s66, v253, 4
	v_readlane_b32 s67, v253, 5
	v_readlane_b32 s70, v253, 8
	v_readlane_b32 s71, v253, 9
	v_readlane_b32 s72, v253, 10
	v_readlane_b32 s73, v253, 11
	v_readlane_b32 s74, v253, 12
	v_readlane_b32 s75, v253, 13
	v_readlane_b32 s76, v253, 14
	v_readlane_b32 s77, v253, 15
	s_waitcnt vmcnt(0)
	ds_write2_b32 v81, v0, v1 offset1:1
	ds_write2_b32 v81, v2, v3 offset0:2 offset1:3
	ds_write2_b32 v92, v4, v5 offset1:1
	ds_write2_b32 v93, v6, v7 offset1:1
	ds_write2_b32 v94, v8, v9 offset1:1
	ds_write2_b32 v95, v10, v11 offset1:1
	ds_write2_b32 v96, v12, v13 offset1:1
	ds_write2_b32 v97, v14, v15 offset1:1
	ds_write2_b32 v98, v16, v17 offset1:1
	ds_write2_b32 v99, v18, v19 offset1:1
	ds_write2_b32 v100, v20, v21 offset1:1
	ds_write2_b32 v101, v22, v23 offset1:1
	ds_write2_b32 v102, v24, v25 offset1:1
	ds_write2_b32 v103, v26, v27 offset1:1
	ds_write2_b32 v104, v28, v29 offset1:1
	ds_write2_b32 v105, v30, v31 offset1:1
	ds_write2_b32 v106, v32, v33 offset1:1
	ds_write2_b32 v107, v34, v35 offset1:1
	ds_write2_b32 v108, v36, v37 offset1:1
	ds_write2_b32 v109, v38, v39 offset1:1
	ds_write2_b32 v110, v40, v41 offset1:1
	ds_write2_b32 v111, v42, v43 offset1:1
	ds_write2_b32 v112, v44, v45 offset1:1
	ds_write2_b32 v113, v46, v47 offset1:1
	ds_write2_b32 v114, v48, v49 offset1:1
	ds_write2_b32 v115, v50, v51 offset1:1
	ds_write2_b32 v116, v52, v53 offset1:1
	ds_write2_b32 v117, v54, v55 offset1:1
	ds_write2_b32 v118, v56, v57 offset1:1
	ds_write2_b32 v119, v58, v59 offset1:1
	ds_write2_b32 v120, v60, v61 offset1:1
	ds_write2_b32 v121, v62, v63 offset1:1
	s_waitcnt lgkmcnt(0)
; #define LDS_WAIT() asm volatile("s_waitcnt lgkmcnt(0)" ::: "memory")
; __device__ __forceinline__ unsigned pk2(float lo, float hi) { unsigned r; asm("v_cvt_pk_bf16_f32 %0, %1, %2" : "=v"(r) : "v"(lo), "v"(hi)); return r; }
; __device__ __forceinline__ void p0_transpose_item(const float* W, int K, int N, bf16* WT, float* scr, int item, int lane, const float* scale, const float* cb, float* c1, float* c2) {
;     ...
;     LDS_WAIT(); asm volatile("" ::: "memory");
;     const int c = lane & 7;
; #pragma unroll
;     for (int j = 0; j < 8; ++j) { const int n = (lane >> 3) + 8 * j; const float* sp = scr + (8 * c) * 65 + n;
;         v4u o; o.x = pk2(sp[0 * 65], sp[1 * 65]); o.y = pk2(sp[2 * 65], sp[3 * 65]); o.z = pk2(sp[4 * 65], sp[5 * 65]); o.w = pk2(sp[6 * 65], sp[7 * 65]);
;         *(v4u*)(WT + (size_t)(n0 + n) * K + k0 + 8 * c) = o; }
	ds_read_b32 v0, v83
	ds_read_b32 v1, v83 offset:260
	ds_read_b32 v2, v83 offset:520
	ds_read_b32 v3, v83 offset:780
	ds_read_b32 v6, v83 offset:1040
	ds_read_b32 v7, v83 offset:1300
	ds_read_b32 v8, v83 offset:1560
	ds_read_b32 v9, v83 offset:1820
	s_waitcnt lgkmcnt(0)
	v_cvt_pk_bf16_f32 v0, v0, v1
	v_cvt_pk_bf16_f32 v1, v2, v3
	v_cvt_pk_bf16_f32 v2, v6, v7
	v_or_b32_e32 v6, s4, v82
	v_ashrrev_i32_e32 v7, 31, v6
	v_lshl_add_u64 v[4:5], s[6:7], 0, v[74:75]
	v_lshlrev_b64 v[6:7], 12, v[6:7]
	v_lshl_add_u64 v[6:7], v[4:5], 0, v[6:7]
	v_cvt_pk_bf16_f32 v3, v8, v9
	global_store_dwordx4 v[6:7], v[0:3], off
	ds_read_b32 v0, v83 offset:32
	ds_read_b32 v1, v83 offset:292
	ds_read_b32 v2, v83 offset:552
	ds_read_b32 v3, v83 offset:812
	ds_read_b32 v6, v83 offset:1072
	ds_read_b32 v7, v83 offset:1332
	ds_read_b32 v8, v83 offset:1592
	ds_read_b32 v9, v83 offset:1852
	s_waitcnt lgkmcnt(0)
	v_cvt_pk_bf16_f32 v0, v0, v1
	v_cvt_pk_bf16_f32 v1, v2, v3
	v_cvt_pk_bf16_f32 v2, v6, v7
	v_or_b32_e32 v6, s4, v84
	v_ashrrev_i32_e32 v7, 31, v6
	v_lshlrev_b64 v[6:7], 12, v[6:7]
	v_lshl_add_u64 v[6:7], v[4:5], 0, v[6:7]
	v_cvt_pk_bf16_f32 v3, v8, v9
	global_store_dwordx4 v[6:7], v[0:3], off
	ds_read_b32 v0, v83 offset:64
	ds_read_b32 v1, v83 offset:324
	ds_read_b32 v2, v83 offset:584
	ds_read_b32 v3, v83 offset:844
	ds_read_b32 v6, v83 offset:1104
	ds_read_b32 v7, v83 offset:1364
	ds_read_b32 v8, v83 offset:1624
	ds_read_b32 v9, v83 offset:1884
	s_waitcnt lgkmcnt(0)
	v_cvt_pk_bf16_f32 v0, v0, v1
	v_cvt_pk_bf16_f32 v1, v2, v3
	v_cvt_pk_bf16_f32 v2, v6, v7
	v_or_b32_e32 v6, s4, v85
	v_ashrrev_i32_e32 v7, 31, v6
	v_lshlrev_b64 v[6:7], 12, v[6:7]
	v_lshl_add_u64 v[6:7], v[4:5], 0, v[6:7]
	v_cvt_pk_bf16_f32 v3, v8, v9
	global_store_dwordx4 v[6:7], v[0:3], off
	ds_read_b32 v0, v83 offset:96
	ds_read_b32 v1, v83 offset:356
	ds_read_b32 v2, v83 offset:616
	ds_read_b32 v3, v83 offset:876
	ds_read_b32 v6, v83 offset:1136
	ds_read_b32 v7, v83 offset:1396
	ds_read_b32 v8, v83 offset:1656
	ds_read_b32 v9, v83 offset:1916
	s_waitcnt lgkmcnt(0)
	v_cvt_pk_bf16_f32 v0, v0, v1
	v_cvt_pk_bf16_f32 v1, v2, v3
	v_cvt_pk_bf16_f32 v2, v6, v7
	v_or_b32_e32 v6, s4, v86
	v_ashrrev_i32_e32 v7, 31, v6
	v_lshlrev_b64 v[6:7], 12, v[6:7]
	v_lshl_add_u64 v[6:7], v[4:5], 0, v[6:7]
	v_cvt_pk_bf16_f32 v3, v8, v9
	global_store_dwordx4 v[6:7], v[0:3], off
	ds_read_b32 v0, v83 offset:128
	ds_read_b32 v1, v83 offset:388
	ds_read_b32 v2, v83 offset:648
	ds_read_b32 v3, v83 offset:908
	ds_read_b32 v6, v83 offset:1168
	ds_read_b32 v7, v83 offset:1428
	ds_read_b32 v8, v83 offset:1688
	ds_read_b32 v9, v83 offset:1948
	s_waitcnt lgkmcnt(0)
	v_cvt_pk_bf16_f32 v0, v0, v1
	v_cvt_pk_bf16_f32 v1, v2, v3
	v_cvt_pk_bf16_f32 v2, v6, v7
	v_or_b32_e32 v6, s4, v87
	v_ashrrev_i32_e32 v7, 31, v6
	v_lshlrev_b64 v[6:7], 12, v[6:7]
	v_lshl_add_u64 v[6:7], v[4:5], 0, v[6:7]
	v_cvt_pk_bf16_f32 v3, v8, v9
	global_store_dwordx4 v[6:7], v[0:3], off
	ds_read_b32 v0, v83 offset:160
	ds_read_b32 v1, v83 offset:420
	ds_read_b32 v2, v83 offset:680
	ds_read_b32 v3, v83 offset:940
	ds_read_b32 v6, v83 offset:1200
	ds_read_b32 v7, v83 offset:1460
	ds_read_b32 v8, v83 offset:1720
	ds_read_b32 v9, v83 offset:1980
	s_waitcnt lgkmcnt(0)
	v_cvt_pk_bf16_f32 v0, v0, v1
	v_cvt_pk_bf16_f32 v1, v2, v3
	v_cvt_pk_bf16_f32 v2, v6, v7
	v_or_b32_e32 v6, s4, v88
	v_ashrrev_i32_e32 v7, 31, v6
	v_lshlrev_b64 v[6:7], 12, v[6:7]
	v_lshl_add_u64 v[6:7], v[4:5], 0, v[6:7]
	v_cvt_pk_bf16_f32 v3, v8, v9
	global_store_dwordx4 v[6:7], v[0:3], off
	ds_read_b32 v0, v83 offset:192
	ds_read_b32 v1, v83 offset:452
	ds_read_b32 v2, v83 offset:712
	ds_read_b32 v3, v83 offset:972
	ds_read_b32 v6, v83 offset:1232
	ds_read_b32 v7, v83 offset:1492
	ds_read_b32 v8, v83 offset:1752
	ds_read_b32 v9, v83 offset:2012
	s_waitcnt lgkmcnt(0)
	v_cvt_pk_bf16_f32 v0, v0, v1
	v_cvt_pk_bf16_f32 v1, v2, v3
	v_cvt_pk_bf16_f32 v2, v6, v7
	v_or_b32_e32 v6, s4, v89
	v_ashrrev_i32_e32 v7, 31, v6
	v_lshlrev_b64 v[6:7], 12, v[6:7]
	v_lshl_add_u64 v[6:7], v[4:5], 0, v[6:7]
	v_cvt_pk_bf16_f32 v3, v8, v9
	global_store_dwordx4 v[6:7], v[0:3], off
	ds_read_b32 v0, v83 offset:224
	ds_read_b32 v1, v83 offset:484
	ds_read_b32 v2, v83 offset:744
	ds_read_b32 v3, v83 offset:1004
	ds_read_b32 v6, v83 offset:1264
	ds_read_b32 v7, v83 offset:1524
	ds_read_b32 v8, v83 offset:1784
	ds_read_b32 v9, v83 offset:2044
	s_waitcnt lgkmcnt(0)
	v_cvt_pk_bf16_f32 v0, v0, v1
	v_cvt_pk_bf16_f32 v1, v2, v3
	v_cvt_pk_bf16_f32 v2, v6, v7
	v_or_b32_e32 v6, s4, v90
	v_ashrrev_i32_e32 v7, 31, v6
	v_lshlrev_b64 v[6:7], 12, v[6:7]
	v_lshl_add_u64 v[4:5], v[4:5], 0, v[6:7]
	v_cvt_pk_bf16_f32 v3, v8, v9
	global_store_dwordx4 v[4:5], v[0:3], off
	s_waitcnt lgkmcnt(0)
	v_readlane_b32 s78, v253, 16
	v_readlane_b32 s79, v253, 17
	s_branch .LBB0_20

; __device__ __forceinline__ unsigned pk2(float lo, float hi) { unsigned r; asm("v_cvt_pk_bf16_f32 %0, %1, %2" : "=v"(r) : "v"(lo), "v"(hi)); return r; }
; __global__ void __launch_bounds__(512, 2) mk_fwd(Args args) {
;     ...
;         for (int i0 = gtid; i0 < MT * DM / 4; i0 += 8 * gstride) { f32x4 v[8];
; #pragma unroll
;             for (int u = 0; u < 8; ++u) { const int i = i0 + u * gstride; if (i < MT * DM / 4) v[u] = ((const f32x4*)args.in[0])[i]; }
; #pragma unroll
;             for (int u = 0; u < 8; ++u) { const int i = i0 + u * gstride; if (i < MT * DM / 4) { v2u w; w.x = pk2(v[u][0], v[u][1]); w.y = pk2(v[u][2], v[u][3]); ((v2u*)XB)[i] = w; } } }
.LBB0_84:
	s_or_b64 exec, exec, s[34:35]
	s_waitcnt vmcnt(0)
	v_cvt_pk_bf16_f32 v48, v28, v29
	v_lshl_add_u64 v[28:29], v[34:35], 3, s[28:29]
	v_cvt_pk_bf16_f32 v49, v30, v31
	global_store_dwordx2 v[28:29], v[48:49], off
	s_and_saveexec_b64 s[34:35], vcc
	s_cbranch_execnz .LBB0_91
	s_or_b64 exec, exec, s[34:35]
	s_and_saveexec_b64 s[34:35], s[4:5]
	s_cbranch_execnz .LBB0_92

; __device__ __forceinline__ unsigned pk2(float lo, float hi) { unsigned r; asm("v_cvt_pk_bf16_f32 %0, %1, %2" : "=v"(r) : "v"(lo), "v"(hi)); return r; }
; __global__ void __launch_bounds__(512, 2) mk_fwd(Args args) {
;     ...
;             for (int u = 0; u < 8; ++u) { const int i = i0 + u * gstride; if (i < MT * DM / 4) v[u] = ((const f32x4*)args.in[0])[i]; }
; #pragma unroll
;             for (int u = 0; u < 8; ++u) { const int i = i0 + u * gstride; if (i < MT * DM / 4) { v2u w; w.x = pk2(v[u][0], v[u][1]); w.y = pk2(v[u][2], v[u][3]); ((v2u*)XB)[i] = w; } } }
.LBB0_91:
	v_lshl_add_u64 v[28:29], s[2:3], 3, v[28:29]
	v_cvt_pk_bf16_f32 v30, v0, v1
	v_cvt_pk_bf16_f32 v31, v2, v3
	global_store_dwordx2 v[28:29], v[30:31], off
	s_or_b64 exec, exec, s[34:35]
	s_and_saveexec_b64 s[34:35], s[4:5]
	s_cbranch_execz .LBB0_86
.LBB0_92:
	v_ashrrev_i32_e32 v37, 31, v36
	v_lshl_add_u64 v[30:31], v[36:37], 3, s[28:29]
	v_cvt_pk_bf16_f32 v28, v4, v5
	v_cvt_pk_bf16_f32 v29, v6, v7
	global_store_dwordx2 v[30:31], v[28:29], off
	s_or_b64 exec, exec, s[34:35]
	s_and_saveexec_b64 s[4:5], s[6:7]
	s_cbranch_execz .LBB0_87
.LBB0_93:
	v_ashrrev_i32_e32 v39, 31, v38
	v_lshl_add_u64 v[30:31], v[38:39], 3, s[28:29]
	v_cvt_pk_bf16_f32 v28, v8, v9
	v_cvt_pk_bf16_f32 v29, v10, v11
	global_store_dwordx2 v[30:31], v[28:29], off
	s_or_b64 exec, exec, s[4:5]
	s_and_saveexec_b64 s[4:5], s[8:9]
	s_cbranch_execz .LBB0_88
.LBB0_94:
	v_ashrrev_i32_e32 v41, 31, v40
	v_lshl_add_u64 v[30:31], v[40:41], 3, s[28:29]
	v_cvt_pk_bf16_f32 v28, v12, v13
	v_cvt_pk_bf16_f32 v29, v14, v15
	global_store_dwordx2 v[30:31], v[28:29], off
	s_or_b64 exec, exec, s[4:5]
	s_and_saveexec_b64 s[4:5], s[10:11]
	s_cbranch_execz .LBB0_89
.LBB0_95:
	v_ashrrev_i32_e32 v43, 31, v42
	v_lshl_add_u64 v[30:31], v[42:43], 3, s[28:29]
	v_cvt_pk_bf16_f32 v28, v16, v17
	v_cvt_pk_bf16_f32 v29, v18, v19
	global_store_dwordx2 v[30:31], v[28:29], off
	s_or_b64 exec, exec, s[4:5]
	s_and_saveexec_b64 s[4:5], s[12:13]
	s_cbranch_execz .LBB0_90
.LBB0_96:
	v_ashrrev_i32_e32 v45, 31, v44
	v_lshl_add_u64 v[30:31], v[44:45], 3, s[28:29]
	v_cvt_pk_bf16_f32 v28, v20, v21
	v_cvt_pk_bf16_f32 v29, v22, v23
	global_store_dwordx2 v[30:31], v[28:29], off
	s_or_b64 exec, exec, s[4:5]
	s_and_saveexec_b64 s[4:5], s[14:15]
	s_cbranch_execz .LBB0_69
.LBB0_97:
	v_ashrrev_i32_e32 v47, 31, v46
	v_lshl_add_u64 v[30:31], v[46:47], 3, s[28:29]
	v_cvt_pk_bf16_f32 v28, v24, v25
	v_cvt_pk_bf16_f32 v29, v26, v27
	global_store_dwordx2 v[30:31], v[28:29], off
	s_branch .LBB0_69

; __device__ __forceinline__ unsigned pk2(float lo, float hi) { unsigned r; asm("v_cvt_pk_bf16_f32 %0, %1, %2" : "=v"(r) : "v"(lo), "v"(hi)); return r; }
; __global__ void __launch_bounds__(512, 2) mk_fwd(Args args) {
;     ...
;         for (int i0 = gtid; i0 < DEPTH * MT * PLE / 4; i0 += 8 * gstride) { f32x4 v[8];
; #pragma unroll
;             for (int u = 0; u < 8; ++u) { const int i = i0 + u * gstride; if (i < DEPTH * MT * PLE / 4) v[u] = ((const f32x4*)args.in[1])[i]; }
; #pragma unroll
;             for (int u = 0; u < 8; ++u) { const int i = i0 + u * gstride; if (i < DEPTH * MT * PLE / 4) { v2u w; w.x = pk2(v[u][0], v[u][1]); w.y = pk2(v[u][2], v[u][3]); ((v2u*)PB)[i] = w; } } }
.LBB0_115:
	s_or_b64 exec, exec, s[30:31]
	s_waitcnt vmcnt(0)
	v_cvt_pk_bf16_f32 v48, v28, v29
	v_lshl_add_u64 v[28:29], v[32:33], 3, s[24:25]
	v_cvt_pk_bf16_f32 v49, v30, v31
	global_store_dwordx2 v[28:29], v[48:49], off
	s_and_saveexec_b64 s[30:31], vcc
	s_cbranch_execnz .LBB0_122
	s_or_b64 exec, exec, s[30:31]
	s_and_saveexec_b64 s[30:31], s[4:5]
	s_cbranch_execnz .LBB0_123

; __device__ __forceinline__ unsigned pk2(float lo, float hi) { unsigned r; asm("v_cvt_pk_bf16_f32 %0, %1, %2" : "=v"(r) : "v"(lo), "v"(hi)); return r; }
; __global__ void __launch_bounds__(512, 2) mk_fwd(Args args) {
;     ...
;             for (int u = 0; u < 8; ++u) { const int i = i0 + u * gstride; if (i < DEPTH * MT * PLE / 4) v[u] = ((const f32x4*)args.in[1])[i]; }
; #pragma unroll
;             for (int u = 0; u < 8; ++u) { const int i = i0 + u * gstride; if (i < DEPTH * MT * PLE / 4) { v2u w; w.x = pk2(v[u][0], v[u][1]); w.y = pk2(v[u][2], v[u][3]); ((v2u*)PB)[i] = w; } } }
.LBB0_122:
	v_lshl_add_u64 v[28:29], s[2:3], 3, v[28:29]
	v_cvt_pk_bf16_f32 v30, v0, v1
	v_cvt_pk_bf16_f32 v31, v2, v3
	global_store_dwordx2 v[28:29], v[30:31], off
	s_or_b64 exec, exec, s[30:31]
	s_and_saveexec_b64 s[30:31], s[4:5]
	s_cbranch_execz .LBB0_117
.LBB0_123:
	v_ashrrev_i32_e32 v35, 31, v34
	v_lshl_add_u64 v[30:31], v[34:35], 3, s[24:25]
	v_cvt_pk_bf16_f32 v28, v4, v5
	v_cvt_pk_bf16_f32 v29, v6, v7
	global_store_dwordx2 v[30:31], v[28:29], off
	s_or_b64 exec, exec, s[30:31]
	s_and_saveexec_b64 s[4:5], s[6:7]
	s_cbranch_execz .LBB0_118
.LBB0_124:
	v_ashrrev_i32_e32 v37, 31, v36
	v_lshl_add_u64 v[30:31], v[36:37], 3, s[24:25]
	v_cvt_pk_bf16_f32 v28, v8, v9
	v_cvt_pk_bf16_f32 v29, v10, v11
	global_store_dwordx2 v[30:31], v[28:29], off
	s_or_b64 exec, exec, s[4:5]
	s_and_saveexec_b64 s[4:5], s[8:9]
	s_cbranch_execz .LBB0_119
.LBB0_125:
	v_ashrrev_i32_e32 v39, 31, v38
	v_lshl_add_u64 v[30:31], v[38:39], 3, s[24:25]
	v_cvt_pk_bf16_f32 v28, v12, v13
	v_cvt_pk_bf16_f32 v29, v14, v15
	global_store_dwordx2 v[30:31], v[28:29], off
	s_or_b64 exec, exec, s[4:5]
	s_and_saveexec_b64 s[4:5], s[10:11]
	s_cbranch_execz .LBB0_120
.LBB0_126:
	v_ashrrev_i32_e32 v41, 31, v40
	v_lshl_add_u64 v[30:31], v[40:41], 3, s[24:25]
	v_cvt_pk_bf16_f32 v28, v16, v17
	v_cvt_pk_bf16_f32 v29, v18, v19
	global_store_dwordx2 v[30:31], v[28:29], off
	s_or_b64 exec, exec, s[4:5]
	s_and_saveexec_b64 s[4:5], s[12:13]
	s_cbranch_execz .LBB0_121
.LBB0_127:
	v_ashrrev_i32_e32 v43, 31, v42
	v_lshl_add_u64 v[30:31], v[42:43], 3, s[24:25]
	v_cvt_pk_bf16_f32 v28, v20, v21
	v_cvt_pk_bf16_f32 v29, v22, v23
	global_store_dwordx2 v[30:31], v[28:29], off
	s_or_b64 exec, exec, s[4:5]
	s_and_saveexec_b64 s[4:5], s[14:15]
	s_cbranch_execz .LBB0_100
.LBB0_128:
	v_ashrrev_i32_e32 v45, 31, v44
	v_lshl_add_u64 v[30:31], v[44:45], 3, s[24:25]
	v_cvt_pk_bf16_f32 v28, v24, v25
	v_cvt_pk_bf16_f32 v29, v26, v27
	global_store_dwordx2 v[30:31], v[28:29], off
	s_branch .LBB0_100

; __device__ __forceinline__ void p0_transpose_item(const float* W, int K, int N, bf16* WT, float* scr, int item, int lane, const float* scale, const float* cb, float* c1, float* c2) {
;     const int nblk = N / 64, kb = item / nblk, nb = item % nblk, k0 = 64 * kb, n0 = 64 * nb;
;     const int lr = lane >> 4, lc = (lane & 15) * 4;
;     f32x4 v[16];
; #pragma unroll
;     for (int i = 0; i < 16; ++i) v[i] = *(const f32x4*)(W + (size_t)(k0 + 4 * i + lr) * N + n0 + lc);
; #pragma unroll
;     for (int i = 0; i < 16; ++i) { const int kk = 4 * i + lr; f32x4 w = v[i]; if (scale) w = w * scale[k0 + kk]; float* d = scr + kk * 65 + lc; d[0] = w[0]; d[1] = w[1]; d[2] = w[2]; d[3] = w[3]; }
.LBB0_163:
	s_mul_hi_i32 s2, s15, 0xae4c415d
	s_add_i32 s2, s2, s15
	s_lshr_b32 s3, s2, 31
	s_ashr_i32 s2, s2, 12
	s_add_i32 s2, s2, s3
	s_mul_i32 s3, s2, 0x1780
	s_sub_i32 s62, s15, s3
	s_cmpk_gt_i32 s62, 0xeff
	s_mov_b64 s[4:5], -1
	s_cbranch_scc0 .LBB0_199
	s_cmpk_gt_u32 s62, 0x12ff
	s_cbranch_scc0 .LBB0_196
	s_ashr_i32 s3, s2, 31
	s_cmpk_gt_u32 s62, 0x16ff
	s_cbranch_scc0 .LBB0_167
	v_readlane_b32 s64, v253, 18
	s_lshl_b64 s[4:5], s[2:3], 21
	v_readlane_b32 s78, v253, 32
	v_readlane_b32 s79, v253, 33
	s_add_u32 s6, s78, s4
	s_addc_u32 s7, s79, s5
	s_lshl_b64 s[4:5], s[2:3], 20
	s_add_u32 s8, s30, s4
	s_addc_u32 s5, s31, s5
	s_lshl_b32 s4, s62, 1
	s_and_b32 s9, s4, 0x1c0
	s_lshl_b32 s4, s62, 6
	s_and_b32 s4, s4, 0x7c0
	s_lshl_b32 s10, s4, 2
	s_add_u32 s6, s6, s10
	v_or_b32_e32 v2, s9, v80
	s_addc_u32 s7, s7, 0
	v_lshl_add_u64 v[0:1], s[6:7], 0, v[68:69]
	v_lshlrev_b32_e32 v2, 13, v2
	v_mov_b32_e32 v3, v69
	v_lshl_add_u64 v[60:61], v[0:1], 0, v[2:3]
	v_add_co_u32_e32 v4, vcc, s39, v60
	s_lshl_b32 s6, s9, 1
	s_nop 0
	v_addc_co_u32_e32 v5, vcc, 0, v61, vcc
	v_add_co_u32_e32 v8, vcc, s40, v60
	global_load_dwordx4 v[0:3], v[60:61], off
	s_nop 0
	global_load_dwordx4 v[4:7], v[4:5], off
	v_addc_co_u32_e32 v9, vcc, 0, v61, vcc
	v_add_co_u32_e32 v12, vcc, s41, v60
	s_add_u32 s6, s8, s6
	s_nop 0
	v_addc_co_u32_e32 v13, vcc, 0, v61, vcc
	v_add_co_u32_e32 v16, vcc, s42, v60
	global_load_dwordx4 v[8:11], v[8:9], off
	s_nop 0
	global_load_dwordx4 v[12:15], v[12:13], off
	v_addc_co_u32_e32 v17, vcc, 0, v61, vcc
	v_add_co_u32_e32 v20, vcc, s43, v60
	s_addc_u32 s7, s5, 0
	s_nop 0
	v_addc_co_u32_e32 v21, vcc, 0, v61, vcc
	v_add_co_u32_e32 v24, vcc, s44, v60
	global_load_dwordx4 v[16:19], v[16:17], off
	s_nop 0
	global_load_dwordx4 v[20:23], v[20:21], off
	v_addc_co_u32_e32 v25, vcc, 0, v61, vcc
	v_add_co_u32_e32 v28, vcc, s45, v60
	v_mov_b32_e32 v75, v69
	s_nop 0
	v_addc_co_u32_e32 v29, vcc, 0, v61, vcc
	v_add_co_u32_e32 v32, vcc, s46, v60
	global_load_dwordx4 v[24:27], v[24:25], off
	s_nop 0
	global_load_dwordx4 v[28:31], v[28:29], off
	v_addc_co_u32_e32 v33, vcc, 0, v61, vcc
	v_add_co_u32_e32 v36, vcc, s47, v60
	v_readlane_b32 s65, v253, 19
	s_nop 0
	v_addc_co_u32_e32 v37, vcc, 0, v61, vcc
	v_add_co_u32_e32 v40, vcc, s48, v60
	global_load_dwordx4 v[32:35], v[32:33], off
	s_nop 0
	global_load_dwordx4 v[36:39], v[36:37], off
	v_addc_co_u32_e32 v41, vcc, 0, v61, vcc
	v_add_co_u32_e32 v44, vcc, s49, v60
	v_readlane_b32 s66, v253, 20
	s_nop 0
	v_addc_co_u32_e32 v45, vcc, 0, v61, vcc
	v_add_co_u32_e32 v48, vcc, s50, v60
	global_load_dwordx4 v[40:43], v[40:41], off
	s_nop 0
	global_load_dwordx4 v[44:47], v[44:45], off
	v_addc_co_u32_e32 v49, vcc, 0, v61, vcc
	v_add_co_u32_e32 v52, vcc, s51, v60
	v_readlane_b32 s67, v253, 21
	s_nop 0
	v_addc_co_u32_e32 v53, vcc, 0, v61, vcc
	global_load_dwordx4 v[48:51], v[48:49], off
	s_nop 0
	global_load_dwordx4 v[52:55], v[52:53], off
	v_add_co_u32_e32 v56, vcc, s52, v60
	v_readlane_b32 s68, v253, 22
	s_nop 0
	v_addc_co_u32_e32 v57, vcc, 0, v61, vcc
	global_load_dwordx4 v[56:59], v[56:57], off
	v_add_co_u32_e32 v60, vcc, s53, v60
	v_readlane_b32 s69, v253, 23
	s_nop 0
	v_addc_co_u32_e32 v61, vcc, 0, v61, vcc
	global_load_dwordx4 v[60:63], v[60:61], off
	v_readlane_b32 s70, v253, 24
	v_readlane_b32 s71, v253, 25
	v_readlane_b32 s72, v253, 26
	v_readlane_b32 s73, v253, 27
	v_readlane_b32 s74, v253, 28
	v_readlane_b32 s75, v253, 29
	v_readlane_b32 s76, v253, 30
	v_readlane_b32 s77, v253, 31
	s_waitcnt vmcnt(0)
	ds_write2_b32 v81, v0, v1 offset1:1
	ds_write2_b32 v81, v2, v3 offset0:2 offset1:3
	ds_write2_b32 v92, v4, v5 offset1:1
	ds_write2_b32 v93, v6, v7 offset1:1
	ds_write2_b32 v94, v8, v9 offset1:1
	ds_write2_b32 v95, v10, v11 offset1:1
	ds_write2_b32 v96, v12, v13 offset1:1
	ds_write2_b32 v97, v14, v15 offset1:1
	ds_write2_b32 v98, v16, v17 offset1:1
	ds_write2_b32 v99, v18, v19 offset1:1
	ds_write2_b32 v100, v20, v21 offset1:1
	ds_write2_b32 v101, v22, v23 offset1:1
	ds_write2_b32 v102, v24, v25 offset1:1
	ds_write2_b32 v103, v26, v27 offset1:1
	ds_write2_b32 v104, v28, v29 offset1:1
	ds_write2_b32 v105, v30, v31 offset1:1
	ds_write2_b32 v106, v32, v33 offset1:1
	ds_write2_b32 v107, v34, v35 offset1:1
	ds_write2_b32 v108, v36, v37 offset1:1
	ds_write2_b32 v109, v38, v39 offset1:1
	ds_write2_b32 v110, v40, v41 offset1:1
	ds_write2_b32 v111, v42, v43 offset1:1
	ds_write2_b32 v112, v44, v45 offset1:1
	ds_write2_b32 v113, v46, v47 offset1:1
	ds_write2_b32 v114, v48, v49 offset1:1
	ds_write2_b32 v115, v50, v51 offset1:1
	ds_write2_b32 v116, v52, v53 offset1:1
	ds_write2_b32 v117, v54, v55 offset1:1
	ds_write2_b32 v118, v56, v57 offset1:1
	ds_write2_b32 v119, v58, v59 offset1:1
	ds_write2_b32 v120, v60, v61 offset1:1
	ds_write2_b32 v121, v62, v63 offset1:1
	s_waitcnt lgkmcnt(0)
; #define LDS_WAIT() asm volatile("s_waitcnt lgkmcnt(0)" ::: "memory")
; __device__ __forceinline__ unsigned pk2(float lo, float hi) { unsigned r; asm("v_cvt_pk_bf16_f32 %0, %1, %2" : "=v"(r) : "v"(lo), "v"(hi)); return r; }
; __device__ __forceinline__ void p0_transpose_item(const float* W, int K, int N, bf16* WT, float* scr, int item, int lane, const float* scale, const float* cb, float* c1, float* c2) {
;     ...
;     LDS_WAIT(); asm volatile("" ::: "memory");
;     const int c = lane & 7;
; #pragma unroll
;     for (int j = 0; j < 8; ++j) { const int n = (lane >> 3) + 8 * j; const float* sp = scr + (8 * c) * 65 + n;
;         v4u o; o.x = pk2(sp[0 * 65], sp[1 * 65]); o.y = pk2(sp[2 * 65], sp[3 * 65]); o.z = pk2(sp[4 * 65], sp[5 * 65]); o.w = pk2(sp[6 * 65], sp[7 * 65]);
;         *(v4u*)(WT + (size_t)(n0 + n) * K + k0 + 8 * c) = o; }
	ds_read_b32 v0, v83
	ds_read_b32 v1, v83 offset:260
	ds_read_b32 v2, v83 offset:520
	ds_read_b32 v3, v83 offset:780
	ds_read_b32 v6, v83 offset:1040
	ds_read_b32 v7, v83 offset:1300
	ds_read_b32 v8, v83 offset:1560
	ds_read_b32 v9, v83 offset:1820
	s_waitcnt lgkmcnt(0)
	v_cvt_pk_bf16_f32 v0, v0, v1
	s_waitcnt lgkmcnt(4)
	v_cvt_pk_bf16_f32 v1, v2, v3
	s_waitcnt lgkmcnt(2)
	v_cvt_pk_bf16_f32 v2, v6, v7
	v_or_b32_e32 v6, s4, v82
	v_lshl_add_u64 v[4:5], s[6:7], 0, v[74:75]
	v_lshlrev_b32_e32 v6, 9, v6
	v_mov_b32_e32 v7, v69
	v_lshl_add_u64 v[6:7], v[4:5], 0, v[6:7]
	s_waitcnt lgkmcnt(0)
	v_cvt_pk_bf16_f32 v3, v8, v9
	global_store_dwordx4 v[6:7], v[0:3], off
	ds_read_b32 v0, v83 offset:32
	ds_read_b32 v1, v83 offset:292
	ds_read_b32 v2, v83 offset:552
	ds_read_b32 v3, v83 offset:812
	ds_read_b32 v6, v83 offset:1072
	ds_read_b32 v7, v83 offset:1332
	ds_read_b32 v8, v83 offset:1592
	ds_read_b32 v9, v83 offset:1852
	s_waitcnt lgkmcnt(0)
	v_cvt_pk_bf16_f32 v0, v0, v1
	v_cvt_pk_bf16_f32 v1, v2, v3
	v_cvt_pk_bf16_f32 v2, v6, v7
	v_or_b32_e32 v6, s4, v84
	v_lshlrev_b32_e32 v6, 9, v6
	v_mov_b32_e32 v7, v69
	v_lshl_add_u64 v[6:7], v[4:5], 0, v[6:7]
	v_cvt_pk_bf16_f32 v3, v8, v9
	global_store_dwordx4 v[6:7], v[0:3], off
	ds_read_b32 v0, v83 offset:64
	ds_read_b32 v1, v83 offset:324
	ds_read_b32 v2, v83 offset:584
	ds_read_b32 v3, v83 offset:844
	ds_read_b32 v6, v83 offset:1104
	ds_read_b32 v7, v83 offset:1364
	ds_read_b32 v8, v83 offset:1624
	ds_read_b32 v9, v83 offset:1884
	s_waitcnt lgkmcnt(0)
	v_cvt_pk_bf16_f32 v0, v0, v1
	v_cvt_pk_bf16_f32 v1, v2, v3
	v_cvt_pk_bf16_f32 v2, v6, v7
	v_or_b32_e32 v6, s4, v85
	v_lshlrev_b32_e32 v6, 9, v6
	v_mov_b32_e32 v7, v69
	v_lshl_add_u64 v[6:7], v[4:5], 0, v[6:7]
	v_cvt_pk_bf16_f32 v3, v8, v9
	global_store_dwordx4 v[6:7], v[0:3], off
	ds_read_b32 v0, v83 offset:96
	ds_read_b32 v1, v83 offset:356
	ds_read_b32 v2, v83 offset:616
	ds_read_b32 v3, v83 offset:876
	ds_read_b32 v6, v83 offset:1136
	ds_read_b32 v7, v83 offset:1396
	ds_read_b32 v8, v83 offset:1656
	ds_read_b32 v9, v83 offset:1916
	s_waitcnt lgkmcnt(0)
	v_cvt_pk_bf16_f32 v0, v0, v1
	v_cvt_pk_bf16_f32 v1, v2, v3
	v_cvt_pk_bf16_f32 v2, v6, v7
	v_or_b32_e32 v6, s4, v86
	v_lshlrev_b32_e32 v6, 9, v6
	v_mov_b32_e32 v7, v69
	v_lshl_add_u64 v[6:7], v[4:5], 0, v[6:7]
	v_cvt_pk_bf16_f32 v3, v8, v9
	global_store_dwordx4 v[6:7], v[0:3], off
	ds_read_b32 v0, v83 offset:128
	ds_read_b32 v1, v83 offset:388
	ds_read_b32 v2, v83 offset:648
	ds_read_b32 v3, v83 offset:908
	ds_read_b32 v6, v83 offset:1168
	ds_read_b32 v7, v83 offset:1428
	ds_read_b32 v8, v83 offset:1688
	ds_read_b32 v9, v83 offset:1948
	s_waitcnt lgkmcnt(0)
	v_cvt_pk_bf16_f32 v0, v0, v1
	v_cvt_pk_bf16_f32 v1, v2, v3
	v_cvt_pk_bf16_f32 v2, v6, v7
	v_or_b32_e32 v6, s4, v87
	v_lshlrev_b32_e32 v6, 9, v6
	v_mov_b32_e32 v7, v69
	v_lshl_add_u64 v[6:7], v[4:5], 0, v[6:7]
	v_cvt_pk_bf16_f32 v3, v8, v9
	global_store_dwordx4 v[6:7], v[0:3], off
	ds_read_b32 v0, v83 offset:160
	ds_read_b32 v1, v83 offset:420
	ds_read_b32 v2, v83 offset:680
	ds_read_b32 v3, v83 offset:940
	ds_read_b32 v6, v83 offset:1200
	ds_read_b32 v7, v83 offset:1460
	ds_read_b32 v8, v83 offset:1720
	ds_read_b32 v9, v83 offset:1980
	s_waitcnt lgkmcnt(0)
	v_cvt_pk_bf16_f32 v0, v0, v1
	v_cvt_pk_bf16_f32 v1, v2, v3
	v_cvt_pk_bf16_f32 v2, v6, v7
	v_or_b32_e32 v6, s4, v88
	v_lshlrev_b32_e32 v6, 9, v6
	v_mov_b32_e32 v7, v69
	v_lshl_add_u64 v[6:7], v[4:5], 0, v[6:7]
	v_cvt_pk_bf16_f32 v3, v8, v9
	global_store_dwordx4 v[6:7], v[0:3], off
	ds_read_b32 v0, v83 offset:192
	ds_read_b32 v1, v83 offset:452
	ds_read_b32 v2, v83 offset:712
	ds_read_b32 v3, v83 offset:972
	ds_read_b32 v6, v83 offset:1232
	ds_read_b32 v7, v83 offset:1492
	ds_read_b32 v8, v83 offset:1752
	ds_read_b32 v9, v83 offset:2012
	s_waitcnt lgkmcnt(0)
	v_cvt_pk_bf16_f32 v0, v0, v1
	v_cvt_pk_bf16_f32 v1, v2, v3
	v_cvt_pk_bf16_f32 v2, v6, v7
	v_or_b32_e32 v6, s4, v89
	v_lshlrev_b32_e32 v6, 9, v6
	v_mov_b32_e32 v7, v69
	v_lshl_add_u64 v[6:7], v[4:5], 0, v[6:7]
	v_cvt_pk_bf16_f32 v3, v8, v9
	global_store_dwordx4 v[6:7], v[0:3], off
	ds_read_b32 v0, v83 offset:224
	ds_read_b32 v1, v83 offset:484
	ds_read_b32 v2, v83 offset:744
	ds_read_b32 v3, v83 offset:1004
	ds_read_b32 v6, v83 offset:1264
	ds_read_b32 v7, v83 offset:1524
	ds_read_b32 v8, v83 offset:1784
	ds_read_b32 v9, v83 offset:2044
	s_waitcnt lgkmcnt(0)
	v_cvt_pk_bf16_f32 v0, v0, v1
	v_cvt_pk_bf16_f32 v1, v2, v3
	v_cvt_pk_bf16_f32 v2, v6, v7
	v_or_b32_e32 v6, s4, v90
	v_lshlrev_b32_e32 v6, 9, v6
	v_mov_b32_e32 v7, v69
	v_lshl_add_u64 v[4:5], v[4:5], 0, v[6:7]
	v_cvt_pk_bf16_f32 v3, v8, v9
	global_store_dwordx4 v[4:5], v[0:3], off
	s_waitcnt lgkmcnt(0)
	s_mov_b64 s[4:5], 0

; #define LDS_WAIT() asm volatile("s_waitcnt lgkmcnt(0)" ::: "memory")
; __device__ __forceinline__ unsigned pk2(float lo, float hi) { unsigned r; asm("v_cvt_pk_bf16_f32 %0, %1, %2" : "=v"(r) : "v"(lo), "v"(hi)); return r; }
; __device__ __forceinline__ unsigned f2bf(float f) { return pk2(f, 0.f) & 0xffffu; }
; __device__ __forceinline__ void p0_transpose_item(const float* W, int K, int N, bf16* WT, float* scr, int item, int lane, const float* scale, const float* cb, float* c1, float* c2) {
;     ...
;     for (int i = 0; i < 16; ++i) { const int kk = 4 * i + lr; f32x4 w = v[i]; if (scale) w = w * scale[k0 + kk]; float* d = scr + kk * 65 + lc; d[0] = w[0]; d[1] = w[1]; d[2] = w[2]; d[3] = w[3]; }
;     LDS_WAIT(); asm volatile("" ::: "memory");
;     const int c = lane & 7;
; #pragma unroll
;     for (int j = 0; j < 8; ++j) { const int n = (lane >> 3) + 8 * j; const float* sp = scr + (8 * c) * 65 + n;
;         v4u o; o.x = pk2(sp[0 * 65], sp[1 * 65]); o.y = pk2(sp[2 * 65], sp[3 * 65]); o.z = pk2(sp[4 * 65], sp[5 * 65]); o.w = pk2(sp[6 * 65], sp[7 * 65]);
;         *(v4u*)(WT + (size_t)(n0 + n) * K + k0 + 8 * c) = o; }
;     if (c1) { float a1 = 0.f, a2 = 0.f;
;         for (int kk = 0; kk < 64; ++kk) { a1 += __uint_as_float(f2bf(scr[kk * 65 + lane]) << 16); a2 += cb[k0 + kk] * W[(size_t)(k0 + kk) * N + n0 + lane]; }
.LBB0_192:
	v_add_u32_e32 v0, 0x34d0, v122
	ds_write2_b32 v0, v14, v15 offset1:1
	v_add_u32_e32 v0, 0x34d8, v122
	ds_write2_b32 v0, v12, v13 offset1:1
	v_add_u32_e32 v0, 0x38e0, v122
	ds_write2_b32 v0, v8, v9 offset1:1
	v_add_u32_e32 v0, 0x38e8, v122
	ds_write2_b32 v0, v10, v11 offset1:1
	s_lshl_b64 s[4:5], s[2:3], 22
	s_waitcnt lgkmcnt(0)
	s_lshl_b64 s[4:5], s[4:5], 1
	s_add_u32 s3, s28, s4
	ds_read_b32 v0, v83
	ds_read_b32 v1, v83 offset:260
	ds_read_b32 v2, v83 offset:520
	ds_read_b32 v3, v83 offset:780
	ds_read_b32 v6, v83 offset:1040
	ds_read_b32 v7, v83 offset:1300
	ds_read_b32 v8, v83 offset:1560
	ds_read_b32 v9, v83 offset:1820
	s_addc_u32 s5, s29, s5
	s_lshl_b32 s4, s65, 1
	s_add_u32 s4, s3, s4
	s_addc_u32 s5, s5, 0
	v_mov_b32_e32 v75, v69
	s_waitcnt lgkmcnt(0)
	v_cvt_pk_bf16_f32 v0, v0, v1
	v_cvt_pk_bf16_f32 v1, v2, v3
	v_cvt_pk_bf16_f32 v2, v6, v7
	v_or_b32_e32 v6, s66, v82
	v_lshl_add_u64 v[4:5], s[4:5], 0, v[74:75]
	v_lshlrev_b32_e32 v6, 12, v6
	v_mov_b32_e32 v7, v69
	v_lshl_add_u64 v[6:7], v[4:5], 0, v[6:7]
	v_cvt_pk_bf16_f32 v3, v8, v9
	global_store_dwordx4 v[6:7], v[0:3], off
	ds_read_b32 v0, v83 offset:32
	ds_read_b32 v1, v83 offset:292
	ds_read_b32 v2, v83 offset:552
	ds_read_b32 v3, v83 offset:812
	ds_read_b32 v6, v83 offset:1072
	ds_read_b32 v7, v83 offset:1332
	ds_read_b32 v8, v83 offset:1592
	ds_read_b32 v9, v83 offset:1852
	s_waitcnt lgkmcnt(0)
	v_cvt_pk_bf16_f32 v0, v0, v1
	v_cvt_pk_bf16_f32 v1, v2, v3
	v_cvt_pk_bf16_f32 v2, v6, v7
	v_or_b32_e32 v6, s66, v84
	v_lshlrev_b32_e32 v6, 12, v6
	v_mov_b32_e32 v7, v69
	v_lshl_add_u64 v[6:7], v[4:5], 0, v[6:7]
	v_cvt_pk_bf16_f32 v3, v8, v9
	global_store_dwordx4 v[6:7], v[0:3], off
	ds_read_b32 v0, v83 offset:64
	ds_read_b32 v1, v83 offset:324
	ds_read_b32 v2, v83 offset:584
	ds_read_b32 v3, v83 offset:844
	ds_read_b32 v6, v83 offset:1104
	ds_read_b32 v7, v83 offset:1364
	ds_read_b32 v8, v83 offset:1624
	ds_read_b32 v9, v83 offset:1884
	s_waitcnt lgkmcnt(0)
	v_cvt_pk_bf16_f32 v0, v0, v1
	v_cvt_pk_bf16_f32 v1, v2, v3
	v_cvt_pk_bf16_f32 v2, v6, v7
	v_or_b32_e32 v6, s66, v85
	v_lshlrev_b32_e32 v6, 12, v6
	v_mov_b32_e32 v7, v69
	v_lshl_add_u64 v[6:7], v[4:5], 0, v[6:7]
	v_cvt_pk_bf16_f32 v3, v8, v9
	global_store_dwordx4 v[6:7], v[0:3], off
	ds_read_b32 v0, v83 offset:96
	ds_read_b32 v1, v83 offset:356
	ds_read_b32 v2, v83 offset:616
	ds_read_b32 v3, v83 offset:876
	ds_read_b32 v6, v83 offset:1136
	ds_read_b32 v7, v83 offset:1396
	ds_read_b32 v8, v83 offset:1656
	ds_read_b32 v9, v83 offset:1916
	s_waitcnt lgkmcnt(0)
	v_cvt_pk_bf16_f32 v0, v0, v1
	v_cvt_pk_bf16_f32 v1, v2, v3
	v_cvt_pk_bf16_f32 v2, v6, v7
	v_or_b32_e32 v6, s66, v86
	v_lshlrev_b32_e32 v6, 12, v6
	v_mov_b32_e32 v7, v69
	v_lshl_add_u64 v[6:7], v[4:5], 0, v[6:7]
	v_cvt_pk_bf16_f32 v3, v8, v9
	global_store_dwordx4 v[6:7], v[0:3], off
	ds_read_b32 v0, v83 offset:128
	ds_read_b32 v1, v83 offset:388
	ds_read_b32 v2, v83 offset:648
	ds_read_b32 v3, v83 offset:908
	ds_read_b32 v6, v83 offset:1168
	ds_read_b32 v7, v83 offset:1428
	ds_read_b32 v8, v83 offset:1688
	ds_read_b32 v9, v83 offset:1948
	s_waitcnt lgkmcnt(0)
	v_cvt_pk_bf16_f32 v0, v0, v1
	v_cvt_pk_bf16_f32 v1, v2, v3
	v_cvt_pk_bf16_f32 v2, v6, v7
	v_or_b32_e32 v6, s66, v87
	v_lshlrev_b32_e32 v6, 12, v6
	v_mov_b32_e32 v7, v69
	v_lshl_add_u64 v[6:7], v[4:5], 0, v[6:7]
	v_cvt_pk_bf16_f32 v3, v8, v9
	global_store_dwordx4 v[6:7], v[0:3], off
	ds_read_b32 v0, v83 offset:160
	ds_read_b32 v1, v83 offset:420
	ds_read_b32 v2, v83 offset:680
	ds_read_b32 v3, v83 offset:940
	ds_read_b32 v6, v83 offset:1200
	ds_read_b32 v7, v83 offset:1460
	ds_read_b32 v8, v83 offset:1720
	ds_read_b32 v9, v83 offset:1980
	s_waitcnt lgkmcnt(0)
	v_cvt_pk_bf16_f32 v0, v0, v1
	v_cvt_pk_bf16_f32 v1, v2, v3
	v_cvt_pk_bf16_f32 v2, v6, v7
	v_or_b32_e32 v6, s66, v88
	v_lshlrev_b32_e32 v6, 12, v6
	v_mov_b32_e32 v7, v69
	v_lshl_add_u64 v[6:7], v[4:5], 0, v[6:7]
	v_cvt_pk_bf16_f32 v3, v8, v9
	global_store_dwordx4 v[6:7], v[0:3], off
	ds_read_b32 v0, v83 offset:192
	ds_read_b32 v1, v83 offset:452
	ds_read_b32 v2, v83 offset:712
	ds_read_b32 v3, v83 offset:972
	ds_read_b32 v6, v83 offset:1232
	ds_read_b32 v7, v83 offset:1492
	ds_read_b32 v8, v83 offset:1752
	ds_read_b32 v9, v83 offset:2012
	s_waitcnt lgkmcnt(0)
	v_cvt_pk_bf16_f32 v0, v0, v1
	v_cvt_pk_bf16_f32 v1, v2, v3
	v_cvt_pk_bf16_f32 v2, v6, v7
	v_or_b32_e32 v6, s66, v89
	v_lshlrev_b32_e32 v6, 12, v6
	v_mov_b32_e32 v7, v69
	v_lshl_add_u64 v[6:7], v[4:5], 0, v[6:7]
	v_cvt_pk_bf16_f32 v3, v8, v9
	global_store_dwordx4 v[6:7], v[0:3], off
	s_lshl_b32 s3, s64, 13
	ds_read_b32 v0, v83 offset:224
	ds_read_b32 v1, v83 offset:484
	ds_read_b32 v2, v83 offset:744
	ds_read_b32 v3, v83 offset:1004
	ds_read_b32 v6, v83 offset:1264
	ds_read_b32 v7, v83 offset:1524
	ds_read_b32 v8, v83 offset:1784
	ds_read_b32 v9, v83 offset:2044
	s_and_b32 s3, s3, 0x3ff80000
	s_add_u32 s3, s8, s3
	s_addc_u32 s5, s9, 0
	s_and_b32 s4, s62, 31
	s_waitcnt lgkmcnt(0)
	v_cvt_pk_bf16_f32 v0, v0, v1
	v_cvt_pk_bf16_f32 v1, v2, v3
	v_cvt_pk_bf16_f32 v2, v6, v7
	v_or_b32_e32 v6, s66, v90
	s_lshl_b32 s4, s4, 8
	v_readlane_b32 s68, v253, 18
	v_lshlrev_b32_e32 v6, 12, v6
	v_mov_b32_e32 v7, v69
	s_or_b32 s4, s3, s4
	s_lshl_b32 s3, s65, 2
	v_readlane_b32 s80, v253, 30
	v_lshl_add_u64 v[4:5], v[4:5], 0, v[6:7]
	v_readlane_b32 s81, v253, 31
	s_add_u32 s3, s80, s3
	v_cvt_pk_bf16_f32 v3, v8, v9
	global_store_dwordx4 v[4:5], v[0:3], off
	s_addc_u32 s10, s81, 0
	v_mov_b32_e32 v4, v91
	v_lshl_add_u64 v[0:1], v[70:71], 0, s[4:5]
	s_lshl_b32 s4, s64, 2
	s_and_b32 s4, s4, 0x7ff00
	s_add_u32 s11, s80, s4
	v_mov_b32_e32 v2, 0
	s_addc_u32 s12, s81, 0
	s_mov_b64 s[4:5], 0
	v_mov_b32_e32 v3, v2
	v_readlane_b32 s69, v253, 19
	v_readlane_b32 s70, v253, 20
	v_readlane_b32 s71, v253, 21
	v_readlane_b32 s72, v253, 22
	v_readlane_b32 s73, v253, 23
	v_readlane_b32 s74, v253, 24
	v_readlane_b32 s75, v253, 25
	v_readlane_b32 s76, v253, 26
	v_readlane_b32 s77, v253, 27
	v_readlane_b32 s78, v253, 28
	v_readlane_b32 s79, v253, 29
	v_readlane_b32 s82, v253, 32
	v_readlane_b32 s83, v253, 33
; #define LDS_WAIT() asm volatile("s_waitcnt lgkmcnt(0)" ::: "memory")
; __device__ __forceinline__ unsigned f2bf(float f) { return pk2(f, 0.f) & 0xffffu; }
; __device__ __forceinline__ void p0_transpose_item(const float* W, int K, int N, bf16* WT, float* scr, int item, int lane, const float* scale, const float* cb, float* c1, float* c2) {
;     ...
;     if (c1) { float a1 = 0.f, a2 = 0.f;
;         for (int kk = 0; kk < 64; ++kk) { a1 += __uint_as_float(f2bf(scr[kk * 65 + lane]) << 16); a2 += cb[k0 + kk] * W[(size_t)(k0 + kk) * N + n0 + lane]; }
;         atomicAdd(c1 + n0 + lane, a1); atomicAdd(c2 + n0 + lane, a2); }
;     LDS_WAIT(); asm volatile("" ::: "memory");
.LBB0_193:
	v_lshl_add_u64 v[6:7], v[0:1], 0, s[4:5]
	s_movk_i32 s13, 0x2000
	v_add_co_u32_e32 v8, vcc, s13, v6
	s_movk_i32 s13, 0x4000
	s_nop 0
	v_addc_co_u32_e32 v9, vcc, 0, v7, vcc
	v_add_co_u32_e32 v10, vcc, s13, v6
	s_movk_i32 s13, 0x6000
	s_nop 0
	v_addc_co_u32_e32 v11, vcc, 0, v7, vcc
	v_add_co_u32_e32 v12, vcc, s13, v6
	s_mov_b32 s13, 0xa000
	s_nop 0
	v_addc_co_u32_e32 v13, vcc, 0, v7, vcc
	v_add_co_u32_e32 v14, vcc, s39, v6
	s_add_u32 s8, s11, s6
	s_nop 0
	v_addc_co_u32_e32 v15, vcc, 0, v7, vcc
	v_add_co_u32_e32 v16, vcc, s13, v6
	s_addc_u32 s9, s12, s7
	s_nop 0
	v_addc_co_u32_e32 v17, vcc, 0, v7, vcc
	s_mov_b32 s13, 0xc000
	global_load_dword v5, v[6:7], off
	v_add_co_u32_e32 v18, vcc, s13, v6
	global_load_dword v22, v69, s[8:9]
	s_nop 0
	v_addc_co_u32_e32 v19, vcc, 0, v7, vcc
	s_mov_b32 s13, 0xe000
	s_add_u32 s8, s3, s6
	v_add_co_u32_e32 v20, vcc, s13, v6
	s_addc_u32 s9, s10, s7
	s_nop 0
	v_addc_co_u32_e32 v21, vcc, 0, v7, vcc
	global_load_dword v24, v[8:9], off
	global_load_dword v26, v[10:11], off
	global_load_dword v28, v[12:13], off
	global_load_dword v29, v[14:15], off
	global_load_dword v30, v[16:17], off
	global_load_dword v31, v[18:19], off
	global_load_dwordx4 v[6:9], v69, s[8:9] offset:4
	s_nop 0
	global_load_dwordx3 v[10:12], v69, s[8:9] offset:20
	global_load_dword v32, v[20:21], off
	ds_read2_b32 v[14:15], v4 offset1:65
	ds_read2_b32 v[16:17], v4 offset0:130 offset1:195
	v_add_u32_e32 v13, 0x400, v4
	ds_read2_b32 v[18:19], v13 offset0:4 offset1:69
	ds_read2_b32 v[20:21], v13 offset0:134 offset1:199
	s_waitcnt lgkmcnt(0)
	v_cvt_pk_bf16_f32 v13, v14, v69
	v_cvt_pk_bf16_f32 v14, v15, v69
	v_cvt_pk_bf16_f32 v16, v16, v69
	v_cvt_pk_bf16_f32 v25, v17, v69
	s_nop 0
	v_lshlrev_b32_e32 v15, 16, v13
	v_lshlrev_b32_e32 v17, 16, v14
	v_cvt_pk_bf16_f32 v14, v19, v69
	v_lshlrev_b32_e32 v23, 16, v16
	v_cvt_pk_bf16_f32 v13, v18, v69
	v_cvt_pk_bf16_f32 v16, v20, v69
	v_cvt_pk_bf16_f32 v18, v21, v69
	v_lshlrev_b32_e32 v21, 16, v14
	v_lshlrev_b32_e32 v27, 16, v16
	s_add_u32 s4, s4, 0x10000
	s_addc_u32 s5, s5, 0
	v_lshlrev_b32_e32 v25, 16, v25
	s_add_u32 s3, s3, 32
	v_lshlrev_b32_e32 v19, 16, v13
	v_lshlrev_b32_e32 v13, 16, v18
	s_addc_u32 s10, s10, 0
	s_add_u32 s11, s11, 32
	s_addc_u32 s12, s12, 0
	v_add_u32_e32 v4, 0x820, v4
	s_cmp_lg_u32 s4, 0x80000
	s_waitcnt vmcnt(0)
	v_mul_f32_e32 v14, v22, v5
	v_pk_add_f32 v[2:3], v[2:3], v[14:15]
	v_mul_f32_e32 v16, v6, v24
	v_mul_f32_e32 v22, v7, v26
	v_pk_add_f32 v[2:3], v[2:3], v[16:17]
	v_mul_f32_e32 v24, v8, v28
	v_pk_add_f32 v[2:3], v[2:3], v[22:23]
	v_mul_f32_e32 v18, v9, v29
	v_pk_add_f32 v[2:3], v[2:3], v[24:25]
	v_mul_f32_e32 v20, v10, v30
	v_pk_add_f32 v[2:3], v[2:3], v[18:19]
	v_mul_f32_e32 v26, v11, v31
	v_pk_add_f32 v[2:3], v[2:3], v[20:21]
	v_mul_f32_e32 v12, v12, v32
	v_pk_add_f32 v[2:3], v[2:3], v[26:27]
	s_nop 0
	v_pk_add_f32 v[2:3], v[2:3], v[12:13]
	s_cbranch_scc1 .LBB0_193
	s_add_u32 s3, s34, s6
	s_addc_u32 s5, s35, s7
	s_add_u32 s6, s37, s6
	s_addc_u32 s7, s38, s7
	s_add_u32 s4, s3, s63
	s_addc_u32 s5, s5, 0
	v_mov_b32_e32 v73, v69
	v_lshl_add_u64 v[0:1], s[4:5], 0, v[72:73]
	s_add_u32 s4, s6, s63
	s_addc_u32 s5, s7, 0
	global_atomic_add_f32 v[0:1], v3, off
	v_lshl_add_u64 v[0:1], s[4:5], 0, v[72:73]
	global_atomic_add_f32 v[0:1], v2, off
	s_waitcnt lgkmcnt(0)

; __device__ __forceinline__ void p0_transpose_item(const float* W, int K, int N, bf16* WT, float* scr, int item, int lane, const float* scale, const float* cb, float* c1, float* c2) {
;     const int nblk = N / 64, kb = item / nblk, nb = item % nblk, k0 = 64 * kb, n0 = 64 * nb;
;     const int lr = lane >> 4, lc = (lane & 15) * 4;
;     f32x4 v[16];
; #pragma unroll
;     for (int i = 0; i < 16; ++i) v[i] = *(const f32x4*)(W + (size_t)(k0 + 4 * i + lr) * N + n0 + lc);
; #pragma unroll
;     for (int i = 0; i < 16; ++i) { const int kk = 4 * i + lr; f32x4 w = v[i]; if (scale) w = w * scale[k0 + kk]; float* d = scr + kk * 65 + lc; d[0] = w[0]; d[1] = w[1]; d[2] = w[2]; d[3] = w[3]; }
.LBB0_196:
	s_andn2_b64 vcc, exec, s[4:5]
	s_cbranch_vccnz .LBB0_198
	s_ashr_i32 s3, s2, 31
	v_readlane_b32 s64, v253, 18
	s_lshl_b64 s[4:5], s[2:3], 24
	v_readlane_b32 s72, v253, 26
	v_readlane_b32 s73, v253, 27
	s_add_u32 s6, s72, s4
	s_addc_u32 s7, s73, s5
	s_lshl_b64 s[4:5], s[2:3], 23
	s_add_u32 s8, s26, s4
	s_addc_u32 s9, s27, s5
	s_lshl_b32 s3, s62, 1
	s_add_i32 s3, s3, 0x1e200
	s_and_b32 s10, s3, 0x1ffc0
	s_lshl_b32 s3, s62, 6
	s_and_b32 s3, s3, 0x7c0
	s_lshl_b32 s4, s3, 2
	s_add_u32 s4, s6, s4
	v_or_b32_e32 v2, s10, v80
	s_addc_u32 s5, s7, 0
	v_lshl_add_u64 v[0:1], s[4:5], 0, v[68:69]
	v_lshlrev_b32_e32 v2, 13, v2
	v_mov_b32_e32 v3, v69
	v_lshl_add_u64 v[60:61], v[0:1], 0, v[2:3]
	v_add_co_u32_e32 v4, vcc, s39, v60
	s_lshl_b32 s4, s10, 1
	s_nop 0
	v_addc_co_u32_e32 v5, vcc, 0, v61, vcc
	v_add_co_u32_e32 v8, vcc, s40, v60
	global_load_dwordx4 v[0:3], v[60:61], off
	s_nop 0
	global_load_dwordx4 v[4:7], v[4:5], off
	v_addc_co_u32_e32 v9, vcc, 0, v61, vcc
	v_add_co_u32_e32 v12, vcc, s41, v60
	s_add_u32 s4, s8, s4
	s_nop 0
	v_addc_co_u32_e32 v13, vcc, 0, v61, vcc
	v_add_co_u32_e32 v16, vcc, s42, v60
	global_load_dwordx4 v[8:11], v[8:9], off
	s_nop 0
	global_load_dwordx4 v[12:15], v[12:13], off
	v_addc_co_u32_e32 v17, vcc, 0, v61, vcc
	v_add_co_u32_e32 v20, vcc, s43, v60
	s_addc_u32 s5, s9, 0
	s_nop 0
	v_addc_co_u32_e32 v21, vcc, 0, v61, vcc
	v_add_co_u32_e32 v24, vcc, s44, v60
	global_load_dwordx4 v[16:19], v[16:17], off
	s_nop 0
	global_load_dwordx4 v[20:23], v[20:21], off
	v_addc_co_u32_e32 v25, vcc, 0, v61, vcc
	v_add_co_u32_e32 v28, vcc, s45, v60
	v_mov_b32_e32 v75, v69
	s_nop 0
	v_addc_co_u32_e32 v29, vcc, 0, v61, vcc
	v_add_co_u32_e32 v32, vcc, s46, v60
	global_load_dwordx4 v[24:27], v[24:25], off
	s_nop 0
	global_load_dwordx4 v[28:31], v[28:29], off
	v_addc_co_u32_e32 v33, vcc, 0, v61, vcc
	v_add_co_u32_e32 v36, vcc, s47, v60
	v_readlane_b32 s65, v253, 19
	s_nop 0
	v_addc_co_u32_e32 v37, vcc, 0, v61, vcc
	v_add_co_u32_e32 v40, vcc, s48, v60
	global_load_dwordx4 v[32:35], v[32:33], off
	s_nop 0
	global_load_dwordx4 v[36:39], v[36:37], off
	v_addc_co_u32_e32 v41, vcc, 0, v61, vcc
	v_add_co_u32_e32 v44, vcc, s49, v60
	v_readlane_b32 s66, v253, 20
	s_nop 0
	v_addc_co_u32_e32 v45, vcc, 0, v61, vcc
	v_add_co_u32_e32 v48, vcc, s50, v60
	global_load_dwordx4 v[40:43], v[40:41], off
	s_nop 0
	global_load_dwordx4 v[44:47], v[44:45], off
	v_addc_co_u32_e32 v49, vcc, 0, v61, vcc
	v_add_co_u32_e32 v52, vcc, s51, v60
	v_readlane_b32 s67, v253, 21
	s_nop 0
	v_addc_co_u32_e32 v53, vcc, 0, v61, vcc
	global_load_dwordx4 v[48:51], v[48:49], off
	s_nop 0
	global_load_dwordx4 v[52:55], v[52:53], off
	v_add_co_u32_e32 v56, vcc, s52, v60
	v_readlane_b32 s68, v253, 22
	s_nop 0
	v_addc_co_u32_e32 v57, vcc, 0, v61, vcc
	global_load_dwordx4 v[56:59], v[56:57], off
	v_add_co_u32_e32 v60, vcc, s53, v60
	v_readlane_b32 s69, v253, 23
	s_nop 0
	v_addc_co_u32_e32 v61, vcc, 0, v61, vcc
	global_load_dwordx4 v[60:63], v[60:61], off
	v_readlane_b32 s70, v253, 24
	v_readlane_b32 s71, v253, 25
	v_readlane_b32 s74, v253, 28
	v_readlane_b32 s75, v253, 29
	v_readlane_b32 s76, v253, 30
	v_readlane_b32 s77, v253, 31
	v_readlane_b32 s78, v253, 32
	v_readlane_b32 s79, v253, 33
	s_waitcnt vmcnt(0)
	ds_write2_b32 v81, v0, v1 offset1:1
	ds_write2_b32 v81, v2, v3 offset0:2 offset1:3
	ds_write2_b32 v92, v4, v5 offset1:1
	ds_write2_b32 v93, v6, v7 offset1:1
	ds_write2_b32 v94, v8, v9 offset1:1
	ds_write2_b32 v95, v10, v11 offset1:1
	ds_write2_b32 v96, v12, v13 offset1:1
	ds_write2_b32 v97, v14, v15 offset1:1
	ds_write2_b32 v98, v16, v17 offset1:1
	ds_write2_b32 v99, v18, v19 offset1:1
	ds_write2_b32 v100, v20, v21 offset1:1
	ds_write2_b32 v101, v22, v23 offset1:1
	ds_write2_b32 v102, v24, v25 offset1:1
	ds_write2_b32 v103, v26, v27 offset1:1
	ds_write2_b32 v104, v28, v29 offset1:1
	ds_write2_b32 v105, v30, v31 offset1:1
	ds_write2_b32 v106, v32, v33 offset1:1
	ds_write2_b32 v107, v34, v35 offset1:1
	ds_write2_b32 v108, v36, v37 offset1:1
	ds_write2_b32 v109, v38, v39 offset1:1
	ds_write2_b32 v110, v40, v41 offset1:1
	ds_write2_b32 v111, v42, v43 offset1:1
	ds_write2_b32 v112, v44, v45 offset1:1
	ds_write2_b32 v113, v46, v47 offset1:1
	ds_write2_b32 v114, v48, v49 offset1:1
	ds_write2_b32 v115, v50, v51 offset1:1
	ds_write2_b32 v116, v52, v53 offset1:1
	ds_write2_b32 v117, v54, v55 offset1:1
	ds_write2_b32 v118, v56, v57 offset1:1
	ds_write2_b32 v119, v58, v59 offset1:1
	ds_write2_b32 v120, v60, v61 offset1:1
	ds_write2_b32 v121, v62, v63 offset1:1
	s_waitcnt lgkmcnt(0)
; #define LDS_WAIT() asm volatile("s_waitcnt lgkmcnt(0)" ::: "memory")
; __device__ __forceinline__ unsigned pk2(float lo, float hi) { unsigned r; asm("v_cvt_pk_bf16_f32 %0, %1, %2" : "=v"(r) : "v"(lo), "v"(hi)); return r; }
; __device__ __forceinline__ void p0_transpose_item(const float* W, int K, int N, bf16* WT, float* scr, int item, int lane, const float* scale, const float* cb, float* c1, float* c2) {
;     ...
;     LDS_WAIT(); asm volatile("" ::: "memory");
;     const int c = lane & 7;
; #pragma unroll
;     for (int j = 0; j < 8; ++j) { const int n = (lane >> 3) + 8 * j; const float* sp = scr + (8 * c) * 65 + n;
;         v4u o; o.x = pk2(sp[0 * 65], sp[1 * 65]); o.y = pk2(sp[2 * 65], sp[3 * 65]); o.z = pk2(sp[4 * 65], sp[5 * 65]); o.w = pk2(sp[6 * 65], sp[7 * 65]);
;         *(v4u*)(WT + (size_t)(n0 + n) * K + k0 + 8 * c) = o; }
	ds_read_b32 v0, v83
	ds_read_b32 v1, v83 offset:260
	ds_read_b32 v2, v83 offset:520
	ds_read_b32 v3, v83 offset:780
	ds_read_b32 v6, v83 offset:1040
	ds_read_b32 v7, v83 offset:1300
	ds_read_b32 v8, v83 offset:1560
	ds_read_b32 v9, v83 offset:1820
	s_waitcnt lgkmcnt(0)
	v_cvt_pk_bf16_f32 v0, v0, v1
	v_cvt_pk_bf16_f32 v1, v2, v3
	v_cvt_pk_bf16_f32 v2, v6, v7
	v_or_b32_e32 v6, s3, v82
	v_lshl_add_u64 v[4:5], s[4:5], 0, v[74:75]
	v_lshlrev_b32_e32 v6, 12, v6
	v_mov_b32_e32 v7, v69
	v_lshl_add_u64 v[6:7], v[4:5], 0, v[6:7]
	v_cvt_pk_bf16_f32 v3, v8, v9
	global_store_dwordx4 v[6:7], v[0:3], off
	ds_read_b32 v0, v83 offset:32
	ds_read_b32 v1, v83 offset:292
	ds_read_b32 v2, v83 offset:552
	ds_read_b32 v3, v83 offset:812
	ds_read_b32 v6, v83 offset:1072
	ds_read_b32 v7, v83 offset:1332
	ds_read_b32 v8, v83 offset:1592
	ds_read_b32 v9, v83 offset:1852
	s_waitcnt lgkmcnt(0)
	v_cvt_pk_bf16_f32 v0, v0, v1
	v_cvt_pk_bf16_f32 v1, v2, v3
	v_cvt_pk_bf16_f32 v2, v6, v7
	v_or_b32_e32 v6, s3, v84
	v_lshlrev_b32_e32 v6, 12, v6
	v_mov_b32_e32 v7, v69
	v_lshl_add_u64 v[6:7], v[4:5], 0, v[6:7]
	v_cvt_pk_bf16_f32 v3, v8, v9
	global_store_dwordx4 v[6:7], v[0:3], off
	ds_read_b32 v0, v83 offset:64
	ds_read_b32 v1, v83 offset:324
	ds_read_b32 v2, v83 offset:584
	ds_read_b32 v3, v83 offset:844
	ds_read_b32 v6, v83 offset:1104
	ds_read_b32 v7, v83 offset:1364
	ds_read_b32 v8, v83 offset:1624
	ds_read_b32 v9, v83 offset:1884
	s_waitcnt lgkmcnt(0)
	v_cvt_pk_bf16_f32 v0, v0, v1
	v_cvt_pk_bf16_f32 v1, v2, v3
	v_cvt_pk_bf16_f32 v2, v6, v7
	v_or_b32_e32 v6, s3, v85
	v_lshlrev_b32_e32 v6, 12, v6
	v_mov_b32_e32 v7, v69
	v_lshl_add_u64 v[6:7], v[4:5], 0, v[6:7]
	v_cvt_pk_bf16_f32 v3, v8, v9
	global_store_dwordx4 v[6:7], v[0:3], off
	ds_read_b32 v0, v83 offset:96
	ds_read_b32 v1, v83 offset:356
	ds_read_b32 v2, v83 offset:616
	ds_read_b32 v3, v83 offset:876
	ds_read_b32 v6, v83 offset:1136
	ds_read_b32 v7, v83 offset:1396
	ds_read_b32 v8, v83 offset:1656
	ds_read_b32 v9, v83 offset:1916
	s_waitcnt lgkmcnt(0)
	v_cvt_pk_bf16_f32 v0, v0, v1
	v_cvt_pk_bf16_f32 v1, v2, v3
	v_cvt_pk_bf16_f32 v2, v6, v7
	v_or_b32_e32 v6, s3, v86
	v_lshlrev_b32_e32 v6, 12, v6
	v_mov_b32_e32 v7, v69
	v_lshl_add_u64 v[6:7], v[4:5], 0, v[6:7]
	v_cvt_pk_bf16_f32 v3, v8, v9
	global_store_dwordx4 v[6:7], v[0:3], off
	ds_read_b32 v0, v83 offset:128
	ds_read_b32 v1, v83 offset:388
	ds_read_b32 v2, v83 offset:648
	ds_read_b32 v3, v83 offset:908
	ds_read_b32 v6, v83 offset:1168
	ds_read_b32 v7, v83 offset:1428
	ds_read_b32 v8, v83 offset:1688
	ds_read_b32 v9, v83 offset:1948
	s_waitcnt lgkmcnt(0)
	v_cvt_pk_bf16_f32 v0, v0, v1
	v_cvt_pk_bf16_f32 v1, v2, v3
	v_cvt_pk_bf16_f32 v2, v6, v7
	v_or_b32_e32 v6, s3, v87
	v_lshlrev_b32_e32 v6, 12, v6
	v_mov_b32_e32 v7, v69
	v_lshl_add_u64 v[6:7], v[4:5], 0, v[6:7]
	v_cvt_pk_bf16_f32 v3, v8, v9
	global_store_dwordx4 v[6:7], v[0:3], off
	ds_read_b32 v0, v83 offset:160
	ds_read_b32 v1, v83 offset:420
	ds_read_b32 v2, v83 offset:680
	ds_read_b32 v3, v83 offset:940
	ds_read_b32 v6, v83 offset:1200
	ds_read_b32 v7, v83 offset:1460
	ds_read_b32 v8, v83 offset:1720
	ds_read_b32 v9, v83 offset:1980
	s_waitcnt lgkmcnt(0)
	v_cvt_pk_bf16_f32 v0, v0, v1
	v_cvt_pk_bf16_f32 v1, v2, v3
	v_cvt_pk_bf16_f32 v2, v6, v7
	v_or_b32_e32 v6, s3, v88
	v_lshlrev_b32_e32 v6, 12, v6
	v_mov_b32_e32 v7, v69
	v_lshl_add_u64 v[6:7], v[4:5], 0, v[6:7]
	v_cvt_pk_bf16_f32 v3, v8, v9
	global_store_dwordx4 v[6:7], v[0:3], off
	ds_read_b32 v0, v83 offset:192
	ds_read_b32 v1, v83 offset:452
	ds_read_b32 v2, v83 offset:712
	ds_read_b32 v3, v83 offset:972
	ds_read_b32 v6, v83 offset:1232
	ds_read_b32 v7, v83 offset:1492
	ds_read_b32 v8, v83 offset:1752
	ds_read_b32 v9, v83 offset:2012
	s_waitcnt lgkmcnt(0)
	v_cvt_pk_bf16_f32 v0, v0, v1
	v_cvt_pk_bf16_f32 v1, v2, v3
	v_cvt_pk_bf16_f32 v2, v6, v7
	v_or_b32_e32 v6, s3, v89
	v_lshlrev_b32_e32 v6, 12, v6
	v_mov_b32_e32 v7, v69
	v_lshl_add_u64 v[6:7], v[4:5], 0, v[6:7]
	v_cvt_pk_bf16_f32 v3, v8, v9
	global_store_dwordx4 v[6:7], v[0:3], off
	ds_read_b32 v0, v83 offset:224
	ds_read_b32 v1, v83 offset:484
	ds_read_b32 v2, v83 offset:744
	ds_read_b32 v3, v83 offset:1004
	ds_read_b32 v6, v83 offset:1264
	ds_read_b32 v7, v83 offset:1524
	ds_read_b32 v8, v83 offset:1784
	ds_read_b32 v9, v83 offset:2044
	s_waitcnt lgkmcnt(0)
	v_cvt_pk_bf16_f32 v0, v0, v1
	v_cvt_pk_bf16_f32 v1, v2, v3
	v_cvt_pk_bf16_f32 v2, v6, v7
	v_or_b32_e32 v6, s3, v90
	v_lshlrev_b32_e32 v6, 12, v6
	v_mov_b32_e32 v7, v69
	v_lshl_add_u64 v[4:5], v[4:5], 0, v[6:7]
	v_cvt_pk_bf16_f32 v3, v8, v9
	global_store_dwordx4 v[4:5], v[0:3], off
	s_waitcnt lgkmcnt(0)

; __device__ __forceinline__ void p0_transpose_item(const float* W, int K, int N, bf16* WT, float* scr, int item, int lane, const float* scale, const float* cb, float* c1, float* c2) {
;     const int nblk = N / 64, kb = item / nblk, nb = item % nblk, k0 = 64 * kb, n0 = 64 * nb;
;     const int lr = lane >> 4, lc = (lane & 15) * 4;
;     f32x4 v[16];
; #pragma unroll
;     for (int i = 0; i < 16; ++i) v[i] = *(const f32x4*)(W + (size_t)(k0 + 4 * i + lr) * N + n0 + lc);
; #pragma unroll
;     for (int i = 0; i < 16; ++i) { const int kk = 4 * i + lr; f32x4 w = v[i]; if (scale) w = w * scale[k0 + kk]; float* d = scr + kk * 65 + lc; d[0] = w[0]; d[1] = w[1]; d[2] = w[2]; d[3] = w[3]; }
.LBB0_199:
	s_andn2_b64 vcc, exec, s[4:5]
	s_cbranch_vccnz .LBB0_162
	v_readlane_b32 s64, v253, 2
	s_mul_i32 s4, s2, 0x3c00000
	v_readlane_b32 s68, v253, 6
	s_mul_hi_i32 s3, s2, 0x3c00000
	v_readlane_b32 s69, v253, 7
	s_add_u32 s5, s68, s4
	s_addc_u32 s8, s69, s3
	s_mul_hi_i32 s3, s2, 0x1e00000
	s_mul_i32 s2, s2, 0x1e00000
	s_add_u32 s9, s24, s2
	s_mul_i32 s2, s62, 0xffff8889
	s_addc_u32 s10, s25, s3
	s_lshr_b32 s2, s2, 16
	s_add_i32 s2, s2, s62
	s_sext_i32_i16 s3, s2
	s_ashr_i32 s3, s3, 6
	s_bfe_u32 s2, s2, 0x1000f
	s_add_i32 s2, s3, s2
	s_sext_i32_i16 s3, s2
	s_mulk_i32 s2, 0x78
	s_sub_i32 s2, s62, s2
	s_sext_i32_i16 s2, s2
	s_lshl_b32 s2, s2, 6
	s_lshl_b32 s4, s3, 6
	s_ashr_i32 s3, s2, 31
	s_lshl_b64 s[6:7], s[2:3], 2
	v_or_b32_e32 v2, s4, v80
	s_add_u32 s6, s5, s6
	s_addc_u32 s7, s8, s7
	v_mul_i32_i24_e32 v2, 0x1e00, v2
	v_lshl_add_u64 v[0:1], s[6:7], 0, v[68:69]
	v_ashrrev_i32_e32 v3, 31, v2
	v_lshl_add_u64 v[60:61], v[2:3], 2, v[0:1]
	s_mov_b32 s3, 0x1e000
	v_add_co_u32_e32 v4, vcc, s3, v60
	s_mov_b32 s3, 0x3c000
	s_nop 0
	v_addc_co_u32_e32 v5, vcc, 0, v61, vcc
	v_add_co_u32_e32 v8, vcc, s3, v60
	s_mov_b32 s3, 0x5a000
	s_nop 0
	v_addc_co_u32_e32 v9, vcc, 0, v61, vcc
	v_add_co_u32_e32 v12, vcc, s3, v60
	s_mov_b32 s3, 0x96000
	s_nop 0
	v_addc_co_u32_e32 v13, vcc, 0, v61, vcc
	v_add_co_u32_e32 v16, vcc, s53, v60
	global_load_dwordx4 v[0:3], v[60:61], off
	s_nop 0
	global_load_dwordx4 v[4:7], v[4:5], off
	v_addc_co_u32_e32 v17, vcc, 0, v61, vcc
	v_add_co_u32_e32 v20, vcc, s3, v60
	s_mov_b32 s3, 0xb4000
	s_nop 0
	v_addc_co_u32_e32 v21, vcc, 0, v61, vcc
	v_add_co_u32_e32 v24, vcc, s3, v60
	s_mov_b32 s3, 0xd2000
	s_nop 0
	v_addc_co_u32_e32 v25, vcc, 0, v61, vcc
	v_add_co_u32_e32 v28, vcc, s3, v60
	global_load_dwordx4 v[8:11], v[8:9], off
	s_nop 0
	global_load_dwordx4 v[12:15], v[12:13], off
	v_addc_co_u32_e32 v29, vcc, 0, v61, vcc
	v_add_co_u32_e32 v32, vcc, s54, v60
	global_load_dwordx4 v[16:19], v[16:17], off
	s_nop 0
	global_load_dwordx4 v[20:23], v[20:21], off
	v_addc_co_u32_e32 v33, vcc, 0, v61, vcc
	v_add_co_u32_e32 v36, vcc, s55, v60
	global_load_dwordx4 v[24:27], v[24:25], off
	s_nop 0
	global_load_dwordx4 v[28:31], v[28:29], off
	v_addc_co_u32_e32 v37, vcc, 0, v61, vcc
	v_add_co_u32_e32 v40, vcc, s56, v60
	global_load_dwordx4 v[32:35], v[32:33], off
	s_nop 0
	global_load_dwordx4 v[36:39], v[36:37], off
	v_addc_co_u32_e32 v41, vcc, 0, v61, vcc
	v_add_co_u32_e32 v44, vcc, s57, v60
	s_ashr_i32 s5, s4, 31
	s_nop 0
	v_addc_co_u32_e32 v45, vcc, 0, v61, vcc
	v_add_co_u32_e32 v48, vcc, s58, v60
	global_load_dwordx4 v[40:43], v[40:41], off
	s_nop 0
	global_load_dwordx4 v[44:47], v[44:45], off
	v_addc_co_u32_e32 v49, vcc, 0, v61, vcc
	v_add_co_u32_e32 v52, vcc, s59, v60
	s_lshl_b64 s[4:5], s[4:5], 1
	s_nop 0
	v_addc_co_u32_e32 v53, vcc, 0, v61, vcc
	global_load_dwordx4 v[48:51], v[48:49], off
	s_nop 0
	global_load_dwordx4 v[52:55], v[52:53], off
	v_add_co_u32_e32 v56, vcc, s60, v60
	s_add_u32 s4, s9, s4
	s_nop 0
	v_addc_co_u32_e32 v57, vcc, 0, v61, vcc
	global_load_dwordx4 v[56:59], v[56:57], off
	v_add_co_u32_e32 v60, vcc, s61, v60
	s_addc_u32 s5, s10, s5
	s_nop 0
	v_addc_co_u32_e32 v61, vcc, 0, v61, vcc
	global_load_dwordx4 v[60:63], v[60:61], off
	v_mov_b32_e32 v75, v69
	v_readlane_b32 s65, v253, 3
	v_readlane_b32 s66, v253, 4
	v_readlane_b32 s67, v253, 5
	v_readlane_b32 s70, v253, 8
	v_readlane_b32 s71, v253, 9
	v_readlane_b32 s72, v253, 10
	v_readlane_b32 s73, v253, 11
	v_readlane_b32 s74, v253, 12
	v_readlane_b32 s75, v253, 13
	v_readlane_b32 s76, v253, 14
	v_readlane_b32 s77, v253, 15
	v_readlane_b32 s78, v253, 16
	v_readlane_b32 s79, v253, 17
	s_waitcnt vmcnt(0)
	ds_write2_b32 v81, v0, v1 offset1:1
	ds_write2_b32 v81, v2, v3 offset0:2 offset1:3
	ds_write2_b32 v92, v4, v5 offset1:1
	ds_write2_b32 v93, v6, v7 offset1:1
	ds_write2_b32 v94, v8, v9 offset1:1
	ds_write2_b32 v95, v10, v11 offset1:1
	ds_write2_b32 v96, v12, v13 offset1:1
	ds_write2_b32 v97, v14, v15 offset1:1
	ds_write2_b32 v98, v16, v17 offset1:1
	ds_write2_b32 v99, v18, v19 offset1:1
	ds_write2_b32 v100, v20, v21 offset1:1
	ds_write2_b32 v101, v22, v23 offset1:1
	ds_write2_b32 v102, v24, v25 offset1:1
	ds_write2_b32 v103, v26, v27 offset1:1
	ds_write2_b32 v104, v28, v29 offset1:1
	ds_write2_b32 v105, v30, v31 offset1:1
	ds_write2_b32 v106, v32, v33 offset1:1
	ds_write2_b32 v107, v34, v35 offset1:1
	ds_write2_b32 v108, v36, v37 offset1:1
	ds_write2_b32 v109, v38, v39 offset1:1
	ds_write2_b32 v110, v40, v41 offset1:1
	ds_write2_b32 v111, v42, v43 offset1:1
	ds_write2_b32 v112, v44, v45 offset1:1
	ds_write2_b32 v113, v46, v47 offset1:1
	ds_write2_b32 v114, v48, v49 offset1:1
	ds_write2_b32 v115, v50, v51 offset1:1
	ds_write2_b32 v116, v52, v53 offset1:1
	ds_write2_b32 v117, v54, v55 offset1:1
	ds_write2_b32 v118, v56, v57 offset1:1
	ds_write2_b32 v119, v58, v59 offset1:1
	ds_write2_b32 v120, v60, v61 offset1:1
	ds_write2_b32 v121, v62, v63 offset1:1
	s_waitcnt lgkmcnt(0)
; #define LDS_WAIT() asm volatile("s_waitcnt lgkmcnt(0)" ::: "memory")
; __device__ __forceinline__ unsigned pk2(float lo, float hi) { unsigned r; asm("v_cvt_pk_bf16_f32 %0, %1, %2" : "=v"(r) : "v"(lo), "v"(hi)); return r; }
; __device__ __forceinline__ void p0_transpose_item(const float* W, int K, int N, bf16* WT, float* scr, int item, int lane, const float* scale, const float* cb, float* c1, float* c2) {
;     ...
;     LDS_WAIT(); asm volatile("" ::: "memory");
;     const int c = lane & 7;
; #pragma unroll
;     for (int j = 0; j < 8; ++j) { const int n = (lane >> 3) + 8 * j; const float* sp = scr + (8 * c) * 65 + n;
;         v4u o; o.x = pk2(sp[0 * 65], sp[1 * 65]); o.y = pk2(sp[2 * 65], sp[3 * 65]); o.z = pk2(sp[4 * 65], sp[5 * 65]); o.w = pk2(sp[6 * 65], sp[7 * 65]);
;         *(v4u*)(WT + (size_t)(n0 + n) * K + k0 + 8 * c) = o; }
	ds_read_b32 v0, v83
	ds_read_b32 v1, v83 offset:260
	ds_read_b32 v2, v83 offset:520
	ds_read_b32 v3, v83 offset:780
	ds_read_b32 v6, v83 offset:1040
	ds_read_b32 v7, v83 offset:1300
	ds_read_b32 v8, v83 offset:1560
	ds_read_b32 v9, v83 offset:1820
	s_waitcnt lgkmcnt(0)
	v_cvt_pk_bf16_f32 v0, v0, v1
	v_cvt_pk_bf16_f32 v1, v2, v3
	v_cvt_pk_bf16_f32 v2, v6, v7
	v_or_b32_e32 v6, s2, v82
	v_ashrrev_i32_e32 v7, 31, v6
	v_lshl_add_u64 v[4:5], s[4:5], 0, v[74:75]
	v_lshlrev_b64 v[6:7], 12, v[6:7]
	v_lshl_add_u64 v[6:7], v[4:5], 0, v[6:7]
	v_cvt_pk_bf16_f32 v3, v8, v9
	global_store_dwordx4 v[6:7], v[0:3], off
	ds_read_b32 v0, v83 offset:32
	ds_read_b32 v1, v83 offset:292
	ds_read_b32 v2, v83 offset:552
	ds_read_b32 v3, v83 offset:812
	ds_read_b32 v6, v83 offset:1072
	ds_read_b32 v7, v83 offset:1332
	ds_read_b32 v8, v83 offset:1592
	ds_read_b32 v9, v83 offset:1852
	s_waitcnt lgkmcnt(0)
	v_cvt_pk_bf16_f32 v0, v0, v1
	v_cvt_pk_bf16_f32 v1, v2, v3
	v_cvt_pk_bf16_f32 v2, v6, v7
	v_or_b32_e32 v6, s2, v84
	v_ashrrev_i32_e32 v7, 31, v6
	v_lshlrev_b64 v[6:7], 12, v[6:7]
	v_lshl_add_u64 v[6:7], v[4:5], 0, v[6:7]
	v_cvt_pk_bf16_f32 v3, v8, v9
	global_store_dwordx4 v[6:7], v[0:3], off
	ds_read_b32 v0, v83 offset:64
	ds_read_b32 v1, v83 offset:324
	ds_read_b32 v2, v83 offset:584
	ds_read_b32 v3, v83 offset:844
	ds_read_b32 v6, v83 offset:1104
	ds_read_b32 v7, v83 offset:1364
	ds_read_b32 v8, v83 offset:1624
	ds_read_b32 v9, v83 offset:1884
	s_waitcnt lgkmcnt(0)
	v_cvt_pk_bf16_f32 v0, v0, v1
	v_cvt_pk_bf16_f32 v1, v2, v3
	v_cvt_pk_bf16_f32 v2, v6, v7
	v_or_b32_e32 v6, s2, v85
	v_ashrrev_i32_e32 v7, 31, v6
	v_lshlrev_b64 v[6:7], 12, v[6:7]
	v_lshl_add_u64 v[6:7], v[4:5], 0, v[6:7]
	v_cvt_pk_bf16_f32 v3, v8, v9
	global_store_dwordx4 v[6:7], v[0:3], off
	ds_read_b32 v0, v83 offset:96
	ds_read_b32 v1, v83 offset:356
	ds_read_b32 v2, v83 offset:616
	ds_read_b32 v3, v83 offset:876
	ds_read_b32 v6, v83 offset:1136
	ds_read_b32 v7, v83 offset:1396
	ds_read_b32 v8, v83 offset:1656
	ds_read_b32 v9, v83 offset:1916
	s_waitcnt lgkmcnt(0)
	v_cvt_pk_bf16_f32 v0, v0, v1
	v_cvt_pk_bf16_f32 v1, v2, v3
	v_cvt_pk_bf16_f32 v2, v6, v7
	v_or_b32_e32 v6, s2, v86
	v_ashrrev_i32_e32 v7, 31, v6
	v_lshlrev_b64 v[6:7], 12, v[6:7]
	v_lshl_add_u64 v[6:7], v[4:5], 0, v[6:7]
	v_cvt_pk_bf16_f32 v3, v8, v9
	global_store_dwordx4 v[6:7], v[0:3], off
	ds_read_b32 v0, v83 offset:128
	ds_read_b32 v1, v83 offset:388
	ds_read_b32 v2, v83 offset:648
	ds_read_b32 v3, v83 offset:908
	ds_read_b32 v6, v83 offset:1168
	ds_read_b32 v7, v83 offset:1428
	ds_read_b32 v8, v83 offset:1688
	ds_read_b32 v9, v83 offset:1948
	s_waitcnt lgkmcnt(0)
	v_cvt_pk_bf16_f32 v0, v0, v1
	v_cvt_pk_bf16_f32 v1, v2, v3
	v_cvt_pk_bf16_f32 v2, v6, v7
	v_or_b32_e32 v6, s2, v87
	v_ashrrev_i32_e32 v7, 31, v6
	v_lshlrev_b64 v[6:7], 12, v[6:7]
	v_lshl_add_u64 v[6:7], v[4:5], 0, v[6:7]
	v_cvt_pk_bf16_f32 v3, v8, v9
	global_store_dwordx4 v[6:7], v[0:3], off
	ds_read_b32 v0, v83 offset:160
	ds_read_b32 v1, v83 offset:420
	ds_read_b32 v2, v83 offset:680
	ds_read_b32 v3, v83 offset:940
	ds_read_b32 v6, v83 offset:1200
	ds_read_b32 v7, v83 offset:1460
	ds_read_b32 v8, v83 offset:1720
	ds_read_b32 v9, v83 offset:1980
	s_waitcnt lgkmcnt(0)
	v_cvt_pk_bf16_f32 v0, v0, v1
	v_cvt_pk_bf16_f32 v1, v2, v3
	v_cvt_pk_bf16_f32 v2, v6, v7
	v_or_b32_e32 v6, s2, v88
	v_ashrrev_i32_e32 v7, 31, v6
	v_lshlrev_b64 v[6:7], 12, v[6:7]
	v_lshl_add_u64 v[6:7], v[4:5], 0, v[6:7]
	v_cvt_pk_bf16_f32 v3, v8, v9
	global_store_dwordx4 v[6:7], v[0:3], off
	ds_read_b32 v0, v83 offset:192
	ds_read_b32 v1, v83 offset:452
	ds_read_b32 v2, v83 offset:712
	ds_read_b32 v3, v83 offset:972
	ds_read_b32 v6, v83 offset:1232
	ds_read_b32 v7, v83 offset:1492
	ds_read_b32 v8, v83 offset:1752
	ds_read_b32 v9, v83 offset:2012
	s_waitcnt lgkmcnt(0)
	v_cvt_pk_bf16_f32 v0, v0, v1
	v_cvt_pk_bf16_f32 v1, v2, v3
	v_cvt_pk_bf16_f32 v2, v6, v7
	v_or_b32_e32 v6, s2, v89
	v_ashrrev_i32_e32 v7, 31, v6
	v_lshlrev_b64 v[6:7], 12, v[6:7]
	v_lshl_add_u64 v[6:7], v[4:5], 0, v[6:7]
	v_cvt_pk_bf16_f32 v3, v8, v9
	global_store_dwordx4 v[6:7], v[0:3], off
	ds_read_b32 v0, v83 offset:224
	ds_read_b32 v1, v83 offset:484
	ds_read_b32 v2, v83 offset:744
	ds_read_b32 v3, v83 offset:1004
	ds_read_b32 v6, v83 offset:1264
	ds_read_b32 v7, v83 offset:1524
	ds_read_b32 v8, v83 offset:1784
	ds_read_b32 v9, v83 offset:2044
	s_waitcnt lgkmcnt(0)
	v_cvt_pk_bf16_f32 v0, v0, v1
	v_cvt_pk_bf16_f32 v1, v2, v3
	v_cvt_pk_bf16_f32 v2, v6, v7
	v_or_b32_e32 v6, s2, v90
	v_ashrrev_i32_e32 v7, 31, v6
	v_lshlrev_b64 v[6:7], 12, v[6:7]
	v_lshl_add_u64 v[4:5], v[4:5], 0, v[6:7]
	v_cvt_pk_bf16_f32 v3, v8, v9
	global_store_dwordx4 v[4:5], v[0:3], off
	s_waitcnt lgkmcnt(0)
	s_branch .LBB0_162

; __device__ __forceinline__ unsigned cvt_pk_bf16(float lo, float hi) { unsigned r; asm volatile("v_cvt_pk_bf16_f32 %0, %1, %2" : "=v"(r) : "v"(lo), "v"(hi)); return r; }
;     __device__ __forceinline__ void operator()(const f32x4 (&acc)[2][2][4][2], const Unit& u, int wr, int wc, int fr, int fq) const {
;     ...
;             for (int m = 0; m < 4; ++m) { bf16_t* rowp = O + (size_t)(row0 + ai * HALF + m * 16) * ldc + col0;
; #pragma unroll
;                 for (int bj = 0; bj < 2; ++bj) { f32x4 v0 = acc[ai][bj][m][0], v1 = acc[ai][bj][m][1];
;                     if (act != 0) {
;                         const float k0 = (act == 1) ? -1.5957691216057308f * 1.4426950408889634f : -1.4426950408889634f, k1 = (act == 1) ? -1.5957691216057308f * 0.044715f * 1.4426950408889634f : 0.f;
;                         const f32x4 a0 = v0 * ((v0 * v0) * k1 + k0), a1 = v1 * ((v1 * v1) * k1 + k0); f32x4 r0, r1;
; #pragma unroll
;                         for (int e = 0; e < 4; ++e) { r0[e] = __builtin_amdgcn_rcpf(1.f + __builtin_amdgcn_exp2f(a0[e])); r1[e] = __builtin_amdgcn_rcpf(1.f + __builtin_amdgcn_exp2f(a1[e])); }
;                         v0 = v0 * r0; v1 = v1 * r1; }
;                     u32x4 w; w.x = cvt_pk_bf16(v0[0], v0[1]); w.y = cvt_pk_bf16(v0[2], v0[3]); w.z = cvt_pk_bf16(v1[0], v1[1]); w.w = cvt_pk_bf16(v1[2], v1[3]);
;                     *(u32x4*)(rowp + bj * HALF) = w; } }
.LBB0_270:
	v_lshl_add_u32 v150, s58, 8, v146
	v_lshl_or_b32 v142, s57, 8, v148
	v_mov_b64_e32 v[144:145], s[2:3]
	v_ashrrev_i32_e32 v143, 31, v142
	v_mad_i64_i32 v[144:145], s[6:7], v150, s13, v[144:145]
	v_cvt_pk_bf16_f32 v124, v124, v125
	v_cvt_pk_bf16_f32 v125, v126, v127
	v_cvt_pk_bf16_f32 v126, v120, v121
	v_cndmask_b32_e64 v120, 0, 1, s[24:25]
	v_lshl_add_u64 v[144:145], v[142:143], 1, v[144:145]
	v_cmp_ne_u32_e64 s[6:7], 1, v120
	s_andn2_b64 vcc, exec, s[24:25]
	v_cvt_pk_bf16_f32 v127, v122, v123
	global_store_dwordx4 v[144:145], v[124:127], off
	s_cbranch_vccnz .LBB0_272
	v_pk_mul_f32 v[120:121], v[118:119], v[118:119]
	v_pk_mul_f32 v[122:123], v[116:117], v[116:117]
	v_mov_b32_e32 v124, v138
	v_mov_b32_e32 v125, v138
	v_mov_b32_e32 v126, v140
	v_mov_b32_e32 v127, v140
	v_pk_mul_f32 v[152:153], v[114:115], v[114:115]
	v_pk_mul_f32 v[154:155], v[112:113], v[112:113]
	v_pk_fma_f32 v[120:121], v[126:127], v[120:121], v[124:125]
	v_pk_fma_f32 v[122:123], v[140:141], v[122:123], v[138:139]
	v_pk_fma_f32 v[124:125], v[126:127], v[152:153], v[124:125]
	v_pk_fma_f32 v[126:127], v[140:141], v[154:155], v[138:139]
	v_pk_mul_f32 v[120:121], v[118:119], v[120:121]
	v_pk_mul_f32 v[122:123], v[116:117], v[122:123]
	v_pk_mul_f32 v[124:125], v[114:115], v[124:125]
	v_pk_mul_f32 v[126:127], v[112:113], v[126:127]
	v_exp_f32_e32 v122, v122
	v_exp_f32_e32 v126, v126
	v_exp_f32_e32 v123, v123
	v_exp_f32_e32 v127, v127
	v_exp_f32_e32 v120, v120
	v_exp_f32_e32 v124, v124
	v_exp_f32_e32 v121, v121
	v_exp_f32_e32 v125, v125
	v_add_f32_e32 v122, 1.0, v122
	v_add_f32_e32 v126, 1.0, v126
	v_add_f32_e32 v123, 1.0, v123
	v_add_f32_e32 v127, 1.0, v127
	v_add_f32_e32 v120, 1.0, v120
	v_add_f32_e32 v124, 1.0, v124
	v_add_f32_e32 v121, 1.0, v121
	v_add_f32_e32 v125, 1.0, v125
	v_rcp_f32_e32 v122, v122
	v_rcp_f32_e32 v126, v126
	v_rcp_f32_e32 v123, v123
	v_rcp_f32_e32 v120, v120
	v_rcp_f32_e32 v124, v124
	v_rcp_f32_e32 v121, v121
	v_rcp_f32_e32 v125, v125
	v_rcp_f32_e32 v127, v127
	v_pk_mul_f32 v[116:117], v[116:117], v[122:123]
	v_pk_mul_f32 v[118:119], v[118:119], v[120:121]
	v_pk_mul_f32 v[114:115], v[114:115], v[124:125]
	v_pk_mul_f32 v[112:113], v[112:113], v[126:127]
.LBB0_272:
	s_and_b64 vcc, exec, s[6:7]
	v_cvt_pk_bf16_f32 v116, v116, v117
	v_cvt_pk_bf16_f32 v117, v118, v119
	v_cvt_pk_bf16_f32 v118, v112, v113
	v_cvt_pk_bf16_f32 v119, v114, v115
	global_store_dwordx4 v[144:145], v[116:119], off offset:256
	s_cbranch_vccnz .LBB0_274
	v_pk_mul_f32 v[112:113], v[110:111], v[110:111]
	v_pk_mul_f32 v[114:115], v[108:109], v[108:109]
	v_mov_b32_e32 v116, v138
	v_mov_b32_e32 v117, v138
	v_mov_b32_e32 v118, v140
	v_mov_b32_e32 v119, v140
	v_pk_mul_f32 v[120:121], v[106:107], v[106:107]
	v_pk_mul_f32 v[122:123], v[104:105], v[104:105]
	v_pk_fma_f32 v[112:113], v[118:119], v[112:113], v[116:117]
	v_pk_fma_f32 v[114:115], v[140:141], v[114:115], v[138:139]
	v_pk_fma_f32 v[116:117], v[118:119], v[120:121], v[116:117]
	v_pk_fma_f32 v[118:119], v[140:141], v[122:123], v[138:139]
	v_pk_mul_f32 v[112:113], v[110:111], v[112:113]
	v_pk_mul_f32 v[114:115], v[108:109], v[114:115]
	v_pk_mul_f32 v[116:117], v[106:107], v[116:117]
	v_pk_mul_f32 v[118:119], v[104:105], v[118:119]
	v_exp_f32_e32 v114, v114
	v_exp_f32_e32 v118, v118
	v_exp_f32_e32 v115, v115
	v_exp_f32_e32 v119, v119
	v_exp_f32_e32 v112, v112
	v_exp_f32_e32 v116, v116
	v_exp_f32_e32 v113, v113
	v_exp_f32_e32 v117, v117
	v_add_f32_e32 v114, 1.0, v114
	v_add_f32_e32 v118, 1.0, v118
	v_add_f32_e32 v115, 1.0, v115
	v_add_f32_e32 v119, 1.0, v119
	v_add_f32_e32 v112, 1.0, v112
	v_add_f32_e32 v116, 1.0, v116
	v_add_f32_e32 v113, 1.0, v113
	v_add_f32_e32 v117, 1.0, v117
	v_rcp_f32_e32 v114, v114
	v_rcp_f32_e32 v118, v118
	v_rcp_f32_e32 v115, v115
	v_rcp_f32_e32 v112, v112
	v_rcp_f32_e32 v116, v116
	v_rcp_f32_e32 v113, v113
	v_rcp_f32_e32 v117, v117
	v_rcp_f32_e32 v119, v119
	v_pk_mul_f32 v[108:109], v[108:109], v[114:115]
	v_pk_mul_f32 v[110:111], v[110:111], v[112:113]
	v_pk_mul_f32 v[106:107], v[106:107], v[116:117]
	v_pk_mul_f32 v[104:105], v[104:105], v[118:119]
.LBB0_274:
	v_or_b32_e32 v114, 16, v150
	v_mov_b64_e32 v[112:113], s[2:3]
	v_mad_i64_i32 v[112:113], s[24:25], v114, s13, v[112:113]
	v_lshl_add_u64 v[112:113], v[142:143], 1, v[112:113]
	s_and_b64 vcc, exec, s[6:7]
	v_cvt_pk_bf16_f32 v108, v108, v109
	v_cvt_pk_bf16_f32 v109, v110, v111
	v_cvt_pk_bf16_f32 v110, v104, v105
	v_cvt_pk_bf16_f32 v111, v106, v107
	global_store_dwordx4 v[112:113], v[108:111], off
	s_cbranch_vccnz .LBB0_276
	v_pk_mul_f32 v[104:105], v[102:103], v[102:103]
	v_pk_mul_f32 v[106:107], v[100:101], v[100:101]
	v_mov_b32_e32 v108, v138
	v_mov_b32_e32 v109, v138
	v_mov_b32_e32 v110, v140
	v_mov_b32_e32 v111, v140
	v_pk_mul_f32 v[114:115], v[98:99], v[98:99]
	v_pk_mul_f32 v[116:117], v[96:97], v[96:97]
	v_pk_fma_f32 v[104:105], v[110:111], v[104:105], v[108:109]
	v_pk_fma_f32 v[106:107], v[140:141], v[106:107], v[138:139]
	v_pk_fma_f32 v[108:109], v[110:111], v[114:115], v[108:109]
	v_pk_fma_f32 v[110:111], v[140:141], v[116:117], v[138:139]
	v_pk_mul_f32 v[104:105], v[102:103], v[104:105]
	v_pk_mul_f32 v[106:107], v[100:101], v[106:107]
	v_pk_mul_f32 v[108:109], v[98:99], v[108:109]
	v_pk_mul_f32 v[110:111], v[96:97], v[110:111]
	v_exp_f32_e32 v106, v106
	v_exp_f32_e32 v110, v110
	v_exp_f32_e32 v107, v107
	v_exp_f32_e32 v111, v111
	v_exp_f32_e32 v104, v104
	v_exp_f32_e32 v108, v108
	v_exp_f32_e32 v105, v105
	v_exp_f32_e32 v109, v109
	v_add_f32_e32 v106, 1.0, v106
	v_add_f32_e32 v110, 1.0, v110
	v_add_f32_e32 v107, 1.0, v107
	v_add_f32_e32 v111, 1.0, v111
	v_add_f32_e32 v104, 1.0, v104
	v_add_f32_e32 v108, 1.0, v108
	v_add_f32_e32 v105, 1.0, v105
	v_add_f32_e32 v109, 1.0, v109
	v_rcp_f32_e32 v106, v106
	v_rcp_f32_e32 v110, v110
	v_rcp_f32_e32 v107, v107
	v_rcp_f32_e32 v104, v104
	v_rcp_f32_e32 v108, v108
	v_rcp_f32_e32 v105, v105
	v_rcp_f32_e32 v109, v109
	v_rcp_f32_e32 v111, v111
	v_pk_mul_f32 v[100:101], v[100:101], v[106:107]
	v_pk_mul_f32 v[102:103], v[102:103], v[104:105]
	v_pk_mul_f32 v[98:99], v[98:99], v[108:109]
	v_pk_mul_f32 v[96:97], v[96:97], v[110:111]
; __device__ __forceinline__ unsigned cvt_pk_bf16(float lo, float hi) { unsigned r; asm volatile("v_cvt_pk_bf16_f32 %0, %1, %2" : "=v"(r) : "v"(lo), "v"(hi)); return r; }
;     __device__ __forceinline__ void operator()(const f32x4 (&acc)[2][2][4][2], const Unit& u, int wr, int wc, int fr, int fq) const {
;     ...
;             for (int m = 0; m < 4; ++m) { bf16_t* rowp = O + (size_t)(row0 + ai * HALF + m * 16) * ldc + col0;
; #pragma unroll
;                 for (int bj = 0; bj < 2; ++bj) { f32x4 v0 = acc[ai][bj][m][0], v1 = acc[ai][bj][m][1];
;                     if (act != 0) {
;                         const float k0 = (act == 1) ? -1.5957691216057308f * 1.4426950408889634f : -1.4426950408889634f, k1 = (act == 1) ? -1.5957691216057308f * 0.044715f * 1.4426950408889634f : 0.f;
;                         const f32x4 a0 = v0 * ((v0 * v0) * k1 + k0), a1 = v1 * ((v1 * v1) * k1 + k0); f32x4 r0, r1;
; #pragma unroll
;                         for (int e = 0; e < 4; ++e) { r0[e] = __builtin_amdgcn_rcpf(1.f + __builtin_amdgcn_exp2f(a0[e])); r1[e] = __builtin_amdgcn_rcpf(1.f + __builtin_amdgcn_exp2f(a1[e])); }
;                         v0 = v0 * r0; v1 = v1 * r1; }
;                     u32x4 w; w.x = cvt_pk_bf16(v0[0], v0[1]); w.y = cvt_pk_bf16(v0[2], v0[3]); w.z = cvt_pk_bf16(v1[0], v1[1]); w.w = cvt_pk_bf16(v1[2], v1[3]);
;                     *(u32x4*)(rowp + bj * HALF) = w; } }
.LBB0_276:
	s_and_b64 vcc, exec, s[6:7]
	v_cvt_pk_bf16_f32 v100, v100, v101
	v_cvt_pk_bf16_f32 v101, v102, v103
	v_cvt_pk_bf16_f32 v102, v96, v97
	v_cvt_pk_bf16_f32 v103, v98, v99
	global_store_dwordx4 v[112:113], v[100:103], off offset:256
	s_cbranch_vccnz .LBB0_278
	v_pk_mul_f32 v[96:97], v[94:95], v[94:95]
	v_pk_mul_f32 v[98:99], v[92:93], v[92:93]
	v_mov_b32_e32 v100, v138
	v_mov_b32_e32 v101, v138
	v_mov_b32_e32 v102, v140
	v_mov_b32_e32 v103, v140
	v_pk_mul_f32 v[104:105], v[90:91], v[90:91]
	v_pk_mul_f32 v[106:107], v[88:89], v[88:89]
	v_pk_fma_f32 v[96:97], v[102:103], v[96:97], v[100:101]
	v_pk_fma_f32 v[98:99], v[140:141], v[98:99], v[138:139]
	v_pk_fma_f32 v[100:101], v[102:103], v[104:105], v[100:101]
	v_pk_fma_f32 v[102:103], v[140:141], v[106:107], v[138:139]
	v_pk_mul_f32 v[96:97], v[94:95], v[96:97]
	v_pk_mul_f32 v[98:99], v[92:93], v[98:99]
	v_pk_mul_f32 v[100:101], v[90:91], v[100:101]
	v_pk_mul_f32 v[102:103], v[88:89], v[102:103]
	v_exp_f32_e32 v98, v98
	v_exp_f32_e32 v102, v102
	v_exp_f32_e32 v99, v99
	v_exp_f32_e32 v103, v103
	v_exp_f32_e32 v96, v96
	v_exp_f32_e32 v100, v100
	v_exp_f32_e32 v97, v97
	v_exp_f32_e32 v101, v101
	v_add_f32_e32 v98, 1.0, v98
	v_add_f32_e32 v102, 1.0, v102
	v_add_f32_e32 v99, 1.0, v99
	v_add_f32_e32 v103, 1.0, v103
	v_add_f32_e32 v96, 1.0, v96
	v_add_f32_e32 v100, 1.0, v100
	v_add_f32_e32 v97, 1.0, v97
	v_add_f32_e32 v101, 1.0, v101
	v_rcp_f32_e32 v98, v98
	v_rcp_f32_e32 v102, v102
	v_rcp_f32_e32 v99, v99
	v_rcp_f32_e32 v96, v96
	v_rcp_f32_e32 v100, v100
	v_rcp_f32_e32 v97, v97
	v_rcp_f32_e32 v101, v101
	v_rcp_f32_e32 v103, v103
	v_pk_mul_f32 v[92:93], v[92:93], v[98:99]
	v_pk_mul_f32 v[94:95], v[94:95], v[96:97]
	v_pk_mul_f32 v[90:91], v[90:91], v[100:101]
	v_pk_mul_f32 v[88:89], v[88:89], v[102:103]
.LBB0_278:
	v_or_b32_e32 v98, 32, v150
	v_mov_b64_e32 v[96:97], s[2:3]
	v_mad_i64_i32 v[96:97], s[24:25], v98, s13, v[96:97]
	v_lshl_add_u64 v[96:97], v[142:143], 1, v[96:97]
	s_and_b64 vcc, exec, s[6:7]
	v_cvt_pk_bf16_f32 v92, v92, v93
	v_cvt_pk_bf16_f32 v93, v94, v95
	v_cvt_pk_bf16_f32 v94, v88, v89
	v_cvt_pk_bf16_f32 v95, v90, v91
	global_store_dwordx4 v[96:97], v[92:95], off
	s_cbranch_vccnz .LBB0_280
	v_pk_mul_f32 v[88:89], v[86:87], v[86:87]
	v_pk_mul_f32 v[90:91], v[84:85], v[84:85]
	v_mov_b32_e32 v92, v138
	v_mov_b32_e32 v93, v138
	v_mov_b32_e32 v94, v140
	v_mov_b32_e32 v95, v140
	v_pk_mul_f32 v[98:99], v[82:83], v[82:83]
	v_pk_mul_f32 v[100:101], v[80:81], v[80:81]
	v_pk_fma_f32 v[88:89], v[94:95], v[88:89], v[92:93]
	v_pk_fma_f32 v[90:91], v[140:141], v[90:91], v[138:139]
	v_pk_fma_f32 v[92:93], v[94:95], v[98:99], v[92:93]
	v_pk_fma_f32 v[94:95], v[140:141], v[100:101], v[138:139]
	v_pk_mul_f32 v[88:89], v[86:87], v[88:89]
	v_pk_mul_f32 v[90:91], v[84:85], v[90:91]
	v_pk_mul_f32 v[92:93], v[82:83], v[92:93]
	v_pk_mul_f32 v[94:95], v[80:81], v[94:95]
	v_exp_f32_e32 v90, v90
	v_exp_f32_e32 v94, v94
	v_exp_f32_e32 v91, v91
	v_exp_f32_e32 v95, v95
	v_exp_f32_e32 v88, v88
	v_exp_f32_e32 v92, v92
	v_exp_f32_e32 v89, v89
	v_exp_f32_e32 v93, v93
	v_add_f32_e32 v90, 1.0, v90
	v_add_f32_e32 v94, 1.0, v94
	v_add_f32_e32 v91, 1.0, v91
	v_add_f32_e32 v95, 1.0, v95
	v_add_f32_e32 v88, 1.0, v88
	v_add_f32_e32 v92, 1.0, v92
	v_add_f32_e32 v89, 1.0, v89
	v_add_f32_e32 v93, 1.0, v93
	v_rcp_f32_e32 v90, v90
	v_rcp_f32_e32 v94, v94
	v_rcp_f32_e32 v91, v91
	v_rcp_f32_e32 v88, v88
	v_rcp_f32_e32 v92, v92
	v_rcp_f32_e32 v89, v89
	v_rcp_f32_e32 v93, v93
	v_rcp_f32_e32 v95, v95
	v_pk_mul_f32 v[84:85], v[84:85], v[90:91]
	v_pk_mul_f32 v[86:87], v[86:87], v[88:89]
	v_pk_mul_f32 v[82:83], v[82:83], v[92:93]
	v_pk_mul_f32 v[80:81], v[80:81], v[94:95]
.LBB0_280:
	s_and_b64 vcc, exec, s[6:7]
	v_cvt_pk_bf16_f32 v84, v84, v85
	v_cvt_pk_bf16_f32 v85, v86, v87
	v_cvt_pk_bf16_f32 v86, v80, v81
	v_cvt_pk_bf16_f32 v87, v82, v83
	global_store_dwordx4 v[96:97], v[84:87], off offset:256
	s_cbranch_vccnz .LBB0_282
	v_pk_mul_f32 v[80:81], v[78:79], v[78:79]
	v_pk_mul_f32 v[82:83], v[76:77], v[76:77]
	v_mov_b32_e32 v84, v138
	v_mov_b32_e32 v85, v138
	v_mov_b32_e32 v86, v140
	v_mov_b32_e32 v87, v140
	v_pk_mul_f32 v[88:89], v[74:75], v[74:75]
	v_pk_mul_f32 v[90:91], v[72:73], v[72:73]
	v_pk_fma_f32 v[80:81], v[86:87], v[80:81], v[84:85]
	v_pk_fma_f32 v[82:83], v[140:141], v[82:83], v[138:139]
	v_pk_fma_f32 v[84:85], v[86:87], v[88:89], v[84:85]
	v_pk_fma_f32 v[86:87], v[140:141], v[90:91], v[138:139]
	v_pk_mul_f32 v[80:81], v[78:79], v[80:81]
	v_pk_mul_f32 v[82:83], v[76:77], v[82:83]
	v_pk_mul_f32 v[84:85], v[74:75], v[84:85]
	v_pk_mul_f32 v[86:87], v[72:73], v[86:87]
	v_exp_f32_e32 v82, v82
	v_exp_f32_e32 v86, v86
	v_exp_f32_e32 v83, v83
	v_exp_f32_e32 v87, v87
	v_exp_f32_e32 v80, v80
	v_exp_f32_e32 v84, v84
	v_exp_f32_e32 v81, v81
	v_exp_f32_e32 v85, v85
	v_add_f32_e32 v82, 1.0, v82
	v_add_f32_e32 v86, 1.0, v86
	v_add_f32_e32 v83, 1.0, v83
	v_add_f32_e32 v87, 1.0, v87
	v_add_f32_e32 v80, 1.0, v80
	v_add_f32_e32 v84, 1.0, v84
	v_add_f32_e32 v81, 1.0, v81
	v_add_f32_e32 v85, 1.0, v85
	v_rcp_f32_e32 v82, v82
	v_rcp_f32_e32 v86, v86
	v_rcp_f32_e32 v83, v83
	v_rcp_f32_e32 v80, v80
	v_rcp_f32_e32 v84, v84
	v_rcp_f32_e32 v81, v81
	v_rcp_f32_e32 v85, v85
	v_rcp_f32_e32 v87, v87
	v_pk_mul_f32 v[76:77], v[76:77], v[82:83]
	v_pk_mul_f32 v[78:79], v[78:79], v[80:81]
	v_pk_mul_f32 v[74:75], v[74:75], v[84:85]
	v_pk_mul_f32 v[72:73], v[72:73], v[86:87]
; __device__ __forceinline__ unsigned cvt_pk_bf16(float lo, float hi) { unsigned r; asm volatile("v_cvt_pk_bf16_f32 %0, %1, %2" : "=v"(r) : "v"(lo), "v"(hi)); return r; }
;     __device__ __forceinline__ void operator()(const f32x4 (&acc)[2][2][4][2], const Unit& u, int wr, int wc, int fr, int fq) const {
;     ...
;             for (int m = 0; m < 4; ++m) { bf16_t* rowp = O + (size_t)(row0 + ai * HALF + m * 16) * ldc + col0;
; #pragma unroll
;                 for (int bj = 0; bj < 2; ++bj) { f32x4 v0 = acc[ai][bj][m][0], v1 = acc[ai][bj][m][1];
;                     if (act != 0) {
;                         const float k0 = (act == 1) ? -1.5957691216057308f * 1.4426950408889634f : -1.4426950408889634f, k1 = (act == 1) ? -1.5957691216057308f * 0.044715f * 1.4426950408889634f : 0.f;
;                         const f32x4 a0 = v0 * ((v0 * v0) * k1 + k0), a1 = v1 * ((v1 * v1) * k1 + k0); f32x4 r0, r1;
; #pragma unroll
;                         for (int e = 0; e < 4; ++e) { r0[e] = __builtin_amdgcn_rcpf(1.f + __builtin_amdgcn_exp2f(a0[e])); r1[e] = __builtin_amdgcn_rcpf(1.f + __builtin_amdgcn_exp2f(a1[e])); }
;                         v0 = v0 * r0; v1 = v1 * r1; }
;                     u32x4 w; w.x = cvt_pk_bf16(v0[0], v0[1]); w.y = cvt_pk_bf16(v0[2], v0[3]); w.z = cvt_pk_bf16(v1[0], v1[1]); w.w = cvt_pk_bf16(v1[2], v1[3]);
;                     *(u32x4*)(rowp + bj * HALF) = w; } }
.LBB0_282:
	v_or_b32_e32 v82, 48, v150
	v_mov_b64_e32 v[80:81], s[2:3]
	v_mad_i64_i32 v[80:81], s[24:25], v82, s13, v[80:81]
	v_lshl_add_u64 v[80:81], v[142:143], 1, v[80:81]
	s_and_b64 vcc, exec, s[6:7]
	v_cvt_pk_bf16_f32 v76, v76, v77
	v_cvt_pk_bf16_f32 v77, v78, v79
	v_cvt_pk_bf16_f32 v78, v72, v73
	v_cvt_pk_bf16_f32 v79, v74, v75
	global_store_dwordx4 v[80:81], v[76:79], off
	s_cbranch_vccnz .LBB0_284
	v_pk_mul_f32 v[72:73], v[70:71], v[70:71]
	v_pk_mul_f32 v[74:75], v[68:69], v[68:69]
	v_mov_b32_e32 v76, v138
	v_mov_b32_e32 v77, v138
	v_mov_b32_e32 v78, v140
	v_mov_b32_e32 v79, v140
	v_pk_mul_f32 v[82:83], v[66:67], v[66:67]
	v_pk_mul_f32 v[84:85], v[64:65], v[64:65]
	v_pk_fma_f32 v[72:73], v[78:79], v[72:73], v[76:77]
	v_pk_fma_f32 v[74:75], v[140:141], v[74:75], v[138:139]
	v_pk_fma_f32 v[76:77], v[78:79], v[82:83], v[76:77]
	v_pk_fma_f32 v[78:79], v[140:141], v[84:85], v[138:139]
	v_pk_mul_f32 v[72:73], v[70:71], v[72:73]
	v_pk_mul_f32 v[74:75], v[68:69], v[74:75]
	v_pk_mul_f32 v[76:77], v[66:67], v[76:77]
	v_pk_mul_f32 v[78:79], v[64:65], v[78:79]
	v_exp_f32_e32 v74, v74
	v_exp_f32_e32 v78, v78
	v_exp_f32_e32 v75, v75
	v_exp_f32_e32 v79, v79
	v_exp_f32_e32 v72, v72
	v_exp_f32_e32 v76, v76
	v_exp_f32_e32 v73, v73
	v_exp_f32_e32 v77, v77
	v_add_f32_e32 v74, 1.0, v74
	v_add_f32_e32 v78, 1.0, v78
	v_add_f32_e32 v75, 1.0, v75
	v_add_f32_e32 v79, 1.0, v79
	v_add_f32_e32 v72, 1.0, v72
	v_add_f32_e32 v76, 1.0, v76
	v_add_f32_e32 v73, 1.0, v73
	v_add_f32_e32 v77, 1.0, v77
	v_rcp_f32_e32 v74, v74
	v_rcp_f32_e32 v78, v78
	v_rcp_f32_e32 v75, v75
	v_rcp_f32_e32 v72, v72
	v_rcp_f32_e32 v76, v76
	v_rcp_f32_e32 v73, v73
	v_rcp_f32_e32 v77, v77
	v_rcp_f32_e32 v79, v79
	v_pk_mul_f32 v[68:69], v[68:69], v[74:75]
	v_pk_mul_f32 v[70:71], v[70:71], v[72:73]
	v_pk_mul_f32 v[66:67], v[66:67], v[76:77]
	v_pk_mul_f32 v[64:65], v[64:65], v[78:79]
.LBB0_284:
	s_and_b64 vcc, exec, s[6:7]
	v_cvt_pk_bf16_f32 v68, v68, v69
	v_cvt_pk_bf16_f32 v69, v70, v71
	v_cvt_pk_bf16_f32 v70, v64, v65
	v_cvt_pk_bf16_f32 v71, v66, v67
	global_store_dwordx4 v[80:81], v[68:71], off offset:256
	s_cbranch_vccnz .LBB0_286
	v_pk_mul_f32 v[64:65], v[62:63], v[62:63]
	v_pk_mul_f32 v[66:67], v[60:61], v[60:61]
	v_mov_b32_e32 v68, v138
	v_mov_b32_e32 v69, v138
	v_mov_b32_e32 v70, v140
	v_mov_b32_e32 v71, v140
	v_pk_mul_f32 v[72:73], v[58:59], v[58:59]
	v_pk_mul_f32 v[74:75], v[56:57], v[56:57]
	v_pk_fma_f32 v[64:65], v[70:71], v[64:65], v[68:69]
	v_pk_fma_f32 v[66:67], v[140:141], v[66:67], v[138:139]
	v_pk_fma_f32 v[68:69], v[70:71], v[72:73], v[68:69]
	v_pk_fma_f32 v[70:71], v[140:141], v[74:75], v[138:139]
	v_pk_mul_f32 v[64:65], v[62:63], v[64:65]
	v_pk_mul_f32 v[66:67], v[60:61], v[66:67]
	v_pk_mul_f32 v[68:69], v[58:59], v[68:69]
	v_pk_mul_f32 v[70:71], v[56:57], v[70:71]
	v_exp_f32_e32 v66, v66
	v_exp_f32_e32 v70, v70
	v_exp_f32_e32 v67, v67
	v_exp_f32_e32 v71, v71
	v_exp_f32_e32 v64, v64
	v_exp_f32_e32 v68, v68
	v_exp_f32_e32 v65, v65
	v_exp_f32_e32 v69, v69
	v_add_f32_e32 v66, 1.0, v66
	v_add_f32_e32 v70, 1.0, v70
	v_add_f32_e32 v67, 1.0, v67
	v_add_f32_e32 v71, 1.0, v71
	v_add_f32_e32 v64, 1.0, v64
	v_add_f32_e32 v68, 1.0, v68
	v_add_f32_e32 v65, 1.0, v65
	v_add_f32_e32 v69, 1.0, v69
	v_rcp_f32_e32 v66, v66
	v_rcp_f32_e32 v70, v70
	v_rcp_f32_e32 v67, v67
	v_rcp_f32_e32 v64, v64
	v_rcp_f32_e32 v68, v68
	v_rcp_f32_e32 v65, v65
	v_rcp_f32_e32 v69, v69
	v_rcp_f32_e32 v71, v71
	v_pk_mul_f32 v[60:61], v[60:61], v[66:67]
	v_pk_mul_f32 v[62:63], v[62:63], v[64:65]
	v_pk_mul_f32 v[58:59], v[58:59], v[68:69]
	v_pk_mul_f32 v[56:57], v[56:57], v[70:71]
.LBB0_286:
	v_add_u32_e32 v66, 0x80, v150
	v_mov_b64_e32 v[64:65], s[2:3]
	v_mad_i64_i32 v[64:65], s[24:25], v66, s13, v[64:65]
	v_lshl_add_u64 v[64:65], v[142:143], 1, v[64:65]
	s_and_b64 vcc, exec, s[6:7]
	v_cvt_pk_bf16_f32 v60, v60, v61
	v_cvt_pk_bf16_f32 v61, v62, v63
	v_cvt_pk_bf16_f32 v62, v56, v57
	v_cvt_pk_bf16_f32 v63, v58, v59
	global_store_dwordx4 v[64:65], v[60:63], off
	s_cbranch_vccnz .LBB0_288
	v_pk_mul_f32 v[56:57], v[54:55], v[54:55]
	v_pk_mul_f32 v[58:59], v[52:53], v[52:53]
	v_mov_b32_e32 v60, v138
	v_mov_b32_e32 v61, v138
	v_mov_b32_e32 v62, v140
	v_mov_b32_e32 v63, v140
	v_pk_mul_f32 v[66:67], v[50:51], v[50:51]
	v_pk_mul_f32 v[68:69], v[48:49], v[48:49]
	v_pk_fma_f32 v[56:57], v[62:63], v[56:57], v[60:61]
	v_pk_fma_f32 v[58:59], v[140:141], v[58:59], v[138:139]
	v_pk_fma_f32 v[60:61], v[62:63], v[66:67], v[60:61]
	v_pk_fma_f32 v[62:63], v[140:141], v[68:69], v[138:139]
	v_pk_mul_f32 v[56:57], v[54:55], v[56:57]
	v_pk_mul_f32 v[58:59], v[52:53], v[58:59]
	v_pk_mul_f32 v[60:61], v[50:51], v[60:61]
	v_pk_mul_f32 v[62:63], v[48:49], v[62:63]
	v_exp_f32_e32 v58, v58
	v_exp_f32_e32 v62, v62
	v_exp_f32_e32 v59, v59
	v_exp_f32_e32 v63, v63
	v_exp_f32_e32 v56, v56
	v_exp_f32_e32 v60, v60
	v_exp_f32_e32 v57, v57
	v_exp_f32_e32 v61, v61
	v_add_f32_e32 v58, 1.0, v58
	v_add_f32_e32 v62, 1.0, v62
	v_add_f32_e32 v59, 1.0, v59
	v_add_f32_e32 v63, 1.0, v63
	v_add_f32_e32 v56, 1.0, v56
	v_add_f32_e32 v60, 1.0, v60
	v_add_f32_e32 v57, 1.0, v57
	v_add_f32_e32 v61, 1.0, v61
	v_rcp_f32_e32 v58, v58
	v_rcp_f32_e32 v62, v62
	v_rcp_f32_e32 v59, v59
	v_rcp_f32_e32 v56, v56
	v_rcp_f32_e32 v60, v60
	v_rcp_f32_e32 v57, v57
	v_rcp_f32_e32 v61, v61
	v_rcp_f32_e32 v63, v63
	v_pk_mul_f32 v[52:53], v[52:53], v[58:59]
	v_pk_mul_f32 v[54:55], v[54:55], v[56:57]
	v_pk_mul_f32 v[50:51], v[50:51], v[60:61]
	v_pk_mul_f32 v[48:49], v[48:49], v[62:63]
; __device__ __forceinline__ unsigned cvt_pk_bf16(float lo, float hi) { unsigned r; asm volatile("v_cvt_pk_bf16_f32 %0, %1, %2" : "=v"(r) : "v"(lo), "v"(hi)); return r; }
;     __device__ __forceinline__ void operator()(const f32x4 (&acc)[2][2][4][2], const Unit& u, int wr, int wc, int fr, int fq) const {
;     ...
;             for (int m = 0; m < 4; ++m) { bf16_t* rowp = O + (size_t)(row0 + ai * HALF + m * 16) * ldc + col0;
; #pragma unroll
;                 for (int bj = 0; bj < 2; ++bj) { f32x4 v0 = acc[ai][bj][m][0], v1 = acc[ai][bj][m][1];
;                     if (act != 0) {
;                         const float k0 = (act == 1) ? -1.5957691216057308f * 1.4426950408889634f : -1.4426950408889634f, k1 = (act == 1) ? -1.5957691216057308f * 0.044715f * 1.4426950408889634f : 0.f;
;                         const f32x4 a0 = v0 * ((v0 * v0) * k1 + k0), a1 = v1 * ((v1 * v1) * k1 + k0); f32x4 r0, r1;
; #pragma unroll
;                         for (int e = 0; e < 4; ++e) { r0[e] = __builtin_amdgcn_rcpf(1.f + __builtin_amdgcn_exp2f(a0[e])); r1[e] = __builtin_amdgcn_rcpf(1.f + __builtin_amdgcn_exp2f(a1[e])); }
;                         v0 = v0 * r0; v1 = v1 * r1; }
;                     u32x4 w; w.x = cvt_pk_bf16(v0[0], v0[1]); w.y = cvt_pk_bf16(v0[2], v0[3]); w.z = cvt_pk_bf16(v1[0], v1[1]); w.w = cvt_pk_bf16(v1[2], v1[3]);
;                     *(u32x4*)(rowp + bj * HALF) = w; } }
.LBB0_288:
	s_and_b64 vcc, exec, s[6:7]
	v_cvt_pk_bf16_f32 v52, v52, v53
	v_cvt_pk_bf16_f32 v53, v54, v55
	v_cvt_pk_bf16_f32 v54, v48, v49
	v_cvt_pk_bf16_f32 v55, v50, v51
	global_store_dwordx4 v[64:65], v[52:55], off offset:256
	s_cbranch_vccnz .LBB0_290
	v_pk_mul_f32 v[48:49], v[46:47], v[46:47]
	v_pk_mul_f32 v[50:51], v[44:45], v[44:45]
	v_mov_b32_e32 v52, v138
	v_mov_b32_e32 v53, v138
	v_mov_b32_e32 v54, v140
	v_mov_b32_e32 v55, v140
	v_pk_mul_f32 v[56:57], v[42:43], v[42:43]
	v_pk_mul_f32 v[58:59], v[40:41], v[40:41]
	v_pk_fma_f32 v[48:49], v[54:55], v[48:49], v[52:53]
	v_pk_fma_f32 v[50:51], v[140:141], v[50:51], v[138:139]
	v_pk_fma_f32 v[52:53], v[54:55], v[56:57], v[52:53]
	v_pk_fma_f32 v[54:55], v[140:141], v[58:59], v[138:139]
	v_pk_mul_f32 v[48:49], v[46:47], v[48:49]
	v_pk_mul_f32 v[50:51], v[44:45], v[50:51]
	v_pk_mul_f32 v[52:53], v[42:43], v[52:53]
	v_pk_mul_f32 v[54:55], v[40:41], v[54:55]
	v_exp_f32_e32 v50, v50
	v_exp_f32_e32 v54, v54
	v_exp_f32_e32 v51, v51
	v_exp_f32_e32 v55, v55
	v_exp_f32_e32 v48, v48
	v_exp_f32_e32 v52, v52
	v_exp_f32_e32 v49, v49
	v_exp_f32_e32 v53, v53
	v_add_f32_e32 v50, 1.0, v50
	v_add_f32_e32 v54, 1.0, v54
	v_add_f32_e32 v51, 1.0, v51
	v_add_f32_e32 v55, 1.0, v55
	v_add_f32_e32 v48, 1.0, v48
	v_add_f32_e32 v52, 1.0, v52
	v_add_f32_e32 v49, 1.0, v49
	v_add_f32_e32 v53, 1.0, v53
	v_rcp_f32_e32 v50, v50
	v_rcp_f32_e32 v54, v54
	v_rcp_f32_e32 v51, v51
	v_rcp_f32_e32 v48, v48
	v_rcp_f32_e32 v52, v52
	v_rcp_f32_e32 v49, v49
	v_rcp_f32_e32 v53, v53
	v_rcp_f32_e32 v55, v55
	v_pk_mul_f32 v[44:45], v[44:45], v[50:51]
	v_pk_mul_f32 v[46:47], v[46:47], v[48:49]
	v_pk_mul_f32 v[42:43], v[42:43], v[52:53]
	v_pk_mul_f32 v[40:41], v[40:41], v[54:55]
.LBB0_290:
	v_add_u32_e32 v50, 0x90, v150
	v_mov_b64_e32 v[48:49], s[2:3]
	v_mad_i64_i32 v[48:49], s[24:25], v50, s13, v[48:49]
	v_lshl_add_u64 v[48:49], v[142:143], 1, v[48:49]
	s_and_b64 vcc, exec, s[6:7]
	v_cvt_pk_bf16_f32 v44, v44, v45
	v_cvt_pk_bf16_f32 v45, v46, v47
	v_cvt_pk_bf16_f32 v46, v40, v41
	v_cvt_pk_bf16_f32 v47, v42, v43
	global_store_dwordx4 v[48:49], v[44:47], off
	s_cbranch_vccnz .LBB0_292
	v_pk_mul_f32 v[40:41], v[38:39], v[38:39]
	v_pk_mul_f32 v[42:43], v[36:37], v[36:37]
	v_mov_b32_e32 v44, v138
	v_mov_b32_e32 v45, v138
	v_mov_b32_e32 v46, v140
	v_mov_b32_e32 v47, v140
	v_pk_mul_f32 v[50:51], v[34:35], v[34:35]
	v_pk_mul_f32 v[52:53], v[32:33], v[32:33]
	v_pk_fma_f32 v[40:41], v[46:47], v[40:41], v[44:45]
	v_pk_fma_f32 v[42:43], v[140:141], v[42:43], v[138:139]
	v_pk_fma_f32 v[44:45], v[46:47], v[50:51], v[44:45]
	v_pk_fma_f32 v[46:47], v[140:141], v[52:53], v[138:139]
	v_pk_mul_f32 v[40:41], v[38:39], v[40:41]
	v_pk_mul_f32 v[42:43], v[36:37], v[42:43]
	v_pk_mul_f32 v[44:45], v[34:35], v[44:45]
	v_pk_mul_f32 v[46:47], v[32:33], v[46:47]
	v_exp_f32_e32 v42, v42
	v_exp_f32_e32 v46, v46
	v_exp_f32_e32 v43, v43
	v_exp_f32_e32 v47, v47
	v_exp_f32_e32 v40, v40
	v_exp_f32_e32 v44, v44
	v_exp_f32_e32 v41, v41
	v_exp_f32_e32 v45, v45
	v_add_f32_e32 v42, 1.0, v42
	v_add_f32_e32 v46, 1.0, v46
	v_add_f32_e32 v43, 1.0, v43
	v_add_f32_e32 v47, 1.0, v47
	v_add_f32_e32 v40, 1.0, v40
	v_add_f32_e32 v44, 1.0, v44
	v_add_f32_e32 v41, 1.0, v41
	v_add_f32_e32 v45, 1.0, v45
	v_rcp_f32_e32 v42, v42
	v_rcp_f32_e32 v46, v46
	v_rcp_f32_e32 v43, v43
	v_rcp_f32_e32 v40, v40
	v_rcp_f32_e32 v44, v44
	v_rcp_f32_e32 v41, v41
	v_rcp_f32_e32 v45, v45
	v_rcp_f32_e32 v47, v47
	v_pk_mul_f32 v[36:37], v[36:37], v[42:43]
	v_pk_mul_f32 v[38:39], v[38:39], v[40:41]
	v_pk_mul_f32 v[34:35], v[34:35], v[44:45]
	v_pk_mul_f32 v[32:33], v[32:33], v[46:47]
.LBB0_292:
	s_and_b64 vcc, exec, s[6:7]
	v_cvt_pk_bf16_f32 v36, v36, v37
	v_cvt_pk_bf16_f32 v37, v38, v39
	v_cvt_pk_bf16_f32 v38, v32, v33
	v_cvt_pk_bf16_f32 v39, v34, v35
	global_store_dwordx4 v[48:49], v[36:39], off offset:256
	s_cbranch_vccnz .LBB0_294
	v_pk_mul_f32 v[32:33], v[30:31], v[30:31]
	v_pk_mul_f32 v[34:35], v[28:29], v[28:29]
	v_mov_b32_e32 v36, v138
	v_mov_b32_e32 v37, v138
	v_mov_b32_e32 v38, v140
	v_mov_b32_e32 v39, v140
	v_pk_mul_f32 v[40:41], v[26:27], v[26:27]
	v_pk_mul_f32 v[42:43], v[24:25], v[24:25]
	v_pk_fma_f32 v[32:33], v[38:39], v[32:33], v[36:37]
	v_pk_fma_f32 v[34:35], v[140:141], v[34:35], v[138:139]
	v_pk_fma_f32 v[36:37], v[38:39], v[40:41], v[36:37]
	v_pk_fma_f32 v[38:39], v[140:141], v[42:43], v[138:139]
	v_pk_mul_f32 v[32:33], v[30:31], v[32:33]
	v_pk_mul_f32 v[34:35], v[28:29], v[34:35]
	v_pk_mul_f32 v[36:37], v[26:27], v[36:37]
	v_pk_mul_f32 v[38:39], v[24:25], v[38:39]
	v_exp_f32_e32 v34, v34
	v_exp_f32_e32 v38, v38
	v_exp_f32_e32 v35, v35
	v_exp_f32_e32 v39, v39
	v_exp_f32_e32 v32, v32
	v_exp_f32_e32 v36, v36
	v_exp_f32_e32 v33, v33
	v_exp_f32_e32 v37, v37
	v_add_f32_e32 v34, 1.0, v34
	v_add_f32_e32 v38, 1.0, v38
	v_add_f32_e32 v35, 1.0, v35
	v_add_f32_e32 v39, 1.0, v39
	v_add_f32_e32 v32, 1.0, v32
	v_add_f32_e32 v36, 1.0, v36
	v_add_f32_e32 v33, 1.0, v33
	v_add_f32_e32 v37, 1.0, v37
	v_rcp_f32_e32 v34, v34
	v_rcp_f32_e32 v38, v38
	v_rcp_f32_e32 v35, v35
	v_rcp_f32_e32 v32, v32
	v_rcp_f32_e32 v36, v36
	v_rcp_f32_e32 v33, v33
	v_rcp_f32_e32 v37, v37
	v_rcp_f32_e32 v39, v39
	v_pk_mul_f32 v[28:29], v[28:29], v[34:35]
	v_pk_mul_f32 v[30:31], v[30:31], v[32:33]
	v_pk_mul_f32 v[26:27], v[26:27], v[36:37]
	v_pk_mul_f32 v[24:25], v[24:25], v[38:39]
; __device__ __forceinline__ unsigned cvt_pk_bf16(float lo, float hi) { unsigned r; asm volatile("v_cvt_pk_bf16_f32 %0, %1, %2" : "=v"(r) : "v"(lo), "v"(hi)); return r; }
; #define PG8_BAR __builtin_amdgcn_s_barrier()
;     __device__ __forceinline__ void operator()(const f32x4 (&acc)[2][2][4][2], const Unit& u, int wr, int wc, int fr, int fq) const {
;     ...
;             for (int m = 0; m < 4; ++m) { bf16_t* rowp = O + (size_t)(row0 + ai * HALF + m * 16) * ldc + col0;
; #pragma unroll
;                 for (int bj = 0; bj < 2; ++bj) { f32x4 v0 = acc[ai][bj][m][0], v1 = acc[ai][bj][m][1];
;                     if (act != 0) {
;                         const float k0 = (act == 1) ? -1.5957691216057308f * 1.4426950408889634f : -1.4426950408889634f, k1 = (act == 1) ? -1.5957691216057308f * 0.044715f * 1.4426950408889634f : 0.f;
;                         const f32x4 a0 = v0 * ((v0 * v0) * k1 + k0), a1 = v1 * ((v1 * v1) * k1 + k0); f32x4 r0, r1;
; #pragma unroll
;                         for (int e = 0; e < 4; ++e) { r0[e] = __builtin_amdgcn_rcpf(1.f + __builtin_amdgcn_exp2f(a0[e])); r1[e] = __builtin_amdgcn_rcpf(1.f + __builtin_amdgcn_exp2f(a1[e])); }
;                         v0 = v0 * r0; v1 = v1 * r1; }
;                     u32x4 w; w.x = cvt_pk_bf16(v0[0], v0[1]); w.y = cvt_pk_bf16(v0[2], v0[3]); w.z = cvt_pk_bf16(v1[0], v1[1]); w.w = cvt_pk_bf16(v1[2], v1[3]);
;                     *(u32x4*)(rowp + bj * HALF) = w; } }
; template <class Epi, class Sched, bool ALIGN_EPI = false, bool SP2 = false>
; __device__ __forceinline__ void gemm_phase(PG8_LAS unsigned char* lds, const Gemm g, const Sched& S, const Epi& E) {
;     ...
;         if (!has_next) break;
; #pragma unroll
;         for (int a = 0; a < 2; ++a)
; #pragma unroll
;             for (int b = 0; b < 2; ++b)
; #pragma unroll
;                 for (int m = 0; m < 4; ++m)
; #pragma unroll
;                     for (int n = 0; n < 2; ++n) acc[a][b][m][n] = (f32x4){0.f, 0.f, 0.f, 0.f};
;         cur = nxt; cA = nA; cB = nB; ++ui;
;         if constexpr (ALIGN_EPI) { if (wr == 1) PG8_BAR; }
.LBB0_294:
	v_add_u32_e32 v34, 0xa0, v150
	v_mov_b64_e32 v[32:33], s[2:3]
	v_mad_i64_i32 v[32:33], s[24:25], v34, s13, v[32:33]
	v_lshl_add_u64 v[32:33], v[142:143], 1, v[32:33]
	s_and_b64 vcc, exec, s[6:7]
	v_cvt_pk_bf16_f32 v28, v28, v29
	v_cvt_pk_bf16_f32 v29, v30, v31
	v_cvt_pk_bf16_f32 v30, v24, v25
	v_cvt_pk_bf16_f32 v31, v26, v27
	global_store_dwordx4 v[32:33], v[28:31], off
	s_cbranch_vccnz .LBB0_296
	v_pk_mul_f32 v[24:25], v[22:23], v[22:23]
	v_pk_mul_f32 v[26:27], v[20:21], v[20:21]
	v_mov_b32_e32 v28, v138
	v_mov_b32_e32 v29, v138
	v_mov_b32_e32 v30, v140
	v_mov_b32_e32 v31, v140
	v_pk_mul_f32 v[34:35], v[18:19], v[18:19]
	v_pk_mul_f32 v[36:37], v[16:17], v[16:17]
	v_pk_fma_f32 v[24:25], v[30:31], v[24:25], v[28:29]
	v_pk_fma_f32 v[26:27], v[140:141], v[26:27], v[138:139]
	v_pk_fma_f32 v[28:29], v[30:31], v[34:35], v[28:29]
	v_pk_fma_f32 v[30:31], v[140:141], v[36:37], v[138:139]
	v_pk_mul_f32 v[24:25], v[22:23], v[24:25]
	v_pk_mul_f32 v[26:27], v[20:21], v[26:27]
	v_pk_mul_f32 v[28:29], v[18:19], v[28:29]
	v_pk_mul_f32 v[30:31], v[16:17], v[30:31]
	v_exp_f32_e32 v26, v26
	v_exp_f32_e32 v30, v30
	v_exp_f32_e32 v27, v27
	v_exp_f32_e32 v31, v31
	v_exp_f32_e32 v24, v24
	v_exp_f32_e32 v28, v28
	v_exp_f32_e32 v25, v25
	v_exp_f32_e32 v29, v29
	v_add_f32_e32 v26, 1.0, v26
	v_add_f32_e32 v30, 1.0, v30
	v_add_f32_e32 v27, 1.0, v27
	v_add_f32_e32 v31, 1.0, v31
	v_add_f32_e32 v24, 1.0, v24
	v_add_f32_e32 v28, 1.0, v28
	v_add_f32_e32 v25, 1.0, v25
	v_add_f32_e32 v29, 1.0, v29
	v_rcp_f32_e32 v26, v26
	v_rcp_f32_e32 v30, v30
	v_rcp_f32_e32 v27, v27
	v_rcp_f32_e32 v24, v24
	v_rcp_f32_e32 v28, v28
	v_rcp_f32_e32 v25, v25
	v_rcp_f32_e32 v29, v29
	v_rcp_f32_e32 v31, v31
	v_pk_mul_f32 v[20:21], v[20:21], v[26:27]
	v_pk_mul_f32 v[22:23], v[22:23], v[24:25]
	v_pk_mul_f32 v[18:19], v[18:19], v[28:29]
	v_pk_mul_f32 v[16:17], v[16:17], v[30:31]
.LBB0_296:
	s_and_b64 vcc, exec, s[6:7]
	v_cvt_pk_bf16_f32 v20, v20, v21
	v_cvt_pk_bf16_f32 v21, v22, v23
	v_cvt_pk_bf16_f32 v22, v16, v17
	v_cvt_pk_bf16_f32 v23, v18, v19
	global_store_dwordx4 v[32:33], v[20:23], off offset:256
	s_cbranch_vccnz .LBB0_298
	v_pk_mul_f32 v[16:17], v[14:15], v[14:15]
	v_pk_mul_f32 v[18:19], v[12:13], v[12:13]
	v_mov_b32_e32 v20, v138
	v_mov_b32_e32 v21, v138
	v_mov_b32_e32 v22, v140
	v_mov_b32_e32 v23, v140
	v_pk_mul_f32 v[24:25], v[10:11], v[10:11]
	v_pk_mul_f32 v[26:27], v[8:9], v[8:9]
	v_pk_fma_f32 v[16:17], v[22:23], v[16:17], v[20:21]
	v_pk_fma_f32 v[18:19], v[140:141], v[18:19], v[138:139]
	v_pk_fma_f32 v[20:21], v[22:23], v[24:25], v[20:21]
	v_pk_fma_f32 v[22:23], v[140:141], v[26:27], v[138:139]
	v_pk_mul_f32 v[16:17], v[14:15], v[16:17]
	v_pk_mul_f32 v[18:19], v[12:13], v[18:19]
	v_pk_mul_f32 v[20:21], v[10:11], v[20:21]
	v_pk_mul_f32 v[22:23], v[8:9], v[22:23]
	v_exp_f32_e32 v18, v18
	v_exp_f32_e32 v22, v22
	v_exp_f32_e32 v19, v19
	v_exp_f32_e32 v23, v23
	v_exp_f32_e32 v16, v16
	v_exp_f32_e32 v20, v20
	v_exp_f32_e32 v17, v17
	v_exp_f32_e32 v21, v21
	v_add_f32_e32 v18, 1.0, v18
	v_add_f32_e32 v22, 1.0, v22
	v_add_f32_e32 v19, 1.0, v19
	v_add_f32_e32 v23, 1.0, v23
	v_add_f32_e32 v16, 1.0, v16
	v_add_f32_e32 v20, 1.0, v20
	v_add_f32_e32 v17, 1.0, v17
	v_add_f32_e32 v21, 1.0, v21
	v_rcp_f32_e32 v18, v18
	v_rcp_f32_e32 v22, v22
	v_rcp_f32_e32 v19, v19
	v_rcp_f32_e32 v16, v16
	v_rcp_f32_e32 v20, v20
	v_rcp_f32_e32 v17, v17
	v_rcp_f32_e32 v21, v21
	v_rcp_f32_e32 v23, v23
	v_pk_mul_f32 v[12:13], v[12:13], v[18:19]
	v_pk_mul_f32 v[14:15], v[14:15], v[16:17]
	v_pk_mul_f32 v[10:11], v[10:11], v[20:21]
	v_pk_mul_f32 v[8:9], v[8:9], v[22:23]
.LBB0_298:
	v_add_u32_e32 v18, 0xb0, v150
	v_mov_b64_e32 v[16:17], s[2:3]
	v_mad_i64_i32 v[16:17], s[24:25], v18, s13, v[16:17]
	v_lshl_add_u64 v[16:17], v[142:143], 1, v[16:17]
	s_and_b64 vcc, exec, s[6:7]
	v_cvt_pk_bf16_f32 v12, v12, v13
	v_cvt_pk_bf16_f32 v13, v14, v15
	v_cvt_pk_bf16_f32 v14, v8, v9
	v_cvt_pk_bf16_f32 v15, v10, v11
	global_store_dwordx4 v[16:17], v[12:15], off
	s_cbranch_vccnz .LBB0_300
	v_pk_mul_f32 v[8:9], v[6:7], v[6:7]
	v_pk_mul_f32 v[10:11], v[4:5], v[4:5]
	v_mov_b32_e32 v12, v138
	v_mov_b32_e32 v13, v138
	v_mov_b32_e32 v14, v140
	v_mov_b32_e32 v15, v140
	v_pk_mul_f32 v[18:19], v[2:3], v[2:3]
	v_pk_mul_f32 v[20:21], v[0:1], v[0:1]
	v_pk_fma_f32 v[8:9], v[14:15], v[8:9], v[12:13]
	v_pk_fma_f32 v[10:11], v[140:141], v[10:11], v[138:139]
	v_pk_fma_f32 v[12:13], v[14:15], v[18:19], v[12:13]
	v_pk_fma_f32 v[14:15], v[140:141], v[20:21], v[138:139]
	v_pk_mul_f32 v[8:9], v[6:7], v[8:9]
	v_pk_mul_f32 v[10:11], v[4:5], v[10:11]
	v_pk_mul_f32 v[12:13], v[2:3], v[12:13]
	v_pk_mul_f32 v[14:15], v[0:1], v[14:15]
	v_exp_f32_e32 v10, v10
	v_exp_f32_e32 v14, v14
	v_exp_f32_e32 v11, v11
	v_exp_f32_e32 v15, v15
	v_exp_f32_e32 v8, v8
	v_exp_f32_e32 v12, v12
	v_exp_f32_e32 v9, v9
	v_exp_f32_e32 v13, v13
	v_add_f32_e32 v10, 1.0, v10
	v_add_f32_e32 v14, 1.0, v14
	v_add_f32_e32 v11, 1.0, v11
	v_add_f32_e32 v15, 1.0, v15
	v_add_f32_e32 v8, 1.0, v8
	v_add_f32_e32 v12, 1.0, v12
	v_add_f32_e32 v9, 1.0, v9
	v_add_f32_e32 v13, 1.0, v13
	v_rcp_f32_e32 v10, v10
	v_rcp_f32_e32 v14, v14
	v_rcp_f32_e32 v11, v11
	v_rcp_f32_e32 v8, v8
	v_rcp_f32_e32 v12, v12
	v_rcp_f32_e32 v9, v9
	v_rcp_f32_e32 v13, v13
	v_rcp_f32_e32 v15, v15
	v_pk_mul_f32 v[4:5], v[4:5], v[10:11]
	v_pk_mul_f32 v[6:7], v[6:7], v[8:9]
	v_pk_mul_f32 v[2:3], v[2:3], v[12:13]
	v_pk_mul_f32 v[0:1], v[0:1], v[14:15]
.LBB0_300:
	s_andn2_b64 vcc, exec, s[4:5]
	s_mov_b64 s[4:5], -1
	v_cvt_pk_bf16_f32 v4, v4, v5
	v_cvt_pk_bf16_f32 v5, v6, v7
	v_cvt_pk_bf16_f32 v6, v0, v1
	v_cvt_pk_bf16_f32 v7, v2, v3
	global_store_dwordx4 v[16:17], v[4:7], off offset:256
	s_cbranch_vccnz .LBB0_261
	s_andn2_b64 vcc, exec, s[0:1]
	s_cbranch_vccnz .LBB0_260
	s_barrier
	s_branch .LBB0_260

; __device__ __forceinline__ unsigned cvt_pk_bf16(float lo, float hi) { unsigned r; asm volatile("v_cvt_pk_bf16_f32 %0, %1, %2" : "=v"(r) : "v"(lo), "v"(hi)); return r; }
;     __device__ __forceinline__ void operator()(const f32x4 (&acc)[2][2][4][2], const Unit& u, int wr, int wc, int fr, int fq) const {
;     ...
;             for (int m = 0; m < 4; ++m) { bf16_t* rowp = O + (size_t)(row0 + ai * HALF + m * 16) * ldc + col0;
; #pragma unroll
;                 for (int bj = 0; bj < 2; ++bj) { f32x4 v0 = acc[ai][bj][m][0], v1 = acc[ai][bj][m][1];
;                     if (act != 0) {
;                         const float k0 = (act == 1) ? -1.5957691216057308f * 1.4426950408889634f : -1.4426950408889634f, k1 = (act == 1) ? -1.5957691216057308f * 0.044715f * 1.4426950408889634f : 0.f;
;                         const f32x4 a0 = v0 * ((v0 * v0) * k1 + k0), a1 = v1 * ((v1 * v1) * k1 + k0); f32x4 r0, r1;
; #pragma unroll
;                         for (int e = 0; e < 4; ++e) { r0[e] = __builtin_amdgcn_rcpf(1.f + __builtin_amdgcn_exp2f(a0[e])); r1[e] = __builtin_amdgcn_rcpf(1.f + __builtin_amdgcn_exp2f(a1[e])); }
;                         v0 = v0 * r0; v1 = v1 * r1; }
;                     u32x4 w; w.x = cvt_pk_bf16(v0[0], v0[1]); w.y = cvt_pk_bf16(v0[2], v0[3]); w.z = cvt_pk_bf16(v1[0], v1[1]); w.w = cvt_pk_bf16(v1[2], v1[3]);
;                     *(u32x4*)(rowp + bj * HALF) = w; } }
.LBB0_320:
	v_lshl_add_u32 v144, s58, 8, v140
	v_lshl_or_b32 v138, s57, 8, v142
	v_ashrrev_i32_e32 v145, 31, v144
	v_ashrrev_i32_e32 v139, 31, v138
	v_lshlrev_b64 v[146:147], 14, v[144:145]
	v_lshl_add_u64 v[146:147], s[2:3], 0, v[146:147]
	v_lshlrev_b64 v[148:149], 1, v[138:139]
	v_lshl_add_u64 v[138:139], v[146:147], 0, v[148:149]
	v_cvt_pk_bf16_f32 v124, v124, v125
	v_cvt_pk_bf16_f32 v125, v126, v127
	v_cvt_pk_bf16_f32 v126, v120, v121
	v_cvt_pk_bf16_f32 v127, v122, v123
	global_store_dwordx4 v[138:139], v[124:127], off
	v_cvt_pk_bf16_f32 v112, v112, v113
	v_cvt_pk_bf16_f32 v113, v114, v115
	v_cvt_pk_bf16_f32 v114, v104, v105
	v_or_b32_e32 v104, 16, v144
	v_ashrrev_i32_e32 v105, 31, v104
	v_lshlrev_b64 v[104:105], 14, v[104:105]
	v_lshl_add_u64 v[104:105], s[2:3], 0, v[104:105]
	v_cvt_pk_bf16_f32 v115, v106, v107
	global_store_dwordx4 v[138:139], v[112:115], off offset:256
	s_mov_b32 s15, 0x200000
	s_mov_b64 s[40:41], 0x200000
	v_lshl_add_u64 v[112:113], v[104:105], 0, v[148:149]
	v_cvt_pk_bf16_f32 v104, v116, v117
	v_cvt_pk_bf16_f32 v105, v118, v119
	v_cvt_pk_bf16_f32 v106, v108, v109
	v_cvt_pk_bf16_f32 v107, v110, v111
	global_store_dwordx4 v[112:113], v[104:107], off
	v_cvt_pk_bf16_f32 v96, v96, v97
	v_cvt_pk_bf16_f32 v97, v98, v99
	v_cvt_pk_bf16_f32 v98, v88, v89
	v_or_b32_e32 v88, 32, v144
	v_ashrrev_i32_e32 v89, 31, v88
	v_lshlrev_b64 v[88:89], 14, v[88:89]
	v_lshl_add_u64 v[88:89], s[2:3], 0, v[88:89]
	v_cvt_pk_bf16_f32 v99, v90, v91
	global_store_dwordx4 v[112:113], v[96:99], off offset:256
	s_nop 1
	v_lshl_add_u64 v[96:97], v[88:89], 0, v[148:149]
	v_cvt_pk_bf16_f32 v88, v100, v101
	v_cvt_pk_bf16_f32 v89, v102, v103
	v_cvt_pk_bf16_f32 v90, v92, v93
	v_cvt_pk_bf16_f32 v91, v94, v95
	global_store_dwordx4 v[96:97], v[88:91], off
	v_cvt_pk_bf16_f32 v80, v80, v81
	v_cvt_pk_bf16_f32 v81, v82, v83
	v_cvt_pk_bf16_f32 v82, v72, v73
	v_or_b32_e32 v72, 48, v144
	v_ashrrev_i32_e32 v73, 31, v72
	v_lshlrev_b64 v[72:73], 14, v[72:73]
	v_lshl_add_u64 v[72:73], s[2:3], 0, v[72:73]
	v_cvt_pk_bf16_f32 v83, v74, v75
	global_store_dwordx4 v[96:97], v[80:83], off offset:256
	s_nop 1
	v_lshl_add_u64 v[80:81], v[72:73], 0, v[148:149]
	v_cvt_pk_bf16_f32 v72, v84, v85
	v_cvt_pk_bf16_f32 v73, v86, v87
	v_cvt_pk_bf16_f32 v74, v76, v77
	v_cvt_pk_bf16_f32 v75, v78, v79
	global_store_dwordx4 v[80:81], v[72:75], off
	v_cvt_pk_bf16_f32 v68, v68, v69
	v_cvt_pk_bf16_f32 v69, v70, v71
	v_cvt_pk_bf16_f32 v70, v64, v65
	v_cvt_pk_bf16_f32 v71, v66, v67
	global_store_dwordx4 v[80:81], v[68:71], off offset:256
	v_cvt_pk_bf16_f32 v60, v60, v61
	v_cvt_pk_bf16_f32 v61, v62, v63
	v_cvt_pk_bf16_f32 v62, v56, v57
	v_add_co_u32_e32 v56, vcc, s15, v138
	v_lshl_add_u64 v[64:65], v[138:139], 0, s[40:41]
	s_nop 0
	v_addc_co_u32_e32 v57, vcc, 0, v139, vcc
	s_mov_b32 s15, 0x240000
	v_cvt_pk_bf16_f32 v63, v58, v59
	global_store_dwordx4 v[56:57], v[60:63], off
	v_cvt_pk_bf16_f32 v48, v48, v49
	v_cvt_pk_bf16_f32 v49, v50, v51
	v_cvt_pk_bf16_f32 v50, v40, v41
	v_cvt_pk_bf16_f32 v51, v42, v43
	global_store_dwordx4 v[64:65], v[48:51], off offset:256
	s_mov_b64 s[40:41], 0x240000
	v_cvt_pk_bf16_f32 v40, v52, v53
	v_cvt_pk_bf16_f32 v41, v54, v55
	v_cvt_pk_bf16_f32 v42, v44, v45
	v_add_co_u32_e32 v44, vcc, s15, v138
	v_lshl_add_u64 v[48:49], v[138:139], 0, s[40:41]
	s_nop 0
	v_addc_co_u32_e32 v45, vcc, 0, v139, vcc
	s_mov_b32 s15, 0x280000
	v_cvt_pk_bf16_f32 v43, v46, v47
	global_store_dwordx4 v[44:45], v[40:43], off
	v_cvt_pk_bf16_f32 v32, v32, v33
	v_cvt_pk_bf16_f32 v33, v34, v35
	v_cvt_pk_bf16_f32 v34, v24, v25
	v_cvt_pk_bf16_f32 v35, v26, v27
	global_store_dwordx4 v[48:49], v[32:35], off offset:256
	s_mov_b64 s[40:41], 0x280000
	v_cvt_pk_bf16_f32 v24, v36, v37
	v_cvt_pk_bf16_f32 v25, v38, v39
	v_cvt_pk_bf16_f32 v26, v28, v29
	v_add_co_u32_e32 v28, vcc, s15, v138
	v_lshl_add_u64 v[32:33], v[138:139], 0, s[40:41]
	s_nop 0
	v_addc_co_u32_e32 v29, vcc, 0, v139, vcc
	s_mov_b32 s15, 0x2c0000
	v_cvt_pk_bf16_f32 v27, v30, v31
	global_store_dwordx4 v[28:29], v[24:27], off
	v_cvt_pk_bf16_f32 v16, v16, v17
	v_cvt_pk_bf16_f32 v17, v18, v19
	v_cvt_pk_bf16_f32 v18, v8, v9
	v_cvt_pk_bf16_f32 v19, v10, v11
	global_store_dwordx4 v[32:33], v[16:19], off offset:256
	v_cvt_pk_bf16_f32 v8, v20, v21
	v_cvt_pk_bf16_f32 v9, v22, v23
	v_cvt_pk_bf16_f32 v10, v12, v13
	v_add_co_u32_e32 v12, vcc, s15, v138
	s_mov_b64 s[40:41], 0x2c0000
	s_nop 0
	v_addc_co_u32_e32 v13, vcc, 0, v139, vcc
	v_lshl_add_u64 v[16:17], v[138:139], 0, s[40:41]
	s_andn2_b64 vcc, exec, s[6:7]
	s_mov_b64 s[6:7], -1
	v_cvt_pk_bf16_f32 v11, v14, v15
	global_store_dwordx4 v[12:13], v[8:11], off
	v_cvt_pk_bf16_f32 v4, v4, v5
	v_cvt_pk_bf16_f32 v5, v6, v7
	v_cvt_pk_bf16_f32 v6, v0, v1
	v_cvt_pk_bf16_f32 v7, v2, v3
	global_store_dwordx4 v[16:17], v[4:7], off offset:256
	s_cbranch_vccnz .LBB0_309
	s_andn2_b64 vcc, exec, s[0:1]
	s_cbranch_vccnz .LBB0_308
	s_barrier
	s_branch .LBB0_308

; __device__ __forceinline__ unsigned cvt_pk_bf16(float lo, float hi) { unsigned r; asm volatile("v_cvt_pk_bf16_f32 %0, %1, %2" : "=v"(r) : "v"(lo), "v"(hi)); return r; }
;     __device__ __forceinline__ void operator()(const f32x4 (&acc)[2][2][4][2], const Unit& u, int wr, int wc, int fr, int fq) const {
;     ...
;             for (int m = 0; m < 4; ++m) { bf16_t* rowp = O + (size_t)(row0 + ai * HALF + m * 16) * ldc + col0;
; #pragma unroll
;                 for (int bj = 0; bj < 2; ++bj) { f32x4 v0 = acc[ai][bj][m][0], v1 = acc[ai][bj][m][1];
;                     if (act != 0) {
;                         const float k0 = (act == 1) ? -1.5957691216057308f * 1.4426950408889634f : -1.4426950408889634f, k1 = (act == 1) ? -1.5957691216057308f * 0.044715f * 1.4426950408889634f : 0.f;
;                         const f32x4 a0 = v0 * ((v0 * v0) * k1 + k0), a1 = v1 * ((v1 * v1) * k1 + k0); f32x4 r0, r1;
; #pragma unroll
;                         for (int e = 0; e < 4; ++e) { r0[e] = __builtin_amdgcn_rcpf(1.f + __builtin_amdgcn_exp2f(a0[e])); r1[e] = __builtin_amdgcn_rcpf(1.f + __builtin_amdgcn_exp2f(a1[e])); }
;                         v0 = v0 * r0; v1 = v1 * r1; }
;                     u32x4 w; w.x = cvt_pk_bf16(v0[0], v0[1]); w.y = cvt_pk_bf16(v0[2], v0[3]); w.z = cvt_pk_bf16(v1[0], v1[1]); w.w = cvt_pk_bf16(v1[2], v1[3]);
;                     *(u32x4*)(rowp + bj * HALF) = w; } }
.LBB0_340:
	v_lshl_add_u32 v140, s68, 8, v136
	v_lshl_or_b32 v134, s67, 8, v138
	v_ashrrev_i32_e32 v141, 31, v140
	v_ashrrev_i32_e32 v135, 31, v134
	v_lshlrev_b64 v[142:143], 12, v[140:141]
	v_lshl_add_u64 v[142:143], s[2:3], 0, v[142:143]
	v_lshlrev_b64 v[144:145], 1, v[134:135]
	v_lshl_add_u64 v[134:135], v[142:143], 0, v[144:145]
	v_cvt_pk_bf16_f32 v124, v124, v125
	v_cvt_pk_bf16_f32 v125, v126, v127
	v_cvt_pk_bf16_f32 v126, v120, v121
	v_cvt_pk_bf16_f32 v127, v122, v123
	global_store_dwordx4 v[134:135], v[124:127], off
	v_cvt_pk_bf16_f32 v112, v112, v113
	v_cvt_pk_bf16_f32 v113, v114, v115
	v_cvt_pk_bf16_f32 v114, v104, v105
	v_or_b32_e32 v104, 16, v140
	v_ashrrev_i32_e32 v105, 31, v104
	v_lshlrev_b64 v[104:105], 12, v[104:105]
	v_lshl_add_u64 v[104:105], s[2:3], 0, v[104:105]
	v_cvt_pk_bf16_f32 v115, v106, v107
	global_store_dwordx4 v[134:135], v[112:115], off offset:256
	s_mov_b32 s15, 0x80000
	s_mov_b64 s[74:75], 0x80000
	v_lshl_add_u64 v[112:113], v[104:105], 0, v[144:145]
	v_cvt_pk_bf16_f32 v104, v116, v117
	v_cvt_pk_bf16_f32 v105, v118, v119
	v_cvt_pk_bf16_f32 v106, v108, v109
	v_cvt_pk_bf16_f32 v107, v110, v111
	global_store_dwordx4 v[112:113], v[104:107], off
	v_cvt_pk_bf16_f32 v96, v96, v97
	v_cvt_pk_bf16_f32 v97, v98, v99
	v_cvt_pk_bf16_f32 v98, v88, v89
	v_or_b32_e32 v88, 32, v140
	v_ashrrev_i32_e32 v89, 31, v88
	v_lshlrev_b64 v[88:89], 12, v[88:89]
	v_lshl_add_u64 v[88:89], s[2:3], 0, v[88:89]
	v_cvt_pk_bf16_f32 v99, v90, v91
	global_store_dwordx4 v[112:113], v[96:99], off offset:256
	s_mov_b64 s[38:39], 0x90000
	s_mov_b32 s71, 0xe000
	v_lshl_add_u64 v[96:97], v[88:89], 0, v[144:145]
	v_cvt_pk_bf16_f32 v88, v100, v101
	v_cvt_pk_bf16_f32 v89, v102, v103
	v_cvt_pk_bf16_f32 v90, v92, v93
	v_cvt_pk_bf16_f32 v91, v94, v95
	global_store_dwordx4 v[96:97], v[88:91], off
	v_cvt_pk_bf16_f32 v80, v80, v81
	v_cvt_pk_bf16_f32 v81, v82, v83
	v_cvt_pk_bf16_f32 v82, v72, v73
	v_or_b32_e32 v72, 48, v140
	v_ashrrev_i32_e32 v73, 31, v72
	v_lshlrev_b64 v[72:73], 12, v[72:73]
	v_lshl_add_u64 v[72:73], s[2:3], 0, v[72:73]
	v_cvt_pk_bf16_f32 v83, v74, v75
	global_store_dwordx4 v[96:97], v[80:83], off offset:256
	s_mov_b32 s72, 0x42a00000
	s_nop 0
	v_lshl_add_u64 v[80:81], v[72:73], 0, v[144:145]
	v_cvt_pk_bf16_f32 v72, v84, v85
	v_cvt_pk_bf16_f32 v73, v86, v87
	v_cvt_pk_bf16_f32 v74, v76, v77
	v_cvt_pk_bf16_f32 v75, v78, v79
	global_store_dwordx4 v[80:81], v[72:75], off
	v_cvt_pk_bf16_f32 v68, v68, v69
	v_cvt_pk_bf16_f32 v69, v70, v71
	v_cvt_pk_bf16_f32 v70, v64, v65
	v_cvt_pk_bf16_f32 v71, v66, v67
	global_store_dwordx4 v[80:81], v[68:71], off offset:256
	v_cvt_pk_bf16_f32 v60, v60, v61
	v_cvt_pk_bf16_f32 v61, v62, v63
	v_cvt_pk_bf16_f32 v62, v56, v57
	v_add_co_u32_e32 v56, vcc, s15, v134
	v_lshl_add_u64 v[64:65], v[134:135], 0, s[74:75]
	s_nop 0
	v_addc_co_u32_e32 v57, vcc, 0, v135, vcc
	s_mov_b32 s15, 0x90000
	v_cvt_pk_bf16_f32 v63, v58, v59
	global_store_dwordx4 v[56:57], v[60:63], off
	v_cvt_pk_bf16_f32 v48, v48, v49
	v_cvt_pk_bf16_f32 v49, v50, v51
	v_cvt_pk_bf16_f32 v50, v40, v41
	v_cvt_pk_bf16_f32 v51, v42, v43
	global_store_dwordx4 v[64:65], v[48:51], off offset:256
	v_cvt_pk_bf16_f32 v40, v52, v53
	v_cvt_pk_bf16_f32 v41, v54, v55
	v_cvt_pk_bf16_f32 v42, v44, v45
	v_add_co_u32_e32 v44, vcc, s15, v134
	s_nop 0
	v_lshl_add_u64 v[48:49], v[134:135], 0, s[38:39]
	v_addc_co_u32_e32 v45, vcc, 0, v135, vcc
	s_mov_b32 s15, 0xa0000
	v_cvt_pk_bf16_f32 v43, v46, v47
	global_store_dwordx4 v[44:45], v[40:43], off
	v_cvt_pk_bf16_f32 v32, v32, v33
	v_cvt_pk_bf16_f32 v33, v34, v35
	v_cvt_pk_bf16_f32 v34, v24, v25
	v_cvt_pk_bf16_f32 v35, v26, v27
	global_store_dwordx4 v[48:49], v[32:35], off offset:256
	s_mov_b64 s[38:39], 0xa0000
	v_cvt_pk_bf16_f32 v24, v36, v37
	v_cvt_pk_bf16_f32 v25, v38, v39
	v_cvt_pk_bf16_f32 v26, v28, v29
	v_add_co_u32_e32 v28, vcc, s15, v134
	v_lshl_add_u64 v[32:33], v[134:135], 0, s[38:39]
	s_nop 0
	v_addc_co_u32_e32 v29, vcc, 0, v135, vcc
	s_mov_b32 s15, 0xb0000
	v_cvt_pk_bf16_f32 v27, v30, v31
	global_store_dwordx4 v[28:29], v[24:27], off
	v_cvt_pk_bf16_f32 v16, v16, v17
	v_cvt_pk_bf16_f32 v17, v18, v19
	v_cvt_pk_bf16_f32 v18, v8, v9
	v_cvt_pk_bf16_f32 v19, v10, v11
	global_store_dwordx4 v[32:33], v[16:19], off offset:256
	v_cvt_pk_bf16_f32 v8, v20, v21
	v_cvt_pk_bf16_f32 v9, v22, v23
	v_cvt_pk_bf16_f32 v10, v12, v13
	v_add_co_u32_e32 v12, vcc, s15, v134
	s_mov_b64 s[38:39], 0xb0000
	s_nop 0
	v_addc_co_u32_e32 v13, vcc, 0, v135, vcc
	v_lshl_add_u64 v[16:17], v[134:135], 0, s[38:39]
	s_andn2_b64 vcc, exec, s[4:5]
	s_mov_b64 s[4:5], -1
	v_cvt_pk_bf16_f32 v11, v14, v15
	global_store_dwordx4 v[12:13], v[8:11], off
	v_cvt_pk_bf16_f32 v4, v4, v5
	v_cvt_pk_bf16_f32 v5, v6, v7
	v_cvt_pk_bf16_f32 v6, v0, v1
	v_cvt_pk_bf16_f32 v7, v2, v3
	global_store_dwordx4 v[16:17], v[4:7], off offset:256
	s_cbranch_vccnz .LBB0_329
	s_andn2_b64 vcc, exec, s[0:1]
	s_cbranch_vccnz .LBB0_328
	s_barrier
	s_branch .LBB0_328

; __device__ __forceinline__ void p0_transpose_item(const float* W, int K, int N, bf16* WT, float* scr, int item, int lane, const float* scale, const float* cb, float* c1, float* c2) {
;     const int nblk = N / 64, kb = item / nblk, nb = item % nblk, k0 = 64 * kb, n0 = 64 * nb;
;     const int lr = lane >> 4, lc = (lane & 15) * 4;
;     f32x4 v[16];
; #pragma unroll
;     for (int i = 0; i < 16; ++i) v[i] = *(const f32x4*)(W + (size_t)(k0 + 4 * i + lr) * N + n0 + lc);
; #pragma unroll
;     for (int i = 0; i < 16; ++i) { const int kk = 4 * i + lr; f32x4 w = v[i]; if (scale) w = w * scale[k0 + kk]; float* d = scr + kk * 65 + lc; d[0] = w[0]; d[1] = w[1]; d[2] = w[2]; d[3] = w[3]; }
.LBB0_430:
	s_mul_hi_i32 s0, s26, 0xae4c415d
	s_add_i32 s0, s0, s26
	s_lshr_b32 s1, s0, 31
	s_ashr_i32 s0, s0, 12
	s_add_i32 s0, s0, s1
	s_mul_i32 s1, s0, 0x1780
	s_sub_i32 s47, s26, s1
	s_cmpk_gt_i32 s47, 0xeff
	s_mov_b64 s[2:3], -1
	s_cbranch_scc0 .LBB0_466
	s_cmpk_gt_u32 s47, 0x12ff
	s_cbranch_scc0 .LBB0_463
	s_ashr_i32 s1, s0, 31
	s_cmpk_gt_u32 s47, 0x16ff
	s_cbranch_scc0 .LBB0_434
	v_readlane_b32 s48, v253, 18
	s_lshl_b64 s[2:3], s[0:1], 21
	v_readlane_b32 s62, v253, 32
	v_readlane_b32 s63, v253, 33
	s_add_u32 s4, s62, s2
	s_addc_u32 s5, s63, s3
	s_lshl_b64 s[2:3], s[0:1], 20
	s_add_u32 s6, s41, s2
	s_addc_u32 s3, s42, s3
	s_lshl_b32 s2, s47, 1
	s_and_b32 s7, s2, 0x1c0
	s_lshl_b32 s2, s47, 6
	s_and_b32 s2, s2, 0x7c0
	s_lshl_b32 s14, s2, 2
	s_add_u32 s4, s4, s14
	v_or_b32_e32 v2, s7, v69
	s_addc_u32 s5, s5, 0
	v_lshlrev_b32_e32 v168, 2, v68
	v_lshl_add_u64 v[0:1], s[4:5], 0, v[168:169]
	v_lshlrev_b32_e32 v168, 13, v2
	v_lshl_add_u64 v[60:61], v[0:1], 0, v[168:169]
	v_add_co_u32_e32 v4, vcc, s90, v60
	s_mov_b32 s4, 0x20000
	s_nop 0
	v_addc_co_u32_e32 v5, vcc, 0, v61, vcc
	v_add_co_u32_e32 v8, vcc, s88, v60
	global_load_dwordx4 v[0:3], v[60:61], off
	s_nop 0
	global_load_dwordx4 v[4:7], v[4:5], off
	v_addc_co_u32_e32 v9, vcc, 0, v61, vcc
	v_add_co_u32_e32 v12, vcc, s85, v60
	v_lshlrev_b32_e32 v168, 1, v70
	s_nop 0
	v_addc_co_u32_e32 v13, vcc, 0, v61, vcc
	global_load_dwordx4 v[8:11], v[8:9], off
	s_nop 0
	global_load_dwordx4 v[12:15], v[12:13], off
	v_add_co_u32_e32 v16, vcc, s4, v60
	s_mov_b32 s4, 0x28000
	s_nop 0
	v_addc_co_u32_e32 v17, vcc, 0, v61, vcc
	v_add_co_u32_e32 v20, vcc, s4, v60
	s_mov_b32 s4, 0x30000
	s_nop 0
	v_addc_co_u32_e32 v21, vcc, 0, v61, vcc
	global_load_dwordx4 v[16:19], v[16:17], off
	s_nop 0
	global_load_dwordx4 v[20:23], v[20:21], off
	v_add_co_u32_e32 v24, vcc, s4, v60
	s_mov_b32 s4, 0x38000
	s_nop 0
	v_addc_co_u32_e32 v25, vcc, 0, v61, vcc
	v_add_co_u32_e32 v28, vcc, s4, v60
	s_mov_b32 s4, 0x40000
	s_nop 0
	v_addc_co_u32_e32 v29, vcc, 0, v61, vcc
	global_load_dwordx4 v[24:27], v[24:25], off
	s_nop 0
	global_load_dwordx4 v[28:31], v[28:29], off
	v_add_co_u32_e32 v32, vcc, s4, v60
	s_mov_b32 s4, 0x48000
	s_nop 0
	v_addc_co_u32_e32 v33, vcc, 0, v61, vcc
	v_add_co_u32_e32 v36, vcc, s4, v60
	s_mov_b32 s4, 0x50000
	s_nop 0
	v_addc_co_u32_e32 v37, vcc, 0, v61, vcc
	global_load_dwordx4 v[32:35], v[32:33], off
	s_nop 0
	global_load_dwordx4 v[36:39], v[36:37], off
	v_add_co_u32_e32 v40, vcc, s4, v60
	s_mov_b32 s4, 0x58000
	s_nop 0
	v_addc_co_u32_e32 v41, vcc, 0, v61, vcc
	v_add_co_u32_e32 v44, vcc, s4, v60
	s_mov_b32 s4, 0x60000
	s_nop 0
	v_addc_co_u32_e32 v45, vcc, 0, v61, vcc
	global_load_dwordx4 v[40:43], v[40:41], off
	s_nop 0
	global_load_dwordx4 v[44:47], v[44:45], off
	v_add_co_u32_e32 v48, vcc, s4, v60
	s_mov_b32 s4, 0x68000
	s_nop 0
	v_addc_co_u32_e32 v49, vcc, 0, v61, vcc
	global_load_dwordx4 v[48:51], v[48:49], off
	v_add_co_u32_e32 v52, vcc, s4, v60
	s_mov_b32 s4, 0x70000
	s_nop 0
	v_addc_co_u32_e32 v53, vcc, 0, v61, vcc
	global_load_dwordx4 v[52:55], v[52:53], off
	v_add_co_u32_e32 v56, vcc, s4, v60
	s_mov_b32 s4, 0x78000
	s_nop 0
	v_addc_co_u32_e32 v57, vcc, 0, v61, vcc
	global_load_dwordx4 v[56:59], v[56:57], off
	v_add_co_u32_e32 v60, vcc, s4, v60
	s_lshl_b32 s4, s7, 1
	s_nop 0
	v_addc_co_u32_e32 v61, vcc, 0, v61, vcc
	global_load_dwordx4 v[60:63], v[60:61], off
	s_waitcnt vmcnt(0)
	ds_write2_b32 v71, v0, v1 offset1:1
	ds_write2_b32 v71, v2, v3 offset0:2 offset1:3
	v_add_u32_e32 v0, 0x410, v71
	s_waitcnt vmcnt(14)
	ds_write2_b32 v0, v4, v5 offset1:1
	v_add_u32_e32 v0, 0x418, v71
	ds_write2_b32 v0, v6, v7 offset1:1
	v_add_u32_e32 v0, 0x820, v71
	s_add_u32 s4, s6, s4
	s_addc_u32 s5, s3, 0
	s_waitcnt vmcnt(13)
	ds_write2_b32 v0, v8, v9 offset1:1
	v_add_u32_e32 v0, 0x828, v71
	ds_write2_b32 v0, v10, v11 offset1:1
	v_add_u32_e32 v0, 0xc30, v71
	s_waitcnt vmcnt(12)
	ds_write2_b32 v0, v12, v13 offset1:1
	v_add_u32_e32 v0, 0xc38, v71
	ds_write2_b32 v0, v14, v15 offset1:1
	v_add_u32_e32 v0, 0x1040, v71
	v_lshl_add_u64 v[4:5], s[4:5], 0, v[168:169]
	v_readlane_b32 s49, v253, 19
	v_readlane_b32 s50, v253, 20
	s_waitcnt vmcnt(11)
	ds_write2_b32 v0, v16, v17 offset1:1
	v_add_u32_e32 v0, 0x1048, v71
	ds_write2_b32 v0, v18, v19 offset1:1
	v_add_u32_e32 v0, 0x1450, v71
	s_waitcnt vmcnt(10)
	ds_write2_b32 v0, v20, v21 offset1:1
	v_add_u32_e32 v0, 0x1458, v71
	ds_write2_b32 v0, v22, v23 offset1:1
	v_add_u32_e32 v0, 0x1860, v71
	v_readlane_b32 s51, v253, 21
	v_readlane_b32 s52, v253, 22
	v_readlane_b32 s53, v253, 23
	s_waitcnt vmcnt(9)
	ds_write2_b32 v0, v24, v25 offset1:1
	v_add_u32_e32 v0, 0x1868, v71
	ds_write2_b32 v0, v26, v27 offset1:1
	v_add_u32_e32 v0, 0x1c70, v71
	s_waitcnt vmcnt(8)
	ds_write2_b32 v0, v28, v29 offset1:1
	v_add_u32_e32 v0, 0x1c78, v71
	ds_write2_b32 v0, v30, v31 offset1:1
	v_add_u32_e32 v0, 0x2080, v71
	v_readlane_b32 s54, v253, 24
	v_readlane_b32 s55, v253, 25
	v_readlane_b32 s56, v253, 26
	s_waitcnt vmcnt(7)
	ds_write2_b32 v0, v32, v33 offset1:1
	v_add_u32_e32 v0, 0x2088, v71
	ds_write2_b32 v0, v34, v35 offset1:1
	v_add_u32_e32 v0, 0x2490, v71
	s_waitcnt vmcnt(6)
	ds_write2_b32 v0, v36, v37 offset1:1
	v_add_u32_e32 v0, 0x2498, v71
	ds_write2_b32 v0, v38, v39 offset1:1
	v_add_u32_e32 v0, 0x28a0, v71
	v_readlane_b32 s57, v253, 27
	v_readlane_b32 s58, v253, 28
	v_readlane_b32 s59, v253, 29
	s_waitcnt vmcnt(5)
; #define LDS_WAIT() asm volatile("s_waitcnt lgkmcnt(0)" ::: "memory")
; __device__ __forceinline__ unsigned pk2(float lo, float hi) { unsigned r; asm("v_cvt_pk_bf16_f32 %0, %1, %2" : "=v"(r) : "v"(lo), "v"(hi)); return r; }
; __device__ __forceinline__ void p0_transpose_item(const float* W, int K, int N, bf16* WT, float* scr, int item, int lane, const float* scale, const float* cb, float* c1, float* c2) {
;     ...
;     for (int i = 0; i < 16; ++i) { const int kk = 4 * i + lr; f32x4 w = v[i]; if (scale) w = w * scale[k0 + kk]; float* d = scr + kk * 65 + lc; d[0] = w[0]; d[1] = w[1]; d[2] = w[2]; d[3] = w[3]; }
;     LDS_WAIT(); asm volatile("" ::: "memory");
;     const int c = lane & 7;
; #pragma unroll
;     for (int j = 0; j < 8; ++j) { const int n = (lane >> 3) + 8 * j; const float* sp = scr + (8 * c) * 65 + n;
;         v4u o; o.x = pk2(sp[0 * 65], sp[1 * 65]); o.y = pk2(sp[2 * 65], sp[3 * 65]); o.z = pk2(sp[4 * 65], sp[5 * 65]); o.w = pk2(sp[6 * 65], sp[7 * 65]);
;         *(v4u*)(WT + (size_t)(n0 + n) * K + k0 + 8 * c) = o; }
	ds_write2_b32 v0, v40, v41 offset1:1
	v_add_u32_e32 v0, 0x28a8, v71
	ds_write2_b32 v0, v42, v43 offset1:1
	v_add_u32_e32 v0, 0x2cb0, v71
	s_waitcnt vmcnt(4)
	ds_write2_b32 v0, v44, v45 offset1:1
	v_add_u32_e32 v0, 0x2cb8, v71
	ds_write2_b32 v0, v46, v47 offset1:1
	v_add_u32_e32 v0, 0x30c0, v71
	s_waitcnt vmcnt(3)
	ds_write2_b32 v0, v48, v49 offset1:1
	v_add_u32_e32 v0, 0x30c8, v71
	ds_write2_b32 v0, v50, v51 offset1:1
	v_add_u32_e32 v0, 0x34d0, v71
	v_readlane_b32 s60, v253, 30
	s_waitcnt vmcnt(2)
	ds_write2_b32 v0, v52, v53 offset1:1
	v_add_u32_e32 v0, 0x34d8, v71
	ds_write2_b32 v0, v54, v55 offset1:1
	v_add_u32_e32 v0, 0x38e0, v71
	v_readlane_b32 s61, v253, 31
	s_waitcnt vmcnt(1)
	ds_write2_b32 v0, v56, v57 offset1:1
	v_add_u32_e32 v0, 0x38e8, v71
	ds_write2_b32 v0, v58, v59 offset1:1
	v_add_u32_e32 v0, 0x3cf0, v71
	s_waitcnt vmcnt(0)
	ds_write2_b32 v0, v60, v61 offset1:1
	v_add_u32_e32 v0, 0x3cf8, v71
	ds_write2_b32 v0, v62, v63 offset1:1
	s_waitcnt lgkmcnt(0)
	ds_read_b32 v0, v81
	ds_read_b32 v1, v81 offset:260
	ds_read_b32 v2, v81 offset:520
	ds_read_b32 v3, v81 offset:780
	ds_read_b32 v6, v81 offset:1040
	ds_read_b32 v7, v81 offset:1300
	ds_read_b32 v8, v81 offset:1560
	ds_read_b32 v9, v81 offset:1820
	s_waitcnt lgkmcnt(6)
	v_cvt_pk_bf16_f32 v0, v0, v1
	s_waitcnt lgkmcnt(4)
	v_cvt_pk_bf16_f32 v1, v2, v3
	s_waitcnt lgkmcnt(2)
	v_cvt_pk_bf16_f32 v2, v6, v7
	v_or_b32_e32 v6, s2, v80
	v_lshlrev_b32_e32 v168, 9, v6
	v_lshl_add_u64 v[6:7], v[4:5], 0, v[168:169]
	s_waitcnt lgkmcnt(0)
	v_cvt_pk_bf16_f32 v3, v8, v9
	global_store_dwordx4 v[6:7], v[0:3], off
	ds_read_b32 v0, v81 offset:32
	ds_read_b32 v1, v81 offset:292
	ds_read_b32 v2, v81 offset:552
	ds_read_b32 v3, v81 offset:812
	ds_read_b32 v6, v81 offset:1072
	ds_read_b32 v7, v81 offset:1332
	ds_read_b32 v8, v81 offset:1592
	ds_read_b32 v9, v81 offset:1852
	s_waitcnt lgkmcnt(0)
	v_cvt_pk_bf16_f32 v0, v0, v1
	v_cvt_pk_bf16_f32 v1, v2, v3
	v_cvt_pk_bf16_f32 v2, v6, v7
	v_or_b32_e32 v6, s2, v82
	v_lshlrev_b32_e32 v168, 9, v6
	v_lshl_add_u64 v[6:7], v[4:5], 0, v[168:169]
	v_cvt_pk_bf16_f32 v3, v8, v9
	global_store_dwordx4 v[6:7], v[0:3], off
	ds_read_b32 v0, v81 offset:64
	ds_read_b32 v1, v81 offset:324
	ds_read_b32 v2, v81 offset:584
	ds_read_b32 v3, v81 offset:844
	ds_read_b32 v6, v81 offset:1104
	ds_read_b32 v7, v81 offset:1364
	ds_read_b32 v8, v81 offset:1624
	ds_read_b32 v9, v81 offset:1884
	s_waitcnt lgkmcnt(0)
	v_cvt_pk_bf16_f32 v0, v0, v1
	v_cvt_pk_bf16_f32 v1, v2, v3
	v_cvt_pk_bf16_f32 v2, v6, v7
	v_or_b32_e32 v6, s2, v83
	v_lshlrev_b32_e32 v168, 9, v6
	v_lshl_add_u64 v[6:7], v[4:5], 0, v[168:169]
	v_cvt_pk_bf16_f32 v3, v8, v9
	global_store_dwordx4 v[6:7], v[0:3], off
	ds_read_b32 v0, v81 offset:96
	ds_read_b32 v1, v81 offset:356
	ds_read_b32 v2, v81 offset:616
	ds_read_b32 v3, v81 offset:876
	ds_read_b32 v6, v81 offset:1136
	ds_read_b32 v7, v81 offset:1396
	ds_read_b32 v8, v81 offset:1656
	ds_read_b32 v9, v81 offset:1916
	s_waitcnt lgkmcnt(0)
	v_cvt_pk_bf16_f32 v0, v0, v1
	v_cvt_pk_bf16_f32 v1, v2, v3
	v_cvt_pk_bf16_f32 v2, v6, v7
	v_or_b32_e32 v6, s2, v84
	v_lshlrev_b32_e32 v168, 9, v6
	v_lshl_add_u64 v[6:7], v[4:5], 0, v[168:169]
	v_cvt_pk_bf16_f32 v3, v8, v9
	global_store_dwordx4 v[6:7], v[0:3], off
	ds_read_b32 v0, v81 offset:128
	ds_read_b32 v1, v81 offset:388
	ds_read_b32 v2, v81 offset:648
	ds_read_b32 v3, v81 offset:908
	ds_read_b32 v6, v81 offset:1168
	ds_read_b32 v7, v81 offset:1428
	ds_read_b32 v8, v81 offset:1688
	ds_read_b32 v9, v81 offset:1948
	s_waitcnt lgkmcnt(0)
	v_cvt_pk_bf16_f32 v0, v0, v1
	v_cvt_pk_bf16_f32 v1, v2, v3
	v_cvt_pk_bf16_f32 v2, v6, v7
	v_or_b32_e32 v6, s2, v85
	v_lshlrev_b32_e32 v168, 9, v6
	v_lshl_add_u64 v[6:7], v[4:5], 0, v[168:169]
	v_cvt_pk_bf16_f32 v3, v8, v9
	global_store_dwordx4 v[6:7], v[0:3], off
	ds_read_b32 v0, v81 offset:160
	ds_read_b32 v1, v81 offset:420
	ds_read_b32 v2, v81 offset:680
	ds_read_b32 v3, v81 offset:940
	ds_read_b32 v6, v81 offset:1200
	ds_read_b32 v7, v81 offset:1460
	ds_read_b32 v8, v81 offset:1720
	ds_read_b32 v9, v81 offset:1980
	s_waitcnt lgkmcnt(0)
	v_cvt_pk_bf16_f32 v0, v0, v1
	v_cvt_pk_bf16_f32 v1, v2, v3
	v_cvt_pk_bf16_f32 v2, v6, v7
	v_or_b32_e32 v6, s2, v86
	v_lshlrev_b32_e32 v168, 9, v6
	v_lshl_add_u64 v[6:7], v[4:5], 0, v[168:169]
	v_cvt_pk_bf16_f32 v3, v8, v9
	global_store_dwordx4 v[6:7], v[0:3], off
	ds_read_b32 v0, v81 offset:192
	ds_read_b32 v1, v81 offset:452
	ds_read_b32 v2, v81 offset:712
	ds_read_b32 v3, v81 offset:972
	ds_read_b32 v6, v81 offset:1232
	ds_read_b32 v7, v81 offset:1492
	ds_read_b32 v8, v81 offset:1752
	ds_read_b32 v9, v81 offset:2012
	s_waitcnt lgkmcnt(0)
	v_cvt_pk_bf16_f32 v0, v0, v1
	v_cvt_pk_bf16_f32 v1, v2, v3
	v_cvt_pk_bf16_f32 v2, v6, v7
	v_or_b32_e32 v6, s2, v87
	v_lshlrev_b32_e32 v168, 9, v6
	v_lshl_add_u64 v[6:7], v[4:5], 0, v[168:169]
	v_cvt_pk_bf16_f32 v3, v8, v9
	global_store_dwordx4 v[6:7], v[0:3], off
	ds_read_b32 v0, v81 offset:224
	ds_read_b32 v1, v81 offset:484
	ds_read_b32 v2, v81 offset:744
	ds_read_b32 v3, v81 offset:1004
	ds_read_b32 v6, v81 offset:1264
	ds_read_b32 v7, v81 offset:1524
	ds_read_b32 v8, v81 offset:1784
	ds_read_b32 v9, v81 offset:2044
	s_waitcnt lgkmcnt(0)
	v_cvt_pk_bf16_f32 v0, v0, v1
	v_cvt_pk_bf16_f32 v1, v2, v3
	v_cvt_pk_bf16_f32 v2, v6, v7
	v_or_b32_e32 v6, s2, v88
	v_lshlrev_b32_e32 v168, 9, v6
	v_lshl_add_u64 v[4:5], v[4:5], 0, v[168:169]
	v_cvt_pk_bf16_f32 v3, v8, v9
	global_store_dwordx4 v[4:5], v[0:3], off
	s_waitcnt lgkmcnt(0)
	s_mov_b64 s[2:3], 0

; #define LDS_WAIT() asm volatile("s_waitcnt lgkmcnt(0)" ::: "memory")
; __device__ __forceinline__ unsigned pk2(float lo, float hi) { unsigned r; asm("v_cvt_pk_bf16_f32 %0, %1, %2" : "=v"(r) : "v"(lo), "v"(hi)); return r; }
; __device__ __forceinline__ unsigned f2bf(float f) { return pk2(f, 0.f) & 0xffffu; }
; __device__ __forceinline__ void p0_transpose_item(const float* W, int K, int N, bf16* WT, float* scr, int item, int lane, const float* scale, const float* cb, float* c1, float* c2) {
;     ...
;     for (int i = 0; i < 16; ++i) { const int kk = 4 * i + lr; f32x4 w = v[i]; if (scale) w = w * scale[k0 + kk]; float* d = scr + kk * 65 + lc; d[0] = w[0]; d[1] = w[1]; d[2] = w[2]; d[3] = w[3]; }
;     LDS_WAIT(); asm volatile("" ::: "memory");
;     const int c = lane & 7;
; #pragma unroll
;     for (int j = 0; j < 8; ++j) { const int n = (lane >> 3) + 8 * j; const float* sp = scr + (8 * c) * 65 + n;
;         v4u o; o.x = pk2(sp[0 * 65], sp[1 * 65]); o.y = pk2(sp[2 * 65], sp[3 * 65]); o.z = pk2(sp[4 * 65], sp[5 * 65]); o.w = pk2(sp[6 * 65], sp[7 * 65]);
;         *(v4u*)(WT + (size_t)(n0 + n) * K + k0 + 8 * c) = o; }
;     if (c1) { float a1 = 0.f, a2 = 0.f;
;         for (int kk = 0; kk < 64; ++kk) { a1 += __uint_as_float(f2bf(scr[kk * 65 + lane]) << 16); a2 += cb[k0 + kk] * W[(size_t)(k0 + kk) * N + n0 + lane]; }
.LBB0_459:
	v_add_u32_e32 v0, 0x34d0, v90
	ds_write2_b32 v0, v14, v15 offset1:1
	v_add_u32_e32 v0, 0x34d8, v90
	ds_write2_b32 v0, v12, v13 offset1:1
	v_add_u32_e32 v0, 0x38e0, v90
	ds_write2_b32 v0, v8, v9 offset1:1
	v_add_u32_e32 v0, 0x38e8, v90
	ds_write2_b32 v0, v10, v11 offset1:1
	s_waitcnt lgkmcnt(0)
	ds_read_b32 v2, v81
	ds_read_b32 v3, v81 offset:260
	s_lshl_b64 s[4:5], s[0:1], 22
	s_waitcnt lgkmcnt(0)
	v_cvt_pk_bf16_f32 v2, v2, v3
	ds_read_b32 v3, v81 offset:520
	ds_read_b32 v4, v81 offset:780
	s_waitcnt lgkmcnt(0)
	v_cvt_pk_bf16_f32 v3, v3, v4
	ds_read_b32 v4, v81 offset:1040
	ds_read_b32 v5, v81 offset:1300
	s_waitcnt lgkmcnt(0)
	v_cvt_pk_bf16_f32 v4, v4, v5
	ds_read_b32 v5, v81 offset:1560
	ds_read_b32 v6, v81 offset:1820
	s_lshl_b64 s[4:5], s[4:5], 1
	s_add_u32 s1, s39, s4
	s_addc_u32 s5, s40, s5
	s_lshl_b32 s4, s50, 1
	s_add_u32 s4, s1, s4
	s_addc_u32 s5, s5, 0
	v_lshlrev_b32_e32 v168, 1, v70
	s_waitcnt lgkmcnt(0)
	v_cvt_pk_bf16_f32 v5, v5, v6
	v_or_b32_e32 v6, s51, v80
	v_lshl_add_u64 v[0:1], s[4:5], 0, v[168:169]
	v_lshlrev_b32_e32 v168, 12, v6
	v_lshl_add_u64 v[6:7], v[0:1], 0, v[168:169]
	global_store_dwordx4 v[6:7], v[2:5], off
	ds_read_b32 v2, v81 offset:32
	ds_read_b32 v3, v81 offset:292
	s_waitcnt lgkmcnt(0)
	v_cvt_pk_bf16_f32 v2, v2, v3
	ds_read_b32 v3, v81 offset:552
	ds_read_b32 v4, v81 offset:812
	s_waitcnt lgkmcnt(0)
	v_cvt_pk_bf16_f32 v3, v3, v4
	ds_read_b32 v4, v81 offset:1072
	ds_read_b32 v5, v81 offset:1332
	s_waitcnt lgkmcnt(0)
	v_cvt_pk_bf16_f32 v4, v4, v5
	ds_read_b32 v5, v81 offset:1592
	ds_read_b32 v6, v81 offset:1852
	s_waitcnt lgkmcnt(0)
	v_cvt_pk_bf16_f32 v5, v5, v6
	v_or_b32_e32 v6, s51, v82
	v_lshlrev_b32_e32 v168, 12, v6
	v_lshl_add_u64 v[6:7], v[0:1], 0, v[168:169]
	global_store_dwordx4 v[6:7], v[2:5], off
	ds_read_b32 v2, v81 offset:64
	ds_read_b32 v3, v81 offset:324
	s_waitcnt lgkmcnt(0)
	v_cvt_pk_bf16_f32 v2, v2, v3
	ds_read_b32 v3, v81 offset:584
	ds_read_b32 v4, v81 offset:844
	s_waitcnt lgkmcnt(0)
	v_cvt_pk_bf16_f32 v3, v3, v4
	ds_read_b32 v4, v81 offset:1104
	ds_read_b32 v5, v81 offset:1364
	s_waitcnt lgkmcnt(0)
	v_cvt_pk_bf16_f32 v4, v4, v5
	ds_read_b32 v5, v81 offset:1624
	ds_read_b32 v6, v81 offset:1884
	s_waitcnt lgkmcnt(0)
	v_cvt_pk_bf16_f32 v5, v5, v6
	v_or_b32_e32 v6, s51, v83
	v_lshlrev_b32_e32 v168, 12, v6
	v_lshl_add_u64 v[6:7], v[0:1], 0, v[168:169]
	global_store_dwordx4 v[6:7], v[2:5], off
	ds_read_b32 v2, v81 offset:96
	ds_read_b32 v3, v81 offset:356
	s_waitcnt lgkmcnt(0)
	v_cvt_pk_bf16_f32 v2, v2, v3
	ds_read_b32 v3, v81 offset:616
	ds_read_b32 v4, v81 offset:876
	s_waitcnt lgkmcnt(0)
	v_cvt_pk_bf16_f32 v3, v3, v4
	ds_read_b32 v4, v81 offset:1136
	ds_read_b32 v5, v81 offset:1396
	s_waitcnt lgkmcnt(0)
	v_cvt_pk_bf16_f32 v4, v4, v5
	ds_read_b32 v5, v81 offset:1656
	ds_read_b32 v6, v81 offset:1916
	s_waitcnt lgkmcnt(0)
	v_cvt_pk_bf16_f32 v5, v5, v6
	v_or_b32_e32 v6, s51, v84
	v_lshlrev_b32_e32 v168, 12, v6
	v_lshl_add_u64 v[6:7], v[0:1], 0, v[168:169]
	global_store_dwordx4 v[6:7], v[2:5], off
	ds_read_b32 v2, v81 offset:128
	ds_read_b32 v3, v81 offset:388
	s_waitcnt lgkmcnt(0)
	v_cvt_pk_bf16_f32 v2, v2, v3
	ds_read_b32 v3, v81 offset:648
	ds_read_b32 v4, v81 offset:908
	s_waitcnt lgkmcnt(0)
	v_cvt_pk_bf16_f32 v3, v3, v4
	ds_read_b32 v4, v81 offset:1168
	ds_read_b32 v5, v81 offset:1428
	s_waitcnt lgkmcnt(0)
	v_cvt_pk_bf16_f32 v4, v4, v5
	ds_read_b32 v5, v81 offset:1688
	ds_read_b32 v6, v81 offset:1948
	s_waitcnt lgkmcnt(0)
	v_cvt_pk_bf16_f32 v5, v5, v6
	v_or_b32_e32 v6, s51, v85
	v_lshlrev_b32_e32 v168, 12, v6
	v_lshl_add_u64 v[6:7], v[0:1], 0, v[168:169]
	global_store_dwordx4 v[6:7], v[2:5], off
	ds_read_b32 v2, v81 offset:160
	ds_read_b32 v3, v81 offset:420
	s_waitcnt lgkmcnt(0)
	v_cvt_pk_bf16_f32 v2, v2, v3
	ds_read_b32 v3, v81 offset:680
	ds_read_b32 v4, v81 offset:940
	s_waitcnt lgkmcnt(0)
	v_cvt_pk_bf16_f32 v3, v3, v4
	ds_read_b32 v4, v81 offset:1200
	ds_read_b32 v5, v81 offset:1460
	s_waitcnt lgkmcnt(0)
	v_cvt_pk_bf16_f32 v4, v4, v5
	ds_read_b32 v5, v81 offset:1720
	ds_read_b32 v6, v81 offset:1980
	s_waitcnt lgkmcnt(0)
	v_cvt_pk_bf16_f32 v5, v5, v6
	v_or_b32_e32 v6, s51, v86
	v_lshlrev_b32_e32 v168, 12, v6
	v_lshl_add_u64 v[6:7], v[0:1], 0, v[168:169]
	global_store_dwordx4 v[6:7], v[2:5], off
	ds_read_b32 v2, v81 offset:192
	ds_read_b32 v3, v81 offset:452
	s_waitcnt lgkmcnt(0)
	v_cvt_pk_bf16_f32 v2, v2, v3
	ds_read_b32 v3, v81 offset:712
	ds_read_b32 v4, v81 offset:972
	s_waitcnt lgkmcnt(0)
	v_cvt_pk_bf16_f32 v3, v3, v4
	ds_read_b32 v4, v81 offset:1232
	ds_read_b32 v5, v81 offset:1492
	s_waitcnt lgkmcnt(0)
	v_cvt_pk_bf16_f32 v4, v4, v5
	ds_read_b32 v5, v81 offset:1752
	ds_read_b32 v6, v81 offset:2012
	s_waitcnt lgkmcnt(0)
	v_cvt_pk_bf16_f32 v5, v5, v6
	v_or_b32_e32 v6, s51, v87
	v_lshlrev_b32_e32 v168, 12, v6
	v_lshl_add_u64 v[6:7], v[0:1], 0, v[168:169]
	global_store_dwordx4 v[6:7], v[2:5], off
	ds_read_b32 v2, v81 offset:224
	ds_read_b32 v3, v81 offset:484
	s_waitcnt lgkmcnt(0)
	v_cvt_pk_bf16_f32 v2, v2, v3
	ds_read_b32 v3, v81 offset:744
	ds_read_b32 v4, v81 offset:1004
	s_waitcnt lgkmcnt(0)
	v_cvt_pk_bf16_f32 v3, v3, v4
	ds_read_b32 v4, v81 offset:1264
	ds_read_b32 v5, v81 offset:1524
	s_waitcnt lgkmcnt(0)
	v_cvt_pk_bf16_f32 v4, v4, v5
	ds_read_b32 v5, v81 offset:1784
	ds_read_b32 v6, v81 offset:2044
	s_lshl_b32 s1, s49, 13
	s_and_b32 s1, s1, 0x3ff80000
	s_add_u32 s1, s6, s1
	s_addc_u32 s5, s7, 0
	s_and_b32 s4, s47, 31
	s_waitcnt lgkmcnt(0)
	v_cvt_pk_bf16_f32 v5, v5, v6
	v_or_b32_e32 v6, s51, v88
	s_lshl_b32 s4, s4, 8
	v_readlane_b32 s52, v253, 18
	v_lshlrev_b32_e32 v168, 12, v6
	s_or_b32 s4, s1, s4
	s_lshl_b32 s1, s50, 2
	v_readlane_b32 s64, v253, 30
	v_lshl_add_u64 v[0:1], v[0:1], 0, v[168:169]
	v_readlane_b32 s65, v253, 31
	s_add_u32 s1, s64, s1
	global_store_dwordx4 v[0:1], v[2:5], off
	v_lshl_add_u64 v[0:1], v[72:73], 0, s[4:5]
	s_addc_u32 s14, s65, 0
	s_lshl_b32 s4, s49, 2
	s_and_b32 s4, s4, 0x7ff00
	s_add_u32 s15, s64, s4
	v_mov_b32_e32 v2, 0
	s_addc_u32 s24, s65, 0
	s_mov_b64 s[4:5], 0
	v_mov_b32_e32 v6, v89
	v_mov_b32_e32 v3, v2
	v_readlane_b32 s53, v253, 19
	v_readlane_b32 s54, v253, 20
	v_readlane_b32 s55, v253, 21
	v_readlane_b32 s56, v253, 22
	v_readlane_b32 s57, v253, 23
	v_readlane_b32 s58, v253, 24
	v_readlane_b32 s59, v253, 25
	v_readlane_b32 s60, v253, 26
	v_readlane_b32 s61, v253, 27
	v_readlane_b32 s62, v253, 28
	v_readlane_b32 s63, v253, 29
	v_readlane_b32 s66, v253, 32
	v_readlane_b32 s67, v253, 33
; __device__ __forceinline__ unsigned f2bf(float f) { return pk2(f, 0.f) & 0xffffu; }
; __device__ __forceinline__ void p0_transpose_item(const float* W, int K, int N, bf16* WT, float* scr, int item, int lane, const float* scale, const float* cb, float* c1, float* c2) {
;     ...
;     if (c1) { float a1 = 0.f, a2 = 0.f;
;         for (int kk = 0; kk < 64; ++kk) { a1 += __uint_as_float(f2bf(scr[kk * 65 + lane]) << 16); a2 += cb[k0 + kk] * W[(size_t)(k0 + kk) * N + n0 + lane]; }
;         atomicAdd(c1 + n0 + lane, a1); atomicAdd(c2 + n0 + lane, a2); }
.LBB0_460:
	ds_read2_b32 v[8:9], v6 offset1:65
	s_waitcnt lgkmcnt(0)
	v_cvt_pk_bf16_f32 v4, v8, v169
	s_add_u32 s6, s15, s2
	v_lshlrev_b32_e32 v11, 16, v4
	s_addc_u32 s7, s24, s3
	v_lshl_add_u64 v[4:5], v[0:1], 0, s[4:5]
	global_load_dword v7, v169, s[6:7]
	global_load_dword v8, v[4:5], off
	s_add_u32 s6, s1, s2
	v_add_co_u32_e32 v14, vcc, s69, v4
	s_addc_u32 s7, s14, s3
	s_nop 0
	v_addc_co_u32_e32 v15, vcc, 0, v5, vcc
	v_add_co_u32_e32 v16, vcc, s89, v4
	s_add_u32 s4, s4, 0x10000
	s_nop 0
	v_addc_co_u32_e32 v17, vcc, 0, v5, vcc
	s_addc_u32 s5, s5, 0
	s_add_u32 s1, s1, 32
	s_addc_u32 s14, s14, 0
	s_add_u32 s15, s15, 32
	s_addc_u32 s24, s24, 0
	s_cmp_lg_u32 s4, 0x80000
	s_waitcnt vmcnt(0)
	v_mul_f32_e32 v10, v7, v8
	v_cvt_pk_bf16_f32 v7, v9, v169
	v_pk_add_f32 v[2:3], v[2:3], v[10:11]
	v_lshlrev_b32_e32 v13, 16, v7
	global_load_dwordx4 v[8:11], v169, s[6:7] offset:4
	global_load_dword v7, v[14:15], off
	s_waitcnt vmcnt(0)
	v_mul_f32_e32 v12, v8, v7
	v_pk_add_f32 v[2:3], v[2:3], v[12:13]
	ds_read2_b32 v[12:13], v6 offset0:130 offset1:195
	s_waitcnt lgkmcnt(0)
	v_cvt_pk_bf16_f32 v7, v12, v169
	v_add_co_u32_e32 v12, vcc, s84, v4
	v_lshlrev_b32_e32 v15, 16, v7
	global_load_dword v7, v[16:17], off
	s_waitcnt vmcnt(0)
	v_mul_f32_e32 v14, v9, v7
	v_cvt_pk_bf16_f32 v7, v13, v169
	v_addc_co_u32_e32 v13, vcc, 0, v5, vcc
	v_lshlrev_b32_e32 v9, 16, v7
	global_load_dword v7, v[12:13], off
	v_pk_add_f32 v[2:3], v[2:3], v[14:15]
	v_add_co_u32_e32 v14, vcc, s90, v4
	s_waitcnt vmcnt(0)
	v_mul_f32_e32 v8, v10, v7
	v_add_u32_e32 v7, 0x400, v6
	v_pk_add_f32 v[2:3], v[2:3], v[8:9]
	ds_read2_b32 v[8:9], v7 offset0:4 offset1:69
	s_waitcnt lgkmcnt(0)
	v_cvt_pk_bf16_f32 v8, v8, v169
	v_addc_co_u32_e32 v15, vcc, 0, v5, vcc
	v_lshlrev_b32_e32 v13, 16, v8
	global_load_dword v8, v[14:15], off
	v_add_co_u32_e32 v14, vcc, s70, v4
	v_add_u32_e32 v6, 0x820, v6
	s_nop 0
	v_addc_co_u32_e32 v15, vcc, 0, v5, vcc
	v_add_co_u32_e32 v16, vcc, s91, v4
	s_waitcnt vmcnt(0)
	v_mul_f32_e32 v12, v11, v8
	v_cvt_pk_bf16_f32 v8, v9, v169
	v_pk_add_f32 v[2:3], v[2:3], v[12:13]
	v_lshlrev_b32_e32 v13, 16, v8
	global_load_dwordx3 v[8:10], v169, s[6:7] offset:20
	global_load_dword v11, v[14:15], off
	v_addc_co_u32_e32 v17, vcc, 0, v5, vcc
	v_add_co_u32_e32 v4, vcc, s71, v4
	s_nop 1
	v_addc_co_u32_e32 v5, vcc, 0, v5, vcc
	global_load_dword v4, v[4:5], off
	s_waitcnt vmcnt(1)
	v_mul_f32_e32 v12, v8, v11
	v_pk_add_f32 v[2:3], v[2:3], v[12:13]
	ds_read2_b32 v[12:13], v7 offset0:134 offset1:199
	s_waitcnt lgkmcnt(0)
	v_cvt_pk_bf16_f32 v7, v12, v169
	s_waitcnt vmcnt(0)
	v_mul_f32_e32 v8, v10, v4
	v_lshlrev_b32_e32 v15, 16, v7
	global_load_dword v7, v[16:17], off
	s_waitcnt vmcnt(0)
	v_mul_f32_e32 v14, v9, v7
	v_pk_add_f32 v[2:3], v[2:3], v[14:15]
	v_cvt_pk_bf16_f32 v7, v13, v169
	s_nop 0
	v_lshlrev_b32_e32 v9, 16, v7
	v_pk_add_f32 v[2:3], v[2:3], v[8:9]
	s_cbranch_scc1 .LBB0_460
	s_add_u32 s1, s43, s2
	s_addc_u32 s4, s44, s3
	s_add_u32 s5, s45, s2
	s_addc_u32 s6, s46, s3
	s_add_u32 s2, s1, s48
	s_addc_u32 s3, s4, 0
	v_mov_b32_e32 v75, v169
	v_lshl_add_u64 v[0:1], s[2:3], 0, v[74:75]
	s_add_u32 s2, s5, s48
	s_addc_u32 s3, s6, 0
	global_atomic_add_f32 v[0:1], v3, off
	v_lshl_add_u64 v[0:1], s[2:3], 0, v[74:75]
	global_atomic_add_f32 v[0:1], v2, off
	s_waitcnt lgkmcnt(0)

; __device__ __forceinline__ void p0_transpose_item(const float* W, int K, int N, bf16* WT, float* scr, int item, int lane, const float* scale, const float* cb, float* c1, float* c2) {
;     const int nblk = N / 64, kb = item / nblk, nb = item % nblk, k0 = 64 * kb, n0 = 64 * nb;
;     const int lr = lane >> 4, lc = (lane & 15) * 4;
;     f32x4 v[16];
; #pragma unroll
;     for (int i = 0; i < 16; ++i) v[i] = *(const f32x4*)(W + (size_t)(k0 + 4 * i + lr) * N + n0 + lc);
; #pragma unroll
;     for (int i = 0; i < 16; ++i) { const int kk = 4 * i + lr; f32x4 w = v[i]; if (scale) w = w * scale[k0 + kk]; float* d = scr + kk * 65 + lc; d[0] = w[0]; d[1] = w[1]; d[2] = w[2]; d[3] = w[3]; }
.LBB0_463:
	s_andn2_b64 vcc, exec, s[2:3]
	s_cbranch_vccnz .LBB0_465
	s_ashr_i32 s1, s0, 31
	v_readlane_b32 s48, v253, 18
	s_lshl_b64 s[2:3], s[0:1], 24
	v_readlane_b32 s56, v253, 26
	v_readlane_b32 s57, v253, 27
	s_add_u32 s4, s56, s2
	s_addc_u32 s5, s57, s3
	s_lshl_b64 s[2:3], s[0:1], 23
	s_add_u32 s6, s37, s2
	s_addc_u32 s7, s38, s3
	s_lshl_b32 s1, s47, 1
	s_add_i32 s1, s1, 0x1e200
	s_and_b32 s14, s1, 0x1ffc0
	s_lshl_b32 s1, s47, 6
	s_and_b32 s1, s1, 0x7c0
	s_lshl_b32 s2, s1, 2
	s_add_u32 s2, s4, s2
	v_or_b32_e32 v2, s14, v69
	s_addc_u32 s3, s5, 0
	v_lshlrev_b32_e32 v168, 2, v68
	v_lshl_add_u64 v[0:1], s[2:3], 0, v[168:169]
	v_lshlrev_b32_e32 v168, 13, v2
	v_lshl_add_u64 v[60:61], v[0:1], 0, v[168:169]
	v_add_co_u32_e32 v4, vcc, s90, v60
	s_mov_b32 s2, 0x20000
	s_nop 0
	v_addc_co_u32_e32 v5, vcc, 0, v61, vcc
	v_add_co_u32_e32 v8, vcc, s88, v60
	global_load_dwordx4 v[0:3], v[60:61], off
	s_nop 0
	global_load_dwordx4 v[4:7], v[4:5], off
	v_addc_co_u32_e32 v9, vcc, 0, v61, vcc
	v_add_co_u32_e32 v12, vcc, s85, v60
	v_lshlrev_b32_e32 v168, 1, v70
	s_nop 0
	v_addc_co_u32_e32 v13, vcc, 0, v61, vcc
	global_load_dwordx4 v[8:11], v[8:9], off
	s_nop 0
	global_load_dwordx4 v[12:15], v[12:13], off
	v_add_co_u32_e32 v16, vcc, s2, v60
	s_mov_b32 s2, 0x28000
	s_nop 0
	v_addc_co_u32_e32 v17, vcc, 0, v61, vcc
	v_add_co_u32_e32 v20, vcc, s2, v60
	s_mov_b32 s2, 0x30000
	s_nop 0
	v_addc_co_u32_e32 v21, vcc, 0, v61, vcc
	global_load_dwordx4 v[16:19], v[16:17], off
	s_nop 0
	global_load_dwordx4 v[20:23], v[20:21], off
	v_add_co_u32_e32 v24, vcc, s2, v60
	s_mov_b32 s2, 0x38000
	s_nop 0
	v_addc_co_u32_e32 v25, vcc, 0, v61, vcc
	v_add_co_u32_e32 v28, vcc, s2, v60
	s_mov_b32 s2, 0x40000
	s_nop 0
	v_addc_co_u32_e32 v29, vcc, 0, v61, vcc
	global_load_dwordx4 v[24:27], v[24:25], off
	s_nop 0
	global_load_dwordx4 v[28:31], v[28:29], off
	v_add_co_u32_e32 v32, vcc, s2, v60
	s_mov_b32 s2, 0x48000
	s_nop 0
	v_addc_co_u32_e32 v33, vcc, 0, v61, vcc
	v_add_co_u32_e32 v36, vcc, s2, v60
	s_mov_b32 s2, 0x50000
	s_nop 0
	v_addc_co_u32_e32 v37, vcc, 0, v61, vcc
	global_load_dwordx4 v[32:35], v[32:33], off
	s_nop 0
	global_load_dwordx4 v[36:39], v[36:37], off
	v_add_co_u32_e32 v40, vcc, s2, v60
	s_mov_b32 s2, 0x58000
	s_nop 0
	v_addc_co_u32_e32 v41, vcc, 0, v61, vcc
	v_add_co_u32_e32 v44, vcc, s2, v60
	s_mov_b32 s2, 0x60000
	s_nop 0
	v_addc_co_u32_e32 v45, vcc, 0, v61, vcc
	global_load_dwordx4 v[40:43], v[40:41], off
	s_nop 0
	global_load_dwordx4 v[44:47], v[44:45], off
	v_add_co_u32_e32 v48, vcc, s2, v60
	s_mov_b32 s2, 0x68000
	s_nop 0
	v_addc_co_u32_e32 v49, vcc, 0, v61, vcc
	global_load_dwordx4 v[48:51], v[48:49], off
	v_add_co_u32_e32 v52, vcc, s2, v60
	s_mov_b32 s2, 0x70000
	s_nop 0
	v_addc_co_u32_e32 v53, vcc, 0, v61, vcc
	global_load_dwordx4 v[52:55], v[52:53], off
	v_add_co_u32_e32 v56, vcc, s2, v60
	s_mov_b32 s2, 0x78000
	s_nop 0
	v_addc_co_u32_e32 v57, vcc, 0, v61, vcc
	global_load_dwordx4 v[56:59], v[56:57], off
	v_add_co_u32_e32 v60, vcc, s2, v60
	s_lshl_b32 s2, s14, 1
	s_nop 0
	v_addc_co_u32_e32 v61, vcc, 0, v61, vcc
	global_load_dwordx4 v[60:63], v[60:61], off
	s_waitcnt vmcnt(0)
	ds_write2_b32 v71, v0, v1 offset1:1
	ds_write2_b32 v71, v2, v3 offset0:2 offset1:3
	v_add_u32_e32 v0, 0x410, v71
	ds_write2_b32 v0, v4, v5 offset1:1
	v_add_u32_e32 v0, 0x418, v71
	ds_write2_b32 v0, v6, v7 offset1:1
	v_add_u32_e32 v0, 0x820, v71
	s_add_u32 s2, s6, s2
	s_addc_u32 s3, s7, 0
	ds_write2_b32 v0, v8, v9 offset1:1
	v_add_u32_e32 v0, 0x828, v71
	ds_write2_b32 v0, v10, v11 offset1:1
	v_add_u32_e32 v0, 0xc30, v71
	ds_write2_b32 v0, v12, v13 offset1:1
	v_add_u32_e32 v0, 0xc38, v71
	ds_write2_b32 v0, v14, v15 offset1:1
	v_add_u32_e32 v0, 0x1040, v71
	v_lshl_add_u64 v[4:5], s[2:3], 0, v[168:169]
	v_readlane_b32 s49, v253, 19
	v_readlane_b32 s50, v253, 20
	ds_write2_b32 v0, v16, v17 offset1:1
	v_add_u32_e32 v0, 0x1048, v71
	ds_write2_b32 v0, v18, v19 offset1:1
	v_add_u32_e32 v0, 0x1450, v71
	ds_write2_b32 v0, v20, v21 offset1:1
	v_add_u32_e32 v0, 0x1458, v71
	ds_write2_b32 v0, v22, v23 offset1:1
	v_add_u32_e32 v0, 0x1860, v71
	v_readlane_b32 s51, v253, 21
	v_readlane_b32 s52, v253, 22
	v_readlane_b32 s53, v253, 23
	ds_write2_b32 v0, v24, v25 offset1:1
	v_add_u32_e32 v0, 0x1868, v71
	ds_write2_b32 v0, v26, v27 offset1:1
	v_add_u32_e32 v0, 0x1c70, v71
	ds_write2_b32 v0, v28, v29 offset1:1
	v_add_u32_e32 v0, 0x1c78, v71
	ds_write2_b32 v0, v30, v31 offset1:1
	v_add_u32_e32 v0, 0x2080, v71
	v_readlane_b32 s54, v253, 24
	v_readlane_b32 s55, v253, 25
	v_readlane_b32 s58, v253, 28
	ds_write2_b32 v0, v32, v33 offset1:1
	v_add_u32_e32 v0, 0x2088, v71
	ds_write2_b32 v0, v34, v35 offset1:1
	v_add_u32_e32 v0, 0x2490, v71
	ds_write2_b32 v0, v36, v37 offset1:1
	v_add_u32_e32 v0, 0x2498, v71
	ds_write2_b32 v0, v38, v39 offset1:1
	v_add_u32_e32 v0, 0x28a0, v71
	v_readlane_b32 s59, v253, 29
	v_readlane_b32 s60, v253, 30
	v_readlane_b32 s61, v253, 31
	ds_write2_b32 v0, v40, v41 offset1:1
	v_add_u32_e32 v0, 0x28a8, v71
	ds_write2_b32 v0, v42, v43 offset1:1
	v_add_u32_e32 v0, 0x2cb0, v71
	ds_write2_b32 v0, v44, v45 offset1:1
	v_add_u32_e32 v0, 0x2cb8, v71
	ds_write2_b32 v0, v46, v47 offset1:1
	v_add_u32_e32 v0, 0x30c0, v71
	ds_write2_b32 v0, v48, v49 offset1:1
	v_add_u32_e32 v0, 0x30c8, v71
	ds_write2_b32 v0, v50, v51 offset1:1
	v_add_u32_e32 v0, 0x34d0, v71
	v_readlane_b32 s62, v253, 32
	ds_write2_b32 v0, v52, v53 offset1:1
	v_add_u32_e32 v0, 0x34d8, v71
	ds_write2_b32 v0, v54, v55 offset1:1
	v_add_u32_e32 v0, 0x38e0, v71
	v_readlane_b32 s63, v253, 33
	ds_write2_b32 v0, v56, v57 offset1:1
	v_add_u32_e32 v0, 0x38e8, v71
	ds_write2_b32 v0, v58, v59 offset1:1
	v_add_u32_e32 v0, 0x3cf0, v71
	ds_write2_b32 v0, v60, v61 offset1:1
	v_add_u32_e32 v0, 0x3cf8, v71
	ds_write2_b32 v0, v62, v63 offset1:1
	s_waitcnt lgkmcnt(0)
; #define LDS_WAIT() asm volatile("s_waitcnt lgkmcnt(0)" ::: "memory")
; __device__ __forceinline__ unsigned pk2(float lo, float hi) { unsigned r; asm("v_cvt_pk_bf16_f32 %0, %1, %2" : "=v"(r) : "v"(lo), "v"(hi)); return r; }
; __device__ __forceinline__ void p0_transpose_item(const float* W, int K, int N, bf16* WT, float* scr, int item, int lane, const float* scale, const float* cb, float* c1, float* c2) {
;     ...
;     LDS_WAIT(); asm volatile("" ::: "memory");
;     const int c = lane & 7;
; #pragma unroll
;     for (int j = 0; j < 8; ++j) { const int n = (lane >> 3) + 8 * j; const float* sp = scr + (8 * c) * 65 + n;
;         v4u o; o.x = pk2(sp[0 * 65], sp[1 * 65]); o.y = pk2(sp[2 * 65], sp[3 * 65]); o.z = pk2(sp[4 * 65], sp[5 * 65]); o.w = pk2(sp[6 * 65], sp[7 * 65]);
;         *(v4u*)(WT + (size_t)(n0 + n) * K + k0 + 8 * c) = o; }
	ds_read_b32 v0, v81
	ds_read_b32 v1, v81 offset:260
	ds_read_b32 v2, v81 offset:520
	ds_read_b32 v3, v81 offset:780
	ds_read_b32 v6, v81 offset:1040
	ds_read_b32 v7, v81 offset:1300
	ds_read_b32 v8, v81 offset:1560
	ds_read_b32 v9, v81 offset:1820
	s_waitcnt lgkmcnt(0)
	v_cvt_pk_bf16_f32 v0, v0, v1
	v_cvt_pk_bf16_f32 v1, v2, v3
	v_cvt_pk_bf16_f32 v2, v6, v7
	v_or_b32_e32 v6, s1, v80
	v_lshlrev_b32_e32 v168, 12, v6
	v_lshl_add_u64 v[6:7], v[4:5], 0, v[168:169]
	v_cvt_pk_bf16_f32 v3, v8, v9
	global_store_dwordx4 v[6:7], v[0:3], off
	ds_read_b32 v0, v81 offset:32
	ds_read_b32 v1, v81 offset:292
	ds_read_b32 v2, v81 offset:552
	ds_read_b32 v3, v81 offset:812
	ds_read_b32 v6, v81 offset:1072
	ds_read_b32 v7, v81 offset:1332
	ds_read_b32 v8, v81 offset:1592
	ds_read_b32 v9, v81 offset:1852
	s_waitcnt lgkmcnt(0)
	v_cvt_pk_bf16_f32 v0, v0, v1
	v_cvt_pk_bf16_f32 v1, v2, v3
	v_cvt_pk_bf16_f32 v2, v6, v7
	v_or_b32_e32 v6, s1, v82
	v_lshlrev_b32_e32 v168, 12, v6
	v_lshl_add_u64 v[6:7], v[4:5], 0, v[168:169]
	v_cvt_pk_bf16_f32 v3, v8, v9
	global_store_dwordx4 v[6:7], v[0:3], off
	ds_read_b32 v0, v81 offset:64
	ds_read_b32 v1, v81 offset:324
	ds_read_b32 v2, v81 offset:584
	ds_read_b32 v3, v81 offset:844
	ds_read_b32 v6, v81 offset:1104
	ds_read_b32 v7, v81 offset:1364
	ds_read_b32 v8, v81 offset:1624
	ds_read_b32 v9, v81 offset:1884
	s_waitcnt lgkmcnt(0)
	v_cvt_pk_bf16_f32 v0, v0, v1
	v_cvt_pk_bf16_f32 v1, v2, v3
	v_cvt_pk_bf16_f32 v2, v6, v7
	v_or_b32_e32 v6, s1, v83
	v_lshlrev_b32_e32 v168, 12, v6
	v_lshl_add_u64 v[6:7], v[4:5], 0, v[168:169]
	v_cvt_pk_bf16_f32 v3, v8, v9
	global_store_dwordx4 v[6:7], v[0:3], off
	ds_read_b32 v0, v81 offset:96
	ds_read_b32 v1, v81 offset:356
	ds_read_b32 v2, v81 offset:616
	ds_read_b32 v3, v81 offset:876
	ds_read_b32 v6, v81 offset:1136
	ds_read_b32 v7, v81 offset:1396
	ds_read_b32 v8, v81 offset:1656
	ds_read_b32 v9, v81 offset:1916
	s_waitcnt lgkmcnt(0)
	v_cvt_pk_bf16_f32 v0, v0, v1
	v_cvt_pk_bf16_f32 v1, v2, v3
	v_cvt_pk_bf16_f32 v2, v6, v7
	v_or_b32_e32 v6, s1, v84
	v_lshlrev_b32_e32 v168, 12, v6
	v_lshl_add_u64 v[6:7], v[4:5], 0, v[168:169]
	v_cvt_pk_bf16_f32 v3, v8, v9
	global_store_dwordx4 v[6:7], v[0:3], off
	ds_read_b32 v0, v81 offset:128
	ds_read_b32 v1, v81 offset:388
	ds_read_b32 v2, v81 offset:648
	ds_read_b32 v3, v81 offset:908
	ds_read_b32 v6, v81 offset:1168
	ds_read_b32 v7, v81 offset:1428
	ds_read_b32 v8, v81 offset:1688
	ds_read_b32 v9, v81 offset:1948
	s_waitcnt lgkmcnt(0)
	v_cvt_pk_bf16_f32 v0, v0, v1
	v_cvt_pk_bf16_f32 v1, v2, v3
	v_cvt_pk_bf16_f32 v2, v6, v7
	v_or_b32_e32 v6, s1, v85
	v_lshlrev_b32_e32 v168, 12, v6
	v_lshl_add_u64 v[6:7], v[4:5], 0, v[168:169]
	v_cvt_pk_bf16_f32 v3, v8, v9
	global_store_dwordx4 v[6:7], v[0:3], off
	ds_read_b32 v0, v81 offset:160
	ds_read_b32 v1, v81 offset:420
	ds_read_b32 v2, v81 offset:680
	ds_read_b32 v3, v81 offset:940
	ds_read_b32 v6, v81 offset:1200
	ds_read_b32 v7, v81 offset:1460
	ds_read_b32 v8, v81 offset:1720
	ds_read_b32 v9, v81 offset:1980
	s_waitcnt lgkmcnt(0)
	v_cvt_pk_bf16_f32 v0, v0, v1
	v_cvt_pk_bf16_f32 v1, v2, v3
	v_cvt_pk_bf16_f32 v2, v6, v7
	v_or_b32_e32 v6, s1, v86
	v_lshlrev_b32_e32 v168, 12, v6
	v_lshl_add_u64 v[6:7], v[4:5], 0, v[168:169]
	v_cvt_pk_bf16_f32 v3, v8, v9
	global_store_dwordx4 v[6:7], v[0:3], off
	ds_read_b32 v0, v81 offset:192
	ds_read_b32 v1, v81 offset:452
	ds_read_b32 v2, v81 offset:712
	ds_read_b32 v3, v81 offset:972
	ds_read_b32 v6, v81 offset:1232
	ds_read_b32 v7, v81 offset:1492
	ds_read_b32 v8, v81 offset:1752
	ds_read_b32 v9, v81 offset:2012
	s_waitcnt lgkmcnt(0)
	v_cvt_pk_bf16_f32 v0, v0, v1
	v_cvt_pk_bf16_f32 v1, v2, v3
	v_cvt_pk_bf16_f32 v2, v6, v7
	v_or_b32_e32 v6, s1, v87
	v_lshlrev_b32_e32 v168, 12, v6
	v_lshl_add_u64 v[6:7], v[4:5], 0, v[168:169]
	v_cvt_pk_bf16_f32 v3, v8, v9
	global_store_dwordx4 v[6:7], v[0:3], off
	ds_read_b32 v0, v81 offset:224
	ds_read_b32 v1, v81 offset:484
	ds_read_b32 v2, v81 offset:744
	ds_read_b32 v3, v81 offset:1004
	ds_read_b32 v6, v81 offset:1264
	ds_read_b32 v7, v81 offset:1524
	ds_read_b32 v8, v81 offset:1784
	ds_read_b32 v9, v81 offset:2044
	s_waitcnt lgkmcnt(0)
	v_cvt_pk_bf16_f32 v0, v0, v1
	v_cvt_pk_bf16_f32 v1, v2, v3
	v_cvt_pk_bf16_f32 v2, v6, v7
	v_or_b32_e32 v6, s1, v88
	v_lshlrev_b32_e32 v168, 12, v6
	v_lshl_add_u64 v[4:5], v[4:5], 0, v[168:169]
	v_cvt_pk_bf16_f32 v3, v8, v9
	global_store_dwordx4 v[4:5], v[0:3], off
	s_waitcnt lgkmcnt(0)

; __device__ __forceinline__ void p0_transpose_item(const float* W, int K, int N, bf16* WT, float* scr, int item, int lane, const float* scale, const float* cb, float* c1, float* c2) {
;     const int nblk = N / 64, kb = item / nblk, nb = item % nblk, k0 = 64 * kb, n0 = 64 * nb;
;     const int lr = lane >> 4, lc = (lane & 15) * 4;
;     f32x4 v[16];
; #pragma unroll
;     for (int i = 0; i < 16; ++i) v[i] = *(const f32x4*)(W + (size_t)(k0 + 4 * i + lr) * N + n0 + lc);
; #pragma unroll
;     for (int i = 0; i < 16; ++i) { const int kk = 4 * i + lr; f32x4 w = v[i]; if (scale) w = w * scale[k0 + kk]; float* d = scr + kk * 65 + lc; d[0] = w[0]; d[1] = w[1]; d[2] = w[2]; d[3] = w[3]; }
.LBB0_466:
	s_andn2_b64 vcc, exec, s[2:3]
	s_cbranch_vccnz .LBB0_429
	v_readlane_b32 s48, v253, 2
	s_mul_i32 s2, s0, 0x3c00000
	v_readlane_b32 s52, v253, 6
	s_mul_hi_i32 s1, s0, 0x3c00000
	v_readlane_b32 s53, v253, 7
	s_add_u32 s3, s52, s2
	s_addc_u32 s6, s53, s1
	s_mul_hi_i32 s1, s0, 0x1e00000
	s_mul_i32 s0, s0, 0x1e00000
	s_add_u32 s7, s27, s0
	s_mul_i32 s0, s47, 0xffff8889
	s_addc_u32 s14, s36, s1
	s_lshr_b32 s0, s0, 16
	s_add_i32 s0, s0, s47
	s_sext_i32_i16 s1, s0
	s_ashr_i32 s1, s1, 6
	s_bfe_u32 s0, s0, 0x1000f
	s_add_i32 s0, s1, s0
	s_sext_i32_i16 s1, s0
	s_mulk_i32 s0, 0x78
	s_sub_i32 s0, s47, s0
	s_sext_i32_i16 s0, s0
	s_lshl_b32 s0, s0, 6
	s_lshl_b32 s2, s1, 6
	s_ashr_i32 s1, s0, 31
	s_lshl_b64 s[4:5], s[0:1], 2
	v_or_b32_e32 v2, s2, v69
	s_add_u32 s4, s3, s4
	s_addc_u32 s5, s6, s5
	v_lshlrev_b32_e32 v168, 2, v68
	v_mul_i32_i24_e32 v2, 0x1e00, v2
	v_lshl_add_u64 v[0:1], s[4:5], 0, v[168:169]
	v_ashrrev_i32_e32 v3, 31, v2
	v_lshl_add_u64 v[60:61], v[2:3], 2, v[0:1]
	s_mov_b32 s1, 0x1e000
	v_add_co_u32_e32 v4, vcc, s1, v60
	s_mov_b32 s1, 0x3c000
	s_nop 0
	v_addc_co_u32_e32 v5, vcc, 0, v61, vcc
	v_add_co_u32_e32 v8, vcc, s1, v60
	global_load_dwordx4 v[0:3], v[60:61], off
	s_nop 0
	global_load_dwordx4 v[4:7], v[4:5], off
	v_addc_co_u32_e32 v9, vcc, 0, v61, vcc
	s_mov_b32 s1, 0x5a000
	v_add_co_u32_e32 v12, vcc, s1, v60
	s_mov_b32 s1, 0x78000
	s_nop 0
	v_addc_co_u32_e32 v13, vcc, 0, v61, vcc
	global_load_dwordx4 v[8:11], v[8:9], off
	s_nop 0
	global_load_dwordx4 v[12:15], v[12:13], off
	v_add_co_u32_e32 v16, vcc, s1, v60
	s_mov_b32 s1, 0x96000
	s_nop 0
	v_addc_co_u32_e32 v17, vcc, 0, v61, vcc
	v_add_co_u32_e32 v20, vcc, s1, v60
	s_mov_b32 s1, 0xb4000
	s_nop 0
	v_addc_co_u32_e32 v21, vcc, 0, v61, vcc
	global_load_dwordx4 v[16:19], v[16:17], off
	s_nop 0
	global_load_dwordx4 v[20:23], v[20:21], off
	v_add_co_u32_e32 v24, vcc, s1, v60
	s_mov_b32 s1, 0xd2000
	s_nop 0
	v_addc_co_u32_e32 v25, vcc, 0, v61, vcc
	v_add_co_u32_e32 v28, vcc, s1, v60
	s_mov_b32 s1, 0xf0000
	s_nop 0
	v_addc_co_u32_e32 v29, vcc, 0, v61, vcc
	global_load_dwordx4 v[24:27], v[24:25], off
	s_nop 0
	global_load_dwordx4 v[28:31], v[28:29], off
	v_add_co_u32_e32 v32, vcc, s1, v60
	s_mov_b32 s1, 0x10e000
	s_nop 0
	v_addc_co_u32_e32 v33, vcc, 0, v61, vcc
	v_add_co_u32_e32 v36, vcc, s1, v60
	s_mov_b32 s1, 0x12c000
	s_nop 0
	v_addc_co_u32_e32 v37, vcc, 0, v61, vcc
	global_load_dwordx4 v[32:35], v[32:33], off
	s_nop 0
	global_load_dwordx4 v[36:39], v[36:37], off
	v_add_co_u32_e32 v40, vcc, s1, v60
	s_mov_b32 s1, 0x14a000
	s_nop 0
	v_addc_co_u32_e32 v41, vcc, 0, v61, vcc
	v_add_co_u32_e32 v44, vcc, s1, v60
	s_mov_b32 s1, 0x168000
	s_nop 0
	v_addc_co_u32_e32 v45, vcc, 0, v61, vcc
	global_load_dwordx4 v[40:43], v[40:41], off
	s_nop 0
	global_load_dwordx4 v[44:47], v[44:45], off
	v_add_co_u32_e32 v48, vcc, s1, v60
	s_mov_b32 s1, 0x186000
	s_nop 0
	v_addc_co_u32_e32 v49, vcc, 0, v61, vcc
	global_load_dwordx4 v[48:51], v[48:49], off
	v_add_co_u32_e32 v52, vcc, s1, v60
	s_mov_b32 s1, 0x1a4000
	s_nop 0
	v_addc_co_u32_e32 v53, vcc, 0, v61, vcc
	global_load_dwordx4 v[52:55], v[52:53], off
	v_add_co_u32_e32 v56, vcc, s1, v60
	s_mov_b32 s1, 0x1c2000
	s_nop 0
	v_addc_co_u32_e32 v57, vcc, 0, v61, vcc
	global_load_dwordx4 v[56:59], v[56:57], off
	v_add_co_u32_e32 v60, vcc, s1, v60
	s_ashr_i32 s3, s2, 31
	s_nop 0
	v_addc_co_u32_e32 v61, vcc, 0, v61, vcc
	global_load_dwordx4 v[60:63], v[60:61], off
	s_waitcnt vmcnt(0)
	ds_write2_b32 v71, v0, v1 offset1:1
	ds_write2_b32 v71, v2, v3 offset0:2 offset1:3
	v_add_u32_e32 v0, 0x410, v71
	ds_write2_b32 v0, v4, v5 offset1:1
	v_add_u32_e32 v0, 0x418, v71
	ds_write2_b32 v0, v6, v7 offset1:1
	v_add_u32_e32 v0, 0x820, v71
	s_lshl_b64 s[2:3], s[2:3], 1
	s_add_u32 s2, s7, s2
	s_addc_u32 s3, s14, s3
	ds_write2_b32 v0, v8, v9 offset1:1
	v_add_u32_e32 v0, 0x828, v71
	ds_write2_b32 v0, v10, v11 offset1:1
	v_add_u32_e32 v0, 0xc30, v71
	ds_write2_b32 v0, v12, v13 offset1:1
	v_add_u32_e32 v0, 0xc38, v71
	ds_write2_b32 v0, v14, v15 offset1:1
	v_add_u32_e32 v0, 0x1040, v71
	v_lshlrev_b32_e32 v168, 1, v70
	v_lshl_add_u64 v[4:5], s[2:3], 0, v[168:169]
	v_readlane_b32 s49, v253, 3
	ds_write2_b32 v0, v16, v17 offset1:1
	v_add_u32_e32 v0, 0x1048, v71
	ds_write2_b32 v0, v18, v19 offset1:1
	v_add_u32_e32 v0, 0x1450, v71
	ds_write2_b32 v0, v20, v21 offset1:1
	v_add_u32_e32 v0, 0x1458, v71
	ds_write2_b32 v0, v22, v23 offset1:1
	v_add_u32_e32 v0, 0x1860, v71
	v_readlane_b32 s50, v253, 4
	v_readlane_b32 s51, v253, 5
	v_readlane_b32 s54, v253, 8
	ds_write2_b32 v0, v24, v25 offset1:1
	v_add_u32_e32 v0, 0x1868, v71
	ds_write2_b32 v0, v26, v27 offset1:1
	v_add_u32_e32 v0, 0x1c70, v71
	ds_write2_b32 v0, v28, v29 offset1:1
	v_add_u32_e32 v0, 0x1c78, v71
	ds_write2_b32 v0, v30, v31 offset1:1
	v_add_u32_e32 v0, 0x2080, v71
	v_readlane_b32 s55, v253, 9
	v_readlane_b32 s56, v253, 10
	v_readlane_b32 s57, v253, 11
	ds_write2_b32 v0, v32, v33 offset1:1
	v_add_u32_e32 v0, 0x2088, v71
	ds_write2_b32 v0, v34, v35 offset1:1
	v_add_u32_e32 v0, 0x2490, v71
	ds_write2_b32 v0, v36, v37 offset1:1
	v_add_u32_e32 v0, 0x2498, v71
	ds_write2_b32 v0, v38, v39 offset1:1
	v_add_u32_e32 v0, 0x28a0, v71
	v_readlane_b32 s58, v253, 12
	v_readlane_b32 s59, v253, 13
	v_readlane_b32 s60, v253, 14
	ds_write2_b32 v0, v40, v41 offset1:1
	v_add_u32_e32 v0, 0x28a8, v71
	ds_write2_b32 v0, v42, v43 offset1:1
	v_add_u32_e32 v0, 0x2cb0, v71
	ds_write2_b32 v0, v44, v45 offset1:1
	v_add_u32_e32 v0, 0x2cb8, v71
	ds_write2_b32 v0, v46, v47 offset1:1
	v_add_u32_e32 v0, 0x30c0, v71
	ds_write2_b32 v0, v48, v49 offset1:1
	v_add_u32_e32 v0, 0x30c8, v71
	ds_write2_b32 v0, v50, v51 offset1:1
	v_add_u32_e32 v0, 0x34d0, v71
	v_readlane_b32 s61, v253, 15
	ds_write2_b32 v0, v52, v53 offset1:1
	v_add_u32_e32 v0, 0x34d8, v71
	ds_write2_b32 v0, v54, v55 offset1:1
	v_add_u32_e32 v0, 0x38e0, v71
	v_readlane_b32 s62, v253, 16
	v_readlane_b32 s63, v253, 17
	ds_write2_b32 v0, v56, v57 offset1:1
	v_add_u32_e32 v0, 0x38e8, v71
	ds_write2_b32 v0, v58, v59 offset1:1
	v_add_u32_e32 v0, 0x3cf0, v71
	ds_write2_b32 v0, v60, v61 offset1:1
	v_add_u32_e32 v0, 0x3cf8, v71
	ds_write2_b32 v0, v62, v63 offset1:1
	s_waitcnt lgkmcnt(0)
; #define LDS_WAIT() asm volatile("s_waitcnt lgkmcnt(0)" ::: "memory")
; __device__ __forceinline__ unsigned pk2(float lo, float hi) { unsigned r; asm("v_cvt_pk_bf16_f32 %0, %1, %2" : "=v"(r) : "v"(lo), "v"(hi)); return r; }
; __device__ __forceinline__ void p0_transpose_item(const float* W, int K, int N, bf16* WT, float* scr, int item, int lane, const float* scale, const float* cb, float* c1, float* c2) {
;     ...
;     LDS_WAIT(); asm volatile("" ::: "memory");
;     const int c = lane & 7;
; #pragma unroll
;     for (int j = 0; j < 8; ++j) { const int n = (lane >> 3) + 8 * j; const float* sp = scr + (8 * c) * 65 + n;
;         v4u o; o.x = pk2(sp[0 * 65], sp[1 * 65]); o.y = pk2(sp[2 * 65], sp[3 * 65]); o.z = pk2(sp[4 * 65], sp[5 * 65]); o.w = pk2(sp[6 * 65], sp[7 * 65]);
;         *(v4u*)(WT + (size_t)(n0 + n) * K + k0 + 8 * c) = o; }
	ds_read_b32 v0, v81
	ds_read_b32 v1, v81 offset:260
	ds_read_b32 v2, v81 offset:520
	ds_read_b32 v3, v81 offset:780
	ds_read_b32 v6, v81 offset:1040
	ds_read_b32 v7, v81 offset:1300
	ds_read_b32 v8, v81 offset:1560
	ds_read_b32 v9, v81 offset:1820
	s_waitcnt lgkmcnt(0)
	v_cvt_pk_bf16_f32 v0, v0, v1
	v_cvt_pk_bf16_f32 v1, v2, v3
	v_cvt_pk_bf16_f32 v2, v6, v7
	v_or_b32_e32 v6, s0, v80
	v_ashrrev_i32_e32 v7, 31, v6
	v_lshlrev_b64 v[6:7], 12, v[6:7]
	v_lshl_add_u64 v[6:7], v[4:5], 0, v[6:7]
	v_cvt_pk_bf16_f32 v3, v8, v9
	global_store_dwordx4 v[6:7], v[0:3], off
	ds_read_b32 v0, v81 offset:32
	ds_read_b32 v1, v81 offset:292
	ds_read_b32 v2, v81 offset:552
	ds_read_b32 v3, v81 offset:812
	ds_read_b32 v6, v81 offset:1072
	ds_read_b32 v7, v81 offset:1332
	ds_read_b32 v8, v81 offset:1592
	ds_read_b32 v9, v81 offset:1852
	s_waitcnt lgkmcnt(0)
	v_cvt_pk_bf16_f32 v0, v0, v1
	v_cvt_pk_bf16_f32 v1, v2, v3
	v_cvt_pk_bf16_f32 v2, v6, v7
	v_or_b32_e32 v6, s0, v82
	v_ashrrev_i32_e32 v7, 31, v6
	v_lshlrev_b64 v[6:7], 12, v[6:7]
	v_lshl_add_u64 v[6:7], v[4:5], 0, v[6:7]
	v_cvt_pk_bf16_f32 v3, v8, v9
	global_store_dwordx4 v[6:7], v[0:3], off
	ds_read_b32 v0, v81 offset:64
	ds_read_b32 v1, v81 offset:324
	ds_read_b32 v2, v81 offset:584
	ds_read_b32 v3, v81 offset:844
	ds_read_b32 v6, v81 offset:1104
	ds_read_b32 v7, v81 offset:1364
	ds_read_b32 v8, v81 offset:1624
	ds_read_b32 v9, v81 offset:1884
	s_waitcnt lgkmcnt(0)
	v_cvt_pk_bf16_f32 v0, v0, v1
	v_cvt_pk_bf16_f32 v1, v2, v3
	v_cvt_pk_bf16_f32 v2, v6, v7
	v_or_b32_e32 v6, s0, v83
	v_ashrrev_i32_e32 v7, 31, v6
	v_lshlrev_b64 v[6:7], 12, v[6:7]
	v_lshl_add_u64 v[6:7], v[4:5], 0, v[6:7]
	v_cvt_pk_bf16_f32 v3, v8, v9
	global_store_dwordx4 v[6:7], v[0:3], off
	ds_read_b32 v0, v81 offset:96
	ds_read_b32 v1, v81 offset:356
	ds_read_b32 v2, v81 offset:616
	ds_read_b32 v3, v81 offset:876
	ds_read_b32 v6, v81 offset:1136
	ds_read_b32 v7, v81 offset:1396
	ds_read_b32 v8, v81 offset:1656
	ds_read_b32 v9, v81 offset:1916
	s_waitcnt lgkmcnt(0)
	v_cvt_pk_bf16_f32 v0, v0, v1
	v_cvt_pk_bf16_f32 v1, v2, v3
	v_cvt_pk_bf16_f32 v2, v6, v7
	v_or_b32_e32 v6, s0, v84
	v_ashrrev_i32_e32 v7, 31, v6
	v_lshlrev_b64 v[6:7], 12, v[6:7]
	v_lshl_add_u64 v[6:7], v[4:5], 0, v[6:7]
	v_cvt_pk_bf16_f32 v3, v8, v9
	global_store_dwordx4 v[6:7], v[0:3], off
	ds_read_b32 v0, v81 offset:128
	ds_read_b32 v1, v81 offset:388
	ds_read_b32 v2, v81 offset:648
	ds_read_b32 v3, v81 offset:908
	ds_read_b32 v6, v81 offset:1168
	ds_read_b32 v7, v81 offset:1428
	ds_read_b32 v8, v81 offset:1688
	ds_read_b32 v9, v81 offset:1948
	s_waitcnt lgkmcnt(0)
	v_cvt_pk_bf16_f32 v0, v0, v1
	v_cvt_pk_bf16_f32 v1, v2, v3
	v_cvt_pk_bf16_f32 v2, v6, v7
	v_or_b32_e32 v6, s0, v85
	v_ashrrev_i32_e32 v7, 31, v6
	v_lshlrev_b64 v[6:7], 12, v[6:7]
	v_lshl_add_u64 v[6:7], v[4:5], 0, v[6:7]
	v_cvt_pk_bf16_f32 v3, v8, v9
	global_store_dwordx4 v[6:7], v[0:3], off
	ds_read_b32 v0, v81 offset:160
	ds_read_b32 v1, v81 offset:420
	ds_read_b32 v2, v81 offset:680
	ds_read_b32 v3, v81 offset:940
	ds_read_b32 v6, v81 offset:1200
	ds_read_b32 v7, v81 offset:1460
	ds_read_b32 v8, v81 offset:1720
	ds_read_b32 v9, v81 offset:1980
	s_waitcnt lgkmcnt(0)
	v_cvt_pk_bf16_f32 v0, v0, v1
	v_cvt_pk_bf16_f32 v1, v2, v3
	v_cvt_pk_bf16_f32 v2, v6, v7
	v_or_b32_e32 v6, s0, v86
	v_ashrrev_i32_e32 v7, 31, v6
	v_lshlrev_b64 v[6:7], 12, v[6:7]
	v_lshl_add_u64 v[6:7], v[4:5], 0, v[6:7]
	v_cvt_pk_bf16_f32 v3, v8, v9
	global_store_dwordx4 v[6:7], v[0:3], off
	ds_read_b32 v0, v81 offset:192
	ds_read_b32 v1, v81 offset:452
	ds_read_b32 v2, v81 offset:712
	ds_read_b32 v3, v81 offset:972
	ds_read_b32 v6, v81 offset:1232
	ds_read_b32 v7, v81 offset:1492
	ds_read_b32 v8, v81 offset:1752
	ds_read_b32 v9, v81 offset:2012
	s_waitcnt lgkmcnt(0)
	v_cvt_pk_bf16_f32 v0, v0, v1
	v_cvt_pk_bf16_f32 v1, v2, v3
	v_cvt_pk_bf16_f32 v2, v6, v7
	v_or_b32_e32 v6, s0, v87
	v_ashrrev_i32_e32 v7, 31, v6
	v_lshlrev_b64 v[6:7], 12, v[6:7]
	v_lshl_add_u64 v[6:7], v[4:5], 0, v[6:7]
	v_cvt_pk_bf16_f32 v3, v8, v9
	global_store_dwordx4 v[6:7], v[0:3], off
	ds_read_b32 v0, v81 offset:224
	ds_read_b32 v1, v81 offset:484
	ds_read_b32 v2, v81 offset:744
	ds_read_b32 v3, v81 offset:1004
	ds_read_b32 v6, v81 offset:1264
	ds_read_b32 v7, v81 offset:1524
	ds_read_b32 v8, v81 offset:1784
	ds_read_b32 v9, v81 offset:2044
	s_waitcnt lgkmcnt(0)
	v_cvt_pk_bf16_f32 v0, v0, v1
	v_cvt_pk_bf16_f32 v1, v2, v3
	v_cvt_pk_bf16_f32 v2, v6, v7
	v_or_b32_e32 v6, s0, v88
	v_ashrrev_i32_e32 v7, 31, v6
	v_lshlrev_b64 v[6:7], 12, v[6:7]
	v_lshl_add_u64 v[4:5], v[4:5], 0, v[6:7]
	v_cvt_pk_bf16_f32 v3, v8, v9
	global_store_dwordx4 v[4:5], v[0:3], off
	s_waitcnt lgkmcnt(0)
	s_branch .LBB0_429

; __device__ __forceinline__ void hgrn_pass1(const bf16* h, const float* lbraw, int layer, float* US, float* DD, char* lds, int wg, int G) {
;     ...
;         __syncthreads();
; #pragma unroll
;         for (int mbi = 0; mbi < 2; ++mbi) { const int mb = 2 * hw + mbi;
;             pg8::f32x4 acc[8];
; #pragma unroll
;             for (int nb = 0; nb < 8; ++nb) acc[nb] = (pg8::f32x4){0.f, 0.f, 0.f, 0.f};
; #pragma unroll
;             for (int ks = 0; ks < 2; ++ks) { const hbf16x8 af = *(const hbf16x8*)(L + (16 * mb + li) * 160 + ks * 64 + g * 16);
; #pragma unroll
;                 for (int nb = 0; nb < 8; ++nb) { const hbf16x8 bb = *(const hbf16x8*)(L + 20480 + (16 * nb + li) * 160 + ks * 64 + g * 16); acc[nb] = __builtin_amdgcn_mfma_f32_16x16x32_bf16(af, bb, acc[nb], 0, 0, 0); } }
; #pragma unroll
;             for (int nb = 0; nb < 8; ++nb) *(pg8::f32x4*)(US + (size_t)item * 16384 + (16 * nb + li) * 128 + 16 * mb + 4 * g) = acc[nb]; }
;         __syncthreads();
.LBB0_518:
	s_or_b64 exec, exec, s[8:9]
	s_waitcnt lgkmcnt(0)
	s_barrier
	ds_read_b128 v[0:3], v41
	ds_read_b128 v[4:7], v42 offset:20480
	ds_read_b128 v[8:11], v42 offset:23040
	ds_read_b128 v[60:63], v42 offset:38400
	ds_read_b128 v[12:15], v42 offset:25600
	ds_read_b128 v[44:47], v42 offset:28160
	ds_read_b128 v[48:51], v42 offset:30720
	ds_read_b128 v[52:55], v42 offset:33280
	ds_read_b128 v[56:59], v42 offset:35840
	s_waitcnt lgkmcnt(0)
	v_mfma_f32_16x16x32_bf16 v[4:7], v[0:3], v[4:7], 0
	s_ashr_i32 s7, s6, 31
	s_lshl_b64 s[8:9], s[6:7], 16
	v_lshl_add_u64 v[68:69], v[20:21], 0, s[8:9]
	v_mfma_f32_16x16x32_bf16 v[8:11], v[0:3], v[8:11], 0
	v_mov_b32_e32 v25, v169
	v_lshl_add_u64 v[70:71], v[68:69], 0, v[24:25]
	v_mov_b32_e32 v27, v169
	v_mfma_f32_16x16x32_bf16 v[12:15], v[0:3], v[12:15], 0
	v_mov_b32_e32 v29, v169
	v_mov_b32_e32 v31, v169
	v_mov_b32_e32 v33, v169
	v_mfma_f32_16x16x32_bf16 v[44:47], v[0:3], v[44:47], 0
	v_mov_b32_e32 v35, v169
	v_mov_b32_e32 v37, v169
	v_mov_b32_e32 v39, v169
	v_mfma_f32_16x16x32_bf16 v[48:51], v[0:3], v[48:51], 0
	v_readlane_b32 s7, v255, 11
	s_add_i32 s24, s24, s86
	v_mfma_f32_16x16x32_bf16 v[52:55], v[0:3], v[52:55], 0
	v_add_u32_e32 v22, s7, v22
	v_readlane_b32 s7, v255, 13
	s_add_i32 s6, s6, s7
	v_mfma_f32_16x16x32_bf16 v[56:59], v[0:3], v[56:59], 0
	v_readlane_b32 s7, v255, 15
	s_add_i32 s14, s14, s7
	v_readlane_b32 s7, v255, 17
	v_mfma_f32_16x16x32_bf16 v[0:3], v[0:3], v[60:63], 0
	ds_read_b128 v[60:63], v41 offset:64
	ds_read_b128 v[64:67], v42 offset:20544
	s_add_i32 s15, s15, s7
	s_cmpk_lt_i32 s24, 0x100
	s_waitcnt lgkmcnt(0)
	v_mfma_f32_16x16x32_bf16 v[4:7], v[60:63], v[64:67], v[4:7]
	ds_read_b128 v[64:67], v42 offset:23104
	s_waitcnt lgkmcnt(0)
	v_mfma_f32_16x16x32_bf16 v[8:11], v[60:63], v[64:67], v[8:11]
	ds_read_b128 v[64:67], v42 offset:25664
	s_waitcnt lgkmcnt(0)
	v_mfma_f32_16x16x32_bf16 v[12:15], v[60:63], v[64:67], v[12:15]
	ds_read_b128 v[64:67], v42 offset:28224
	s_waitcnt lgkmcnt(0)
	v_mfma_f32_16x16x32_bf16 v[44:47], v[60:63], v[64:67], v[44:47]
	ds_read_b128 v[64:67], v42 offset:30784
	s_waitcnt lgkmcnt(0)
	v_mfma_f32_16x16x32_bf16 v[48:51], v[60:63], v[64:67], v[48:51]
	ds_read_b128 v[64:67], v42 offset:33344
	s_waitcnt lgkmcnt(0)
	v_mfma_f32_16x16x32_bf16 v[52:55], v[60:63], v[64:67], v[52:55]
	ds_read_b128 v[64:67], v42 offset:35904
	s_waitcnt lgkmcnt(0)
	v_mfma_f32_16x16x32_bf16 v[56:59], v[60:63], v[64:67], v[56:59]
	ds_read_b128 v[64:67], v42 offset:38464
	global_store_dwordx4 v[70:71], v[4:7], off
	s_waitcnt lgkmcnt(0)
	v_mfma_f32_16x16x32_bf16 v[0:3], v[60:63], v[64:67], v[0:3]
	v_lshl_add_u64 v[4:5], v[68:69], 0, v[26:27]
	global_store_dwordx4 v[4:5], v[8:11], off
	v_lshl_add_u64 v[4:5], v[68:69], 0, v[28:29]
	global_store_dwordx4 v[4:5], v[12:15], off
	v_lshl_add_u64 v[4:5], v[68:69], 0, v[30:31]
	global_store_dwordx4 v[4:5], v[44:47], off
	v_lshl_add_u64 v[4:5], v[68:69], 0, v[32:33]
	global_store_dwordx4 v[4:5], v[48:51], off
	v_lshl_add_u64 v[4:5], v[68:69], 0, v[34:35]
	global_store_dwordx4 v[4:5], v[52:55], off
	v_lshl_add_u64 v[4:5], v[68:69], 0, v[36:37]
	global_store_dwordx4 v[4:5], v[56:59], off
	v_lshl_add_u64 v[4:5], v[68:69], 0, v[38:39]
	global_store_dwordx4 v[4:5], v[0:3], off
	ds_read_b128 v[0:3], v43
	ds_read_b128 v[4:7], v42 offset:20480
	ds_read_b128 v[8:11], v42 offset:23040
	ds_read_b128 v[60:63], v42 offset:38400
	ds_read_b128 v[12:15], v42 offset:25600
	ds_read_b128 v[44:47], v42 offset:28160
	ds_read_b128 v[48:51], v42 offset:30720
	ds_read_b128 v[52:55], v42 offset:33280
	ds_read_b128 v[56:59], v42 offset:35840
	s_waitcnt lgkmcnt(0)
	v_mfma_f32_16x16x32_bf16 v[4:7], v[0:3], v[4:7], 0
	v_mfma_f32_16x16x32_bf16 v[8:11], v[0:3], v[8:11], 0
	v_mfma_f32_16x16x32_bf16 v[12:15], v[0:3], v[12:15], 0
	v_mfma_f32_16x16x32_bf16 v[44:47], v[0:3], v[44:47], 0
	v_mfma_f32_16x16x32_bf16 v[48:51], v[0:3], v[48:51], 0
	v_mfma_f32_16x16x32_bf16 v[52:55], v[0:3], v[52:55], 0
	v_mfma_f32_16x16x32_bf16 v[56:59], v[0:3], v[56:59], 0
	v_mfma_f32_16x16x32_bf16 v[0:3], v[0:3], v[60:63], 0
	ds_read_b128 v[60:63], v43 offset:64
	ds_read_b128 v[64:67], v42 offset:20544
	s_waitcnt lgkmcnt(0)
	v_mfma_f32_16x16x32_bf16 v[4:7], v[60:63], v[64:67], v[4:7]
	ds_read_b128 v[64:67], v42 offset:23104
	s_waitcnt lgkmcnt(0)
	v_mfma_f32_16x16x32_bf16 v[8:11], v[60:63], v[64:67], v[8:11]
	ds_read_b128 v[64:67], v42 offset:25664
	s_waitcnt lgkmcnt(0)
	v_mfma_f32_16x16x32_bf16 v[12:15], v[60:63], v[64:67], v[12:15]
	ds_read_b128 v[64:67], v42 offset:28224
	s_waitcnt lgkmcnt(0)
	v_mfma_f32_16x16x32_bf16 v[44:47], v[60:63], v[64:67], v[44:47]
	ds_read_b128 v[64:67], v42 offset:30784
	s_waitcnt lgkmcnt(0)
	v_mfma_f32_16x16x32_bf16 v[48:51], v[60:63], v[64:67], v[48:51]
	ds_read_b128 v[64:67], v42 offset:33344
	s_waitcnt lgkmcnt(0)
	v_mfma_f32_16x16x32_bf16 v[52:55], v[60:63], v[64:67], v[52:55]
	ds_read_b128 v[64:67], v42 offset:35904
	s_waitcnt lgkmcnt(0)
	v_mfma_f32_16x16x32_bf16 v[56:59], v[60:63], v[64:67], v[56:59]
	ds_read_b128 v[64:67], v42 offset:38464
	global_store_dwordx4 v[70:71], v[4:7], off offset:64
	s_waitcnt lgkmcnt(0)
	v_mfma_f32_16x16x32_bf16 v[0:3], v[60:63], v[64:67], v[0:3]
	v_lshl_add_u64 v[60:61], v[68:69], 0, 64
	v_lshl_add_u64 v[4:5], v[60:61], 0, v[26:27]
	global_store_dwordx4 v[4:5], v[8:11], off
	v_lshl_add_u64 v[4:5], v[60:61], 0, v[28:29]
	global_store_dwordx4 v[4:5], v[12:15], off
	v_lshl_add_u64 v[4:5], v[60:61], 0, v[30:31]
	global_store_dwordx4 v[4:5], v[44:47], off
	v_lshl_add_u64 v[4:5], v[60:61], 0, v[32:33]
	global_store_dwordx4 v[4:5], v[48:51], off
	v_lshl_add_u64 v[4:5], v[60:61], 0, v[34:35]
	global_store_dwordx4 v[4:5], v[52:55], off
	v_lshl_add_u64 v[4:5], v[60:61], 0, v[36:37]
	global_store_dwordx4 v[4:5], v[56:59], off
	v_lshl_add_u64 v[4:5], v[60:61], 0, v[38:39]
	global_store_dwordx4 v[4:5], v[0:3], off
	s_waitcnt lgkmcnt(0)
	s_barrier
	s_cbranch_scc0 .LBB0_523
; __device__ __forceinline__ void hgrn_pass1(const bf16* h, const float* lbraw, int layer, float* US, float* DD, char* lds, int wg, int G) {
;     ...
;         const int item = 2 * pair + half, c = item & 63, bh = item >> 6, hh = bh & 3, b = bh >> 2; const size_t m0 = (size_t)b * SEQ + c * 64 + 32 * seg2;
;         const bf16* hp = h + m0 * NH + hh * 128 + k;
;         bf16 fzv[32], ivv[32];
; #pragma unroll
;         for (int i = 0; i < 32; ++i) { fzv[i] = hp[(size_t)i * NH + C_BF]; ivv[i] = hp[(size_t)i * NH + C_BI]; }
.LBB0_519:
	s_ashr_i32 s8, s6, 8
	s_ashr_i32 s9, s8, 31
	s_lshl_b64 s[8:9], s[8:9], 12
	s_and_b32 s7, s15, 0xfc0
	s_or_b32 s7, s8, s7
	v_or_b32_e32 v2, s7, v18
	v_mov_b64_e32 v[0:1], s[0:1]
	v_mad_u64_u32 v[0:1], s[26:27], v2, s13, v[0:1]
	s_and_b32 s7, s14, 0x180
	v_mad_i32_i24 v1, s9, v217, v1
	s_lshl_b32 s28, s7, 1
	v_lshl_add_u64 v[0:1], v[0:1], 0, s[28:29]
	v_lshl_add_u64 v[0:1], v[0:1], 0, v[168:169]
	v_add_co_u32_e32 v2, vcc, s92, v0
	s_movk_i32 s8, 0x5000
	s_nop 0
	v_addc_co_u32_e32 v3, vcc, 0, v1, vcc
	v_add_co_u32_e32 v4, vcc, s89, v0
	global_load_ushort v29, v[2:3], off
	s_nop 0
	global_load_ushort v2, v[2:3], off offset:1024
	v_addc_co_u32_e32 v5, vcc, 0, v1, vcc
	global_load_ushort v37, v[4:5], off offset:3072
	v_add_co_u32_e32 v4, vcc, s8, v0
	s_mov_b32 s8, 0x13000
	s_nop 0
	v_addc_co_u32_e32 v5, vcc, 0, v1, vcc
	global_load_ushort v3, v[4:5], off
	v_add_co_u32_e32 v4, vcc, s90, v0
	v_mov_b32_e32 v27, 0
	s_nop 0
	v_addc_co_u32_e32 v5, vcc, 0, v1, vcc
	v_add_co_u32_e32 v6, vcc, s91, v0
	global_load_ushort v45, v[4:5], off offset:2048
	s_nop 0
	global_load_ushort v4, v[4:5], off offset:3072
	v_addc_co_u32_e32 v7, vcc, 0, v1, vcc
	global_load_ushort v49, v[6:7], off offset:1024
	global_load_ushort v5, v[6:7], off offset:2048
	v_add_co_u32_e32 v6, vcc, s88, v0
	s_nop 1
	v_addc_co_u32_e32 v7, vcc, 0, v1, vcc
	v_add_co_u32_e32 v8, vcc, s8, v0
	s_mov_b32 s8, 0x14000
	s_nop 0
	v_addc_co_u32_e32 v9, vcc, 0, v1, vcc
	global_load_ushort v51, v[6:7], off
	s_nop 0
	global_load_ushort v6, v[6:7], off offset:1024
	s_nop 0
	global_load_ushort v55, v[8:9], off offset:3072
	v_add_co_u32_e32 v8, vcc, s8, v0
	s_mov_b32 s8, 0x17000
	s_nop 0
	v_addc_co_u32_e32 v9, vcc, 0, v1, vcc
	global_load_ushort v7, v[8:9], off
	v_add_co_u32_e32 v8, vcc, s8, v0
	s_mov_b32 s8, 0x1b000
	s_nop 0
	v_addc_co_u32_e32 v9, vcc, 0, v1, vcc
	v_add_co_u32_e32 v10, vcc, s8, v0
	s_mov_b32 s8, 0x1f000
	s_nop 0
	v_addc_co_u32_e32 v11, vcc, 0, v1, vcc
	global_load_ushort v57, v[8:9], off offset:2048
	s_nop 0
	global_load_ushort v8, v[8:9], off offset:3072
	s_nop 0
	global_load_ushort v61, v[10:11], off offset:1024
	global_load_ushort v9, v[10:11], off offset:2048
	v_add_co_u32_e32 v10, vcc, s8, v0
	s_mov_b32 s8, 0x22000
	s_nop 0
	v_addc_co_u32_e32 v11, vcc, 0, v1, vcc
	v_add_co_u32_e32 v12, vcc, s8, v0
	s_mov_b32 s8, 0x23000
	s_nop 0
	v_addc_co_u32_e32 v13, vcc, 0, v1, vcc
	global_load_ushort v64, v[10:11], off
	s_nop 0
	global_load_ushort v10, v[10:11], off offset:1024
	s_nop 0
	global_load_ushort v67, v[12:13], off offset:3072
	v_add_co_u32_e32 v12, vcc, s8, v0
	s_mov_b32 s8, 0x26000
	s_nop 0
	v_addc_co_u32_e32 v13, vcc, 0, v1, vcc
	global_load_ushort v11, v[12:13], off
	v_add_co_u32_e32 v12, vcc, s8, v0
	s_mov_b32 s8, 0x2a000
	s_nop 0
	v_addc_co_u32_e32 v13, vcc, 0, v1, vcc
	v_add_co_u32_e32 v14, vcc, s8, v0
	s_mov_b32 s8, 0x2e000
	s_nop 0
	v_addc_co_u32_e32 v15, vcc, 0, v1, vcc
	global_load_ushort v70, v[12:13], off offset:2048
	s_nop 0
	global_load_ushort v12, v[12:13], off offset:3072
	s_nop 0
	global_load_ushort v74, v[14:15], off offset:1024
	global_load_ushort v13, v[14:15], off offset:2048
	v_add_co_u32_e32 v14, vcc, s8, v0
	s_mov_b32 s8, 0x31000
	s_nop 0
	v_addc_co_u32_e32 v15, vcc, 0, v1, vcc
	v_add_co_u32_e32 v46, vcc, s8, v0
	s_mov_b32 s8, 0x32000
	s_nop 0
	v_addc_co_u32_e32 v47, vcc, 0, v1, vcc
	global_load_ushort v77, v[14:15], off
	s_nop 0
	global_load_ushort v14, v[14:15], off offset:1024
	s_nop 0
	global_load_ushort v80, v[46:47], off offset:3072
	v_add_co_u32_e32 v46, vcc, s8, v0
	s_mov_b32 s8, 0x35000
	s_nop 0
	v_addc_co_u32_e32 v47, vcc, 0, v1, vcc
	global_load_ushort v15, v[46:47], off
	v_add_co_u32_e32 v46, vcc, s8, v0
	s_mov_b32 s8, 0x39000
	s_nop 0
	v_addc_co_u32_e32 v47, vcc, 0, v1, vcc
	global_load_ushort v81, v[46:47], off offset:2048
	global_load_ushort v31, v[46:47], off offset:3072
	v_add_co_u32_e32 v46, vcc, s8, v0
	s_mov_b32 s8, 0x3d000
	s_nop 0
	v_addc_co_u32_e32 v47, vcc, 0, v1, vcc
	global_load_ushort v79, v[46:47], off offset:1024
	global_load_ushort v35, v[46:47], off offset:2048
	v_add_co_u32_e32 v46, vcc, s8, v0
	s_mov_b32 s8, 0x40000
	s_nop 0
	v_addc_co_u32_e32 v47, vcc, 0, v1, vcc
	global_load_ushort v76, v[46:47], off
	global_load_ushort v44, v[46:47], off offset:1024
	v_add_co_u32_e32 v46, vcc, s8, v0
	s_mov_b32 s8, 0x41000
	s_nop 0
	v_addc_co_u32_e32 v47, vcc, 0, v1, vcc
	global_load_ushort v73, v[46:47], off offset:3072
	v_add_co_u32_e32 v46, vcc, s8, v0
	s_mov_b32 s8, 0x44000
	s_nop 0
	v_addc_co_u32_e32 v47, vcc, 0, v1, vcc
	v_add_co_u32_e32 v52, vcc, s8, v0
	s_mov_b32 s8, 0x48000
	s_nop 0
	v_addc_co_u32_e32 v53, vcc, 0, v1, vcc
	global_load_ushort v46, v[46:47], off
	s_nop 0
	global_load_ushort v71, v[52:53], off offset:2048
	global_load_ushort v50, v[52:53], off offset:3072
	v_add_co_u32_e32 v52, vcc, s8, v0
	s_mov_b32 s8, 0x4c000
	s_nop 0
	v_addc_co_u32_e32 v53, vcc, 0, v1, vcc
	v_add_co_u32_e32 v58, vcc, s8, v0
	s_mov_b32 s8, 0x4f000
	s_nop 0
	v_addc_co_u32_e32 v59, vcc, 0, v1, vcc
	global_load_ushort v69, v[52:53], off offset:1024
	s_nop 0
	global_load_ushort v53, v[52:53], off offset:2048
	s_nop 0
	global_load_ushort v66, v[58:59], off
	global_load_ushort v56, v[58:59], off offset:1024
	v_add_co_u32_e32 v58, vcc, s8, v0
	s_mov_b32 s8, 0x50000
	s_nop 0
	v_addc_co_u32_e32 v59, vcc, 0, v1, vcc
	global_load_ushort v62, v[58:59], off offset:3072
	v_add_co_u32_e32 v58, vcc, s8, v0
	s_mov_b32 s8, 0x53000
	s_nop 0
	v_addc_co_u32_e32 v59, vcc, 0, v1, vcc
	v_add_co_u32_e32 v82, vcc, s8, v0
	s_mov_b32 s8, 0x57000
	s_nop 0
	v_addc_co_u32_e32 v83, vcc, 0, v1, vcc
	global_load_ushort v59, v[58:59], off
	s_nop 0
; __device__ __forceinline__ float bf1(bf16 b) { return __uint_as_float(((unsigned)b) << 16); }
; __device__ __forceinline__ float hg_lb(const float* lbraw, int layer, int ch) { if (layer == 0) return 0.f; const float e0 = __expf(lbraw[ch]), e1 = __expf(lbraw[GW + ch]); return e1 / (e0 + e1); }
; __device__ __forceinline__ void hg_gate(float fzraw, float lb, float& gl, float& kk) { const float fz = fminf(fmaxf(fzraw, -80.f), 80.f), ex = __expf(-fz), sg = __builtin_amdgcn_rcpf(1.f + ex);
;     gl = __builtin_amdgcn_logf(fmaxf(lb + (1.f - lb) * sg, 1e-30f)) * 0.6931471805599453f;     kk = (1.f - lb) * (ex * sg); }
; __device__ __forceinline__ void hgrn_pass1(const bf16* h, const float* lbraw, int layer, float* US, float* DD, char* lds, int wg, int G) {
;     ...
;         for (int i = 0; i < 32; ++i) { fzv[i] = hp[(size_t)i * NH + C_BF]; ivv[i] = hp[(size_t)i * NH + C_BI]; }
;         const float lb = hg_lb(lbraw, layer, hh * 128 + k);
;         float bl[32], kk[32], run = 0.f;
; #pragma unroll
;         for (int i = 0; i < 32; ++i) { float gl; hg_gate(bf1(fzv[i]), lb, gl, kk[i]); run += gl; bl[i] = run; }
	global_load_ushort v60, v[82:83], off offset:2048
	global_load_ushort v63, v[82:83], off offset:3072
	v_add_co_u32_e32 v82, vcc, s8, v0
	s_mov_b32 s8, 0x5b000
	s_nop 0
	v_addc_co_u32_e32 v83, vcc, 0, v1, vcc
	global_load_ushort v58, v[82:83], off offset:1024
	global_load_ushort v65, v[82:83], off offset:2048
	v_add_co_u32_e32 v82, vcc, s8, v0
	s_mov_b32 s8, 0x5e000
	s_nop 0
	v_addc_co_u32_e32 v83, vcc, 0, v1, vcc
	global_load_ushort v54, v[82:83], off
	global_load_ushort v68, v[82:83], off offset:1024
	v_add_co_u32_e32 v82, vcc, s8, v0
	s_mov_b32 s8, 0x5f000
	s_nop 0
	v_addc_co_u32_e32 v83, vcc, 0, v1, vcc
	global_load_ushort v52, v[82:83], off offset:3072
	v_add_co_u32_e32 v82, vcc, s8, v0
	s_mov_b32 s8, 0x62000
	s_nop 0
	v_addc_co_u32_e32 v83, vcc, 0, v1, vcc
	global_load_ushort v72, v[82:83], off
	v_add_co_u32_e32 v82, vcc, s8, v0
	s_mov_b32 s8, 0x66000
	s_nop 0
	v_addc_co_u32_e32 v83, vcc, 0, v1, vcc
	global_load_ushort v48, v[82:83], off offset:2048
	global_load_ushort v75, v[82:83], off offset:3072
	v_add_co_u32_e32 v82, vcc, s8, v0
	s_mov_b32 s8, 0x6a000
	s_nop 0
	v_addc_co_u32_e32 v83, vcc, 0, v1, vcc
	global_load_ushort v47, v[82:83], off offset:1024
	global_load_ushort v78, v[82:83], off offset:2048
	v_add_co_u32_e32 v82, vcc, s8, v0
	s_mov_b32 s8, 0x6d000
	s_nop 0
	v_addc_co_u32_e32 v83, vcc, 0, v1, vcc
	v_add_co_u32_e32 v84, vcc, s8, v0
	s_mov_b32 s8, 0x6e000
	s_nop 0
	v_addc_co_u32_e32 v85, vcc, 0, v1, vcc
	global_load_ushort v39, v[82:83], off
	s_nop 0
	global_load_ushort v82, v[82:83], off offset:1024
	s_nop 0
	global_load_ushort v33, v[84:85], off offset:3072
	v_add_co_u32_e32 v84, vcc, s8, v0
	s_nop 1
	v_addc_co_u32_e32 v85, vcc, 0, v1, vcc
	global_load_ushort v83, v[84:85], off
	v_add_co_u32_e32 v84, vcc, 0x71000, v0
	s_nop 1
	v_addc_co_u32_e32 v85, vcc, 0, v1, vcc
	v_add_co_u32_e32 v0, vcc, 0x75000, v0
	global_load_ushort v25, v[84:85], off offset:2048
	s_nop 0
	global_load_ushort v84, v[84:85], off offset:3072
	v_addc_co_u32_e32 v1, vcc, 0, v1, vcc
	global_load_ushort v23, v[0:1], off offset:1024
	global_load_ushort v85, v[0:1], off offset:2048
	s_andn2_b64 vcc, exec, s[94:95]
	s_cbranch_vccnz .LBB0_521
	v_or_b32_e32 v0, s7, v16
	v_readlane_b32 s36, v253, 2
	v_lshlrev_b32_e32 v0, 2, v0
	v_readlane_b32 s44, v253, 10
	v_readlane_b32 s45, v253, 11
	s_nop 4
	global_load_dword v1, v0, s[44:45]
	s_nop 0
	global_load_dword v0, v0, s[44:45] offset:2048
	v_readlane_b32 s37, v253, 3
	v_readlane_b32 s38, v253, 4
	v_readlane_b32 s39, v253, 5
	v_readlane_b32 s40, v253, 6
	v_readlane_b32 s41, v253, 7
	v_readlane_b32 s42, v253, 8
	v_readlane_b32 s43, v253, 9
	v_readlane_b32 s46, v253, 12
	v_readlane_b32 s47, v253, 13
	v_readlane_b32 s48, v253, 14
	v_readlane_b32 s49, v253, 15
	v_readlane_b32 s50, v253, 16
	v_readlane_b32 s51, v253, 17
	s_waitcnt vmcnt(0)
	v_mul_f32_e32 v1, 0x3fb8aa3b, v1
	v_mul_f32_e32 v0, 0x3fb8aa3b, v0
	v_exp_f32_e32 v1, v1
	v_exp_f32_e32 v0, v0
	s_nop 0
	v_add_f32_e32 v1, v1, v0
	v_div_scale_f32 v27, s[8:9], v1, v1, v0
	v_rcp_f32_e32 v86, v27
	v_div_scale_f32 v87, vcc, v0, v1, v0
	v_fma_f32 v88, -v27, v86, 1.0
	v_fmac_f32_e32 v86, v88, v86
	v_mul_f32_e32 v88, v87, v86
	v_fma_f32 v89, -v27, v88, v87
	v_fmac_f32_e32 v88, v89, v86
	v_fma_f32 v27, -v27, v88, v87
	v_div_fmas_f32 v27, v27, v86, v88
	v_div_fixup_f32 v27, v27, v1, v0
.LBB0_521:
	s_waitcnt vmcnt(0) lgkmcnt(0)
	v_lshlrev_b32_e32 v29, 16, v29
	v_max_f32_e32 v29, v29, v29
	v_med3_f32 v29, v29, s11, v218
	v_mul_f32_e32 v29, 0xbfb8aa3b, v29
	v_exp_f32_e32 v29, v29
	v_lshlrev_b32_e32 v0, 16, v3
	v_or_b32_sdwa v0, v0, v2 dst_sel:DWORD dst_unused:UNUSED_PAD src0_sel:DWORD src1_sel:WORD_0
	v_lshlrev_b32_e32 v2, 16, v7
	v_lshlrev_b32_e32 v7, 16, v35
	v_or_b32_sdwa v7, v7, v31 dst_sel:DWORD dst_unused:UNUSED_PAD src0_sel:DWORD src1_sel:WORD_0
	v_add_f32_e32 v31, 1.0, v29
	v_rcp_f32_e32 v31, v31
	v_lshlrev_b32_e32 v3, 16, v9
	v_lshlrev_b32_e32 v37, 16, v37
	v_or_b32_sdwa v3, v3, v8 dst_sel:DWORD dst_unused:UNUSED_PAD src0_sel:DWORD src1_sel:WORD_0
	v_lshlrev_b32_e32 v8, 16, v46
	v_sub_f32_e32 v35, 1.0, v27
	v_max_f32_e32 v37, v37, v37
	v_or_b32_sdwa v8, v8, v44 dst_sel:DWORD dst_unused:UNUSED_PAD src0_sel:DWORD src1_sel:WORD_0
	v_fma_f32 v44, v31, v35, v27
	v_med3_f32 v37, v37, s11, v218
	v_max_f32_e32 v44, 0xda24260, v44
	v_mul_f32_e32 v37, 0xbfb8aa3b, v37
	v_log_f32_e32 v44, v44
	v_exp_f32_e32 v37, v37
	s_mov_b32 s7, 0x3f317218
	v_mul_f32_e32 v29, v29, v31
	v_fma_f32 v31, v44, s7, 0
	v_add_f32_e32 v44, 1.0, v37
	v_rcp_f32_e32 v44, v44
	v_lshlrev_b32_e32 v45, 16, v45
	v_max_f32_e32 v45, v45, v45
	v_med3_f32 v45, v45, s11, v218
	v_fma_f32 v46, v44, v35, v27
	v_max_f32_e32 v46, 0xda24260, v46
	v_mul_f32_e32 v45, 0xbfb8aa3b, v45
	v_log_f32_e32 v46, v46
	v_exp_f32_e32 v45, v45
	v_mul_f32_e32 v37, v37, v44
	v_lshlrev_b32_e32 v49, 16, v49
	v_fmamk_f32 v44, v46, 0x3f317218, v31
	v_add_f32_e32 v46, 1.0, v45
	v_rcp_f32_e32 v46, v46
	v_lshlrev_b32_e32 v9, 16, v53
	v_max_f32_e32 v49, v49, v49
	v_or_b32_sdwa v9, v9, v50 dst_sel:DWORD dst_unused:UNUSED_PAD src0_sel:DWORD src1_sel:WORD_0
	v_fma_f32 v50, v46, v35, v27
	v_med3_f32 v49, v49, s11, v218
	v_max_f32_e32 v50, 0xda24260, v50
	v_mul_f32_e32 v49, 0xbfb8aa3b, v49
	v_log_f32_e32 v50, v50
	v_exp_f32_e32 v49, v49
	v_mul_f32_e32 v45, v45, v46
	v_lshlrev_b32_e32 v51, 16, v51
	v_fmamk_f32 v46, v50, 0x3f317218, v44
	v_add_f32_e32 v50, 1.0, v49
	v_rcp_f32_e32 v50, v50
	v_max_f32_e32 v51, v51, v51
	v_med3_f32 v51, v51, s11, v218
	v_mul_f32_e32 v51, 0xbfb8aa3b, v51
	v_fma_f32 v53, v50, v35, v27
	v_max_f32_e32 v53, 0xda24260, v53
	v_log_f32_e32 v53, v53
	v_exp_f32_e32 v51, v51
	v_mul_f32_e32 v49, v49, v50
	v_lshlrev_b32_e32 v1, 16, v5
; __device__ __forceinline__ float bf1(bf16 b) { return __uint_as_float(((unsigned)b) << 16); }
; __device__ __forceinline__ void hg_gate(float fzraw, float lb, float& gl, float& kk) { const float fz = fminf(fmaxf(fzraw, -80.f), 80.f), ex = __expf(-fz), sg = __builtin_amdgcn_rcpf(1.f + ex);
;     gl = __builtin_amdgcn_logf(fmaxf(lb + (1.f - lb) * sg, 1e-30f)) * 0.6931471805599453f;     kk = (1.f - lb) * (ex * sg); }
; __device__ __forceinline__ void hgrn_pass1(const bf16* h, const float* lbraw, int layer, float* US, float* DD, char* lds, int wg, int G) {
;     ...
;         float bl[32], kk[32], run = 0.f;
; #pragma unroll
;         for (int i = 0; i < 32; ++i) { float gl; hg_gate(bf1(fzv[i]), lb, gl, kk[i]); run += gl; bl[i] = run; }
	v_fmamk_f32 v50, v53, 0x3f317218, v46
	v_add_f32_e32 v53, 1.0, v51
	v_rcp_f32_e32 v53, v53
	v_or_b32_sdwa v1, v1, v4 dst_sel:DWORD dst_unused:UNUSED_PAD src0_sel:DWORD src1_sel:WORD_0
	v_lshlrev_b32_e32 v4, 16, v11
	v_lshlrev_b32_e32 v55, 16, v55
	v_or_b32_sdwa v4, v4, v10 dst_sel:DWORD dst_unused:UNUSED_PAD src0_sel:DWORD src1_sel:WORD_0
	v_lshlrev_b32_e32 v10, 16, v59
	v_max_f32_e32 v55, v55, v55
	v_or_b32_sdwa v10, v10, v56 dst_sel:DWORD dst_unused:UNUSED_PAD src0_sel:DWORD src1_sel:WORD_0
	v_fma_f32 v56, v53, v35, v27
	v_med3_f32 v55, v55, s11, v218
	v_max_f32_e32 v56, 0xda24260, v56
	v_mul_f32_e32 v55, 0xbfb8aa3b, v55
	v_log_f32_e32 v56, v56
	v_exp_f32_e32 v55, v55
	v_mul_f32_e32 v51, v51, v53
	v_lshlrev_b32_e32 v57, 16, v57
	v_fmamk_f32 v53, v56, 0x3f317218, v50
	v_add_f32_e32 v56, 1.0, v55
	v_rcp_f32_e32 v56, v56
	v_max_f32_e32 v57, v57, v57
	v_med3_f32 v57, v57, s11, v218
	v_mul_f32_e32 v57, 0xbfb8aa3b, v57
	v_fma_f32 v59, v56, v35, v27
	v_max_f32_e32 v59, 0xda24260, v59
	v_log_f32_e32 v59, v59
	v_exp_f32_e32 v57, v57
	v_mul_f32_e32 v55, v55, v56
	v_lshlrev_b32_e32 v61, 16, v61
	v_fmamk_f32 v56, v59, 0x3f317218, v53
	v_add_f32_e32 v59, 1.0, v57
	v_rcp_f32_e32 v59, v59
	v_lshlrev_b32_e32 v11, 16, v65
	v_max_f32_e32 v61, v61, v61
	v_or_b32_sdwa v11, v11, v63 dst_sel:DWORD dst_unused:UNUSED_PAD src0_sel:DWORD src1_sel:WORD_0
	v_fma_f32 v63, v59, v35, v27
	v_med3_f32 v61, v61, s11, v218
	v_max_f32_e32 v63, 0xda24260, v63
	v_mul_f32_e32 v61, 0xbfb8aa3b, v61
	v_log_f32_e32 v63, v63
	v_exp_f32_e32 v61, v61
	v_mul_f32_e32 v57, v57, v59
	v_lshlrev_b32_e32 v64, 16, v64
	v_fmamk_f32 v59, v63, 0x3f317218, v56
	v_add_f32_e32 v63, 1.0, v61
	v_rcp_f32_e32 v63, v63
	v_max_f32_e32 v64, v64, v64
	v_med3_f32 v64, v64, s11, v218
	v_mul_f32_e32 v64, 0xbfb8aa3b, v64
	v_fma_f32 v65, v63, v35, v27
	v_max_f32_e32 v65, 0xda24260, v65
	v_log_f32_e32 v65, v65
	v_exp_f32_e32 v64, v64
	v_mul_f32_e32 v61, v61, v63
	v_lshlrev_b32_e32 v5, 16, v13
	v_fmamk_f32 v63, v65, 0x3f317218, v59
	v_add_f32_e32 v65, 1.0, v64
	v_rcp_f32_e32 v65, v65
	v_lshlrev_b32_e32 v67, 16, v67
	v_or_b32_sdwa v5, v5, v12 dst_sel:DWORD dst_unused:UNUSED_PAD src0_sel:DWORD src1_sel:WORD_0
	v_lshlrev_b32_e32 v12, 16, v72
	v_max_f32_e32 v67, v67, v67
	v_or_b32_sdwa v12, v12, v68 dst_sel:DWORD dst_unused:UNUSED_PAD src0_sel:DWORD src1_sel:WORD_0
	v_fma_f32 v68, v65, v35, v27
	v_med3_f32 v67, v67, s11, v218
	v_max_f32_e32 v68, 0xda24260, v68
	v_mul_f32_e32 v67, 0xbfb8aa3b, v67
	v_log_f32_e32 v68, v68
	v_exp_f32_e32 v67, v67
	v_mul_f32_e32 v64, v64, v65
	v_lshlrev_b32_e32 v70, 16, v70
	v_fmamk_f32 v65, v68, 0x3f317218, v63
	v_add_f32_e32 v68, 1.0, v67
	v_rcp_f32_e32 v68, v68
	v_max_f32_e32 v70, v70, v70
	v_med3_f32 v70, v70, s11, v218
	v_mul_f32_e32 v70, 0xbfb8aa3b, v70
	v_fma_f32 v72, v68, v35, v27
	v_max_f32_e32 v72, 0xda24260, v72
	v_log_f32_e32 v72, v72
	v_exp_f32_e32 v70, v70
	v_mul_f32_e32 v67, v67, v68
	v_lshlrev_b32_e32 v74, 16, v74
	v_fmamk_f32 v68, v72, 0x3f317218, v65
	v_add_f32_e32 v72, 1.0, v70
	v_rcp_f32_e32 v72, v72
	v_lshlrev_b32_e32 v13, 16, v78
	v_max_f32_e32 v74, v74, v74
	v_or_b32_sdwa v13, v13, v75 dst_sel:DWORD dst_unused:UNUSED_PAD src0_sel:DWORD src1_sel:WORD_0
	v_fma_f32 v75, v72, v35, v27
	v_med3_f32 v74, v74, s11, v218
	v_max_f32_e32 v75, 0xda24260, v75
	v_mul_f32_e32 v74, 0xbfb8aa3b, v74
	v_log_f32_e32 v75, v75
	v_exp_f32_e32 v74, v74
	v_mul_f32_e32 v70, v70, v72
	v_lshlrev_b32_e32 v77, 16, v77
	v_fmamk_f32 v72, v75, 0x3f317218, v68
	v_add_f32_e32 v75, 1.0, v74
	v_rcp_f32_e32 v75, v75
	v_max_f32_e32 v77, v77, v77
	v_med3_f32 v77, v77, s11, v218
	v_mul_f32_e32 v77, 0xbfb8aa3b, v77
	v_fma_f32 v78, v75, v35, v27
	v_max_f32_e32 v78, 0xda24260, v78
	v_log_f32_e32 v78, v78
	v_exp_f32_e32 v77, v77
	v_mul_f32_e32 v74, v74, v75
	v_or_b32_sdwa v2, v2, v6 dst_sel:DWORD dst_unused:UNUSED_PAD src0_sel:DWORD src1_sel:WORD_0
	v_fmamk_f32 v75, v78, 0x3f317218, v72
	v_add_f32_e32 v78, 1.0, v77
	v_rcp_f32_e32 v78, v78
	v_lshlrev_b32_e32 v6, 16, v15
	v_lshlrev_b32_e32 v80, 16, v80
	v_or_b32_sdwa v6, v6, v14 dst_sel:DWORD dst_unused:UNUSED_PAD src0_sel:DWORD src1_sel:WORD_0
	v_lshlrev_b32_e32 v14, 16, v83
	v_max_f32_e32 v80, v80, v80
	v_or_b32_sdwa v14, v14, v82 dst_sel:DWORD dst_unused:UNUSED_PAD src0_sel:DWORD src1_sel:WORD_0
	v_fma_f32 v82, v78, v35, v27
	v_med3_f32 v80, v80, s11, v218
	v_max_f32_e32 v82, 0xda24260, v82
	v_mul_f32_e32 v80, 0xbfb8aa3b, v80
	v_log_f32_e32 v82, v82
	v_exp_f32_e32 v80, v80
	v_mul_f32_e32 v77, v77, v78
	v_lshlrev_b32_e32 v81, 16, v81
	v_fmamk_f32 v78, v82, 0x3f317218, v75
	v_add_f32_e32 v82, 1.0, v80
	v_rcp_f32_e32 v82, v82
	v_max_f32_e32 v81, v81, v81
	v_med3_f32 v81, v81, s11, v218
	v_mul_f32_e32 v81, 0xbfb8aa3b, v81
	v_fma_f32 v83, v82, v35, v27
	v_max_f32_e32 v83, 0xda24260, v83
	v_log_f32_e32 v83, v83
	v_exp_f32_e32 v81, v81
	v_mul_f32_e32 v80, v80, v82
	v_lshlrev_b32_e32 v79, 16, v79
	v_fmamk_f32 v82, v83, 0x3f317218, v78
	v_add_f32_e32 v83, 1.0, v81
	v_rcp_f32_e32 v83, v83
	v_lshlrev_b32_e32 v15, 16, v85
	v_max_f32_e32 v79, v79, v79
	v_or_b32_sdwa v15, v15, v84 dst_sel:DWORD dst_unused:UNUSED_PAD src0_sel:DWORD src1_sel:WORD_0
	v_fma_f32 v84, v83, v35, v27
	v_med3_f32 v79, v79, s11, v218
	v_max_f32_e32 v84, 0xda24260, v84
	v_mul_f32_e32 v79, 0xbfb8aa3b, v79
	v_log_f32_e32 v84, v84
	v_exp_f32_e32 v79, v79
	v_mul_f32_e32 v81, v81, v83
	v_lshlrev_b32_e32 v76, 16, v76
	v_fmamk_f32 v83, v84, 0x3f317218, v82
	v_add_f32_e32 v84, 1.0, v79
	v_rcp_f32_e32 v84, v84
	v_max_f32_e32 v76, v76, v76
	v_med3_f32 v76, v76, s11, v218
	v_mul_f32_e32 v76, 0xbfb8aa3b, v76
	v_fma_f32 v85, v84, v35, v27
	v_max_f32_e32 v85, 0xda24260, v85
	v_log_f32_e32 v85, v85
; __device__ __forceinline__ float bf1(bf16 b) { return __uint_as_float(((unsigned)b) << 16); }
; __device__ __forceinline__ void hg_gate(float fzraw, float lb, float& gl, float& kk) { const float fz = fminf(fmaxf(fzraw, -80.f), 80.f), ex = __expf(-fz), sg = __builtin_amdgcn_rcpf(1.f + ex);
;     gl = __builtin_amdgcn_logf(fmaxf(lb + (1.f - lb) * sg, 1e-30f)) * 0.6931471805599453f;     kk = (1.f - lb) * (ex * sg); }
; __device__ __forceinline__ void hgrn_pass1(const bf16* h, const float* lbraw, int layer, float* US, float* DD, char* lds, int wg, int G) {
;     ...
;         float bl[32], kk[32], run = 0.f;
; #pragma unroll
;         for (int i = 0; i < 32; ++i) { float gl; hg_gate(bf1(fzv[i]), lb, gl, kk[i]); run += gl; bl[i] = run; }
;         TOT[seg2 * 128 + k] = run;
;         { v4u w[4];
; #pragma unroll
;           for (int i = 0; i < 32; i += 2) w[i >> 3][(i >> 1) & 3] = (unsigned)ivv[i] | ((unsigned)ivv[i + 1] << 16);
; #pragma unroll
;           for (int j = 0; j < 4; ++j) *(v4u*)(L + 20480 + k * 160 + seg2 * 64 + j * 16) = w[j]; }
;         __syncthreads();
	v_exp_f32_e32 v76, v76
	v_mul_f32_e32 v79, v79, v84
	v_lshlrev_b32_e32 v73, 16, v73
	v_fmamk_f32 v84, v85, 0x3f317218, v83
	v_add_f32_e32 v85, 1.0, v76
	v_rcp_f32_e32 v85, v85
	v_max_f32_e32 v73, v73, v73
	v_med3_f32 v73, v73, s11, v218
	v_mul_f32_e32 v73, 0xbfb8aa3b, v73
	v_fma_f32 v86, v85, v35, v27
	v_max_f32_e32 v86, 0xda24260, v86
	v_log_f32_e32 v86, v86
	v_exp_f32_e32 v73, v73
	v_mul_f32_e32 v76, v76, v85
	v_lshlrev_b32_e32 v71, 16, v71
	v_fmamk_f32 v85, v86, 0x3f317218, v84
	v_add_f32_e32 v86, 1.0, v73
	v_rcp_f32_e32 v86, v86
	v_max_f32_e32 v71, v71, v71
	v_med3_f32 v71, v71, s11, v218
	v_mul_f32_e32 v71, 0xbfb8aa3b, v71
	v_fma_f32 v87, v86, v35, v27
	v_max_f32_e32 v87, 0xda24260, v87
	v_log_f32_e32 v87, v87
	v_exp_f32_e32 v71, v71
	v_mul_f32_e32 v73, v73, v86
	v_lshlrev_b32_e32 v69, 16, v69
	v_fmamk_f32 v86, v87, 0x3f317218, v85
	v_add_f32_e32 v87, 1.0, v71
	v_rcp_f32_e32 v87, v87
	v_max_f32_e32 v69, v69, v69
	v_med3_f32 v69, v69, s11, v218
	v_mul_f32_e32 v69, 0xbfb8aa3b, v69
	v_fma_f32 v88, v87, v35, v27
	v_max_f32_e32 v88, 0xda24260, v88
	v_log_f32_e32 v88, v88
	v_exp_f32_e32 v69, v69
	v_mul_f32_e32 v71, v71, v87
	v_lshlrev_b32_e32 v66, 16, v66
	v_fmamk_f32 v87, v88, 0x3f317218, v86
	v_add_f32_e32 v88, 1.0, v69
	v_rcp_f32_e32 v88, v88
	v_max_f32_e32 v66, v66, v66
	v_med3_f32 v66, v66, s11, v218
	v_mul_f32_e32 v66, 0xbfb8aa3b, v66
	v_fma_f32 v89, v88, v35, v27
	v_max_f32_e32 v89, 0xda24260, v89
	v_log_f32_e32 v89, v89
	v_exp_f32_e32 v66, v66
	v_mul_f32_e32 v69, v69, v88
	v_lshlrev_b32_e32 v62, 16, v62
	v_fmamk_f32 v88, v89, 0x3f317218, v87
	v_add_f32_e32 v89, 1.0, v66
	v_rcp_f32_e32 v89, v89
	v_max_f32_e32 v62, v62, v62
	v_med3_f32 v62, v62, s11, v218
	v_mul_f32_e32 v62, 0xbfb8aa3b, v62
	v_fma_f32 v90, v89, v35, v27
	v_max_f32_e32 v90, 0xda24260, v90
	v_log_f32_e32 v90, v90
	v_exp_f32_e32 v62, v62
	v_mul_f32_e32 v66, v66, v89
	v_lshlrev_b32_e32 v60, 16, v60
	v_fmamk_f32 v89, v90, 0x3f317218, v88
	v_add_f32_e32 v90, 1.0, v62
	v_rcp_f32_e32 v90, v90
	v_max_f32_e32 v60, v60, v60
	v_med3_f32 v60, v60, s11, v218
	v_mul_f32_e32 v60, 0xbfb8aa3b, v60
	v_fma_f32 v91, v90, v35, v27
	v_max_f32_e32 v91, 0xda24260, v91
	v_log_f32_e32 v91, v91
	v_exp_f32_e32 v60, v60
	v_mul_f32_e32 v62, v62, v90
	v_lshlrev_b32_e32 v58, 16, v58
	v_fmamk_f32 v90, v91, 0x3f317218, v89
	v_add_f32_e32 v91, 1.0, v60
	v_rcp_f32_e32 v91, v91
	v_max_f32_e32 v58, v58, v58
	v_med3_f32 v58, v58, s11, v218
	v_mul_f32_e32 v58, 0xbfb8aa3b, v58
	v_fma_f32 v92, v91, v35, v27
	v_max_f32_e32 v92, 0xda24260, v92
	v_log_f32_e32 v92, v92
	v_exp_f32_e32 v58, v58
	v_mul_f32_e32 v60, v60, v91
	v_lshlrev_b32_e32 v54, 16, v54
	v_fmamk_f32 v91, v92, 0x3f317218, v90
	v_add_f32_e32 v92, 1.0, v58
	v_rcp_f32_e32 v92, v92
	v_max_f32_e32 v54, v54, v54
	v_med3_f32 v54, v54, s11, v218
	v_mul_f32_e32 v54, 0xbfb8aa3b, v54
	v_fma_f32 v93, v92, v35, v27
	v_max_f32_e32 v93, 0xda24260, v93
	v_log_f32_e32 v93, v93
	v_exp_f32_e32 v54, v54
	v_mul_f32_e32 v58, v58, v92
	v_lshlrev_b32_e32 v52, 16, v52
	v_fmamk_f32 v92, v93, 0x3f317218, v91
	v_add_f32_e32 v93, 1.0, v54
	v_rcp_f32_e32 v93, v93
	v_max_f32_e32 v52, v52, v52
	v_med3_f32 v52, v52, s11, v218
	v_mul_f32_e32 v52, 0xbfb8aa3b, v52
	v_fma_f32 v94, v93, v35, v27
	v_max_f32_e32 v94, 0xda24260, v94
	v_log_f32_e32 v94, v94
	v_exp_f32_e32 v52, v52
	v_mul_f32_e32 v54, v54, v93
	v_lshlrev_b32_e32 v48, 16, v48
	v_fmamk_f32 v93, v94, 0x3f317218, v92
	v_add_f32_e32 v94, 1.0, v52
	v_rcp_f32_e32 v94, v94
	v_max_f32_e32 v48, v48, v48
	v_med3_f32 v48, v48, s11, v218
	v_mul_f32_e32 v48, 0xbfb8aa3b, v48
	v_fma_f32 v95, v94, v35, v27
	v_max_f32_e32 v95, 0xda24260, v95
	v_log_f32_e32 v95, v95
	v_exp_f32_e32 v48, v48
	v_mul_f32_e32 v52, v52, v94
	v_lshlrev_b32_e32 v47, 16, v47
	v_fmamk_f32 v94, v95, 0x3f317218, v93
	v_add_f32_e32 v95, 1.0, v48
	v_rcp_f32_e32 v95, v95
	v_max_f32_e32 v47, v47, v47
	v_med3_f32 v47, v47, s11, v218
	v_mul_f32_e32 v47, 0xbfb8aa3b, v47
	v_fma_f32 v96, v95, v35, v27
	v_max_f32_e32 v96, 0xda24260, v96
	v_log_f32_e32 v96, v96
	v_exp_f32_e32 v47, v47
	v_mul_f32_e32 v48, v48, v95
	v_lshlrev_b32_e32 v39, 16, v39
	v_fmamk_f32 v95, v96, 0x3f317218, v94
	v_add_f32_e32 v96, 1.0, v47
	v_rcp_f32_e32 v96, v96
	v_max_f32_e32 v39, v39, v39
	v_med3_f32 v39, v39, s11, v218
	v_mul_f32_e32 v39, 0xbfb8aa3b, v39
	v_fma_f32 v97, v96, v35, v27
	v_max_f32_e32 v97, 0xda24260, v97
	v_log_f32_e32 v97, v97
	v_exp_f32_e32 v39, v39
	v_mul_f32_e32 v47, v47, v96
	v_lshlrev_b32_e32 v33, 16, v33
	v_fmamk_f32 v96, v97, 0x3f317218, v95
	v_add_f32_e32 v97, 1.0, v39
	v_rcp_f32_e32 v97, v97
	v_max_f32_e32 v33, v33, v33
	v_med3_f32 v33, v33, s11, v218
	v_mul_f32_e32 v33, 0xbfb8aa3b, v33
	v_fma_f32 v98, v97, v35, v27
	v_max_f32_e32 v98, 0xda24260, v98
	v_log_f32_e32 v98, v98
	v_exp_f32_e32 v33, v33
	v_mul_f32_e32 v39, v39, v97
	v_lshlrev_b32_e32 v25, 16, v25
	v_fmamk_f32 v97, v98, 0x3f317218, v96
	v_add_f32_e32 v98, 1.0, v33
	v_rcp_f32_e32 v98, v98
	v_max_f32_e32 v25, v25, v25
	v_med3_f32 v25, v25, s11, v218
	v_mul_f32_e32 v25, 0xbfb8aa3b, v25
	v_fma_f32 v99, v98, v35, v27
	v_max_f32_e32 v99, 0xda24260, v99
	v_log_f32_e32 v99, v99
	v_exp_f32_e32 v25, v25
	v_mul_f32_e32 v33, v33, v98
	v_lshlrev_b32_e32 v23, 16, v23
	v_fmamk_f32 v98, v99, 0x3f317218, v97
	v_add_f32_e32 v99, 1.0, v25
	v_rcp_f32_e32 v99, v99
	v_max_f32_e32 v23, v23, v23
	v_med3_f32 v23, v23, s11, v218
	v_mul_f32_e32 v23, 0xbfb8aa3b, v23
	v_fma_f32 v100, v99, v35, v27
	v_max_f32_e32 v100, 0xda24260, v100
	v_log_f32_e32 v100, v100
	v_exp_f32_e32 v23, v23
	v_mul_f32_e32 v25, v25, v99
	v_mul_f32_e32 v29, v29, v35
	v_fmamk_f32 v99, v100, 0x3f317218, v98
	v_add_f32_e32 v100, 1.0, v23
	v_rcp_f32_e32 v100, v100
	v_mul_f32_e32 v37, v37, v35
	v_mul_f32_e32 v45, v45, v35
	v_mul_f32_e32 v49, v49, v35
	v_fmac_f32_e32 v27, v100, v35
	v_max_f32_e32 v27, 0xda24260, v27
	v_log_f32_e32 v27, v27
	v_mul_f32_e32 v51, v51, v35
	v_mul_f32_e32 v55, v55, v35
	v_mul_f32_e32 v57, v57, v35
	v_fmamk_f32 v27, v27, 0x3f317218, v99
	ds_write_b32 v17, v27 offset:40960
	ds_write_b128 v19, v[0:3] offset:20480
	ds_write_b128 v19, v[4:7] offset:20496
	ds_write_b128 v19, v[8:11] offset:20512
	ds_write_b128 v19, v[12:15] offset:20528
	s_waitcnt lgkmcnt(0)
	s_barrier
; __device__ __forceinline__ unsigned pk2(float lo, float hi) { unsigned r; asm("v_cvt_pk_bf16_f32 %0, %1, %2" : "=v"(r) : "v"(lo), "v"(hi)); return r; }
; __device__ __forceinline__ void hgrn_pass1(const bf16* h, const float* lbraw, int layer, float* US, float* DD, char* lds, int wg, int G) {
;     ...
;         const float tot0 = TOT[k], tot1 = TOT[128 + k], b63 = tot0 + tot1, base = b63 - (seg2 ? tot0 : 0.f);
;         { v4u w[4];
; #pragma unroll
;           for (int i = 0; i < 32; i += 2) w[i >> 3][(i >> 1) & 3] = pk2(kk[i] * __expf(base - bl[i]), kk[i + 1] * __expf(base - bl[i + 1]));
; #pragma unroll
;           for (int j = 0; j < 4; ++j) *(v4u*)(L + k * 160 + seg2 * 64 + j * 16) = w[j]; }
;         if (seg2 == 0) DD[item * 128 + k] = __expf(b63);
	ds_read2st64_b32 v[0:1], v40 offset0:160 offset1:162
	v_mul_f32_e32 v61, v61, v35
	v_mul_f32_e32 v64, v64, v35
	v_mul_f32_e32 v67, v67, v35
	v_mul_f32_e32 v70, v70, v35
	s_waitcnt lgkmcnt(0)
	v_add_f32_e32 v8, v0, v1
	v_cndmask_b32_e64 v0, v0, 0, s[4:5]
	v_sub_f32_e32 v9, v8, v0
	v_sub_f32_e32 v0, v9, v31
	v_sub_f32_e32 v1, v9, v44
	v_mul_f32_e32 v0, 0x3fb8aa3b, v0
	v_mul_f32_e32 v1, 0x3fb8aa3b, v1
	v_exp_f32_e32 v0, v0
	v_exp_f32_e32 v1, v1
	v_sub_f32_e32 v2, v9, v50
	v_mul_f32_e32 v2, 0x3fb8aa3b, v2
	v_mul_f32_e32 v0, v29, v0
	v_mul_f32_e32 v1, v37, v1
	v_cvt_pk_bf16_f32 v0, v0, v1
	v_sub_f32_e32 v1, v9, v46
	v_mul_f32_e32 v1, 0x3fb8aa3b, v1
	v_exp_f32_e32 v1, v1
	v_exp_f32_e32 v2, v2
	v_sub_f32_e32 v3, v9, v56
	v_mul_f32_e32 v3, 0x3fb8aa3b, v3
	v_mul_f32_e32 v1, v45, v1
	v_mul_f32_e32 v2, v49, v2
	v_cvt_pk_bf16_f32 v1, v1, v2
	v_sub_f32_e32 v2, v9, v53
	v_mul_f32_e32 v2, 0x3fb8aa3b, v2
	v_exp_f32_e32 v2, v2
	v_exp_f32_e32 v3, v3
	v_sub_f32_e32 v4, v9, v63
	v_mul_f32_e32 v4, 0x3fb8aa3b, v4
	v_mul_f32_e32 v2, v51, v2
	v_mul_f32_e32 v3, v55, v3
	v_cvt_pk_bf16_f32 v2, v2, v3
	v_sub_f32_e32 v3, v9, v59
	v_mul_f32_e32 v3, 0x3fb8aa3b, v3
	v_exp_f32_e32 v3, v3
	v_exp_f32_e32 v4, v4
	v_sub_f32_e32 v5, v9, v68
	v_mul_f32_e32 v5, 0x3fb8aa3b, v5
	v_mul_f32_e32 v3, v57, v3
	v_mul_f32_e32 v4, v61, v4
	v_cvt_pk_bf16_f32 v3, v3, v4
	v_sub_f32_e32 v4, v9, v65
	v_mul_f32_e32 v4, 0x3fb8aa3b, v4
	v_exp_f32_e32 v4, v4
	v_exp_f32_e32 v5, v5
	v_sub_f32_e32 v6, v9, v75
	v_mul_f32_e32 v6, 0x3fb8aa3b, v6
	v_mul_f32_e32 v4, v64, v4
	v_mul_f32_e32 v5, v67, v5
	v_cvt_pk_bf16_f32 v4, v4, v5
	v_sub_f32_e32 v5, v9, v72
	v_mul_f32_e32 v5, 0x3fb8aa3b, v5
	v_exp_f32_e32 v5, v5
	v_exp_f32_e32 v6, v6
	v_mul_f32_e32 v74, v74, v35
	v_sub_f32_e32 v7, v9, v82
	v_mul_f32_e32 v5, v70, v5
	v_mul_f32_e32 v6, v74, v6
	v_cvt_pk_bf16_f32 v5, v5, v6
	v_sub_f32_e32 v6, v9, v78
	v_mul_f32_e32 v6, 0x3fb8aa3b, v6
	v_mul_f32_e32 v7, 0x3fb8aa3b, v7
	v_exp_f32_e32 v6, v6
	v_exp_f32_e32 v7, v7
	v_mul_f32_e32 v77, v77, v35
	v_mul_f32_e32 v80, v80, v35
	v_mul_f32_e32 v6, v77, v6
	v_mul_f32_e32 v7, v80, v7
	v_cvt_pk_bf16_f32 v6, v6, v7
	v_sub_f32_e32 v7, v9, v83
	v_sub_f32_e32 v10, v9, v84
	v_mul_f32_e32 v7, 0x3fb8aa3b, v7
	v_mul_f32_e32 v10, 0x3fb8aa3b, v10
	v_exp_f32_e32 v7, v7
	v_exp_f32_e32 v10, v10
	v_mul_f32_e32 v81, v81, v35
	v_mul_f32_e32 v79, v79, v35
	v_mul_f32_e32 v7, v81, v7
	v_mul_f32_e32 v10, v79, v10
	v_cvt_pk_bf16_f32 v7, v7, v10
	v_sub_f32_e32 v10, v9, v85
	v_sub_f32_e32 v11, v9, v86
	v_mul_f32_e32 v10, 0x3fb8aa3b, v10
	v_mul_f32_e32 v11, 0x3fb8aa3b, v11
	v_exp_f32_e32 v10, v10
	v_exp_f32_e32 v11, v11
	v_mul_f32_e32 v76, v76, v35
	v_mul_f32_e32 v73, v73, v35
	v_mul_f32_e32 v10, v76, v10
	v_mul_f32_e32 v11, v73, v11
	v_cvt_pk_bf16_f32 v10, v10, v11
	v_sub_f32_e32 v11, v9, v87
	v_sub_f32_e32 v12, v9, v88
	v_mul_f32_e32 v11, 0x3fb8aa3b, v11
	v_mul_f32_e32 v12, 0x3fb8aa3b, v12
	v_exp_f32_e32 v11, v11
	v_exp_f32_e32 v12, v12
	v_mul_f32_e32 v71, v71, v35
	v_mul_f32_e32 v69, v69, v35
	v_mul_f32_e32 v11, v71, v11
	v_mul_f32_e32 v12, v69, v12
	v_cvt_pk_bf16_f32 v11, v11, v12
	v_sub_f32_e32 v12, v9, v89
	v_sub_f32_e32 v13, v9, v90
	v_mul_f32_e32 v12, 0x3fb8aa3b, v12
	v_mul_f32_e32 v13, 0x3fb8aa3b, v13
	v_exp_f32_e32 v12, v12
	v_exp_f32_e32 v13, v13
	v_mul_f32_e32 v66, v66, v35
	v_mul_f32_e32 v62, v62, v35
	v_mul_f32_e32 v12, v66, v12
	v_mul_f32_e32 v13, v62, v13
	v_cvt_pk_bf16_f32 v12, v12, v13
	v_sub_f32_e32 v13, v9, v91
	v_sub_f32_e32 v14, v9, v92
	v_mul_f32_e32 v13, 0x3fb8aa3b, v13
	v_mul_f32_e32 v14, 0x3fb8aa3b, v14
	v_exp_f32_e32 v13, v13
	v_exp_f32_e32 v14, v14
	v_mul_f32_e32 v60, v60, v35
	v_mul_f32_e32 v58, v58, v35
	v_mul_f32_e32 v13, v60, v13
	v_mul_f32_e32 v14, v58, v14
	v_cvt_pk_bf16_f32 v13, v13, v14
	v_sub_f32_e32 v14, v9, v93
	v_mul_f32_e32 v14, 0x3fb8aa3b, v14
	v_sub_f32_e32 v15, v9, v94
	v_exp_f32_e32 v14, v14
	v_mul_f32_e32 v15, 0x3fb8aa3b, v15
	v_exp_f32_e32 v15, v15
	v_mul_f32_e32 v54, v54, v35
	v_mul_f32_e32 v52, v52, v35
	v_mul_f32_e32 v14, v54, v14
	v_mul_f32_e32 v15, v52, v15
	v_cvt_pk_bf16_f32 v44, v14, v15
	v_sub_f32_e32 v14, v9, v95
	v_mul_f32_e32 v14, 0x3fb8aa3b, v14
	v_sub_f32_e32 v15, v9, v96
	v_exp_f32_e32 v14, v14
	v_mul_f32_e32 v15, 0x3fb8aa3b, v15
	v_exp_f32_e32 v15, v15
	v_mul_f32_e32 v48, v48, v35
	v_mul_f32_e32 v47, v47, v35
	v_mul_f32_e32 v14, v48, v14
	v_mul_f32_e32 v15, v47, v15
	v_cvt_pk_bf16_f32 v45, v14, v15
	v_sub_f32_e32 v14, v9, v97
	v_mul_f32_e32 v14, 0x3fb8aa3b, v14
	v_sub_f32_e32 v15, v9, v98
	v_exp_f32_e32 v14, v14
	v_mul_f32_e32 v15, 0x3fb8aa3b, v15
	v_exp_f32_e32 v15, v15
	v_mul_f32_e32 v39, v39, v35
	v_mul_f32_e32 v33, v33, v35
	v_mul_f32_e32 v14, v39, v14
	v_mul_f32_e32 v15, v33, v15
	v_cvt_pk_bf16_f32 v46, v14, v15
	v_sub_f32_e32 v14, v9, v99
	v_sub_f32_e32 v9, v9, v27
	v_mul_f32_e32 v14, 0x3fb8aa3b, v14
	v_mul_f32_e32 v9, 0x3fb8aa3b, v9
	v_exp_f32_e32 v14, v14
	v_exp_f32_e32 v9, v9
	v_mul_f32_e32 v23, v23, v100
	v_mul_f32_e32 v25, v25, v35
	v_mul_f32_e32 v23, v23, v35
	v_mul_f32_e32 v14, v25, v14
	v_mul_f32_e32 v9, v23, v9
	v_cvt_pk_bf16_f32 v47, v14, v9
	ds_write_b128 v19, v[0:3]
	ds_write_b128 v19, v[4:7] offset:16
	ds_write_b128 v19, v[10:13] offset:32
	ds_write_b128 v19, v[44:47] offset:48
	s_and_saveexec_b64 s[8:9], s[4:5]
	s_cbranch_execz .LBB0_518
	v_mul_f32_e32 v0, 0x3fb8aa3b, v8
	v_exp_f32_e32 v2, v0
	v_ashrrev_i32_e32 v23, 31, v22
	v_lshl_add_u64 v[0:1], v[22:23], 2, s[2:3]
	global_store_dword v[0:1], v2, off
	s_branch .LBB0_518

; template <bool DO_S, bool DO_PV, bool DIAG>
; __device__ __forceinline__ void attn_step(const char* Ks, const char* Vs, const bf16x8_t (&qf)[2], bf16x8_t (&pf)[2], pg8::f32x4 (&oacc)[8], float& mrun, float& lsum, bool diag, int rs, int li, int g) {
;     ...
;     const char* kp = Ks + li * KROW + g * 16; const char* vp = Vs + li * KROW + g * 16;
;     pg8::f32x4 sacc[4];
;     if (DO_S) {
;         bf16x8_t kf[8];
; #pragma unroll
;         for (int i = 0; i < 8; ++i) kf[i] = *(const bf16x8_t*)(kp + (i >> 1) * 16 * KROW + (i & 1) * 64);
; #pragma unroll
;         for (int kb = 0; kb < 4; ++kb) { sacc[kb] = __builtin_amdgcn_mfma_f32_16x16x32_bf16(kf[2 * kb], qf[0], (pg8::f32x4){0.f, 0.f, 0.f, 0.f}, 0, 0, 0); sacc[kb] = __builtin_amdgcn_mfma_f32_16x16x32_bf16(kf[2 * kb + 1], qf[1], sacc[kb], 0, 0, 0); }
;     }
;     bf16x8_t vf[16];
;     if (DO_PV) {
; #pragma unroll
;         for (int i = 0; i < 16; ++i) vf[i] = *(const bf16x8_t*)(vp + (i >> 1) * 16 * KROW + (i & 1) * 64);
;     }
;     __builtin_amdgcn_sched_barrier(0);
;     const bf16x8_t p0 = pf[0], p1 = pf[1];
;     if (DO_PV) {
; #pragma unroll
;         for (int i = 0; i < 16; ++i) oacc[i >> 1] = __builtin_amdgcn_mfma_f32_16x16x32_bf16(vf[i], (i & 1) ? p1 : p0, oacc[i >> 1], 0, 0, 0);
;     }
;     float alpha = 1.f; bool grow = false;
;     if (DO_S) {
;         float mx = -INFINITY;
; #pragma unroll
;         for (int kb = 0; kb < 4; ++kb)
; #pragma unroll
;             for (int r = 0; r < 4; ++r) { float sv = sacc[kb][r]; if (DIAG && (16 * kb + 4 * g + r) > (16 * rs + li)) sv = -INFINITY; sacc[kb][r] = sv; mx = fmaxf(mx, sv); }
;         mx = xmax16_32(mx);
;         grow = mx > mrun + 8.0f / SC; const float mnew = grow ? mx : mrun; alpha = __builtin_amdgcn_exp2f((mrun - mnew) * SC); mrun = mnew;
;         const float nm = -mnew * SC; pg8::f32x4 psv = (pg8::f32x4){0.f, 0.f, 0.f, 0.f};
; #pragma unroll
;         for (int kb = 0; kb < 4; ++kb) { pg8::f32x4 tt = sacc[kb] * SC + nm;
;             tt[0] = __builtin_amdgcn_exp2f(tt[0]); tt[1] = __builtin_amdgcn_exp2f(tt[1]); tt[2] = __builtin_amdgcn_exp2f(tt[2]); tt[3] = __builtin_amdgcn_exp2f(tt[3]); sacc[kb] = tt; psv += tt; }
.LBB0_576:
	v_add_u32_e32 v96, s14, v225
	ds_read_b128 v[36:39], v96
	ds_read_b128 v[40:43], v96 offset:64
	ds_read_b128 v[44:47], v96 offset:2560
	ds_read_b128 v[48:51], v96 offset:2624
	ds_read_b128 v[52:55], v96 offset:5120
	ds_read_b128 v[60:63], v96 offset:7680
	ds_read_b128 v[56:59], v96 offset:5184
	ds_read_b128 v[96:99], v96 offset:7744
	s_waitcnt lgkmcnt(7)
	v_mfma_f32_16x16x32_bf16 v[36:39], v[36:39], v[80:83], 0
	s_waitcnt lgkmcnt(6)
	v_mfma_f32_16x16x32_bf16 v[38:41], v[40:43], v[84:87], v[36:39]
	s_waitcnt lgkmcnt(5)
	v_mfma_f32_16x16x32_bf16 v[42:45], v[44:47], v[80:83], 0
	s_nop 3
	v_add_u32_e32 v36, s1, v155
	ds_read_b128 v[100:103], v36 offset:23104
	ds_read_b128 v[104:107], v36 offset:25600
	s_waitcnt lgkmcnt(6)
	v_mfma_f32_16x16x32_bf16 v[42:45], v[48:51], v[84:87], v[42:45]
	ds_read_b128 v[108:111], v36 offset:25664
	ds_read_b128 v[112:115], v36 offset:28160
	ds_read_b128 v[116:119], v36 offset:28224
	s_waitcnt lgkmcnt(8)
	v_mfma_f32_16x16x32_bf16 v[46:49], v[52:55], v[80:83], 0
	ds_read_b128 v[120:123], v36 offset:30720
	ds_read_b128 v[124:127], v36 offset:30784
	ds_read_b128 v[128:131], v36 offset:33280
	s_waitcnt lgkmcnt(10)
	v_mfma_f32_16x16x32_bf16 v[50:53], v[60:63], v[80:83], 0
	ds_read_b128 v[132:135], v36 offset:33344
	ds_read_b128 v[136:139], v36 offset:35840
	ds_read_b128 v[200:203], v36 offset:35904
	s_waitcnt lgkmcnt(12)
	v_mfma_f32_16x16x32_bf16 v[46:49], v[56:59], v[84:87], v[46:49]
	ds_read_b128 v[54:57], v36 offset:20480
	ds_read_b128 v[58:61], v36 offset:20544
	ds_read_b128 v[204:207], v36 offset:38400
	s_waitcnt lgkmcnt(14)
	v_mfma_f32_16x16x32_bf16 v[50:53], v[96:99], v[84:87], v[50:53]
	ds_read_b128 v[96:99], v36 offset:23040
	ds_read_b128 v[208:211], v36 offset:38464
	s_waitcnt lgkmcnt(4)
	v_mfma_f32_16x16x32_bf16 v[0:3], v[54:57], v[88:91], v[0:3]
	v_max3_f32 v36, v38, s33, v39
	v_max3_f32 v36, v36, v40, v41
	v_max3_f32 v36, v36, v42, v43
	v_max3_f32 v36, v36, v44, v45
	v_max3_f32 v36, v36, v46, v47
	v_max3_f32 v36, v36, v48, v49
	v_max3_f32 v36, v36, v50, v51
	s_waitcnt lgkmcnt(3)
	v_mfma_f32_16x16x32_bf16 v[0:3], v[58:61], v[92:95], v[0:3]
	v_max3_f32 v36, v36, v52, v53
	v_mov_b32_e32 v37, v36
	s_nop 1
	v_permlane16_swap_b32_e32 v36, v37
	v_max_f32_e32 v37, v37, v37
	v_max_f32_e32 v36, v36, v36
	v_max_f32_e32 v36, v36, v37
	v_mov_b32_e32 v37, v36
	s_waitcnt lgkmcnt(1)
	v_mfma_f32_16x16x32_bf16 v[4:7], v[96:99], v[88:91], v[4:7]
	v_permlane32_swap_b32_e32 v36, v37
	v_max_f32_e32 v37, v37, v37
	v_max_f32_e32 v36, v36, v36
	v_max_f32_e32 v36, v36, v37
	v_add_f32_e32 v37, 0x42317218, v165
	v_cmp_gt_f32_e32 vcc, v36, v37
	s_nop 1
	v_cndmask_b32_e32 v37, v165, v36, vcc
	v_mfma_f32_16x16x32_bf16 v[4:7], v[100:103], v[92:95], v[4:7]
	v_sub_f32_e32 v36, v165, v37
	v_mul_f32_e32 v60, 0x3e38aa3b, v36
	v_mul_f32_e32 v36, 0xbe38aa3b, v37
	v_fma_f32 v40, v40, s10, v36
	v_fma_f32 v41, v41, s10, v36
	v_fma_f32 v38, v38, s10, v36
	v_fma_f32 v39, v39, s10, v36
	v_fma_f32 v44, v44, s10, v36
	v_fma_f32 v45, v45, s10, v36
	v_fma_f32 v42, v42, s10, v36
	v_fma_f32 v43, v43, s10, v36
	v_mfma_f32_16x16x32_bf16 v[8:11], v[104:107], v[88:91], v[8:11]
	v_fma_f32 v54, v48, s10, v36
	v_fma_f32 v55, v49, s10, v36
	v_fma_f32 v56, v46, s10, v36
	v_fma_f32 v57, v47, s10, v36
	v_fma_f32 v58, v52, s10, v36
	v_fma_f32 v59, v53, s10, v36
	v_fma_f32 v50, v50, s10, v36
	v_fma_f32 v51, v51, s10, v36
	v_mfma_f32_16x16x32_bf16 v[8:11], v[108:111], v[92:95], v[8:11]
	v_exp_f32_e32 v48, v38
	v_exp_f32_e32 v49, v39
	v_exp_f32_e32 v46, v40
	v_mfma_f32_16x16x32_bf16 v[12:15], v[112:115], v[88:91], v[12:15]
	v_exp_f32_e32 v47, v41
	v_exp_f32_e32 v40, v42
	v_exp_f32_e32 v41, v43
	v_mfma_f32_16x16x32_bf16 v[12:15], v[116:119], v[92:95], v[12:15]
	v_exp_f32_e32 v52, v44
	v_exp_f32_e32 v53, v45
	v_exp_f32_e32 v44, v56
	v_mfma_f32_16x16x32_bf16 v[16:19], v[120:123], v[88:91], v[16:19]
	v_exp_f32_e32 v45, v57
	v_exp_f32_e32 v42, v54
	v_exp_f32_e32 v43, v55
	v_mfma_f32_16x16x32_bf16 v[16:19], v[124:127], v[92:95], v[16:19]
	v_exp_f32_e32 v38, v50
	v_exp_f32_e32 v39, v51
	v_exp_f32_e32 v50, v58
	v_mfma_f32_16x16x32_bf16 v[20:23], v[128:131], v[88:91], v[20:23]
	v_exp_f32_e32 v51, v59
	v_exp_f32_e32 v36, v60
	v_mfma_f32_16x16x32_bf16 v[20:23], v[132:135], v[92:95], v[20:23]
	v_mfma_f32_16x16x32_bf16 v[24:27], v[136:139], v[88:91], v[24:27]
	v_mfma_f32_16x16x32_bf16 v[24:27], v[200:203], v[92:95], v[24:27]
	v_mfma_f32_16x16x32_bf16 v[28:31], v[204:207], v[88:91], v[28:31]
	v_cvt_pk_bf16_f32 v88, v48, v49
	v_cvt_pk_bf16_f32 v89, v46, v47
	v_cvt_pk_bf16_f32 v90, v40, v41
	s_waitcnt lgkmcnt(0)
	v_mfma_f32_16x16x32_bf16 v[28:31], v[208:211], v[92:95], v[28:31]
	v_cvt_pk_bf16_f32 v91, v52, v53
	v_cvt_pk_bf16_f32 v92, v44, v45
	v_cvt_pk_bf16_f32 v93, v42, v43
	v_cvt_pk_bf16_f32 v94, v38, v39
	v_cvt_pk_bf16_f32 v95, v50, v51
	s_cbranch_vccz .LBB0_578
	s_nop 6
	v_pk_mul_f32 v[30:31], v[30:31], v[36:37] op_sel_hi:[1,0]
	v_pk_mul_f32 v[26:27], v[26:27], v[36:37] op_sel_hi:[1,0]
	v_pk_mul_f32 v[22:23], v[22:23], v[36:37] op_sel_hi:[1,0]
	v_pk_mul_f32 v[18:19], v[18:19], v[36:37] op_sel_hi:[1,0]
	v_pk_mul_f32 v[14:15], v[14:15], v[36:37] op_sel_hi:[1,0]
	v_pk_mul_f32 v[10:11], v[10:11], v[36:37] op_sel_hi:[1,0]
	v_pk_mul_f32 v[6:7], v[6:7], v[36:37] op_sel_hi:[1,0]
	v_pk_mul_f32 v[2:3], v[2:3], v[36:37] op_sel_hi:[1,0]
	v_pk_mul_f32 v[28:29], v[28:29], v[36:37] op_sel_hi:[1,0]
	v_pk_mul_f32 v[24:25], v[24:25], v[36:37] op_sel_hi:[1,0]
	v_pk_mul_f32 v[20:21], v[20:21], v[36:37] op_sel_hi:[1,0]
	v_pk_mul_f32 v[16:17], v[16:17], v[36:37] op_sel_hi:[1,0]
	v_pk_mul_f32 v[12:13], v[12:13], v[36:37] op_sel_hi:[1,0]
	v_pk_mul_f32 v[8:9], v[8:9], v[36:37] op_sel_hi:[1,0]
	v_pk_mul_f32 v[4:5], v[4:5], v[36:37] op_sel_hi:[1,0]
	v_pk_mul_f32 v[0:1], v[0:1], v[36:37] op_sel_hi:[1,0]

; #define ATT_LOAD(S, t) do { S[0] = *(const GAS v4u*)(gsrc[0] + (size_t)(t) * 64 * NH); S[1] = *(const GAS v4u*)(gsrc[1] + (size_t)(t) * 64 * NH); S[2] = *(const GAS v4u*)(gsrc[2] + (t) * 64); S[3] = *(const GAS v4u*)(gsrc[3] + (t) * 64); } while (0)
; #define ATT_STORE(S, boff) do { _Pragma("unroll") for (int i_ = 0; i_ < 2; ++i_) *(v4u*)(lds + (boff) + ldst[i_]) = S[i_]; \
;     _Pragma("unroll") for (int i_ = 2; i_ < 4; ++i_) { v2u lo_, hi_; lo_.x = S[i_].x; lo_.y = S[i_].y; hi_.x = S[i_].z; hi_.y = S[i_].w; *(v2u*)(lds + (boff) + ldst[i_]) = lo_; *(v2u*)(lds + (boff) + ldst[i_] + 16) = hi_; } } while (0)
; template <bool DO_S, bool DO_PV, bool DIAG>
; __device__ __forceinline__ void attn_step(const char* Ks, const char* Vs, const bf16x8_t (&qf)[2], bf16x8_t (&pf)[2], pg8::f32x4 (&oacc)[8], float& mrun, float& lsum, bool diag, int rs, int li, int g) {
;     ...
;         const float nm = -mnew * SC; pg8::f32x4 psv = (pg8::f32x4){0.f, 0.f, 0.f, 0.f};
; #pragma unroll
;         for (int kb = 0; kb < 4; ++kb) { pg8::f32x4 tt = sacc[kb] * SC + nm;
;             tt[0] = __builtin_amdgcn_exp2f(tt[0]); tt[1] = __builtin_amdgcn_exp2f(tt[1]); tt[2] = __builtin_amdgcn_exp2f(tt[2]); tt[3] = __builtin_amdgcn_exp2f(tt[3]); sacc[kb] = tt; psv += tt; }
;         const float ps = (psv[0] + psv[1]) + (psv[2] + psv[3]);
;         lsum = lsum * alpha + ps;
; __device__ __forceinline__ void mix_attn(const bf16* h, const bf16* VT, const float* dl, int layer, const float* ng, bf16* ycat, char* lds, int wg, int G) {
;     ...
;             for (int t = 0; t < qb; ++t) {
;                 if (t + 2 <= qb) ATT_LOAD(stA, t + 2);
;                 if (t + 1 == qb) attn_step<true, true, true>(lds + b1 + st * K2OFF, lds + b0 + VOFF, qf, pf, oacc, mrun, lsum, true, rs, li, g);
;                 else attn_step<true, true, false>(lds + b1 + st * K2OFF, lds + b0 + VOFF, qf, pf, oacc, mrun, lsum, false, rs, li, g);
;                 if (t + 2 <= qb) ATT_STORE(stA, b2);
;                 __syncthreads();
;                 const int tmp = b0; b0 = b1; b1 = b2; b2 = tmp;
;             }
.LBB0_580:
	v_add_f32_e32 v48, 0, v48
	v_add_f32_e32 v49, 0, v49
	v_add_f32_e32 v46, 0, v46
	v_add_f32_e32 v47, 0, v47
	v_add_f32_e32 v40, v40, v48
	v_add_f32_e32 v41, v41, v49
	v_add_f32_e32 v46, v52, v46
	v_add_f32_e32 v47, v53, v47
	v_add_f32_e32 v40, v44, v40
	v_add_f32_e32 v41, v45, v41
	v_add_f32_e32 v42, v42, v46
	v_add_f32_e32 v43, v43, v47
	v_add_f32_e32 v38, v38, v40
	v_add_f32_e32 v39, v39, v41
	v_add_f32_e32 v42, v50, v42
	v_add_f32_e32 v43, v51, v43
	v_add_f32_e32 v38, v38, v39
	v_add_f32_e32 v39, v42, v43
	s_add_i32 s80, s80, 1
	v_add_f32_e32 v96, v38, v39
	s_add_i32 s28, s28, 64
	v_fmac_f32_e32 v96, v157, v36
	v_lshl_add_u64 v[34:35], v[34:35], 0, s[34:35]
	s_cmp_eq_u32 s15, s80
	v_lshl_add_u64 v[32:33], v[32:33], 0, s[34:35]
	s_waitcnt lgkmcnt(0)
	s_barrier
	s_cbranch_scc1 .LBB0_584
	v_mov_b32_e32 v157, v96
	s_mov_b32 s81, s14
	s_mov_b32 s14, s78
	s_mov_b32 s78, s1
	v_mov_b32_e32 v165, v37
	s_branch .LBB0_574

; __device__ __forceinline__ unsigned f2bf(float f) { return pk2(f, 0.f) & 0xffffu; }
; __device__ __forceinline__ void hgrn_scan(const float* US, const float* DD, bf16* SB, int gtid, int gstride) {
;     for (int e = gtid; e < 8 * 16384; e += gstride) { const int chain = e >> 14, idx = e & 16383, k = idx & 127; float run = 0.f;
;         for (int c0 = 0; c0 < 64; c0 += 16) { float u[16], d[16];
; #pragma unroll
;             for (int j = 0; j < 16; ++j) { u[j] = US[(size_t)(chain * 64 + c0 + j) * 16384 + idx]; d[j] = DD[(chain * 64 + c0 + j) * 128 + k]; }
; #pragma unroll
;             for (int j = 0; j < 16; ++j) { SB[(size_t)(chain * 64 + c0 + j) * 16384 + idx] = (bf16)f2bf(run); run = d[j] * run + u[j]; } } }
.LBB0_644:
	v_lshl_add_u64 v[6:7], s[0:1], 0, v[4:5]
	v_add_co_u32_e32 v12, vcc, 0x1a800000, v6
	v_add_u32_e32 v14, 0xfffff880, v0
	s_nop 0
	v_addc_co_u32_e32 v13, vcc, 0, v7, vcc
	v_add_co_u32_e32 v16, vcc, 0x1a810000, v6
	v_ashrrev_i32_e32 v15, 31, v14
	s_nop 0
	v_addc_co_u32_e32 v17, vcc, 0, v7, vcc
	v_add_co_u32_e32 v18, vcc, 0x1a820000, v6
	v_lshl_add_u64 v[14:15], v[14:15], 2, s[4:5]
	s_nop 0
	v_addc_co_u32_e32 v19, vcc, 0, v7, vcc
	v_add_co_u32_e32 v20, vcc, 0x1a830000, v6
	global_load_dword v12, v[12:13], off
	s_nop 0
	v_addc_co_u32_e32 v21, vcc, 0, v7, vcc
	global_load_dword v14, v[14:15], off
	v_add_co_u32_e32 v22, vcc, 0x1a840000, v6
	global_load_dword v13, v[16:17], off
	v_add_u32_e32 v16, 0xfffff900, v0
	global_load_dword v15, v[18:19], off
	v_add_u32_e32 v18, 0xfffff980, v0
	v_ashrrev_i32_e32 v17, 31, v16
	v_ashrrev_i32_e32 v19, 31, v18
	v_lshl_add_u64 v[16:17], v[16:17], 2, s[4:5]
	v_lshl_add_u64 v[18:19], v[18:19], 2, s[4:5]
	v_addc_co_u32_e32 v23, vcc, 0, v7, vcc
	global_load_dword v16, v[16:17], off
	v_ashrrev_i32_e32 v1, 31, v0
	global_load_dword v18, v[18:19], off
	s_add_i32 s14, s14, 16
	global_load_dword v17, v[20:21], off
	v_add_u32_e32 v20, 0xfffffa00, v0
	global_load_dword v19, v[22:23], off
	v_add_u32_e32 v22, 0xfffffa80, v0
	v_ashrrev_i32_e32 v21, 31, v20
	v_ashrrev_i32_e32 v23, 31, v22
	v_lshl_add_u64 v[20:21], v[20:21], 2, s[4:5]
	v_lshl_add_u64 v[22:23], v[22:23], 2, s[4:5]
	global_load_dword v20, v[20:21], off
	s_mov_b64 s[24:25], 0x100000
	global_load_dword v21, v[22:23], off
	v_add_co_u32_e32 v22, vcc, 0x1a850000, v6
	v_lshl_add_u64 v[4:5], v[4:5], 0, s[24:25]
	s_nop 0
	v_addc_co_u32_e32 v23, vcc, 0, v7, vcc
	global_load_dword v26, v[22:23], off
	v_add_u32_e32 v22, 0xfffffb00, v0
	v_ashrrev_i32_e32 v23, 31, v22
	v_lshl_add_u64 v[22:23], v[22:23], 2, s[4:5]
	global_load_dword v27, v[22:23], off
	v_add_co_u32_e32 v22, vcc, 0x1a860000, v6
	s_cmp_lt_u32 s14, 48
	s_nop 0
	v_addc_co_u32_e32 v23, vcc, 0, v7, vcc
	global_load_dword v28, v[22:23], off
	v_add_u32_e32 v22, 0xfffffb80, v0
	v_ashrrev_i32_e32 v23, 31, v22
	v_lshl_add_u64 v[22:23], v[22:23], 2, s[4:5]
	global_load_dword v29, v[22:23], off
	v_add_co_u32_e32 v22, vcc, 0x1a870000, v6
	s_waitcnt vmcnt(0) lgkmcnt(0)
	v_fmac_f32_e32 v12, v11, v14
	v_addc_co_u32_e32 v23, vcc, 0, v7, vcc
	global_load_dword v30, v[22:23], off
	v_add_u32_e32 v22, 0xfffffc00, v0
	v_ashrrev_i32_e32 v23, 31, v22
	v_lshl_add_u64 v[22:23], v[22:23], 2, s[4:5]
	global_load_dword v31, v[22:23], off
	v_add_co_u32_e32 v22, vcc, 0x1a880000, v6
	v_fmac_f32_e32 v13, v12, v16
	s_nop 0
	v_addc_co_u32_e32 v23, vcc, 0, v7, vcc
	global_load_dword v32, v[22:23], off
	v_add_u32_e32 v22, 0xfffffc80, v0
	v_ashrrev_i32_e32 v23, 31, v22
	v_lshl_add_u64 v[22:23], v[22:23], 2, s[4:5]
	global_load_dword v33, v[22:23], off
	v_add_co_u32_e32 v22, vcc, 0x1a890000, v6
	v_fmac_f32_e32 v15, v13, v18
	s_nop 0
	v_addc_co_u32_e32 v23, vcc, 0, v7, vcc
	global_load_dword v34, v[22:23], off
	v_add_u32_e32 v22, 0xfffffd00, v0
	v_ashrrev_i32_e32 v23, 31, v22
	v_lshl_add_u64 v[22:23], v[22:23], 2, s[4:5]
	global_load_dword v35, v[22:23], off
	v_add_co_u32_e32 v22, vcc, 0x1a8a0000, v6
	v_fmac_f32_e32 v17, v15, v20
	s_nop 0
	v_addc_co_u32_e32 v23, vcc, 0, v7, vcc
	global_load_dword v36, v[22:23], off
	v_add_u32_e32 v22, 0xfffffd80, v0
	v_ashrrev_i32_e32 v23, 31, v22
	v_lshl_add_u64 v[22:23], v[22:23], 2, s[4:5]
	global_load_dword v37, v[22:23], off
	v_add_co_u32_e32 v22, vcc, 0x1a8b0000, v6
	v_fmac_f32_e32 v19, v17, v21
	s_nop 0
	v_addc_co_u32_e32 v23, vcc, 0, v7, vcc
	global_load_dword v38, v[22:23], off
	v_add_u32_e32 v22, 0xfffffe00, v0
	v_ashrrev_i32_e32 v23, 31, v22
	v_lshl_add_u64 v[22:23], v[22:23], 2, s[4:5]
	global_load_dword v39, v[22:23], off
	v_add_co_u32_e32 v22, vcc, 0x1a8c0000, v6
	v_fmac_f32_e32 v26, v19, v27
	s_nop 0
	v_addc_co_u32_e32 v23, vcc, 0, v7, vcc
	global_load_dword v40, v[22:23], off
	v_add_u32_e32 v22, 0xfffffe80, v0
	v_ashrrev_i32_e32 v23, 31, v22
	v_lshl_add_u64 v[22:23], v[22:23], 2, s[4:5]
	global_load_dword v41, v[22:23], off
	v_add_co_u32_e32 v22, vcc, 0x1a8d0000, v6
	v_fmac_f32_e32 v28, v26, v29
	s_nop 0
	v_addc_co_u32_e32 v23, vcc, 0, v7, vcc
	global_load_dword v42, v[22:23], off
	v_add_u32_e32 v22, 0xffffff00, v0
	v_ashrrev_i32_e32 v23, 31, v22
	v_lshl_add_u64 v[22:23], v[22:23], 2, s[4:5]
	global_load_dword v43, v[22:23], off
	v_add_co_u32_e32 v22, vcc, 0x1a8e0000, v6
	s_waitcnt vmcnt(0) lgkmcnt(0)
; __device__ __forceinline__ unsigned f2bf(float f) { return pk2(f, 0.f) & 0xffffu; }
; __device__ __forceinline__ void hgrn_scan(const float* US, const float* DD, bf16* SB, int gtid, int gstride) {
;     for (int e = gtid; e < 8 * 16384; e += gstride) { const int chain = e >> 14, idx = e & 16383, k = idx & 127; float run = 0.f;
;         for (int c0 = 0; c0 < 64; c0 += 16) { float u[16], d[16];
; #pragma unroll
;             for (int j = 0; j < 16; ++j) { u[j] = US[(size_t)(chain * 64 + c0 + j) * 16384 + idx]; d[j] = DD[(chain * 64 + c0 + j) * 128 + k]; }
; #pragma unroll
;             for (int j = 0; j < 16; ++j) { SB[(size_t)(chain * 64 + c0 + j) * 16384 + idx] = (bf16)f2bf(run); run = d[j] * run + u[j]; } } }
	v_fmac_f32_e32 v30, v28, v31
	v_addc_co_u32_e32 v23, vcc, 0, v7, vcc
	global_load_dword v44, v[22:23], off
	v_add_u32_e32 v22, 0xffffff80, v0
	v_ashrrev_i32_e32 v23, 31, v22
	v_lshl_add_u64 v[22:23], v[22:23], 2, s[4:5]
	v_add_co_u32_e32 v6, vcc, 0x1a8f0000, v6
	global_load_dword v45, v[22:23], off
	s_nop 0
	v_addc_co_u32_e32 v7, vcc, 0, v7, vcc
	v_lshl_add_u64 v[22:23], v[0:1], 2, s[4:5]
	global_load_dword v6, v[6:7], off
	v_cvt_pk_bf16_f32 v7, v11, v169
	global_load_dword v1, v[22:23], off
	v_lshl_add_u64 v[22:23], s[0:1], 0, v[2:3]
	v_add_co_u32_e32 v24, vcc, 0x1c800000, v22
	v_fmac_f32_e32 v32, v30, v33
	s_nop 0
	v_addc_co_u32_e32 v25, vcc, 0, v23, vcc
	global_store_short v[24:25], v7, off
	v_add_co_u32_e32 v24, vcc, 0x1c808000, v22
	v_cvt_pk_bf16_f32 v7, v12, v169
	v_fmac_f32_e32 v34, v32, v35
	s_nop 0
	v_addc_co_u32_e32 v25, vcc, 0, v23, vcc
	global_store_short v[24:25], v7, off
	v_add_co_u32_e32 v24, vcc, 0x1c810000, v22
	v_cvt_pk_bf16_f32 v7, v13, v169
	v_fmac_f32_e32 v36, v34, v37
	s_nop 0
	v_addc_co_u32_e32 v25, vcc, 0, v23, vcc
	v_add_co_u32_e32 v12, vcc, 0x1c818000, v22
	global_store_short v[24:25], v7, off
	s_nop 0
	v_addc_co_u32_e32 v13, vcc, 0, v23, vcc
	v_cvt_pk_bf16_f32 v7, v15, v169
	global_store_short v[12:13], v7, off
	v_add_co_u32_e32 v12, vcc, 0x1c820000, v22
	v_cvt_pk_bf16_f32 v7, v17, v169
	v_fmac_f32_e32 v38, v36, v39
	s_nop 0
	v_addc_co_u32_e32 v13, vcc, 0, v23, vcc
	global_store_short v[12:13], v7, off
	v_add_co_u32_e32 v12, vcc, 0x1c828000, v22
	v_cvt_pk_bf16_f32 v7, v19, v169
	v_fmac_f32_e32 v40, v38, v41
	s_nop 0
	v_addc_co_u32_e32 v13, vcc, 0, v23, vcc
	global_store_short v[12:13], v7, off
	v_add_co_u32_e32 v12, vcc, 0x1c830000, v22
	v_cvt_pk_bf16_f32 v7, v26, v169
	v_add_u32_e32 v0, 0x800, v0
	s_nop 0
	v_addc_co_u32_e32 v13, vcc, 0, v23, vcc
	global_store_short v[12:13], v7, off
	v_add_co_u32_e32 v12, vcc, 0x1c838000, v22
	v_cvt_pk_bf16_f32 v7, v28, v169
	v_fmac_f32_e32 v42, v40, v43
	s_nop 0
	v_addc_co_u32_e32 v13, vcc, 0, v23, vcc
	global_store_short v[12:13], v7, off
	v_add_co_u32_e32 v12, vcc, 0x1c840000, v22
	v_cvt_pk_bf16_f32 v7, v30, v169
	v_lshl_add_u64 v[2:3], v[2:3], 0, s[74:75]
	s_nop 0
	v_addc_co_u32_e32 v13, vcc, 0, v23, vcc
	global_store_short v[12:13], v7, off
	v_add_co_u32_e32 v12, vcc, 0x1c848000, v22
	v_cvt_pk_bf16_f32 v7, v32, v169
	s_waitcnt vmcnt(0) lgkmcnt(0)
	v_fmac_f32_e32 v44, v42, v45
	v_addc_co_u32_e32 v13, vcc, 0, v23, vcc
	global_store_short v[12:13], v7, off
	v_add_co_u32_e32 v12, vcc, 0x1c850000, v22
	v_cvt_pk_bf16_f32 v7, v34, v169
	v_fmac_f32_e32 v6, v44, v1
	s_nop 0
	v_addc_co_u32_e32 v13, vcc, 0, v23, vcc
	global_store_short v[12:13], v7, off
	v_add_co_u32_e32 v12, vcc, 0x1c858000, v22
	v_cvt_pk_bf16_f32 v7, v36, v169
	v_mov_b32_e32 v11, v6
	s_nop 0
	v_addc_co_u32_e32 v13, vcc, 0, v23, vcc
	global_store_short v[12:13], v7, off
	v_add_co_u32_e32 v12, vcc, 0x1c860000, v22
	v_cvt_pk_bf16_f32 v7, v38, v169
	s_nop 1
	v_addc_co_u32_e32 v13, vcc, 0, v23, vcc
	global_store_short v[12:13], v7, off
	v_add_co_u32_e32 v12, vcc, 0x1c868000, v22
	v_cvt_pk_bf16_f32 v7, v40, v169
	s_nop 1
	v_addc_co_u32_e32 v13, vcc, 0, v23, vcc
	global_store_short v[12:13], v7, off
	v_add_co_u32_e32 v12, vcc, 0x1c870000, v22
	v_cvt_pk_bf16_f32 v7, v42, v169
	s_nop 1
	v_addc_co_u32_e32 v13, vcc, 0, v23, vcc
	global_store_short v[12:13], v7, off
	v_add_co_u32_e32 v12, vcc, 0x1c878000, v22
	v_cvt_pk_bf16_f32 v7, v44, v169
	s_nop 1
	v_addc_co_u32_e32 v13, vcc, 0, v23, vcc
	global_store_short v[12:13], v7, off
	s_cbranch_scc1 .LBB0_644
	v_readlane_b32 s15, v254, 39
	s_mov_b32 s14, 0x1ffff
	s_nop 0
	v_add_u32_e32 v8, s15, v8
	v_cmp_lt_i32_e32 vcc, s14, v8
	s_or_b64 s[8:9], vcc, s[8:9]
	v_add_u16_e32 v10, s15, v10
	s_andn2_b64 exec, exec, s[8:9]
	s_cbranch_execnz .LBB0_643

; __device__ __forceinline__ unsigned pk2(float lo, float hi) { unsigned r; asm("v_cvt_pk_bf16_f32 %0, %1, %2" : "=v"(r) : "v"(lo), "v"(hi)); return r; }
; __device__ __forceinline__ void mix_sgu(const bf16* h, const float* lng, const float* lnb, const float* sgw, const float* sgb, bf16* ycat, char* lds, int wg, int nwg) {
;     ...
;         { const int t = 16 * wid + li; const float bias = sgb[grp * 128 + t];
;           const bf16* hr = h + (m0 + t) * NH + 128 * grp + 4 * g; bf16* yr = ycat + (m0 + t) * DM + Y_D + 128 * grp + 4 * g;
; #pragma unroll
;           for (int nb = 0; nb < 8; ++nb) { const v2u uu = *(const v2u*)(hr + C_DU + 16 * nb), gd = *(const v2u*)(hr + C_GD + 16 * nb);
;               v2u o; o.x = pk2(__uint_as_float(uu.x << 16) * (acc[nb][0] + bias) * __uint_as_float(gd.x << 16), __uint_as_float(uu.x & 0xffff0000u) * (acc[nb][1] + bias) * __uint_as_float(gd.x & 0xffff0000u));
;               o.y = pk2(__uint_as_float(uu.y << 16) * (acc[nb][2] + bias) * __uint_as_float(gd.y << 16), __uint_as_float(uu.y & 0xffff0000u) * (acc[nb][3] + bias) * __uint_as_float(gd.y & 0xffff0000u));
;               *(v2u*)(yr + 16 * nb) = o; } }
.LBB0_675:
	v_add_u32_e32 v58, s40, v38
	v_ashrrev_i32_e32 v59, 31, v58
	v_lshl_add_u64 v[58:59], v[58:59], 2, s[2:3]
	global_load_dword v77, v[58:59], off
	v_lshl_add_u64 v[58:59], s[24:25], 0, v[38:39]
	v_mov_b64_e32 v[60:61], s[0:1]
	v_mad_u64_u32 v[60:61], s[24:25], v58, s13, v[60:61]
	v_mov_b32_e32 v62, v61
	v_mad_u64_u32 v[62:63], s[24:25], v59, s13, v[62:63]
	v_lshlrev_b64 v[58:59], 12, v[58:59]
	s_lshl_b32 s28, s40, 1
	v_lshl_add_u64 v[58:59], s[38:39], 0, v[58:59]
	v_mov_b32_e32 v61, v62
	v_mov_b32_e32 v57, v169
	v_lshl_add_u64 v[58:59], v[58:59], 0, s[28:29]
	v_lshl_add_u64 v[60:61], v[60:61], 0, s[28:29]
	v_lshl_add_u64 v[78:79], v[58:59], 0, v[56:57]
	s_mov_b64 s[24:25], 0x12800c00
	v_lshl_add_u64 v[60:61], v[60:61], 0, v[56:57]
	v_lshl_add_u64 v[58:59], v[78:79], 0, s[24:25]
	s_movk_i32 s24, 0x2000
	v_add_co_u32_e32 v62, vcc, s24, v60
	s_movk_i32 s24, 0x3000
	s_nop 0
	v_addc_co_u32_e32 v63, vcc, 0, v61, vcc
	v_add_co_u32_e32 v60, vcc, s24, v60
	global_load_dwordx2 v[80:81], v[62:63], off offset:1024
	s_nop 0
	v_addc_co_u32_e32 v61, vcc, 0, v61, vcc
	global_load_dwordx2 v[82:83], v[60:61], off offset:2048
	s_mov_b32 s24, 0x12800000
	s_add_i32 s26, s26, s86
	s_cmpk_gt_i32 s26, 0xff
	s_waitcnt vmcnt(0)
	v_add_f32_e32 v28, v77, v28
	v_add_f32_e32 v29, v77, v29
	v_add_f32_e32 v30, v77, v30
	v_add_f32_e32 v31, v77, v31
	v_add_f32_e32 v24, v77, v24
	v_add_f32_e32 v25, v77, v25
	v_add_f32_e32 v26, v77, v26
	v_add_f32_e32 v27, v77, v27
	v_add_f32_e32 v20, v77, v20
	v_add_f32_e32 v21, v77, v21
	v_add_f32_e32 v22, v77, v22
	v_add_f32_e32 v23, v77, v23
	v_add_f32_e32 v16, v77, v16
	v_add_f32_e32 v17, v77, v17
	v_add_f32_e32 v18, v77, v18
	v_add_f32_e32 v19, v77, v19
	v_add_f32_e32 v12, v77, v12
	v_add_f32_e32 v13, v77, v13
	v_add_f32_e32 v14, v77, v14
	v_add_f32_e32 v15, v77, v15
	v_add_f32_e32 v8, v77, v8
	v_add_f32_e32 v9, v77, v9
	v_add_f32_e32 v10, v77, v10
	v_add_f32_e32 v11, v77, v11
	v_add_f32_e32 v4, v77, v4
	v_add_f32_e32 v5, v77, v5
	v_add_f32_e32 v6, v77, v6
	s_waitcnt lgkmcnt(0)
	v_lshlrev_b32_e32 v57, 16, v80
	v_mul_f32_e32 v28, v28, v57
	v_add_f32_e32 v7, v77, v7
	v_lshlrev_b32_e32 v57, 16, v82
	v_mul_f32_e32 v28, v28, v57
	v_and_b32_e32 v57, 0xffff0000, v80
	v_mul_f32_e32 v29, v29, v57
	v_and_b32_e32 v57, 0xffff0000, v82
	v_mul_f32_e32 v29, v29, v57
	v_cvt_pk_bf16_f32 v28, v28, v29
	v_lshlrev_b32_e32 v29, 16, v81
	v_mul_f32_e32 v29, v30, v29
	v_lshlrev_b32_e32 v30, 16, v83
	v_mul_f32_e32 v29, v29, v30
	v_and_b32_e32 v30, 0xffff0000, v81
	v_mul_f32_e32 v30, v31, v30
	v_and_b32_e32 v31, 0xffff0000, v83
	v_mul_f32_e32 v30, v30, v31
	v_cvt_pk_bf16_f32 v29, v29, v30
	v_add_co_u32_e32 v30, vcc, s24, v78
	v_add_f32_e32 v0, v77, v0
	s_nop 0
	v_addc_co_u32_e32 v31, vcc, 0, v79, vcc
	global_store_dwordx2 v[30:31], v[28:29], off offset:3072
	global_load_dwordx2 v[28:29], v[62:63], off offset:1056
	s_nop 0
	global_load_dwordx2 v[30:31], v[60:61], off offset:2080
	v_add_f32_e32 v1, v77, v1
	v_add_f32_e32 v2, v77, v2
	v_add_f32_e32 v3, v77, v3
	s_waitcnt vmcnt(0) lgkmcnt(0)
	v_lshlrev_b32_e32 v57, 16, v28
	v_and_b32_e32 v28, 0xffff0000, v28
	v_mul_f32_e32 v24, v24, v57
	v_lshlrev_b32_e32 v57, 16, v30
	v_mul_f32_e32 v25, v25, v28
	v_and_b32_e32 v28, 0xffff0000, v30
	v_mul_f32_e32 v24, v24, v57
	v_mul_f32_e32 v25, v25, v28
	v_cvt_pk_bf16_f32 v24, v24, v25
	v_lshlrev_b32_e32 v25, 16, v29
	v_mul_f32_e32 v25, v26, v25
	v_lshlrev_b32_e32 v26, 16, v31
	v_mul_f32_e32 v25, v25, v26
	v_and_b32_e32 v26, 0xffff0000, v29
	v_mul_f32_e32 v26, v27, v26
	v_and_b32_e32 v27, 0xffff0000, v31
	v_mul_f32_e32 v26, v26, v27
	v_cvt_pk_bf16_f32 v25, v25, v26
	global_store_dwordx2 v[58:59], v[24:25], off offset:32
	global_load_dwordx2 v[24:25], v[62:63], off offset:1088
	s_nop 0
	global_load_dwordx2 v[26:27], v[60:61], off offset:2112
	s_waitcnt vmcnt(0) lgkmcnt(0)
	v_lshlrev_b32_e32 v28, 16, v24
	v_and_b32_e32 v24, 0xffff0000, v24
	v_mul_f32_e32 v20, v20, v28
	v_lshlrev_b32_e32 v28, 16, v26
	v_mul_f32_e32 v21, v21, v24
	v_and_b32_e32 v24, 0xffff0000, v26
	v_mul_f32_e32 v20, v20, v28
	v_mul_f32_e32 v21, v21, v24
	v_cvt_pk_bf16_f32 v20, v20, v21
	v_lshlrev_b32_e32 v21, 16, v25
	v_mul_f32_e32 v21, v22, v21
	v_lshlrev_b32_e32 v22, 16, v27
	v_mul_f32_e32 v21, v21, v22
	v_and_b32_e32 v22, 0xffff0000, v25
	v_mul_f32_e32 v22, v23, v22
	v_and_b32_e32 v23, 0xffff0000, v27
	v_mul_f32_e32 v22, v22, v23
	v_cvt_pk_bf16_f32 v21, v21, v22
	global_store_dwordx2 v[58:59], v[20:21], off offset:64
	global_load_dwordx2 v[20:21], v[62:63], off offset:1120
	s_nop 0
	global_load_dwordx2 v[22:23], v[60:61], off offset:2144
	s_waitcnt vmcnt(0) lgkmcnt(0)
	v_lshlrev_b32_e32 v24, 16, v20
	v_and_b32_e32 v20, 0xffff0000, v20
	v_mul_f32_e32 v16, v16, v24
	v_lshlrev_b32_e32 v24, 16, v22
	v_mul_f32_e32 v17, v17, v20
	v_and_b32_e32 v20, 0xffff0000, v22
	v_mul_f32_e32 v16, v16, v24
	v_mul_f32_e32 v17, v17, v20
	v_cvt_pk_bf16_f32 v16, v16, v17
	v_lshlrev_b32_e32 v17, 16, v21
	v_mul_f32_e32 v17, v18, v17
	v_lshlrev_b32_e32 v18, 16, v23
	v_mul_f32_e32 v17, v17, v18
	v_and_b32_e32 v18, 0xffff0000, v21
	v_mul_f32_e32 v18, v19, v18
	v_and_b32_e32 v19, 0xffff0000, v23
	v_mul_f32_e32 v18, v18, v19
	v_cvt_pk_bf16_f32 v17, v17, v18
	global_store_dwordx2 v[58:59], v[16:17], off offset:96
	global_load_dwordx2 v[16:17], v[62:63], off offset:1152
	s_nop 0
	global_load_dwordx2 v[18:19], v[60:61], off offset:2176
	s_waitcnt vmcnt(0) lgkmcnt(0)
; __device__ __forceinline__ unsigned pk2(float lo, float hi) { unsigned r; asm("v_cvt_pk_bf16_f32 %0, %1, %2" : "=v"(r) : "v"(lo), "v"(hi)); return r; }
; __device__ __forceinline__ void mix_sgu(const bf16* h, const float* lng, const float* lnb, const float* sgw, const float* sgb, bf16* ycat, char* lds, int wg, int nwg) {
;     ...
;     for (int item = wg; item < NB * 32 * 4; item += nwg) {
;         const int grp = item & 3, n = (item >> 2) & 31, b = item >> 7;
;         const size_t m0 = (size_t)b * SEQ + n * 128;
; #pragma unroll
;         for (int i = 0; i < 8; ++i) { const int idx = tid + 512 * i, t = idx >> 5, s4 = (idx & 31) * 4; const f32x4 w = *(const f32x4*)(sgw + (size_t)grp * 16384 + t * 128 + s4);
;             typedef _Float16 h4 __attribute__((ext_vector_type(4))); h4 o; o[0] = (_Float16)(s4 <= t ? w[0] : 0.f); o[1] = (_Float16)(s4 + 1 <= t ? w[1] : 0.f); o[2] = (_Float16)(s4 + 2 <= t ? w[2] : 0.f); o[3] = (_Float16)(s4 + 3 <= t ? w[3] : 0.f); *(h4*)(lds + t * 288 + s4 * 2) = o; }
;     ...
;         { const int t = 16 * wid + li; const float bias = sgb[grp * 128 + t];
;           const bf16* hr = h + (m0 + t) * NH + 128 * grp + 4 * g; bf16* yr = ycat + (m0 + t) * DM + Y_D + 128 * grp + 4 * g;
; #pragma unroll
;           for (int nb = 0; nb < 8; ++nb) { const v2u uu = *(const v2u*)(hr + C_DU + 16 * nb), gd = *(const v2u*)(hr + C_GD + 16 * nb);
;               v2u o; o.x = pk2(__uint_as_float(uu.x << 16) * (acc[nb][0] + bias) * __uint_as_float(gd.x << 16), __uint_as_float(uu.x & 0xffff0000u) * (acc[nb][1] + bias) * __uint_as_float(gd.x & 0xffff0000u));
;               o.y = pk2(__uint_as_float(uu.y << 16) * (acc[nb][2] + bias) * __uint_as_float(gd.y << 16), __uint_as_float(uu.y & 0xffff0000u) * (acc[nb][3] + bias) * __uint_as_float(gd.y & 0xffff0000u));
;               *(v2u*)(yr + 16 * nb) = o; } }
;         __syncthreads();
	v_lshlrev_b32_e32 v20, 16, v16
	v_and_b32_e32 v16, 0xffff0000, v16
	v_mul_f32_e32 v12, v12, v20
	v_lshlrev_b32_e32 v20, 16, v18
	v_mul_f32_e32 v13, v13, v16
	v_and_b32_e32 v16, 0xffff0000, v18
	v_mul_f32_e32 v12, v12, v20
	v_mul_f32_e32 v13, v13, v16
	v_cvt_pk_bf16_f32 v12, v12, v13
	v_lshlrev_b32_e32 v13, 16, v17
	v_mul_f32_e32 v13, v14, v13
	v_lshlrev_b32_e32 v14, 16, v19
	v_mul_f32_e32 v13, v13, v14
	v_and_b32_e32 v14, 0xffff0000, v17
	v_mul_f32_e32 v14, v15, v14
	v_and_b32_e32 v15, 0xffff0000, v19
	v_mul_f32_e32 v14, v14, v15
	v_cvt_pk_bf16_f32 v13, v13, v14
	global_store_dwordx2 v[58:59], v[12:13], off offset:128
	global_load_dwordx2 v[12:13], v[62:63], off offset:1184
	s_nop 0
	global_load_dwordx2 v[14:15], v[60:61], off offset:2208
	s_waitcnt vmcnt(0) lgkmcnt(0)
	v_lshlrev_b32_e32 v16, 16, v12
	v_and_b32_e32 v12, 0xffff0000, v12
	v_mul_f32_e32 v8, v8, v16
	v_lshlrev_b32_e32 v16, 16, v14
	v_mul_f32_e32 v9, v9, v12
	v_and_b32_e32 v12, 0xffff0000, v14
	v_mul_f32_e32 v8, v8, v16
	v_mul_f32_e32 v9, v9, v12
	v_cvt_pk_bf16_f32 v8, v8, v9
	v_lshlrev_b32_e32 v9, 16, v13
	v_mul_f32_e32 v9, v10, v9
	v_lshlrev_b32_e32 v10, 16, v15
	v_mul_f32_e32 v9, v9, v10
	v_and_b32_e32 v10, 0xffff0000, v13
	v_mul_f32_e32 v10, v11, v10
	v_and_b32_e32 v11, 0xffff0000, v15
	v_mul_f32_e32 v10, v10, v11
	v_cvt_pk_bf16_f32 v9, v9, v10
	global_store_dwordx2 v[58:59], v[8:9], off offset:160
	global_load_dwordx2 v[8:9], v[62:63], off offset:1216
	s_nop 0
	global_load_dwordx2 v[10:11], v[60:61], off offset:2240
	s_waitcnt vmcnt(0) lgkmcnt(0)
	v_lshlrev_b32_e32 v12, 16, v8
	v_and_b32_e32 v8, 0xffff0000, v8
	v_mul_f32_e32 v4, v4, v12
	v_lshlrev_b32_e32 v12, 16, v10
	v_mul_f32_e32 v5, v5, v8
	v_and_b32_e32 v8, 0xffff0000, v10
	v_mul_f32_e32 v4, v4, v12
	v_mul_f32_e32 v5, v5, v8
	v_cvt_pk_bf16_f32 v4, v4, v5
	v_lshlrev_b32_e32 v5, 16, v9
	v_mul_f32_e32 v5, v6, v5
	v_lshlrev_b32_e32 v6, 16, v11
	v_mul_f32_e32 v5, v5, v6
	v_and_b32_e32 v6, 0xffff0000, v9
	v_mul_f32_e32 v6, v7, v6
	v_and_b32_e32 v7, 0xffff0000, v11
	v_mul_f32_e32 v6, v6, v7
	v_cvt_pk_bf16_f32 v5, v5, v6
	global_store_dwordx2 v[58:59], v[4:5], off offset:192
	global_load_dwordx2 v[4:5], v[62:63], off offset:1248
	s_nop 0
	global_load_dwordx2 v[6:7], v[60:61], off offset:2272
	s_waitcnt vmcnt(0) lgkmcnt(0)
	v_lshlrev_b32_e32 v8, 16, v4
	v_and_b32_e32 v4, 0xffff0000, v4
	v_mul_f32_e32 v0, v0, v8
	v_lshlrev_b32_e32 v8, 16, v6
	v_mul_f32_e32 v1, v1, v4
	v_and_b32_e32 v4, 0xffff0000, v6
	v_mul_f32_e32 v0, v0, v8
	v_mul_f32_e32 v1, v1, v4
	v_cvt_pk_bf16_f32 v0, v0, v1
	v_lshlrev_b32_e32 v1, 16, v5
	v_mul_f32_e32 v1, v2, v1
	v_lshlrev_b32_e32 v2, 16, v7
	v_mul_f32_e32 v1, v1, v2
	v_and_b32_e32 v2, 0xffff0000, v5
	v_mul_f32_e32 v2, v3, v2
	v_and_b32_e32 v3, 0xffff0000, v7
	v_mul_f32_e32 v2, v2, v3
	v_cvt_pk_bf16_f32 v1, v1, v2
	global_store_dwordx2 v[58:59], v[0:1], off offset:224
	s_waitcnt lgkmcnt(0)
	s_barrier
	s_cbranch_scc1 .LBB0_679
.LBB0_676:
	s_and_b32 s27, s26, 3
	s_lshl_b32 s28, s27, 16
	v_lshl_add_u64 v[28:29], v[32:33], 0, s[28:29]
	v_lshl_add_u64 v[0:1], v[40:41], 2, v[28:29]
	global_load_dwordx4 v[0:3], v[0:1], off
	v_lshl_add_u64 v[4:5], v[42:43], 2, v[28:29]
	v_lshl_add_u64 v[8:9], v[44:45], 2, v[28:29]
	v_lshl_add_u64 v[12:13], v[46:47], 2, v[28:29]
	v_lshl_add_u64 v[16:17], v[48:49], 2, v[28:29]
	v_lshl_add_u64 v[20:21], v[50:51], 2, v[28:29]
	global_load_dwordx4 v[4:7], v[4:5], off
	v_lshl_add_u64 v[24:25], v[52:53], 2, v[28:29]
	global_load_dwordx4 v[8:11], v[8:9], off
	v_lshl_add_u64 v[28:29], v[54:55], 2, v[28:29]
	global_load_dwordx4 v[12:15], v[12:13], off
	v_readlane_b32 s40, v255, 56
	global_load_dwordx4 v[16:19], v[16:17], off
	v_readlane_b32 s41, v255, 57
	global_load_dwordx4 v[20:23], v[20:21], off
	s_ashr_i32 s24, s26, 7
	global_load_dwordx4 v[24:27], v[24:25], off
	s_lshl_b32 s28, s26, 5
	global_load_dwordx4 v[28:31], v[28:29], off
	s_ashr_i32 s25, s24, 31
	s_and_b32 s28, s28, 0xf80
	s_lshl_b64 s[24:25], s[24:25], 12
	s_or_b32 s24, s24, s28
	s_lshl_b32 s28, s27, 8
	s_waitcnt vmcnt(0)
	v_cvt_f16_f32_e32 v0, v0
	v_cvt_f16_f32_e32 v1, v1
	v_cvt_f16_f32_e32 v2, v2
	v_cvt_f16_f32_e32 v3, v3
	v_cndmask_b32_e64 v0, v0, 0, s[40:41]
	v_readlane_b32 s40, v255, 58
	v_cvt_f16_f32_e32 v4, v4
	v_cvt_f16_f32_e32 v5, v5
	v_cvt_f16_f32_e32 v6, v6
	v_cvt_f16_f32_e32 v7, v7
	v_cvt_f16_f32_e32 v8, v8
	v_cvt_f16_f32_e32 v9, v9
	v_cvt_f16_f32_e32 v10, v10
	v_cvt_f16_f32_e32 v11, v11
	v_cvt_f16_f32_e32 v12, v12
	v_cvt_f16_f32_e32 v13, v13
	v_cvt_f16_f32_e32 v14, v14
	v_cvt_f16_f32_e32 v15, v15
	v_cvt_f16_f32_e32 v16, v16
	v_cvt_f16_f32_e32 v17, v17
	v_cvt_f16_f32_e32 v18, v18
	v_cvt_f16_f32_e32 v19, v19
	v_cvt_f16_f32_e32 v20, v20
	v_cvt_f16_f32_e32 v21, v21
	v_cvt_f16_f32_e32 v22, v22
	v_cvt_f16_f32_e32 v23, v23
	v_readlane_b32 s41, v255, 59
	v_cndmask_b32_e64 v4, v4, 0, s[48:49]
	v_cndmask_b32_e64 v5, 0, v5, s[50:51]
	v_cndmask_b32_e64 v57, 0, v1, s[40:41]
	v_cndmask_b32_e64 v1, v2, 0, s[44:45]
	v_cndmask_b32_e64 v2, v3, 0, s[46:47]
	v_cndmask_b32_e64 v3, v6, 0, s[52:53]
	v_cndmask_b32_e64 v6, v7, 0, s[54:55]
	v_cndmask_b32_e64 v7, v8, 0, s[56:57]
	v_cndmask_b32_e64 v8, 0, v9, s[58:59]
	v_cndmask_b32_e64 v9, v10, 0, s[60:61]
	v_cndmask_b32_e64 v10, v11, 0, s[62:63]
	v_cndmask_b32_e64 v11, v12, 0, s[64:65]
	v_cndmask_b32_e64 v12, 0, v13, s[66:67]
	v_cndmask_b32_e64 v13, v14, 0, s[68:69]
	v_cndmask_b32_e64 v14, v15, 0, s[70:71]
	v_cndmask_b32_e64 v15, v16, 0, s[72:73]
	v_cndmask_b32_e64 v16, 0, v17, s[74:75]
	v_cndmask_b32_e64 v17, v18, 0, s[76:77]
	v_cndmask_b32_e64 v18, v19, 0, s[78:79]
	v_cndmask_b32_e64 v19, v20, 0, s[80:81]
	v_cndmask_b32_e64 v20, 0, v21, s[82:83]
	v_cndmask_b32_e64 v21, v22, 0, s[84:85]
; __device__ __forceinline__ float bfe(const v4u& v, int e) { const unsigned w = v[e >> 1]; return (e & 1) ? __uint_as_float(w & 0xffff0000u) : __uint_as_float(w << 16); }
; __device__ __forceinline__ void mix_sgu(const bf16* h, const float* lng, const float* lnb, const float* sgw, const float* sgb, bf16* ycat, char* lds, int wg, int nwg) {
;     ...
;         for (int i = 0; i < 8; ++i) { const int idx = tid + 512 * i, t = idx >> 5, s4 = (idx & 31) * 4; const f32x4 w = *(const f32x4*)(sgw + (size_t)grp * 16384 + t * 128 + s4);
;             typedef _Float16 h4 __attribute__((ext_vector_type(4))); h4 o; o[0] = (_Float16)(s4 <= t ? w[0] : 0.f); o[1] = (_Float16)(s4 + 1 <= t ? w[1] : 0.f); o[2] = (_Float16)(s4 + 2 <= t ? w[2] : 0.f); o[3] = (_Float16)(s4 + 3 <= t ? w[3] : 0.f); *(h4*)(lds + t * 288 + s4 * 2) = o; }
;         { const int row = tid >> 2, q = tid & 3; const bf16* vr = h + (m0 + row) * NH + C_DV;
;           float s1 = 0.f, s2 = 0.f;
; #pragma unroll
;           for (int j = 0; j < 16; ++j) { const v4u vv = *(const v4u*)(vr + (4 * j + q) * 8);
; #pragma unroll
;               for (int e = 0; e < 8; ++e) { const float x = bfe(vv, e); s1 += x; s2 += x * x; } }
	v_cndmask_b32_e64 v22, v23, 0, s[42:43]
	v_pack_b32_f16 v1, v1, v2
	v_pack_b32_f16 v0, v0, v57
	v_cvt_f16_f32_e32 v24, v24
	v_cvt_f16_f32_e32 v25, v25
	v_pack_b32_f16 v3, v3, v6
	v_pack_b32_f16 v2, v4, v5
	v_pack_b32_f16 v5, v9, v10
	v_pack_b32_f16 v4, v7, v8
	v_pack_b32_f16 v7, v13, v14
	v_pack_b32_f16 v6, v11, v12
	v_pack_b32_f16 v9, v17, v18
	v_pack_b32_f16 v8, v15, v16
	v_pack_b32_f16 v11, v21, v22
	v_pack_b32_f16 v10, v19, v20
	ds_write_b64 v67, v[0:1]
	ds_write_b64 v68, v[2:3]
	ds_write_b64 v69, v[4:5]
	ds_write_b64 v70, v[6:7]
	ds_write_b64 v71, v[8:9]
	ds_write_b64 v72, v[10:11]
	v_cvt_f16_f32_e32 v0, v26
	v_cvt_f16_f32_e32 v1, v27
	v_cndmask_b32_e64 v2, v24, 0, s[88:89]
	v_cndmask_b32_e64 v3, 0, v25, s[90:91]
	v_cndmask_b32_e64 v0, v0, 0, s[92:93]
	v_cndmask_b32_e64 v1, v1, 0, s[94:95]
	v_pack_b32_f16 v1, v0, v1
	v_pack_b32_f16 v0, v2, v3
	ds_write_b64 v73, v[0:1]
	v_cvt_f16_f32_e32 v0, v28
	v_cvt_f16_f32_e32 v1, v29
	v_cvt_f16_f32_e32 v2, v30
	v_cvt_f16_f32_e32 v3, v31
	v_cndmask_b32_e64 v0, v0, 0, s[96:97]
	v_cndmask_b32_e64 v4, 0, v1, s[4:5]
	v_cndmask_b32_e64 v1, v2, 0, s[6:7]
	v_cndmask_b32_e64 v2, v3, 0, s[8:9]
	v_pack_b32_f16 v1, v1, v2
	v_pack_b32_f16 v0, v0, v4
	ds_write_b64 v74, v[0:1]
	v_lshl_add_u64 v[0:1], s[24:25], 0, v[34:35]
	v_mov_b64_e32 v[2:3], s[0:1]
	v_mad_u64_u32 v[2:3], s[40:41], v0, s13, v[2:3]
	v_mad_i32_i24 v3, v1, s13, v3
	s_mov_b64 s[40:41], 0x2800
	v_lshl_add_u64 v[8:9], v[2:3], 0, s[40:41]
	v_lshl_add_u64 v[10:11], v[8:9], 0, v[168:169]
	global_load_dwordx4 v[12:15], v[10:11], off
	global_load_dwordx4 v[16:19], v[10:11], off offset:64
	global_load_dwordx4 v[20:23], v[10:11], off offset:128
	global_load_dwordx4 v[24:27], v[10:11], off offset:192
	global_load_dwordx4 v[28:31], v[10:11], off offset:256
	global_load_dwordx4 v[4:7], v[10:11], off offset:320
	global_load_dwordx4 v[0:3], v[10:11], off offset:384
	s_lshl_b32 s40, s27, 7
	s_mov_b32 s27, 0x800000
	s_waitcnt vmcnt(0) lgkmcnt(0)
	v_lshlrev_b32_e32 v57, 16, v12
	v_and_b32_e32 v58, 0xffff0000, v12
	v_add_f32_e32 v83, 0, v57
	v_mul_f32_e32 v12, v58, v58
	v_lshlrev_b32_e32 v59, 16, v13
	v_add_f32_e32 v58, v83, v58
	v_fmac_f32_e32 v12, v57, v57
	v_and_b32_e32 v13, 0xffff0000, v13
	v_add_f32_e32 v57, v58, v59
	v_fmac_f32_e32 v12, v59, v59
	v_lshlrev_b32_e32 v60, 16, v14
	v_add_f32_e32 v57, v57, v13
	v_fmac_f32_e32 v12, v13, v13
	v_and_b32_e32 v14, 0xffff0000, v14
	v_add_f32_e32 v13, v57, v60
	v_fmac_f32_e32 v12, v60, v60
	v_lshlrev_b32_e32 v61, 16, v15
	v_add_f32_e32 v13, v13, v14
	v_fmac_f32_e32 v12, v14, v14
	v_and_b32_e32 v15, 0xffff0000, v15
	v_add_f32_e32 v13, v13, v61
	v_fmac_f32_e32 v12, v61, v61
	v_lshlrev_b32_e32 v62, 16, v16
	v_add_f32_e32 v13, v13, v15
	v_fmac_f32_e32 v12, v15, v15
	v_and_b32_e32 v16, 0xffff0000, v16
	v_add_f32_e32 v13, v13, v62
	v_fmac_f32_e32 v12, v62, v62
	v_lshlrev_b32_e32 v63, 16, v17
	v_add_f32_e32 v13, v13, v16
	v_fmac_f32_e32 v12, v16, v16
	v_and_b32_e32 v17, 0xffff0000, v17
	v_add_f32_e32 v13, v13, v63
	v_fmac_f32_e32 v12, v63, v63
	v_lshlrev_b32_e32 v77, 16, v18
	v_add_f32_e32 v13, v13, v17
	v_fmac_f32_e32 v12, v17, v17
	v_and_b32_e32 v18, 0xffff0000, v18
	v_add_f32_e32 v13, v13, v77
	v_fmac_f32_e32 v12, v77, v77
	v_lshlrev_b32_e32 v78, 16, v19
	v_add_f32_e32 v13, v13, v18
	v_fmac_f32_e32 v12, v18, v18
	v_and_b32_e32 v19, 0xffff0000, v19
	v_add_f32_e32 v13, v13, v78
	v_fmac_f32_e32 v12, v78, v78
	v_lshlrev_b32_e32 v79, 16, v20
	v_add_f32_e32 v13, v13, v19
	v_fmac_f32_e32 v12, v19, v19
	v_and_b32_e32 v20, 0xffff0000, v20
	v_add_f32_e32 v13, v13, v79
	v_fmac_f32_e32 v12, v79, v79
	v_lshlrev_b32_e32 v80, 16, v21
	v_add_f32_e32 v13, v13, v20
	v_fmac_f32_e32 v12, v20, v20
	v_and_b32_e32 v21, 0xffff0000, v21
	v_add_f32_e32 v13, v13, v80
	v_fmac_f32_e32 v12, v80, v80
	v_lshlrev_b32_e32 v81, 16, v22
	v_add_f32_e32 v13, v13, v21
	v_fmac_f32_e32 v12, v21, v21
	v_and_b32_e32 v22, 0xffff0000, v22
	v_add_f32_e32 v13, v13, v81
	v_fmac_f32_e32 v12, v81, v81
	v_lshlrev_b32_e32 v82, 16, v23
	v_add_f32_e32 v13, v13, v22
	v_fmac_f32_e32 v12, v22, v22
	v_add_f32_e32 v13, v13, v82
	v_fmac_f32_e32 v12, v82, v82
	v_and_b32_e32 v14, 0xffff0000, v23
	v_add_f32_e32 v13, v13, v14
	v_fmac_f32_e32 v12, v14, v14
	v_lshlrev_b32_e32 v14, 16, v24
	v_add_f32_e32 v13, v13, v14
	v_fmac_f32_e32 v12, v14, v14
	v_and_b32_e32 v14, 0xffff0000, v24
	v_add_f32_e32 v13, v13, v14
	v_fmac_f32_e32 v12, v14, v14
	v_lshlrev_b32_e32 v14, 16, v25
	v_add_f32_e32 v13, v13, v14
	v_fmac_f32_e32 v12, v14, v14
	v_and_b32_e32 v14, 0xffff0000, v25
	v_add_f32_e32 v13, v13, v14
	v_fmac_f32_e32 v12, v14, v14
	v_lshlrev_b32_e32 v14, 16, v26
	v_add_f32_e32 v13, v13, v14
	v_fmac_f32_e32 v12, v14, v14
	v_and_b32_e32 v14, 0xffff0000, v26
	v_add_f32_e32 v13, v13, v14
	v_fmac_f32_e32 v12, v14, v14
	global_load_dwordx4 v[14:17], v[10:11], off offset:448
	v_lshlrev_b32_e32 v18, 16, v27
	v_add_f32_e32 v13, v13, v18
	v_fmac_f32_e32 v12, v18, v18
	v_and_b32_e32 v18, 0xffff0000, v27
	v_add_f32_e32 v13, v13, v18
	v_fmac_f32_e32 v12, v18, v18
	v_lshlrev_b32_e32 v18, 16, v28
	v_add_f32_e32 v13, v13, v18
	v_fmac_f32_e32 v12, v18, v18
	v_and_b32_e32 v18, 0xffff0000, v28
	v_add_f32_e32 v13, v13, v18
	v_fmac_f32_e32 v12, v18, v18
	v_lshlrev_b32_e32 v18, 16, v29
	v_add_f32_e32 v13, v13, v18
	v_fmac_f32_e32 v12, v18, v18
	v_and_b32_e32 v18, 0xffff0000, v29
	v_add_f32_e32 v13, v13, v18
	v_fmac_f32_e32 v12, v18, v18
	v_lshlrev_b32_e32 v18, 16, v30
	v_add_f32_e32 v13, v13, v18
	v_fmac_f32_e32 v12, v18, v18
	v_and_b32_e32 v18, 0xffff0000, v30
	v_add_f32_e32 v13, v13, v18
	v_fmac_f32_e32 v12, v18, v18
	global_load_dwordx4 v[18:21], v[10:11], off offset:512
	v_lshlrev_b32_e32 v22, 16, v31
; __device__ __forceinline__ float bfe(const v4u& v, int e) { const unsigned w = v[e >> 1]; return (e & 1) ? __uint_as_float(w & 0xffff0000u) : __uint_as_float(w << 16); }
; __device__ __forceinline__ void mix_sgu(const bf16* h, const float* lng, const float* lnb, const float* sgw, const float* sgb, bf16* ycat, char* lds, int wg, int nwg) {
;     ...
;           for (int j = 0; j < 16; ++j) { const v4u vv = *(const v4u*)(vr + (4 * j + q) * 8);
; #pragma unroll
;               for (int e = 0; e < 8; ++e) { const float x = bfe(vv, e); s1 += x; s2 += x * x; } }
	v_add_f32_e32 v13, v13, v22
	v_fmac_f32_e32 v12, v22, v22
	v_and_b32_e32 v22, 0xffff0000, v31
	v_add_f32_e32 v13, v13, v22
	v_fmac_f32_e32 v12, v22, v22
	v_lshlrev_b32_e32 v22, 16, v4
	v_add_f32_e32 v13, v13, v22
	v_fmac_f32_e32 v12, v22, v22
	global_load_dwordx4 v[22:25], v[10:11], off offset:576
	v_and_b32_e32 v4, 0xffff0000, v4
	v_add_f32_e32 v13, v13, v4
	v_fmac_f32_e32 v12, v4, v4
	v_lshlrev_b32_e32 v4, 16, v5
	v_add_f32_e32 v13, v13, v4
	v_fmac_f32_e32 v12, v4, v4
	v_and_b32_e32 v4, 0xffff0000, v5
	v_add_f32_e32 v5, v13, v4
	v_fmac_f32_e32 v12, v4, v4
	v_lshlrev_b32_e32 v4, 16, v6
	v_add_f32_e32 v5, v5, v4
	v_fmac_f32_e32 v12, v4, v4
	v_and_b32_e32 v4, 0xffff0000, v6
	v_add_f32_e32 v5, v5, v4
	v_fmac_f32_e32 v12, v4, v4
	v_lshlrev_b32_e32 v4, 16, v7
	v_add_f32_e32 v5, v5, v4
	v_fmac_f32_e32 v12, v4, v4
	v_and_b32_e32 v4, 0xffff0000, v7
	v_add_f32_e32 v5, v5, v4
	v_fmac_f32_e32 v12, v4, v4
	v_lshlrev_b32_e32 v4, 16, v0
	v_add_f32_e32 v5, v5, v4
	v_fmac_f32_e32 v12, v4, v4
	v_and_b32_e32 v0, 0xffff0000, v0
	v_add_f32_e32 v4, v5, v0
	v_fmac_f32_e32 v12, v0, v0
	v_lshlrev_b32_e32 v0, 16, v1
	v_add_f32_e32 v4, v4, v0
	v_fmac_f32_e32 v12, v0, v0
	v_and_b32_e32 v0, 0xffff0000, v1
	v_add_f32_e32 v1, v4, v0
	global_load_dwordx4 v[4:7], v[10:11], off offset:640
	v_fmac_f32_e32 v12, v0, v0
	v_lshlrev_b32_e32 v0, 16, v2
	v_add_f32_e32 v1, v1, v0
	v_fmac_f32_e32 v12, v0, v0
	v_and_b32_e32 v0, 0xffff0000, v2
	v_add_f32_e32 v1, v1, v0
	v_fmac_f32_e32 v12, v0, v0
	v_lshlrev_b32_e32 v0, 16, v3
	v_add_f32_e32 v1, v1, v0
	v_fmac_f32_e32 v12, v0, v0
	v_and_b32_e32 v0, 0xffff0000, v3
	v_add_f32_e32 v1, v1, v0
	v_fmac_f32_e32 v12, v0, v0
	s_waitcnt vmcnt(0) lgkmcnt(0)
	v_lshlrev_b32_e32 v0, 16, v14
	v_add_f32_e32 v1, v1, v0
	v_fmac_f32_e32 v12, v0, v0
	v_and_b32_e32 v0, 0xffff0000, v14
	v_add_f32_e32 v1, v1, v0
	v_fmac_f32_e32 v12, v0, v0
	v_lshlrev_b32_e32 v0, 16, v15
	v_add_f32_e32 v1, v1, v0
	v_fmac_f32_e32 v12, v0, v0
	v_and_b32_e32 v0, 0xffff0000, v15
	v_add_f32_e32 v1, v1, v0
	v_fmac_f32_e32 v12, v0, v0
	v_lshlrev_b32_e32 v0, 16, v16
	v_add_f32_e32 v1, v1, v0
	v_fmac_f32_e32 v12, v0, v0
	v_and_b32_e32 v0, 0xffff0000, v16
	v_add_f32_e32 v1, v1, v0
	v_lshlrev_b32_e32 v13, 16, v17
	v_fmac_f32_e32 v12, v0, v0
	v_add_f32_e32 v14, v1, v13
	global_load_dwordx4 v[0:3], v[10:11], off offset:704
	v_fmac_f32_e32 v12, v13, v13
	v_and_b32_e32 v13, 0xffff0000, v17
	v_add_f32_e32 v14, v14, v13
	v_fmac_f32_e32 v12, v13, v13
	v_lshlrev_b32_e32 v13, 16, v18
	v_add_f32_e32 v14, v14, v13
	v_fmac_f32_e32 v12, v13, v13
	v_and_b32_e32 v13, 0xffff0000, v18
	v_add_f32_e32 v14, v14, v13
	v_fmac_f32_e32 v12, v13, v13
	v_lshlrev_b32_e32 v13, 16, v19
	v_add_f32_e32 v14, v14, v13
	v_fmac_f32_e32 v12, v13, v13
	v_and_b32_e32 v13, 0xffff0000, v19
	v_add_f32_e32 v14, v14, v13
	v_fmac_f32_e32 v12, v13, v13
	v_lshlrev_b32_e32 v13, 16, v20
	v_add_f32_e32 v14, v14, v13
	v_fmac_f32_e32 v12, v13, v13
	v_and_b32_e32 v13, 0xffff0000, v20
	v_add_f32_e32 v18, v14, v13
	global_load_dwordx4 v[14:17], v[10:11], off offset:768
	v_fmac_f32_e32 v12, v13, v13
	v_lshlrev_b32_e32 v13, 16, v21
	v_add_f32_e32 v18, v18, v13
	v_fmac_f32_e32 v12, v13, v13
	v_and_b32_e32 v13, 0xffff0000, v21
	v_add_f32_e32 v18, v18, v13
	v_fmac_f32_e32 v12, v13, v13
	v_lshlrev_b32_e32 v13, 16, v22
	v_add_f32_e32 v18, v18, v13
	v_fmac_f32_e32 v12, v13, v13
	v_and_b32_e32 v13, 0xffff0000, v22
	v_add_f32_e32 v18, v18, v13
	v_fmac_f32_e32 v12, v13, v13
	v_lshlrev_b32_e32 v13, 16, v23
	v_add_f32_e32 v18, v18, v13
	v_fmac_f32_e32 v12, v13, v13
	v_and_b32_e32 v13, 0xffff0000, v23
	v_add_f32_e32 v18, v18, v13
	v_fmac_f32_e32 v12, v13, v13
	v_lshlrev_b32_e32 v13, 16, v24
	v_add_f32_e32 v18, v18, v13
	v_fmac_f32_e32 v12, v13, v13
	v_and_b32_e32 v13, 0xffff0000, v24
	v_add_f32_e32 v22, v18, v13
	global_load_dwordx4 v[18:21], v[10:11], off offset:832
	v_fmac_f32_e32 v12, v13, v13
	v_lshlrev_b32_e32 v13, 16, v25
	v_add_f32_e32 v22, v22, v13
	v_fmac_f32_e32 v12, v13, v13
	v_and_b32_e32 v13, 0xffff0000, v25
	v_add_f32_e32 v22, v22, v13
	v_fmac_f32_e32 v12, v13, v13
	v_lshlrev_b32_e32 v13, 16, v4
	v_add_f32_e32 v22, v22, v13
	v_and_b32_e32 v4, 0xffff0000, v4
	v_fmac_f32_e32 v12, v13, v13
	v_add_f32_e32 v13, v22, v4
	global_load_dwordx4 v[22:25], v[10:11], off offset:896
	v_fmac_f32_e32 v12, v4, v4
	v_lshlrev_b32_e32 v4, 16, v5
	v_add_f32_e32 v13, v13, v4
	v_fmac_f32_e32 v12, v4, v4
	v_and_b32_e32 v4, 0xffff0000, v5
	v_add_f32_e32 v5, v13, v4
	v_fmac_f32_e32 v12, v4, v4
	v_lshlrev_b32_e32 v4, 16, v6
	v_add_f32_e32 v5, v5, v4
	v_fmac_f32_e32 v12, v4, v4
	v_and_b32_e32 v4, 0xffff0000, v6
	v_add_f32_e32 v5, v5, v4
	v_fmac_f32_e32 v12, v4, v4
	v_lshlrev_b32_e32 v4, 16, v7
	v_add_f32_e32 v5, v5, v4
	v_fmac_f32_e32 v12, v4, v4
	v_and_b32_e32 v4, 0xffff0000, v7
	v_add_f32_e32 v5, v5, v4
	v_fmac_f32_e32 v12, v4, v4
	s_waitcnt vmcnt(0) lgkmcnt(0)
; __device__ __forceinline__ float bfe(const v4u& v, int e) { const unsigned w = v[e >> 1]; return (e & 1) ? __uint_as_float(w & 0xffff0000u) : __uint_as_float(w << 16); }
; __device__ __forceinline__ void mix_sgu(const bf16* h, const float* lng, const float* lnb, const float* sgw, const float* sgb, bf16* ycat, char* lds, int wg, int nwg) {
;     ...
;           for (int j = 0; j < 16; ++j) { const v4u vv = *(const v4u*)(vr + (4 * j + q) * 8);
; #pragma unroll
;               for (int e = 0; e < 8; ++e) { const float x = bfe(vv, e); s1 += x; s2 += x * x; } }
;           s1 += __shfl_xor(s1, 1); s1 += __shfl_xor(s1, 2); s2 += __shfl_xor(s2, 1); s2 += __shfl_xor(s2, 2);
;           const float mu = s1 * (1.f / 512.f), rstd = rsqrtf(fmaxf(s2 * (1.f / 512.f) - mu * mu, 0.f) + LN_EPS);
; #pragma unroll
;           for (int j = 0; j < 4; ++j) { const int c0 = 32 * q + 8 * j; const v4u vv = *(const v4u*)(vr + 128 * grp + c0);
; #pragma unroll
;               for (int e = 0; e < 8; ++e) { const float y = (bfe(vv, e) - mu) * rstd * lng[128 * grp + c0 + e] + lnb[128 * grp + c0 + e]; *(_Float16*)(lds + 36864 + (c0 + e) * 288 + row * 2) = (_Float16)y; } } }
	v_lshlrev_b32_e32 v4, 16, v0
	v_add_f32_e32 v5, v5, v4
	v_fmac_f32_e32 v12, v4, v4
	v_and_b32_e32 v0, 0xffff0000, v0
	v_add_f32_e32 v4, v5, v0
	v_fmac_f32_e32 v12, v0, v0
	v_lshlrev_b32_e32 v0, 16, v1
	v_add_f32_e32 v4, v4, v0
	v_fmac_f32_e32 v12, v0, v0
	v_and_b32_e32 v0, 0xffff0000, v1
	v_add_f32_e32 v1, v4, v0
	v_fmac_f32_e32 v12, v0, v0
	v_lshlrev_b32_e32 v0, 16, v2
	v_add_f32_e32 v1, v1, v0
	v_fmac_f32_e32 v12, v0, v0
	v_and_b32_e32 v0, 0xffff0000, v2
	v_add_f32_e32 v1, v1, v0
	v_fmac_f32_e32 v12, v0, v0
	v_lshlrev_b32_e32 v0, 16, v3
	v_add_f32_e32 v1, v1, v0
	v_fmac_f32_e32 v12, v0, v0
	v_and_b32_e32 v0, 0xffff0000, v3
	v_add_f32_e32 v1, v1, v0
	v_fmac_f32_e32 v12, v0, v0
	v_lshlrev_b32_e32 v0, 16, v14
	v_add_f32_e32 v1, v1, v0
	v_and_b32_e32 v4, 0xffff0000, v14
	v_fmac_f32_e32 v12, v0, v0
	v_add_f32_e32 v5, v1, v4
	global_load_dwordx4 v[0:3], v[10:11], off offset:960
	v_fmac_f32_e32 v12, v4, v4
	v_lshlrev_b32_e32 v4, 16, v15
	v_add_f32_e32 v5, v5, v4
	v_fmac_f32_e32 v12, v4, v4
	v_and_b32_e32 v4, 0xffff0000, v15
	v_add_f32_e32 v5, v5, v4
	v_fmac_f32_e32 v12, v4, v4
	v_lshlrev_b32_e32 v4, 16, v16
	v_add_f32_e32 v5, v5, v4
	v_fmac_f32_e32 v12, v4, v4
	v_and_b32_e32 v4, 0xffff0000, v16
	v_add_f32_e32 v5, v5, v4
	v_fmac_f32_e32 v12, v4, v4
	v_lshlrev_b32_e32 v4, 16, v17
	v_add_f32_e32 v5, v5, v4
	v_fmac_f32_e32 v12, v4, v4
	v_and_b32_e32 v4, 0xffff0000, v17
	v_add_f32_e32 v5, v5, v4
	v_fmac_f32_e32 v12, v4, v4
	v_lshlrev_b32_e32 v4, 16, v18
	v_add_f32_e32 v5, v5, v4
	v_fmac_f32_e32 v12, v4, v4
	v_and_b32_e32 v4, 0xffff0000, v18
	v_add_f32_e32 v5, v5, v4
	v_fmac_f32_e32 v12, v4, v4
	v_lshlrev_b32_e32 v4, 16, v19
	v_add_f32_e32 v5, v5, v4
	v_fmac_f32_e32 v12, v4, v4
	v_and_b32_e32 v4, 0xffff0000, v19
	v_add_f32_e32 v5, v5, v4
	v_fmac_f32_e32 v12, v4, v4
	v_lshlrev_b32_e32 v4, 16, v20
	v_add_f32_e32 v5, v5, v4
	v_fmac_f32_e32 v12, v4, v4
	v_and_b32_e32 v4, 0xffff0000, v20
	v_add_f32_e32 v5, v5, v4
	v_fmac_f32_e32 v12, v4, v4
	v_lshlrev_b32_e32 v4, 16, v21
	v_add_f32_e32 v5, v5, v4
	v_fmac_f32_e32 v12, v4, v4
	v_and_b32_e32 v4, 0xffff0000, v21
	v_add_f32_e32 v5, v5, v4
	v_fmac_f32_e32 v12, v4, v4
	v_lshlrev_b32_e32 v4, 16, v22
	v_add_f32_e32 v5, v5, v4
	v_and_b32_e32 v13, 0xffff0000, v22
	v_fmac_f32_e32 v12, v4, v4
	v_add_f32_e32 v22, v5, v13
	v_lshl_add_u64 v[4:5], v[8:9], 0, s[28:29]
	v_lshlrev_b32_e32 v6, 1, v36
	v_mov_b32_e32 v7, v169
	v_lshl_add_u64 v[30:31], v[4:5], 0, v[6:7]
	global_load_dwordx4 v[4:7], v[30:31], off
	v_or_b32_e32 v8, s40, v36
	v_lshlrev_b32_e32 v57, 2, v8
	global_load_dwordx4 v[8:11], v57, s[36:37] offset:16
	global_load_dwordx4 v[14:17], v57, s[36:37]
	global_load_dwordx4 v[18:21], v57, s[14:15] offset:16
	global_load_dwordx4 v[26:29], v57, s[14:15]
	v_fmac_f32_e32 v12, v13, v13
	v_lshlrev_b32_e32 v13, 16, v23
	v_add_f32_e32 v22, v22, v13
	v_lshlrev_b32_e32 v59, 16, v24
	v_and_b32_e32 v58, 0xffff0000, v23
	v_fmac_f32_e32 v12, v13, v13
	v_add_f32_e32 v13, v22, v58
	v_pk_mul_f32 v[22:23], v[58:59], v[58:59]
	s_mov_b32 s28, 0x3b000000
	v_add_f32_e32 v12, v22, v12
	v_add_f32_e32 v22, v13, v59
	v_add_f32_e32 v58, v23, v12
	v_lshlrev_b32_e32 v13, 16, v25
	v_and_b32_e32 v12, 0xffff0000, v24
	v_add_f32_e32 v24, v22, v12
	v_pk_mul_f32 v[22:23], v[12:13], v[12:13]
	s_nop 0
	v_add_f32_e32 v12, v22, v58
	v_add_f32_e32 v22, v24, v13
	v_add_f32_e32 v24, v23, v12
	v_and_b32_e32 v13, 0xffff0000, v25
	v_add_f32_e32 v25, v22, v13
	s_waitcnt vmcnt(0) lgkmcnt(0)
	v_lshlrev_b32_e32 v12, 16, v0
	v_pk_mul_f32 v[22:23], v[12:13], v[12:13]
	s_nop 0
	v_add_f32_e32 v13, v23, v24
	v_add_f32_e32 v23, v25, v12
	v_add_f32_e32 v24, v22, v13
	v_lshlrev_b32_e32 v13, 16, v1
	v_and_b32_e32 v12, 0xffff0000, v0
	v_add_f32_e32 v0, v23, v12
	v_pk_mul_f32 v[22:23], v[12:13], v[12:13]
	v_add_f32_e32 v0, v0, v13
	v_add_f32_e32 v12, v22, v24
	v_add_f32_e32 v22, v23, v12
	v_lshlrev_b32_e32 v13, 16, v2
	v_and_b32_e32 v12, 0xffff0000, v1
	v_add_f32_e32 v23, v0, v12
	v_pk_mul_f32 v[0:1], v[12:13], v[12:13]
	v_add_f32_e32 v12, v23, v13
	v_add_f32_e32 v0, v0, v22
	v_add_f32_e32 v22, v1, v0
	v_lshlrev_b32_e32 v1, 16, v3
	v_and_b32_e32 v0, 0xffff0000, v2
	v_add_f32_e32 v2, v12, v0
	v_pk_mul_f32 v[12:13], v[0:1], v[0:1]
	v_and_b32_e32 v3, 0xffff0000, v3
	v_add_f32_e32 v0, v12, v22
	v_add_f32_e32 v1, v2, v1
	v_add_f32_e32 v2, v13, v0
	v_mul_f32_e32 v0, v3, v3
	v_pk_add_f32 v[0:1], v[0:1], v[2:3]
	ds_bpermute_b32 v3, v37, v1
	ds_bpermute_b32 v2, v37, v0
	s_waitcnt lgkmcnt(0)
	v_pk_add_f32 v[0:1], v[0:1], v[2:3]
	ds_bpermute_b32 v3, v64, v1
	ds_bpermute_b32 v2, v64, v0
	s_waitcnt lgkmcnt(0)
	v_pk_add_f32 v[0:1], v[0:1], v[2:3]
	s_nop 0
	v_pk_mul_f32 v[24:25], v[0:1], s[28:29] op_sel_hi:[1,0]
	s_nop 0
	v_fma_f32 v0, -v25, v25, v24
	v_max_f32_e32 v0, 0, v0
	v_add_f32_e32 v0, 0x3727c5ac, v0
	v_mul_f32_e32 v1, 0x4b800000, v0
	v_cmp_gt_f32_e32 vcc, s27, v0
	s_nop 1
	v_cndmask_b32_e32 v0, v0, v1, vcc
	v_rsq_f32_e32 v0, v0
	s_nop 0
	v_mul_f32_e32 v1, 0x45800000, v0
	v_cndmask_b32_e32 v24, v0, v1, vcc
	v_lshlrev_b32_e32 v0, 16, v4
	v_sub_f32_e32 v0, v0, v25
	v_mul_f32_e32 v0, v0, v24
	v_fma_mixlo_f16 v0, v14, v0, v26
	ds_write_b16 v75, v0 offset:36864
	v_and_b32_e32 v0, 0xffff0000, v4
	v_sub_f32_e32 v0, v0, v25
	v_mul_f32_e32 v0, v0, v24
	v_fma_mixlo_f16 v0, v15, v0, v27
	ds_write_b16 v75, v0 offset:37152
	v_lshlrev_b32_e32 v0, 16, v5
	v_sub_f32_e32 v0, v0, v25
	v_mul_f32_e32 v0, v0, v24
	v_fma_mixlo_f16 v0, v16, v0, v28
	ds_write_b16 v75, v0 offset:37440
	v_and_b32_e32 v0, 0xffff0000, v5
	v_sub_f32_e32 v0, v0, v25
	v_mul_f32_e32 v0, v0, v24
	v_fma_mixlo_f16 v0, v17, v0, v29
	ds_write_b16 v75, v0 offset:37728
	v_lshlrev_b32_e32 v0, 16, v6
	v_sub_f32_e32 v0, v0, v25
	v_mul_f32_e32 v0, v0, v24
	v_fma_mixlo_f16 v0, v8, v0, v18
	ds_write_b16 v75, v0 offset:38016
	v_and_b32_e32 v0, 0xffff0000, v6
	v_sub_f32_e32 v0, v0, v25
	v_mul_f32_e32 v0, v0, v24
	v_fma_mixlo_f16 v0, v9, v0, v19
	ds_write_b16 v75, v0 offset:38304
	v_lshlrev_b32_e32 v0, 16, v7
	v_sub_f32_e32 v0, v0, v25
	v_mul_f32_e32 v0, v0, v24
	v_fma_mixlo_f16 v0, v10, v0, v20
	ds_write_b16 v75, v0 offset:38592
	v_and_b32_e32 v0, 0xffff0000, v7
	v_sub_f32_e32 v0, v0, v25
	v_mul_f32_e32 v0, v0, v24
	v_fma_mixlo_f16 v0, v11, v0, v21
	ds_write_b16 v75, v0 offset:38880
	global_load_dwordx4 v[0:3], v[30:31], off offset:16
	global_load_dwordx4 v[4:7], v57, s[14:15] offset:32
	global_load_dwordx4 v[8:11], v57, s[36:37] offset:32
	global_load_dwordx4 v[12:15], v57, s[36:37] offset:48
	global_load_dwordx4 v[16:19], v57, s[14:15] offset:48
	v_readlane_b32 vcc_lo, v255, 54
	v_readlane_b32 vcc_hi, v255, 55
	s_andn2_b64 vcc, exec, vcc
	s_waitcnt vmcnt(0) lgkmcnt(0)
; __device__ __forceinline__ float bfe(const v4u& v, int e) { const unsigned w = v[e >> 1]; return (e & 1) ? __uint_as_float(w & 0xffff0000u) : __uint_as_float(w << 16); }
; __device__ __forceinline__ void mix_sgu(const bf16* h, const float* lng, const float* lnb, const float* sgw, const float* sgb, bf16* ycat, char* lds, int wg, int nwg) {
;     ...
;           for (int j = 0; j < 4; ++j) { const int c0 = 32 * q + 8 * j; const v4u vv = *(const v4u*)(vr + 128 * grp + c0);
; #pragma unroll
;               for (int e = 0; e < 8; ++e) { const float y = (bfe(vv, e) - mu) * rstd * lng[128 * grp + c0 + e] + lnb[128 * grp + c0 + e]; *(_Float16*)(lds + 36864 + (c0 + e) * 288 + row * 2) = (_Float16)y; } } }
;         __syncthreads();
;         pg8::f32x4 acc[8];
; #pragma unroll
;         for (int nb = 0; nb < 8; ++nb) acc[nb] = (pg8::f32x4){0.f, 0.f, 0.f, 0.f};
;         const int nks = (16 * wid + 15) / 32 + 1;
	v_lshlrev_b32_e32 v20, 16, v0
	v_and_b32_e32 v0, 0xffff0000, v0
	v_sub_f32_e32 v20, v20, v25
	v_sub_f32_e32 v0, v0, v25
	v_mul_f32_e32 v20, v20, v24
	v_mul_f32_e32 v0, v0, v24
	v_fma_mixlo_f16 v4, v8, v20, v4
	v_fma_mixlo_f16 v0, v9, v0, v5
	ds_write_b16 v76, v4 offset:36864
	ds_write_b16 v75, v0 offset:39456
	v_lshlrev_b32_e32 v0, 16, v1
	v_sub_f32_e32 v0, v0, v25
	v_mul_f32_e32 v0, v0, v24
	v_fma_mixlo_f16 v0, v10, v0, v6
	ds_write_b16 v75, v0 offset:39744
	v_and_b32_e32 v0, 0xffff0000, v1
	v_sub_f32_e32 v0, v0, v25
	v_mul_f32_e32 v0, v0, v24
	v_fma_mixlo_f16 v0, v11, v0, v7
	ds_write_b16 v75, v0 offset:40032
	v_lshlrev_b32_e32 v0, 16, v2
	v_sub_f32_e32 v0, v0, v25
	v_mul_f32_e32 v0, v0, v24
	v_fma_mixlo_f16 v0, v12, v0, v16
	ds_write_b16 v75, v0 offset:40320
	v_and_b32_e32 v0, 0xffff0000, v2
	v_sub_f32_e32 v0, v0, v25
	v_mul_f32_e32 v0, v0, v24
	v_fma_mixlo_f16 v0, v13, v0, v17
	ds_write_b16 v75, v0 offset:40608
	v_lshlrev_b32_e32 v0, 16, v3
	v_sub_f32_e32 v0, v0, v25
	v_mul_f32_e32 v0, v0, v24
	v_fma_mixlo_f16 v0, v14, v0, v18
	ds_write_b16 v75, v0 offset:40896
	v_and_b32_e32 v0, 0xffff0000, v3
	v_sub_f32_e32 v0, v0, v25
	v_mul_f32_e32 v0, v0, v24
	v_fma_mixlo_f16 v0, v15, v0, v19
	ds_write_b16 v75, v0 offset:41184
	global_load_dwordx4 v[0:3], v[30:31], off offset:32
	global_load_dwordx4 v[4:7], v57, s[14:15] offset:64
	global_load_dwordx4 v[8:11], v57, s[36:37] offset:64
	global_load_dwordx4 v[12:15], v57, s[36:37] offset:80
	global_load_dwordx4 v[16:19], v57, s[14:15] offset:80
	s_waitcnt vmcnt(0) lgkmcnt(0)
	v_lshlrev_b32_e32 v20, 16, v0
	v_and_b32_e32 v0, 0xffff0000, v0
	v_sub_f32_e32 v20, v20, v25
	v_sub_f32_e32 v0, v0, v25
	v_mul_f32_e32 v20, v20, v24
	v_mul_f32_e32 v0, v0, v24
	v_fma_mixlo_f16 v4, v8, v20, v4
	v_fma_mixlo_f16 v0, v9, v0, v5
	ds_write_b16 v76, v4 offset:39168
	ds_write_b16 v75, v0 offset:41760
	v_lshlrev_b32_e32 v0, 16, v1
	v_sub_f32_e32 v0, v0, v25
	v_mul_f32_e32 v0, v0, v24
	v_fma_mixlo_f16 v0, v10, v0, v6
	ds_write_b16 v75, v0 offset:42048
	v_and_b32_e32 v0, 0xffff0000, v1
	v_sub_f32_e32 v0, v0, v25
	v_mul_f32_e32 v0, v0, v24
	v_fma_mixlo_f16 v0, v11, v0, v7
	ds_write_b16 v75, v0 offset:42336
	v_lshlrev_b32_e32 v0, 16, v2
	v_sub_f32_e32 v0, v0, v25
	v_mul_f32_e32 v0, v0, v24
	v_fma_mixlo_f16 v0, v12, v0, v16
	ds_write_b16 v75, v0 offset:42624
	v_and_b32_e32 v0, 0xffff0000, v2
	v_sub_f32_e32 v0, v0, v25
	v_mul_f32_e32 v0, v0, v24
	v_fma_mixlo_f16 v0, v13, v0, v17
	ds_write_b16 v75, v0 offset:42912
	v_lshlrev_b32_e32 v0, 16, v3
	v_sub_f32_e32 v0, v0, v25
	v_mul_f32_e32 v0, v0, v24
	v_fma_mixlo_f16 v0, v14, v0, v18
	ds_write_b16 v75, v0 offset:43200
	v_and_b32_e32 v0, 0xffff0000, v3
	v_sub_f32_e32 v0, v0, v25
	v_mul_f32_e32 v0, v0, v24
	v_fma_mixlo_f16 v0, v15, v0, v19
	ds_write_b16 v75, v0 offset:43488
	global_load_dwordx4 v[4:7], v[30:31], off offset:48
	global_load_dwordx4 v[8:11], v57, s[14:15] offset:96
	global_load_dwordx4 v[12:15], v57, s[36:37] offset:96
	global_load_dwordx4 v[16:19], v57, s[36:37] offset:112
	global_load_dwordx4 v[20:23], v57, s[14:15] offset:112
	v_mov_b32_e32 v3, 0
	v_mov_b32_e32 v2, v3
	v_mov_b32_e32 v1, v3
	v_mov_b32_e32 v27, v3
	v_mov_b32_e32 v26, v3
	v_mov_b32_e32 v31, v3
	v_mov_b32_e32 v30, v3
	v_mov_b32_e32 v29, v3
	v_mov_b32_e32 v28, v3
	s_waitcnt vmcnt(0) lgkmcnt(0)
	v_lshlrev_b32_e32 v0, 16, v4
	v_sub_f32_e32 v0, v0, v25
	v_mul_f32_e32 v0, v0, v24
	v_fma_mixlo_f16 v0, v12, v0, v8
	ds_write_b16 v76, v0 offset:41472
	v_and_b32_e32 v0, 0xffff0000, v4
	v_sub_f32_e32 v0, v0, v25
	v_mul_f32_e32 v0, v0, v24
	v_fma_mixlo_f16 v0, v13, v0, v9
	ds_write_b16 v75, v0 offset:44064
	v_lshlrev_b32_e32 v0, 16, v5
	v_sub_f32_e32 v0, v0, v25
	v_mul_f32_e32 v0, v0, v24
	v_fma_mixlo_f16 v0, v14, v0, v10
	ds_write_b16 v75, v0 offset:44352
	v_and_b32_e32 v0, 0xffff0000, v5
	v_sub_f32_e32 v0, v0, v25
	v_mul_f32_e32 v0, v0, v24
	v_fma_mixlo_f16 v0, v15, v0, v11
	ds_write_b16 v75, v0 offset:44640
	v_lshlrev_b32_e32 v0, 16, v6
	v_sub_f32_e32 v0, v0, v25
	v_mul_f32_e32 v0, v0, v24
	v_fma_mixlo_f16 v0, v16, v0, v20
	ds_write_b16 v75, v0 offset:44928
	v_and_b32_e32 v0, 0xffff0000, v6
	v_sub_f32_e32 v0, v0, v25
	v_mul_f32_e32 v0, v0, v24
	v_fma_mixlo_f16 v0, v17, v0, v21
	ds_write_b16 v75, v0 offset:45216
	v_lshlrev_b32_e32 v0, 16, v7
	v_sub_f32_e32 v0, v0, v25
	v_mul_f32_e32 v0, v0, v24
	v_fma_mixlo_f16 v0, v18, v0, v22
	ds_write_b16 v75, v0 offset:45504
	v_and_b32_e32 v0, 0xffff0000, v7
	v_sub_f32_e32 v0, v0, v25
	v_mul_f32_e32 v0, v0, v24
	v_fma_mixlo_f16 v0, v19, v0, v23
	ds_write_b16 v75, v0 offset:45792
	v_mov_b32_e32 v0, v3
	v_mov_b32_e32 v7, v3
	v_mov_b32_e32 v6, v3
	v_mov_b32_e32 v5, v3
	v_mov_b32_e32 v4, v3
	v_mov_b32_e32 v11, v3
	v_mov_b32_e32 v10, v3
	v_mov_b32_e32 v9, v3
	v_mov_b32_e32 v8, v3
	v_mov_b32_e32 v15, v3
	v_mov_b32_e32 v14, v3
	v_mov_b32_e32 v13, v3
	v_mov_b32_e32 v12, v3
	v_mov_b32_e32 v19, v3
	v_mov_b32_e32 v18, v3
	v_mov_b32_e32 v17, v3
	v_mov_b32_e32 v16, v3
	v_mov_b32_e32 v23, v3
	v_mov_b32_e32 v22, v3
	v_mov_b32_e32 v21, v3
	v_mov_b32_e32 v20, v3
	v_mov_b32_e32 v25, v3
	v_mov_b32_e32 v24, v3
	s_waitcnt lgkmcnt(0)
	s_barrier
	s_cbranch_vccnz .LBB0_675
	v_mov_b32_e32 v0, 0
	v_mov_b32_e32 v57, v65
	v_mov_b32_e32 v58, v66
	v_readlane_b32 s27, v255, 60
	v_mov_b32_e32 v1, v0
	v_mov_b32_e32 v2, v0
	v_mov_b32_e32 v3, v0
	v_mov_b32_e32 v28, v0
	v_mov_b32_e32 v29, v0
	v_mov_b32_e32 v30, v0
	v_mov_b32_e32 v31, v0
	v_mov_b32_e32 v24, v0
	v_mov_b32_e32 v25, v0
	v_mov_b32_e32 v26, v0
	v_mov_b32_e32 v27, v0
	v_mov_b32_e32 v20, v0
	v_mov_b32_e32 v21, v0
	v_mov_b32_e32 v22, v0
	v_mov_b32_e32 v23, v0
	v_mov_b32_e32 v16, v0
	v_mov_b32_e32 v17, v0
	v_mov_b32_e32 v18, v0
	v_mov_b32_e32 v19, v0
	v_mov_b32_e32 v12, v0
	v_mov_b32_e32 v13, v0
	v_mov_b32_e32 v14, v0
	v_mov_b32_e32 v15, v0
	v_mov_b32_e32 v8, v0
	v_mov_b32_e32 v9, v0
	v_mov_b32_e32 v10, v0
	v_mov_b32_e32 v11, v0
	v_mov_b32_e32 v4, v0
	v_mov_b32_e32 v5, v0
	v_mov_b32_e32 v6, v0
	v_mov_b32_e32 v7, v0

; __device__ __forceinline__ unsigned pk2(float lo, float hi) { unsigned r; asm("v_cvt_pk_bf16_f32 %0, %1, %2" : "=v"(r) : "v"(lo), "v"(hi)); return r; }
; __device__ __forceinline__ float bfe(const v4u& v, int e) { const unsigned w = v[e >> 1]; return (e & 1) ? __uint_as_float(w & 0xffff0000u) : __uint_as_float(w << 16); }
; __device__ __forceinline__ void mix_conv(const bf16* h, const float* cw, bf16* ycat, int gtid, int gstride) {
;     for (int it = gtid; it < MT * 64; it += gstride) {
;         const int m = it >> 6, c = (it & 63) * 8, t = m & (SEQ - 1);
;         const bf16* hr = h + (size_t)m * NH;
;         const v4u bb = *(const v4u*)(hr + C_AB + c), ga = *(const v4u*)(hr + C_GA + c);
;         float acc[8];
; #pragma unroll
;         for (int e = 0; e < 8; ++e) acc[e] = 0.f;
; #pragma unroll
;         for (int j = 0; j < 3; ++j) { const int dt = 2 - j;
;             if (t - dt >= 0) { const bf16* hp = hr - (size_t)dt * NH; const v4u cc = *(const v4u*)(hp + C_AC + c), xx = *(const v4u*)(hp + C_AX + c);
; #pragma unroll
;                 for (int e = 0; e < 8; ++e) acc[e] += cw[j * GW + c + e] * (bfe(cc, e) * bfe(xx, e)); } }
;         v4u o;
; #pragma unroll
;         for (int e = 0; e < 4; ++e) o[e] = pk2(bfe(bb, 2 * e) * acc[2 * e] * bfe(ga, 2 * e), bfe(bb, 2 * e + 1) * acc[2 * e + 1] * bfe(ga, 2 * e + 1));
;         *(v4u*)(ycat + (size_t)m * DM + Y_A + c) = o;
.LBB0_680:
	s_cmpk_lg_i32 s86, 0x100
	s_cbranch_scc1 .Lconv_orig
	v_readlane_b32 s0, v254, 38
	s_mov_b64 s[4:5], s[20:21]
	v_readfirstlane_b32 s8, v252
	s_add_u32 s2, s4, 0xa800000
	s_addc_u32 s3, s5, 0
	s_add_u32 s4, s4, 0x12800000
	s_addc_u32 s5, s5, 0
	v_readlane_b32 s6, v255, 45
	v_readlane_b32 s42, v253, 8
	v_readlane_b32 s43, v253, 9
	s_nop 0
	s_mul_i32 s28, s6, 0x600
	s_lshl_b64 s[6:7], s[28:29], 2
	s_add_u32 s6, s42, s6
	s_addc_u32 s7, s43, s7
	s_lshr_b32 s8, s8, 6
	s_lshr_b32 s9, s0, 6
	s_add_i32 s8, s8, s9
	s_mul_i32 s9, s8, 0x3c00
	s_lshl_b32 s14, s8, 12
	v_and_b32_e32 v1, 63, v252
	v_lshlrev_b32_e32 v2, 4, v1
	v_lshlrev_b32_e32 v3, 5, v1
	v_add_u32_e32 v4, 0x1000, v3
	v_add_u32_e32 v160, s9, v2
	v_add_u32_e32 v182, s14, v2
	v_add_u32_e32 v161, 0x2c00, v160
	v_subrev_u32_e32 v162, 0x3c00, v160
	v_subrev_u32_e32 v163, 0x7800, v160
	v_max_i32_e32 v162, 0, v162
	v_max_i32_e32 v163, 0, v163
	v_add_u32_e32 v164, 0x1e00000, v160
	v_add_u32_e32 v183, 0x800000, v182
	v_add_u32_e32 v165, 0x2c00, v164
	v_subrev_u32_e32 v166, 0x3c00, v164
	v_subrev_u32_e32 v167, 0x7800, v164
	v_max_i32_e32 v166, 0, v166
	v_max_i32_e32 v167, 0, v167
	v_add_u32_e32 v174, 0x1e00000, v164
	v_add_u32_e32 v184, 0x800000, v183
	v_add_u32_e32 v175, 0x2c00, v174
	v_subrev_u32_e32 v176, 0x3c00, v174
	v_subrev_u32_e32 v177, 0x7800, v174
	v_max_i32_e32 v176, 0, v176
	v_max_i32_e32 v177, 0, v177
	v_add_u32_e32 v178, 0x1e00000, v174
	v_add_u32_e32 v185, 0x800000, v184
	v_add_u32_e32 v179, 0x2c00, v178
	v_subrev_u32_e32 v180, 0x3c00, v178
	v_subrev_u32_e32 v181, 0x7800, v178
	v_max_i32_e32 v180, 0, v180
	v_max_i32_e32 v181, 0, v181
	global_load_dwordx4 v[8:11], v3, s[6:7]
	global_load_dwordx4 v[12:15], v3, s[6:7] offset:16
	global_load_dwordx4 v[16:19], v3, s[6:7] offset:2048
	global_load_dwordx4 v[20:23], v3, s[6:7] offset:2064
	global_load_dwordx4 v[24:27], v4, s[6:7]
	global_load_dwordx4 v[28:31], v4, s[6:7] offset:16
	global_load_dwordx4 v[32:35], v160, s[2:3]
	global_load_dwordx4 v[36:39], v161, s[2:3]
	global_load_dwordx4 v[40:43], v163, s[2:3] offset:1024
	global_load_dwordx4 v[44:47], v163, s[2:3] offset:2048
	global_load_dwordx4 v[48:51], v162, s[2:3] offset:1024
	global_load_dwordx4 v[52:55], v162, s[2:3] offset:2048
	global_load_dwordx4 v[56:59], v160, s[2:3] offset:1024
	global_load_dwordx4 v[60:63], v160, s[2:3] offset:2048
	global_load_dwordx4 v[64:67], v164, s[2:3]
	global_load_dwordx4 v[68:71], v165, s[2:3]
	global_load_dwordx4 v[72:75], v167, s[2:3] offset:1024
	global_load_dwordx4 v[76:79], v167, s[2:3] offset:2048
	global_load_dwordx4 v[80:83], v166, s[2:3] offset:1024
	global_load_dwordx4 v[84:87], v166, s[2:3] offset:2048
	global_load_dwordx4 v[88:91], v164, s[2:3] offset:1024
	global_load_dwordx4 v[92:95], v164, s[2:3] offset:2048
	global_load_dwordx4 v[96:99], v174, s[2:3]
	global_load_dwordx4 v[100:103], v175, s[2:3]
	global_load_dwordx4 v[104:107], v177, s[2:3] offset:1024
	global_load_dwordx4 v[108:111], v177, s[2:3] offset:2048
	global_load_dwordx4 v[112:115], v176, s[2:3] offset:1024
	global_load_dwordx4 v[116:119], v176, s[2:3] offset:2048
	global_load_dwordx4 v[120:123], v174, s[2:3] offset:1024
	global_load_dwordx4 v[124:127], v174, s[2:3] offset:2048
	global_load_dwordx4 v[128:131], v178, s[2:3]
	global_load_dwordx4 v[132:135], v179, s[2:3]
	global_load_dwordx4 v[136:139], v181, s[2:3] offset:1024
	global_load_dwordx4 v[140:143], v181, s[2:3] offset:2048
	global_load_dwordx4 v[144:147], v180, s[2:3] offset:1024
	global_load_dwordx4 v[148:151], v180, s[2:3] offset:2048
	global_load_dwordx4 v[152:155], v178, s[2:3] offset:1024
	global_load_dwordx4 v[156:159], v178, s[2:3] offset:2048
	s_waitcnt vmcnt(24)
	s_cmp_gt_u32 s8, 1
	s_cbranch_scc1 .Lconv_ok0
	v_mov_b32_e32 v40, 0
	v_mov_b32_e32 v41, 0
	v_mov_b32_e32 v42, 0
	v_mov_b32_e32 v43, 0
	v_mov_b32_e32 v44, 0
	v_mov_b32_e32 v45, 0
	v_mov_b32_e32 v46, 0
	v_mov_b32_e32 v47, 0
	s_cmp_eq_u32 s8, 0
	s_cbranch_scc0 .Lconv_ok0
	v_mov_b32_e32 v48, 0
	v_mov_b32_e32 v49, 0
	v_mov_b32_e32 v50, 0
	v_mov_b32_e32 v51, 0
	v_mov_b32_e32 v52, 0
	v_mov_b32_e32 v53, 0
	v_mov_b32_e32 v54, 0
	v_mov_b32_e32 v55, 0
.Lconv_ok0:
	v_lshlrev_b32_e32 v186, 16, v40
	v_and_b32_e32 v187, 0xffff0000, v40
	v_lshlrev_b32_e32 v194, 16, v44
	v_and_b32_e32 v195, 0xffff0000, v44
	v_lshlrev_b32_e32 v188, 16, v41
	v_and_b32_e32 v189, 0xffff0000, v41
	v_lshlrev_b32_e32 v196, 16, v45
	v_and_b32_e32 v197, 0xffff0000, v45
	v_lshlrev_b32_e32 v190, 16, v42
	v_and_b32_e32 v191, 0xffff0000, v42
	v_lshlrev_b32_e32 v198, 16, v46
	v_and_b32_e32 v199, 0xffff0000, v46
	v_lshlrev_b32_e32 v192, 16, v43
	v_and_b32_e32 v193, 0xffff0000, v43
	v_lshlrev_b32_e32 v200, 16, v47
	v_and_b32_e32 v201, 0xffff0000, v47
	v_pk_mul_f32 v[186:187], v[186:187], v[194:195]
	v_pk_mul_f32 v[188:189], v[188:189], v[196:197]
	v_pk_mul_f32 v[190:191], v[190:191], v[198:199]
	v_pk_mul_f32 v[192:193], v[192:193], v[200:201]
	v_pk_mul_f32 v[202:203], v[8:9], v[186:187]
	v_pk_mul_f32 v[204:205], v[10:11], v[188:189]
	v_pk_mul_f32 v[206:207], v[12:13], v[190:191]
	v_pk_mul_f32 v[208:209], v[14:15], v[192:193]
	v_lshlrev_b32_e32 v186, 16, v48
	v_and_b32_e32 v187, 0xffff0000, v48
	v_lshlrev_b32_e32 v194, 16, v52
	v_and_b32_e32 v195, 0xffff0000, v52
	v_lshlrev_b32_e32 v188, 16, v49
	v_and_b32_e32 v189, 0xffff0000, v49
	v_lshlrev_b32_e32 v196, 16, v53
	v_and_b32_e32 v197, 0xffff0000, v53
	v_lshlrev_b32_e32 v190, 16, v50
	v_and_b32_e32 v191, 0xffff0000, v50
	v_lshlrev_b32_e32 v198, 16, v54
	v_and_b32_e32 v199, 0xffff0000, v54
	v_lshlrev_b32_e32 v192, 16, v51
	v_and_b32_e32 v193, 0xffff0000, v51
	v_lshlrev_b32_e32 v200, 16, v55
	v_and_b32_e32 v201, 0xffff0000, v55
; __device__ __forceinline__ unsigned pk2(float lo, float hi) { unsigned r; asm("v_cvt_pk_bf16_f32 %0, %1, %2" : "=v"(r) : "v"(lo), "v"(hi)); return r; }
; __device__ __forceinline__ float bfe(const v4u& v, int e) { const unsigned w = v[e >> 1]; return (e & 1) ? __uint_as_float(w & 0xffff0000u) : __uint_as_float(w << 16); }
; __device__ __forceinline__ void mix_conv(const bf16* h, const float* cw, bf16* ycat, int gtid, int gstride) {
;     for (int it = gtid; it < MT * 64; it += gstride) {
;         const int m = it >> 6, c = (it & 63) * 8, t = m & (SEQ - 1);
;         const bf16* hr = h + (size_t)m * NH;
;         const v4u bb = *(const v4u*)(hr + C_AB + c), ga = *(const v4u*)(hr + C_GA + c);
;         float acc[8];
; #pragma unroll
;         for (int e = 0; e < 8; ++e) acc[e] = 0.f;
; #pragma unroll
;         for (int j = 0; j < 3; ++j) { const int dt = 2 - j;
;             if (t - dt >= 0) { const bf16* hp = hr - (size_t)dt * NH; const v4u cc = *(const v4u*)(hp + C_AC + c), xx = *(const v4u*)(hp + C_AX + c);
; #pragma unroll
;                 for (int e = 0; e < 8; ++e) acc[e] += cw[j * GW + c + e] * (bfe(cc, e) * bfe(xx, e)); } }
;         v4u o;
; #pragma unroll
;         for (int e = 0; e < 4; ++e) o[e] = pk2(bfe(bb, 2 * e) * acc[2 * e] * bfe(ga, 2 * e), bfe(bb, 2 * e + 1) * acc[2 * e + 1] * bfe(ga, 2 * e + 1));
;         *(v4u*)(ycat + (size_t)m * DM + Y_A + c) = o;
	v_pk_mul_f32 v[186:187], v[186:187], v[194:195]
	v_pk_mul_f32 v[188:189], v[188:189], v[196:197]
	v_pk_mul_f32 v[190:191], v[190:191], v[198:199]
	v_pk_mul_f32 v[192:193], v[192:193], v[200:201]
	v_pk_fma_f32 v[202:203], v[16:17], v[186:187], v[202:203]
	v_pk_fma_f32 v[204:205], v[18:19], v[188:189], v[204:205]
	v_pk_fma_f32 v[206:207], v[20:21], v[190:191], v[206:207]
	v_pk_fma_f32 v[208:209], v[22:23], v[192:193], v[208:209]
	v_lshlrev_b32_e32 v186, 16, v56
	v_and_b32_e32 v187, 0xffff0000, v56
	v_lshlrev_b32_e32 v194, 16, v60
	v_and_b32_e32 v195, 0xffff0000, v60
	v_lshlrev_b32_e32 v188, 16, v57
	v_and_b32_e32 v189, 0xffff0000, v57
	v_lshlrev_b32_e32 v196, 16, v61
	v_and_b32_e32 v197, 0xffff0000, v61
	v_lshlrev_b32_e32 v190, 16, v58
	v_and_b32_e32 v191, 0xffff0000, v58
	v_lshlrev_b32_e32 v198, 16, v62
	v_and_b32_e32 v199, 0xffff0000, v62
	v_lshlrev_b32_e32 v192, 16, v59
	v_and_b32_e32 v193, 0xffff0000, v59
	v_lshlrev_b32_e32 v200, 16, v63
	v_and_b32_e32 v201, 0xffff0000, v63
	v_pk_mul_f32 v[186:187], v[186:187], v[194:195]
	v_pk_mul_f32 v[188:189], v[188:189], v[196:197]
	v_pk_mul_f32 v[190:191], v[190:191], v[198:199]
	v_pk_mul_f32 v[192:193], v[192:193], v[200:201]
	v_pk_fma_f32 v[202:203], v[24:25], v[186:187], v[202:203]
	v_pk_fma_f32 v[204:205], v[26:27], v[188:189], v[204:205]
	v_pk_fma_f32 v[206:207], v[28:29], v[190:191], v[206:207]
	v_pk_fma_f32 v[208:209], v[30:31], v[192:193], v[208:209]
	v_lshlrev_b32_e32 v194, 16, v32
	v_and_b32_e32 v195, 0xffff0000, v32
	v_lshlrev_b32_e32 v186, 16, v36
	v_and_b32_e32 v187, 0xffff0000, v36
	v_lshlrev_b32_e32 v196, 16, v33
	v_and_b32_e32 v197, 0xffff0000, v33
	v_lshlrev_b32_e32 v188, 16, v37
	v_and_b32_e32 v189, 0xffff0000, v37
	v_lshlrev_b32_e32 v198, 16, v34
	v_and_b32_e32 v199, 0xffff0000, v34
	v_lshlrev_b32_e32 v190, 16, v38
	v_and_b32_e32 v191, 0xffff0000, v38
	v_lshlrev_b32_e32 v200, 16, v35
	v_and_b32_e32 v201, 0xffff0000, v35
	v_lshlrev_b32_e32 v192, 16, v39
	v_and_b32_e32 v193, 0xffff0000, v39
	v_pk_mul_f32 v[202:203], v[202:203], v[194:195]
	v_pk_mul_f32 v[204:205], v[204:205], v[196:197]
	v_pk_mul_f32 v[206:207], v[206:207], v[198:199]
	v_pk_mul_f32 v[208:209], v[208:209], v[200:201]
	v_pk_mul_f32 v[202:203], v[202:203], v[186:187]
	v_pk_mul_f32 v[204:205], v[204:205], v[188:189]
	v_pk_mul_f32 v[206:207], v[206:207], v[190:191]
	v_pk_mul_f32 v[208:209], v[208:209], v[192:193]
	v_cvt_pk_bf16_f32 v210, v202, v203
	v_cvt_pk_bf16_f32 v211, v204, v205
	v_cvt_pk_bf16_f32 v212, v206, v207
	v_cvt_pk_bf16_f32 v213, v208, v209
	global_store_dwordx4 v182, v[210:213], s[4:5]
	s_waitcnt vmcnt(17)
	v_lshlrev_b32_e32 v186, 16, v72
	v_and_b32_e32 v187, 0xffff0000, v72
	v_lshlrev_b32_e32 v194, 16, v76
	v_and_b32_e32 v195, 0xffff0000, v76
	v_lshlrev_b32_e32 v188, 16, v73
	v_and_b32_e32 v189, 0xffff0000, v73
	v_lshlrev_b32_e32 v196, 16, v77
	v_and_b32_e32 v197, 0xffff0000, v77
	v_lshlrev_b32_e32 v190, 16, v74
	v_and_b32_e32 v191, 0xffff0000, v74
	v_lshlrev_b32_e32 v198, 16, v78
	v_and_b32_e32 v199, 0xffff0000, v78
	v_lshlrev_b32_e32 v192, 16, v75
	v_and_b32_e32 v193, 0xffff0000, v75
	v_lshlrev_b32_e32 v200, 16, v79
	v_and_b32_e32 v201, 0xffff0000, v79
	v_pk_mul_f32 v[186:187], v[186:187], v[194:195]
	v_pk_mul_f32 v[188:189], v[188:189], v[196:197]
	v_pk_mul_f32 v[190:191], v[190:191], v[198:199]
	v_pk_mul_f32 v[192:193], v[192:193], v[200:201]
	v_pk_mul_f32 v[202:203], v[8:9], v[186:187]
	v_pk_mul_f32 v[204:205], v[10:11], v[188:189]
	v_pk_mul_f32 v[206:207], v[12:13], v[190:191]
	v_pk_mul_f32 v[208:209], v[14:15], v[192:193]
	v_lshlrev_b32_e32 v186, 16, v80
	v_and_b32_e32 v187, 0xffff0000, v80
	v_lshlrev_b32_e32 v194, 16, v84
	v_and_b32_e32 v195, 0xffff0000, v84
	v_lshlrev_b32_e32 v188, 16, v81
	v_and_b32_e32 v189, 0xffff0000, v81
	v_lshlrev_b32_e32 v196, 16, v85
	v_and_b32_e32 v197, 0xffff0000, v85
	v_lshlrev_b32_e32 v190, 16, v82
	v_and_b32_e32 v191, 0xffff0000, v82
	v_lshlrev_b32_e32 v198, 16, v86
	v_and_b32_e32 v199, 0xffff0000, v86
	v_lshlrev_b32_e32 v192, 16, v83
	v_and_b32_e32 v193, 0xffff0000, v83
	v_lshlrev_b32_e32 v200, 16, v87
	v_and_b32_e32 v201, 0xffff0000, v87
	v_pk_mul_f32 v[186:187], v[186:187], v[194:195]
	v_pk_mul_f32 v[188:189], v[188:189], v[196:197]
	v_pk_mul_f32 v[190:191], v[190:191], v[198:199]
	v_pk_mul_f32 v[192:193], v[192:193], v[200:201]
	v_pk_fma_f32 v[202:203], v[16:17], v[186:187], v[202:203]
	v_pk_fma_f32 v[204:205], v[18:19], v[188:189], v[204:205]
	v_pk_fma_f32 v[206:207], v[20:21], v[190:191], v[206:207]
	v_pk_fma_f32 v[208:209], v[22:23], v[192:193], v[208:209]
	v_lshlrev_b32_e32 v186, 16, v88
	v_and_b32_e32 v187, 0xffff0000, v88
	v_lshlrev_b32_e32 v194, 16, v92
	v_and_b32_e32 v195, 0xffff0000, v92
	v_lshlrev_b32_e32 v188, 16, v89
	v_and_b32_e32 v189, 0xffff0000, v89
	v_lshlrev_b32_e32 v196, 16, v93
	v_and_b32_e32 v197, 0xffff0000, v93
	v_lshlrev_b32_e32 v190, 16, v90
	v_and_b32_e32 v191, 0xffff0000, v90
	v_lshlrev_b32_e32 v198, 16, v94
	v_and_b32_e32 v199, 0xffff0000, v94
	v_lshlrev_b32_e32 v192, 16, v91
	v_and_b32_e32 v193, 0xffff0000, v91
	v_lshlrev_b32_e32 v200, 16, v95
	v_and_b32_e32 v201, 0xffff0000, v95
	v_pk_mul_f32 v[186:187], v[186:187], v[194:195]
	v_pk_mul_f32 v[188:189], v[188:189], v[196:197]
	v_pk_mul_f32 v[190:191], v[190:191], v[198:199]
	v_pk_mul_f32 v[192:193], v[192:193], v[200:201]
	v_pk_fma_f32 v[202:203], v[24:25], v[186:187], v[202:203]
	v_pk_fma_f32 v[204:205], v[26:27], v[188:189], v[204:205]
	v_pk_fma_f32 v[206:207], v[28:29], v[190:191], v[206:207]
	v_pk_fma_f32 v[208:209], v[30:31], v[192:193], v[208:209]
	v_lshlrev_b32_e32 v194, 16, v64
	v_and_b32_e32 v195, 0xffff0000, v64
	v_lshlrev_b32_e32 v186, 16, v68
	v_and_b32_e32 v187, 0xffff0000, v68
	v_lshlrev_b32_e32 v196, 16, v65
	v_and_b32_e32 v197, 0xffff0000, v65
	v_lshlrev_b32_e32 v188, 16, v69
	v_and_b32_e32 v189, 0xffff0000, v69
	v_lshlrev_b32_e32 v198, 16, v66
	v_and_b32_e32 v199, 0xffff0000, v66
	v_lshlrev_b32_e32 v190, 16, v70
	v_and_b32_e32 v191, 0xffff0000, v70
	v_lshlrev_b32_e32 v200, 16, v67
	v_and_b32_e32 v201, 0xffff0000, v67
	v_lshlrev_b32_e32 v192, 16, v71
	v_and_b32_e32 v193, 0xffff0000, v71
	v_pk_mul_f32 v[202:203], v[202:203], v[194:195]
	v_pk_mul_f32 v[204:205], v[204:205], v[196:197]
	v_pk_mul_f32 v[206:207], v[206:207], v[198:199]
	v_pk_mul_f32 v[208:209], v[208:209], v[200:201]
	v_pk_mul_f32 v[202:203], v[202:203], v[186:187]
	v_pk_mul_f32 v[204:205], v[204:205], v[188:189]
	v_pk_mul_f32 v[206:207], v[206:207], v[190:191]
	v_pk_mul_f32 v[208:209], v[208:209], v[192:193]
	v_cvt_pk_bf16_f32 v210, v202, v203
	v_cvt_pk_bf16_f32 v211, v204, v205
	v_cvt_pk_bf16_f32 v212, v206, v207
	v_cvt_pk_bf16_f32 v213, v208, v209
	global_store_dwordx4 v183, v[210:213], s[4:5]
	s_waitcnt vmcnt(10)
	s_cmp_gt_u32 s8, 1
	s_cbranch_scc1 .Lconv_ok2
; __device__ __forceinline__ unsigned pk2(float lo, float hi) { unsigned r; asm("v_cvt_pk_bf16_f32 %0, %1, %2" : "=v"(r) : "v"(lo), "v"(hi)); return r; }
; __device__ __forceinline__ float bfe(const v4u& v, int e) { const unsigned w = v[e >> 1]; return (e & 1) ? __uint_as_float(w & 0xffff0000u) : __uint_as_float(w << 16); }
; __device__ __forceinline__ void mix_conv(const bf16* h, const float* cw, bf16* ycat, int gtid, int gstride) {
;     for (int it = gtid; it < MT * 64; it += gstride) {
;         const int m = it >> 6, c = (it & 63) * 8, t = m & (SEQ - 1);
;         const bf16* hr = h + (size_t)m * NH;
;         const v4u bb = *(const v4u*)(hr + C_AB + c), ga = *(const v4u*)(hr + C_GA + c);
;         float acc[8];
; #pragma unroll
;         for (int e = 0; e < 8; ++e) acc[e] = 0.f;
; #pragma unroll
;         for (int j = 0; j < 3; ++j) { const int dt = 2 - j;
;             if (t - dt >= 0) { const bf16* hp = hr - (size_t)dt * NH; const v4u cc = *(const v4u*)(hp + C_AC + c), xx = *(const v4u*)(hp + C_AX + c);
; #pragma unroll
;                 for (int e = 0; e < 8; ++e) acc[e] += cw[j * GW + c + e] * (bfe(cc, e) * bfe(xx, e)); } }
;         v4u o;
; #pragma unroll
;         for (int e = 0; e < 4; ++e) o[e] = pk2(bfe(bb, 2 * e) * acc[2 * e] * bfe(ga, 2 * e), bfe(bb, 2 * e + 1) * acc[2 * e + 1] * bfe(ga, 2 * e + 1));
;         *(v4u*)(ycat + (size_t)m * DM + Y_A + c) = o;
	v_mov_b32_e32 v104, 0
	v_mov_b32_e32 v105, 0
	v_mov_b32_e32 v106, 0
	v_mov_b32_e32 v107, 0
	v_mov_b32_e32 v108, 0
	v_mov_b32_e32 v109, 0
	v_mov_b32_e32 v110, 0
	v_mov_b32_e32 v111, 0
	s_cmp_eq_u32 s8, 0
	s_cbranch_scc0 .Lconv_ok2
	v_mov_b32_e32 v112, 0
	v_mov_b32_e32 v113, 0
	v_mov_b32_e32 v114, 0
	v_mov_b32_e32 v115, 0
	v_mov_b32_e32 v116, 0
	v_mov_b32_e32 v117, 0
	v_mov_b32_e32 v118, 0
	v_mov_b32_e32 v119, 0
.Lconv_ok2:
	v_lshlrev_b32_e32 v186, 16, v104
	v_and_b32_e32 v187, 0xffff0000, v104
	v_lshlrev_b32_e32 v194, 16, v108
	v_and_b32_e32 v195, 0xffff0000, v108
	v_lshlrev_b32_e32 v188, 16, v105
	v_and_b32_e32 v189, 0xffff0000, v105
	v_lshlrev_b32_e32 v196, 16, v109
	v_and_b32_e32 v197, 0xffff0000, v109
	v_lshlrev_b32_e32 v190, 16, v106
	v_and_b32_e32 v191, 0xffff0000, v106
	v_lshlrev_b32_e32 v198, 16, v110
	v_and_b32_e32 v199, 0xffff0000, v110
	v_lshlrev_b32_e32 v192, 16, v107
	v_and_b32_e32 v193, 0xffff0000, v107
	v_lshlrev_b32_e32 v200, 16, v111
	v_and_b32_e32 v201, 0xffff0000, v111
	v_pk_mul_f32 v[186:187], v[186:187], v[194:195]
	v_pk_mul_f32 v[188:189], v[188:189], v[196:197]
	v_pk_mul_f32 v[190:191], v[190:191], v[198:199]
	v_pk_mul_f32 v[192:193], v[192:193], v[200:201]
	v_pk_mul_f32 v[202:203], v[8:9], v[186:187]
	v_pk_mul_f32 v[204:205], v[10:11], v[188:189]
	v_pk_mul_f32 v[206:207], v[12:13], v[190:191]
	v_pk_mul_f32 v[208:209], v[14:15], v[192:193]
	v_lshlrev_b32_e32 v186, 16, v112
	v_and_b32_e32 v187, 0xffff0000, v112
	v_lshlrev_b32_e32 v194, 16, v116
	v_and_b32_e32 v195, 0xffff0000, v116
	v_lshlrev_b32_e32 v188, 16, v113
	v_and_b32_e32 v189, 0xffff0000, v113
	v_lshlrev_b32_e32 v196, 16, v117
	v_and_b32_e32 v197, 0xffff0000, v117
	v_lshlrev_b32_e32 v190, 16, v114
	v_and_b32_e32 v191, 0xffff0000, v114
	v_lshlrev_b32_e32 v198, 16, v118
	v_and_b32_e32 v199, 0xffff0000, v118
	v_lshlrev_b32_e32 v192, 16, v115
	v_and_b32_e32 v193, 0xffff0000, v115
	v_lshlrev_b32_e32 v200, 16, v119
	v_and_b32_e32 v201, 0xffff0000, v119
	v_pk_mul_f32 v[186:187], v[186:187], v[194:195]
	v_pk_mul_f32 v[188:189], v[188:189], v[196:197]
	v_pk_mul_f32 v[190:191], v[190:191], v[198:199]
	v_pk_mul_f32 v[192:193], v[192:193], v[200:201]
	v_pk_fma_f32 v[202:203], v[16:17], v[186:187], v[202:203]
	v_pk_fma_f32 v[204:205], v[18:19], v[188:189], v[204:205]
	v_pk_fma_f32 v[206:207], v[20:21], v[190:191], v[206:207]
	v_pk_fma_f32 v[208:209], v[22:23], v[192:193], v[208:209]
	v_lshlrev_b32_e32 v186, 16, v120
	v_and_b32_e32 v187, 0xffff0000, v120
	v_lshlrev_b32_e32 v194, 16, v124
	v_and_b32_e32 v195, 0xffff0000, v124
	v_lshlrev_b32_e32 v188, 16, v121
	v_and_b32_e32 v189, 0xffff0000, v121
	v_lshlrev_b32_e32 v196, 16, v125
	v_and_b32_e32 v197, 0xffff0000, v125
	v_lshlrev_b32_e32 v190, 16, v122
	v_and_b32_e32 v191, 0xffff0000, v122
	v_lshlrev_b32_e32 v198, 16, v126
	v_and_b32_e32 v199, 0xffff0000, v126
	v_lshlrev_b32_e32 v192, 16, v123
	v_and_b32_e32 v193, 0xffff0000, v123
	v_lshlrev_b32_e32 v200, 16, v127
	v_and_b32_e32 v201, 0xffff0000, v127
	v_pk_mul_f32 v[186:187], v[186:187], v[194:195]
	v_pk_mul_f32 v[188:189], v[188:189], v[196:197]
	v_pk_mul_f32 v[190:191], v[190:191], v[198:199]
	v_pk_mul_f32 v[192:193], v[192:193], v[200:201]
	v_pk_fma_f32 v[202:203], v[24:25], v[186:187], v[202:203]
	v_pk_fma_f32 v[204:205], v[26:27], v[188:189], v[204:205]
	v_pk_fma_f32 v[206:207], v[28:29], v[190:191], v[206:207]
	v_pk_fma_f32 v[208:209], v[30:31], v[192:193], v[208:209]
	v_lshlrev_b32_e32 v194, 16, v96
	v_and_b32_e32 v195, 0xffff0000, v96
	v_lshlrev_b32_e32 v186, 16, v100
	v_and_b32_e32 v187, 0xffff0000, v100
	v_lshlrev_b32_e32 v196, 16, v97
	v_and_b32_e32 v197, 0xffff0000, v97
	v_lshlrev_b32_e32 v188, 16, v101
	v_and_b32_e32 v189, 0xffff0000, v101
	v_lshlrev_b32_e32 v198, 16, v98
	v_and_b32_e32 v199, 0xffff0000, v98
	v_lshlrev_b32_e32 v190, 16, v102
	v_and_b32_e32 v191, 0xffff0000, v102
	v_lshlrev_b32_e32 v200, 16, v99
	v_and_b32_e32 v201, 0xffff0000, v99
	v_lshlrev_b32_e32 v192, 16, v103
	v_and_b32_e32 v193, 0xffff0000, v103
	v_pk_mul_f32 v[202:203], v[202:203], v[194:195]
	v_pk_mul_f32 v[204:205], v[204:205], v[196:197]
	v_pk_mul_f32 v[206:207], v[206:207], v[198:199]
	v_pk_mul_f32 v[208:209], v[208:209], v[200:201]
	v_pk_mul_f32 v[202:203], v[202:203], v[186:187]
	v_pk_mul_f32 v[204:205], v[204:205], v[188:189]
	v_pk_mul_f32 v[206:207], v[206:207], v[190:191]
	v_pk_mul_f32 v[208:209], v[208:209], v[192:193]
	v_cvt_pk_bf16_f32 v210, v202, v203
	v_cvt_pk_bf16_f32 v211, v204, v205
	v_cvt_pk_bf16_f32 v212, v206, v207
	v_cvt_pk_bf16_f32 v213, v208, v209
	global_store_dwordx4 v184, v[210:213], s[4:5]
	s_waitcnt vmcnt(3)
; __device__ __forceinline__ unsigned pk2(float lo, float hi) { unsigned r; asm("v_cvt_pk_bf16_f32 %0, %1, %2" : "=v"(r) : "v"(lo), "v"(hi)); return r; }
; __device__ __forceinline__ float bfe(const v4u& v, int e) { const unsigned w = v[e >> 1]; return (e & 1) ? __uint_as_float(w & 0xffff0000u) : __uint_as_float(w << 16); }
; __device__ __forceinline__ void mix_conv(const bf16* h, const float* cw, bf16* ycat, int gtid, int gstride) {
;     for (int it = gtid; it < MT * 64; it += gstride) {
;         const int m = it >> 6, c = (it & 63) * 8, t = m & (SEQ - 1);
;         const bf16* hr = h + (size_t)m * NH;
;         const v4u bb = *(const v4u*)(hr + C_AB + c), ga = *(const v4u*)(hr + C_GA + c);
;         float acc[8];
; #pragma unroll
;         for (int e = 0; e < 8; ++e) acc[e] = 0.f;
; #pragma unroll
;         for (int j = 0; j < 3; ++j) { const int dt = 2 - j;
;             if (t - dt >= 0) { const bf16* hp = hr - (size_t)dt * NH; const v4u cc = *(const v4u*)(hp + C_AC + c), xx = *(const v4u*)(hp + C_AX + c);
; #pragma unroll
;                 for (int e = 0; e < 8; ++e) acc[e] += cw[j * GW + c + e] * (bfe(cc, e) * bfe(xx, e)); } }
;         v4u o;
; #pragma unroll
;         for (int e = 0; e < 4; ++e) o[e] = pk2(bfe(bb, 2 * e) * acc[2 * e] * bfe(ga, 2 * e), bfe(bb, 2 * e + 1) * acc[2 * e + 1] * bfe(ga, 2 * e + 1));
;         *(v4u*)(ycat + (size_t)m * DM + Y_A + c) = o;
	v_lshlrev_b32_e32 v186, 16, v136
	v_and_b32_e32 v187, 0xffff0000, v136
	v_lshlrev_b32_e32 v194, 16, v140
	v_and_b32_e32 v195, 0xffff0000, v140
	v_lshlrev_b32_e32 v188, 16, v137
	v_and_b32_e32 v189, 0xffff0000, v137
	v_lshlrev_b32_e32 v196, 16, v141
	v_and_b32_e32 v197, 0xffff0000, v141
	v_lshlrev_b32_e32 v190, 16, v138
	v_and_b32_e32 v191, 0xffff0000, v138
	v_lshlrev_b32_e32 v198, 16, v142
	v_and_b32_e32 v199, 0xffff0000, v142
	v_lshlrev_b32_e32 v192, 16, v139
	v_and_b32_e32 v193, 0xffff0000, v139
	v_lshlrev_b32_e32 v200, 16, v143
	v_and_b32_e32 v201, 0xffff0000, v143
	v_pk_mul_f32 v[186:187], v[186:187], v[194:195]
	v_pk_mul_f32 v[188:189], v[188:189], v[196:197]
	v_pk_mul_f32 v[190:191], v[190:191], v[198:199]
	v_pk_mul_f32 v[192:193], v[192:193], v[200:201]
	v_pk_mul_f32 v[202:203], v[8:9], v[186:187]
	v_pk_mul_f32 v[204:205], v[10:11], v[188:189]
	v_pk_mul_f32 v[206:207], v[12:13], v[190:191]
	v_pk_mul_f32 v[208:209], v[14:15], v[192:193]
	v_lshlrev_b32_e32 v186, 16, v144
	v_and_b32_e32 v187, 0xffff0000, v144
	v_lshlrev_b32_e32 v194, 16, v148
	v_and_b32_e32 v195, 0xffff0000, v148
	v_lshlrev_b32_e32 v188, 16, v145
	v_and_b32_e32 v189, 0xffff0000, v145
	v_lshlrev_b32_e32 v196, 16, v149
	v_and_b32_e32 v197, 0xffff0000, v149
	v_lshlrev_b32_e32 v190, 16, v146
	v_and_b32_e32 v191, 0xffff0000, v146
	v_lshlrev_b32_e32 v198, 16, v150
	v_and_b32_e32 v199, 0xffff0000, v150
	v_lshlrev_b32_e32 v192, 16, v147
	v_and_b32_e32 v193, 0xffff0000, v147
	v_lshlrev_b32_e32 v200, 16, v151
	v_and_b32_e32 v201, 0xffff0000, v151
	v_pk_mul_f32 v[186:187], v[186:187], v[194:195]
	v_pk_mul_f32 v[188:189], v[188:189], v[196:197]
	v_pk_mul_f32 v[190:191], v[190:191], v[198:199]
	v_pk_mul_f32 v[192:193], v[192:193], v[200:201]
	v_pk_fma_f32 v[202:203], v[16:17], v[186:187], v[202:203]
	v_pk_fma_f32 v[204:205], v[18:19], v[188:189], v[204:205]
	v_pk_fma_f32 v[206:207], v[20:21], v[190:191], v[206:207]
	v_pk_fma_f32 v[208:209], v[22:23], v[192:193], v[208:209]
	v_lshlrev_b32_e32 v186, 16, v152
	v_and_b32_e32 v187, 0xffff0000, v152
	v_lshlrev_b32_e32 v194, 16, v156
	v_and_b32_e32 v195, 0xffff0000, v156
	v_lshlrev_b32_e32 v188, 16, v153
	v_and_b32_e32 v189, 0xffff0000, v153
	v_lshlrev_b32_e32 v196, 16, v157
	v_and_b32_e32 v197, 0xffff0000, v157
	v_lshlrev_b32_e32 v190, 16, v154
	v_and_b32_e32 v191, 0xffff0000, v154
	v_lshlrev_b32_e32 v198, 16, v158
	v_and_b32_e32 v199, 0xffff0000, v158
	v_lshlrev_b32_e32 v192, 16, v155
	v_and_b32_e32 v193, 0xffff0000, v155
	v_lshlrev_b32_e32 v200, 16, v159
	v_and_b32_e32 v201, 0xffff0000, v159
	v_pk_mul_f32 v[186:187], v[186:187], v[194:195]
	v_pk_mul_f32 v[188:189], v[188:189], v[196:197]
	v_pk_mul_f32 v[190:191], v[190:191], v[198:199]
	v_pk_mul_f32 v[192:193], v[192:193], v[200:201]
	v_pk_fma_f32 v[202:203], v[24:25], v[186:187], v[202:203]
	v_pk_fma_f32 v[204:205], v[26:27], v[188:189], v[204:205]
	v_pk_fma_f32 v[206:207], v[28:29], v[190:191], v[206:207]
	v_pk_fma_f32 v[208:209], v[30:31], v[192:193], v[208:209]
	v_lshlrev_b32_e32 v194, 16, v128
	v_and_b32_e32 v195, 0xffff0000, v128
	v_lshlrev_b32_e32 v186, 16, v132
	v_and_b32_e32 v187, 0xffff0000, v132
	v_lshlrev_b32_e32 v196, 16, v129
	v_and_b32_e32 v197, 0xffff0000, v129
	v_lshlrev_b32_e32 v188, 16, v133
	v_and_b32_e32 v189, 0xffff0000, v133
	v_lshlrev_b32_e32 v198, 16, v130
	v_and_b32_e32 v199, 0xffff0000, v130
	v_lshlrev_b32_e32 v190, 16, v134
	v_and_b32_e32 v191, 0xffff0000, v134
	v_lshlrev_b32_e32 v200, 16, v131
	v_and_b32_e32 v201, 0xffff0000, v131
	v_lshlrev_b32_e32 v192, 16, v135
	v_and_b32_e32 v193, 0xffff0000, v135
	v_pk_mul_f32 v[202:203], v[202:203], v[194:195]
	v_pk_mul_f32 v[204:205], v[204:205], v[196:197]
	v_pk_mul_f32 v[206:207], v[206:207], v[198:199]
	v_pk_mul_f32 v[208:209], v[208:209], v[200:201]
	v_pk_mul_f32 v[202:203], v[202:203], v[186:187]
	v_pk_mul_f32 v[204:205], v[204:205], v[188:189]
	v_pk_mul_f32 v[206:207], v[206:207], v[190:191]
	v_pk_mul_f32 v[208:209], v[208:209], v[192:193]
	v_cvt_pk_bf16_f32 v210, v202, v203
	v_cvt_pk_bf16_f32 v211, v204, v205
	v_cvt_pk_bf16_f32 v212, v206, v207
	v_cvt_pk_bf16_f32 v213, v208, v209
	global_store_dwordx4 v185, v[210:213], s[4:5]
	v_readlane_b32 s36, v253, 2
	v_readlane_b32 s37, v253, 3
	v_readlane_b32 s38, v253, 4
	v_readlane_b32 s39, v253, 5
	v_readlane_b32 s40, v253, 6
	v_readlane_b32 s41, v253, 7
	v_readlane_b32 s42, v253, 8
	v_readlane_b32 s43, v253, 9
	v_readlane_b32 s44, v253, 10
	v_readlane_b32 s45, v253, 11
	v_readlane_b32 s46, v253, 12
	v_readlane_b32 s47, v253, 13
	v_readlane_b32 s48, v253, 14
	v_readlane_b32 s49, v253, 15
	v_readlane_b32 s50, v253, 16
	v_readlane_b32 s51, v253, 17
	s_mov_b64 s[0:1], exec
	s_mov_b64 s[8:9], exec
	s_mov_b32 s14, 0x7ffff
	s_mov_b32 s15, 0
	s_branch .LBB0_687

; __device__ __forceinline__ unsigned pk2(float lo, float hi) { unsigned r; asm("v_cvt_pk_bf16_f32 %0, %1, %2" : "=v"(r) : "v"(lo), "v"(hi)); return r; }
; __device__ __forceinline__ float bfe(const v4u& v, int e) { const unsigned w = v[e >> 1]; return (e & 1) ? __uint_as_float(w & 0xffff0000u) : __uint_as_float(w << 16); }
; __device__ __forceinline__ void mix_conv(const bf16* h, const float* cw, bf16* ycat, int gtid, int gstride) {
;     for (int it = gtid; it < MT * 64; it += gstride) {
;         const int m = it >> 6, c = (it & 63) * 8, t = m & (SEQ - 1);
;         const bf16* hr = h + (size_t)m * NH;
;         const v4u bb = *(const v4u*)(hr + C_AB + c), ga = *(const v4u*)(hr + C_GA + c);
;         float acc[8];
; #pragma unroll
;         for (int e = 0; e < 8; ++e) acc[e] = 0.f;
; #pragma unroll
;         for (int j = 0; j < 3; ++j) { const int dt = 2 - j;
;             if (t - dt >= 0) { const bf16* hp = hr - (size_t)dt * NH; const v4u cc = *(const v4u*)(hp + C_AC + c), xx = *(const v4u*)(hp + C_AX + c);
; #pragma unroll
;                 for (int e = 0; e < 8; ++e) acc[e] += cw[j * GW + c + e] * (bfe(cc, e) * bfe(xx, e)); } }
;         v4u o;
; #pragma unroll
;         for (int e = 0; e < 4; ++e) o[e] = pk2(bfe(bb, 2 * e) * acc[2 * e] * bfe(ga, 2 * e), bfe(bb, 2 * e + 1) * acc[2 * e + 1] * bfe(ga, 2 * e + 1));
;         *(v4u*)(ycat + (size_t)m * DM + Y_A + c) = o;
.LBB0_682:
	s_or_b64 exec, exec, s[14:15]
	global_load_dwordx4 v[26:29], v[12:13], off offset:1024
	global_load_dwordx4 v[30:33], v[12:13], off offset:2048
	v_mov_b32_e32 v15, v169
	s_mov_b64 s[14:15], 0x1000
	v_ashrrev_i32_e32 v9, 31, v8
	s_waitcnt vmcnt(0) lgkmcnt(0)
	v_lshlrev_b32_e32 v12, 16, v26
	v_lshlrev_b32_e32 v13, 16, v30
	v_mul_f32_e32 v38, v13, v12
	v_lshl_add_u64 v[12:13], s[6:7], 0, v[14:15]
	v_lshl_add_u64 v[22:23], v[12:13], 0, s[14:15]
	v_add_co_u32_e32 v12, vcc, s92, v12
	v_readlane_b32 s14, v254, 39
	s_nop 0
	v_addc_co_u32_e32 v13, vcc, 0, v13, vcc
	global_load_dwordx4 v[12:15], v[12:13], off
	s_nop 0
	global_load_dwordx4 v[34:37], v[22:23], off offset:16
	v_and_b32_e32 v22, 0xffff0000, v26
	v_add_u32_e32 v24, s14, v24
	v_readlane_b32 s14, v255, 21
	s_waitcnt vmcnt(1)
	v_fma_f32 v12, v12, v38, v20
	v_and_b32_e32 v20, 0xffff0000, v30
	v_mul_f32_e32 v20, v20, v22
	v_fma_f32 v13, v13, v20, v21
	v_lshlrev_b32_e32 v20, 16, v27
	v_lshlrev_b32_e32 v21, 16, v31
	v_mul_f32_e32 v20, v21, v20
	v_fma_f32 v14, v14, v20, v18
	v_and_b32_e32 v18, 0xffff0000, v31
	v_and_b32_e32 v20, 0xffff0000, v27
	v_mul_f32_e32 v18, v18, v20
	v_fma_f32 v15, v18, v15, v19
	v_lshlrev_b32_e32 v18, 16, v28
	v_lshlrev_b32_e32 v19, 16, v32
	v_mul_f32_e32 v18, v19, v18
	s_waitcnt vmcnt(0)
	v_fma_f32 v16, v18, v34, v16
	v_and_b32_e32 v18, 0xffff0000, v32
	v_and_b32_e32 v19, 0xffff0000, v28
	v_mul_f32_e32 v18, v18, v19
	v_fma_f32 v17, v18, v35, v17
	v_lshlrev_b32_e32 v18, 16, v29
	v_lshlrev_b32_e32 v19, 16, v33
	v_mul_f32_e32 v18, v19, v18
	v_fma_f32 v10, v18, v36, v10
	v_and_b32_e32 v18, 0xffff0000, v33
	v_and_b32_e32 v19, 0xffff0000, v29
	v_mul_f32_e32 v18, v18, v19
	v_fmac_f32_e32 v11, v18, v37
	v_lshlrev_b32_e32 v18, 16, v4
	v_and_b32_e32 v4, 0xffff0000, v4
	v_mul_f32_e32 v12, v12, v18
	v_lshlrev_b32_e32 v18, 16, v0
	v_mul_f32_e32 v4, v13, v4
	v_and_b32_e32 v0, 0xffff0000, v0
	v_mul_f32_e32 v12, v12, v18
	v_mul_f32_e32 v0, v4, v0
	v_lshlrev_b32_e32 v4, 16, v5
	v_and_b32_e32 v5, 0xffff0000, v5
	v_cvt_pk_bf16_f32 v0, v12, v0
	v_mul_f32_e32 v4, v14, v4
	v_lshlrev_b32_e32 v12, 16, v1
	v_mul_f32_e32 v5, v15, v5
	v_and_b32_e32 v1, 0xffff0000, v1
	v_mul_f32_e32 v4, v4, v12
	v_mul_f32_e32 v1, v5, v1
	v_cvt_pk_bf16_f32 v1, v4, v1
	v_lshlrev_b32_e32 v4, 16, v6
	v_mul_f32_e32 v4, v16, v4
	v_lshlrev_b32_e32 v5, 16, v2
	v_mul_f32_e32 v4, v4, v5
	v_and_b32_e32 v5, 0xffff0000, v6
	v_mul_f32_e32 v5, v17, v5
	v_and_b32_e32 v2, 0xffff0000, v2
	v_mul_f32_e32 v2, v5, v2
	v_cvt_pk_bf16_f32 v2, v4, v2
	v_lshlrev_b32_e32 v4, 16, v7
	v_mul_f32_e32 v4, v10, v4
	v_lshlrev_b32_e32 v5, 16, v3
	v_mul_f32_e32 v4, v4, v5
	v_and_b32_e32 v5, 0xffff0000, v7
	v_mul_f32_e32 v5, v11, v5
	v_and_b32_e32 v3, 0xffff0000, v3
	v_mul_f32_e32 v3, v5, v3
	v_cvt_pk_bf16_f32 v3, v4, v3
	v_lshlrev_b64 v[4:5], 12, v[8:9]
	v_add_u32_e32 v25, s14, v25
	s_mov_b32 s14, 0x7ffff
	v_lshl_add_u64 v[4:5], s[4:5], 0, v[4:5]
	v_cmp_lt_i32_e32 vcc, s14, v24
	v_lshl_add_u64 v[4:5], v[4:5], 0, v[168:169]
	s_or_b64 s[8:9], vcc, s[8:9]
	global_store_dwordx4 v[4:5], v[0:3], off
	s_andn2_b64 exec, exec, s[8:9]
	s_cbranch_execz .LBB0_687
.LBB0_683:
	v_ashrrev_i32_e32 v8, 6, v24
	v_and_b32_e32 v14, 0x1f8, v25
	v_mov_b64_e32 v[0:1], s[2:3]
	v_mad_i64_i32 v[22:23], s[14:15], v8, s13, v[0:1]
	v_lshlrev_b32_e32 v168, 1, v14
	v_lshl_add_u64 v[12:13], v[22:23], 0, v[168:169]
	v_add_co_u32_e32 v0, vcc, 0x2000, v12
	v_and_b32_e32 v9, 0xfff, v8
	s_nop 0
	v_addc_co_u32_e32 v1, vcc, 0, v13, vcc
	global_load_dwordx4 v[4:7], v[12:13], off
	s_nop 0
	global_load_dwordx4 v[0:3], v[0:1], off offset:3072
	v_cmp_lt_u32_e32 vcc, 1, v9
	v_mov_b32_e32 v20, v169
	v_mov_b32_e32 v21, v169
	v_mov_b32_e32 v18, v169
	v_mov_b32_e32 v19, v169
	v_mov_b32_e32 v16, v169
	v_mov_b32_e32 v17, v169
	v_mov_b32_e32 v10, v169
	v_mov_b32_e32 v11, v169
	v_lshlrev_b32_e32 v14, 2, v14
	s_and_saveexec_b64 s[14:15], vcc
	s_cbranch_execz .LBB0_685
	v_add_co_u32_e32 v10, vcc, 0xffff8c00, v12
	s_nop 1
	v_addc_co_u32_e32 v11, vcc, -1, v13, vcc
	global_load_dwordx4 v[16:19], v[10:11], off
	v_add_co_u32_e32 v10, vcc, 0xffff9000, v12
	s_nop 1
	v_addc_co_u32_e32 v11, vcc, -1, v13, vcc
	global_load_dwordx4 v[26:29], v[10:11], off
	global_load_dwordx4 v[30:33], v14, s[6:7] offset:16
	global_load_dwordx4 v[34:37], v14, s[6:7]
	s_waitcnt vmcnt(0) lgkmcnt(0)
	v_lshlrev_b32_e32 v10, 16, v16
	v_and_b32_e32 v11, 0xffff0000, v16
	v_lshlrev_b32_e32 v20, 16, v26
	v_and_b32_e32 v21, 0xffff0000, v26
	v_pk_mul_f32 v[20:21], v[10:11], v[20:21]
	v_lshlrev_b32_e32 v10, 16, v17
	v_and_b32_e32 v11, 0xffff0000, v17
	v_lshlrev_b32_e32 v16, 16, v27
	v_and_b32_e32 v17, 0xffff0000, v27
	v_pk_mul_f32 v[16:17], v[10:11], v[16:17]
	v_lshlrev_b32_e32 v10, 16, v18
	v_and_b32_e32 v11, 0xffff0000, v18
	v_lshlrev_b32_e32 v26, 16, v28
	v_and_b32_e32 v27, 0xffff0000, v28
	v_pk_mul_f32 v[26:27], v[10:11], v[26:27]
	v_lshlrev_b32_e32 v10, 16, v19
	v_lshlrev_b32_e32 v28, 16, v29
	v_and_b32_e32 v29, 0xffff0000, v29
	v_and_b32_e32 v11, 0xffff0000, v19
	v_pk_mul_f32 v[10:11], v[10:11], v[28:29]
	v_pk_fma_f32 v[18:19], v[36:37], v[16:17], 0 op_sel_hi:[1,1,0]
	v_pk_fma_f32 v[10:11], v[10:11], v[32:33], 0 op_sel_hi:[1,1,0]
	v_pk_fma_f32 v[16:17], v[26:27], v[30:31], 0 op_sel_hi:[1,1,0]
	v_pk_fma_f32 v[20:21], v[34:35], v[20:21], 0 op_sel_hi:[1,1,0]
.LBB0_685:
	s_or_b64 exec, exec, s[14:15]
	v_cmp_ne_u32_e32 vcc, 0, v9
	s_and_saveexec_b64 s[14:15], vcc
	s_cbranch_execz .LBB0_682
	v_lshl_add_u64 v[22:23], v[22:23], 0, v[168:169]
	v_add_co_u32_e32 v26, vcc, 0xffffc800, v22
	s_nop 1
	v_addc_co_u32_e32 v27, vcc, -1, v23, vcc
	global_load_dwordx4 v[26:29], v[26:27], off
	v_add_co_u32_e32 v22, vcc, 0xffffcc00, v22
	s_nop 1
	v_addc_co_u32_e32 v23, vcc, -1, v23, vcc
	global_load_dwordx4 v[30:33], v[22:23], off
	global_load_dwordx4 v[34:37], v14, s[6:7] offset:2064
	global_load_dwordx4 v[38:41], v14, s[6:7] offset:2048
	s_waitcnt vmcnt(0) lgkmcnt(0)
	v_lshlrev_b32_e32 v22, 16, v26
	v_and_b32_e32 v23, 0xffff0000, v26
	v_lshlrev_b32_e32 v26, 16, v27
	v_and_b32_e32 v27, 0xffff0000, v27
	v_lshlrev_b32_e32 v42, 16, v30
	v_and_b32_e32 v43, 0xffff0000, v30
	v_lshlrev_b32_e32 v30, 16, v31
	v_and_b32_e32 v31, 0xffff0000, v31
	v_pk_mul_f32 v[22:23], v[22:23], v[42:43]
	v_pk_mul_f32 v[26:27], v[26:27], v[30:31]
	v_lshlrev_b32_e32 v30, 16, v28
	v_and_b32_e32 v31, 0xffff0000, v28
	v_lshlrev_b32_e32 v42, 16, v32
	v_and_b32_e32 v43, 0xffff0000, v32
	v_lshlrev_b32_e32 v28, 16, v29
	v_lshlrev_b32_e32 v32, 16, v33
	v_and_b32_e32 v33, 0xffff0000, v33
	v_and_b32_e32 v29, 0xffff0000, v29
	v_pk_mul_f32 v[30:31], v[30:31], v[42:43]
	v_pk_mul_f32 v[28:29], v[28:29], v[32:33]
	v_pk_fma_f32 v[18:19], v[40:41], v[26:27], v[18:19]
	v_pk_fma_f32 v[10:11], v[28:29], v[36:37], v[10:11]
	v_pk_fma_f32 v[16:17], v[30:31], v[34:35], v[16:17]
	v_pk_fma_f32 v[20:21], v[38:39], v[22:23], v[20:21]
	s_branch .LBB0_682

; __device__ __forceinline__ unsigned pk2(float lo, float hi) { unsigned r; asm("v_cvt_pk_bf16_f32 %0, %1, %2" : "=v"(r) : "v"(lo), "v"(hi)); return r; }
; __device__ __forceinline__ void hgrn_pass3(const bf16* h, const float* lbraw, int layer, const bf16* SB, const float* ng, bf16* ycat, char* lds, int wg, int G) {
;     ...
;         const int c = item & 63, bh = item >> 6, hh = bh & 3, b = bh >> 2; const size_t m0 = (size_t)b * SEQ + c * 64;
;         const bf16* hp = h + (m0 + 16 * seg) * NH + hh * 128 + k;
;         bf16 fzv[16], qv[16], ivv[16];
; #pragma unroll
;         for (int i = 0; i < 16; ++i) { fzv[i] = hp[(size_t)i * NH + C_BF]; qv[i] = hp[(size_t)i * NH + C_BQ]; ivv[i] = hp[(size_t)i * NH + C_BI]; }
;     ...
;         { const int t = 16 * tb + li; const float rsn = rsqrtf((SS[t * 2] + SS[t * 2 + 1]) * (1.f / 128.f) + RMS_EPS);
;           bf16* yp = ycat + (m0 + t) * DM + Y_B + hh * 128 + 4 * g; const float* ngp = ng + hh * 128 + 4 * g;
; #pragma unroll
;           for (int nb = 0; nb < 4; ++nb) { const int v0 = 16 * (vh * 4 + nb); const pg8::f32x4 nv = *(const pg8::f32x4*)(ngp + v0); const v2u gt = gate[nb];
;               v2u w; w.x = pk2(oacc[nb][0] * rsn * nv[0] * __uint_as_float(gt.x << 16), oacc[nb][1] * rsn * nv[1] * __uint_as_float(gt.x & 0xffff0000u));
;               w.y = pk2(oacc[nb][2] * rsn * nv[2] * __uint_as_float(gt.y << 16), oacc[nb][3] * rsn * nv[3] * __uint_as_float(gt.y & 0xffff0000u));
;               *(v2u*)(yp + v0) = w; } }
.LBB0_731:
	s_or_b64 exec, exec, s[0:1]
	s_waitcnt lgkmcnt(0)
	s_barrier
	ds_read_b64 v[8:9], v122
	s_mov_b32 s0, 0x800000
	v_mov_b32_e32 v101, v169
	v_lshlrev_b32_e32 v14, 16, v108
	v_and_b32_e32 v15, 0xffff0000, v108
	s_waitcnt lgkmcnt(0)
	v_add_f32_e32 v8, v8, v9
	v_fmamk_f32 v8, v8, 0x3c000000, v215
	v_cmp_gt_f32_e32 vcc, s0, v8
	v_mul_f32_e32 v9, 0x4b800000, v8
	s_mov_b64 s[0:1], 0x12800400
	v_cndmask_b32_e32 v8, v8, v9, vcc
	v_rsq_f32_e32 v8, v8
	s_add_i32 s27, s27, s86
	v_mul_f32_e32 v9, 0x45800000, v8
	v_cndmask_b32_e32 v12, v8, v9, vcc
	v_lshlrev_b64 v[8:9], 12, v[110:111]
	v_lshl_add_u64 v[8:9], s[4:5], 0, v[8:9]
	v_lshl_add_u64 v[8:9], v[8:9], 0, s[28:29]
	s_lshl_b32 s28, s36, 2
	v_lshl_add_u64 v[10:11], v[8:9], 0, v[100:101]
	v_lshl_add_u64 v[8:9], v[88:89], 0, s[28:29]
	global_load_dwordx4 v[24:27], v[8:9], off
	global_load_dwordx4 v[28:31], v[8:9], off offset:64
	global_load_dwordx4 v[32:35], v[8:9], off offset:128
	global_load_dwordx4 v[36:39], v[8:9], off offset:192
	v_mul_f32_e32 v13, v20, v12
	v_and_b32_e32 v20, 0xffff0000, v109
	v_mul_f32_e32 v4, v4, v12
	v_mul_f32_e32 v5, v5, v12
	v_mul_f32_e32 v0, v0, v12
	v_mul_f32_e32 v1, v1, v12
	s_waitcnt vmcnt(0)
	v_mul_f32_e32 v13, v24, v13
	v_mul_f32_e32 v13, v13, v14
	v_mul_f32_e32 v14, v21, v12
	v_mul_f32_e32 v14, v25, v14
	v_mul_f32_e32 v14, v14, v15
	v_cvt_pk_bf16_f32 v14, v13, v14
	v_mul_f32_e32 v13, v22, v12
	v_mul_f32_e32 v13, v26, v13
	v_lshlrev_b32_e32 v15, 16, v109
	v_mul_f32_e32 v13, v13, v15
	v_mul_f32_e32 v15, v23, v12
	v_mul_f32_e32 v15, v27, v15
	v_mul_f32_e32 v15, v15, v20
	v_lshl_add_u64 v[20:21], s[8:9], 1, v[10:11]
	v_lshl_add_u64 v[10:11], v[20:21], 0, s[0:1]
	s_mov_b32 s0, 0x12800000
	v_add_co_u32_e32 v20, vcc, s0, v20
	v_cvt_pk_bf16_f32 v15, v13, v15
	v_mul_f32_e32 v13, v16, v12
	s_nop 0
	v_addc_co_u32_e32 v21, vcc, 0, v21, vcc
	global_store_dwordx2 v[20:21], v[14:15], off offset:1024
	v_lshlrev_b32_e32 v14, 16, v106
	v_and_b32_e32 v15, 0xffff0000, v106
	v_and_b32_e32 v16, 0xffff0000, v107
	v_readlane_b32 s0, v255, 23
	s_add_i32 s26, s26, s0
	v_readlane_b32 s0, v255, 13
	s_add_i32 s25, s25, s0
	v_readlane_b32 s0, v255, 39
	v_readlane_b32 s1, v255, 40
	s_cmpk_lt_i32 s27, 0x200
	v_mul_f32_e32 v13, v28, v13
	v_mul_f32_e32 v13, v13, v14
	v_mul_f32_e32 v14, v17, v12
	v_mul_f32_e32 v14, v29, v14
	v_mul_f32_e32 v14, v14, v15
	v_cvt_pk_bf16_f32 v14, v13, v14
	v_mul_f32_e32 v13, v18, v12
	v_mul_f32_e32 v13, v30, v13
	v_lshlrev_b32_e32 v15, 16, v107
	v_mul_f32_e32 v13, v13, v15
	v_mul_f32_e32 v15, v19, v12
	v_mul_f32_e32 v15, v31, v15
	v_mul_f32_e32 v15, v15, v16
	v_cvt_pk_bf16_f32 v15, v13, v15
	global_store_dwordx2 v[10:11], v[14:15], off offset:32
	v_lshlrev_b32_e32 v13, 16, v104
	v_lshl_add_u64 v[92:93], v[92:93], 0, s[0:1]
	v_mul_f32_e32 v4, v4, v32
	v_mul_f32_e32 v4, v4, v13
	v_mul_f32_e32 v5, v5, v33
	v_and_b32_e32 v13, 0xffff0000, v104
	v_mul_f32_e32 v5, v5, v13
	v_cvt_pk_bf16_f32 v4, v4, v5
	v_mul_f32_e32 v5, v6, v12
	v_mul_f32_e32 v5, v5, v34
	v_lshlrev_b32_e32 v6, 16, v105
	v_mul_f32_e32 v5, v5, v6
	v_mul_f32_e32 v6, v7, v12
	v_mul_f32_e32 v6, v6, v35
	v_and_b32_e32 v7, 0xffff0000, v105
	v_mul_f32_e32 v6, v6, v7
	v_cvt_pk_bf16_f32 v5, v5, v6
	global_store_dwordx2 v[10:11], v[4:5], off offset:64
	v_mul_f32_e32 v0, v0, v36
	v_lshlrev_b32_e32 v4, 16, v102
	v_mul_f32_e32 v0, v0, v4
	v_mul_f32_e32 v1, v1, v37
	v_and_b32_e32 v4, 0xffff0000, v102
	v_mul_f32_e32 v1, v1, v4
	v_cvt_pk_bf16_f32 v0, v0, v1
	v_mul_f32_e32 v1, v2, v12
	v_mul_f32_e32 v1, v1, v38
	v_lshlrev_b32_e32 v2, 16, v103
	v_mul_f32_e32 v1, v1, v2
	v_mul_f32_e32 v2, v3, v12
	v_mul_f32_e32 v2, v2, v39
	v_and_b32_e32 v3, 0xffff0000, v103
	v_mul_f32_e32 v2, v2, v3
	v_cvt_pk_bf16_f32 v1, v1, v2
	global_store_dwordx2 v[10:11], v[0:1], off offset:96
	s_waitcnt lgkmcnt(0)
	s_barrier
	s_cbranch_scc0 .LBB0_896
.LBB0_732:
	s_ashr_i32 s0, s27, 8
	s_ashr_i32 s1, s0, 31
	s_lshl_b64 s[0:1], s[0:1], 12
	s_and_b32 s2, s26, 0xfc0
	s_or_b32 s0, s0, s2
	v_lshl_add_u64 v[0:1], s[0:1], 0, v[82:83]
	v_mov_b64_e32 v[64:65], s[6:7]
	v_mad_u64_u32 v[2:3], s[2:3], v0, s13, v[64:65]
	s_and_b32 s36, s25, 0x180
	v_mad_i32_i24 v3, v1, s13, v3
	s_lshl_b32 s28, s36, 1
	v_lshl_add_u64 v[0:1], v[2:3], 0, s[28:29]
	v_lshl_add_u64 v[0:1], v[0:1], 0, v[168:169]
	s_movk_i32 s2, 0x1000
	v_add_co_u32_e32 v2, vcc, s2, v0
	s_movk_i32 s2, 0x4000
	s_nop 0
	v_addc_co_u32_e32 v3, vcc, 0, v1, vcc
	v_add_co_u32_e32 v4, vcc, s2, v0
	s_movk_i32 s2, 0x5000
	s_nop 0
	v_addc_co_u32_e32 v5, vcc, 0, v1, vcc
	v_add_co_u32_e32 v6, vcc, s2, v0
	s_mov_b32 s2, 0x8000
	s_nop 0
	v_addc_co_u32_e32 v7, vcc, 0, v1, vcc
	v_add_co_u32_e32 v8, vcc, s2, v0
	s_mov_b32 s2, 0xc000
	s_nop 0
	v_addc_co_u32_e32 v9, vcc, 0, v1, vcc
	global_load_ushort v146, v[2:3], off
	global_load_ushort v66, v[2:3], off offset:1024
	global_load_ushort v145, v[4:5], off offset:3072
	global_load_ushort v67, v[6:7], off
	global_load_ushort v143, v[8:9], off offset:2048
	global_load_ushort v148, v[8:9], off offset:1024
	global_load_ushort v155, v[4:5], off offset:2048
	global_load_ushort v160, v[0:1], off offset:3072
	v_add_co_u32_e32 v2, vcc, s2, v0
	s_mov_b32 s2, 0x10000
	s_nop 0
	v_addc_co_u32_e32 v3, vcc, 0, v1, vcc
	v_add_co_u32_e32 v4, vcc, s2, v0
	s_mov_b32 s2, 0xf000
	s_nop 0
	v_addc_co_u32_e32 v5, vcc, 0, v1, vcc
	v_add_co_u32_e32 v6, vcc, s2, v0
	s_mov_b32 s2, 0x13000
	s_nop 0
	v_addc_co_u32_e32 v7, vcc, 0, v1, vcc
	v_add_co_u32_e32 v10, vcc, s2, v0
	s_mov_b32 s2, 0x14000
	s_nop 0
	v_addc_co_u32_e32 v11, vcc, 0, v1, vcc
	global_load_ushort v68, v[8:9], off offset:3072
	global_load_ushort v142, v[2:3], off offset:1024
	global_load_ushort v69, v[2:3], off offset:2048
; __device__ __forceinline__ float hg_lb(const float* lbraw, int layer, int ch) { if (layer == 0) return 0.f; const float e0 = __expf(lbraw[ch]), e1 = __expf(lbraw[GW + ch]); return e1 / (e0 + e1); }
; __device__ __forceinline__ void hgrn_pass3(const bf16* h, const float* lbraw, int layer, const bf16* SB, const float* ng, bf16* ycat, char* lds, int wg, int G) {
;     ...
;         const int c = item & 63, bh = item >> 6, hh = bh & 3, b = bh >> 2; const size_t m0 = (size_t)b * SEQ + c * 64;
;         const bf16* hp = h + (m0 + 16 * seg) * NH + hh * 128 + k;
;         bf16 fzv[16], qv[16], ivv[16];
; #pragma unroll
;         for (int i = 0; i < 16; ++i) { fzv[i] = hp[(size_t)i * NH + C_BF]; qv[i] = hp[(size_t)i * NH + C_BQ]; ivv[i] = hp[(size_t)i * NH + C_BI]; }
;         hbf16x8 sbf[4][4];
; #pragma unroll
;         for (int ks = 0; ks < 4; ++ks)
; #pragma unroll
;             for (int nb = 0; nb < 4; ++nb) sbf[ks][nb] = *(const hbf16x8*)(SB + (size_t)item * 16384 + (16 * (vh * 4 + nb) + li) * 128 + ks * 32 + 8 * g);
;         v2u gate[4];
; #pragma unroll
;         for (int nb = 0; nb < 4; ++nb) gate[nb] = *(const v2u*)(h + (m0 + 16 * tb + li) * NH + C_GB + hh * 128 + 16 * (vh * 4 + nb) + 4 * g);
;         const float lb = hg_lb(lbraw, layer, hh * 128 + k);
	global_load_ushort v141, v[4:5], off
	global_load_ushort v138, v[6:7], off offset:3072
	global_load_ushort v133, v[10:11], off offset:2048
	global_load_ushort v70, v[4:5], off offset:1024
	global_load_ushort v144, v[2:3], off
	v_add_co_u32_e32 v2, vcc, s2, v0
	s_mov_b32 s2, 0x17000
	s_nop 0
	v_addc_co_u32_e32 v3, vcc, 0, v1, vcc
	v_add_co_u32_e32 v4, vcc, s2, v0
	s_mov_b32 s2, 0x1b000
	s_nop 0
	v_addc_co_u32_e32 v5, vcc, 0, v1, vcc
	v_add_co_u32_e32 v6, vcc, s2, v0
	s_mov_b32 s2, 0x1f000
	s_nop 0
	v_addc_co_u32_e32 v7, vcc, 0, v1, vcc
	global_load_ushort v140, v[10:11], off offset:3072
	global_load_ushort v74, v[2:3], off
	global_load_ushort v139, v[4:5], off offset:2048
	global_load_ushort v71, v[4:5], off offset:3072
	global_load_ushort v137, v[6:7], off offset:1024
	global_load_ushort v147, v[6:7], off offset:2048
	global_load_ushort v126, v[6:7], off
	global_load_ushort v127, v[4:5], off offset:1024
	v_add_co_u32_e32 v2, vcc, s2, v0
	s_mov_b32 s2, 0x1e000
	s_nop 0
	v_addc_co_u32_e32 v3, vcc, 0, v1, vcc
	v_add_co_u32_e32 v4, vcc, s2, v0
	s_mov_b32 s2, 0x22000
	s_nop 0
	v_addc_co_u32_e32 v5, vcc, 0, v1, vcc
	v_add_co_u32_e32 v6, vcc, s2, v0
	s_mov_b32 s2, 0x23000
	s_nop 0
	v_addc_co_u32_e32 v7, vcc, 0, v1, vcc
	v_add_co_u32_e32 v8, vcc, s2, v0
	s_mov_b32 s2, 0x26000
	s_nop 0
	v_addc_co_u32_e32 v9, vcc, 0, v1, vcc
	v_add_co_u32_e32 v10, vcc, s2, v0
	s_mov_b32 s2, 0x2a000
	s_nop 0
	v_addc_co_u32_e32 v11, vcc, 0, v1, vcc
	global_load_ushort v136, v[2:3], off
	global_load_ushort v125, v[4:5], off offset:3072
	global_load_ushort v135, v[6:7], off offset:3072
	global_load_ushort v149, v[8:9], off
	global_load_ushort v134, v[10:11], off offset:2048
	global_load_ushort v78, v[10:11], off offset:1024
	global_load_ushort v79, v[6:7], off offset:2048
	global_load_ushort v150, v[2:3], off offset:1024
	v_add_co_u32_e32 v2, vcc, s2, v0
	s_mov_b32 s2, 0x2e000
	s_nop 0
	v_addc_co_u32_e32 v3, vcc, 0, v1, vcc
	v_add_co_u32_e32 v4, vcc, s2, v0
	s_mov_b32 s2, 0x2d000
	s_nop 0
	v_addc_co_u32_e32 v5, vcc, 0, v1, vcc
	v_add_co_u32_e32 v6, vcc, s2, v0
	s_mov_b32 s2, 0x31000
	s_nop 0
	v_addc_co_u32_e32 v7, vcc, 0, v1, vcc
	v_add_co_u32_e32 v8, vcc, s2, v0
	s_mov_b32 s2, 0x32000
	s_nop 0
	v_addc_co_u32_e32 v9, vcc, 0, v1, vcc
	global_load_ushort v151, v[10:11], off offset:3072
	global_load_ushort v132, v[2:3], off offset:1024
	global_load_ushort v152, v[2:3], off offset:2048
	global_load_ushort v131, v[4:5], off
	global_load_ushort v76, v[6:7], off offset:3072
	global_load_ushort v75, v[8:9], off offset:2048
	global_load_ushort v153, v[4:5], off offset:1024
	global_load_ushort v77, v[2:3], off
	v_add_co_u32_e32 v2, vcc, s2, v0
	s_mov_b32 s2, 0x35000
	s_nop 0
	v_addc_co_u32_e32 v3, vcc, 0, v1, vcc
	v_add_co_u32_e32 v4, vcc, s2, v0
	s_mov_b32 s2, 0x39000
	s_nop 0
	v_addc_co_u32_e32 v5, vcc, 0, v1, vcc
	v_add_co_u32_e32 v0, vcc, s2, v0
	s_mov_b32 s2, 0x1c800000
	s_nop 0
	v_addc_co_u32_e32 v1, vcc, 0, v1, vcc
	global_load_ushort v130, v[8:9], off offset:3072
	global_load_ushort v156, v[2:3], off
	global_load_ushort v129, v[4:5], off offset:2048
	global_load_ushort v154, v[4:5], off offset:3072
	global_load_ushort v128, v[0:1], off offset:1024
	global_load_ushort v157, v[0:1], off offset:2048
	global_load_ushort v72, v[0:1], off
	global_load_ushort v73, v[4:5], off offset:1024
	v_lshl_add_u64 v[0:1], v[92:93], 0, v[90:91]
	v_add_co_u32_e32 v0, vcc, s2, v0
	v_lshl_add_u64 v[2:3], v[92:93], 0, v[98:99]
	s_nop 0
	v_addc_co_u32_e32 v1, vcc, 0, v1, vcc
	v_add_co_u32_e32 v4, vcc, s2, v2
	v_or_b32_e32 v110, s0, v84
	s_nop 0
	v_addc_co_u32_e32 v5, vcc, 0, v3, vcc
	v_lshl_add_u64 v[2:3], v[92:93], 0, v[96:97]
	v_add_co_u32_e32 v8, vcc, s2, v2
	v_mov_b32_e32 v101, v169
	s_nop 0
	v_addc_co_u32_e32 v9, vcc, 0, v3, vcc
	v_lshl_add_u64 v[2:3], v[92:93], 0, v[94:95]
	v_add_co_u32_e32 v12, vcc, s2, v2
	v_mad_u64_u32 v[64:65], s[2:3], v110, s13, v[64:65]
	s_nop 0
	v_addc_co_u32_e32 v13, vcc, 0, v3, vcc
	global_load_dwordx4 v[48:51], v[0:1], off
	global_load_dwordx4 v[16:19], v[0:1], off offset:64
	global_load_dwordx4 v[52:55], v[4:5], off
	global_load_dwordx4 v[20:23], v[4:5], off offset:64
	global_load_dwordx4 v[56:59], v[8:9], off
	global_load_dwordx4 v[24:27], v[8:9], off offset:64
	global_load_dwordx4 v[60:63], v[12:13], off
	global_load_dwordx4 v[32:35], v[12:13], off offset:64
	global_load_dwordx4 v[28:31], v[0:1], off offset:128
	s_nop 0
	global_load_dwordx4 v[0:3], v[0:1], off offset:192
	s_nop 0
	global_load_dwordx4 v[36:39], v[4:5], off offset:128
	s_nop 0
	global_load_dwordx4 v[4:7], v[4:5], off offset:192
	s_nop 0
	global_load_dwordx4 v[40:43], v[8:9], off offset:128
	s_nop 0
	global_load_dwordx4 v[8:11], v[8:9], off offset:192
	s_nop 0
	global_load_dwordx4 v[44:47], v[12:13], off offset:128
	s_nop 0
	global_load_dwordx4 v[12:15], v[12:13], off offset:192
	v_mad_i32_i24 v65, s1, v217, v65
	v_lshl_add_u64 v[64:65], v[64:65], 0, s[28:29]
	v_lshl_add_u64 v[64:65], v[64:65], 0, v[100:101]
	v_lshl_add_u64 v[64:65], s[8:9], 1, v[64:65]
	s_mov_b64 s[2:3], 0x3000
	v_lshl_add_u64 v[102:103], v[64:65], 0, s[2:3]
	v_add_co_u32_e32 v64, vcc, 0x3000, v64
	v_mov_b32_e32 v111, s1
	s_nop 0
	v_addc_co_u32_e32 v65, vcc, 0, v65, vcc
	global_load_dwordx2 v[108:109], v[64:65], off
	global_load_dwordx2 v[106:107], v[102:103], off offset:32
	global_load_dwordx2 v[104:105], v[102:103], off offset:64
	s_nop 0
	global_load_dwordx2 v[102:103], v[102:103], off offset:96
	s_andn2_b64 vcc, exec, s[94:95]
	v_mov_b32_e32 v186, 0
	s_cbranch_vccnz .LBB0_734
	v_or_b32_e32 v64, s36, v80
	v_readlane_b32 s64, v253, 2
	v_lshlrev_b32_e32 v64, 2, v64
	v_readlane_b32 s72, v253, 10
	v_readlane_b32 s73, v253, 11
	s_nop 4
	global_load_dword v65, v64, s[72:73]
	s_nop 0
	global_load_dword v64, v64, s[72:73] offset:2048
	v_readlane_b32 s69, v253, 7
	v_readlane_b32 s70, v253, 8
	v_readlane_b32 s71, v253, 9
	v_readlane_b32 s74, v253, 12
	v_readlane_b32 s75, v253, 13
	s_mov_b64 s[74:75], 0x80000
	s_mov_b32 s71, 0xe000
	s_mov_b32 s70, 0xa000
	s_movk_i32 s69, 0x2000
	s_mov_b32 s72, 0x42a00000
	v_readlane_b32 s65, v253, 3
	v_readlane_b32 s66, v253, 4
	v_readlane_b32 s67, v253, 5
	v_readlane_b32 s68, v253, 6
	v_readlane_b32 s76, v253, 14
	v_readlane_b32 s77, v253, 15
	v_readlane_b32 s78, v253, 16
	v_readlane_b32 s79, v253, 17
	s_waitcnt vmcnt(0)
	v_mul_f32_e32 v65, 0x3fb8aa3b, v65
	v_mul_f32_e32 v64, 0x3fb8aa3b, v64
	v_exp_f32_e32 v65, v65
	v_exp_f32_e32 v64, v64
	s_nop 0
	v_add_f32_e32 v65, v65, v64
	v_div_scale_f32 v101, s[0:1], v65, v65, v64
	v_rcp_f32_e32 v158, v101
	v_div_scale_f32 v159, vcc, v64, v65, v64
	v_fma_f32 v161, -v101, v158, 1.0
	v_fmac_f32_e32 v158, v161, v158
	v_mul_f32_e32 v161, v159, v158
	v_fma_f32 v162, -v101, v161, v159
	v_fmac_f32_e32 v161, v162, v158
	v_fma_f32 v101, -v101, v161, v159
	v_div_fmas_f32 v101, v101, v158, v161
	v_div_fixup_f32 v186, v101, v65, v64

; #define LDS_WAIT() asm volatile("s_waitcnt lgkmcnt(0)" ::: "memory")
; __device__ __forceinline__ void p0_transpose_item(const float* W, int K, int N, bf16* WT, float* scr, int item, int lane, const float* scale, const float* cb, float* c1, float* c2) {
;     const int nblk = N / 64, kb = item / nblk, nb = item % nblk, k0 = 64 * kb, n0 = 64 * nb;
;     const int lr = lane >> 4, lc = (lane & 15) * 4;
;     f32x4 v[16];
; #pragma unroll
;     for (int i = 0; i < 16; ++i) v[i] = *(const f32x4*)(W + (size_t)(k0 + 4 * i + lr) * N + n0 + lc);
; #pragma unroll
;     for (int i = 0; i < 16; ++i) { const int kk = 4 * i + lr; f32x4 w = v[i]; if (scale) w = w * scale[k0 + kk]; float* d = scr + kk * 65 + lc; d[0] = w[0]; d[1] = w[1]; d[2] = w[2]; d[3] = w[3]; }
;     LDS_WAIT(); asm volatile("" ::: "memory");
.LBB0_983:
	s_mul_hi_i32 s0, s24, 0xae4c415d
	s_add_i32 s0, s0, s24
	s_lshr_b32 s1, s0, 31
	s_ashr_i32 s0, s0, 12
	s_add_i32 s0, s0, s1
	s_mul_i32 s1, s0, 0x1780
	s_sub_i32 s45, s24, s1
	s_cmpk_gt_i32 s45, 0xeff
	s_mov_b64 s[2:3], -1
	s_cbranch_scc0 .LBB0_1019
	s_cmpk_gt_u32 s45, 0x12ff
	s_cbranch_scc0 .LBB0_1016
	s_ashr_i32 s1, s0, 31
	s_cmpk_gt_u32 s45, 0x16ff
	s_cbranch_scc0 .LBB0_987
	v_readlane_b32 s48, v253, 18
	s_lshl_b64 s[2:3], s[0:1], 21
	v_readlane_b32 s62, v253, 32
	v_readlane_b32 s63, v253, 33
	s_add_u32 s4, s62, s2
	s_addc_u32 s5, s63, s3
	s_lshl_b64 s[2:3], s[0:1], 20
	s_add_u32 s6, s39, s2
	s_addc_u32 s3, s40, s3
	s_lshl_b32 s2, s45, 1
	s_and_b32 s7, s2, 0x1c0
	s_lshl_b32 s2, s45, 6
	s_and_b32 s2, s2, 0x7c0
	s_lshl_b32 s8, s2, 2
	s_add_u32 s4, s4, s8
	v_or_b32_e32 v2, s7, v69
	s_addc_u32 s5, s5, 0
	v_lshlrev_b32_e32 v168, 2, v68
	v_lshl_add_u64 v[0:1], s[4:5], 0, v[168:169]
	v_lshlrev_b32_e32 v168, 13, v2
	v_lshl_add_u64 v[60:61], v[0:1], 0, v[168:169]
	v_add_co_u32_e32 v4, vcc, s90, v60
	s_mov_b32 s4, 0x20000
	s_nop 0
	v_addc_co_u32_e32 v5, vcc, 0, v61, vcc
	v_add_co_u32_e32 v8, vcc, s88, v60
	global_load_dwordx4 v[0:3], v[60:61], off
	s_nop 0
	global_load_dwordx4 v[4:7], v[4:5], off
	v_addc_co_u32_e32 v9, vcc, 0, v61, vcc
	v_add_co_u32_e32 v12, vcc, s85, v60
	v_lshlrev_b32_e32 v168, 1, v70
	s_nop 0
	v_addc_co_u32_e32 v13, vcc, 0, v61, vcc
	global_load_dwordx4 v[8:11], v[8:9], off
	s_nop 0
	global_load_dwordx4 v[12:15], v[12:13], off
	v_add_co_u32_e32 v16, vcc, s4, v60
	s_mov_b32 s4, 0x28000
	s_nop 0
	v_addc_co_u32_e32 v17, vcc, 0, v61, vcc
	v_add_co_u32_e32 v20, vcc, s4, v60
	s_mov_b32 s4, 0x30000
	s_nop 0
	v_addc_co_u32_e32 v21, vcc, 0, v61, vcc
	global_load_dwordx4 v[16:19], v[16:17], off
	s_nop 0
	global_load_dwordx4 v[20:23], v[20:21], off
	v_add_co_u32_e32 v24, vcc, s4, v60
	s_mov_b32 s4, 0x38000
	s_nop 0
	v_addc_co_u32_e32 v25, vcc, 0, v61, vcc
	v_add_co_u32_e32 v28, vcc, s4, v60
	s_mov_b32 s4, 0x40000
	s_nop 0
	v_addc_co_u32_e32 v29, vcc, 0, v61, vcc
	global_load_dwordx4 v[24:27], v[24:25], off
	s_nop 0
	global_load_dwordx4 v[28:31], v[28:29], off
	v_add_co_u32_e32 v32, vcc, s4, v60
	s_mov_b32 s4, 0x48000
	s_nop 0
	v_addc_co_u32_e32 v33, vcc, 0, v61, vcc
	v_add_co_u32_e32 v36, vcc, s4, v60
	s_mov_b32 s4, 0x50000
	s_nop 0
	v_addc_co_u32_e32 v37, vcc, 0, v61, vcc
	global_load_dwordx4 v[32:35], v[32:33], off
	s_nop 0
	global_load_dwordx4 v[36:39], v[36:37], off
	v_add_co_u32_e32 v40, vcc, s4, v60
	s_mov_b32 s4, 0x58000
	s_nop 0
	v_addc_co_u32_e32 v41, vcc, 0, v61, vcc
	v_add_co_u32_e32 v44, vcc, s4, v60
	s_mov_b32 s4, 0x60000
	s_nop 0
	v_addc_co_u32_e32 v45, vcc, 0, v61, vcc
	global_load_dwordx4 v[40:43], v[40:41], off
	s_nop 0
	global_load_dwordx4 v[44:47], v[44:45], off
	v_add_co_u32_e32 v48, vcc, s4, v60
	s_mov_b32 s4, 0x68000
	s_nop 0
	v_addc_co_u32_e32 v49, vcc, 0, v61, vcc
	global_load_dwordx4 v[48:51], v[48:49], off
	v_add_co_u32_e32 v52, vcc, s4, v60
	s_mov_b32 s4, 0x70000
	s_nop 0
	v_addc_co_u32_e32 v53, vcc, 0, v61, vcc
	global_load_dwordx4 v[52:55], v[52:53], off
	v_add_co_u32_e32 v56, vcc, s4, v60
	s_mov_b32 s4, 0x78000
	s_nop 0
	v_addc_co_u32_e32 v57, vcc, 0, v61, vcc
	global_load_dwordx4 v[56:59], v[56:57], off
	v_add_co_u32_e32 v60, vcc, s4, v60
	s_lshl_b32 s4, s7, 1
	s_nop 0
	v_addc_co_u32_e32 v61, vcc, 0, v61, vcc
	global_load_dwordx4 v[60:63], v[60:61], off
	s_waitcnt vmcnt(0)
	ds_write2_b32 v71, v0, v1 offset1:1
	ds_write2_b32 v71, v2, v3 offset0:2 offset1:3
	v_add_u32_e32 v0, 0x410, v71
	s_waitcnt vmcnt(14)
	ds_write2_b32 v0, v4, v5 offset1:1
	v_add_u32_e32 v0, 0x418, v71
	ds_write2_b32 v0, v6, v7 offset1:1
	v_add_u32_e32 v0, 0x820, v71
	s_add_u32 s4, s6, s4
	s_addc_u32 s5, s3, 0
	s_waitcnt vmcnt(13)
	ds_write2_b32 v0, v8, v9 offset1:1
	v_add_u32_e32 v0, 0x828, v71
	ds_write2_b32 v0, v10, v11 offset1:1
	v_add_u32_e32 v0, 0xc30, v71
	s_waitcnt vmcnt(12)
	ds_write2_b32 v0, v12, v13 offset1:1
	v_add_u32_e32 v0, 0xc38, v71
	ds_write2_b32 v0, v14, v15 offset1:1
	v_add_u32_e32 v0, 0x1040, v71
	v_lshl_add_u64 v[4:5], s[4:5], 0, v[168:169]
	v_readlane_b32 s49, v253, 19
	v_readlane_b32 s50, v253, 20
	s_waitcnt vmcnt(11)
	ds_write2_b32 v0, v16, v17 offset1:1
	v_add_u32_e32 v0, 0x1048, v71
	ds_write2_b32 v0, v18, v19 offset1:1
	v_add_u32_e32 v0, 0x1450, v71
	s_waitcnt vmcnt(10)
	ds_write2_b32 v0, v20, v21 offset1:1
	v_add_u32_e32 v0, 0x1458, v71
	ds_write2_b32 v0, v22, v23 offset1:1
	v_add_u32_e32 v0, 0x1860, v71
	v_readlane_b32 s51, v253, 21
	v_readlane_b32 s52, v253, 22
	v_readlane_b32 s53, v253, 23
	s_waitcnt vmcnt(9)
	ds_write2_b32 v0, v24, v25 offset1:1
	v_add_u32_e32 v0, 0x1868, v71
	ds_write2_b32 v0, v26, v27 offset1:1
	v_add_u32_e32 v0, 0x1c70, v71
	s_waitcnt vmcnt(8)
	ds_write2_b32 v0, v28, v29 offset1:1
	v_add_u32_e32 v0, 0x1c78, v71
	ds_write2_b32 v0, v30, v31 offset1:1
	v_add_u32_e32 v0, 0x2080, v71
	v_readlane_b32 s54, v253, 24
	v_readlane_b32 s55, v253, 25
	v_readlane_b32 s56, v253, 26
	s_waitcnt vmcnt(7)
	ds_write2_b32 v0, v32, v33 offset1:1
	v_add_u32_e32 v0, 0x2088, v71
	ds_write2_b32 v0, v34, v35 offset1:1
	v_add_u32_e32 v0, 0x2490, v71
	s_waitcnt vmcnt(6)
	ds_write2_b32 v0, v36, v37 offset1:1
	v_add_u32_e32 v0, 0x2498, v71
	ds_write2_b32 v0, v38, v39 offset1:1
	v_add_u32_e32 v0, 0x28a0, v71
	v_readlane_b32 s57, v253, 27
	v_readlane_b32 s58, v253, 28
	v_readlane_b32 s59, v253, 29
	s_waitcnt vmcnt(5)
; __device__ __forceinline__ unsigned pk2(float lo, float hi) { unsigned r; asm("v_cvt_pk_bf16_f32 %0, %1, %2" : "=v"(r) : "v"(lo), "v"(hi)); return r; }
; __device__ __forceinline__ void p0_transpose_item(const float* W, int K, int N, bf16* WT, float* scr, int item, int lane, const float* scale, const float* cb, float* c1, float* c2) {
;     ...
;     const int c = lane & 7;
; #pragma unroll
;     for (int j = 0; j < 8; ++j) { const int n = (lane >> 3) + 8 * j; const float* sp = scr + (8 * c) * 65 + n;
;         v4u o; o.x = pk2(sp[0 * 65], sp[1 * 65]); o.y = pk2(sp[2 * 65], sp[3 * 65]); o.z = pk2(sp[4 * 65], sp[5 * 65]); o.w = pk2(sp[6 * 65], sp[7 * 65]);
;         *(v4u*)(WT + (size_t)(n0 + n) * K + k0 + 8 * c) = o; }
	ds_write2_b32 v0, v40, v41 offset1:1
	v_add_u32_e32 v0, 0x28a8, v71
	ds_write2_b32 v0, v42, v43 offset1:1
	v_add_u32_e32 v0, 0x2cb0, v71
	s_waitcnt vmcnt(4)
	ds_write2_b32 v0, v44, v45 offset1:1
	v_add_u32_e32 v0, 0x2cb8, v71
	ds_write2_b32 v0, v46, v47 offset1:1
	v_add_u32_e32 v0, 0x30c0, v71
	s_waitcnt vmcnt(3)
	ds_write2_b32 v0, v48, v49 offset1:1
	v_add_u32_e32 v0, 0x30c8, v71
	ds_write2_b32 v0, v50, v51 offset1:1
	v_add_u32_e32 v0, 0x34d0, v71
	v_readlane_b32 s60, v253, 30
	s_waitcnt vmcnt(2)
	ds_write2_b32 v0, v52, v53 offset1:1
	v_add_u32_e32 v0, 0x34d8, v71
	ds_write2_b32 v0, v54, v55 offset1:1
	v_add_u32_e32 v0, 0x38e0, v71
	v_readlane_b32 s61, v253, 31
	s_waitcnt vmcnt(1)
	ds_write2_b32 v0, v56, v57 offset1:1
	v_add_u32_e32 v0, 0x38e8, v71
	ds_write2_b32 v0, v58, v59 offset1:1
	v_add_u32_e32 v0, 0x3cf0, v71
	s_waitcnt vmcnt(0)
	ds_write2_b32 v0, v60, v61 offset1:1
	v_add_u32_e32 v0, 0x3cf8, v71
	ds_write2_b32 v0, v62, v63 offset1:1
	s_waitcnt lgkmcnt(0)
	ds_read_b32 v0, v81
	ds_read_b32 v1, v81 offset:260
	ds_read_b32 v2, v81 offset:520
	ds_read_b32 v3, v81 offset:780
	ds_read_b32 v6, v81 offset:1040
	ds_read_b32 v7, v81 offset:1300
	ds_read_b32 v8, v81 offset:1560
	ds_read_b32 v9, v81 offset:1820
	s_waitcnt lgkmcnt(6)
	v_cvt_pk_bf16_f32 v0, v0, v1
	s_waitcnt lgkmcnt(4)
	v_cvt_pk_bf16_f32 v1, v2, v3
	s_waitcnt lgkmcnt(2)
	v_cvt_pk_bf16_f32 v2, v6, v7
	v_or_b32_e32 v6, s2, v80
	v_lshlrev_b32_e32 v168, 9, v6
	v_lshl_add_u64 v[6:7], v[4:5], 0, v[168:169]
	s_waitcnt lgkmcnt(0)
	v_cvt_pk_bf16_f32 v3, v8, v9
	global_store_dwordx4 v[6:7], v[0:3], off
	ds_read_b32 v0, v81 offset:32
	ds_read_b32 v1, v81 offset:292
	ds_read_b32 v2, v81 offset:552
	ds_read_b32 v3, v81 offset:812
	ds_read_b32 v6, v81 offset:1072
	ds_read_b32 v7, v81 offset:1332
	ds_read_b32 v8, v81 offset:1592
	ds_read_b32 v9, v81 offset:1852
	s_waitcnt lgkmcnt(0)
	v_cvt_pk_bf16_f32 v0, v0, v1
	v_cvt_pk_bf16_f32 v1, v2, v3
	v_cvt_pk_bf16_f32 v2, v6, v7
	v_or_b32_e32 v6, s2, v82
	v_lshlrev_b32_e32 v168, 9, v6
	v_lshl_add_u64 v[6:7], v[4:5], 0, v[168:169]
	v_cvt_pk_bf16_f32 v3, v8, v9
	global_store_dwordx4 v[6:7], v[0:3], off
	ds_read_b32 v0, v81 offset:64
	ds_read_b32 v1, v81 offset:324
	ds_read_b32 v2, v81 offset:584
	ds_read_b32 v3, v81 offset:844
	ds_read_b32 v6, v81 offset:1104
	ds_read_b32 v7, v81 offset:1364
	ds_read_b32 v8, v81 offset:1624
	ds_read_b32 v9, v81 offset:1884
	s_waitcnt lgkmcnt(0)
	v_cvt_pk_bf16_f32 v0, v0, v1
	v_cvt_pk_bf16_f32 v1, v2, v3
	v_cvt_pk_bf16_f32 v2, v6, v7
	v_or_b32_e32 v6, s2, v83
	v_lshlrev_b32_e32 v168, 9, v6
	v_lshl_add_u64 v[6:7], v[4:5], 0, v[168:169]
	v_cvt_pk_bf16_f32 v3, v8, v9
	global_store_dwordx4 v[6:7], v[0:3], off
	ds_read_b32 v0, v81 offset:96
	ds_read_b32 v1, v81 offset:356
	ds_read_b32 v2, v81 offset:616
	ds_read_b32 v3, v81 offset:876
	ds_read_b32 v6, v81 offset:1136
	ds_read_b32 v7, v81 offset:1396
	ds_read_b32 v8, v81 offset:1656
	ds_read_b32 v9, v81 offset:1916
	s_waitcnt lgkmcnt(0)
	v_cvt_pk_bf16_f32 v0, v0, v1
	v_cvt_pk_bf16_f32 v1, v2, v3
	v_cvt_pk_bf16_f32 v2, v6, v7
	v_or_b32_e32 v6, s2, v84
	v_lshlrev_b32_e32 v168, 9, v6
	v_lshl_add_u64 v[6:7], v[4:5], 0, v[168:169]
	v_cvt_pk_bf16_f32 v3, v8, v9
	global_store_dwordx4 v[6:7], v[0:3], off
	ds_read_b32 v0, v81 offset:128
	ds_read_b32 v1, v81 offset:388
	ds_read_b32 v2, v81 offset:648
	ds_read_b32 v3, v81 offset:908
	ds_read_b32 v6, v81 offset:1168
	ds_read_b32 v7, v81 offset:1428
	ds_read_b32 v8, v81 offset:1688
	ds_read_b32 v9, v81 offset:1948
	s_waitcnt lgkmcnt(0)
	v_cvt_pk_bf16_f32 v0, v0, v1
	v_cvt_pk_bf16_f32 v1, v2, v3
	v_cvt_pk_bf16_f32 v2, v6, v7
	v_or_b32_e32 v6, s2, v85
	v_lshlrev_b32_e32 v168, 9, v6
	v_lshl_add_u64 v[6:7], v[4:5], 0, v[168:169]
	v_cvt_pk_bf16_f32 v3, v8, v9
	global_store_dwordx4 v[6:7], v[0:3], off
	ds_read_b32 v0, v81 offset:160
	ds_read_b32 v1, v81 offset:420
	ds_read_b32 v2, v81 offset:680
	ds_read_b32 v3, v81 offset:940
	ds_read_b32 v6, v81 offset:1200
	ds_read_b32 v7, v81 offset:1460
	ds_read_b32 v8, v81 offset:1720
	ds_read_b32 v9, v81 offset:1980
	s_waitcnt lgkmcnt(0)
	v_cvt_pk_bf16_f32 v0, v0, v1
	v_cvt_pk_bf16_f32 v1, v2, v3
	v_cvt_pk_bf16_f32 v2, v6, v7
	v_or_b32_e32 v6, s2, v86
	v_lshlrev_b32_e32 v168, 9, v6
	v_lshl_add_u64 v[6:7], v[4:5], 0, v[168:169]
	v_cvt_pk_bf16_f32 v3, v8, v9
	global_store_dwordx4 v[6:7], v[0:3], off
	ds_read_b32 v0, v81 offset:192
	ds_read_b32 v1, v81 offset:452
	ds_read_b32 v2, v81 offset:712
	ds_read_b32 v3, v81 offset:972
	ds_read_b32 v6, v81 offset:1232
	ds_read_b32 v7, v81 offset:1492
	ds_read_b32 v8, v81 offset:1752
	ds_read_b32 v9, v81 offset:2012
	s_waitcnt lgkmcnt(0)
	v_cvt_pk_bf16_f32 v0, v0, v1
	v_cvt_pk_bf16_f32 v1, v2, v3
	v_cvt_pk_bf16_f32 v2, v6, v7
	v_or_b32_e32 v6, s2, v87
	v_lshlrev_b32_e32 v168, 9, v6
	v_lshl_add_u64 v[6:7], v[4:5], 0, v[168:169]
	v_cvt_pk_bf16_f32 v3, v8, v9
	global_store_dwordx4 v[6:7], v[0:3], off
	ds_read_b32 v0, v81 offset:224
	ds_read_b32 v1, v81 offset:484
	ds_read_b32 v2, v81 offset:744
	ds_read_b32 v3, v81 offset:1004
	ds_read_b32 v6, v81 offset:1264
	ds_read_b32 v7, v81 offset:1524
	ds_read_b32 v8, v81 offset:1784
	ds_read_b32 v9, v81 offset:2044
	s_waitcnt lgkmcnt(0)
	v_cvt_pk_bf16_f32 v0, v0, v1
	v_cvt_pk_bf16_f32 v1, v2, v3
	v_cvt_pk_bf16_f32 v2, v6, v7
	v_or_b32_e32 v6, s2, v88
	v_lshlrev_b32_e32 v168, 9, v6
	v_lshl_add_u64 v[4:5], v[4:5], 0, v[168:169]
	v_cvt_pk_bf16_f32 v3, v8, v9
	global_store_dwordx4 v[4:5], v[0:3], off
	s_waitcnt lgkmcnt(0)
	s_mov_b64 s[2:3], 0

; __device__ __forceinline__ unsigned pk2(float lo, float hi) { unsigned r; asm("v_cvt_pk_bf16_f32 %0, %1, %2" : "=v"(r) : "v"(lo), "v"(hi)); return r; }
; __device__ __forceinline__ unsigned f2bf(float f) { return pk2(f, 0.f) & 0xffffu; }
; __device__ __forceinline__ void p0_transpose_item(const float* W, int K, int N, bf16* WT, float* scr, int item, int lane, const float* scale, const float* cb, float* c1, float* c2) {
;     ...
;     const int c = lane & 7;
; #pragma unroll
;     for (int j = 0; j < 8; ++j) { const int n = (lane >> 3) + 8 * j; const float* sp = scr + (8 * c) * 65 + n;
;         v4u o; o.x = pk2(sp[0 * 65], sp[1 * 65]); o.y = pk2(sp[2 * 65], sp[3 * 65]); o.z = pk2(sp[4 * 65], sp[5 * 65]); o.w = pk2(sp[6 * 65], sp[7 * 65]);
;         *(v4u*)(WT + (size_t)(n0 + n) * K + k0 + 8 * c) = o; }
;     if (c1) { float a1 = 0.f, a2 = 0.f;
;         for (int kk = 0; kk < 64; ++kk) { a1 += __uint_as_float(f2bf(scr[kk * 65 + lane]) << 16); a2 += cb[k0 + kk] * W[(size_t)(k0 + kk) * N + n0 + lane]; }
.LBB0_1012:
	v_add_u32_e32 v0, 0x34d0, v90
	ds_write2_b32 v0, v14, v15 offset1:1
	v_add_u32_e32 v0, 0x34d8, v90
	ds_write2_b32 v0, v12, v13 offset1:1
	v_add_u32_e32 v0, 0x38e0, v90
	ds_write2_b32 v0, v8, v9 offset1:1
	v_add_u32_e32 v0, 0x38e8, v90
	ds_write2_b32 v0, v10, v11 offset1:1
	s_waitcnt lgkmcnt(0)
	ds_read_b32 v2, v81
	ds_read_b32 v3, v81 offset:260
	s_lshl_b64 s[4:5], s[0:1], 22
	s_waitcnt lgkmcnt(0)
	v_cvt_pk_bf16_f32 v2, v2, v3
	ds_read_b32 v3, v81 offset:520
	ds_read_b32 v4, v81 offset:780
	s_waitcnt lgkmcnt(0)
	v_cvt_pk_bf16_f32 v3, v3, v4
	ds_read_b32 v4, v81 offset:1040
	ds_read_b32 v5, v81 offset:1300
	s_waitcnt lgkmcnt(0)
	v_cvt_pk_bf16_f32 v4, v4, v5
	ds_read_b32 v5, v81 offset:1560
	ds_read_b32 v6, v81 offset:1820
	s_lshl_b64 s[4:5], s[4:5], 1
	s_add_u32 s1, s37, s4
	s_addc_u32 s5, s38, s5
	s_lshl_b32 s4, s48, 1
	s_add_u32 s4, s1, s4
	s_addc_u32 s5, s5, 0
	v_lshlrev_b32_e32 v168, 1, v70
	s_waitcnt lgkmcnt(0)
	v_cvt_pk_bf16_f32 v5, v5, v6
	v_or_b32_e32 v6, s49, v80
	v_lshl_add_u64 v[0:1], s[4:5], 0, v[168:169]
	v_lshlrev_b32_e32 v168, 12, v6
	v_lshl_add_u64 v[6:7], v[0:1], 0, v[168:169]
	global_store_dwordx4 v[6:7], v[2:5], off
	ds_read_b32 v2, v81 offset:32
	ds_read_b32 v3, v81 offset:292
	s_waitcnt lgkmcnt(0)
	v_cvt_pk_bf16_f32 v2, v2, v3
	ds_read_b32 v3, v81 offset:552
	ds_read_b32 v4, v81 offset:812
	s_waitcnt lgkmcnt(0)
	v_cvt_pk_bf16_f32 v3, v3, v4
	ds_read_b32 v4, v81 offset:1072
	ds_read_b32 v5, v81 offset:1332
	s_waitcnt lgkmcnt(0)
	v_cvt_pk_bf16_f32 v4, v4, v5
	ds_read_b32 v5, v81 offset:1592
	ds_read_b32 v6, v81 offset:1852
	s_waitcnt lgkmcnt(0)
	v_cvt_pk_bf16_f32 v5, v5, v6
	v_or_b32_e32 v6, s49, v82
	v_lshlrev_b32_e32 v168, 12, v6
	v_lshl_add_u64 v[6:7], v[0:1], 0, v[168:169]
	global_store_dwordx4 v[6:7], v[2:5], off
	ds_read_b32 v2, v81 offset:64
	ds_read_b32 v3, v81 offset:324
	s_waitcnt lgkmcnt(0)
	v_cvt_pk_bf16_f32 v2, v2, v3
	ds_read_b32 v3, v81 offset:584
	ds_read_b32 v4, v81 offset:844
	s_waitcnt lgkmcnt(0)
	v_cvt_pk_bf16_f32 v3, v3, v4
	ds_read_b32 v4, v81 offset:1104
	ds_read_b32 v5, v81 offset:1364
	s_waitcnt lgkmcnt(0)
	v_cvt_pk_bf16_f32 v4, v4, v5
	ds_read_b32 v5, v81 offset:1624
	ds_read_b32 v6, v81 offset:1884
	s_waitcnt lgkmcnt(0)
	v_cvt_pk_bf16_f32 v5, v5, v6
	v_or_b32_e32 v6, s49, v83
	v_lshlrev_b32_e32 v168, 12, v6
	v_lshl_add_u64 v[6:7], v[0:1], 0, v[168:169]
	global_store_dwordx4 v[6:7], v[2:5], off
	ds_read_b32 v2, v81 offset:96
	ds_read_b32 v3, v81 offset:356
	s_waitcnt lgkmcnt(0)
	v_cvt_pk_bf16_f32 v2, v2, v3
	ds_read_b32 v3, v81 offset:616
	ds_read_b32 v4, v81 offset:876
	s_waitcnt lgkmcnt(0)
	v_cvt_pk_bf16_f32 v3, v3, v4
	ds_read_b32 v4, v81 offset:1136
	ds_read_b32 v5, v81 offset:1396
	s_waitcnt lgkmcnt(0)
	v_cvt_pk_bf16_f32 v4, v4, v5
	ds_read_b32 v5, v81 offset:1656
	ds_read_b32 v6, v81 offset:1916
	s_waitcnt lgkmcnt(0)
	v_cvt_pk_bf16_f32 v5, v5, v6
	v_or_b32_e32 v6, s49, v84
	v_lshlrev_b32_e32 v168, 12, v6
	v_lshl_add_u64 v[6:7], v[0:1], 0, v[168:169]
	global_store_dwordx4 v[6:7], v[2:5], off
	ds_read_b32 v2, v81 offset:128
	ds_read_b32 v3, v81 offset:388
	s_waitcnt lgkmcnt(0)
	v_cvt_pk_bf16_f32 v2, v2, v3
	ds_read_b32 v3, v81 offset:648
	ds_read_b32 v4, v81 offset:908
	s_waitcnt lgkmcnt(0)
	v_cvt_pk_bf16_f32 v3, v3, v4
	ds_read_b32 v4, v81 offset:1168
	ds_read_b32 v5, v81 offset:1428
	s_waitcnt lgkmcnt(0)
	v_cvt_pk_bf16_f32 v4, v4, v5
	ds_read_b32 v5, v81 offset:1688
	ds_read_b32 v6, v81 offset:1948
	s_waitcnt lgkmcnt(0)
	v_cvt_pk_bf16_f32 v5, v5, v6
	v_or_b32_e32 v6, s49, v85
	v_lshlrev_b32_e32 v168, 12, v6
	v_lshl_add_u64 v[6:7], v[0:1], 0, v[168:169]
	global_store_dwordx4 v[6:7], v[2:5], off
	ds_read_b32 v2, v81 offset:160
	ds_read_b32 v3, v81 offset:420
	s_waitcnt lgkmcnt(0)
	v_cvt_pk_bf16_f32 v2, v2, v3
	ds_read_b32 v3, v81 offset:680
	ds_read_b32 v4, v81 offset:940
	s_waitcnt lgkmcnt(0)
	v_cvt_pk_bf16_f32 v3, v3, v4
	ds_read_b32 v4, v81 offset:1200
	ds_read_b32 v5, v81 offset:1460
	s_waitcnt lgkmcnt(0)
	v_cvt_pk_bf16_f32 v4, v4, v5
	ds_read_b32 v5, v81 offset:1720
	ds_read_b32 v6, v81 offset:1980
	s_waitcnt lgkmcnt(0)
	v_cvt_pk_bf16_f32 v5, v5, v6
	v_or_b32_e32 v6, s49, v86
	v_lshlrev_b32_e32 v168, 12, v6
	v_lshl_add_u64 v[6:7], v[0:1], 0, v[168:169]
	global_store_dwordx4 v[6:7], v[2:5], off
	ds_read_b32 v2, v81 offset:192
	ds_read_b32 v3, v81 offset:452
	s_waitcnt lgkmcnt(0)
	v_cvt_pk_bf16_f32 v2, v2, v3
	ds_read_b32 v3, v81 offset:712
	ds_read_b32 v4, v81 offset:972
	s_waitcnt lgkmcnt(0)
	v_cvt_pk_bf16_f32 v3, v3, v4
	ds_read_b32 v4, v81 offset:1232
	ds_read_b32 v5, v81 offset:1492
	s_waitcnt lgkmcnt(0)
	v_cvt_pk_bf16_f32 v4, v4, v5
	ds_read_b32 v5, v81 offset:1752
	ds_read_b32 v6, v81 offset:2012
	s_waitcnt lgkmcnt(0)
	v_cvt_pk_bf16_f32 v5, v5, v6
	v_or_b32_e32 v6, s49, v87
	v_lshlrev_b32_e32 v168, 12, v6
	v_lshl_add_u64 v[6:7], v[0:1], 0, v[168:169]
	global_store_dwordx4 v[6:7], v[2:5], off
	ds_read_b32 v2, v81 offset:224
	ds_read_b32 v3, v81 offset:484
	s_waitcnt lgkmcnt(0)
	v_cvt_pk_bf16_f32 v2, v2, v3
	ds_read_b32 v3, v81 offset:744
	ds_read_b32 v4, v81 offset:1004
	s_waitcnt lgkmcnt(0)
	v_cvt_pk_bf16_f32 v3, v3, v4
	ds_read_b32 v4, v81 offset:1264
	ds_read_b32 v5, v81 offset:1524
	s_waitcnt lgkmcnt(0)
	v_cvt_pk_bf16_f32 v4, v4, v5
	ds_read_b32 v5, v81 offset:1784
	ds_read_b32 v6, v81 offset:2044
	s_lshl_b32 s1, s47, 13
	s_and_b32 s1, s1, 0x3ff80000
	s_add_u32 s1, s6, s1
	s_addc_u32 s5, s7, 0
	s_and_b32 s4, s45, 31
	s_lshl_b32 s4, s4, 8
	s_waitcnt lgkmcnt(0)
	v_cvt_pk_bf16_f32 v5, v5, v6
	v_or_b32_e32 v6, s49, v88
	s_or_b32 s4, s1, s4
	s_lshl_b32 s1, s48, 2
	v_readlane_b32 s48, v253, 18
	v_lshlrev_b32_e32 v168, 12, v6
	v_readlane_b32 s60, v253, 30
	v_lshl_add_u64 v[0:1], v[0:1], 0, v[168:169]
	v_readlane_b32 s61, v253, 31
	s_add_u32 s1, s60, s1
	global_store_dwordx4 v[0:1], v[2:5], off
	v_lshl_add_u64 v[0:1], v[72:73], 0, s[4:5]
	s_addc_u32 s8, s61, 0
	s_lshl_b32 s4, s47, 2
	s_and_b32 s4, s4, 0x7ff00
	s_add_u32 s9, s60, s4
	v_mov_b32_e32 v2, 0
	s_addc_u32 s14, s61, 0
	s_mov_b64 s[4:5], 0
	v_mov_b32_e32 v6, v89
	v_mov_b32_e32 v3, v2
	v_readlane_b32 s49, v253, 19
	v_readlane_b32 s50, v253, 20
	v_readlane_b32 s51, v253, 21
	v_readlane_b32 s52, v253, 22
	v_readlane_b32 s53, v253, 23
	v_readlane_b32 s54, v253, 24
	v_readlane_b32 s55, v253, 25
	v_readlane_b32 s56, v253, 26
	v_readlane_b32 s57, v253, 27
	v_readlane_b32 s58, v253, 28
	v_readlane_b32 s59, v253, 29
	v_readlane_b32 s62, v253, 32
	v_readlane_b32 s63, v253, 33
; __device__ __forceinline__ unsigned f2bf(float f) { return pk2(f, 0.f) & 0xffffu; }
; __device__ __forceinline__ void p0_transpose_item(const float* W, int K, int N, bf16* WT, float* scr, int item, int lane, const float* scale, const float* cb, float* c1, float* c2) {
;     ...
;     if (c1) { float a1 = 0.f, a2 = 0.f;
;         for (int kk = 0; kk < 64; ++kk) { a1 += __uint_as_float(f2bf(scr[kk * 65 + lane]) << 16); a2 += cb[k0 + kk] * W[(size_t)(k0 + kk) * N + n0 + lane]; }
;         atomicAdd(c1 + n0 + lane, a1); atomicAdd(c2 + n0 + lane, a2); }
.LBB0_1013:
	ds_read2_b32 v[8:9], v6 offset1:65
	s_waitcnt lgkmcnt(0)
	v_cvt_pk_bf16_f32 v4, v8, v169
	s_add_u32 s6, s9, s2
	v_lshlrev_b32_e32 v11, 16, v4
	s_addc_u32 s7, s14, s3
	v_lshl_add_u64 v[4:5], v[0:1], 0, s[4:5]
	global_load_dword v7, v169, s[6:7]
	global_load_dword v8, v[4:5], off
	s_add_u32 s6, s1, s2
	v_add_co_u32_e32 v14, vcc, s69, v4
	s_addc_u32 s7, s8, s3
	s_nop 0
	v_addc_co_u32_e32 v15, vcc, 0, v5, vcc
	v_add_co_u32_e32 v16, vcc, s89, v4
	s_add_u32 s4, s4, 0x10000
	s_nop 0
	v_addc_co_u32_e32 v17, vcc, 0, v5, vcc
	s_addc_u32 s5, s5, 0
	s_add_u32 s1, s1, 32
	s_addc_u32 s8, s8, 0
	s_add_u32 s9, s9, 32
	s_addc_u32 s14, s14, 0
	s_cmp_lg_u32 s4, 0x80000
	s_waitcnt vmcnt(0)
	v_mul_f32_e32 v10, v7, v8
	v_cvt_pk_bf16_f32 v7, v9, v169
	v_pk_add_f32 v[2:3], v[2:3], v[10:11]
	v_lshlrev_b32_e32 v13, 16, v7
	global_load_dwordx4 v[8:11], v169, s[6:7] offset:4
	global_load_dword v7, v[14:15], off
	s_waitcnt vmcnt(0)
	v_mul_f32_e32 v12, v8, v7
	v_pk_add_f32 v[2:3], v[2:3], v[12:13]
	ds_read2_b32 v[12:13], v6 offset0:130 offset1:195
	s_waitcnt lgkmcnt(0)
	v_cvt_pk_bf16_f32 v7, v12, v169
	v_add_co_u32_e32 v12, vcc, s84, v4
	v_lshlrev_b32_e32 v15, 16, v7
	global_load_dword v7, v[16:17], off
	s_waitcnt vmcnt(0)
	v_mul_f32_e32 v14, v9, v7
	v_cvt_pk_bf16_f32 v7, v13, v169
	v_addc_co_u32_e32 v13, vcc, 0, v5, vcc
	v_lshlrev_b32_e32 v9, 16, v7
	global_load_dword v7, v[12:13], off
	v_pk_add_f32 v[2:3], v[2:3], v[14:15]
	v_add_co_u32_e32 v14, vcc, s90, v4
	s_waitcnt vmcnt(0)
	v_mul_f32_e32 v8, v10, v7
	v_add_u32_e32 v7, 0x400, v6
	v_pk_add_f32 v[2:3], v[2:3], v[8:9]
	ds_read2_b32 v[8:9], v7 offset0:4 offset1:69
	s_waitcnt lgkmcnt(0)
	v_cvt_pk_bf16_f32 v8, v8, v169
	v_addc_co_u32_e32 v15, vcc, 0, v5, vcc
	v_lshlrev_b32_e32 v13, 16, v8
	global_load_dword v8, v[14:15], off
	v_add_co_u32_e32 v14, vcc, s70, v4
	v_add_u32_e32 v6, 0x820, v6
	s_nop 0
	v_addc_co_u32_e32 v15, vcc, 0, v5, vcc
	v_add_co_u32_e32 v16, vcc, s91, v4
	s_waitcnt vmcnt(0)
	v_mul_f32_e32 v12, v11, v8
	v_cvt_pk_bf16_f32 v8, v9, v169
	v_pk_add_f32 v[2:3], v[2:3], v[12:13]
	v_lshlrev_b32_e32 v13, 16, v8
	global_load_dwordx3 v[8:10], v169, s[6:7] offset:20
	global_load_dword v11, v[14:15], off
	v_addc_co_u32_e32 v17, vcc, 0, v5, vcc
	v_add_co_u32_e32 v4, vcc, s71, v4
	s_waitcnt vmcnt(0)
	v_mul_f32_e32 v12, v8, v11
	v_pk_add_f32 v[2:3], v[2:3], v[12:13]
	ds_read2_b32 v[12:13], v7 offset0:134 offset1:199
	s_waitcnt lgkmcnt(0)
	v_cvt_pk_bf16_f32 v7, v12, v169
	v_addc_co_u32_e32 v5, vcc, 0, v5, vcc
	v_lshlrev_b32_e32 v15, 16, v7
	global_load_dword v7, v[16:17], off
	s_waitcnt vmcnt(0)
	v_mul_f32_e32 v14, v9, v7
	global_load_dword v4, v[4:5], off
	v_pk_add_f32 v[2:3], v[2:3], v[14:15]
	v_cvt_pk_bf16_f32 v7, v13, v169
	s_waitcnt vmcnt(0)
	v_mul_f32_e32 v8, v10, v4
	v_lshlrev_b32_e32 v9, 16, v7
	v_pk_add_f32 v[2:3], v[2:3], v[8:9]
	s_cbranch_scc1 .LBB0_1013
	s_add_u32 s1, s41, s2
	s_addc_u32 s4, s42, s3
	s_add_u32 s5, s43, s2
	s_addc_u32 s6, s44, s3
	s_add_u32 s2, s1, s46
	s_addc_u32 s3, s4, 0
	v_mov_b32_e32 v75, v169
	v_lshl_add_u64 v[0:1], s[2:3], 0, v[74:75]
	s_add_u32 s2, s5, s46
	s_addc_u32 s3, s6, 0
	global_atomic_add_f32 v[0:1], v3, off
	v_lshl_add_u64 v[0:1], s[2:3], 0, v[74:75]
	global_atomic_add_f32 v[0:1], v2, off
	s_waitcnt lgkmcnt(0)

; #define LDS_WAIT() asm volatile("s_waitcnt lgkmcnt(0)" ::: "memory")
; __device__ __forceinline__ void p0_transpose_item(const float* W, int K, int N, bf16* WT, float* scr, int item, int lane, const float* scale, const float* cb, float* c1, float* c2) {
;     const int nblk = N / 64, kb = item / nblk, nb = item % nblk, k0 = 64 * kb, n0 = 64 * nb;
;     const int lr = lane >> 4, lc = (lane & 15) * 4;
;     f32x4 v[16];
; #pragma unroll
;     for (int i = 0; i < 16; ++i) v[i] = *(const f32x4*)(W + (size_t)(k0 + 4 * i + lr) * N + n0 + lc);
; #pragma unroll
;     for (int i = 0; i < 16; ++i) { const int kk = 4 * i + lr; f32x4 w = v[i]; if (scale) w = w * scale[k0 + kk]; float* d = scr + kk * 65 + lc; d[0] = w[0]; d[1] = w[1]; d[2] = w[2]; d[3] = w[3]; }
;     LDS_WAIT(); asm volatile("" ::: "memory");
.LBB0_1016:
	s_andn2_b64 vcc, exec, s[2:3]
	s_cbranch_vccnz .LBB0_1018
	s_ashr_i32 s1, s0, 31
	v_readlane_b32 s48, v253, 18
	s_lshl_b64 s[2:3], s[0:1], 24
	v_readlane_b32 s56, v253, 26
	v_readlane_b32 s57, v253, 27
	s_add_u32 s4, s56, s2
	s_addc_u32 s5, s57, s3
	s_lshl_b64 s[2:3], s[0:1], 23
	s_add_u32 s6, s27, s2
	s_addc_u32 s7, s36, s3
	s_lshl_b32 s1, s45, 1
	s_add_i32 s1, s1, 0x1e200
	s_and_b32 s8, s1, 0x1ffc0
	s_lshl_b32 s1, s45, 6
	s_and_b32 s1, s1, 0x7c0
	s_lshl_b32 s2, s1, 2
	s_add_u32 s2, s4, s2
	v_or_b32_e32 v2, s8, v69
	s_addc_u32 s3, s5, 0
	v_lshlrev_b32_e32 v168, 2, v68
	v_lshl_add_u64 v[0:1], s[2:3], 0, v[168:169]
	v_lshlrev_b32_e32 v168, 13, v2
	v_lshl_add_u64 v[60:61], v[0:1], 0, v[168:169]
	v_add_co_u32_e32 v4, vcc, s90, v60
	s_mov_b32 s2, 0x20000
	s_nop 0
	v_addc_co_u32_e32 v5, vcc, 0, v61, vcc
	v_add_co_u32_e32 v8, vcc, s88, v60
	global_load_dwordx4 v[0:3], v[60:61], off
	s_nop 0
	global_load_dwordx4 v[4:7], v[4:5], off
	v_addc_co_u32_e32 v9, vcc, 0, v61, vcc
	v_add_co_u32_e32 v12, vcc, s85, v60
	v_lshlrev_b32_e32 v168, 1, v70
	s_nop 0
	v_addc_co_u32_e32 v13, vcc, 0, v61, vcc
	global_load_dwordx4 v[8:11], v[8:9], off
	s_nop 0
	global_load_dwordx4 v[12:15], v[12:13], off
	v_add_co_u32_e32 v16, vcc, s2, v60
	s_mov_b32 s2, 0x28000
	s_nop 0
	v_addc_co_u32_e32 v17, vcc, 0, v61, vcc
	v_add_co_u32_e32 v20, vcc, s2, v60
	s_mov_b32 s2, 0x30000
	s_nop 0
	v_addc_co_u32_e32 v21, vcc, 0, v61, vcc
	global_load_dwordx4 v[16:19], v[16:17], off
	s_nop 0
	global_load_dwordx4 v[20:23], v[20:21], off
	v_add_co_u32_e32 v24, vcc, s2, v60
	s_mov_b32 s2, 0x38000
	s_nop 0
	v_addc_co_u32_e32 v25, vcc, 0, v61, vcc
	v_add_co_u32_e32 v28, vcc, s2, v60
	s_mov_b32 s2, 0x40000
	s_nop 0
	v_addc_co_u32_e32 v29, vcc, 0, v61, vcc
	global_load_dwordx4 v[24:27], v[24:25], off
	s_nop 0
	global_load_dwordx4 v[28:31], v[28:29], off
	v_add_co_u32_e32 v32, vcc, s2, v60
	s_mov_b32 s2, 0x48000
	s_nop 0
	v_addc_co_u32_e32 v33, vcc, 0, v61, vcc
	v_add_co_u32_e32 v36, vcc, s2, v60
	s_mov_b32 s2, 0x50000
	s_nop 0
	v_addc_co_u32_e32 v37, vcc, 0, v61, vcc
	global_load_dwordx4 v[32:35], v[32:33], off
	s_nop 0
	global_load_dwordx4 v[36:39], v[36:37], off
	v_add_co_u32_e32 v40, vcc, s2, v60
	s_mov_b32 s2, 0x58000
	s_nop 0
	v_addc_co_u32_e32 v41, vcc, 0, v61, vcc
	v_add_co_u32_e32 v44, vcc, s2, v60
	s_mov_b32 s2, 0x60000
	s_nop 0
	v_addc_co_u32_e32 v45, vcc, 0, v61, vcc
	global_load_dwordx4 v[40:43], v[40:41], off
	s_nop 0
	global_load_dwordx4 v[44:47], v[44:45], off
	v_add_co_u32_e32 v48, vcc, s2, v60
	s_mov_b32 s2, 0x68000
	s_nop 0
	v_addc_co_u32_e32 v49, vcc, 0, v61, vcc
	global_load_dwordx4 v[48:51], v[48:49], off
	v_add_co_u32_e32 v52, vcc, s2, v60
	s_mov_b32 s2, 0x70000
	s_nop 0
	v_addc_co_u32_e32 v53, vcc, 0, v61, vcc
	global_load_dwordx4 v[52:55], v[52:53], off
	v_add_co_u32_e32 v56, vcc, s2, v60
	s_mov_b32 s2, 0x78000
	s_nop 0
	v_addc_co_u32_e32 v57, vcc, 0, v61, vcc
	global_load_dwordx4 v[56:59], v[56:57], off
	v_add_co_u32_e32 v60, vcc, s2, v60
	s_lshl_b32 s2, s8, 1
	s_nop 0
	v_addc_co_u32_e32 v61, vcc, 0, v61, vcc
	global_load_dwordx4 v[60:63], v[60:61], off
	s_waitcnt vmcnt(0)
	ds_write2_b32 v71, v0, v1 offset1:1
	ds_write2_b32 v71, v2, v3 offset0:2 offset1:3
	v_add_u32_e32 v0, 0x410, v71
	ds_write2_b32 v0, v4, v5 offset1:1
	v_add_u32_e32 v0, 0x418, v71
	ds_write2_b32 v0, v6, v7 offset1:1
	v_add_u32_e32 v0, 0x820, v71
	s_add_u32 s2, s6, s2
	s_addc_u32 s3, s7, 0
	ds_write2_b32 v0, v8, v9 offset1:1
	v_add_u32_e32 v0, 0x828, v71
	ds_write2_b32 v0, v10, v11 offset1:1
	v_add_u32_e32 v0, 0xc30, v71
	ds_write2_b32 v0, v12, v13 offset1:1
	v_add_u32_e32 v0, 0xc38, v71
	ds_write2_b32 v0, v14, v15 offset1:1
	v_add_u32_e32 v0, 0x1040, v71
	v_lshl_add_u64 v[4:5], s[2:3], 0, v[168:169]
	v_readlane_b32 s49, v253, 19
	v_readlane_b32 s50, v253, 20
	ds_write2_b32 v0, v16, v17 offset1:1
	v_add_u32_e32 v0, 0x1048, v71
	ds_write2_b32 v0, v18, v19 offset1:1
	v_add_u32_e32 v0, 0x1450, v71
	ds_write2_b32 v0, v20, v21 offset1:1
	v_add_u32_e32 v0, 0x1458, v71
	ds_write2_b32 v0, v22, v23 offset1:1
	v_add_u32_e32 v0, 0x1860, v71
	v_readlane_b32 s51, v253, 21
	v_readlane_b32 s52, v253, 22
	v_readlane_b32 s53, v253, 23
	ds_write2_b32 v0, v24, v25 offset1:1
	v_add_u32_e32 v0, 0x1868, v71
	ds_write2_b32 v0, v26, v27 offset1:1
	v_add_u32_e32 v0, 0x1c70, v71
	ds_write2_b32 v0, v28, v29 offset1:1
	v_add_u32_e32 v0, 0x1c78, v71
	ds_write2_b32 v0, v30, v31 offset1:1
	v_add_u32_e32 v0, 0x2080, v71
	v_readlane_b32 s54, v253, 24
	v_readlane_b32 s55, v253, 25
	v_readlane_b32 s58, v253, 28
	ds_write2_b32 v0, v32, v33 offset1:1
	v_add_u32_e32 v0, 0x2088, v71
	ds_write2_b32 v0, v34, v35 offset1:1
	v_add_u32_e32 v0, 0x2490, v71
	ds_write2_b32 v0, v36, v37 offset1:1
	v_add_u32_e32 v0, 0x2498, v71
	ds_write2_b32 v0, v38, v39 offset1:1
	v_add_u32_e32 v0, 0x28a0, v71
	v_readlane_b32 s59, v253, 29
	v_readlane_b32 s60, v253, 30
	v_readlane_b32 s61, v253, 31
	ds_write2_b32 v0, v40, v41 offset1:1
	v_add_u32_e32 v0, 0x28a8, v71
	ds_write2_b32 v0, v42, v43 offset1:1
	v_add_u32_e32 v0, 0x2cb0, v71
	ds_write2_b32 v0, v44, v45 offset1:1
	v_add_u32_e32 v0, 0x2cb8, v71
	ds_write2_b32 v0, v46, v47 offset1:1
	v_add_u32_e32 v0, 0x30c0, v71
	ds_write2_b32 v0, v48, v49 offset1:1
	v_add_u32_e32 v0, 0x30c8, v71
	ds_write2_b32 v0, v50, v51 offset1:1
	v_add_u32_e32 v0, 0x34d0, v71
	v_readlane_b32 s62, v253, 32
	ds_write2_b32 v0, v52, v53 offset1:1
	v_add_u32_e32 v0, 0x34d8, v71
	ds_write2_b32 v0, v54, v55 offset1:1
	v_add_u32_e32 v0, 0x38e0, v71
	v_readlane_b32 s63, v253, 33
	ds_write2_b32 v0, v56, v57 offset1:1
	v_add_u32_e32 v0, 0x38e8, v71
	ds_write2_b32 v0, v58, v59 offset1:1
	v_add_u32_e32 v0, 0x3cf0, v71
	ds_write2_b32 v0, v60, v61 offset1:1
	v_add_u32_e32 v0, 0x3cf8, v71
	ds_write2_b32 v0, v62, v63 offset1:1
	s_waitcnt lgkmcnt(0)
; __device__ __forceinline__ unsigned pk2(float lo, float hi) { unsigned r; asm("v_cvt_pk_bf16_f32 %0, %1, %2" : "=v"(r) : "v"(lo), "v"(hi)); return r; }
; __device__ __forceinline__ void p0_transpose_item(const float* W, int K, int N, bf16* WT, float* scr, int item, int lane, const float* scale, const float* cb, float* c1, float* c2) {
;     ...
;     const int c = lane & 7;
; #pragma unroll
;     for (int j = 0; j < 8; ++j) { const int n = (lane >> 3) + 8 * j; const float* sp = scr + (8 * c) * 65 + n;
;         v4u o; o.x = pk2(sp[0 * 65], sp[1 * 65]); o.y = pk2(sp[2 * 65], sp[3 * 65]); o.z = pk2(sp[4 * 65], sp[5 * 65]); o.w = pk2(sp[6 * 65], sp[7 * 65]);
;         *(v4u*)(WT + (size_t)(n0 + n) * K + k0 + 8 * c) = o; }
	ds_read_b32 v0, v81
	ds_read_b32 v1, v81 offset:260
	ds_read_b32 v2, v81 offset:520
	ds_read_b32 v3, v81 offset:780
	ds_read_b32 v6, v81 offset:1040
	ds_read_b32 v7, v81 offset:1300
	ds_read_b32 v8, v81 offset:1560
	ds_read_b32 v9, v81 offset:1820
	s_waitcnt lgkmcnt(0)
	v_cvt_pk_bf16_f32 v0, v0, v1
	v_cvt_pk_bf16_f32 v1, v2, v3
	v_cvt_pk_bf16_f32 v2, v6, v7
	v_or_b32_e32 v6, s1, v80
	v_lshlrev_b32_e32 v168, 12, v6
	v_lshl_add_u64 v[6:7], v[4:5], 0, v[168:169]
	v_cvt_pk_bf16_f32 v3, v8, v9
	global_store_dwordx4 v[6:7], v[0:3], off
	ds_read_b32 v0, v81 offset:32
	ds_read_b32 v1, v81 offset:292
	ds_read_b32 v2, v81 offset:552
	ds_read_b32 v3, v81 offset:812
	ds_read_b32 v6, v81 offset:1072
	ds_read_b32 v7, v81 offset:1332
	ds_read_b32 v8, v81 offset:1592
	ds_read_b32 v9, v81 offset:1852
	s_waitcnt lgkmcnt(0)
	v_cvt_pk_bf16_f32 v0, v0, v1
	v_cvt_pk_bf16_f32 v1, v2, v3
	v_cvt_pk_bf16_f32 v2, v6, v7
	v_or_b32_e32 v6, s1, v82
	v_lshlrev_b32_e32 v168, 12, v6
	v_lshl_add_u64 v[6:7], v[4:5], 0, v[168:169]
	v_cvt_pk_bf16_f32 v3, v8, v9
	global_store_dwordx4 v[6:7], v[0:3], off
	ds_read_b32 v0, v81 offset:64
	ds_read_b32 v1, v81 offset:324
	ds_read_b32 v2, v81 offset:584
	ds_read_b32 v3, v81 offset:844
	ds_read_b32 v6, v81 offset:1104
	ds_read_b32 v7, v81 offset:1364
	ds_read_b32 v8, v81 offset:1624
	ds_read_b32 v9, v81 offset:1884
	s_waitcnt lgkmcnt(0)
	v_cvt_pk_bf16_f32 v0, v0, v1
	v_cvt_pk_bf16_f32 v1, v2, v3
	v_cvt_pk_bf16_f32 v2, v6, v7
	v_or_b32_e32 v6, s1, v83
	v_lshlrev_b32_e32 v168, 12, v6
	v_lshl_add_u64 v[6:7], v[4:5], 0, v[168:169]
	v_cvt_pk_bf16_f32 v3, v8, v9
	global_store_dwordx4 v[6:7], v[0:3], off
	ds_read_b32 v0, v81 offset:96
	ds_read_b32 v1, v81 offset:356
	ds_read_b32 v2, v81 offset:616
	ds_read_b32 v3, v81 offset:876
	ds_read_b32 v6, v81 offset:1136
	ds_read_b32 v7, v81 offset:1396
	ds_read_b32 v8, v81 offset:1656
	ds_read_b32 v9, v81 offset:1916
	s_waitcnt lgkmcnt(0)
	v_cvt_pk_bf16_f32 v0, v0, v1
	v_cvt_pk_bf16_f32 v1, v2, v3
	v_cvt_pk_bf16_f32 v2, v6, v7
	v_or_b32_e32 v6, s1, v84
	v_lshlrev_b32_e32 v168, 12, v6
	v_lshl_add_u64 v[6:7], v[4:5], 0, v[168:169]
	v_cvt_pk_bf16_f32 v3, v8, v9
	global_store_dwordx4 v[6:7], v[0:3], off
	ds_read_b32 v0, v81 offset:128
	ds_read_b32 v1, v81 offset:388
	ds_read_b32 v2, v81 offset:648
	ds_read_b32 v3, v81 offset:908
	ds_read_b32 v6, v81 offset:1168
	ds_read_b32 v7, v81 offset:1428
	ds_read_b32 v8, v81 offset:1688
	ds_read_b32 v9, v81 offset:1948
	s_waitcnt lgkmcnt(0)
	v_cvt_pk_bf16_f32 v0, v0, v1
	v_cvt_pk_bf16_f32 v1, v2, v3
	v_cvt_pk_bf16_f32 v2, v6, v7
	v_or_b32_e32 v6, s1, v85
	v_lshlrev_b32_e32 v168, 12, v6
	v_lshl_add_u64 v[6:7], v[4:5], 0, v[168:169]
	v_cvt_pk_bf16_f32 v3, v8, v9
	global_store_dwordx4 v[6:7], v[0:3], off
	ds_read_b32 v0, v81 offset:160
	ds_read_b32 v1, v81 offset:420
	ds_read_b32 v2, v81 offset:680
	ds_read_b32 v3, v81 offset:940
	ds_read_b32 v6, v81 offset:1200
	ds_read_b32 v7, v81 offset:1460
	ds_read_b32 v8, v81 offset:1720
	ds_read_b32 v9, v81 offset:1980
	s_waitcnt lgkmcnt(0)
	v_cvt_pk_bf16_f32 v0, v0, v1
	v_cvt_pk_bf16_f32 v1, v2, v3
	v_cvt_pk_bf16_f32 v2, v6, v7
	v_or_b32_e32 v6, s1, v86
	v_lshlrev_b32_e32 v168, 12, v6
	v_lshl_add_u64 v[6:7], v[4:5], 0, v[168:169]
	v_cvt_pk_bf16_f32 v3, v8, v9
	global_store_dwordx4 v[6:7], v[0:3], off
	ds_read_b32 v0, v81 offset:192
	ds_read_b32 v1, v81 offset:452
	ds_read_b32 v2, v81 offset:712
	ds_read_b32 v3, v81 offset:972
	ds_read_b32 v6, v81 offset:1232
	ds_read_b32 v7, v81 offset:1492
	ds_read_b32 v8, v81 offset:1752
	ds_read_b32 v9, v81 offset:2012
	s_waitcnt lgkmcnt(0)
	v_cvt_pk_bf16_f32 v0, v0, v1
	v_cvt_pk_bf16_f32 v1, v2, v3
	v_cvt_pk_bf16_f32 v2, v6, v7
	v_or_b32_e32 v6, s1, v87
	v_lshlrev_b32_e32 v168, 12, v6
	v_lshl_add_u64 v[6:7], v[4:5], 0, v[168:169]
	v_cvt_pk_bf16_f32 v3, v8, v9
	global_store_dwordx4 v[6:7], v[0:3], off
	ds_read_b32 v0, v81 offset:224
	ds_read_b32 v1, v81 offset:484
	ds_read_b32 v2, v81 offset:744
	ds_read_b32 v3, v81 offset:1004
	ds_read_b32 v6, v81 offset:1264
	ds_read_b32 v7, v81 offset:1524
	ds_read_b32 v8, v81 offset:1784
	ds_read_b32 v9, v81 offset:2044
	s_waitcnt lgkmcnt(0)
	v_cvt_pk_bf16_f32 v0, v0, v1
	v_cvt_pk_bf16_f32 v1, v2, v3
	v_cvt_pk_bf16_f32 v2, v6, v7
	v_or_b32_e32 v6, s1, v88
	v_lshlrev_b32_e32 v168, 12, v6
	v_lshl_add_u64 v[4:5], v[4:5], 0, v[168:169]
	v_cvt_pk_bf16_f32 v3, v8, v9
	global_store_dwordx4 v[4:5], v[0:3], off
	s_waitcnt lgkmcnt(0)

; #define LDS_WAIT() asm volatile("s_waitcnt lgkmcnt(0)" ::: "memory")
; __device__ __forceinline__ void p0_transpose_item(const float* W, int K, int N, bf16* WT, float* scr, int item, int lane, const float* scale, const float* cb, float* c1, float* c2) {
;     const int nblk = N / 64, kb = item / nblk, nb = item % nblk, k0 = 64 * kb, n0 = 64 * nb;
;     const int lr = lane >> 4, lc = (lane & 15) * 4;
;     f32x4 v[16];
; #pragma unroll
;     for (int i = 0; i < 16; ++i) v[i] = *(const f32x4*)(W + (size_t)(k0 + 4 * i + lr) * N + n0 + lc);
; #pragma unroll
;     for (int i = 0; i < 16; ++i) { const int kk = 4 * i + lr; f32x4 w = v[i]; if (scale) w = w * scale[k0 + kk]; float* d = scr + kk * 65 + lc; d[0] = w[0]; d[1] = w[1]; d[2] = w[2]; d[3] = w[3]; }
;     LDS_WAIT(); asm volatile("" ::: "memory");
.LBB0_1019:
	s_andn2_b64 vcc, exec, s[2:3]
	s_cbranch_vccnz .LBB0_982
	v_readlane_b32 s48, v253, 2
	s_mul_i32 s2, s0, 0x3c00000
	v_readlane_b32 s52, v253, 6
	s_mul_hi_i32 s1, s0, 0x3c00000
	v_readlane_b32 s53, v253, 7
	s_add_u32 s3, s52, s2
	s_addc_u32 s6, s53, s1
	s_mul_hi_i32 s1, s0, 0x1e00000
	s_mul_i32 s0, s0, 0x1e00000
	s_add_u32 s7, s25, s0
	s_mul_i32 s0, s45, 0xffff8889
	s_addc_u32 s8, s26, s1
	s_lshr_b32 s0, s0, 16
	s_add_i32 s0, s0, s45
	s_sext_i32_i16 s1, s0
	s_ashr_i32 s1, s1, 6
	s_bfe_u32 s0, s0, 0x1000f
	s_add_i32 s0, s1, s0
	s_sext_i32_i16 s1, s0
	s_mulk_i32 s0, 0x78
	s_sub_i32 s0, s45, s0
	s_sext_i32_i16 s0, s0
	s_lshl_b32 s0, s0, 6
	s_lshl_b32 s2, s1, 6
	s_ashr_i32 s1, s0, 31
	s_lshl_b64 s[4:5], s[0:1], 2
	v_or_b32_e32 v2, s2, v69
	s_add_u32 s4, s3, s4
	s_addc_u32 s5, s6, s5
	v_lshlrev_b32_e32 v168, 2, v68
	v_mul_i32_i24_e32 v2, 0x1e00, v2
	v_lshl_add_u64 v[0:1], s[4:5], 0, v[168:169]
	v_ashrrev_i32_e32 v3, 31, v2
	v_lshl_add_u64 v[60:61], v[2:3], 2, v[0:1]
	s_mov_b32 s1, 0x1e000
	v_add_co_u32_e32 v4, vcc, s1, v60
	s_mov_b32 s1, 0x3c000
	s_nop 0
	v_addc_co_u32_e32 v5, vcc, 0, v61, vcc
	v_add_co_u32_e32 v8, vcc, s1, v60
	global_load_dwordx4 v[0:3], v[60:61], off
	s_nop 0
	global_load_dwordx4 v[4:7], v[4:5], off
	v_addc_co_u32_e32 v9, vcc, 0, v61, vcc
	s_mov_b32 s1, 0x5a000
	v_add_co_u32_e32 v12, vcc, s1, v60
	s_mov_b32 s1, 0x78000
	s_nop 0
	v_addc_co_u32_e32 v13, vcc, 0, v61, vcc
	global_load_dwordx4 v[8:11], v[8:9], off
	s_nop 0
	global_load_dwordx4 v[12:15], v[12:13], off
	v_add_co_u32_e32 v16, vcc, s1, v60
	s_mov_b32 s1, 0x96000
	s_nop 0
	v_addc_co_u32_e32 v17, vcc, 0, v61, vcc
	v_add_co_u32_e32 v20, vcc, s1, v60
	s_mov_b32 s1, 0xb4000
	s_nop 0
	v_addc_co_u32_e32 v21, vcc, 0, v61, vcc
	global_load_dwordx4 v[16:19], v[16:17], off
	s_nop 0
	global_load_dwordx4 v[20:23], v[20:21], off
	v_add_co_u32_e32 v24, vcc, s1, v60
	s_mov_b32 s1, 0xd2000
	s_nop 0
	v_addc_co_u32_e32 v25, vcc, 0, v61, vcc
	v_add_co_u32_e32 v28, vcc, s1, v60
	s_mov_b32 s1, 0xf0000
	s_nop 0
	v_addc_co_u32_e32 v29, vcc, 0, v61, vcc
	global_load_dwordx4 v[24:27], v[24:25], off
	s_nop 0
	global_load_dwordx4 v[28:31], v[28:29], off
	v_add_co_u32_e32 v32, vcc, s1, v60
	s_mov_b32 s1, 0x10e000
	s_nop 0
	v_addc_co_u32_e32 v33, vcc, 0, v61, vcc
	v_add_co_u32_e32 v36, vcc, s1, v60
	s_mov_b32 s1, 0x12c000
	s_nop 0
	v_addc_co_u32_e32 v37, vcc, 0, v61, vcc
	global_load_dwordx4 v[32:35], v[32:33], off
	s_nop 0
	global_load_dwordx4 v[36:39], v[36:37], off
	v_add_co_u32_e32 v40, vcc, s1, v60
	s_mov_b32 s1, 0x14a000
	s_nop 0
	v_addc_co_u32_e32 v41, vcc, 0, v61, vcc
	v_add_co_u32_e32 v44, vcc, s1, v60
	s_mov_b32 s1, 0x168000
	s_nop 0
	v_addc_co_u32_e32 v45, vcc, 0, v61, vcc
	global_load_dwordx4 v[40:43], v[40:41], off
	s_nop 0
	global_load_dwordx4 v[44:47], v[44:45], off
	v_add_co_u32_e32 v48, vcc, s1, v60
	s_mov_b32 s1, 0x186000
	s_nop 0
	v_addc_co_u32_e32 v49, vcc, 0, v61, vcc
	global_load_dwordx4 v[48:51], v[48:49], off
	v_add_co_u32_e32 v52, vcc, s1, v60
	s_mov_b32 s1, 0x1a4000
	s_nop 0
	v_addc_co_u32_e32 v53, vcc, 0, v61, vcc
	global_load_dwordx4 v[52:55], v[52:53], off
	v_add_co_u32_e32 v56, vcc, s1, v60
	s_mov_b32 s1, 0x1c2000
	s_nop 0
	v_addc_co_u32_e32 v57, vcc, 0, v61, vcc
	global_load_dwordx4 v[56:59], v[56:57], off
	v_add_co_u32_e32 v60, vcc, s1, v60
	s_ashr_i32 s3, s2, 31
	s_nop 0
	v_addc_co_u32_e32 v61, vcc, 0, v61, vcc
	global_load_dwordx4 v[60:63], v[60:61], off
	s_waitcnt vmcnt(0)
	ds_write2_b32 v71, v0, v1 offset1:1
	ds_write2_b32 v71, v2, v3 offset0:2 offset1:3
	v_add_u32_e32 v0, 0x410, v71
	ds_write2_b32 v0, v4, v5 offset1:1
	v_add_u32_e32 v0, 0x418, v71
	ds_write2_b32 v0, v6, v7 offset1:1
	v_add_u32_e32 v0, 0x820, v71
	s_lshl_b64 s[2:3], s[2:3], 1
	s_add_u32 s2, s7, s2
	s_addc_u32 s3, s8, s3
	ds_write2_b32 v0, v8, v9 offset1:1
	v_add_u32_e32 v0, 0x828, v71
	ds_write2_b32 v0, v10, v11 offset1:1
	v_add_u32_e32 v0, 0xc30, v71
	ds_write2_b32 v0, v12, v13 offset1:1
	v_add_u32_e32 v0, 0xc38, v71
	ds_write2_b32 v0, v14, v15 offset1:1
	v_add_u32_e32 v0, 0x1040, v71
	v_lshlrev_b32_e32 v168, 1, v70
	v_lshl_add_u64 v[4:5], s[2:3], 0, v[168:169]
	v_readlane_b32 s49, v253, 3
	ds_write2_b32 v0, v16, v17 offset1:1
	v_add_u32_e32 v0, 0x1048, v71
	ds_write2_b32 v0, v18, v19 offset1:1
	v_add_u32_e32 v0, 0x1450, v71
	ds_write2_b32 v0, v20, v21 offset1:1
	v_add_u32_e32 v0, 0x1458, v71
	ds_write2_b32 v0, v22, v23 offset1:1
	v_add_u32_e32 v0, 0x1860, v71
	v_readlane_b32 s50, v253, 4
	v_readlane_b32 s51, v253, 5
	v_readlane_b32 s54, v253, 8
	ds_write2_b32 v0, v24, v25 offset1:1
	v_add_u32_e32 v0, 0x1868, v71
	ds_write2_b32 v0, v26, v27 offset1:1
	v_add_u32_e32 v0, 0x1c70, v71
	ds_write2_b32 v0, v28, v29 offset1:1
	v_add_u32_e32 v0, 0x1c78, v71
	ds_write2_b32 v0, v30, v31 offset1:1
	v_add_u32_e32 v0, 0x2080, v71
	v_readlane_b32 s55, v253, 9
	v_readlane_b32 s56, v253, 10
	v_readlane_b32 s57, v253, 11
	ds_write2_b32 v0, v32, v33 offset1:1
	v_add_u32_e32 v0, 0x2088, v71
	ds_write2_b32 v0, v34, v35 offset1:1
	v_add_u32_e32 v0, 0x2490, v71
	ds_write2_b32 v0, v36, v37 offset1:1
	v_add_u32_e32 v0, 0x2498, v71
	ds_write2_b32 v0, v38, v39 offset1:1
	v_add_u32_e32 v0, 0x28a0, v71
	v_readlane_b32 s58, v253, 12
	v_readlane_b32 s59, v253, 13
	v_readlane_b32 s60, v253, 14
	ds_write2_b32 v0, v40, v41 offset1:1
	v_add_u32_e32 v0, 0x28a8, v71
	ds_write2_b32 v0, v42, v43 offset1:1
	v_add_u32_e32 v0, 0x2cb0, v71
	ds_write2_b32 v0, v44, v45 offset1:1
	v_add_u32_e32 v0, 0x2cb8, v71
	ds_write2_b32 v0, v46, v47 offset1:1
	v_add_u32_e32 v0, 0x30c0, v71
	ds_write2_b32 v0, v48, v49 offset1:1
	v_add_u32_e32 v0, 0x30c8, v71
	ds_write2_b32 v0, v50, v51 offset1:1
	v_add_u32_e32 v0, 0x34d0, v71
	v_readlane_b32 s61, v253, 15
	ds_write2_b32 v0, v52, v53 offset1:1
	v_add_u32_e32 v0, 0x34d8, v71
	ds_write2_b32 v0, v54, v55 offset1:1
	v_add_u32_e32 v0, 0x38e0, v71
	v_readlane_b32 s62, v253, 16
	v_readlane_b32 s63, v253, 17
	ds_write2_b32 v0, v56, v57 offset1:1
	v_add_u32_e32 v0, 0x38e8, v71
	ds_write2_b32 v0, v58, v59 offset1:1
	v_add_u32_e32 v0, 0x3cf0, v71
	ds_write2_b32 v0, v60, v61 offset1:1
	v_add_u32_e32 v0, 0x3cf8, v71
	ds_write2_b32 v0, v62, v63 offset1:1
	s_waitcnt lgkmcnt(0)
; __device__ __forceinline__ unsigned pk2(float lo, float hi) { unsigned r; asm("v_cvt_pk_bf16_f32 %0, %1, %2" : "=v"(r) : "v"(lo), "v"(hi)); return r; }
; __device__ __forceinline__ void p0_transpose_item(const float* W, int K, int N, bf16* WT, float* scr, int item, int lane, const float* scale, const float* cb, float* c1, float* c2) {
;     ...
;     const int c = lane & 7;
; #pragma unroll
;     for (int j = 0; j < 8; ++j) { const int n = (lane >> 3) + 8 * j; const float* sp = scr + (8 * c) * 65 + n;
;         v4u o; o.x = pk2(sp[0 * 65], sp[1 * 65]); o.y = pk2(sp[2 * 65], sp[3 * 65]); o.z = pk2(sp[4 * 65], sp[5 * 65]); o.w = pk2(sp[6 * 65], sp[7 * 65]);
;         *(v4u*)(WT + (size_t)(n0 + n) * K + k0 + 8 * c) = o; }
	ds_read_b32 v0, v81
	ds_read_b32 v1, v81 offset:260
	ds_read_b32 v2, v81 offset:520
	ds_read_b32 v3, v81 offset:780
	ds_read_b32 v6, v81 offset:1040
	ds_read_b32 v7, v81 offset:1300
	ds_read_b32 v8, v81 offset:1560
	ds_read_b32 v9, v81 offset:1820
	s_waitcnt lgkmcnt(0)
	v_cvt_pk_bf16_f32 v0, v0, v1
	v_cvt_pk_bf16_f32 v1, v2, v3
	v_cvt_pk_bf16_f32 v2, v6, v7
	v_or_b32_e32 v6, s0, v80
	v_ashrrev_i32_e32 v7, 31, v6
	v_lshlrev_b64 v[6:7], 12, v[6:7]
	v_lshl_add_u64 v[6:7], v[4:5], 0, v[6:7]
	v_cvt_pk_bf16_f32 v3, v8, v9
	global_store_dwordx4 v[6:7], v[0:3], off
	ds_read_b32 v0, v81 offset:32
	ds_read_b32 v1, v81 offset:292
	ds_read_b32 v2, v81 offset:552
	ds_read_b32 v3, v81 offset:812
	ds_read_b32 v6, v81 offset:1072
	ds_read_b32 v7, v81 offset:1332
	ds_read_b32 v8, v81 offset:1592
	ds_read_b32 v9, v81 offset:1852
	s_waitcnt lgkmcnt(0)
	v_cvt_pk_bf16_f32 v0, v0, v1
	v_cvt_pk_bf16_f32 v1, v2, v3
	v_cvt_pk_bf16_f32 v2, v6, v7
	v_or_b32_e32 v6, s0, v82
	v_ashrrev_i32_e32 v7, 31, v6
	v_lshlrev_b64 v[6:7], 12, v[6:7]
	v_lshl_add_u64 v[6:7], v[4:5], 0, v[6:7]
	v_cvt_pk_bf16_f32 v3, v8, v9
	global_store_dwordx4 v[6:7], v[0:3], off
	ds_read_b32 v0, v81 offset:64
	ds_read_b32 v1, v81 offset:324
	ds_read_b32 v2, v81 offset:584
	ds_read_b32 v3, v81 offset:844
	ds_read_b32 v6, v81 offset:1104
	ds_read_b32 v7, v81 offset:1364
	ds_read_b32 v8, v81 offset:1624
	ds_read_b32 v9, v81 offset:1884
	s_waitcnt lgkmcnt(0)
	v_cvt_pk_bf16_f32 v0, v0, v1
	v_cvt_pk_bf16_f32 v1, v2, v3
	v_cvt_pk_bf16_f32 v2, v6, v7
	v_or_b32_e32 v6, s0, v83
	v_ashrrev_i32_e32 v7, 31, v6
	v_lshlrev_b64 v[6:7], 12, v[6:7]
	v_lshl_add_u64 v[6:7], v[4:5], 0, v[6:7]
	v_cvt_pk_bf16_f32 v3, v8, v9
	global_store_dwordx4 v[6:7], v[0:3], off
	ds_read_b32 v0, v81 offset:96
	ds_read_b32 v1, v81 offset:356
	ds_read_b32 v2, v81 offset:616
	ds_read_b32 v3, v81 offset:876
	ds_read_b32 v6, v81 offset:1136
	ds_read_b32 v7, v81 offset:1396
	ds_read_b32 v8, v81 offset:1656
	ds_read_b32 v9, v81 offset:1916
	s_waitcnt lgkmcnt(0)
	v_cvt_pk_bf16_f32 v0, v0, v1
	v_cvt_pk_bf16_f32 v1, v2, v3
	v_cvt_pk_bf16_f32 v2, v6, v7
	v_or_b32_e32 v6, s0, v84
	v_ashrrev_i32_e32 v7, 31, v6
	v_lshlrev_b64 v[6:7], 12, v[6:7]
	v_lshl_add_u64 v[6:7], v[4:5], 0, v[6:7]
	v_cvt_pk_bf16_f32 v3, v8, v9
	global_store_dwordx4 v[6:7], v[0:3], off
	ds_read_b32 v0, v81 offset:128
	ds_read_b32 v1, v81 offset:388
	ds_read_b32 v2, v81 offset:648
	ds_read_b32 v3, v81 offset:908
	ds_read_b32 v6, v81 offset:1168
	ds_read_b32 v7, v81 offset:1428
	ds_read_b32 v8, v81 offset:1688
	ds_read_b32 v9, v81 offset:1948
	s_waitcnt lgkmcnt(0)
	v_cvt_pk_bf16_f32 v0, v0, v1
	v_cvt_pk_bf16_f32 v1, v2, v3
	v_cvt_pk_bf16_f32 v2, v6, v7
	v_or_b32_e32 v6, s0, v85
	v_ashrrev_i32_e32 v7, 31, v6
	v_lshlrev_b64 v[6:7], 12, v[6:7]
	v_lshl_add_u64 v[6:7], v[4:5], 0, v[6:7]
	v_cvt_pk_bf16_f32 v3, v8, v9
	global_store_dwordx4 v[6:7], v[0:3], off
	ds_read_b32 v0, v81 offset:160
	ds_read_b32 v1, v81 offset:420
	ds_read_b32 v2, v81 offset:680
	ds_read_b32 v3, v81 offset:940
	ds_read_b32 v6, v81 offset:1200
	ds_read_b32 v7, v81 offset:1460
	ds_read_b32 v8, v81 offset:1720
	ds_read_b32 v9, v81 offset:1980
	s_waitcnt lgkmcnt(0)
	v_cvt_pk_bf16_f32 v0, v0, v1
	v_cvt_pk_bf16_f32 v1, v2, v3
	v_cvt_pk_bf16_f32 v2, v6, v7
	v_or_b32_e32 v6, s0, v86
	v_ashrrev_i32_e32 v7, 31, v6
	v_lshlrev_b64 v[6:7], 12, v[6:7]
	v_lshl_add_u64 v[6:7], v[4:5], 0, v[6:7]
	v_cvt_pk_bf16_f32 v3, v8, v9
	global_store_dwordx4 v[6:7], v[0:3], off
	ds_read_b32 v0, v81 offset:192
	ds_read_b32 v1, v81 offset:452
	ds_read_b32 v2, v81 offset:712
	ds_read_b32 v3, v81 offset:972
	ds_read_b32 v6, v81 offset:1232
	ds_read_b32 v7, v81 offset:1492
	ds_read_b32 v8, v81 offset:1752
	ds_read_b32 v9, v81 offset:2012
	s_waitcnt lgkmcnt(0)
	v_cvt_pk_bf16_f32 v0, v0, v1
	v_cvt_pk_bf16_f32 v1, v2, v3
	v_cvt_pk_bf16_f32 v2, v6, v7
	v_or_b32_e32 v6, s0, v87
	v_ashrrev_i32_e32 v7, 31, v6
	v_lshlrev_b64 v[6:7], 12, v[6:7]
	v_lshl_add_u64 v[6:7], v[4:5], 0, v[6:7]
	v_cvt_pk_bf16_f32 v3, v8, v9
	global_store_dwordx4 v[6:7], v[0:3], off
	ds_read_b32 v0, v81 offset:224
	ds_read_b32 v1, v81 offset:484
	ds_read_b32 v2, v81 offset:744
	ds_read_b32 v3, v81 offset:1004
	ds_read_b32 v6, v81 offset:1264
	ds_read_b32 v7, v81 offset:1524
	ds_read_b32 v8, v81 offset:1784
	ds_read_b32 v9, v81 offset:2044
	s_waitcnt lgkmcnt(0)
	v_cvt_pk_bf16_f32 v0, v0, v1
	v_cvt_pk_bf16_f32 v1, v2, v3
	v_cvt_pk_bf16_f32 v2, v6, v7
	v_or_b32_e32 v6, s0, v88
	v_ashrrev_i32_e32 v7, 31, v6
	v_lshlrev_b64 v[6:7], 12, v[6:7]
	v_lshl_add_u64 v[4:5], v[4:5], 0, v[6:7]
	v_cvt_pk_bf16_f32 v3, v8, v9
	global_store_dwordx4 v[4:5], v[0:3], off
	s_waitcnt lgkmcnt(0)
	s_branch .LBB0_982

; #define LDS_WAIT() asm volatile("s_waitcnt lgkmcnt(0)" ::: "memory")
; __device__ __forceinline__ void p0_transpose_item(const float* W, int K, int N, bf16* WT, float* scr, int item, int lane, const float* scale, const float* cb, float* c1, float* c2) {
;     const int nblk = N / 64, kb = item / nblk, nb = item % nblk, k0 = 64 * kb, n0 = 64 * nb;
;     const int lr = lane >> 4, lc = (lane & 15) * 4;
;     f32x4 v[16];
; #pragma unroll
;     for (int i = 0; i < 16; ++i) v[i] = *(const f32x4*)(W + (size_t)(k0 + 4 * i + lr) * N + n0 + lc);
; #pragma unroll
;     for (int i = 0; i < 16; ++i) { const int kk = 4 * i + lr; f32x4 w = v[i]; if (scale) w = w * scale[k0 + kk]; float* d = scr + kk * 65 + lc; d[0] = w[0]; d[1] = w[1]; d[2] = w[2]; d[3] = w[3]; }
;     LDS_WAIT(); asm volatile("" ::: "memory");
.LBB0_1032:
	s_mul_hi_i32 s0, s24, 0xae4c415d
	s_add_i32 s0, s0, s24
	s_lshr_b32 s1, s0, 31
	s_ashr_i32 s0, s0, 12
	s_add_i32 s0, s0, s1
	s_mul_i32 s1, s0, 0x1780
	s_sub_i32 s45, s24, s1
	s_cmpk_gt_i32 s45, 0xeff
	s_mov_b64 s[2:3], -1
	s_cbranch_scc0 .LBB0_1068
	s_cmpk_gt_u32 s45, 0x12ff
	s_cbranch_scc0 .LBB0_1065
	s_ashr_i32 s1, s0, 31
	s_cmpk_gt_u32 s45, 0x16ff
	s_cbranch_scc0 .LBB0_1036
	v_readlane_b32 s48, v253, 18
	s_lshl_b64 s[2:3], s[0:1], 21
	v_readlane_b32 s62, v253, 32
	v_readlane_b32 s63, v253, 33
	s_add_u32 s4, s62, s2
	s_addc_u32 s5, s63, s3
	s_lshl_b64 s[2:3], s[0:1], 20
	s_add_u32 s6, s39, s2
	s_addc_u32 s3, s40, s3
	s_lshl_b32 s2, s45, 1
	s_and_b32 s7, s2, 0x1c0
	s_lshl_b32 s2, s45, 6
	s_and_b32 s2, s2, 0x7c0
	s_lshl_b32 s8, s2, 2
	s_add_u32 s4, s4, s8
	v_or_b32_e32 v2, s7, v69
	s_addc_u32 s5, s5, 0
	v_lshlrev_b32_e32 v168, 2, v68
	v_lshl_add_u64 v[0:1], s[4:5], 0, v[168:169]
	v_lshlrev_b32_e32 v168, 13, v2
	v_lshl_add_u64 v[60:61], v[0:1], 0, v[168:169]
	v_add_co_u32_e32 v4, vcc, s90, v60
	s_mov_b32 s4, 0x20000
	s_nop 0
	v_addc_co_u32_e32 v5, vcc, 0, v61, vcc
	v_add_co_u32_e32 v8, vcc, s88, v60
	global_load_dwordx4 v[0:3], v[60:61], off
	s_nop 0
	global_load_dwordx4 v[4:7], v[4:5], off
	v_addc_co_u32_e32 v9, vcc, 0, v61, vcc
	v_add_co_u32_e32 v12, vcc, s85, v60
	v_lshlrev_b32_e32 v168, 1, v70
	s_nop 0
	v_addc_co_u32_e32 v13, vcc, 0, v61, vcc
	global_load_dwordx4 v[8:11], v[8:9], off
	s_nop 0
	global_load_dwordx4 v[12:15], v[12:13], off
	v_add_co_u32_e32 v16, vcc, s4, v60
	s_mov_b32 s4, 0x28000
	s_nop 0
	v_addc_co_u32_e32 v17, vcc, 0, v61, vcc
	v_add_co_u32_e32 v20, vcc, s4, v60
	s_mov_b32 s4, 0x30000
	s_nop 0
	v_addc_co_u32_e32 v21, vcc, 0, v61, vcc
	global_load_dwordx4 v[16:19], v[16:17], off
	s_nop 0
	global_load_dwordx4 v[20:23], v[20:21], off
	v_add_co_u32_e32 v24, vcc, s4, v60
	s_mov_b32 s4, 0x38000
	s_nop 0
	v_addc_co_u32_e32 v25, vcc, 0, v61, vcc
	v_add_co_u32_e32 v28, vcc, s4, v60
	s_mov_b32 s4, 0x40000
	s_nop 0
	v_addc_co_u32_e32 v29, vcc, 0, v61, vcc
	global_load_dwordx4 v[24:27], v[24:25], off
	s_nop 0
	global_load_dwordx4 v[28:31], v[28:29], off
	v_add_co_u32_e32 v32, vcc, s4, v60
	s_mov_b32 s4, 0x48000
	s_nop 0
	v_addc_co_u32_e32 v33, vcc, 0, v61, vcc
	v_add_co_u32_e32 v36, vcc, s4, v60
	s_mov_b32 s4, 0x50000
	s_nop 0
	v_addc_co_u32_e32 v37, vcc, 0, v61, vcc
	global_load_dwordx4 v[32:35], v[32:33], off
	s_nop 0
	global_load_dwordx4 v[36:39], v[36:37], off
	v_add_co_u32_e32 v40, vcc, s4, v60
	s_mov_b32 s4, 0x58000
	s_nop 0
	v_addc_co_u32_e32 v41, vcc, 0, v61, vcc
	v_add_co_u32_e32 v44, vcc, s4, v60
	s_mov_b32 s4, 0x60000
	s_nop 0
	v_addc_co_u32_e32 v45, vcc, 0, v61, vcc
	global_load_dwordx4 v[40:43], v[40:41], off
	s_nop 0
	global_load_dwordx4 v[44:47], v[44:45], off
	v_add_co_u32_e32 v48, vcc, s4, v60
	s_mov_b32 s4, 0x68000
	s_nop 0
	v_addc_co_u32_e32 v49, vcc, 0, v61, vcc
	global_load_dwordx4 v[48:51], v[48:49], off
	v_add_co_u32_e32 v52, vcc, s4, v60
	s_mov_b32 s4, 0x70000
	s_nop 0
	v_addc_co_u32_e32 v53, vcc, 0, v61, vcc
	global_load_dwordx4 v[52:55], v[52:53], off
	v_add_co_u32_e32 v56, vcc, s4, v60
	s_mov_b32 s4, 0x78000
	s_nop 0
	v_addc_co_u32_e32 v57, vcc, 0, v61, vcc
	global_load_dwordx4 v[56:59], v[56:57], off
	v_add_co_u32_e32 v60, vcc, s4, v60
	s_lshl_b32 s4, s7, 1
	s_nop 0
	v_addc_co_u32_e32 v61, vcc, 0, v61, vcc
	global_load_dwordx4 v[60:63], v[60:61], off
	s_waitcnt vmcnt(0)
	ds_write2_b32 v71, v0, v1 offset1:1
	ds_write2_b32 v71, v2, v3 offset0:2 offset1:3
	v_add_u32_e32 v0, 0x410, v71
	ds_write2_b32 v0, v4, v5 offset1:1
	v_add_u32_e32 v0, 0x418, v71
	ds_write2_b32 v0, v6, v7 offset1:1
	v_add_u32_e32 v0, 0x820, v71
	s_add_u32 s4, s6, s4
	s_addc_u32 s5, s3, 0
	ds_write2_b32 v0, v8, v9 offset1:1
	v_add_u32_e32 v0, 0x828, v71
	ds_write2_b32 v0, v10, v11 offset1:1
	v_add_u32_e32 v0, 0xc30, v71
	ds_write2_b32 v0, v12, v13 offset1:1
	v_add_u32_e32 v0, 0xc38, v71
	ds_write2_b32 v0, v14, v15 offset1:1
	v_add_u32_e32 v0, 0x1040, v71
	v_lshl_add_u64 v[4:5], s[4:5], 0, v[168:169]
	v_readlane_b32 s49, v253, 19
	v_readlane_b32 s50, v253, 20
	ds_write2_b32 v0, v16, v17 offset1:1
	v_add_u32_e32 v0, 0x1048, v71
	ds_write2_b32 v0, v18, v19 offset1:1
	v_add_u32_e32 v0, 0x1450, v71
	ds_write2_b32 v0, v20, v21 offset1:1
	v_add_u32_e32 v0, 0x1458, v71
	ds_write2_b32 v0, v22, v23 offset1:1
	v_add_u32_e32 v0, 0x1860, v71
	v_readlane_b32 s51, v253, 21
	v_readlane_b32 s52, v253, 22
	v_readlane_b32 s53, v253, 23
	ds_write2_b32 v0, v24, v25 offset1:1
	v_add_u32_e32 v0, 0x1868, v71
	ds_write2_b32 v0, v26, v27 offset1:1
	v_add_u32_e32 v0, 0x1c70, v71
	ds_write2_b32 v0, v28, v29 offset1:1
	v_add_u32_e32 v0, 0x1c78, v71
	ds_write2_b32 v0, v30, v31 offset1:1
	v_add_u32_e32 v0, 0x2080, v71
	v_readlane_b32 s54, v253, 24
	v_readlane_b32 s55, v253, 25
	v_readlane_b32 s56, v253, 26
	ds_write2_b32 v0, v32, v33 offset1:1
	v_add_u32_e32 v0, 0x2088, v71
	ds_write2_b32 v0, v34, v35 offset1:1
	v_add_u32_e32 v0, 0x2490, v71
	ds_write2_b32 v0, v36, v37 offset1:1
	v_add_u32_e32 v0, 0x2498, v71
	ds_write2_b32 v0, v38, v39 offset1:1
	v_add_u32_e32 v0, 0x28a0, v71
	v_readlane_b32 s57, v253, 27
	v_readlane_b32 s58, v253, 28
	v_readlane_b32 s59, v253, 29
	ds_write2_b32 v0, v40, v41 offset1:1
	v_add_u32_e32 v0, 0x28a8, v71
	ds_write2_b32 v0, v42, v43 offset1:1
	v_add_u32_e32 v0, 0x2cb0, v71
	ds_write2_b32 v0, v44, v45 offset1:1
	v_add_u32_e32 v0, 0x2cb8, v71
	ds_write2_b32 v0, v46, v47 offset1:1
	v_add_u32_e32 v0, 0x30c0, v71
	ds_write2_b32 v0, v48, v49 offset1:1
	v_add_u32_e32 v0, 0x30c8, v71
	ds_write2_b32 v0, v50, v51 offset1:1
	v_add_u32_e32 v0, 0x34d0, v71
	v_readlane_b32 s60, v253, 30
	ds_write2_b32 v0, v52, v53 offset1:1
	v_add_u32_e32 v0, 0x34d8, v71
	ds_write2_b32 v0, v54, v55 offset1:1
	v_add_u32_e32 v0, 0x38e0, v71
	v_readlane_b32 s61, v253, 31
	ds_write2_b32 v0, v56, v57 offset1:1
	v_add_u32_e32 v0, 0x38e8, v71
	ds_write2_b32 v0, v58, v59 offset1:1
	v_add_u32_e32 v0, 0x3cf0, v71
	ds_write2_b32 v0, v60, v61 offset1:1
	v_add_u32_e32 v0, 0x3cf8, v71
	ds_write2_b32 v0, v62, v63 offset1:1
	s_waitcnt lgkmcnt(0)
; __device__ __forceinline__ unsigned pk2(float lo, float hi) { unsigned r; asm("v_cvt_pk_bf16_f32 %0, %1, %2" : "=v"(r) : "v"(lo), "v"(hi)); return r; }
; __device__ __forceinline__ void p0_transpose_item(const float* W, int K, int N, bf16* WT, float* scr, int item, int lane, const float* scale, const float* cb, float* c1, float* c2) {
;     ...
;     const int c = lane & 7;
; #pragma unroll
;     for (int j = 0; j < 8; ++j) { const int n = (lane >> 3) + 8 * j; const float* sp = scr + (8 * c) * 65 + n;
;         v4u o; o.x = pk2(sp[0 * 65], sp[1 * 65]); o.y = pk2(sp[2 * 65], sp[3 * 65]); o.z = pk2(sp[4 * 65], sp[5 * 65]); o.w = pk2(sp[6 * 65], sp[7 * 65]);
;         *(v4u*)(WT + (size_t)(n0 + n) * K + k0 + 8 * c) = o; }
	ds_read_b32 v0, v81
	ds_read_b32 v1, v81 offset:260
	ds_read_b32 v2, v81 offset:520
	ds_read_b32 v3, v81 offset:780
	ds_read_b32 v6, v81 offset:1040
	ds_read_b32 v7, v81 offset:1300
	ds_read_b32 v8, v81 offset:1560
	ds_read_b32 v9, v81 offset:1820
	s_waitcnt lgkmcnt(0)
	v_cvt_pk_bf16_f32 v0, v0, v1
	v_cvt_pk_bf16_f32 v1, v2, v3
	v_cvt_pk_bf16_f32 v2, v6, v7
	v_or_b32_e32 v6, s2, v80
	v_lshlrev_b32_e32 v168, 9, v6
	v_lshl_add_u64 v[6:7], v[4:5], 0, v[168:169]
	v_cvt_pk_bf16_f32 v3, v8, v9
	global_store_dwordx4 v[6:7], v[0:3], off
	ds_read_b32 v0, v81 offset:32
	ds_read_b32 v1, v81 offset:292
	ds_read_b32 v2, v81 offset:552
	ds_read_b32 v3, v81 offset:812
	ds_read_b32 v6, v81 offset:1072
	ds_read_b32 v7, v81 offset:1332
	ds_read_b32 v8, v81 offset:1592
	ds_read_b32 v9, v81 offset:1852
	s_waitcnt lgkmcnt(0)
	v_cvt_pk_bf16_f32 v0, v0, v1
	v_cvt_pk_bf16_f32 v1, v2, v3
	v_cvt_pk_bf16_f32 v2, v6, v7
	v_or_b32_e32 v6, s2, v82
	v_lshlrev_b32_e32 v168, 9, v6
	v_lshl_add_u64 v[6:7], v[4:5], 0, v[168:169]
	v_cvt_pk_bf16_f32 v3, v8, v9
	global_store_dwordx4 v[6:7], v[0:3], off
	ds_read_b32 v0, v81 offset:64
	ds_read_b32 v1, v81 offset:324
	ds_read_b32 v2, v81 offset:584
	ds_read_b32 v3, v81 offset:844
	ds_read_b32 v6, v81 offset:1104
	ds_read_b32 v7, v81 offset:1364
	ds_read_b32 v8, v81 offset:1624
	ds_read_b32 v9, v81 offset:1884
	s_waitcnt lgkmcnt(0)
	v_cvt_pk_bf16_f32 v0, v0, v1
	v_cvt_pk_bf16_f32 v1, v2, v3
	v_cvt_pk_bf16_f32 v2, v6, v7
	v_or_b32_e32 v6, s2, v83
	v_lshlrev_b32_e32 v168, 9, v6
	v_lshl_add_u64 v[6:7], v[4:5], 0, v[168:169]
	v_cvt_pk_bf16_f32 v3, v8, v9
	global_store_dwordx4 v[6:7], v[0:3], off
	ds_read_b32 v0, v81 offset:96
	ds_read_b32 v1, v81 offset:356
	ds_read_b32 v2, v81 offset:616
	ds_read_b32 v3, v81 offset:876
	ds_read_b32 v6, v81 offset:1136
	ds_read_b32 v7, v81 offset:1396
	ds_read_b32 v8, v81 offset:1656
	ds_read_b32 v9, v81 offset:1916
	s_waitcnt lgkmcnt(0)
	v_cvt_pk_bf16_f32 v0, v0, v1
	v_cvt_pk_bf16_f32 v1, v2, v3
	v_cvt_pk_bf16_f32 v2, v6, v7
	v_or_b32_e32 v6, s2, v84
	v_lshlrev_b32_e32 v168, 9, v6
	v_lshl_add_u64 v[6:7], v[4:5], 0, v[168:169]
	v_cvt_pk_bf16_f32 v3, v8, v9
	global_store_dwordx4 v[6:7], v[0:3], off
	ds_read_b32 v0, v81 offset:128
	ds_read_b32 v1, v81 offset:388
	ds_read_b32 v2, v81 offset:648
	ds_read_b32 v3, v81 offset:908
	ds_read_b32 v6, v81 offset:1168
	ds_read_b32 v7, v81 offset:1428
	ds_read_b32 v8, v81 offset:1688
	ds_read_b32 v9, v81 offset:1948
	s_waitcnt lgkmcnt(0)
	v_cvt_pk_bf16_f32 v0, v0, v1
	v_cvt_pk_bf16_f32 v1, v2, v3
	v_cvt_pk_bf16_f32 v2, v6, v7
	v_or_b32_e32 v6, s2, v85
	v_lshlrev_b32_e32 v168, 9, v6
	v_lshl_add_u64 v[6:7], v[4:5], 0, v[168:169]
	v_cvt_pk_bf16_f32 v3, v8, v9
	global_store_dwordx4 v[6:7], v[0:3], off
	ds_read_b32 v0, v81 offset:160
	ds_read_b32 v1, v81 offset:420
	ds_read_b32 v2, v81 offset:680
	ds_read_b32 v3, v81 offset:940
	ds_read_b32 v6, v81 offset:1200
	ds_read_b32 v7, v81 offset:1460
	ds_read_b32 v8, v81 offset:1720
	ds_read_b32 v9, v81 offset:1980
	s_waitcnt lgkmcnt(0)
	v_cvt_pk_bf16_f32 v0, v0, v1
	v_cvt_pk_bf16_f32 v1, v2, v3
	v_cvt_pk_bf16_f32 v2, v6, v7
	v_or_b32_e32 v6, s2, v86
	v_lshlrev_b32_e32 v168, 9, v6
	v_lshl_add_u64 v[6:7], v[4:5], 0, v[168:169]
	v_cvt_pk_bf16_f32 v3, v8, v9
	global_store_dwordx4 v[6:7], v[0:3], off
	ds_read_b32 v0, v81 offset:192
	ds_read_b32 v1, v81 offset:452
	ds_read_b32 v2, v81 offset:712
	ds_read_b32 v3, v81 offset:972
	ds_read_b32 v6, v81 offset:1232
	ds_read_b32 v7, v81 offset:1492
	ds_read_b32 v8, v81 offset:1752
	ds_read_b32 v9, v81 offset:2012
	s_waitcnt lgkmcnt(0)
	v_cvt_pk_bf16_f32 v0, v0, v1
	v_cvt_pk_bf16_f32 v1, v2, v3
	v_cvt_pk_bf16_f32 v2, v6, v7
	v_or_b32_e32 v6, s2, v87
	v_lshlrev_b32_e32 v168, 9, v6
	v_lshl_add_u64 v[6:7], v[4:5], 0, v[168:169]
	v_cvt_pk_bf16_f32 v3, v8, v9
	global_store_dwordx4 v[6:7], v[0:3], off
	ds_read_b32 v0, v81 offset:224
	ds_read_b32 v1, v81 offset:484
	ds_read_b32 v2, v81 offset:744
	ds_read_b32 v3, v81 offset:1004
	ds_read_b32 v6, v81 offset:1264
	ds_read_b32 v7, v81 offset:1524
	ds_read_b32 v8, v81 offset:1784
	ds_read_b32 v9, v81 offset:2044
	s_waitcnt lgkmcnt(0)
	v_cvt_pk_bf16_f32 v0, v0, v1
	v_cvt_pk_bf16_f32 v1, v2, v3
	v_cvt_pk_bf16_f32 v2, v6, v7
	v_or_b32_e32 v6, s2, v88
	v_lshlrev_b32_e32 v168, 9, v6
	v_lshl_add_u64 v[4:5], v[4:5], 0, v[168:169]
	v_cvt_pk_bf16_f32 v3, v8, v9
	global_store_dwordx4 v[4:5], v[0:3], off
	s_waitcnt lgkmcnt(0)
	s_mov_b64 s[2:3], 0

; __device__ __forceinline__ unsigned cvt_pk_bf16(float lo, float hi) { unsigned r; asm volatile("v_cvt_pk_bf16_f32 %0, %1, %2" : "=v"(r) : "v"(lo), "v"(hi)); return r; }
;     __device__ __forceinline__ void operator()(const f32x4 (&acc)[2][2][4][2], const Unit& u, int wr, int wc, int fr, int fq) const {
;     ...
;             for (int m = 0; m < 4; ++m) { const int row = row0 + ai * HALF + m * 16; const size_t off = (size_t)row * ldc + col0; float s1 = 0.f, s2 = 0.f;
; #pragma unroll
;                 for (int bj = 0; bj < 2; ++bj) { const size_t o2 = off + bj * HALF; const f32x4 x0 = *(const f32x4*)(X + o2), x1 = *(const f32x4*)(X + o2 + 4);
;                     const f32x4 z0 = x0 * alpha + acc[ai][bj][m][0], z1 = x1 * alpha + acc[ai][bj][m][1];
;                     u32x4 w; w.x = cvt_pk_bf16(z0[0], z0[1]); w.y = cvt_pk_bf16(z0[2], z0[3]); w.z = cvt_pk_bf16(z1[0], z1[1]); w.w = cvt_pk_bf16(z1[2], z1[3]); *(u32x4*)(ZB + o2) = w;
;                     s1 += ((z0[0] + z0[1]) + (z0[2] + z0[3])) + ((z1[0] + z1[1]) + (z1[2] + z1[3]));
;                     s2 += ((z0[0] * z0[0] + z0[1] * z0[1]) + (z0[2] * z0[2] + z0[3] * z0[3])) + ((z1[0] * z1[0] + z1[1] * z1[1]) + (z1[2] * z1[2] + z1[3] * z1[3])); }
;                 s1 = sum_fq(s1); s2 = sum_fq(s2);
;                 if (fq == 0) { atomicAdd(ST + 2 * row, s1); atomicAdd(ST + 2 * row + 1, s2); } }
.LBB0_1136:
	v_lshl_add_u32 v140, s60, 8, v142
	v_lshl_or_b32 v138, s59, 8, v144
	v_ashrrev_i32_e32 v141, 31, v140
	v_ashrrev_i32_e32 v139, 31, v138
	v_lshlrev_b64 v[146:147], 11, v[140:141]
	v_lshl_add_u64 v[154:155], v[146:147], 0, v[138:139]
	v_lshl_add_u64 v[156:157], v[154:155], 2, s[4:5]
	global_load_dwordx4 v[146:149], v[156:157], off
	global_load_dwordx4 v[150:153], v[156:157], off offset:16
	s_waitcnt vmcnt(0) lgkmcnt(0)
	v_pk_fma_f32 v[126:127], v[148:149], s[12:13], v[126:127] op_sel_hi:[1,0,1]
	v_pk_fma_f32 v[148:149], v[150:151], s[12:13], v[120:121] op_sel_hi:[1,0,1]
	v_lshlrev_b64 v[150:151], 1, v[154:155]
	v_pk_fma_f32 v[124:125], v[146:147], s[12:13], v[124:125] op_sel_hi:[1,0,1]
	v_pk_fma_f32 v[146:147], v[152:153], s[12:13], v[122:123] op_sel_hi:[1,0,1]
	v_cvt_pk_bf16_f32 v120, v124, v125
	v_cvt_pk_bf16_f32 v121, v126, v127
	v_lshl_add_u64 v[152:153], s[8:9], 0, v[150:151]
	v_cvt_pk_bf16_f32 v122, v148, v149
	v_cvt_pk_bf16_f32 v123, v146, v147
	global_store_dwordx4 v[152:153], v[120:123], off
	v_or_b32_e32 v150, 0x100, v150
	s_nop 0
	v_add_f32_e32 v120, v124, v125
	v_add_f32_e32 v121, v126, v127
	v_add_f32_e32 v120, v120, v121
	v_add_f32_e32 v121, v148, v149
	v_add_f32_e32 v122, v146, v147
	v_add_f32_e32 v121, v121, v122
	v_add_f32_e32 v120, v120, v121
	v_add_f32_e32 v141, 0, v120
	v_mul_f32_e32 v120, v125, v125
	v_mul_f32_e32 v121, v127, v127
	v_fmac_f32_e32 v120, v124, v124
	v_fmac_f32_e32 v121, v126, v126
	v_add_f32_e32 v120, v120, v121
	v_mul_f32_e32 v121, v149, v149
	v_mul_f32_e32 v122, v147, v147
	v_fmac_f32_e32 v121, v148, v148
	v_fmac_f32_e32 v122, v146, v146
	v_add_f32_e32 v121, v121, v122
	v_add_f32_e32 v146, v120, v121
	global_load_dwordx4 v[120:123], v[156:157], off offset:512
	global_load_dwordx4 v[124:127], v[156:157], off offset:528
	s_waitcnt vmcnt(0) lgkmcnt(0)
	v_pk_fma_f32 v[118:119], v[122:123], s[12:13], v[118:119] op_sel_hi:[1,0,1]
	v_pk_fma_f32 v[116:117], v[120:121], s[12:13], v[116:117] op_sel_hi:[1,0,1]
	v_pk_fma_f32 v[122:123], v[124:125], s[12:13], v[112:113] op_sel_hi:[1,0,1]
	v_cvt_pk_bf16_f32 v112, v116, v117
	v_cvt_pk_bf16_f32 v113, v118, v119
	v_lshl_add_u64 v[124:125], s[8:9], 0, v[150:151]
	v_pk_fma_f32 v[120:121], v[126:127], s[12:13], v[114:115] op_sel_hi:[1,0,1]
	v_cvt_pk_bf16_f32 v114, v122, v123
	s_nop 0
	v_cvt_pk_bf16_f32 v115, v120, v121
	global_store_dwordx4 v[124:125], v[112:115], off
	s_nop 1
	v_add_f32_e32 v112, v116, v117
	v_add_f32_e32 v113, v118, v119
	v_add_f32_e32 v112, v112, v113
	v_add_f32_e32 v113, v122, v123
	v_add_f32_e32 v114, v120, v121
	v_add_f32_e32 v113, v113, v114
	v_add_f32_e32 v112, v112, v113
	v_mul_f32_e32 v113, v117, v117
	v_mul_f32_e32 v114, v119, v119
	v_fmac_f32_e32 v113, v116, v116
	v_fmac_f32_e32 v114, v118, v118
	v_add_f32_e32 v113, v113, v114
	v_mul_f32_e32 v114, v123, v123
	v_mul_f32_e32 v115, v121, v121
	v_fmac_f32_e32 v114, v122, v122
	v_fmac_f32_e32 v115, v120, v120
	v_add_f32_e32 v114, v114, v115
	v_add_f32_e32 v113, v113, v114
	v_add_f32_e32 v112, v141, v112
	v_add_f32_e32 v114, v146, v113
	v_mov_b32_e32 v113, v112
	v_mov_b32_e32 v115, v114
	s_nop 0
	v_permlane16_swap_b32_e32 v112, v113
	v_permlane16_swap_b32_e32 v114, v115
	v_add_f32_e32 v112, v112, v113
	v_add_f32_e32 v114, v114, v115
	v_mov_b32_e32 v113, v112
	v_mov_b32_e32 v115, v114
	s_nop 0
	v_permlane32_swap_b32_e32 v112, v113
	v_permlane32_swap_b32_e32 v114, v115
	s_and_saveexec_b64 s[0:1], s[40:41]
	s_cbranch_execz .LBB0_1138
	v_add_f32_e32 v114, v114, v115
	v_add_f32_e32 v115, v112, v113
	v_lshlrev_b32_e32 v112, 1, v140
	v_ashrrev_i32_e32 v113, 31, v112
	v_lshl_add_u64 v[112:113], v[112:113], 2, s[44:45]
	global_atomic_add_f32 v[112:113], v115, off
	global_atomic_add_f32 v[112:113], v114, off offset:4
.LBB0_1138:
	s_or_b64 exec, exec, s[0:1]
	v_or_b32_e32 v112, 16, v140
	v_ashrrev_i32_e32 v113, 31, v112
	v_lshlrev_b64 v[114:115], 11, v[112:113]
	v_lshl_add_u64 v[122:123], v[114:115], 0, v[138:139]
	v_lshl_add_u64 v[124:125], v[122:123], 2, s[4:5]
	global_load_dwordx4 v[114:117], v[124:125], off
	global_load_dwordx4 v[118:121], v[124:125], off offset:16
	s_waitcnt vmcnt(0) lgkmcnt(0)
	v_pk_fma_f32 v[110:111], v[116:117], s[12:13], v[110:111] op_sel_hi:[1,0,1]
	v_pk_fma_f32 v[116:117], v[118:119], s[12:13], v[104:105] op_sel_hi:[1,0,1]
	v_lshlrev_b64 v[118:119], 1, v[122:123]
	v_pk_fma_f32 v[108:109], v[114:115], s[12:13], v[108:109] op_sel_hi:[1,0,1]
	v_pk_fma_f32 v[114:115], v[120:121], s[12:13], v[106:107] op_sel_hi:[1,0,1]
	v_cvt_pk_bf16_f32 v104, v108, v109
	v_cvt_pk_bf16_f32 v105, v110, v111
	v_lshl_add_u64 v[120:121], s[8:9], 0, v[118:119]
	v_cvt_pk_bf16_f32 v106, v116, v117
	v_cvt_pk_bf16_f32 v107, v114, v115
	global_store_dwordx4 v[120:121], v[104:107], off
	v_or_b32_e32 v118, 0x100, v118
	s_nop 0
	v_add_f32_e32 v104, v108, v109
	v_add_f32_e32 v105, v110, v111
	v_add_f32_e32 v104, v104, v105
	v_add_f32_e32 v105, v116, v117
	v_add_f32_e32 v106, v114, v115
	v_add_f32_e32 v105, v105, v106
	v_add_f32_e32 v104, v104, v105
	v_add_f32_e32 v113, 0, v104
	v_mul_f32_e32 v104, v109, v109
	v_mul_f32_e32 v105, v111, v111
	v_fmac_f32_e32 v104, v108, v108
	v_fmac_f32_e32 v105, v110, v110
	v_add_f32_e32 v104, v104, v105
	v_mul_f32_e32 v105, v117, v117
	v_mul_f32_e32 v106, v115, v115
	v_fmac_f32_e32 v105, v116, v116
	v_fmac_f32_e32 v106, v114, v114
	v_add_f32_e32 v105, v105, v106
	v_add_f32_e32 v114, v104, v105
	global_load_dwordx4 v[104:107], v[124:125], off offset:512
	global_load_dwordx4 v[108:111], v[124:125], off offset:528
	s_waitcnt vmcnt(0) lgkmcnt(0)
; __device__ __forceinline__ unsigned cvt_pk_bf16(float lo, float hi) { unsigned r; asm volatile("v_cvt_pk_bf16_f32 %0, %1, %2" : "=v"(r) : "v"(lo), "v"(hi)); return r; }
;     __device__ __forceinline__ void operator()(const f32x4 (&acc)[2][2][4][2], const Unit& u, int wr, int wc, int fr, int fq) const {
;     ...
;             for (int m = 0; m < 4; ++m) { const int row = row0 + ai * HALF + m * 16; const size_t off = (size_t)row * ldc + col0; float s1 = 0.f, s2 = 0.f;
; #pragma unroll
;                 for (int bj = 0; bj < 2; ++bj) { const size_t o2 = off + bj * HALF; const f32x4 x0 = *(const f32x4*)(X + o2), x1 = *(const f32x4*)(X + o2 + 4);
;                     const f32x4 z0 = x0 * alpha + acc[ai][bj][m][0], z1 = x1 * alpha + acc[ai][bj][m][1];
;                     u32x4 w; w.x = cvt_pk_bf16(z0[0], z0[1]); w.y = cvt_pk_bf16(z0[2], z0[3]); w.z = cvt_pk_bf16(z1[0], z1[1]); w.w = cvt_pk_bf16(z1[2], z1[3]); *(u32x4*)(ZB + o2) = w;
;                     s1 += ((z0[0] + z0[1]) + (z0[2] + z0[3])) + ((z1[0] + z1[1]) + (z1[2] + z1[3]));
;                     s2 += ((z0[0] * z0[0] + z0[1] * z0[1]) + (z0[2] * z0[2] + z0[3] * z0[3])) + ((z1[0] * z1[0] + z1[1] * z1[1]) + (z1[2] * z1[2] + z1[3] * z1[3])); }
;                 s1 = sum_fq(s1); s2 = sum_fq(s2);
;                 if (fq == 0) { atomicAdd(ST + 2 * row, s1); atomicAdd(ST + 2 * row + 1, s2); } }
	v_pk_fma_f32 v[102:103], v[106:107], s[12:13], v[102:103] op_sel_hi:[1,0,1]
	v_pk_fma_f32 v[100:101], v[104:105], s[12:13], v[100:101] op_sel_hi:[1,0,1]
	v_pk_fma_f32 v[106:107], v[108:109], s[12:13], v[96:97] op_sel_hi:[1,0,1]
	v_cvt_pk_bf16_f32 v96, v100, v101
	v_cvt_pk_bf16_f32 v97, v102, v103
	v_lshl_add_u64 v[108:109], s[8:9], 0, v[118:119]
	v_pk_fma_f32 v[104:105], v[110:111], s[12:13], v[98:99] op_sel_hi:[1,0,1]
	v_cvt_pk_bf16_f32 v98, v106, v107
	s_nop 0
	v_cvt_pk_bf16_f32 v99, v104, v105
	global_store_dwordx4 v[108:109], v[96:99], off
	s_nop 1
	v_add_f32_e32 v96, v100, v101
	v_add_f32_e32 v97, v102, v103
	v_add_f32_e32 v96, v96, v97
	v_add_f32_e32 v97, v106, v107
	v_add_f32_e32 v98, v104, v105
	v_add_f32_e32 v97, v97, v98
	v_add_f32_e32 v96, v96, v97
	v_mul_f32_e32 v97, v101, v101
	v_mul_f32_e32 v98, v103, v103
	v_fmac_f32_e32 v97, v100, v100
	v_fmac_f32_e32 v98, v102, v102
	v_add_f32_e32 v97, v97, v98
	v_mul_f32_e32 v98, v107, v107
	v_mul_f32_e32 v99, v105, v105
	v_fmac_f32_e32 v98, v106, v106
	v_fmac_f32_e32 v99, v104, v104
	v_add_f32_e32 v98, v98, v99
	v_add_f32_e32 v97, v97, v98
	v_add_f32_e32 v96, v113, v96
	v_add_f32_e32 v98, v114, v97
	v_mov_b32_e32 v97, v96
	v_mov_b32_e32 v99, v98
	s_nop 0
	v_permlane16_swap_b32_e32 v96, v97
	v_permlane16_swap_b32_e32 v98, v99
	v_add_f32_e32 v96, v96, v97
	v_add_f32_e32 v98, v98, v99
	v_mov_b32_e32 v97, v96
	v_mov_b32_e32 v99, v98
	s_nop 0
	v_permlane32_swap_b32_e32 v96, v97
	v_permlane32_swap_b32_e32 v98, v99
	s_and_saveexec_b64 s[0:1], s[40:41]
	s_cbranch_execz .LBB0_1140
	v_add_f32_e32 v98, v98, v99
	v_add_f32_e32 v99, v96, v97
	v_lshlrev_b32_e32 v96, 1, v112
	v_ashrrev_i32_e32 v97, 31, v96
	v_lshl_add_u64 v[96:97], v[96:97], 2, s[44:45]
	global_atomic_add_f32 v[96:97], v99, off
	global_atomic_add_f32 v[96:97], v98, off offset:4
.LBB0_1140:
	s_or_b64 exec, exec, s[0:1]
	v_or_b32_e32 v96, 32, v140
	v_ashrrev_i32_e32 v97, 31, v96
	v_lshlrev_b64 v[98:99], 11, v[96:97]
	v_lshl_add_u64 v[106:107], v[98:99], 0, v[138:139]
	v_lshl_add_u64 v[108:109], v[106:107], 2, s[4:5]
	global_load_dwordx4 v[98:101], v[108:109], off
	global_load_dwordx4 v[102:105], v[108:109], off offset:16
	s_waitcnt vmcnt(0) lgkmcnt(0)
	v_pk_fma_f32 v[94:95], v[100:101], s[12:13], v[94:95] op_sel_hi:[1,0,1]
	v_pk_fma_f32 v[100:101], v[102:103], s[12:13], v[88:89] op_sel_hi:[1,0,1]
	v_lshlrev_b64 v[102:103], 1, v[106:107]
	v_pk_fma_f32 v[92:93], v[98:99], s[12:13], v[92:93] op_sel_hi:[1,0,1]
	v_pk_fma_f32 v[98:99], v[104:105], s[12:13], v[90:91] op_sel_hi:[1,0,1]
	v_cvt_pk_bf16_f32 v88, v92, v93
	v_cvt_pk_bf16_f32 v89, v94, v95
	v_lshl_add_u64 v[104:105], s[8:9], 0, v[102:103]
	v_cvt_pk_bf16_f32 v90, v100, v101
	v_cvt_pk_bf16_f32 v91, v98, v99
	global_store_dwordx4 v[104:105], v[88:91], off
	v_or_b32_e32 v102, 0x100, v102
	s_nop 0
	v_add_f32_e32 v88, v92, v93
	v_add_f32_e32 v89, v94, v95
	v_add_f32_e32 v88, v88, v89
	v_add_f32_e32 v89, v100, v101
	v_add_f32_e32 v90, v98, v99
	v_add_f32_e32 v89, v89, v90
	v_add_f32_e32 v88, v88, v89
	v_add_f32_e32 v97, 0, v88
	v_mul_f32_e32 v88, v93, v93
	v_mul_f32_e32 v89, v95, v95
	v_fmac_f32_e32 v88, v92, v92
	v_fmac_f32_e32 v89, v94, v94
	v_add_f32_e32 v88, v88, v89
	v_mul_f32_e32 v89, v101, v101
	v_mul_f32_e32 v90, v99, v99
	v_fmac_f32_e32 v89, v100, v100
	v_fmac_f32_e32 v90, v98, v98
	v_add_f32_e32 v89, v89, v90
	v_add_f32_e32 v98, v88, v89
	global_load_dwordx4 v[88:91], v[108:109], off offset:512
	global_load_dwordx4 v[92:95], v[108:109], off offset:528
	s_waitcnt vmcnt(0) lgkmcnt(0)
	v_pk_fma_f32 v[86:87], v[90:91], s[12:13], v[86:87] op_sel_hi:[1,0,1]
	v_pk_fma_f32 v[84:85], v[88:89], s[12:13], v[84:85] op_sel_hi:[1,0,1]
	v_pk_fma_f32 v[90:91], v[92:93], s[12:13], v[80:81] op_sel_hi:[1,0,1]
	v_cvt_pk_bf16_f32 v80, v84, v85
	v_cvt_pk_bf16_f32 v81, v86, v87
	v_lshl_add_u64 v[92:93], s[8:9], 0, v[102:103]
	v_pk_fma_f32 v[88:89], v[94:95], s[12:13], v[82:83] op_sel_hi:[1,0,1]
	v_cvt_pk_bf16_f32 v82, v90, v91
	s_nop 0
	v_cvt_pk_bf16_f32 v83, v88, v89
	global_store_dwordx4 v[92:93], v[80:83], off
	s_nop 1
	v_add_f32_e32 v80, v84, v85
	v_add_f32_e32 v81, v86, v87
	v_add_f32_e32 v80, v80, v81
	v_add_f32_e32 v81, v90, v91
	v_add_f32_e32 v82, v88, v89
	v_add_f32_e32 v81, v81, v82
	v_add_f32_e32 v80, v80, v81
	v_mul_f32_e32 v81, v85, v85
	v_mul_f32_e32 v82, v87, v87
	v_fmac_f32_e32 v81, v84, v84
	v_fmac_f32_e32 v82, v86, v86
	v_add_f32_e32 v81, v81, v82
	v_mul_f32_e32 v82, v91, v91
	v_mul_f32_e32 v83, v89, v89
	v_fmac_f32_e32 v82, v90, v90
	v_fmac_f32_e32 v83, v88, v88
	v_add_f32_e32 v82, v82, v83
	v_add_f32_e32 v81, v81, v82
	v_add_f32_e32 v80, v97, v80
	v_add_f32_e32 v82, v98, v81
	v_mov_b32_e32 v81, v80
	v_mov_b32_e32 v83, v82
	s_nop 0
	v_permlane16_swap_b32_e32 v80, v81
	v_permlane16_swap_b32_e32 v82, v83
	v_add_f32_e32 v80, v80, v81
	v_add_f32_e32 v82, v82, v83
	v_mov_b32_e32 v81, v80
	v_mov_b32_e32 v83, v82
	s_nop 0
	v_permlane32_swap_b32_e32 v80, v81
	v_permlane32_swap_b32_e32 v82, v83
	s_and_saveexec_b64 s[0:1], s[40:41]
	s_cbranch_execz .LBB0_1142
	v_add_f32_e32 v82, v82, v83
	v_add_f32_e32 v83, v80, v81
	v_lshlrev_b32_e32 v80, 1, v96
	v_ashrrev_i32_e32 v81, 31, v80
	v_lshl_add_u64 v[80:81], v[80:81], 2, s[44:45]
	global_atomic_add_f32 v[80:81], v83, off
	global_atomic_add_f32 v[80:81], v82, off offset:4
; __device__ __forceinline__ unsigned cvt_pk_bf16(float lo, float hi) { unsigned r; asm volatile("v_cvt_pk_bf16_f32 %0, %1, %2" : "=v"(r) : "v"(lo), "v"(hi)); return r; }
;     __device__ __forceinline__ void operator()(const f32x4 (&acc)[2][2][4][2], const Unit& u, int wr, int wc, int fr, int fq) const {
;     ...
;             for (int m = 0; m < 4; ++m) { const int row = row0 + ai * HALF + m * 16; const size_t off = (size_t)row * ldc + col0; float s1 = 0.f, s2 = 0.f;
; #pragma unroll
;                 for (int bj = 0; bj < 2; ++bj) { const size_t o2 = off + bj * HALF; const f32x4 x0 = *(const f32x4*)(X + o2), x1 = *(const f32x4*)(X + o2 + 4);
;                     const f32x4 z0 = x0 * alpha + acc[ai][bj][m][0], z1 = x1 * alpha + acc[ai][bj][m][1];
;                     u32x4 w; w.x = cvt_pk_bf16(z0[0], z0[1]); w.y = cvt_pk_bf16(z0[2], z0[3]); w.z = cvt_pk_bf16(z1[0], z1[1]); w.w = cvt_pk_bf16(z1[2], z1[3]); *(u32x4*)(ZB + o2) = w;
;                     s1 += ((z0[0] + z0[1]) + (z0[2] + z0[3])) + ((z1[0] + z1[1]) + (z1[2] + z1[3]));
;                     s2 += ((z0[0] * z0[0] + z0[1] * z0[1]) + (z0[2] * z0[2] + z0[3] * z0[3])) + ((z1[0] * z1[0] + z1[1] * z1[1]) + (z1[2] * z1[2] + z1[3] * z1[3])); }
;                 s1 = sum_fq(s1); s2 = sum_fq(s2);
;                 if (fq == 0) { atomicAdd(ST + 2 * row, s1); atomicAdd(ST + 2 * row + 1, s2); } }
.LBB0_1142:
	s_or_b64 exec, exec, s[0:1]
	v_or_b32_e32 v80, 48, v140
	v_ashrrev_i32_e32 v81, 31, v80
	v_lshlrev_b64 v[82:83], 11, v[80:81]
	v_lshl_add_u64 v[90:91], v[82:83], 0, v[138:139]
	v_lshl_add_u64 v[92:93], v[90:91], 2, s[4:5]
	global_load_dwordx4 v[82:85], v[92:93], off
	global_load_dwordx4 v[86:89], v[92:93], off offset:16
	s_waitcnt vmcnt(0) lgkmcnt(0)
	v_pk_fma_f32 v[78:79], v[84:85], s[12:13], v[78:79] op_sel_hi:[1,0,1]
	v_pk_fma_f32 v[84:85], v[86:87], s[12:13], v[72:73] op_sel_hi:[1,0,1]
	v_lshlrev_b64 v[86:87], 1, v[90:91]
	v_pk_fma_f32 v[76:77], v[82:83], s[12:13], v[76:77] op_sel_hi:[1,0,1]
	v_pk_fma_f32 v[82:83], v[88:89], s[12:13], v[74:75] op_sel_hi:[1,0,1]
	v_cvt_pk_bf16_f32 v72, v76, v77
	v_cvt_pk_bf16_f32 v73, v78, v79
	v_lshl_add_u64 v[88:89], s[8:9], 0, v[86:87]
	v_cvt_pk_bf16_f32 v74, v84, v85
	v_cvt_pk_bf16_f32 v75, v82, v83
	global_store_dwordx4 v[88:89], v[72:75], off
	v_or_b32_e32 v86, 0x100, v86
	s_nop 0
	v_add_f32_e32 v72, v76, v77
	v_add_f32_e32 v73, v78, v79
	v_add_f32_e32 v72, v72, v73
	v_add_f32_e32 v73, v84, v85
	v_add_f32_e32 v74, v82, v83
	v_add_f32_e32 v73, v73, v74
	v_add_f32_e32 v72, v72, v73
	v_add_f32_e32 v81, 0, v72
	v_mul_f32_e32 v72, v77, v77
	v_mul_f32_e32 v73, v79, v79
	v_fmac_f32_e32 v72, v76, v76
	v_fmac_f32_e32 v73, v78, v78
	v_add_f32_e32 v72, v72, v73
	v_mul_f32_e32 v73, v85, v85
	v_mul_f32_e32 v74, v83, v83
	v_fmac_f32_e32 v73, v84, v84
	v_fmac_f32_e32 v74, v82, v82
	v_add_f32_e32 v73, v73, v74
	v_add_f32_e32 v82, v72, v73
	global_load_dwordx4 v[72:75], v[92:93], off offset:512
	global_load_dwordx4 v[76:79], v[92:93], off offset:528
	s_waitcnt vmcnt(0) lgkmcnt(0)
	v_pk_fma_f32 v[70:71], v[74:75], s[12:13], v[70:71] op_sel_hi:[1,0,1]
	v_pk_fma_f32 v[68:69], v[72:73], s[12:13], v[68:69] op_sel_hi:[1,0,1]
	v_pk_fma_f32 v[74:75], v[76:77], s[12:13], v[64:65] op_sel_hi:[1,0,1]
	v_cvt_pk_bf16_f32 v64, v68, v69
	v_cvt_pk_bf16_f32 v65, v70, v71
	v_lshl_add_u64 v[76:77], s[8:9], 0, v[86:87]
	v_pk_fma_f32 v[72:73], v[78:79], s[12:13], v[66:67] op_sel_hi:[1,0,1]
	v_cvt_pk_bf16_f32 v66, v74, v75
	s_nop 0
	v_cvt_pk_bf16_f32 v67, v72, v73
	global_store_dwordx4 v[76:77], v[64:67], off
	s_nop 1
	v_add_f32_e32 v64, v68, v69
	v_add_f32_e32 v65, v70, v71
	v_add_f32_e32 v64, v64, v65
	v_add_f32_e32 v65, v74, v75
	v_add_f32_e32 v66, v72, v73
	v_add_f32_e32 v65, v65, v66
	v_add_f32_e32 v64, v64, v65
	v_mul_f32_e32 v65, v69, v69
	v_mul_f32_e32 v66, v71, v71
	v_fmac_f32_e32 v65, v68, v68
	v_fmac_f32_e32 v66, v70, v70
	v_add_f32_e32 v65, v65, v66
	v_mul_f32_e32 v66, v75, v75
	v_mul_f32_e32 v67, v73, v73
	v_fmac_f32_e32 v66, v74, v74
	v_fmac_f32_e32 v67, v72, v72
	v_add_f32_e32 v66, v66, v67
	v_add_f32_e32 v65, v65, v66
	v_add_f32_e32 v64, v81, v64
	v_add_f32_e32 v66, v82, v65
	v_mov_b32_e32 v65, v64
	v_mov_b32_e32 v67, v66
	s_nop 0
	v_permlane16_swap_b32_e32 v64, v65
	v_permlane16_swap_b32_e32 v66, v67
	v_add_f32_e32 v64, v64, v65
	v_add_f32_e32 v66, v66, v67
	v_mov_b32_e32 v65, v64
	v_mov_b32_e32 v67, v66
	s_nop 0
	v_permlane32_swap_b32_e32 v64, v65
	v_permlane32_swap_b32_e32 v66, v67
	s_and_saveexec_b64 s[0:1], s[40:41]
	s_cbranch_execz .LBB0_1144
	v_add_f32_e32 v66, v66, v67
	v_add_f32_e32 v67, v64, v65
	v_lshlrev_b32_e32 v64, 1, v80
	v_ashrrev_i32_e32 v65, 31, v64
	v_lshl_add_u64 v[64:65], v[64:65], 2, s[44:45]
	global_atomic_add_f32 v[64:65], v67, off
	global_atomic_add_f32 v[64:65], v66, off offset:4
.LBB0_1144:
	s_or_b64 exec, exec, s[0:1]
	v_add_u32_e32 v64, 0x80, v140
	v_ashrrev_i32_e32 v65, 31, v64
	v_lshlrev_b64 v[66:67], 11, v[64:65]
	v_lshl_add_u64 v[74:75], v[66:67], 0, v[138:139]
	v_lshl_add_u64 v[76:77], v[74:75], 2, s[4:5]
	global_load_dwordx4 v[66:69], v[76:77], off
	global_load_dwordx4 v[70:73], v[76:77], off offset:16
	s_waitcnt vmcnt(0) lgkmcnt(0)
	v_pk_fma_f32 v[62:63], v[68:69], s[12:13], v[62:63] op_sel_hi:[1,0,1]
	v_pk_fma_f32 v[68:69], v[70:71], s[12:13], v[56:57] op_sel_hi:[1,0,1]
	v_lshlrev_b64 v[70:71], 1, v[74:75]
	v_pk_fma_f32 v[60:61], v[66:67], s[12:13], v[60:61] op_sel_hi:[1,0,1]
	v_pk_fma_f32 v[66:67], v[72:73], s[12:13], v[58:59] op_sel_hi:[1,0,1]
	v_cvt_pk_bf16_f32 v56, v60, v61
	v_cvt_pk_bf16_f32 v57, v62, v63
	v_lshl_add_u64 v[72:73], s[8:9], 0, v[70:71]
	v_cvt_pk_bf16_f32 v58, v68, v69
	v_cvt_pk_bf16_f32 v59, v66, v67
	global_store_dwordx4 v[72:73], v[56:59], off
	v_or_b32_e32 v70, 0x100, v70
	s_nop 0
	v_add_f32_e32 v56, v60, v61
	v_add_f32_e32 v57, v62, v63
	v_add_f32_e32 v56, v56, v57
	v_add_f32_e32 v57, v68, v69
	v_add_f32_e32 v58, v66, v67
	v_add_f32_e32 v57, v57, v58
	v_add_f32_e32 v56, v56, v57
	v_add_f32_e32 v65, 0, v56
	v_mul_f32_e32 v56, v61, v61
	v_mul_f32_e32 v57, v63, v63
	v_fmac_f32_e32 v56, v60, v60
	v_fmac_f32_e32 v57, v62, v62
	v_add_f32_e32 v56, v56, v57
	v_mul_f32_e32 v57, v69, v69
	v_mul_f32_e32 v58, v67, v67
	v_fmac_f32_e32 v57, v68, v68
	v_fmac_f32_e32 v58, v66, v66
	v_add_f32_e32 v57, v57, v58
	v_add_f32_e32 v66, v56, v57
	global_load_dwordx4 v[56:59], v[76:77], off offset:512
	global_load_dwordx4 v[60:63], v[76:77], off offset:528
	s_waitcnt vmcnt(0) lgkmcnt(0)
	v_pk_fma_f32 v[54:55], v[58:59], s[12:13], v[54:55] op_sel_hi:[1,0,1]
	v_pk_fma_f32 v[52:53], v[56:57], s[12:13], v[52:53] op_sel_hi:[1,0,1]
	v_pk_fma_f32 v[58:59], v[60:61], s[12:13], v[48:49] op_sel_hi:[1,0,1]
	v_cvt_pk_bf16_f32 v48, v52, v53
	v_cvt_pk_bf16_f32 v49, v54, v55
	v_lshl_add_u64 v[60:61], s[8:9], 0, v[70:71]
	v_pk_fma_f32 v[56:57], v[62:63], s[12:13], v[50:51] op_sel_hi:[1,0,1]
	v_cvt_pk_bf16_f32 v50, v58, v59
	s_nop 0
	v_cvt_pk_bf16_f32 v51, v56, v57
	global_store_dwordx4 v[60:61], v[48:51], off
	s_nop 1
	v_add_f32_e32 v48, v52, v53
	v_add_f32_e32 v49, v54, v55
	v_add_f32_e32 v48, v48, v49
	v_add_f32_e32 v49, v58, v59
	v_add_f32_e32 v50, v56, v57
	v_add_f32_e32 v49, v49, v50
	v_add_f32_e32 v48, v48, v49
	v_mul_f32_e32 v49, v53, v53
	v_mul_f32_e32 v50, v55, v55
	v_fmac_f32_e32 v49, v52, v52
	v_fmac_f32_e32 v50, v54, v54
	v_add_f32_e32 v49, v49, v50
	v_mul_f32_e32 v50, v59, v59
	v_mul_f32_e32 v51, v57, v57
	v_fmac_f32_e32 v50, v58, v58
	v_fmac_f32_e32 v51, v56, v56
	v_add_f32_e32 v50, v50, v51
	v_add_f32_e32 v49, v49, v50
	v_add_f32_e32 v48, v65, v48
	v_add_f32_e32 v50, v66, v49
	v_mov_b32_e32 v49, v48
	v_mov_b32_e32 v51, v50
	s_nop 0
	v_permlane16_swap_b32_e32 v48, v49
	v_permlane16_swap_b32_e32 v50, v51
	v_add_f32_e32 v48, v48, v49
	v_add_f32_e32 v50, v50, v51
	v_mov_b32_e32 v49, v48
	v_mov_b32_e32 v51, v50
	s_nop 0
	v_permlane32_swap_b32_e32 v48, v49
	v_permlane32_swap_b32_e32 v50, v51
	s_and_saveexec_b64 s[0:1], s[40:41]
	s_cbranch_execz .LBB0_1146
	v_add_f32_e32 v50, v50, v51
	v_add_f32_e32 v51, v48, v49
	v_lshlrev_b32_e32 v48, 1, v64
	v_ashrrev_i32_e32 v49, 31, v48
	v_lshl_add_u64 v[48:49], v[48:49], 2, s[44:45]
	global_atomic_add_f32 v[48:49], v51, off
	global_atomic_add_f32 v[48:49], v50, off offset:4
; __device__ __forceinline__ unsigned cvt_pk_bf16(float lo, float hi) { unsigned r; asm volatile("v_cvt_pk_bf16_f32 %0, %1, %2" : "=v"(r) : "v"(lo), "v"(hi)); return r; }
;     __device__ __forceinline__ void operator()(const f32x4 (&acc)[2][2][4][2], const Unit& u, int wr, int wc, int fr, int fq) const {
;     ...
;             for (int m = 0; m < 4; ++m) { const int row = row0 + ai * HALF + m * 16; const size_t off = (size_t)row * ldc + col0; float s1 = 0.f, s2 = 0.f;
; #pragma unroll
;                 for (int bj = 0; bj < 2; ++bj) { const size_t o2 = off + bj * HALF; const f32x4 x0 = *(const f32x4*)(X + o2), x1 = *(const f32x4*)(X + o2 + 4);
;                     const f32x4 z0 = x0 * alpha + acc[ai][bj][m][0], z1 = x1 * alpha + acc[ai][bj][m][1];
;                     u32x4 w; w.x = cvt_pk_bf16(z0[0], z0[1]); w.y = cvt_pk_bf16(z0[2], z0[3]); w.z = cvt_pk_bf16(z1[0], z1[1]); w.w = cvt_pk_bf16(z1[2], z1[3]); *(u32x4*)(ZB + o2) = w;
;                     s1 += ((z0[0] + z0[1]) + (z0[2] + z0[3])) + ((z1[0] + z1[1]) + (z1[2] + z1[3]));
;                     s2 += ((z0[0] * z0[0] + z0[1] * z0[1]) + (z0[2] * z0[2] + z0[3] * z0[3])) + ((z1[0] * z1[0] + z1[1] * z1[1]) + (z1[2] * z1[2] + z1[3] * z1[3])); }
;                 s1 = sum_fq(s1); s2 = sum_fq(s2);
;                 if (fq == 0) { atomicAdd(ST + 2 * row, s1); atomicAdd(ST + 2 * row + 1, s2); } }
.LBB0_1146:
	s_or_b64 exec, exec, s[0:1]
	v_add_u32_e32 v48, 0x90, v140
	v_ashrrev_i32_e32 v49, 31, v48
	v_lshlrev_b64 v[50:51], 11, v[48:49]
	v_lshl_add_u64 v[58:59], v[50:51], 0, v[138:139]
	v_lshl_add_u64 v[60:61], v[58:59], 2, s[4:5]
	global_load_dwordx4 v[50:53], v[60:61], off
	global_load_dwordx4 v[54:57], v[60:61], off offset:16
	s_waitcnt vmcnt(0) lgkmcnt(0)
	v_pk_fma_f32 v[46:47], v[52:53], s[12:13], v[46:47] op_sel_hi:[1,0,1]
	v_pk_fma_f32 v[52:53], v[54:55], s[12:13], v[40:41] op_sel_hi:[1,0,1]
	v_lshlrev_b64 v[54:55], 1, v[58:59]
	v_pk_fma_f32 v[44:45], v[50:51], s[12:13], v[44:45] op_sel_hi:[1,0,1]
	v_pk_fma_f32 v[50:51], v[56:57], s[12:13], v[42:43] op_sel_hi:[1,0,1]
	v_cvt_pk_bf16_f32 v40, v44, v45
	v_cvt_pk_bf16_f32 v41, v46, v47
	v_lshl_add_u64 v[56:57], s[8:9], 0, v[54:55]
	v_cvt_pk_bf16_f32 v42, v52, v53
	v_cvt_pk_bf16_f32 v43, v50, v51
	global_store_dwordx4 v[56:57], v[40:43], off
	v_or_b32_e32 v54, 0x100, v54
	s_nop 0
	v_add_f32_e32 v40, v44, v45
	v_add_f32_e32 v41, v46, v47
	v_add_f32_e32 v40, v40, v41
	v_add_f32_e32 v41, v52, v53
	v_add_f32_e32 v42, v50, v51
	v_add_f32_e32 v41, v41, v42
	v_add_f32_e32 v40, v40, v41
	v_add_f32_e32 v49, 0, v40
	v_mul_f32_e32 v40, v45, v45
	v_mul_f32_e32 v41, v47, v47
	v_fmac_f32_e32 v40, v44, v44
	v_fmac_f32_e32 v41, v46, v46
	v_add_f32_e32 v40, v40, v41
	v_mul_f32_e32 v41, v53, v53
	v_mul_f32_e32 v42, v51, v51
	v_fmac_f32_e32 v41, v52, v52
	v_fmac_f32_e32 v42, v50, v50
	v_add_f32_e32 v41, v41, v42
	v_add_f32_e32 v50, v40, v41
	global_load_dwordx4 v[40:43], v[60:61], off offset:512
	global_load_dwordx4 v[44:47], v[60:61], off offset:528
	s_waitcnt vmcnt(0) lgkmcnt(0)
	v_pk_fma_f32 v[38:39], v[42:43], s[12:13], v[38:39] op_sel_hi:[1,0,1]
	v_pk_fma_f32 v[36:37], v[40:41], s[12:13], v[36:37] op_sel_hi:[1,0,1]
	v_pk_fma_f32 v[42:43], v[44:45], s[12:13], v[32:33] op_sel_hi:[1,0,1]
	v_cvt_pk_bf16_f32 v32, v36, v37
	v_cvt_pk_bf16_f32 v33, v38, v39
	v_lshl_add_u64 v[44:45], s[8:9], 0, v[54:55]
	v_pk_fma_f32 v[40:41], v[46:47], s[12:13], v[34:35] op_sel_hi:[1,0,1]
	v_cvt_pk_bf16_f32 v34, v42, v43
	s_nop 0
	v_cvt_pk_bf16_f32 v35, v40, v41
	global_store_dwordx4 v[44:45], v[32:35], off
	s_nop 1
	v_add_f32_e32 v32, v36, v37
	v_add_f32_e32 v33, v38, v39
	v_add_f32_e32 v32, v32, v33
	v_add_f32_e32 v33, v42, v43
	v_add_f32_e32 v34, v40, v41
	v_add_f32_e32 v33, v33, v34
	v_add_f32_e32 v32, v32, v33
	v_mul_f32_e32 v33, v37, v37
	v_mul_f32_e32 v34, v39, v39
	v_fmac_f32_e32 v33, v36, v36
	v_fmac_f32_e32 v34, v38, v38
	v_add_f32_e32 v33, v33, v34
	v_mul_f32_e32 v34, v43, v43
	v_mul_f32_e32 v35, v41, v41
	v_fmac_f32_e32 v34, v42, v42
	v_fmac_f32_e32 v35, v40, v40
	v_add_f32_e32 v34, v34, v35
	v_add_f32_e32 v33, v33, v34
	v_add_f32_e32 v32, v49, v32
	v_add_f32_e32 v34, v50, v33
	v_mov_b32_e32 v33, v32
	v_mov_b32_e32 v35, v34
	s_nop 0
	v_permlane16_swap_b32_e32 v32, v33
	v_permlane16_swap_b32_e32 v34, v35
	v_add_f32_e32 v32, v32, v33
	v_add_f32_e32 v34, v34, v35
	v_mov_b32_e32 v33, v32
	v_mov_b32_e32 v35, v34
	s_nop 0
	v_permlane32_swap_b32_e32 v32, v33
	v_permlane32_swap_b32_e32 v34, v35
	s_and_saveexec_b64 s[0:1], s[40:41]
	s_cbranch_execz .LBB0_1148
	v_add_f32_e32 v34, v34, v35
	v_add_f32_e32 v35, v32, v33
	v_lshlrev_b32_e32 v32, 1, v48
	v_ashrrev_i32_e32 v33, 31, v32
	v_lshl_add_u64 v[32:33], v[32:33], 2, s[44:45]
	global_atomic_add_f32 v[32:33], v35, off
	global_atomic_add_f32 v[32:33], v34, off offset:4
; __device__ __forceinline__ unsigned cvt_pk_bf16(float lo, float hi) { unsigned r; asm volatile("v_cvt_pk_bf16_f32 %0, %1, %2" : "=v"(r) : "v"(lo), "v"(hi)); return r; }
;     __device__ __forceinline__ void operator()(const f32x4 (&acc)[2][2][4][2], const Unit& u, int wr, int wc, int fr, int fq) const {
;     ...
;             for (int m = 0; m < 4; ++m) { const int row = row0 + ai * HALF + m * 16; const size_t off = (size_t)row * ldc + col0; float s1 = 0.f, s2 = 0.f;
; #pragma unroll
;                 for (int bj = 0; bj < 2; ++bj) { const size_t o2 = off + bj * HALF; const f32x4 x0 = *(const f32x4*)(X + o2), x1 = *(const f32x4*)(X + o2 + 4);
;                     const f32x4 z0 = x0 * alpha + acc[ai][bj][m][0], z1 = x1 * alpha + acc[ai][bj][m][1];
;                     u32x4 w; w.x = cvt_pk_bf16(z0[0], z0[1]); w.y = cvt_pk_bf16(z0[2], z0[3]); w.z = cvt_pk_bf16(z1[0], z1[1]); w.w = cvt_pk_bf16(z1[2], z1[3]); *(u32x4*)(ZB + o2) = w;
;                     s1 += ((z0[0] + z0[1]) + (z0[2] + z0[3])) + ((z1[0] + z1[1]) + (z1[2] + z1[3]));
;                     s2 += ((z0[0] * z0[0] + z0[1] * z0[1]) + (z0[2] * z0[2] + z0[3] * z0[3])) + ((z1[0] * z1[0] + z1[1] * z1[1]) + (z1[2] * z1[2] + z1[3] * z1[3])); }
;                 s1 = sum_fq(s1); s2 = sum_fq(s2);
;                 if (fq == 0) { atomicAdd(ST + 2 * row, s1); atomicAdd(ST + 2 * row + 1, s2); } }
.LBB0_1148:
	s_or_b64 exec, exec, s[0:1]
	v_add_u32_e32 v32, 0xa0, v140
	v_ashrrev_i32_e32 v33, 31, v32
	v_lshlrev_b64 v[34:35], 11, v[32:33]
	v_lshl_add_u64 v[42:43], v[34:35], 0, v[138:139]
	v_lshl_add_u64 v[44:45], v[42:43], 2, s[4:5]
	global_load_dwordx4 v[34:37], v[44:45], off
	global_load_dwordx4 v[38:41], v[44:45], off offset:16
	s_waitcnt vmcnt(0) lgkmcnt(0)
	v_pk_fma_f32 v[30:31], v[36:37], s[12:13], v[30:31] op_sel_hi:[1,0,1]
	v_pk_fma_f32 v[36:37], v[38:39], s[12:13], v[24:25] op_sel_hi:[1,0,1]
	v_lshlrev_b64 v[38:39], 1, v[42:43]
	v_pk_fma_f32 v[28:29], v[34:35], s[12:13], v[28:29] op_sel_hi:[1,0,1]
	v_pk_fma_f32 v[34:35], v[40:41], s[12:13], v[26:27] op_sel_hi:[1,0,1]
	v_cvt_pk_bf16_f32 v24, v28, v29
	v_cvt_pk_bf16_f32 v25, v30, v31
	v_lshl_add_u64 v[40:41], s[8:9], 0, v[38:39]
	v_cvt_pk_bf16_f32 v26, v36, v37
	v_cvt_pk_bf16_f32 v27, v34, v35
	global_store_dwordx4 v[40:41], v[24:27], off
	v_or_b32_e32 v38, 0x100, v38
	s_nop 0
	v_add_f32_e32 v24, v28, v29
	v_add_f32_e32 v25, v30, v31
	v_add_f32_e32 v24, v24, v25
	v_add_f32_e32 v25, v36, v37
	v_add_f32_e32 v26, v34, v35
	v_add_f32_e32 v25, v25, v26
	v_add_f32_e32 v24, v24, v25
	v_add_f32_e32 v33, 0, v24
	v_mul_f32_e32 v24, v29, v29
	v_mul_f32_e32 v25, v31, v31
	v_fmac_f32_e32 v24, v28, v28
	v_fmac_f32_e32 v25, v30, v30
	v_add_f32_e32 v24, v24, v25
	v_mul_f32_e32 v25, v37, v37
	v_mul_f32_e32 v26, v35, v35
	v_fmac_f32_e32 v25, v36, v36
	v_fmac_f32_e32 v26, v34, v34
	v_add_f32_e32 v25, v25, v26
	v_add_f32_e32 v34, v24, v25
	global_load_dwordx4 v[24:27], v[44:45], off offset:512
	global_load_dwordx4 v[28:31], v[44:45], off offset:528
	s_waitcnt vmcnt(0) lgkmcnt(0)
	v_pk_fma_f32 v[22:23], v[26:27], s[12:13], v[22:23] op_sel_hi:[1,0,1]
	v_pk_fma_f32 v[20:21], v[24:25], s[12:13], v[20:21] op_sel_hi:[1,0,1]
	v_pk_fma_f32 v[26:27], v[28:29], s[12:13], v[16:17] op_sel_hi:[1,0,1]
	v_cvt_pk_bf16_f32 v16, v20, v21
	v_cvt_pk_bf16_f32 v17, v22, v23
	v_lshl_add_u64 v[28:29], s[8:9], 0, v[38:39]
	v_pk_fma_f32 v[24:25], v[30:31], s[12:13], v[18:19] op_sel_hi:[1,0,1]
	v_cvt_pk_bf16_f32 v18, v26, v27
	s_nop 0
	v_cvt_pk_bf16_f32 v19, v24, v25
	global_store_dwordx4 v[28:29], v[16:19], off
	s_nop 1
	v_add_f32_e32 v16, v20, v21
	v_add_f32_e32 v17, v22, v23
	v_add_f32_e32 v16, v16, v17
	v_add_f32_e32 v17, v26, v27
	v_add_f32_e32 v18, v24, v25
	v_add_f32_e32 v17, v17, v18
	v_add_f32_e32 v16, v16, v17
	v_mul_f32_e32 v17, v21, v21
	v_mul_f32_e32 v18, v23, v23
	v_fmac_f32_e32 v17, v20, v20
	v_fmac_f32_e32 v18, v22, v22
	v_add_f32_e32 v17, v17, v18
	v_mul_f32_e32 v18, v27, v27
	v_mul_f32_e32 v19, v25, v25
	v_fmac_f32_e32 v18, v26, v26
	v_fmac_f32_e32 v19, v24, v24
	v_add_f32_e32 v18, v18, v19
	v_add_f32_e32 v17, v17, v18
	v_add_f32_e32 v16, v33, v16
	v_add_f32_e32 v18, v34, v17
	v_mov_b32_e32 v17, v16
	v_mov_b32_e32 v19, v18
	s_nop 0
	v_permlane16_swap_b32_e32 v16, v17
	v_permlane16_swap_b32_e32 v18, v19
	v_add_f32_e32 v16, v16, v17
	v_add_f32_e32 v18, v18, v19
	v_mov_b32_e32 v17, v16
	v_mov_b32_e32 v19, v18
	s_nop 0
	v_permlane32_swap_b32_e32 v16, v17
	v_permlane32_swap_b32_e32 v18, v19
	s_and_saveexec_b64 s[0:1], s[40:41]
	s_cbranch_execz .LBB0_1150
	v_add_f32_e32 v18, v18, v19
	v_add_f32_e32 v19, v16, v17
	v_lshlrev_b32_e32 v16, 1, v32
	v_ashrrev_i32_e32 v17, 31, v16
	v_lshl_add_u64 v[16:17], v[16:17], 2, s[44:45]
	global_atomic_add_f32 v[16:17], v19, off
	global_atomic_add_f32 v[16:17], v18, off offset:4
.LBB0_1150:
	s_or_b64 exec, exec, s[0:1]
	v_add_u32_e32 v16, 0xb0, v140
	v_ashrrev_i32_e32 v17, 31, v16
	v_lshlrev_b64 v[18:19], 11, v[16:17]
	v_lshl_add_u64 v[26:27], v[18:19], 0, v[138:139]
	v_lshl_add_u64 v[28:29], v[26:27], 2, s[4:5]
	global_load_dwordx4 v[18:21], v[28:29], off
	global_load_dwordx4 v[22:25], v[28:29], off offset:16
	s_waitcnt vmcnt(0) lgkmcnt(0)
	v_pk_fma_f32 v[14:15], v[20:21], s[12:13], v[14:15] op_sel_hi:[1,0,1]
	v_pk_fma_f32 v[20:21], v[22:23], s[12:13], v[8:9] op_sel_hi:[1,0,1]
	v_lshlrev_b64 v[22:23], 1, v[26:27]
	v_pk_fma_f32 v[12:13], v[18:19], s[12:13], v[12:13] op_sel_hi:[1,0,1]
	v_pk_fma_f32 v[18:19], v[24:25], s[12:13], v[10:11] op_sel_hi:[1,0,1]
	v_cvt_pk_bf16_f32 v8, v12, v13
	v_cvt_pk_bf16_f32 v9, v14, v15
	v_lshl_add_u64 v[24:25], s[8:9], 0, v[22:23]
	v_cvt_pk_bf16_f32 v10, v20, v21
	v_cvt_pk_bf16_f32 v11, v18, v19
	global_store_dwordx4 v[24:25], v[8:11], off
	v_or_b32_e32 v22, 0x100, v22
	s_nop 0
	v_add_f32_e32 v8, v12, v13
	v_add_f32_e32 v9, v14, v15
	v_add_f32_e32 v8, v8, v9
	v_add_f32_e32 v9, v20, v21
	v_add_f32_e32 v10, v18, v19
	v_add_f32_e32 v9, v9, v10
	v_add_f32_e32 v8, v8, v9
	v_add_f32_e32 v17, 0, v8
	v_mul_f32_e32 v8, v13, v13
	v_mul_f32_e32 v9, v15, v15
	v_fmac_f32_e32 v8, v12, v12
	v_fmac_f32_e32 v9, v14, v14
	v_add_f32_e32 v8, v8, v9
	v_mul_f32_e32 v9, v21, v21
	v_mul_f32_e32 v10, v19, v19
	v_fmac_f32_e32 v9, v20, v20
	v_fmac_f32_e32 v10, v18, v18
	v_add_f32_e32 v9, v9, v10
	v_add_f32_e32 v18, v8, v9
	global_load_dwordx4 v[8:11], v[28:29], off offset:512
	global_load_dwordx4 v[12:15], v[28:29], off offset:528
	s_waitcnt vmcnt(0) lgkmcnt(0)
	v_pk_fma_f32 v[6:7], v[10:11], s[12:13], v[6:7] op_sel_hi:[1,0,1]
	v_pk_fma_f32 v[4:5], v[8:9], s[12:13], v[4:5] op_sel_hi:[1,0,1]
	v_pk_fma_f32 v[10:11], v[12:13], s[12:13], v[0:1] op_sel_hi:[1,0,1]
	v_cvt_pk_bf16_f32 v0, v4, v5
	v_cvt_pk_bf16_f32 v1, v6, v7
	v_lshl_add_u64 v[12:13], s[8:9], 0, v[22:23]
	v_pk_fma_f32 v[8:9], v[14:15], s[12:13], v[2:3] op_sel_hi:[1,0,1]
	v_cvt_pk_bf16_f32 v2, v10, v11
	s_nop 0
	v_cvt_pk_bf16_f32 v3, v8, v9
	global_store_dwordx4 v[12:13], v[0:3], off
	s_nop 1
	v_add_f32_e32 v0, v4, v5
	v_add_f32_e32 v1, v6, v7
	v_add_f32_e32 v0, v0, v1
	v_add_f32_e32 v1, v10, v11
	v_add_f32_e32 v2, v8, v9
	v_add_f32_e32 v1, v1, v2
	v_add_f32_e32 v0, v0, v1
	v_mul_f32_e32 v1, v5, v5
	v_mul_f32_e32 v2, v7, v7
	v_fmac_f32_e32 v1, v4, v4
	v_fmac_f32_e32 v2, v6, v6
	v_add_f32_e32 v1, v1, v2
	v_mul_f32_e32 v2, v11, v11
	v_mul_f32_e32 v3, v9, v9
	v_fmac_f32_e32 v2, v10, v10
	v_fmac_f32_e32 v3, v8, v8
	v_add_f32_e32 v2, v2, v3
	v_add_f32_e32 v1, v1, v2
	v_add_f32_e32 v0, v17, v0
	v_add_f32_e32 v2, v18, v1
	v_mov_b32_e32 v1, v0
	v_mov_b32_e32 v3, v2
	s_nop 0
	v_permlane16_swap_b32_e32 v0, v1
	v_permlane16_swap_b32_e32 v2, v3
	v_add_f32_e32 v0, v0, v1
	v_add_f32_e32 v2, v2, v3
	v_mov_b32_e32 v1, v0
	v_mov_b32_e32 v3, v2
	s_nop 0
	v_permlane32_swap_b32_e32 v0, v1
	v_permlane32_swap_b32_e32 v2, v3
	s_and_saveexec_b64 s[0:1], s[40:41]
	s_cbranch_execz .LBB0_1152
	v_add_f32_e32 v2, v2, v3
	v_add_f32_e32 v3, v0, v1
	v_lshlrev_b32_e32 v0, 1, v16
	v_ashrrev_i32_e32 v1, 31, v0
	v_lshl_add_u64 v[0:1], v[0:1], 2, s[44:45]
	global_atomic_add_f32 v[0:1], v3, off
	global_atomic_add_f32 v[0:1], v2, off offset:4

; __device__ __forceinline__ unsigned cvt_pk_bf16(float lo, float hi) { unsigned r; asm volatile("v_cvt_pk_bf16_f32 %0, %1, %2" : "=v"(r) : "v"(lo), "v"(hi)); return r; }
; __device__ __forceinline__ float bf_lo(unsigned w) { return __uint_as_float(w << 16); }
; __device__ __forceinline__ float bf_hi(unsigned w) { return __uint_as_float(w & 0xffff0000u); }
;     __device__ __forceinline__ void operator()(const f32x4 (&acc)[2][2][4][2], const Unit& u, int wr, int wc, int fr, int fq) const {
;     ...
;         for (int bj = 0; bj < 2; ++bj) { const int col = col0 + bj * HALF;
;             f32x4 c1[2], c2[2], lg[2], lb[2];
; #pragma unroll
;             for (int n = 0; n < 2; ++n) { c1[n] = *(const f32x4*)(C1 + col + 4 * n); c2[n] = *(const f32x4*)(C2 + col + 4 * n); lg[n] = *(const f32x4*)(LG + col + 4 * n); lb[n] = *(const f32x4*)(LB + col + 4 * n); }
; #pragma unroll
;             for (int ai = 0; ai < 2; ++ai)
; #pragma unroll
;                 for (int m = 0; m < 4; ++m) { const int row = row0 + ai * HALF + m * 16; const size_t o2 = (size_t)row * ldc + col;
;                     const float s1 = ST[2 * row], s2 = ST[2 * row + 1], mu = s1 * (1.f / 2048.f), rstd = __builtin_amdgcn_rsqf(fmaxf(s2 * (1.f / 2048.f) - mu * mu, 0.f) + 1e-5f);
;                     const u32x4 zw = *(const u32x4*)(Zb + o2), pw = *(const u32x4*)(PE + o2); u32x4 xw;
; #pragma unroll
;                     for (int n = 0; n < 2; ++n) { const unsigned za = n ? zw.z : zw.x, zb2 = n ? zw.w : zw.y, pa = n ? pw.z : pw.x, pb = n ? pw.w : pw.y;
;                         const float zv[4] = {bf_lo(za), bf_hi(za), bf_lo(zb2), bf_hi(zb2)}, pv[4] = {bf_lo(pa), bf_hi(pa), bf_lo(pb), bf_hi(pb)}; const f32x4 a = acc[ai][bj][m][n]; f32x4 o;
; #pragma unroll
;                         for (int e = 0; e < 4; ++e) { const float sv = rstd * (a[e] - mu * c1[n][e]) + c2[n][e]; const float xl = (zv[e] - mu) * rstd * lg[n][e] + lb[n][e]; o[e] = xl + pv[e] * __builtin_amdgcn_rcpf(1.f + __expf(-sv)); }
;                         *(f32x4*)(OUTF + o2 + 4 * n) = o; if (n == 0) { xw.x = cvt_pk_bf16(o[0], o[1]); xw.y = cvt_pk_bf16(o[2], o[3]); } else { xw.z = cvt_pk_bf16(o[0], o[1]); xw.w = cvt_pk_bf16(o[2], o[3]); } }
;                     if (XB) *(u32x4*)(XB + o2) = xw; }
.LBB0_1344:
	v_lshl_add_u32 v198, s41, 8, v205
	v_lshl_or_b32 v188, s40, 8, v207
	v_ashrrev_i32_e32 v189, 31, v188
	v_lshlrev_b32_e32 v160, 1, v198
	v_lshlrev_b64 v[88:89], 2, v[188:189]
	v_ashrrev_i32_e32 v161, 31, v160
	v_lshl_add_u64 v[184:185], s[96:97], 0, v[88:89]
	v_lshl_add_u64 v[196:197], v[160:161], 2, s[94:95]
	v_lshl_add_u64 v[186:187], s[4:5], 0, v[88:89]
	v_lshl_add_u64 v[192:193], s[56:57], 0, v[88:89]
	v_lshl_add_u64 v[190:191], s[58:59], 0, v[88:89]
	global_load_dwordx4 v[116:119], v[184:185], off
	global_load_dwordx4 v[96:99], v[186:187], off
	global_load_dwordx4 v[88:91], v[192:193], off offset:16
	global_load_dwordx4 v[104:107], v[192:193], off
	global_load_dwordx4 v[92:95], v[190:191], off offset:16
	global_load_dwordx4 v[108:111], v[190:191], off
	global_load_dwordx4 v[124:127], v[184:185], off offset:16
	global_load_dwordx4 v[100:103], v[186:187], off offset:16
	global_load_dwordx2 v[160:161], v[196:197], off
	s_mov_b32 s0, 0x3a000000
	v_ashrrev_i32_e32 v199, 31, v198
	v_lshlrev_b64 v[194:195], 11, v[198:199]
	v_lshl_add_u64 v[200:201], v[194:195], 0, v[188:189]
	v_readlane_b32 s2, v255, 48
	v_readlane_b32 s3, v255, 49
	s_andn2_b64 vcc, exec, s[2:3]
	s_mov_b64 s[74:75], 0x80000
	s_waitcnt vmcnt(0) lgkmcnt(0)
	v_pk_mul_f32 v[202:203], v[160:161], s[0:1] op_sel_hi:[1,0]
	s_nop 0
	v_fma_f32 v160, -v202, v202, v203
	v_max_f32_e32 v160, 0, v160
	v_add_f32_e32 v160, 0x3727c5ac, v160
	v_rsq_f32_e32 v204, v160
	v_lshlrev_b64 v[160:161], 1, v[200:201]
	v_lshl_add_u64 v[162:163], s[82:83], 0, v[160:161]
	global_load_dwordx4 v[164:167], v[162:163], off
	v_lshl_add_u64 v[160:161], s[92:93], 0, v[160:161]
	global_load_dwordx4 v[160:163], v[160:161], off
	v_fma_f32 v156, -v116, v202, v156
	v_fma_f32 v157, -v117, v202, v157
	v_fma_f32 v158, -v118, v202, v158
	v_fma_f32 v159, -v119, v202, v159
	v_fma_f32 v156, v156, v204, v96
	v_fma_f32 v157, v157, v204, v97
	v_fma_f32 v158, v158, v204, v98
	v_fma_f32 v159, v159, v204, v99
	v_mul_f32_e32 v156, 0xbfb8aa3b, v156
	v_mul_f32_e32 v157, 0xbfb8aa3b, v157
	v_mul_f32_e32 v158, 0xbfb8aa3b, v158
	v_mul_f32_e32 v159, 0xbfb8aa3b, v159
	v_exp_f32_e32 v156, v156
	v_exp_f32_e32 v157, v157
	v_exp_f32_e32 v158, v158
	v_exp_f32_e32 v159, v159
	v_fma_f32 v152, -v124, v202, v152
	v_fma_f32 v153, -v125, v202, v153
	v_fma_f32 v152, v152, v204, v100
	v_fma_f32 v153, v153, v204, v101
	v_add_f32_e32 v156, 1.0, v156
	v_add_f32_e32 v157, 1.0, v157
	v_add_f32_e32 v158, 1.0, v158
	v_add_f32_e32 v159, 1.0, v159
	v_mul_f32_e32 v152, 0xbfb8aa3b, v152
	v_mul_f32_e32 v153, 0xbfb8aa3b, v153
	v_rcp_f32_e32 v156, v156
	v_rcp_f32_e32 v157, v157
	v_rcp_f32_e32 v158, v158
	v_rcp_f32_e32 v159, v159
	v_exp_f32_e32 v152, v152
	v_exp_f32_e32 v153, v153
	v_fma_f32 v154, -v126, v202, v154
	v_fma_f32 v155, -v127, v202, v155
	v_fma_f32 v154, v154, v204, v102
	v_fma_f32 v155, v155, v204, v103
	v_mul_f32_e32 v154, 0xbfb8aa3b, v154
	v_mul_f32_e32 v155, 0xbfb8aa3b, v155
	v_add_f32_e32 v152, 1.0, v152
	v_add_f32_e32 v153, 1.0, v153
	v_exp_f32_e32 v154, v154
	v_exp_f32_e32 v155, v155
	v_rcp_f32_e32 v152, v152
	v_rcp_f32_e32 v153, v153
	v_add_f32_e32 v154, 1.0, v154
	v_add_f32_e32 v155, 1.0, v155
	v_rcp_f32_e32 v154, v154
	v_rcp_f32_e32 v155, v155
	s_waitcnt vmcnt(0) lgkmcnt(0)
	v_lshlrev_b32_e32 v210, 16, v164
	v_and_b32_e32 v211, 0xffff0000, v164
	v_lshlrev_b32_e32 v164, 16, v165
	v_and_b32_e32 v165, 0xffff0000, v165
	v_pk_add_f32 v[210:211], v[210:211], v[202:203] op_sel_hi:[1,0] neg_lo:[0,1] neg_hi:[0,1]
	v_pk_add_f32 v[164:165], v[164:165], v[202:203] op_sel_hi:[1,0] neg_lo:[0,1] neg_hi:[0,1]
	v_pk_mul_f32 v[210:211], v[204:205], v[210:211] op_sel_hi:[0,1]
	v_pk_mul_f32 v[164:165], v[204:205], v[164:165] op_sel_hi:[0,1]
	v_lshlrev_b32_e32 v212, 16, v160
	v_and_b32_e32 v213, 0xffff0000, v160
	v_pk_fma_f32 v[210:211], v[104:105], v[210:211], v[108:109]
	v_lshlrev_b32_e32 v160, 16, v161
	v_and_b32_e32 v161, 0xffff0000, v161
	v_pk_fma_f32 v[164:165], v[106:107], v[164:165], v[110:111]
	v_pk_fma_f32 v[156:157], v[156:157], v[212:213], v[210:211]
	v_pk_fma_f32 v[158:159], v[158:159], v[160:161], v[164:165]
	v_lshl_add_u64 v[160:161], v[200:201], 2, s[8:9]
	global_store_dwordx4 v[160:161], v[156:159], off
	v_lshlrev_b32_e32 v164, 16, v162
	v_and_b32_e32 v165, 0xffff0000, v162
	v_cvt_pk_bf16_f32 v156, v156, v157
	v_cvt_pk_bf16_f32 v157, v158, v159
	v_lshlrev_b32_e32 v158, 16, v166
	v_and_b32_e32 v159, 0xffff0000, v166
	v_pk_add_f32 v[158:159], v[158:159], v[202:203] op_sel_hi:[1,0] neg_lo:[0,1] neg_hi:[0,1]
	v_lshlrev_b32_e32 v162, 16, v163
	v_pk_mul_f32 v[158:159], v[204:205], v[158:159] op_sel_hi:[0,1]
	v_pk_fma_f32 v[158:159], v[88:89], v[158:159], v[92:93]
	v_and_b32_e32 v163, 0xffff0000, v163
	v_pk_fma_f32 v[152:153], v[152:153], v[164:165], v[158:159]
	v_lshlrev_b32_e32 v158, 16, v167
	v_and_b32_e32 v159, 0xffff0000, v167
	v_pk_add_f32 v[158:159], v[158:159], v[202:203] op_sel_hi:[1,0] neg_lo:[0,1] neg_hi:[0,1]
	s_nop 0
	v_pk_mul_f32 v[158:159], v[204:205], v[158:159] op_sel_hi:[0,1]
	v_pk_fma_f32 v[158:159], v[90:91], v[158:159], v[94:95]
	s_nop 0
	v_pk_fma_f32 v[154:155], v[154:155], v[162:163], v[158:159]
	global_store_dwordx4 v[160:161], v[152:155], off offset:16
	v_cvt_pk_bf16_f32 v158, v152, v153
	v_cvt_pk_bf16_f32 v159, v154, v155
	s_nop 1
	v_cndmask_b32_e64 v152, 0, 1, s[2:3]
	v_cmp_ne_u32_e64 s[40:41], 1, v152
	s_cbranch_vccnz .LBB0_1346
	v_lshl_add_u64 v[152:153], v[200:201], 1, s[90:91]
	global_store_dwordx4 v[152:153], v[156:159], off
; __device__ __forceinline__ unsigned cvt_pk_bf16(float lo, float hi) { unsigned r; asm volatile("v_cvt_pk_bf16_f32 %0, %1, %2" : "=v"(r) : "v"(lo), "v"(hi)); return r; }
; __device__ __forceinline__ float bf_lo(unsigned w) { return __uint_as_float(w << 16); }
; __device__ __forceinline__ float bf_hi(unsigned w) { return __uint_as_float(w & 0xffff0000u); }
;     __device__ __forceinline__ void operator()(const f32x4 (&acc)[2][2][4][2], const Unit& u, int wr, int wc, int fr, int fq) const {
;     ...
;                 for (int m = 0; m < 4; ++m) { const int row = row0 + ai * HALF + m * 16; const size_t o2 = (size_t)row * ldc + col;
;                     const float s1 = ST[2 * row], s2 = ST[2 * row + 1], mu = s1 * (1.f / 2048.f), rstd = __builtin_amdgcn_rsqf(fmaxf(s2 * (1.f / 2048.f) - mu * mu, 0.f) + 1e-5f);
;                     const u32x4 zw = *(const u32x4*)(Zb + o2), pw = *(const u32x4*)(PE + o2); u32x4 xw;
; #pragma unroll
;                     for (int n = 0; n < 2; ++n) { const unsigned za = n ? zw.z : zw.x, zb2 = n ? zw.w : zw.y, pa = n ? pw.z : pw.x, pb = n ? pw.w : pw.y;
;                         const float zv[4] = {bf_lo(za), bf_hi(za), bf_lo(zb2), bf_hi(zb2)}, pv[4] = {bf_lo(pa), bf_hi(pa), bf_lo(pb), bf_hi(pb)}; const f32x4 a = acc[ai][bj][m][n]; f32x4 o;
; #pragma unroll
;                         for (int e = 0; e < 4; ++e) { const float sv = rstd * (a[e] - mu * c1[n][e]) + c2[n][e]; const float xl = (zv[e] - mu) * rstd * lg[n][e] + lb[n][e]; o[e] = xl + pv[e] * __builtin_amdgcn_rcpf(1.f + __expf(-sv)); }
;                         *(f32x4*)(OUTF + o2 + 4 * n) = o; if (n == 0) { xw.x = cvt_pk_bf16(o[0], o[1]); xw.y = cvt_pk_bf16(o[2], o[3]); } else { xw.z = cvt_pk_bf16(o[0], o[1]); xw.w = cvt_pk_bf16(o[2], o[3]); } }
;                     if (XB) *(u32x4*)(XB + o2) = xw; }
.LBB0_1346:
	v_or_b32_e32 v152, 16, v198
	v_lshlrev_b32_e32 v154, 1, v152
	v_ashrrev_i32_e32 v155, 31, v154
	v_lshl_add_u64 v[154:155], v[154:155], 2, s[94:95]
	global_load_dwordx2 v[166:167], v[154:155], off
	v_ashrrev_i32_e32 v153, 31, v152
	v_lshlrev_b64 v[156:157], 11, v[152:153]
	v_lshl_add_u64 v[158:159], v[156:157], 0, v[188:189]
	v_lshlrev_b64 v[152:153], 1, v[158:159]
	v_lshl_add_u64 v[162:163], s[82:83], 0, v[152:153]
	global_load_dwordx4 v[162:165], v[162:163], off
	v_lshl_add_u64 v[152:153], s[92:93], 0, v[152:153]
	global_load_dwordx4 v[200:203], v[152:153], off
	s_and_b64 vcc, exec, s[40:41]
	v_lshl_add_u64 v[152:153], v[158:159], 2, s[8:9]
	s_waitcnt vmcnt(0) lgkmcnt(0)
	v_pk_mul_f32 v[166:167], v[166:167], s[0:1] op_sel_hi:[1,0]
	s_nop 0
	v_fma_f32 v199, -v166, v166, v167
	v_max_f32_e32 v199, 0, v199
	v_add_f32_e32 v199, 0x3727c5ac, v199
	v_rsq_f32_e32 v204, v199
	v_fma_f32 v209, -v116, v166, v148
	v_fma_f32 v210, -v117, v166, v149
	v_fma_f32 v211, -v118, v166, v150
	v_fma_f32 v212, -v119, v166, v151
	v_fma_f32 v213, -v124, v166, v144
	v_fma_f32 v224, -v125, v166, v145
	v_fma_f32 v225, -v126, v166, v146
	v_fma_f32 v226, -v127, v166, v147
	v_lshlrev_b32_e32 v144, 16, v162
	v_and_b32_e32 v145, 0xffff0000, v162
	v_lshlrev_b32_e32 v148, 16, v163
	v_and_b32_e32 v149, 0xffff0000, v163
	v_lshlrev_b32_e32 v162, 16, v164
	v_and_b32_e32 v163, 0xffff0000, v164
	v_lshlrev_b32_e32 v164, 16, v165
	v_and_b32_e32 v165, 0xffff0000, v165
	v_pk_add_f32 v[144:145], v[144:145], v[166:167] op_sel_hi:[1,0] neg_lo:[0,1] neg_hi:[0,1]
	v_pk_add_f32 v[148:149], v[148:149], v[166:167] op_sel_hi:[1,0] neg_lo:[0,1] neg_hi:[0,1]
	v_pk_add_f32 v[162:163], v[162:163], v[166:167] op_sel_hi:[1,0] neg_lo:[0,1] neg_hi:[0,1]
	v_pk_add_f32 v[164:165], v[164:165], v[166:167] op_sel_hi:[1,0] neg_lo:[0,1] neg_hi:[0,1]
	v_fma_f32 v166, v209, v204, v96
	v_fma_f32 v167, v210, v204, v97
	v_fma_f32 v199, v211, v204, v98
	v_fma_f32 v209, v212, v204, v99
	v_fma_f32 v210, v213, v204, v100
	v_fma_f32 v211, v224, v204, v101
	v_fma_f32 v212, v225, v204, v102
	v_fma_f32 v213, v226, v204, v103
	v_pk_mul_f32 v[144:145], v[204:205], v[144:145] op_sel_hi:[0,1]
	v_pk_mul_f32 v[148:149], v[204:205], v[148:149] op_sel_hi:[0,1]
	v_pk_mul_f32 v[162:163], v[204:205], v[162:163] op_sel_hi:[0,1]
	v_pk_mul_f32 v[164:165], v[204:205], v[164:165] op_sel_hi:[0,1]
	v_mul_f32_e32 v166, 0xbfb8aa3b, v166
	v_mul_f32_e32 v167, 0xbfb8aa3b, v167
	v_mul_f32_e32 v199, 0xbfb8aa3b, v199
	v_mul_f32_e32 v204, 0xbfb8aa3b, v209
	v_mul_f32_e32 v209, 0xbfb8aa3b, v210
	v_mul_f32_e32 v210, 0xbfb8aa3b, v211
	v_mul_f32_e32 v211, 0xbfb8aa3b, v212
	v_mul_f32_e32 v212, 0xbfb8aa3b, v213
	v_exp_f32_e32 v166, v166
	v_exp_f32_e32 v167, v167
	v_exp_f32_e32 v199, v199
	v_exp_f32_e32 v204, v204
	v_exp_f32_e32 v209, v209
	v_exp_f32_e32 v210, v210
	v_exp_f32_e32 v211, v211
	v_exp_f32_e32 v212, v212
	v_add_f32_e32 v166, 1.0, v166
	v_add_f32_e32 v167, 1.0, v167
	v_add_f32_e32 v199, 1.0, v199
	v_add_f32_e32 v204, 1.0, v204
	v_add_f32_e32 v209, 1.0, v209
	v_add_f32_e32 v213, 1.0, v210
	v_add_f32_e32 v224, 1.0, v211
	v_add_f32_e32 v225, 1.0, v212
	v_rcp_f32_e32 v166, v166
	v_rcp_f32_e32 v167, v167
	v_rcp_f32_e32 v210, v199
	v_rcp_f32_e32 v211, v204
	v_rcp_f32_e32 v212, v209
	v_rcp_f32_e32 v213, v213
	v_rcp_f32_e32 v224, v224
	v_rcp_f32_e32 v225, v225
	v_lshlrev_b32_e32 v146, 16, v200
	v_and_b32_e32 v147, 0xffff0000, v200
	v_lshlrev_b32_e32 v150, 16, v201
	v_and_b32_e32 v151, 0xffff0000, v201
	v_lshlrev_b32_e32 v200, 16, v202
	v_and_b32_e32 v201, 0xffff0000, v202
	v_lshlrev_b32_e32 v202, 16, v203
	v_and_b32_e32 v203, 0xffff0000, v203
	v_pk_fma_f32 v[144:145], v[104:105], v[144:145], v[108:109]
	v_pk_fma_f32 v[148:149], v[106:107], v[148:149], v[110:111]
	v_pk_fma_f32 v[162:163], v[88:89], v[162:163], v[92:93]
	v_pk_fma_f32 v[164:165], v[90:91], v[164:165], v[94:95]
	v_pk_fma_f32 v[144:145], v[166:167], v[146:147], v[144:145]
	v_pk_fma_f32 v[146:147], v[210:211], v[150:151], v[148:149]
	v_pk_fma_f32 v[148:149], v[212:213], v[200:201], v[162:163]
	v_pk_fma_f32 v[150:151], v[224:225], v[202:203], v[164:165]
	global_store_dwordx4 v[152:153], v[144:147], off
	s_nop 1
	v_cvt_pk_bf16_f32 v144, v144, v145
	v_cvt_pk_bf16_f32 v145, v146, v147
	global_store_dwordx4 v[152:153], v[148:151], off offset:16
	v_cvt_pk_bf16_f32 v146, v148, v149
	v_cvt_pk_bf16_f32 v147, v150, v151
	s_cbranch_vccnz .LBB0_1348
	s_nop 0
	v_lshl_add_u64 v[148:149], v[158:159], 1, s[90:91]
	global_store_dwordx4 v[148:149], v[144:147], off
; __device__ __forceinline__ unsigned cvt_pk_bf16(float lo, float hi) { unsigned r; asm volatile("v_cvt_pk_bf16_f32 %0, %1, %2" : "=v"(r) : "v"(lo), "v"(hi)); return r; }
; __device__ __forceinline__ float bf_lo(unsigned w) { return __uint_as_float(w << 16); }
; __device__ __forceinline__ float bf_hi(unsigned w) { return __uint_as_float(w & 0xffff0000u); }
;     __device__ __forceinline__ void operator()(const f32x4 (&acc)[2][2][4][2], const Unit& u, int wr, int wc, int fr, int fq) const {
;     ...
;                 for (int m = 0; m < 4; ++m) { const int row = row0 + ai * HALF + m * 16; const size_t o2 = (size_t)row * ldc + col;
;                     const float s1 = ST[2 * row], s2 = ST[2 * row + 1], mu = s1 * (1.f / 2048.f), rstd = __builtin_amdgcn_rsqf(fmaxf(s2 * (1.f / 2048.f) - mu * mu, 0.f) + 1e-5f);
;                     const u32x4 zw = *(const u32x4*)(Zb + o2), pw = *(const u32x4*)(PE + o2); u32x4 xw;
; #pragma unroll
;                     for (int n = 0; n < 2; ++n) { const unsigned za = n ? zw.z : zw.x, zb2 = n ? zw.w : zw.y, pa = n ? pw.z : pw.x, pb = n ? pw.w : pw.y;
;                         const float zv[4] = {bf_lo(za), bf_hi(za), bf_lo(zb2), bf_hi(zb2)}, pv[4] = {bf_lo(pa), bf_hi(pa), bf_lo(pb), bf_hi(pb)}; const f32x4 a = acc[ai][bj][m][n]; f32x4 o;
; #pragma unroll
;                         for (int e = 0; e < 4; ++e) { const float sv = rstd * (a[e] - mu * c1[n][e]) + c2[n][e]; const float xl = (zv[e] - mu) * rstd * lg[n][e] + lb[n][e]; o[e] = xl + pv[e] * __builtin_amdgcn_rcpf(1.f + __expf(-sv)); }
;                         *(f32x4*)(OUTF + o2 + 4 * n) = o; if (n == 0) { xw.x = cvt_pk_bf16(o[0], o[1]); xw.y = cvt_pk_bf16(o[2], o[3]); } else { xw.z = cvt_pk_bf16(o[0], o[1]); xw.w = cvt_pk_bf16(o[2], o[3]); } }
;                     if (XB) *(u32x4*)(XB + o2) = xw; }
.LBB0_1348:
	s_nop 1
	v_or_b32_e32 v144, 32, v198
	v_lshlrev_b32_e32 v146, 1, v144
	v_ashrrev_i32_e32 v147, 31, v146
	v_ashrrev_i32_e32 v145, 31, v144
	v_lshl_add_u64 v[146:147], v[146:147], 2, s[94:95]
	v_lshlrev_b64 v[148:149], 11, v[144:145]
	global_load_dwordx2 v[158:159], v[146:147], off
	v_lshl_add_u64 v[150:151], v[148:149], 0, v[188:189]
	v_lshlrev_b64 v[144:145], 1, v[150:151]
	v_lshl_add_u64 v[162:163], s[82:83], 0, v[144:145]
	v_lshl_add_u64 v[144:145], s[92:93], 0, v[144:145]
	global_load_dwordx4 v[200:203], v[144:145], off
	s_and_b64 vcc, exec, s[40:41]
	global_load_dwordx4 v[162:165], v[162:163], off
	v_lshl_add_u64 v[144:145], v[150:151], 2, s[8:9]
	s_waitcnt vmcnt(0) lgkmcnt(0)
	v_pk_mul_f32 v[158:159], v[158:159], s[0:1] op_sel_hi:[1,0]
	s_nop 0
	v_fma_f32 v166, -v158, v158, v159
	v_max_f32_e32 v225, 0, v166
	v_fma_f32 v211, -v124, v158, v136
	v_fma_f32 v212, -v125, v158, v137
	v_lshlrev_b32_e32 v166, 16, v202
	v_and_b32_e32 v167, 0xffff0000, v202
	v_add_f32_e32 v202, 0x3727c5ac, v225
	v_rsq_f32_e32 v202, v202
	v_lshlrev_b32_e32 v136, 16, v162
	v_and_b32_e32 v137, 0xffff0000, v162
	v_fma_f32 v199, -v116, v158, v140
	v_fma_f32 v204, -v117, v158, v141
	v_fma_f32 v209, -v118, v158, v142
	v_fma_f32 v210, -v119, v158, v143
	v_fma_f32 v213, -v126, v158, v138
	v_fma_f32 v224, -v127, v158, v139
	v_lshlrev_b32_e32 v140, 16, v163
	v_and_b32_e32 v141, 0xffff0000, v163
	v_lshlrev_b32_e32 v162, 16, v164
	v_and_b32_e32 v163, 0xffff0000, v164
	v_lshlrev_b32_e32 v164, 16, v165
	v_and_b32_e32 v165, 0xffff0000, v165
	v_pk_add_f32 v[136:137], v[136:137], v[158:159] op_sel_hi:[1,0] neg_lo:[0,1] neg_hi:[0,1]
	v_lshlrev_b32_e32 v138, 16, v200
	v_and_b32_e32 v139, 0xffff0000, v200
	v_lshlrev_b32_e32 v142, 16, v201
	v_and_b32_e32 v143, 0xffff0000, v201
	v_lshlrev_b32_e32 v200, 16, v203
	v_and_b32_e32 v201, 0xffff0000, v203
	v_pk_add_f32 v[140:141], v[140:141], v[158:159] op_sel_hi:[1,0] neg_lo:[0,1] neg_hi:[0,1]
	v_pk_add_f32 v[162:163], v[162:163], v[158:159] op_sel_hi:[1,0] neg_lo:[0,1] neg_hi:[0,1]
	v_pk_add_f32 v[158:159], v[164:165], v[158:159] op_sel_hi:[1,0] neg_lo:[0,1] neg_hi:[0,1]
	v_fma_f32 v164, v199, v202, v96
	v_fma_f32 v165, v204, v202, v97
	v_pk_mul_f32 v[136:137], v[202:203], v[136:137] op_sel_hi:[0,1]
	v_fma_f32 v199, v209, v202, v98
	v_fma_f32 v203, v210, v202, v99
	v_fma_f32 v204, v211, v202, v100
	v_fma_f32 v209, v212, v202, v101
	v_fma_f32 v210, v213, v202, v102
	v_fma_f32 v211, v224, v202, v103
	v_pk_mul_f32 v[140:141], v[202:203], v[140:141] op_sel_hi:[0,1]
	v_pk_mul_f32 v[162:163], v[202:203], v[162:163] op_sel_hi:[0,1]
	v_pk_mul_f32 v[158:159], v[202:203], v[158:159] op_sel_hi:[0,1]
	v_mul_f32_e32 v164, 0xbfb8aa3b, v164
	v_mul_f32_e32 v165, 0xbfb8aa3b, v165
	v_mul_f32_e32 v199, 0xbfb8aa3b, v199
	v_mul_f32_e32 v202, 0xbfb8aa3b, v203
	v_mul_f32_e32 v203, 0xbfb8aa3b, v204
	v_mul_f32_e32 v204, 0xbfb8aa3b, v209
	v_mul_f32_e32 v209, 0xbfb8aa3b, v210
	v_mul_f32_e32 v210, 0xbfb8aa3b, v211
	v_exp_f32_e32 v164, v164
	v_exp_f32_e32 v165, v165
	v_exp_f32_e32 v199, v199
	v_exp_f32_e32 v202, v202
	v_exp_f32_e32 v203, v203
	v_exp_f32_e32 v204, v204
	v_exp_f32_e32 v209, v209
	v_exp_f32_e32 v210, v210
	v_add_f32_e32 v164, 1.0, v164
	v_add_f32_e32 v165, 1.0, v165
	v_add_f32_e32 v199, 1.0, v199
	v_add_f32_e32 v211, 1.0, v202
	v_add_f32_e32 v212, 1.0, v203
	v_add_f32_e32 v204, 1.0, v204
	v_add_f32_e32 v209, 1.0, v209
	v_add_f32_e32 v213, 1.0, v210
	v_rcp_f32_e32 v164, v164
	v_rcp_f32_e32 v165, v165
	v_rcp_f32_e32 v202, v199
	v_rcp_f32_e32 v203, v211
	v_rcp_f32_e32 v210, v212
	v_rcp_f32_e32 v211, v204
	v_rcp_f32_e32 v212, v209
	v_rcp_f32_e32 v213, v213
	v_pk_fma_f32 v[136:137], v[104:105], v[136:137], v[108:109]
	v_pk_fma_f32 v[140:141], v[106:107], v[140:141], v[110:111]
	v_pk_fma_f32 v[162:163], v[88:89], v[162:163], v[92:93]
	v_pk_fma_f32 v[158:159], v[90:91], v[158:159], v[94:95]
	v_pk_fma_f32 v[136:137], v[164:165], v[138:139], v[136:137]
	v_pk_fma_f32 v[138:139], v[202:203], v[142:143], v[140:141]
	v_pk_fma_f32 v[140:141], v[210:211], v[166:167], v[162:163]
	v_pk_fma_f32 v[142:143], v[212:213], v[200:201], v[158:159]
	global_store_dwordx4 v[144:145], v[136:139], off
	s_nop 1
	v_cvt_pk_bf16_f32 v136, v136, v137
	v_cvt_pk_bf16_f32 v137, v138, v139
	global_store_dwordx4 v[144:145], v[140:143], off offset:16
	v_cvt_pk_bf16_f32 v138, v140, v141
	v_cvt_pk_bf16_f32 v139, v142, v143
	s_cbranch_vccnz .LBB0_1350
	s_nop 0
	v_lshl_add_u64 v[140:141], v[150:151], 1, s[90:91]
	global_store_dwordx4 v[140:141], v[136:139], off
; __device__ __forceinline__ unsigned cvt_pk_bf16(float lo, float hi) { unsigned r; asm volatile("v_cvt_pk_bf16_f32 %0, %1, %2" : "=v"(r) : "v"(lo), "v"(hi)); return r; }
; __device__ __forceinline__ float bf_lo(unsigned w) { return __uint_as_float(w << 16); }
; __device__ __forceinline__ float bf_hi(unsigned w) { return __uint_as_float(w & 0xffff0000u); }
;     __device__ __forceinline__ void operator()(const f32x4 (&acc)[2][2][4][2], const Unit& u, int wr, int wc, int fr, int fq) const {
;     ...
;                 for (int m = 0; m < 4; ++m) { const int row = row0 + ai * HALF + m * 16; const size_t o2 = (size_t)row * ldc + col;
;                     const float s1 = ST[2 * row], s2 = ST[2 * row + 1], mu = s1 * (1.f / 2048.f), rstd = __builtin_amdgcn_rsqf(fmaxf(s2 * (1.f / 2048.f) - mu * mu, 0.f) + 1e-5f);
;                     const u32x4 zw = *(const u32x4*)(Zb + o2), pw = *(const u32x4*)(PE + o2); u32x4 xw;
; #pragma unroll
;                     for (int n = 0; n < 2; ++n) { const unsigned za = n ? zw.z : zw.x, zb2 = n ? zw.w : zw.y, pa = n ? pw.z : pw.x, pb = n ? pw.w : pw.y;
;                         const float zv[4] = {bf_lo(za), bf_hi(za), bf_lo(zb2), bf_hi(zb2)}, pv[4] = {bf_lo(pa), bf_hi(pa), bf_lo(pb), bf_hi(pb)}; const f32x4 a = acc[ai][bj][m][n]; f32x4 o;
; #pragma unroll
;                         for (int e = 0; e < 4; ++e) { const float sv = rstd * (a[e] - mu * c1[n][e]) + c2[n][e]; const float xl = (zv[e] - mu) * rstd * lg[n][e] + lb[n][e]; o[e] = xl + pv[e] * __builtin_amdgcn_rcpf(1.f + __expf(-sv)); }
;                         *(f32x4*)(OUTF + o2 + 4 * n) = o; if (n == 0) { xw.x = cvt_pk_bf16(o[0], o[1]); xw.y = cvt_pk_bf16(o[2], o[3]); } else { xw.z = cvt_pk_bf16(o[0], o[1]); xw.w = cvt_pk_bf16(o[2], o[3]); } }
;                     if (XB) *(u32x4*)(XB + o2) = xw; }
.LBB0_1350:
	s_nop 1
	v_or_b32_e32 v136, 48, v198
	v_lshlrev_b32_e32 v138, 1, v136
	v_ashrrev_i32_e32 v139, 31, v138
	v_ashrrev_i32_e32 v137, 31, v136
	v_lshl_add_u64 v[138:139], v[138:139], 2, s[94:95]
	v_lshlrev_b64 v[140:141], 11, v[136:137]
	global_load_dwordx2 v[150:151], v[138:139], off
	v_lshl_add_u64 v[142:143], v[140:141], 0, v[188:189]
	v_lshlrev_b64 v[136:137], 1, v[142:143]
	v_lshl_add_u64 v[158:159], s[82:83], 0, v[136:137]
	v_lshl_add_u64 v[136:137], s[92:93], 0, v[136:137]
	global_load_dwordx4 v[200:203], v[136:137], off
	global_load_dwordx4 v[162:165], v[158:159], off
	s_and_b64 vcc, exec, s[40:41]
	v_lshl_add_u64 v[136:137], v[142:143], 2, s[8:9]
	s_waitcnt vmcnt(0) lgkmcnt(0)
	v_pk_mul_f32 v[150:151], v[150:151], s[0:1] op_sel_hi:[1,0]
	s_nop 0
	v_fma_f32 v158, -v150, v150, v151
	v_max_f32_e32 v225, 0, v158
	v_fma_f32 v213, -v126, v150, v130
	v_fma_f32 v224, -v127, v150, v131
	v_lshlrev_b32_e32 v130, 16, v200
	v_and_b32_e32 v131, 0xffff0000, v200
	v_add_f32_e32 v200, 0x3727c5ac, v225
	v_rsq_f32_e32 v200, v200
	v_fma_f32 v211, -v124, v150, v128
	v_fma_f32 v212, -v125, v150, v129
	v_lshlrev_b32_e32 v128, 16, v162
	v_and_b32_e32 v129, 0xffff0000, v162
	v_fma_f32 v199, -v116, v150, v132
	v_fma_f32 v204, -v117, v150, v133
	v_fma_f32 v209, -v118, v150, v134
	v_fma_f32 v210, -v119, v150, v135
	v_lshlrev_b32_e32 v132, 16, v163
	v_and_b32_e32 v133, 0xffff0000, v163
	v_lshlrev_b32_e32 v158, 16, v164
	v_and_b32_e32 v159, 0xffff0000, v164
	v_lshlrev_b32_e32 v164, 16, v165
	v_and_b32_e32 v165, 0xffff0000, v165
	v_pk_add_f32 v[128:129], v[128:129], v[150:151] op_sel_hi:[1,0] neg_lo:[0,1] neg_hi:[0,1]
	v_lshlrev_b32_e32 v134, 16, v201
	v_and_b32_e32 v135, 0xffff0000, v201
	v_lshlrev_b32_e32 v162, 16, v202
	v_and_b32_e32 v163, 0xffff0000, v202
	v_lshlrev_b32_e32 v166, 16, v203
	v_and_b32_e32 v167, 0xffff0000, v203
	v_pk_add_f32 v[132:133], v[132:133], v[150:151] op_sel_hi:[1,0] neg_lo:[0,1] neg_hi:[0,1]
	v_pk_add_f32 v[158:159], v[158:159], v[150:151] op_sel_hi:[1,0] neg_lo:[0,1] neg_hi:[0,1]
	v_pk_add_f32 v[150:151], v[164:165], v[150:151] op_sel_hi:[1,0] neg_lo:[0,1] neg_hi:[0,1]
	v_fma_f32 v164, v199, v200, v96
	v_fma_f32 v165, v204, v200, v97
	v_pk_mul_f32 v[128:129], v[200:201], v[128:129] op_sel_hi:[0,1]
	v_fma_f32 v199, v209, v200, v98
	v_fma_f32 v201, v210, v200, v99
	v_fma_f32 v202, v211, v200, v100
	v_fma_f32 v203, v212, v200, v101
	v_fma_f32 v204, v213, v200, v102
	v_fma_f32 v209, v224, v200, v103
	v_pk_mul_f32 v[132:133], v[200:201], v[132:133] op_sel_hi:[0,1]
	v_pk_mul_f32 v[158:159], v[200:201], v[158:159] op_sel_hi:[0,1]
	v_pk_mul_f32 v[150:151], v[200:201], v[150:151] op_sel_hi:[0,1]
	v_mul_f32_e32 v164, 0xbfb8aa3b, v164
	v_mul_f32_e32 v165, 0xbfb8aa3b, v165
	v_mul_f32_e32 v199, 0xbfb8aa3b, v199
	v_mul_f32_e32 v200, 0xbfb8aa3b, v201
	v_mul_f32_e32 v201, 0xbfb8aa3b, v202
	v_mul_f32_e32 v202, 0xbfb8aa3b, v203
	v_mul_f32_e32 v203, 0xbfb8aa3b, v204
	v_mul_f32_e32 v204, 0xbfb8aa3b, v209
	v_exp_f32_e32 v164, v164
	v_exp_f32_e32 v165, v165
	v_exp_f32_e32 v199, v199
	v_exp_f32_e32 v200, v200
	v_exp_f32_e32 v201, v201
	v_exp_f32_e32 v202, v202
	v_exp_f32_e32 v203, v203
	v_exp_f32_e32 v204, v204
	v_add_f32_e32 v164, 1.0, v164
	v_add_f32_e32 v165, 1.0, v165
	v_add_f32_e32 v199, 1.0, v199
	v_add_f32_e32 v209, 1.0, v200
	v_add_f32_e32 v210, 1.0, v201
	v_add_f32_e32 v211, 1.0, v202
	v_add_f32_e32 v212, 1.0, v203
	v_add_f32_e32 v204, 1.0, v204
	v_rcp_f32_e32 v164, v164
	v_rcp_f32_e32 v165, v165
	v_rcp_f32_e32 v200, v199
	v_rcp_f32_e32 v201, v209
	v_rcp_f32_e32 v202, v210
	v_rcp_f32_e32 v203, v211
	v_rcp_f32_e32 v210, v212
	v_rcp_f32_e32 v211, v204
	v_pk_fma_f32 v[128:129], v[104:105], v[128:129], v[108:109]
	v_pk_fma_f32 v[132:133], v[106:107], v[132:133], v[110:111]
	v_pk_fma_f32 v[158:159], v[88:89], v[158:159], v[92:93]
	v_pk_fma_f32 v[150:151], v[90:91], v[150:151], v[94:95]
	v_pk_fma_f32 v[128:129], v[164:165], v[130:131], v[128:129]
	v_pk_fma_f32 v[130:131], v[200:201], v[134:135], v[132:133]
	v_pk_fma_f32 v[132:133], v[202:203], v[162:163], v[158:159]
	v_pk_fma_f32 v[134:135], v[210:211], v[166:167], v[150:151]
	global_store_dwordx4 v[136:137], v[128:131], off
	s_nop 1
	v_cvt_pk_bf16_f32 v128, v128, v129
	v_cvt_pk_bf16_f32 v129, v130, v131
	global_store_dwordx4 v[136:137], v[132:135], off offset:16
	v_cvt_pk_bf16_f32 v130, v132, v133
	v_cvt_pk_bf16_f32 v131, v134, v135
	s_cbranch_vccnz .LBB0_1352
	s_nop 0
	v_lshl_add_u64 v[132:133], v[142:143], 1, s[90:91]
	global_store_dwordx4 v[132:133], v[128:131], off
; __device__ __forceinline__ unsigned cvt_pk_bf16(float lo, float hi) { unsigned r; asm volatile("v_cvt_pk_bf16_f32 %0, %1, %2" : "=v"(r) : "v"(lo), "v"(hi)); return r; }
; __device__ __forceinline__ float bf_lo(unsigned w) { return __uint_as_float(w << 16); }
; __device__ __forceinline__ float bf_hi(unsigned w) { return __uint_as_float(w & 0xffff0000u); }
;     __device__ __forceinline__ void operator()(const f32x4 (&acc)[2][2][4][2], const Unit& u, int wr, int wc, int fr, int fq) const {
;     ...
;                 for (int m = 0; m < 4; ++m) { const int row = row0 + ai * HALF + m * 16; const size_t o2 = (size_t)row * ldc + col;
;                     const float s1 = ST[2 * row], s2 = ST[2 * row + 1], mu = s1 * (1.f / 2048.f), rstd = __builtin_amdgcn_rsqf(fmaxf(s2 * (1.f / 2048.f) - mu * mu, 0.f) + 1e-5f);
;                     const u32x4 zw = *(const u32x4*)(Zb + o2), pw = *(const u32x4*)(PE + o2); u32x4 xw;
; #pragma unroll
;                     for (int n = 0; n < 2; ++n) { const unsigned za = n ? zw.z : zw.x, zb2 = n ? zw.w : zw.y, pa = n ? pw.z : pw.x, pb = n ? pw.w : pw.y;
;                         const float zv[4] = {bf_lo(za), bf_hi(za), bf_lo(zb2), bf_hi(zb2)}, pv[4] = {bf_lo(pa), bf_hi(pa), bf_lo(pb), bf_hi(pb)}; const f32x4 a = acc[ai][bj][m][n]; f32x4 o;
; #pragma unroll
;                         for (int e = 0; e < 4; ++e) { const float sv = rstd * (a[e] - mu * c1[n][e]) + c2[n][e]; const float xl = (zv[e] - mu) * rstd * lg[n][e] + lb[n][e]; o[e] = xl + pv[e] * __builtin_amdgcn_rcpf(1.f + __expf(-sv)); }
;                         *(f32x4*)(OUTF + o2 + 4 * n) = o; if (n == 0) { xw.x = cvt_pk_bf16(o[0], o[1]); xw.y = cvt_pk_bf16(o[2], o[3]); } else { xw.z = cvt_pk_bf16(o[0], o[1]); xw.w = cvt_pk_bf16(o[2], o[3]); } }
;                     if (XB) *(u32x4*)(XB + o2) = xw; }
.LBB0_1352:
	s_nop 1
	v_add_u32_e32 v128, 0x80, v198
	v_lshlrev_b32_e32 v130, 1, v128
	v_ashrrev_i32_e32 v131, 31, v130
	v_lshl_add_u64 v[130:131], v[130:131], 2, s[94:95]
	global_load_dwordx2 v[142:143], v[130:131], off
	v_ashrrev_i32_e32 v129, 31, v128
	v_lshlrev_b64 v[132:133], 11, v[128:129]
	v_lshl_add_u64 v[134:135], v[132:133], 0, v[188:189]
	v_lshlrev_b64 v[128:129], 1, v[134:135]
	v_lshl_add_u64 v[150:151], s[82:83], 0, v[128:129]
	global_load_dwordx4 v[162:165], v[150:151], off
	v_lshl_add_u64 v[128:129], s[92:93], 0, v[128:129]
	global_load_dwordx4 v[200:203], v[128:129], off
	s_and_b64 vcc, exec, s[40:41]
	v_lshl_add_u64 v[128:129], v[134:135], 2, s[8:9]
	s_waitcnt vmcnt(0) lgkmcnt(0)
	v_pk_mul_f32 v[142:143], v[142:143], s[0:1] op_sel_hi:[1,0]
	s_nop 0
	v_fma_f32 v150, -v142, v142, v143
	v_max_f32_e32 v166, 0, v150
	v_add_f32_e32 v166, 0x3727c5ac, v166
	v_rsq_f32_e32 v166, v166
	v_fma_f32 v210, -v124, v142, v112
	v_fma_f32 v211, -v125, v142, v113
	v_lshlrev_b32_e32 v112, 16, v162
	v_and_b32_e32 v113, 0xffff0000, v162
	v_fma_f32 v167, -v116, v142, v120
	v_fma_f32 v199, -v117, v142, v121
	v_fma_f32 v204, -v118, v142, v122
	v_fma_f32 v209, -v119, v142, v123
	v_fma_f32 v212, -v126, v142, v114
	v_fma_f32 v213, -v127, v142, v115
	v_lshlrev_b32_e32 v120, 16, v163
	v_and_b32_e32 v121, 0xffff0000, v163
	v_lshlrev_b32_e32 v150, 16, v164
	v_and_b32_e32 v151, 0xffff0000, v164
	v_lshlrev_b32_e32 v162, 16, v165
	v_and_b32_e32 v163, 0xffff0000, v165
	v_pk_add_f32 v[112:113], v[112:113], v[142:143] op_sel_hi:[1,0] neg_lo:[0,1] neg_hi:[0,1]
	v_lshlrev_b32_e32 v114, 16, v200
	v_and_b32_e32 v115, 0xffff0000, v200
	v_lshlrev_b32_e32 v122, 16, v201
	v_and_b32_e32 v123, 0xffff0000, v201
	v_lshlrev_b32_e32 v158, 16, v202
	v_and_b32_e32 v159, 0xffff0000, v202
	v_lshlrev_b32_e32 v164, 16, v203
	v_and_b32_e32 v165, 0xffff0000, v203
	v_pk_add_f32 v[120:121], v[120:121], v[142:143] op_sel_hi:[1,0] neg_lo:[0,1] neg_hi:[0,1]
	v_pk_add_f32 v[150:151], v[150:151], v[142:143] op_sel_hi:[1,0] neg_lo:[0,1] neg_hi:[0,1]
	v_pk_add_f32 v[142:143], v[162:163], v[142:143] op_sel_hi:[1,0] neg_lo:[0,1] neg_hi:[0,1]
	v_fma_f32 v162, v167, v166, v96
	v_fma_f32 v163, v199, v166, v97
	v_pk_mul_f32 v[112:113], v[166:167], v[112:113] op_sel_hi:[0,1]
	v_fma_f32 v167, v204, v166, v98
	v_fma_f32 v199, v209, v166, v99
	v_fma_f32 v200, v210, v166, v100
	v_fma_f32 v201, v211, v166, v101
	v_fma_f32 v202, v212, v166, v102
	v_fma_f32 v203, v213, v166, v103
	v_pk_mul_f32 v[120:121], v[166:167], v[120:121] op_sel_hi:[0,1]
	v_pk_mul_f32 v[150:151], v[166:167], v[150:151] op_sel_hi:[0,1]
	v_pk_mul_f32 v[142:143], v[166:167], v[142:143] op_sel_hi:[0,1]
	v_mul_f32_e32 v162, 0xbfb8aa3b, v162
	v_mul_f32_e32 v163, 0xbfb8aa3b, v163
	v_mul_f32_e32 v166, 0xbfb8aa3b, v167
	v_mul_f32_e32 v167, 0xbfb8aa3b, v199
	v_mul_f32_e32 v199, 0xbfb8aa3b, v200
	v_mul_f32_e32 v200, 0xbfb8aa3b, v201
	v_mul_f32_e32 v201, 0xbfb8aa3b, v202
	v_mul_f32_e32 v202, 0xbfb8aa3b, v203
	v_exp_f32_e32 v162, v162
	v_exp_f32_e32 v163, v163
	v_exp_f32_e32 v166, v166
	v_exp_f32_e32 v167, v167
	v_exp_f32_e32 v199, v199
	v_exp_f32_e32 v200, v200
	v_exp_f32_e32 v201, v201
	v_exp_f32_e32 v202, v202
	v_add_f32_e32 v162, 1.0, v162
	v_add_f32_e32 v163, 1.0, v163
	v_add_f32_e32 v166, 1.0, v166
	v_add_f32_e32 v167, 1.0, v167
	v_add_f32_e32 v199, 1.0, v199
	v_add_f32_e32 v203, 1.0, v200
	v_add_f32_e32 v204, 1.0, v201
	v_add_f32_e32 v209, 1.0, v202
	v_rcp_f32_e32 v162, v162
	v_rcp_f32_e32 v163, v163
	v_rcp_f32_e32 v166, v166
	v_rcp_f32_e32 v167, v167
	v_rcp_f32_e32 v200, v199
	v_rcp_f32_e32 v201, v203
	v_rcp_f32_e32 v202, v204
	v_rcp_f32_e32 v203, v209
	v_pk_fma_f32 v[112:113], v[104:105], v[112:113], v[108:109]
	v_pk_fma_f32 v[120:121], v[106:107], v[120:121], v[110:111]
	v_pk_fma_f32 v[150:151], v[88:89], v[150:151], v[92:93]
	v_pk_fma_f32 v[142:143], v[90:91], v[142:143], v[94:95]
	v_pk_fma_f32 v[112:113], v[162:163], v[114:115], v[112:113]
	v_pk_fma_f32 v[114:115], v[166:167], v[122:123], v[120:121]
	v_pk_fma_f32 v[120:121], v[200:201], v[158:159], v[150:151]
	v_pk_fma_f32 v[122:123], v[202:203], v[164:165], v[142:143]
	global_store_dwordx4 v[128:129], v[112:115], off
	s_nop 1
	v_cvt_pk_bf16_f32 v112, v112, v113
	v_cvt_pk_bf16_f32 v113, v114, v115
	global_store_dwordx4 v[128:129], v[120:123], off offset:16
	v_cvt_pk_bf16_f32 v114, v120, v121
	v_cvt_pk_bf16_f32 v115, v122, v123
	s_cbranch_vccnz .LBB0_1354
	s_nop 0
	v_lshl_add_u64 v[120:121], v[134:135], 1, s[90:91]
	global_store_dwordx4 v[120:121], v[112:115], off
; __device__ __forceinline__ unsigned cvt_pk_bf16(float lo, float hi) { unsigned r; asm volatile("v_cvt_pk_bf16_f32 %0, %1, %2" : "=v"(r) : "v"(lo), "v"(hi)); return r; }
; __device__ __forceinline__ float bf_lo(unsigned w) { return __uint_as_float(w << 16); }
; __device__ __forceinline__ float bf_hi(unsigned w) { return __uint_as_float(w & 0xffff0000u); }
;     __device__ __forceinline__ void operator()(const f32x4 (&acc)[2][2][4][2], const Unit& u, int wr, int wc, int fr, int fq) const {
;     ...
;                 for (int m = 0; m < 4; ++m) { const int row = row0 + ai * HALF + m * 16; const size_t o2 = (size_t)row * ldc + col;
;                     const float s1 = ST[2 * row], s2 = ST[2 * row + 1], mu = s1 * (1.f / 2048.f), rstd = __builtin_amdgcn_rsqf(fmaxf(s2 * (1.f / 2048.f) - mu * mu, 0.f) + 1e-5f);
;                     const u32x4 zw = *(const u32x4*)(Zb + o2), pw = *(const u32x4*)(PE + o2); u32x4 xw;
; #pragma unroll
;                     for (int n = 0; n < 2; ++n) { const unsigned za = n ? zw.z : zw.x, zb2 = n ? zw.w : zw.y, pa = n ? pw.z : pw.x, pb = n ? pw.w : pw.y;
;                         const float zv[4] = {bf_lo(za), bf_hi(za), bf_lo(zb2), bf_hi(zb2)}, pv[4] = {bf_lo(pa), bf_hi(pa), bf_lo(pb), bf_hi(pb)}; const f32x4 a = acc[ai][bj][m][n]; f32x4 o;
; #pragma unroll
;                         for (int e = 0; e < 4; ++e) { const float sv = rstd * (a[e] - mu * c1[n][e]) + c2[n][e]; const float xl = (zv[e] - mu) * rstd * lg[n][e] + lb[n][e]; o[e] = xl + pv[e] * __builtin_amdgcn_rcpf(1.f + __expf(-sv)); }
;                         *(f32x4*)(OUTF + o2 + 4 * n) = o; if (n == 0) { xw.x = cvt_pk_bf16(o[0], o[1]); xw.y = cvt_pk_bf16(o[2], o[3]); } else { xw.z = cvt_pk_bf16(o[0], o[1]); xw.w = cvt_pk_bf16(o[2], o[3]); } }
;                     if (XB) *(u32x4*)(XB + o2) = xw; }
.LBB0_1354:
	s_nop 1
	v_add_u32_e32 v112, 0x90, v198
	v_lshlrev_b32_e32 v114, 1, v112
	v_ashrrev_i32_e32 v115, 31, v114
	v_ashrrev_i32_e32 v113, 31, v112
	v_lshl_add_u64 v[122:123], v[114:115], 2, s[94:95]
	v_lshlrev_b64 v[134:135], 11, v[112:113]
	global_load_dwordx2 v[120:121], v[122:123], off
	v_lshl_add_u64 v[114:115], v[134:135], 0, v[188:189]
	v_lshlrev_b64 v[112:113], 1, v[114:115]
	v_lshl_add_u64 v[142:143], s[82:83], 0, v[112:113]
	global_load_dwordx4 v[162:165], v[142:143], off
	v_lshl_add_u64 v[112:113], s[92:93], 0, v[112:113]
	global_load_dwordx4 v[200:203], v[112:113], off
	s_and_b64 vcc, exec, s[40:41]
	v_lshl_add_u64 v[112:113], v[114:115], 2, s[8:9]
	s_waitcnt vmcnt(0) lgkmcnt(0)
	v_pk_mul_f32 v[120:121], v[120:121], s[0:1] op_sel_hi:[1,0]
	s_nop 0
	v_fma_f32 v142, -v120, v120, v121
	v_max_f32_e32 v213, 0, v142
	v_fma_f32 v209, -v124, v120, v80
	v_lshlrev_b32_e32 v142, 16, v164
	v_and_b32_e32 v143, 0xffff0000, v164
	v_add_f32_e32 v164, 0x3727c5ac, v213
	v_rsq_f32_e32 v164, v164
	v_fma_f32 v210, -v125, v120, v81
	v_lshlrev_b32_e32 v80, 16, v162
	v_and_b32_e32 v81, 0xffff0000, v162
	v_fma_f32 v166, -v116, v120, v84
	v_fma_f32 v167, -v117, v120, v85
	v_fma_f32 v199, -v118, v120, v86
	v_fma_f32 v204, -v119, v120, v87
	v_fma_f32 v211, -v126, v120, v82
	v_fma_f32 v212, -v127, v120, v83
	v_lshlrev_b32_e32 v84, 16, v163
	v_and_b32_e32 v85, 0xffff0000, v163
	v_lshlrev_b32_e32 v158, 16, v165
	v_and_b32_e32 v159, 0xffff0000, v165
	v_pk_add_f32 v[80:81], v[80:81], v[120:121] op_sel_hi:[1,0] neg_lo:[0,1] neg_hi:[0,1]
	v_lshlrev_b32_e32 v82, 16, v200
	v_and_b32_e32 v83, 0xffff0000, v200
	v_lshlrev_b32_e32 v86, 16, v201
	v_and_b32_e32 v87, 0xffff0000, v201
	v_pk_add_f32 v[84:85], v[84:85], v[120:121] op_sel_hi:[1,0] neg_lo:[0,1] neg_hi:[0,1]
	v_pk_add_f32 v[142:143], v[142:143], v[120:121] op_sel_hi:[1,0] neg_lo:[0,1] neg_hi:[0,1]
	v_pk_add_f32 v[120:121], v[158:159], v[120:121] op_sel_hi:[1,0] neg_lo:[0,1] neg_hi:[0,1]
	v_fma_f32 v158, v166, v164, v96
	v_fma_f32 v159, v167, v164, v97
	v_pk_mul_f32 v[80:81], v[164:165], v[80:81] op_sel_hi:[0,1]
	v_fma_f32 v165, v199, v164, v98
	v_fma_f32 v166, v204, v164, v99
	v_fma_f32 v167, v209, v164, v100
	v_fma_f32 v199, v210, v164, v101
	v_fma_f32 v200, v211, v164, v102
	v_fma_f32 v201, v212, v164, v103
	v_pk_mul_f32 v[84:85], v[164:165], v[84:85] op_sel_hi:[0,1]
	v_pk_mul_f32 v[142:143], v[164:165], v[142:143] op_sel_hi:[0,1]
	v_pk_mul_f32 v[120:121], v[164:165], v[120:121] op_sel_hi:[0,1]
	v_mul_f32_e32 v158, 0xbfb8aa3b, v158
	v_mul_f32_e32 v159, 0xbfb8aa3b, v159
	v_mul_f32_e32 v164, 0xbfb8aa3b, v165
	v_mul_f32_e32 v165, 0xbfb8aa3b, v166
	v_mul_f32_e32 v166, 0xbfb8aa3b, v167
	v_mul_f32_e32 v167, 0xbfb8aa3b, v199
	v_mul_f32_e32 v199, 0xbfb8aa3b, v200
	v_mul_f32_e32 v200, 0xbfb8aa3b, v201
	v_exp_f32_e32 v158, v158
	v_exp_f32_e32 v159, v159
	v_exp_f32_e32 v164, v164
	v_exp_f32_e32 v165, v165
	v_exp_f32_e32 v166, v166
	v_exp_f32_e32 v167, v167
	v_exp_f32_e32 v199, v199
	v_exp_f32_e32 v200, v200
	v_add_f32_e32 v158, 1.0, v158
	v_add_f32_e32 v159, 1.0, v159
	v_add_f32_e32 v164, 1.0, v164
	v_add_f32_e32 v165, 1.0, v165
	v_add_f32_e32 v166, 1.0, v166
	v_add_f32_e32 v167, 1.0, v167
	v_add_f32_e32 v199, 1.0, v199
	v_add_f32_e32 v201, 1.0, v200
	v_rcp_f32_e32 v158, v158
	v_rcp_f32_e32 v159, v159
	v_rcp_f32_e32 v164, v164
	v_rcp_f32_e32 v165, v165
	v_rcp_f32_e32 v166, v166
	v_rcp_f32_e32 v167, v167
	v_rcp_f32_e32 v200, v199
	v_rcp_f32_e32 v201, v201
	v_lshlrev_b32_e32 v150, 16, v202
	v_and_b32_e32 v151, 0xffff0000, v202
	v_lshlrev_b32_e32 v162, 16, v203
	v_and_b32_e32 v163, 0xffff0000, v203
	v_pk_fma_f32 v[80:81], v[104:105], v[80:81], v[108:109]
	v_pk_fma_f32 v[84:85], v[106:107], v[84:85], v[110:111]
	v_pk_fma_f32 v[142:143], v[88:89], v[142:143], v[92:93]
	v_pk_fma_f32 v[120:121], v[90:91], v[120:121], v[94:95]
	v_pk_fma_f32 v[80:81], v[158:159], v[82:83], v[80:81]
	v_pk_fma_f32 v[82:83], v[164:165], v[86:87], v[84:85]
	v_pk_fma_f32 v[84:85], v[166:167], v[150:151], v[142:143]
	v_pk_fma_f32 v[86:87], v[200:201], v[162:163], v[120:121]
	global_store_dwordx4 v[112:113], v[80:83], off
	s_nop 1
	v_cvt_pk_bf16_f32 v80, v80, v81
	v_cvt_pk_bf16_f32 v81, v82, v83
	global_store_dwordx4 v[112:113], v[84:87], off offset:16
	v_cvt_pk_bf16_f32 v82, v84, v85
	v_cvt_pk_bf16_f32 v83, v86, v87
	s_cbranch_vccnz .LBB0_1356
	s_nop 0
	v_lshl_add_u64 v[84:85], v[114:115], 1, s[90:91]
	global_store_dwordx4 v[84:85], v[80:83], off
; __device__ __forceinline__ unsigned cvt_pk_bf16(float lo, float hi) { unsigned r; asm volatile("v_cvt_pk_bf16_f32 %0, %1, %2" : "=v"(r) : "v"(lo), "v"(hi)); return r; }
; __device__ __forceinline__ float bf_lo(unsigned w) { return __uint_as_float(w << 16); }
; __device__ __forceinline__ float bf_hi(unsigned w) { return __uint_as_float(w & 0xffff0000u); }
;     __device__ __forceinline__ void operator()(const f32x4 (&acc)[2][2][4][2], const Unit& u, int wr, int wc, int fr, int fq) const {
;     ...
;                 for (int m = 0; m < 4; ++m) { const int row = row0 + ai * HALF + m * 16; const size_t o2 = (size_t)row * ldc + col;
;                     const float s1 = ST[2 * row], s2 = ST[2 * row + 1], mu = s1 * (1.f / 2048.f), rstd = __builtin_amdgcn_rsqf(fmaxf(s2 * (1.f / 2048.f) - mu * mu, 0.f) + 1e-5f);
;                     const u32x4 zw = *(const u32x4*)(Zb + o2), pw = *(const u32x4*)(PE + o2); u32x4 xw;
; #pragma unroll
;                     for (int n = 0; n < 2; ++n) { const unsigned za = n ? zw.z : zw.x, zb2 = n ? zw.w : zw.y, pa = n ? pw.z : pw.x, pb = n ? pw.w : pw.y;
;                         const float zv[4] = {bf_lo(za), bf_hi(za), bf_lo(zb2), bf_hi(zb2)}, pv[4] = {bf_lo(pa), bf_hi(pa), bf_lo(pb), bf_hi(pb)}; const f32x4 a = acc[ai][bj][m][n]; f32x4 o;
; #pragma unroll
;                         for (int e = 0; e < 4; ++e) { const float sv = rstd * (a[e] - mu * c1[n][e]) + c2[n][e]; const float xl = (zv[e] - mu) * rstd * lg[n][e] + lb[n][e]; o[e] = xl + pv[e] * __builtin_amdgcn_rcpf(1.f + __expf(-sv)); }
;                         *(f32x4*)(OUTF + o2 + 4 * n) = o; if (n == 0) { xw.x = cvt_pk_bf16(o[0], o[1]); xw.y = cvt_pk_bf16(o[2], o[3]); } else { xw.z = cvt_pk_bf16(o[0], o[1]); xw.w = cvt_pk_bf16(o[2], o[3]); } }
;                     if (XB) *(u32x4*)(XB + o2) = xw; }
.LBB0_1356:
	s_nop 1
	v_add_u32_e32 v80, 0xa0, v198
	v_lshlrev_b32_e32 v82, 1, v80
	v_ashrrev_i32_e32 v83, 31, v82
	v_ashrrev_i32_e32 v81, 31, v80
	v_lshl_add_u64 v[142:143], v[82:83], 2, s[94:95]
	v_lshlrev_b64 v[150:151], 11, v[80:81]
	global_load_dwordx2 v[86:87], v[142:143], off
	v_lshl_add_u64 v[80:81], v[150:151], 0, v[188:189]
	v_lshlrev_b64 v[114:115], 1, v[80:81]
	v_lshl_add_u64 v[82:83], s[82:83], 0, v[114:115]
	v_lshl_add_u64 v[114:115], s[92:93], 0, v[114:115]
	global_load_dwordx4 v[162:165], v[114:115], off
	s_and_b64 vcc, exec, s[40:41]
	global_load_dwordx4 v[82:85], v[82:83], off
	v_lshl_add_u64 v[114:115], v[80:81], 2, s[8:9]
	s_waitcnt vmcnt(0) lgkmcnt(0)
	v_pk_mul_f32 v[86:87], v[86:87], s[0:1] op_sel_hi:[1,0]
	s_nop 0
	v_fma_f32 v120, -v86, v86, v87
	v_max_f32_e32 v209, 0, v120
	v_fma_f32 v203, -v126, v86, v74
	v_fma_f32 v204, -v127, v86, v75
	v_lshlrev_b32_e32 v74, 16, v162
	v_and_b32_e32 v75, 0xffff0000, v162
	v_add_f32_e32 v162, 0x3727c5ac, v209
	v_rsq_f32_e32 v162, v162
	v_fma_f32 v201, -v124, v86, v72
	v_fma_f32 v202, -v125, v86, v73
	v_lshlrev_b32_e32 v72, 16, v82
	v_and_b32_e32 v73, 0xffff0000, v82
	v_fma_f32 v166, -v116, v86, v76
	v_fma_f32 v167, -v117, v86, v77
	v_fma_f32 v199, -v118, v86, v78
	v_fma_f32 v200, -v119, v86, v79
	v_lshlrev_b32_e32 v76, 16, v83
	v_and_b32_e32 v77, 0xffff0000, v83
	v_lshlrev_b32_e32 v82, 16, v84
	v_and_b32_e32 v83, 0xffff0000, v84
	v_lshlrev_b32_e32 v84, 16, v85
	v_and_b32_e32 v85, 0xffff0000, v85
	v_pk_add_f32 v[72:73], v[72:73], v[86:87] op_sel_hi:[1,0] neg_lo:[0,1] neg_hi:[0,1]
	v_lshlrev_b32_e32 v78, 16, v163
	v_and_b32_e32 v79, 0xffff0000, v163
	v_lshlrev_b32_e32 v120, 16, v164
	v_and_b32_e32 v121, 0xffff0000, v164
	v_lshlrev_b32_e32 v158, 16, v165
	v_and_b32_e32 v159, 0xffff0000, v165
	v_pk_add_f32 v[76:77], v[76:77], v[86:87] op_sel_hi:[1,0] neg_lo:[0,1] neg_hi:[0,1]
	v_pk_add_f32 v[82:83], v[82:83], v[86:87] op_sel_hi:[1,0] neg_lo:[0,1] neg_hi:[0,1]
	v_pk_add_f32 v[84:85], v[84:85], v[86:87] op_sel_hi:[1,0] neg_lo:[0,1] neg_hi:[0,1]
	v_fma_f32 v86, v166, v162, v96
	v_fma_f32 v87, v167, v162, v97
	v_pk_mul_f32 v[72:73], v[162:163], v[72:73] op_sel_hi:[0,1]
	v_fma_f32 v163, v199, v162, v98
	v_fma_f32 v164, v200, v162, v99
	v_fma_f32 v165, v201, v162, v100
	v_fma_f32 v166, v202, v162, v101
	v_fma_f32 v167, v203, v162, v102
	v_fma_f32 v199, v204, v162, v103
	v_pk_mul_f32 v[76:77], v[162:163], v[76:77] op_sel_hi:[0,1]
	v_pk_mul_f32 v[82:83], v[162:163], v[82:83] op_sel_hi:[0,1]
	v_pk_mul_f32 v[84:85], v[162:163], v[84:85] op_sel_hi:[0,1]
	v_mul_f32_e32 v86, 0xbfb8aa3b, v86
	v_mul_f32_e32 v87, 0xbfb8aa3b, v87
	v_mul_f32_e32 v162, 0xbfb8aa3b, v163
	v_mul_f32_e32 v163, 0xbfb8aa3b, v164
	v_mul_f32_e32 v164, 0xbfb8aa3b, v165
	v_mul_f32_e32 v165, 0xbfb8aa3b, v166
	v_mul_f32_e32 v166, 0xbfb8aa3b, v167
	v_mul_f32_e32 v167, 0xbfb8aa3b, v199
	v_exp_f32_e32 v86, v86
	v_exp_f32_e32 v87, v87
	v_exp_f32_e32 v162, v162
	v_exp_f32_e32 v163, v163
	v_exp_f32_e32 v164, v164
	v_exp_f32_e32 v165, v165
	v_exp_f32_e32 v166, v166
	v_exp_f32_e32 v167, v167
	v_add_f32_e32 v86, 1.0, v86
	v_add_f32_e32 v87, 1.0, v87
	v_add_f32_e32 v162, 1.0, v162
	v_add_f32_e32 v163, 1.0, v163
	v_add_f32_e32 v164, 1.0, v164
	v_add_f32_e32 v165, 1.0, v165
	v_add_f32_e32 v166, 1.0, v166
	v_add_f32_e32 v167, 1.0, v167
	v_rcp_f32_e32 v86, v86
	v_rcp_f32_e32 v87, v87
	v_rcp_f32_e32 v162, v162
	v_rcp_f32_e32 v163, v163
	v_rcp_f32_e32 v164, v164
	v_rcp_f32_e32 v165, v165
	v_rcp_f32_e32 v166, v166
	v_rcp_f32_e32 v167, v167
	v_pk_fma_f32 v[72:73], v[104:105], v[72:73], v[108:109]
	v_pk_fma_f32 v[76:77], v[106:107], v[76:77], v[110:111]
	v_pk_fma_f32 v[82:83], v[88:89], v[82:83], v[92:93]
	v_pk_fma_f32 v[84:85], v[90:91], v[84:85], v[94:95]
	v_pk_fma_f32 v[72:73], v[86:87], v[74:75], v[72:73]
	v_pk_fma_f32 v[74:75], v[162:163], v[78:79], v[76:77]
	v_pk_fma_f32 v[76:77], v[164:165], v[120:121], v[82:83]
	v_pk_fma_f32 v[78:79], v[166:167], v[158:159], v[84:85]
	global_store_dwordx4 v[114:115], v[72:75], off
	s_nop 1
	v_cvt_pk_bf16_f32 v72, v72, v73
	v_cvt_pk_bf16_f32 v73, v74, v75
	global_store_dwordx4 v[114:115], v[76:79], off offset:16
	v_cvt_pk_bf16_f32 v74, v76, v77
	v_cvt_pk_bf16_f32 v75, v78, v79
	s_cbranch_vccnz .LBB0_1358
	s_nop 0
	v_lshl_add_u64 v[76:77], v[80:81], 1, s[90:91]
	global_store_dwordx4 v[76:77], v[72:75], off
; __device__ __forceinline__ unsigned cvt_pk_bf16(float lo, float hi) { unsigned r; asm volatile("v_cvt_pk_bf16_f32 %0, %1, %2" : "=v"(r) : "v"(lo), "v"(hi)); return r; }
; __device__ __forceinline__ float bf_lo(unsigned w) { return __uint_as_float(w << 16); }
; __device__ __forceinline__ float bf_hi(unsigned w) { return __uint_as_float(w & 0xffff0000u); }
;     __device__ __forceinline__ void operator()(const f32x4 (&acc)[2][2][4][2], const Unit& u, int wr, int wc, int fr, int fq) const {
;     ...
;         for (int bj = 0; bj < 2; ++bj) { const int col = col0 + bj * HALF;
;             f32x4 c1[2], c2[2], lg[2], lb[2];
; #pragma unroll
;             for (int n = 0; n < 2; ++n) { c1[n] = *(const f32x4*)(C1 + col + 4 * n); c2[n] = *(const f32x4*)(C2 + col + 4 * n); lg[n] = *(const f32x4*)(LG + col + 4 * n); lb[n] = *(const f32x4*)(LB + col + 4 * n); }
;     ...
;                 for (int m = 0; m < 4; ++m) { const int row = row0 + ai * HALF + m * 16; const size_t o2 = (size_t)row * ldc + col;
;                     const float s1 = ST[2 * row], s2 = ST[2 * row + 1], mu = s1 * (1.f / 2048.f), rstd = __builtin_amdgcn_rsqf(fmaxf(s2 * (1.f / 2048.f) - mu * mu, 0.f) + 1e-5f);
;                     const u32x4 zw = *(const u32x4*)(Zb + o2), pw = *(const u32x4*)(PE + o2); u32x4 xw;
; #pragma unroll
;                     for (int n = 0; n < 2; ++n) { const unsigned za = n ? zw.z : zw.x, zb2 = n ? zw.w : zw.y, pa = n ? pw.z : pw.x, pb = n ? pw.w : pw.y;
;                         const float zv[4] = {bf_lo(za), bf_hi(za), bf_lo(zb2), bf_hi(zb2)}, pv[4] = {bf_lo(pa), bf_hi(pa), bf_lo(pb), bf_hi(pb)}; const f32x4 a = acc[ai][bj][m][n]; f32x4 o;
; #pragma unroll
;                         for (int e = 0; e < 4; ++e) { const float sv = rstd * (a[e] - mu * c1[n][e]) + c2[n][e]; const float xl = (zv[e] - mu) * rstd * lg[n][e] + lb[n][e]; o[e] = xl + pv[e] * __builtin_amdgcn_rcpf(1.f + __expf(-sv)); }
;                         *(f32x4*)(OUTF + o2 + 4 * n) = o; if (n == 0) { xw.x = cvt_pk_bf16(o[0], o[1]); xw.y = cvt_pk_bf16(o[2], o[3]); } else { xw.z = cvt_pk_bf16(o[0], o[1]); xw.w = cvt_pk_bf16(o[2], o[3]); } }
;                     if (XB) *(u32x4*)(XB + o2) = xw; }
.LBB0_1358:
	s_nop 1
	v_add_u32_e32 v72, 0xb0, v198
	v_lshlrev_b32_e32 v74, 1, v72
	v_ashrrev_i32_e32 v75, 31, v74
	v_lshl_add_u64 v[158:159], v[74:75], 2, s[94:95]
	global_load_dwordx2 v[82:83], v[158:159], off
	v_ashrrev_i32_e32 v73, 31, v72
	v_lshlrev_b64 v[162:163], 11, v[72:73]
	v_lshl_add_u64 v[72:73], v[162:163], 0, v[188:189]
	v_lshlrev_b64 v[78:79], 1, v[72:73]
	v_lshl_add_u64 v[74:75], s[82:83], 0, v[78:79]
	global_load_dwordx4 v[74:77], v[74:75], off
	v_lshl_add_u64 v[78:79], s[92:93], 0, v[78:79]
	global_load_dwordx4 v[78:81], v[78:79], off
	s_and_b64 vcc, exec, s[40:41]
	v_lshl_add_u64 v[120:121], v[72:73], 2, s[8:9]
	s_waitcnt vmcnt(0) lgkmcnt(0)
	v_pk_mul_f32 v[82:83], v[82:83], s[0:1] op_sel_hi:[1,0]
	s_nop 0
	v_fma_f32 v84, -v82, v82, v83
	v_max_f32_e32 v84, 0, v84
	v_add_f32_e32 v84, 0x3727c5ac, v84
	v_rsq_f32_e32 v84, v84
	v_fma_f32 v86, -v117, v82, v69
	v_fma_f32 v87, -v118, v82, v70
	v_fma_f32 v117, -v124, v82, v64
	v_fma_f32 v118, -v125, v82, v65
	v_lshlrev_b32_e32 v64, 16, v74
	v_and_b32_e32 v65, 0xffff0000, v74
	v_fma_f32 v85, -v116, v82, v68
	v_lshlrev_b32_e32 v68, 16, v75
	v_and_b32_e32 v69, 0xffff0000, v75
	v_lshlrev_b32_e32 v74, 16, v76
	v_and_b32_e32 v75, 0xffff0000, v76
	v_lshlrev_b32_e32 v76, 16, v77
	v_and_b32_e32 v77, 0xffff0000, v77
	v_pk_add_f32 v[64:65], v[64:65], v[82:83] op_sel_hi:[1,0] neg_lo:[0,1] neg_hi:[0,1]
	v_fma_f32 v116, -v119, v82, v71
	v_fma_f32 v119, -v126, v82, v66
	v_fma_f32 v124, -v127, v82, v67
	v_pk_add_f32 v[68:69], v[68:69], v[82:83] op_sel_hi:[1,0] neg_lo:[0,1] neg_hi:[0,1]
	v_pk_add_f32 v[74:75], v[74:75], v[82:83] op_sel_hi:[1,0] neg_lo:[0,1] neg_hi:[0,1]
	v_pk_add_f32 v[76:77], v[76:77], v[82:83] op_sel_hi:[1,0] neg_lo:[0,1] neg_hi:[0,1]
	v_fma_f32 v82, v85, v84, v96
	v_pk_mul_f32 v[64:65], v[84:85], v[64:65] op_sel_hi:[0,1]
	v_fma_f32 v85, v87, v84, v98
	v_fma_f32 v83, v86, v84, v97
	v_fmac_f32_e32 v99, v116, v84
	v_fma_f32 v86, v117, v84, v100
	v_fma_f32 v87, v118, v84, v101
	v_pk_mul_f32 v[74:75], v[84:85], v[74:75] op_sel_hi:[0,1]
	v_fma_f32 v96, v119, v84, v102
	v_fmac_f32_e32 v103, v124, v84
	v_pk_mul_f32 v[68:69], v[84:85], v[68:69] op_sel_hi:[0,1]
	v_pk_mul_f32 v[76:77], v[84:85], v[76:77] op_sel_hi:[0,1]
	v_mul_f32_e32 v82, 0xbfb8aa3b, v82
	v_mul_f32_e32 v83, 0xbfb8aa3b, v83
	v_mul_f32_e32 v84, 0xbfb8aa3b, v85
	v_mul_f32_e32 v85, 0xbfb8aa3b, v99
	v_mul_f32_e32 v86, 0xbfb8aa3b, v86
	v_mul_f32_e32 v87, 0xbfb8aa3b, v87
	v_pk_fma_f32 v[74:75], v[88:89], v[74:75], v[92:93]
	v_mul_f32_e32 v88, 0xbfb8aa3b, v96
	v_mul_f32_e32 v89, 0xbfb8aa3b, v103
	v_exp_f32_e32 v82, v82
	v_exp_f32_e32 v83, v83
	v_exp_f32_e32 v84, v84
	v_exp_f32_e32 v85, v85
	v_exp_f32_e32 v86, v86
	v_exp_f32_e32 v87, v87
	v_exp_f32_e32 v88, v88
	v_exp_f32_e32 v89, v89
	v_add_f32_e32 v82, 1.0, v82
	v_add_f32_e32 v83, 1.0, v83
	v_add_f32_e32 v84, 1.0, v84
	v_add_f32_e32 v85, 1.0, v85
	v_add_f32_e32 v86, 1.0, v86
	v_add_f32_e32 v87, 1.0, v87
	v_add_f32_e32 v88, 1.0, v88
	v_add_f32_e32 v89, 1.0, v89
	v_rcp_f32_e32 v82, v82
	v_rcp_f32_e32 v83, v83
	v_rcp_f32_e32 v84, v84
	v_rcp_f32_e32 v85, v85
	v_rcp_f32_e32 v86, v86
	v_rcp_f32_e32 v87, v87
	v_rcp_f32_e32 v88, v88
	v_rcp_f32_e32 v89, v89
	v_lshlrev_b32_e32 v66, 16, v78
	v_and_b32_e32 v67, 0xffff0000, v78
	v_lshlrev_b32_e32 v70, 16, v79
	v_and_b32_e32 v71, 0xffff0000, v79
	v_lshlrev_b32_e32 v78, 16, v80
	v_and_b32_e32 v79, 0xffff0000, v80
	v_lshlrev_b32_e32 v80, 16, v81
	v_and_b32_e32 v81, 0xffff0000, v81
	v_pk_fma_f32 v[64:65], v[104:105], v[64:65], v[108:109]
	v_pk_fma_f32 v[68:69], v[106:107], v[68:69], v[110:111]
	v_pk_fma_f32 v[76:77], v[90:91], v[76:77], v[94:95]
	v_pk_fma_f32 v[64:65], v[82:83], v[66:67], v[64:65]
	v_pk_fma_f32 v[66:67], v[84:85], v[70:71], v[68:69]
	v_pk_fma_f32 v[68:69], v[86:87], v[78:79], v[74:75]
	v_pk_fma_f32 v[70:71], v[88:89], v[80:81], v[76:77]
	global_store_dwordx4 v[120:121], v[64:67], off
	s_nop 1
	v_cvt_pk_bf16_f32 v64, v64, v65
	v_cvt_pk_bf16_f32 v65, v66, v67
	global_store_dwordx4 v[120:121], v[68:71], off offset:16
	v_cvt_pk_bf16_f32 v66, v68, v69
	v_cvt_pk_bf16_f32 v67, v70, v71
	s_cbranch_vccnz .LBB0_1360
	s_nop 0
	v_lshl_add_u64 v[68:69], v[72:73], 1, s[90:91]
	global_store_dwordx4 v[68:69], v[64:67], off
.LBB0_1360:
	global_load_dwordx4 v[88:91], v[184:185], off offset:512
	global_load_dwordx4 v[72:75], v[186:187], off offset:512
	global_load_dwordx4 v[64:67], v[192:193], off offset:528
	global_load_dwordx4 v[80:83], v[192:193], off offset:512
	global_load_dwordx4 v[68:71], v[190:191], off offset:528
	global_load_dwordx4 v[84:87], v[190:191], off offset:512
	global_load_dwordx4 v[92:95], v[184:185], off offset:528
	global_load_dwordx4 v[76:79], v[186:187], off offset:528
	global_load_dwordx2 v[96:97], v[196:197], off
	v_or_b32_e32 v104, 0x80, v188
	v_ashrrev_i32_e32 v105, 31, v104
	v_lshl_add_u64 v[106:107], v[194:195], 0, v[104:105]
	s_and_b64 vcc, exec, s[40:41]
	s_waitcnt vmcnt(0) lgkmcnt(0)
; __device__ __forceinline__ unsigned cvt_pk_bf16(float lo, float hi) { unsigned r; asm volatile("v_cvt_pk_bf16_f32 %0, %1, %2" : "=v"(r) : "v"(lo), "v"(hi)); return r; }
; __device__ __forceinline__ float bf_lo(unsigned w) { return __uint_as_float(w << 16); }
; __device__ __forceinline__ float bf_hi(unsigned w) { return __uint_as_float(w & 0xffff0000u); }
;     __device__ __forceinline__ void operator()(const f32x4 (&acc)[2][2][4][2], const Unit& u, int wr, int wc, int fr, int fq) const {
;     ...
;                 for (int m = 0; m < 4; ++m) { const int row = row0 + ai * HALF + m * 16; const size_t o2 = (size_t)row * ldc + col;
;                     const float s1 = ST[2 * row], s2 = ST[2 * row + 1], mu = s1 * (1.f / 2048.f), rstd = __builtin_amdgcn_rsqf(fmaxf(s2 * (1.f / 2048.f) - mu * mu, 0.f) + 1e-5f);
;                     const u32x4 zw = *(const u32x4*)(Zb + o2), pw = *(const u32x4*)(PE + o2); u32x4 xw;
; #pragma unroll
;                     for (int n = 0; n < 2; ++n) { const unsigned za = n ? zw.z : zw.x, zb2 = n ? zw.w : zw.y, pa = n ? pw.z : pw.x, pb = n ? pw.w : pw.y;
;                         const float zv[4] = {bf_lo(za), bf_hi(za), bf_lo(zb2), bf_hi(zb2)}, pv[4] = {bf_lo(pa), bf_hi(pa), bf_lo(pb), bf_hi(pb)}; const f32x4 a = acc[ai][bj][m][n]; f32x4 o;
; #pragma unroll
;                         for (int e = 0; e < 4; ++e) { const float sv = rstd * (a[e] - mu * c1[n][e]) + c2[n][e]; const float xl = (zv[e] - mu) * rstd * lg[n][e] + lb[n][e]; o[e] = xl + pv[e] * __builtin_amdgcn_rcpf(1.f + __expf(-sv)); }
;                         *(f32x4*)(OUTF + o2 + 4 * n) = o; if (n == 0) { xw.x = cvt_pk_bf16(o[0], o[1]); xw.y = cvt_pk_bf16(o[2], o[3]); } else { xw.z = cvt_pk_bf16(o[0], o[1]); xw.w = cvt_pk_bf16(o[2], o[3]); } }
;                     if (XB) *(u32x4*)(XB + o2) = xw; }
	v_pk_mul_f32 v[108:109], v[96:97], s[0:1] op_sel_hi:[1,0]
	s_nop 0
	v_fma_f32 v96, -v108, v108, v109
	v_max_f32_e32 v96, 0, v96
	v_add_f32_e32 v96, 0x3727c5ac, v96
	v_rsq_f32_e32 v110, v96
	v_lshlrev_b64 v[96:97], 1, v[106:107]
	v_lshl_add_u64 v[98:99], s[82:83], 0, v[96:97]
	global_load_dwordx4 v[100:103], v[98:99], off
	v_lshl_add_u64 v[96:97], s[92:93], 0, v[96:97]
	global_load_dwordx4 v[96:99], v[96:97], off
	v_fma_f32 v60, -v88, v108, v60
	v_fma_f32 v61, -v89, v108, v61
	v_fma_f32 v62, -v90, v108, v62
	v_fma_f32 v63, -v91, v108, v63
	v_fma_f32 v60, v60, v110, v72
	v_fma_f32 v61, v61, v110, v73
	v_fma_f32 v62, v62, v110, v74
	v_fma_f32 v63, v63, v110, v75
	v_mul_f32_e32 v60, 0xbfb8aa3b, v60
	v_mul_f32_e32 v61, 0xbfb8aa3b, v61
	v_mul_f32_e32 v62, 0xbfb8aa3b, v62
	v_mul_f32_e32 v63, 0xbfb8aa3b, v63
	v_exp_f32_e32 v60, v60
	v_exp_f32_e32 v61, v61
	v_exp_f32_e32 v62, v62
	v_exp_f32_e32 v63, v63
	v_fma_f32 v56, -v92, v108, v56
	v_fma_f32 v57, -v93, v108, v57
	v_fma_f32 v56, v56, v110, v76
	v_fma_f32 v57, v57, v110, v77
	v_add_f32_e32 v60, 1.0, v60
	v_add_f32_e32 v61, 1.0, v61
	v_add_f32_e32 v62, 1.0, v62
	v_add_f32_e32 v63, 1.0, v63
	v_mul_f32_e32 v56, 0xbfb8aa3b, v56
	v_mul_f32_e32 v57, 0xbfb8aa3b, v57
	v_rcp_f32_e32 v60, v60
	v_rcp_f32_e32 v61, v61
	v_rcp_f32_e32 v62, v62
	v_rcp_f32_e32 v63, v63
	v_exp_f32_e32 v56, v56
	v_exp_f32_e32 v57, v57
	v_fma_f32 v58, -v94, v108, v58
	v_fma_f32 v59, -v95, v108, v59
	v_fma_f32 v58, v58, v110, v78
	v_fma_f32 v59, v59, v110, v79
	v_mul_f32_e32 v58, 0xbfb8aa3b, v58
	v_mul_f32_e32 v59, 0xbfb8aa3b, v59
	v_add_f32_e32 v56, 1.0, v56
	v_add_f32_e32 v57, 1.0, v57
	v_exp_f32_e32 v58, v58
	v_exp_f32_e32 v59, v59
	v_rcp_f32_e32 v56, v56
	v_rcp_f32_e32 v57, v57
	v_add_f32_e32 v58, 1.0, v58
	v_add_f32_e32 v59, 1.0, v59
	v_rcp_f32_e32 v58, v58
	v_rcp_f32_e32 v59, v59
	s_waitcnt vmcnt(0) lgkmcnt(0)
	v_lshlrev_b32_e32 v116, 16, v100
	v_and_b32_e32 v117, 0xffff0000, v100
	v_lshlrev_b32_e32 v100, 16, v101
	v_and_b32_e32 v101, 0xffff0000, v101
	v_pk_add_f32 v[116:117], v[116:117], v[108:109] op_sel_hi:[1,0] neg_lo:[0,1] neg_hi:[0,1]
	v_pk_add_f32 v[100:101], v[100:101], v[108:109] op_sel_hi:[1,0] neg_lo:[0,1] neg_hi:[0,1]
	v_pk_mul_f32 v[116:117], v[110:111], v[116:117] op_sel_hi:[0,1]
	v_pk_mul_f32 v[100:101], v[110:111], v[100:101] op_sel_hi:[0,1]
	v_lshlrev_b32_e32 v118, 16, v96
	v_and_b32_e32 v119, 0xffff0000, v96
	v_pk_fma_f32 v[116:117], v[80:81], v[116:117], v[84:85]
	v_lshlrev_b32_e32 v96, 16, v97
	v_and_b32_e32 v97, 0xffff0000, v97
	v_pk_fma_f32 v[100:101], v[82:83], v[100:101], v[86:87]
	v_pk_fma_f32 v[60:61], v[60:61], v[118:119], v[116:117]
	v_pk_fma_f32 v[62:63], v[62:63], v[96:97], v[100:101]
	global_store_dwordx4 v[160:161], v[60:63], off offset:512
	v_lshlrev_b32_e32 v96, 16, v98
	v_and_b32_e32 v97, 0xffff0000, v98
	v_cvt_pk_bf16_f32 v60, v60, v61
	v_cvt_pk_bf16_f32 v61, v62, v63
	v_lshlrev_b32_e32 v62, 16, v102
	v_and_b32_e32 v63, 0xffff0000, v102
	v_pk_add_f32 v[62:63], v[62:63], v[108:109] op_sel_hi:[1,0] neg_lo:[0,1] neg_hi:[0,1]
	s_nop 0
	v_pk_mul_f32 v[62:63], v[110:111], v[62:63] op_sel_hi:[0,1]
	v_pk_fma_f32 v[62:63], v[64:65], v[62:63], v[68:69]
	s_nop 0
	v_pk_fma_f32 v[56:57], v[56:57], v[96:97], v[62:63]
	v_lshlrev_b32_e32 v62, 16, v103
	v_and_b32_e32 v63, 0xffff0000, v103
	v_pk_add_f32 v[62:63], v[62:63], v[108:109] op_sel_hi:[1,0] neg_lo:[0,1] neg_hi:[0,1]
	v_lshlrev_b32_e32 v96, 16, v99
	v_pk_mul_f32 v[62:63], v[110:111], v[62:63] op_sel_hi:[0,1]
	v_and_b32_e32 v97, 0xffff0000, v99
	v_pk_fma_f32 v[62:63], v[66:67], v[62:63], v[70:71]
	s_nop 0
	v_pk_fma_f32 v[58:59], v[58:59], v[96:97], v[62:63]
	global_store_dwordx4 v[160:161], v[56:59], off offset:528
	v_cvt_pk_bf16_f32 v62, v56, v57
	v_cvt_pk_bf16_f32 v63, v58, v59
	s_cbranch_vccnz .LBB0_1362
	s_nop 0
	v_lshl_add_u64 v[56:57], v[106:107], 1, s[90:91]
	global_store_dwordx4 v[56:57], v[60:63], off
.LBB0_1362:
	global_load_dwordx2 v[62:63], v[154:155], off
	v_lshl_add_u64 v[56:57], v[156:157], 0, v[104:105]
	v_lshlrev_b64 v[96:97], 1, v[56:57]
	v_lshl_add_u64 v[58:59], s[82:83], 0, v[96:97]
	global_load_dwordx4 v[58:61], v[58:59], off
	v_lshl_add_u64 v[96:97], s[92:93], 0, v[96:97]
	global_load_dwordx4 v[96:99], v[96:97], off
	s_and_b64 vcc, exec, s[40:41]
	s_waitcnt vmcnt(0) lgkmcnt(0)
; __device__ __forceinline__ unsigned cvt_pk_bf16(float lo, float hi) { unsigned r; asm volatile("v_cvt_pk_bf16_f32 %0, %1, %2" : "=v"(r) : "v"(lo), "v"(hi)); return r; }
; __device__ __forceinline__ float bf_lo(unsigned w) { return __uint_as_float(w << 16); }
; __device__ __forceinline__ float bf_hi(unsigned w) { return __uint_as_float(w & 0xffff0000u); }
;     __device__ __forceinline__ void operator()(const f32x4 (&acc)[2][2][4][2], const Unit& u, int wr, int wc, int fr, int fq) const {
;     ...
;                 for (int m = 0; m < 4; ++m) { const int row = row0 + ai * HALF + m * 16; const size_t o2 = (size_t)row * ldc + col;
;                     const float s1 = ST[2 * row], s2 = ST[2 * row + 1], mu = s1 * (1.f / 2048.f), rstd = __builtin_amdgcn_rsqf(fmaxf(s2 * (1.f / 2048.f) - mu * mu, 0.f) + 1e-5f);
;                     const u32x4 zw = *(const u32x4*)(Zb + o2), pw = *(const u32x4*)(PE + o2); u32x4 xw;
; #pragma unroll
;                     for (int n = 0; n < 2; ++n) { const unsigned za = n ? zw.z : zw.x, zb2 = n ? zw.w : zw.y, pa = n ? pw.z : pw.x, pb = n ? pw.w : pw.y;
;                         const float zv[4] = {bf_lo(za), bf_hi(za), bf_lo(zb2), bf_hi(zb2)}, pv[4] = {bf_lo(pa), bf_hi(pa), bf_lo(pb), bf_hi(pb)}; const f32x4 a = acc[ai][bj][m][n]; f32x4 o;
; #pragma unroll
;                         for (int e = 0; e < 4; ++e) { const float sv = rstd * (a[e] - mu * c1[n][e]) + c2[n][e]; const float xl = (zv[e] - mu) * rstd * lg[n][e] + lb[n][e]; o[e] = xl + pv[e] * __builtin_amdgcn_rcpf(1.f + __expf(-sv)); }
;                         *(f32x4*)(OUTF + o2 + 4 * n) = o; if (n == 0) { xw.x = cvt_pk_bf16(o[0], o[1]); xw.y = cvt_pk_bf16(o[2], o[3]); } else { xw.z = cvt_pk_bf16(o[0], o[1]); xw.w = cvt_pk_bf16(o[2], o[3]); } }
;                     if (XB) *(u32x4*)(XB + o2) = xw; }
	v_pk_mul_f32 v[62:63], v[62:63], s[0:1] op_sel_hi:[1,0]
	s_nop 0
	v_fma_f32 v100, -v62, v62, v63
	v_fma_f32 v107, -v92, v62, v48
	v_max_f32_e32 v48, 0, v100
	v_add_f32_e32 v100, 0x3727c5ac, v48
	v_rsq_f32_e32 v100, v100
	v_fma_f32 v108, -v93, v62, v49
	v_lshlrev_b32_e32 v48, 16, v58
	v_and_b32_e32 v49, 0xffff0000, v58
	v_fma_f32 v101, -v88, v62, v52
	v_fma_f32 v102, -v89, v62, v53
	v_fma_f32 v103, -v90, v62, v54
	v_fma_f32 v106, -v91, v62, v55
	v_fma_f32 v109, -v94, v62, v50
	v_fma_f32 v110, -v95, v62, v51
	v_lshlrev_b32_e32 v52, 16, v59
	v_and_b32_e32 v53, 0xffff0000, v59
	v_lshlrev_b32_e32 v58, 16, v60
	v_and_b32_e32 v59, 0xffff0000, v60
	v_lshlrev_b32_e32 v60, 16, v61
	v_and_b32_e32 v61, 0xffff0000, v61
	v_pk_add_f32 v[48:49], v[48:49], v[62:63] op_sel_hi:[1,0] neg_lo:[0,1] neg_hi:[0,1]
	v_pk_add_f32 v[52:53], v[52:53], v[62:63] op_sel_hi:[1,0] neg_lo:[0,1] neg_hi:[0,1]
	v_pk_add_f32 v[58:59], v[58:59], v[62:63] op_sel_hi:[1,0] neg_lo:[0,1] neg_hi:[0,1]
	v_pk_add_f32 v[60:61], v[60:61], v[62:63] op_sel_hi:[1,0] neg_lo:[0,1] neg_hi:[0,1]
	v_fma_f32 v62, v101, v100, v72
	v_fma_f32 v63, v102, v100, v73
	v_pk_mul_f32 v[48:49], v[100:101], v[48:49] op_sel_hi:[0,1]
	v_fma_f32 v101, v103, v100, v74
	v_fma_f32 v102, v106, v100, v75
	v_fma_f32 v103, v107, v100, v76
	v_fma_f32 v106, v108, v100, v77
	v_fma_f32 v107, v109, v100, v78
	v_fma_f32 v108, v110, v100, v79
	v_pk_mul_f32 v[52:53], v[100:101], v[52:53] op_sel_hi:[0,1]
	v_pk_mul_f32 v[58:59], v[100:101], v[58:59] op_sel_hi:[0,1]
	v_pk_mul_f32 v[60:61], v[100:101], v[60:61] op_sel_hi:[0,1]
	v_mul_f32_e32 v62, 0xbfb8aa3b, v62
	v_mul_f32_e32 v63, 0xbfb8aa3b, v63
	v_mul_f32_e32 v100, 0xbfb8aa3b, v101
	v_mul_f32_e32 v101, 0xbfb8aa3b, v102
	v_mul_f32_e32 v102, 0xbfb8aa3b, v103
	v_mul_f32_e32 v103, 0xbfb8aa3b, v106
	v_mul_f32_e32 v106, 0xbfb8aa3b, v107
	v_mul_f32_e32 v107, 0xbfb8aa3b, v108
	v_exp_f32_e32 v62, v62
	v_exp_f32_e32 v63, v63
	v_exp_f32_e32 v100, v100
	v_exp_f32_e32 v101, v101
	v_exp_f32_e32 v102, v102
	v_exp_f32_e32 v103, v103
	v_exp_f32_e32 v106, v106
	v_exp_f32_e32 v107, v107
	v_add_f32_e32 v62, 1.0, v62
	v_add_f32_e32 v63, 1.0, v63
	v_add_f32_e32 v100, 1.0, v100
	v_add_f32_e32 v101, 1.0, v101
	v_add_f32_e32 v102, 1.0, v102
	v_add_f32_e32 v103, 1.0, v103
	v_add_f32_e32 v106, 1.0, v106
	v_add_f32_e32 v107, 1.0, v107
	v_rcp_f32_e32 v62, v62
	v_rcp_f32_e32 v63, v63
	v_rcp_f32_e32 v100, v100
	v_rcp_f32_e32 v101, v101
	v_rcp_f32_e32 v102, v102
	v_rcp_f32_e32 v103, v103
	v_rcp_f32_e32 v106, v106
	v_rcp_f32_e32 v107, v107
	v_lshlrev_b32_e32 v50, 16, v96
	v_and_b32_e32 v51, 0xffff0000, v96
	v_lshlrev_b32_e32 v54, 16, v97
	v_and_b32_e32 v55, 0xffff0000, v97
	v_lshlrev_b32_e32 v96, 16, v98
	v_and_b32_e32 v97, 0xffff0000, v98
	v_lshlrev_b32_e32 v98, 16, v99
	v_and_b32_e32 v99, 0xffff0000, v99
	v_pk_fma_f32 v[48:49], v[80:81], v[48:49], v[84:85]
	v_pk_fma_f32 v[52:53], v[82:83], v[52:53], v[86:87]
	v_pk_fma_f32 v[58:59], v[64:65], v[58:59], v[68:69]
	v_pk_fma_f32 v[60:61], v[66:67], v[60:61], v[70:71]
	v_pk_fma_f32 v[48:49], v[62:63], v[50:51], v[48:49]
	v_pk_fma_f32 v[50:51], v[100:101], v[54:55], v[52:53]
	v_pk_fma_f32 v[52:53], v[102:103], v[96:97], v[58:59]
	v_pk_fma_f32 v[54:55], v[106:107], v[98:99], v[60:61]
	global_store_dwordx4 v[152:153], v[48:51], off offset:512
	s_nop 1
	v_cvt_pk_bf16_f32 v48, v48, v49
	v_cvt_pk_bf16_f32 v49, v50, v51
	global_store_dwordx4 v[152:153], v[52:55], off offset:528
	v_cvt_pk_bf16_f32 v50, v52, v53
	v_cvt_pk_bf16_f32 v51, v54, v55
	s_cbranch_vccnz .LBB0_1364
	s_nop 0
	v_lshl_add_u64 v[52:53], v[56:57], 1, s[90:91]
	global_store_dwordx4 v[52:53], v[48:51], off
.LBB0_1364:
	global_load_dwordx2 v[58:59], v[146:147], off
	s_nop 0
	v_lshl_add_u64 v[48:49], v[148:149], 0, v[104:105]
	v_lshlrev_b64 v[54:55], 1, v[48:49]
	v_lshl_add_u64 v[50:51], s[82:83], 0, v[54:55]
	global_load_dwordx4 v[50:53], v[50:51], off
	v_lshl_add_u64 v[54:55], s[92:93], 0, v[54:55]
	global_load_dwordx4 v[54:57], v[54:55], off
	s_and_b64 vcc, exec, s[40:41]
	s_waitcnt vmcnt(0) lgkmcnt(0)
	v_pk_mul_f32 v[58:59], v[58:59], s[0:1] op_sel_hi:[1,0]
	s_nop 0
	v_fma_f32 v60, -v58, v58, v59
	v_fma_f32 v97, -v92, v58, v40
	v_max_f32_e32 v40, 0, v60
	v_add_f32_e32 v60, 0x3727c5ac, v40
	v_rsq_f32_e32 v60, v60
	v_fma_f32 v98, -v93, v58, v41
	v_lshlrev_b32_e32 v40, 16, v50
	v_and_b32_e32 v41, 0xffff0000, v50
	v_fma_f32 v61, -v88, v58, v44
	v_fma_f32 v62, -v89, v58, v45
	v_fma_f32 v63, -v90, v58, v46
	v_fma_f32 v96, -v91, v58, v47
	v_fma_f32 v99, -v94, v58, v42
	v_fma_f32 v100, -v95, v58, v43
	v_lshlrev_b32_e32 v44, 16, v51
	v_and_b32_e32 v45, 0xffff0000, v51
	v_lshlrev_b32_e32 v50, 16, v52
	v_and_b32_e32 v51, 0xffff0000, v52
	v_lshlrev_b32_e32 v52, 16, v53
	v_and_b32_e32 v53, 0xffff0000, v53
	v_pk_add_f32 v[40:41], v[40:41], v[58:59] op_sel_hi:[1,0] neg_lo:[0,1] neg_hi:[0,1]
	v_pk_add_f32 v[44:45], v[44:45], v[58:59] op_sel_hi:[1,0] neg_lo:[0,1] neg_hi:[0,1]
	v_pk_add_f32 v[50:51], v[50:51], v[58:59] op_sel_hi:[1,0] neg_lo:[0,1] neg_hi:[0,1]
	v_pk_add_f32 v[52:53], v[52:53], v[58:59] op_sel_hi:[1,0] neg_lo:[0,1] neg_hi:[0,1]
	v_fma_f32 v58, v61, v60, v72
	v_fma_f32 v59, v62, v60, v73
	v_pk_mul_f32 v[40:41], v[60:61], v[40:41] op_sel_hi:[0,1]
	v_fma_f32 v61, v63, v60, v74
	v_fma_f32 v62, v96, v60, v75
	v_fma_f32 v63, v97, v60, v76
	v_fma_f32 v96, v98, v60, v77
	v_fma_f32 v97, v99, v60, v78
	v_fma_f32 v98, v100, v60, v79
	v_pk_mul_f32 v[44:45], v[60:61], v[44:45] op_sel_hi:[0,1]
	v_pk_mul_f32 v[50:51], v[60:61], v[50:51] op_sel_hi:[0,1]
	v_pk_mul_f32 v[52:53], v[60:61], v[52:53] op_sel_hi:[0,1]
	v_mul_f32_e32 v58, 0xbfb8aa3b, v58
	v_mul_f32_e32 v59, 0xbfb8aa3b, v59
	v_mul_f32_e32 v60, 0xbfb8aa3b, v61
; __device__ __forceinline__ unsigned cvt_pk_bf16(float lo, float hi) { unsigned r; asm volatile("v_cvt_pk_bf16_f32 %0, %1, %2" : "=v"(r) : "v"(lo), "v"(hi)); return r; }
; __device__ __forceinline__ float bf_lo(unsigned w) { return __uint_as_float(w << 16); }
; __device__ __forceinline__ float bf_hi(unsigned w) { return __uint_as_float(w & 0xffff0000u); }
;     __device__ __forceinline__ void operator()(const f32x4 (&acc)[2][2][4][2], const Unit& u, int wr, int wc, int fr, int fq) const {
;     ...
;                 for (int m = 0; m < 4; ++m) { const int row = row0 + ai * HALF + m * 16; const size_t o2 = (size_t)row * ldc + col;
;                     const float s1 = ST[2 * row], s2 = ST[2 * row + 1], mu = s1 * (1.f / 2048.f), rstd = __builtin_amdgcn_rsqf(fmaxf(s2 * (1.f / 2048.f) - mu * mu, 0.f) + 1e-5f);
;                     const u32x4 zw = *(const u32x4*)(Zb + o2), pw = *(const u32x4*)(PE + o2); u32x4 xw;
; #pragma unroll
;                     for (int n = 0; n < 2; ++n) { const unsigned za = n ? zw.z : zw.x, zb2 = n ? zw.w : zw.y, pa = n ? pw.z : pw.x, pb = n ? pw.w : pw.y;
;                         const float zv[4] = {bf_lo(za), bf_hi(za), bf_lo(zb2), bf_hi(zb2)}, pv[4] = {bf_lo(pa), bf_hi(pa), bf_lo(pb), bf_hi(pb)}; const f32x4 a = acc[ai][bj][m][n]; f32x4 o;
; #pragma unroll
;                         for (int e = 0; e < 4; ++e) { const float sv = rstd * (a[e] - mu * c1[n][e]) + c2[n][e]; const float xl = (zv[e] - mu) * rstd * lg[n][e] + lb[n][e]; o[e] = xl + pv[e] * __builtin_amdgcn_rcpf(1.f + __expf(-sv)); }
;                         *(f32x4*)(OUTF + o2 + 4 * n) = o; if (n == 0) { xw.x = cvt_pk_bf16(o[0], o[1]); xw.y = cvt_pk_bf16(o[2], o[3]); } else { xw.z = cvt_pk_bf16(o[0], o[1]); xw.w = cvt_pk_bf16(o[2], o[3]); } }
;                     if (XB) *(u32x4*)(XB + o2) = xw; }
	v_mul_f32_e32 v61, 0xbfb8aa3b, v62
	v_mul_f32_e32 v62, 0xbfb8aa3b, v63
	v_mul_f32_e32 v63, 0xbfb8aa3b, v96
	v_mul_f32_e32 v96, 0xbfb8aa3b, v97
	v_mul_f32_e32 v97, 0xbfb8aa3b, v98
	v_exp_f32_e32 v58, v58
	v_exp_f32_e32 v59, v59
	v_exp_f32_e32 v60, v60
	v_exp_f32_e32 v61, v61
	v_exp_f32_e32 v62, v62
	v_exp_f32_e32 v63, v63
	v_exp_f32_e32 v96, v96
	v_exp_f32_e32 v97, v97
	v_add_f32_e32 v58, 1.0, v58
	v_add_f32_e32 v59, 1.0, v59
	v_add_f32_e32 v60, 1.0, v60
	v_add_f32_e32 v61, 1.0, v61
	v_add_f32_e32 v62, 1.0, v62
	v_add_f32_e32 v63, 1.0, v63
	v_add_f32_e32 v96, 1.0, v96
	v_add_f32_e32 v97, 1.0, v97
	v_rcp_f32_e32 v58, v58
	v_rcp_f32_e32 v59, v59
	v_rcp_f32_e32 v60, v60
	v_rcp_f32_e32 v61, v61
	v_rcp_f32_e32 v62, v62
	v_rcp_f32_e32 v63, v63
	v_rcp_f32_e32 v96, v96
	v_rcp_f32_e32 v97, v97
	v_lshlrev_b32_e32 v42, 16, v54
	v_and_b32_e32 v43, 0xffff0000, v54
	v_lshlrev_b32_e32 v46, 16, v55
	v_and_b32_e32 v47, 0xffff0000, v55
	v_lshlrev_b32_e32 v54, 16, v56
	v_and_b32_e32 v55, 0xffff0000, v56
	v_lshlrev_b32_e32 v56, 16, v57
	v_and_b32_e32 v57, 0xffff0000, v57
	v_pk_fma_f32 v[40:41], v[80:81], v[40:41], v[84:85]
	v_pk_fma_f32 v[44:45], v[82:83], v[44:45], v[86:87]
	v_pk_fma_f32 v[50:51], v[64:65], v[50:51], v[68:69]
	v_pk_fma_f32 v[52:53], v[66:67], v[52:53], v[70:71]
	v_pk_fma_f32 v[40:41], v[58:59], v[42:43], v[40:41]
	v_pk_fma_f32 v[42:43], v[60:61], v[46:47], v[44:45]
	v_pk_fma_f32 v[44:45], v[62:63], v[54:55], v[50:51]
	v_pk_fma_f32 v[46:47], v[96:97], v[56:57], v[52:53]
	global_store_dwordx4 v[144:145], v[40:43], off offset:512
	s_nop 1
	v_cvt_pk_bf16_f32 v40, v40, v41
	v_cvt_pk_bf16_f32 v41, v42, v43
	global_store_dwordx4 v[144:145], v[44:47], off offset:528
	v_cvt_pk_bf16_f32 v42, v44, v45
	v_cvt_pk_bf16_f32 v43, v46, v47
	s_cbranch_vccnz .LBB0_1366
	s_nop 0
	v_lshl_add_u64 v[44:45], v[48:49], 1, s[90:91]
	global_store_dwordx4 v[44:45], v[40:43], off
.LBB0_1366:
	global_load_dwordx2 v[50:51], v[138:139], off
	s_nop 0
	v_lshl_add_u64 v[40:41], v[140:141], 0, v[104:105]
	v_lshlrev_b64 v[46:47], 1, v[40:41]
	v_lshl_add_u64 v[42:43], s[82:83], 0, v[46:47]
	global_load_dwordx4 v[42:45], v[42:43], off
	v_lshl_add_u64 v[46:47], s[92:93], 0, v[46:47]
	global_load_dwordx4 v[46:49], v[46:47], off
	s_and_b64 vcc, exec, s[40:41]
	s_waitcnt vmcnt(0) lgkmcnt(0)
	v_pk_mul_f32 v[50:51], v[50:51], s[0:1] op_sel_hi:[1,0]
	s_nop 0
	v_fma_f32 v52, -v50, v50, v51
	v_fma_f32 v57, -v92, v50, v32
	v_max_f32_e32 v32, 0, v52
	v_add_f32_e32 v52, 0x3727c5ac, v32
	v_rsq_f32_e32 v52, v52
	v_fma_f32 v58, -v93, v50, v33
	v_lshlrev_b32_e32 v32, 16, v42
	v_and_b32_e32 v33, 0xffff0000, v42
	v_fma_f32 v53, -v88, v50, v36
	v_fma_f32 v54, -v89, v50, v37
	v_fma_f32 v55, -v90, v50, v38
	v_fma_f32 v56, -v91, v50, v39
	v_fma_f32 v59, -v94, v50, v34
	v_fma_f32 v60, -v95, v50, v35
	v_lshlrev_b32_e32 v36, 16, v43
	v_and_b32_e32 v37, 0xffff0000, v43
	v_lshlrev_b32_e32 v42, 16, v44
	v_and_b32_e32 v43, 0xffff0000, v44
	v_lshlrev_b32_e32 v44, 16, v45
	v_and_b32_e32 v45, 0xffff0000, v45
	v_pk_add_f32 v[32:33], v[32:33], v[50:51] op_sel_hi:[1,0] neg_lo:[0,1] neg_hi:[0,1]
	v_pk_add_f32 v[36:37], v[36:37], v[50:51] op_sel_hi:[1,0] neg_lo:[0,1] neg_hi:[0,1]
	v_pk_add_f32 v[42:43], v[42:43], v[50:51] op_sel_hi:[1,0] neg_lo:[0,1] neg_hi:[0,1]
	v_pk_add_f32 v[44:45], v[44:45], v[50:51] op_sel_hi:[1,0] neg_lo:[0,1] neg_hi:[0,1]
	v_fma_f32 v50, v53, v52, v72
	v_fma_f32 v51, v54, v52, v73
	v_pk_mul_f32 v[32:33], v[52:53], v[32:33] op_sel_hi:[0,1]
	v_fma_f32 v53, v55, v52, v74
	v_fma_f32 v54, v56, v52, v75
	v_fma_f32 v55, v57, v52, v76
	v_fma_f32 v56, v58, v52, v77
	v_fma_f32 v57, v59, v52, v78
	v_fma_f32 v58, v60, v52, v79
	v_pk_mul_f32 v[36:37], v[52:53], v[36:37] op_sel_hi:[0,1]
	v_pk_mul_f32 v[42:43], v[52:53], v[42:43] op_sel_hi:[0,1]
	v_pk_mul_f32 v[44:45], v[52:53], v[44:45] op_sel_hi:[0,1]
	v_mul_f32_e32 v50, 0xbfb8aa3b, v50
	v_mul_f32_e32 v51, 0xbfb8aa3b, v51
	v_mul_f32_e32 v52, 0xbfb8aa3b, v53
	v_mul_f32_e32 v53, 0xbfb8aa3b, v54
	v_mul_f32_e32 v54, 0xbfb8aa3b, v55
	v_mul_f32_e32 v55, 0xbfb8aa3b, v56
	v_mul_f32_e32 v56, 0xbfb8aa3b, v57
	v_mul_f32_e32 v57, 0xbfb8aa3b, v58
	v_exp_f32_e32 v50, v50
	v_exp_f32_e32 v51, v51
	v_exp_f32_e32 v52, v52
	v_exp_f32_e32 v53, v53
	v_exp_f32_e32 v54, v54
	v_exp_f32_e32 v55, v55
	v_exp_f32_e32 v56, v56
	v_exp_f32_e32 v57, v57
	v_add_f32_e32 v50, 1.0, v50
	v_add_f32_e32 v51, 1.0, v51
	v_add_f32_e32 v52, 1.0, v52
	v_add_f32_e32 v53, 1.0, v53
	v_add_f32_e32 v54, 1.0, v54
	v_add_f32_e32 v55, 1.0, v55
	v_add_f32_e32 v56, 1.0, v56
	v_add_f32_e32 v57, 1.0, v57
	v_rcp_f32_e32 v50, v50
	v_rcp_f32_e32 v51, v51
	v_rcp_f32_e32 v52, v52
	v_rcp_f32_e32 v53, v53
	v_rcp_f32_e32 v54, v54
	v_rcp_f32_e32 v55, v55
	v_rcp_f32_e32 v56, v56
	v_rcp_f32_e32 v57, v57
	v_lshlrev_b32_e32 v34, 16, v46
	v_and_b32_e32 v35, 0xffff0000, v46
	v_lshlrev_b32_e32 v38, 16, v47
	v_and_b32_e32 v39, 0xffff0000, v47
	v_lshlrev_b32_e32 v46, 16, v48
	v_and_b32_e32 v47, 0xffff0000, v48
	v_lshlrev_b32_e32 v48, 16, v49
	v_and_b32_e32 v49, 0xffff0000, v49
	v_pk_fma_f32 v[32:33], v[80:81], v[32:33], v[84:85]
	v_pk_fma_f32 v[36:37], v[82:83], v[36:37], v[86:87]
	v_pk_fma_f32 v[42:43], v[64:65], v[42:43], v[68:69]
	v_pk_fma_f32 v[44:45], v[66:67], v[44:45], v[70:71]
	v_pk_fma_f32 v[32:33], v[50:51], v[34:35], v[32:33]
	v_pk_fma_f32 v[34:35], v[52:53], v[38:39], v[36:37]
	v_pk_fma_f32 v[36:37], v[54:55], v[46:47], v[42:43]
	v_pk_fma_f32 v[38:39], v[56:57], v[48:49], v[44:45]
	global_store_dwordx4 v[136:137], v[32:35], off offset:512
	s_nop 1
	v_cvt_pk_bf16_f32 v32, v32, v33
	v_cvt_pk_bf16_f32 v33, v34, v35
	global_store_dwordx4 v[136:137], v[36:39], off offset:528
	v_cvt_pk_bf16_f32 v34, v36, v37
	v_cvt_pk_bf16_f32 v35, v38, v39
	s_cbranch_vccnz .LBB0_1368
	s_nop 0
	v_lshl_add_u64 v[36:37], v[40:41], 1, s[90:91]
	global_store_dwordx4 v[36:37], v[32:35], off
; __device__ __forceinline__ unsigned cvt_pk_bf16(float lo, float hi) { unsigned r; asm volatile("v_cvt_pk_bf16_f32 %0, %1, %2" : "=v"(r) : "v"(lo), "v"(hi)); return r; }
; __device__ __forceinline__ float bf_lo(unsigned w) { return __uint_as_float(w << 16); }
; __device__ __forceinline__ float bf_hi(unsigned w) { return __uint_as_float(w & 0xffff0000u); }
;     __device__ __forceinline__ void operator()(const f32x4 (&acc)[2][2][4][2], const Unit& u, int wr, int wc, int fr, int fq) const {
;     ...
;                 for (int m = 0; m < 4; ++m) { const int row = row0 + ai * HALF + m * 16; const size_t o2 = (size_t)row * ldc + col;
;                     const float s1 = ST[2 * row], s2 = ST[2 * row + 1], mu = s1 * (1.f / 2048.f), rstd = __builtin_amdgcn_rsqf(fmaxf(s2 * (1.f / 2048.f) - mu * mu, 0.f) + 1e-5f);
;                     const u32x4 zw = *(const u32x4*)(Zb + o2), pw = *(const u32x4*)(PE + o2); u32x4 xw;
; #pragma unroll
;                     for (int n = 0; n < 2; ++n) { const unsigned za = n ? zw.z : zw.x, zb2 = n ? zw.w : zw.y, pa = n ? pw.z : pw.x, pb = n ? pw.w : pw.y;
;                         const float zv[4] = {bf_lo(za), bf_hi(za), bf_lo(zb2), bf_hi(zb2)}, pv[4] = {bf_lo(pa), bf_hi(pa), bf_lo(pb), bf_hi(pb)}; const f32x4 a = acc[ai][bj][m][n]; f32x4 o;
; #pragma unroll
;                         for (int e = 0; e < 4; ++e) { const float sv = rstd * (a[e] - mu * c1[n][e]) + c2[n][e]; const float xl = (zv[e] - mu) * rstd * lg[n][e] + lb[n][e]; o[e] = xl + pv[e] * __builtin_amdgcn_rcpf(1.f + __expf(-sv)); }
;                         *(f32x4*)(OUTF + o2 + 4 * n) = o; if (n == 0) { xw.x = cvt_pk_bf16(o[0], o[1]); xw.y = cvt_pk_bf16(o[2], o[3]); } else { xw.z = cvt_pk_bf16(o[0], o[1]); xw.w = cvt_pk_bf16(o[2], o[3]); } }
;                     if (XB) *(u32x4*)(XB + o2) = xw; }
.LBB0_1368:
	global_load_dwordx2 v[42:43], v[130:131], off
	s_nop 0
	v_lshl_add_u64 v[32:33], v[132:133], 0, v[104:105]
	v_lshlrev_b64 v[38:39], 1, v[32:33]
	v_lshl_add_u64 v[34:35], s[82:83], 0, v[38:39]
	global_load_dwordx4 v[34:37], v[34:35], off
	v_lshl_add_u64 v[38:39], s[92:93], 0, v[38:39]
	global_load_dwordx4 v[38:41], v[38:39], off
	s_and_b64 vcc, exec, s[40:41]
	s_waitcnt vmcnt(0) lgkmcnt(0)
	v_pk_mul_f32 v[42:43], v[42:43], s[0:1] op_sel_hi:[1,0]
	s_nop 0
	v_fma_f32 v44, -v42, v42, v43
	v_fma_f32 v49, -v92, v42, v24
	v_max_f32_e32 v24, 0, v44
	v_add_f32_e32 v44, 0x3727c5ac, v24
	v_rsq_f32_e32 v44, v44
	v_fma_f32 v50, -v93, v42, v25
	v_lshlrev_b32_e32 v24, 16, v34
	v_and_b32_e32 v25, 0xffff0000, v34
	v_fma_f32 v45, -v88, v42, v28
	v_fma_f32 v46, -v89, v42, v29
	v_fma_f32 v47, -v90, v42, v30
	v_fma_f32 v48, -v91, v42, v31
	v_fma_f32 v51, -v94, v42, v26
	v_fma_f32 v52, -v95, v42, v27
	v_lshlrev_b32_e32 v28, 16, v35
	v_and_b32_e32 v29, 0xffff0000, v35
	v_lshlrev_b32_e32 v34, 16, v36
	v_and_b32_e32 v35, 0xffff0000, v36
	v_lshlrev_b32_e32 v36, 16, v37
	v_and_b32_e32 v37, 0xffff0000, v37
	v_pk_add_f32 v[24:25], v[24:25], v[42:43] op_sel_hi:[1,0] neg_lo:[0,1] neg_hi:[0,1]
	v_pk_add_f32 v[28:29], v[28:29], v[42:43] op_sel_hi:[1,0] neg_lo:[0,1] neg_hi:[0,1]
	v_pk_add_f32 v[34:35], v[34:35], v[42:43] op_sel_hi:[1,0] neg_lo:[0,1] neg_hi:[0,1]
	v_pk_add_f32 v[36:37], v[36:37], v[42:43] op_sel_hi:[1,0] neg_lo:[0,1] neg_hi:[0,1]
	v_fma_f32 v42, v45, v44, v72
	v_fma_f32 v43, v46, v44, v73
	v_pk_mul_f32 v[24:25], v[44:45], v[24:25] op_sel_hi:[0,1]
	v_fma_f32 v45, v47, v44, v74
	v_fma_f32 v46, v48, v44, v75
	v_fma_f32 v47, v49, v44, v76
	v_fma_f32 v48, v50, v44, v77
	v_fma_f32 v49, v51, v44, v78
	v_fma_f32 v50, v52, v44, v79
	v_pk_mul_f32 v[28:29], v[44:45], v[28:29] op_sel_hi:[0,1]
	v_pk_mul_f32 v[34:35], v[44:45], v[34:35] op_sel_hi:[0,1]
	v_pk_mul_f32 v[36:37], v[44:45], v[36:37] op_sel_hi:[0,1]
	v_mul_f32_e32 v42, 0xbfb8aa3b, v42
	v_mul_f32_e32 v43, 0xbfb8aa3b, v43
	v_mul_f32_e32 v44, 0xbfb8aa3b, v45
	v_mul_f32_e32 v45, 0xbfb8aa3b, v46
	v_mul_f32_e32 v46, 0xbfb8aa3b, v47
	v_mul_f32_e32 v47, 0xbfb8aa3b, v48
	v_mul_f32_e32 v48, 0xbfb8aa3b, v49
	v_mul_f32_e32 v49, 0xbfb8aa3b, v50
	v_exp_f32_e32 v42, v42
	v_exp_f32_e32 v43, v43
	v_exp_f32_e32 v44, v44
	v_exp_f32_e32 v45, v45
	v_exp_f32_e32 v46, v46
	v_exp_f32_e32 v47, v47
	v_exp_f32_e32 v48, v48
	v_exp_f32_e32 v49, v49
	v_add_f32_e32 v42, 1.0, v42
	v_add_f32_e32 v43, 1.0, v43
	v_add_f32_e32 v44, 1.0, v44
	v_add_f32_e32 v45, 1.0, v45
	v_add_f32_e32 v46, 1.0, v46
	v_add_f32_e32 v47, 1.0, v47
	v_add_f32_e32 v48, 1.0, v48
	v_add_f32_e32 v49, 1.0, v49
	v_rcp_f32_e32 v42, v42
	v_rcp_f32_e32 v43, v43
	v_rcp_f32_e32 v44, v44
	v_rcp_f32_e32 v45, v45
	v_rcp_f32_e32 v46, v46
	v_rcp_f32_e32 v47, v47
	v_rcp_f32_e32 v48, v48
	v_rcp_f32_e32 v49, v49
	v_lshlrev_b32_e32 v26, 16, v38
	v_and_b32_e32 v27, 0xffff0000, v38
	v_lshlrev_b32_e32 v30, 16, v39
	v_and_b32_e32 v31, 0xffff0000, v39
	v_lshlrev_b32_e32 v38, 16, v40
	v_and_b32_e32 v39, 0xffff0000, v40
	v_lshlrev_b32_e32 v40, 16, v41
	v_and_b32_e32 v41, 0xffff0000, v41
	v_pk_fma_f32 v[24:25], v[80:81], v[24:25], v[84:85]
	v_pk_fma_f32 v[28:29], v[82:83], v[28:29], v[86:87]
	v_pk_fma_f32 v[34:35], v[64:65], v[34:35], v[68:69]
	v_pk_fma_f32 v[36:37], v[66:67], v[36:37], v[70:71]
	v_pk_fma_f32 v[24:25], v[42:43], v[26:27], v[24:25]
	v_pk_fma_f32 v[26:27], v[44:45], v[30:31], v[28:29]
	v_pk_fma_f32 v[28:29], v[46:47], v[38:39], v[34:35]
	v_pk_fma_f32 v[30:31], v[48:49], v[40:41], v[36:37]
	global_store_dwordx4 v[128:129], v[24:27], off offset:512
	s_nop 1
	v_cvt_pk_bf16_f32 v24, v24, v25
	v_cvt_pk_bf16_f32 v25, v26, v27
	global_store_dwordx4 v[128:129], v[28:31], off offset:528
	v_cvt_pk_bf16_f32 v26, v28, v29
	v_cvt_pk_bf16_f32 v27, v30, v31
	s_cbranch_vccnz .LBB0_1370
	s_nop 0
	v_lshl_add_u64 v[28:29], v[32:33], 1, s[90:91]
	global_store_dwordx4 v[28:29], v[24:27], off
.LBB0_1370:
	global_load_dwordx2 v[34:35], v[122:123], off
	s_nop 0
	v_lshl_add_u64 v[24:25], v[134:135], 0, v[104:105]
	v_lshlrev_b64 v[30:31], 1, v[24:25]
	v_lshl_add_u64 v[26:27], s[82:83], 0, v[30:31]
	global_load_dwordx4 v[26:29], v[26:27], off
	v_lshl_add_u64 v[30:31], s[92:93], 0, v[30:31]
	global_load_dwordx4 v[30:33], v[30:31], off
	s_and_b64 vcc, exec, s[40:41]
	s_waitcnt vmcnt(0) lgkmcnt(0)
; __device__ __forceinline__ unsigned cvt_pk_bf16(float lo, float hi) { unsigned r; asm volatile("v_cvt_pk_bf16_f32 %0, %1, %2" : "=v"(r) : "v"(lo), "v"(hi)); return r; }
; __device__ __forceinline__ float bf_lo(unsigned w) { return __uint_as_float(w << 16); }
; __device__ __forceinline__ float bf_hi(unsigned w) { return __uint_as_float(w & 0xffff0000u); }
;     __device__ __forceinline__ void operator()(const f32x4 (&acc)[2][2][4][2], const Unit& u, int wr, int wc, int fr, int fq) const {
;     ...
;                 for (int m = 0; m < 4; ++m) { const int row = row0 + ai * HALF + m * 16; const size_t o2 = (size_t)row * ldc + col;
;                     const float s1 = ST[2 * row], s2 = ST[2 * row + 1], mu = s1 * (1.f / 2048.f), rstd = __builtin_amdgcn_rsqf(fmaxf(s2 * (1.f / 2048.f) - mu * mu, 0.f) + 1e-5f);
;                     const u32x4 zw = *(const u32x4*)(Zb + o2), pw = *(const u32x4*)(PE + o2); u32x4 xw;
; #pragma unroll
;                     for (int n = 0; n < 2; ++n) { const unsigned za = n ? zw.z : zw.x, zb2 = n ? zw.w : zw.y, pa = n ? pw.z : pw.x, pb = n ? pw.w : pw.y;
;                         const float zv[4] = {bf_lo(za), bf_hi(za), bf_lo(zb2), bf_hi(zb2)}, pv[4] = {bf_lo(pa), bf_hi(pa), bf_lo(pb), bf_hi(pb)}; const f32x4 a = acc[ai][bj][m][n]; f32x4 o;
; #pragma unroll
;                         for (int e = 0; e < 4; ++e) { const float sv = rstd * (a[e] - mu * c1[n][e]) + c2[n][e]; const float xl = (zv[e] - mu) * rstd * lg[n][e] + lb[n][e]; o[e] = xl + pv[e] * __builtin_amdgcn_rcpf(1.f + __expf(-sv)); }
;                         *(f32x4*)(OUTF + o2 + 4 * n) = o; if (n == 0) { xw.x = cvt_pk_bf16(o[0], o[1]); xw.y = cvt_pk_bf16(o[2], o[3]); } else { xw.z = cvt_pk_bf16(o[0], o[1]); xw.w = cvt_pk_bf16(o[2], o[3]); } }
;                     if (XB) *(u32x4*)(XB + o2) = xw; }
	v_pk_mul_f32 v[34:35], v[34:35], s[0:1] op_sel_hi:[1,0]
	s_nop 0
	v_fma_f32 v36, -v34, v34, v35
	v_fma_f32 v41, -v92, v34, v16
	v_max_f32_e32 v16, 0, v36
	v_add_f32_e32 v36, 0x3727c5ac, v16
	v_rsq_f32_e32 v36, v36
	v_fma_f32 v42, -v93, v34, v17
	v_lshlrev_b32_e32 v16, 16, v26
	v_and_b32_e32 v17, 0xffff0000, v26
	v_fma_f32 v37, -v88, v34, v20
	v_fma_f32 v38, -v89, v34, v21
	v_fma_f32 v39, -v90, v34, v22
	v_fma_f32 v40, -v91, v34, v23
	v_fma_f32 v43, -v94, v34, v18
	v_fma_f32 v44, -v95, v34, v19
	v_lshlrev_b32_e32 v20, 16, v27
	v_and_b32_e32 v21, 0xffff0000, v27
	v_lshlrev_b32_e32 v26, 16, v28
	v_and_b32_e32 v27, 0xffff0000, v28
	v_lshlrev_b32_e32 v28, 16, v29
	v_and_b32_e32 v29, 0xffff0000, v29
	v_pk_add_f32 v[16:17], v[16:17], v[34:35] op_sel_hi:[1,0] neg_lo:[0,1] neg_hi:[0,1]
	v_pk_add_f32 v[20:21], v[20:21], v[34:35] op_sel_hi:[1,0] neg_lo:[0,1] neg_hi:[0,1]
	v_pk_add_f32 v[26:27], v[26:27], v[34:35] op_sel_hi:[1,0] neg_lo:[0,1] neg_hi:[0,1]
	v_pk_add_f32 v[28:29], v[28:29], v[34:35] op_sel_hi:[1,0] neg_lo:[0,1] neg_hi:[0,1]
	v_fma_f32 v34, v37, v36, v72
	v_fma_f32 v35, v38, v36, v73
	v_pk_mul_f32 v[16:17], v[36:37], v[16:17] op_sel_hi:[0,1]
	v_fma_f32 v37, v39, v36, v74
	v_fma_f32 v38, v40, v36, v75
	v_fma_f32 v39, v41, v36, v76
	v_fma_f32 v40, v42, v36, v77
	v_fma_f32 v41, v43, v36, v78
	v_fma_f32 v42, v44, v36, v79
	v_pk_mul_f32 v[20:21], v[36:37], v[20:21] op_sel_hi:[0,1]
	v_pk_mul_f32 v[26:27], v[36:37], v[26:27] op_sel_hi:[0,1]
	v_pk_mul_f32 v[28:29], v[36:37], v[28:29] op_sel_hi:[0,1]
	v_mul_f32_e32 v34, 0xbfb8aa3b, v34
	v_mul_f32_e32 v35, 0xbfb8aa3b, v35
	v_mul_f32_e32 v36, 0xbfb8aa3b, v37
	v_mul_f32_e32 v37, 0xbfb8aa3b, v38
	v_mul_f32_e32 v38, 0xbfb8aa3b, v39
	v_mul_f32_e32 v39, 0xbfb8aa3b, v40
	v_mul_f32_e32 v40, 0xbfb8aa3b, v41
	v_mul_f32_e32 v41, 0xbfb8aa3b, v42
	v_exp_f32_e32 v34, v34
	v_exp_f32_e32 v35, v35
	v_exp_f32_e32 v36, v36
	v_exp_f32_e32 v37, v37
	v_exp_f32_e32 v38, v38
	v_exp_f32_e32 v39, v39
	v_exp_f32_e32 v40, v40
	v_exp_f32_e32 v41, v41
	v_add_f32_e32 v34, 1.0, v34
	v_add_f32_e32 v35, 1.0, v35
	v_add_f32_e32 v36, 1.0, v36
	v_add_f32_e32 v37, 1.0, v37
	v_add_f32_e32 v38, 1.0, v38
	v_add_f32_e32 v39, 1.0, v39
	v_add_f32_e32 v40, 1.0, v40
	v_add_f32_e32 v41, 1.0, v41
	v_rcp_f32_e32 v34, v34
	v_rcp_f32_e32 v35, v35
	v_rcp_f32_e32 v36, v36
	v_rcp_f32_e32 v37, v37
	v_rcp_f32_e32 v38, v38
	v_rcp_f32_e32 v39, v39
	v_rcp_f32_e32 v40, v40
	v_rcp_f32_e32 v41, v41
	v_lshlrev_b32_e32 v18, 16, v30
	v_and_b32_e32 v19, 0xffff0000, v30
	v_lshlrev_b32_e32 v22, 16, v31
	v_and_b32_e32 v23, 0xffff0000, v31
	v_lshlrev_b32_e32 v30, 16, v32
	v_and_b32_e32 v31, 0xffff0000, v32
	v_lshlrev_b32_e32 v32, 16, v33
	v_and_b32_e32 v33, 0xffff0000, v33
	v_pk_fma_f32 v[16:17], v[80:81], v[16:17], v[84:85]
	v_pk_fma_f32 v[20:21], v[82:83], v[20:21], v[86:87]
	v_pk_fma_f32 v[26:27], v[64:65], v[26:27], v[68:69]
	v_pk_fma_f32 v[28:29], v[66:67], v[28:29], v[70:71]
	v_pk_fma_f32 v[16:17], v[34:35], v[18:19], v[16:17]
	v_pk_fma_f32 v[18:19], v[36:37], v[22:23], v[20:21]
	v_pk_fma_f32 v[20:21], v[38:39], v[30:31], v[26:27]
	v_pk_fma_f32 v[22:23], v[40:41], v[32:33], v[28:29]
	global_store_dwordx4 v[112:113], v[16:19], off offset:512
	s_nop 1
	v_cvt_pk_bf16_f32 v16, v16, v17
	v_cvt_pk_bf16_f32 v17, v18, v19
	global_store_dwordx4 v[112:113], v[20:23], off offset:528
	v_cvt_pk_bf16_f32 v18, v20, v21
	v_cvt_pk_bf16_f32 v19, v22, v23
	s_cbranch_vccnz .LBB0_1372
	s_nop 0
	v_lshl_add_u64 v[20:21], v[24:25], 1, s[90:91]
	global_store_dwordx4 v[20:21], v[16:19], off
.LBB0_1372:
	global_load_dwordx2 v[26:27], v[142:143], off
	s_nop 0
	v_lshl_add_u64 v[16:17], v[150:151], 0, v[104:105]
	v_lshlrev_b64 v[22:23], 1, v[16:17]
	v_lshl_add_u64 v[18:19], s[82:83], 0, v[22:23]
	global_load_dwordx4 v[18:21], v[18:19], off
	v_lshl_add_u64 v[22:23], s[92:93], 0, v[22:23]
	global_load_dwordx4 v[22:25], v[22:23], off
	s_and_b64 vcc, exec, s[40:41]
	s_waitcnt vmcnt(0) lgkmcnt(0)
	v_pk_mul_f32 v[26:27], v[26:27], s[0:1] op_sel_hi:[1,0]
	s_nop 0
	v_fma_f32 v28, -v26, v26, v27
	v_fma_f32 v33, -v92, v26, v8
	v_max_f32_e32 v8, 0, v28
	v_add_f32_e32 v28, 0x3727c5ac, v8
	v_rsq_f32_e32 v28, v28
	v_fma_f32 v34, -v93, v26, v9
	v_lshlrev_b32_e32 v8, 16, v18
	v_and_b32_e32 v9, 0xffff0000, v18
	v_fma_f32 v29, -v88, v26, v12
	v_fma_f32 v30, -v89, v26, v13
	v_fma_f32 v31, -v90, v26, v14
	v_fma_f32 v32, -v91, v26, v15
	v_fma_f32 v35, -v94, v26, v10
	v_fma_f32 v36, -v95, v26, v11
	v_lshlrev_b32_e32 v12, 16, v19
	v_and_b32_e32 v13, 0xffff0000, v19
	v_lshlrev_b32_e32 v18, 16, v20
	v_and_b32_e32 v19, 0xffff0000, v20
	v_lshlrev_b32_e32 v20, 16, v21
	v_and_b32_e32 v21, 0xffff0000, v21
	v_pk_add_f32 v[8:9], v[8:9], v[26:27] op_sel_hi:[1,0] neg_lo:[0,1] neg_hi:[0,1]
	v_pk_add_f32 v[12:13], v[12:13], v[26:27] op_sel_hi:[1,0] neg_lo:[0,1] neg_hi:[0,1]
	v_pk_add_f32 v[18:19], v[18:19], v[26:27] op_sel_hi:[1,0] neg_lo:[0,1] neg_hi:[0,1]
	v_pk_add_f32 v[20:21], v[20:21], v[26:27] op_sel_hi:[1,0] neg_lo:[0,1] neg_hi:[0,1]
	v_fma_f32 v26, v29, v28, v72
	v_fma_f32 v27, v30, v28, v73
	v_pk_mul_f32 v[8:9], v[28:29], v[8:9] op_sel_hi:[0,1]
	v_fma_f32 v29, v31, v28, v74
	v_fma_f32 v30, v32, v28, v75
	v_fma_f32 v31, v33, v28, v76
	v_fma_f32 v32, v34, v28, v77
	v_fma_f32 v33, v35, v28, v78
	v_fma_f32 v34, v36, v28, v79
	v_pk_mul_f32 v[12:13], v[28:29], v[12:13] op_sel_hi:[0,1]
	v_pk_mul_f32 v[18:19], v[28:29], v[18:19] op_sel_hi:[0,1]
	v_pk_mul_f32 v[20:21], v[28:29], v[20:21] op_sel_hi:[0,1]
	v_mul_f32_e32 v26, 0xbfb8aa3b, v26
	v_mul_f32_e32 v27, 0xbfb8aa3b, v27
	v_mul_f32_e32 v28, 0xbfb8aa3b, v29
	v_mul_f32_e32 v29, 0xbfb8aa3b, v30
	v_mul_f32_e32 v30, 0xbfb8aa3b, v31
; __device__ __forceinline__ unsigned cvt_pk_bf16(float lo, float hi) { unsigned r; asm volatile("v_cvt_pk_bf16_f32 %0, %1, %2" : "=v"(r) : "v"(lo), "v"(hi)); return r; }
; __device__ __forceinline__ float bf_lo(unsigned w) { return __uint_as_float(w << 16); }
; __device__ __forceinline__ float bf_hi(unsigned w) { return __uint_as_float(w & 0xffff0000u); }
;     __device__ __forceinline__ void operator()(const f32x4 (&acc)[2][2][4][2], const Unit& u, int wr, int wc, int fr, int fq) const {
;     ...
;                 for (int m = 0; m < 4; ++m) { const int row = row0 + ai * HALF + m * 16; const size_t o2 = (size_t)row * ldc + col;
;                     const float s1 = ST[2 * row], s2 = ST[2 * row + 1], mu = s1 * (1.f / 2048.f), rstd = __builtin_amdgcn_rsqf(fmaxf(s2 * (1.f / 2048.f) - mu * mu, 0.f) + 1e-5f);
;                     const u32x4 zw = *(const u32x4*)(Zb + o2), pw = *(const u32x4*)(PE + o2); u32x4 xw;
; #pragma unroll
;                     for (int n = 0; n < 2; ++n) { const unsigned za = n ? zw.z : zw.x, zb2 = n ? zw.w : zw.y, pa = n ? pw.z : pw.x, pb = n ? pw.w : pw.y;
;                         const float zv[4] = {bf_lo(za), bf_hi(za), bf_lo(zb2), bf_hi(zb2)}, pv[4] = {bf_lo(pa), bf_hi(pa), bf_lo(pb), bf_hi(pb)}; const f32x4 a = acc[ai][bj][m][n]; f32x4 o;
; #pragma unroll
;                         for (int e = 0; e < 4; ++e) { const float sv = rstd * (a[e] - mu * c1[n][e]) + c2[n][e]; const float xl = (zv[e] - mu) * rstd * lg[n][e] + lb[n][e]; o[e] = xl + pv[e] * __builtin_amdgcn_rcpf(1.f + __expf(-sv)); }
;                         *(f32x4*)(OUTF + o2 + 4 * n) = o; if (n == 0) { xw.x = cvt_pk_bf16(o[0], o[1]); xw.y = cvt_pk_bf16(o[2], o[3]); } else { xw.z = cvt_pk_bf16(o[0], o[1]); xw.w = cvt_pk_bf16(o[2], o[3]); } }
;                     if (XB) *(u32x4*)(XB + o2) = xw; }
	v_mul_f32_e32 v31, 0xbfb8aa3b, v32
	v_mul_f32_e32 v32, 0xbfb8aa3b, v33
	v_mul_f32_e32 v33, 0xbfb8aa3b, v34
	v_exp_f32_e32 v26, v26
	v_exp_f32_e32 v27, v27
	v_exp_f32_e32 v28, v28
	v_exp_f32_e32 v29, v29
	v_exp_f32_e32 v30, v30
	v_exp_f32_e32 v31, v31
	v_exp_f32_e32 v32, v32
	v_exp_f32_e32 v33, v33
	v_add_f32_e32 v26, 1.0, v26
	v_add_f32_e32 v27, 1.0, v27
	v_add_f32_e32 v28, 1.0, v28
	v_add_f32_e32 v29, 1.0, v29
	v_add_f32_e32 v30, 1.0, v30
	v_add_f32_e32 v31, 1.0, v31
	v_add_f32_e32 v32, 1.0, v32
	v_add_f32_e32 v33, 1.0, v33
	v_rcp_f32_e32 v26, v26
	v_rcp_f32_e32 v27, v27
	v_rcp_f32_e32 v28, v28
	v_rcp_f32_e32 v29, v29
	v_rcp_f32_e32 v30, v30
	v_rcp_f32_e32 v31, v31
	v_rcp_f32_e32 v32, v32
	v_rcp_f32_e32 v33, v33
	v_lshlrev_b32_e32 v10, 16, v22
	v_and_b32_e32 v11, 0xffff0000, v22
	v_lshlrev_b32_e32 v14, 16, v23
	v_and_b32_e32 v15, 0xffff0000, v23
	v_lshlrev_b32_e32 v22, 16, v24
	v_and_b32_e32 v23, 0xffff0000, v24
	v_lshlrev_b32_e32 v24, 16, v25
	v_and_b32_e32 v25, 0xffff0000, v25
	v_pk_fma_f32 v[8:9], v[80:81], v[8:9], v[84:85]
	v_pk_fma_f32 v[12:13], v[82:83], v[12:13], v[86:87]
	v_pk_fma_f32 v[18:19], v[64:65], v[18:19], v[68:69]
	v_pk_fma_f32 v[20:21], v[66:67], v[20:21], v[70:71]
	v_pk_fma_f32 v[8:9], v[26:27], v[10:11], v[8:9]
	v_pk_fma_f32 v[10:11], v[28:29], v[14:15], v[12:13]
	v_pk_fma_f32 v[12:13], v[30:31], v[22:23], v[18:19]
	v_pk_fma_f32 v[14:15], v[32:33], v[24:25], v[20:21]
	global_store_dwordx4 v[114:115], v[8:11], off offset:512
	s_nop 1
	v_cvt_pk_bf16_f32 v8, v8, v9
	v_cvt_pk_bf16_f32 v9, v10, v11
	global_store_dwordx4 v[114:115], v[12:15], off offset:528
	v_cvt_pk_bf16_f32 v10, v12, v13
	v_cvt_pk_bf16_f32 v11, v14, v15
	s_cbranch_vccnz .LBB0_1374
	s_nop 0
	v_lshl_add_u64 v[12:13], v[16:17], 1, s[90:91]
	global_store_dwordx4 v[12:13], v[8:11], off
.LBB0_1374:
	global_load_dwordx2 v[18:19], v[158:159], off
	s_nop 0
	v_lshl_add_u64 v[8:9], v[162:163], 0, v[104:105]
	v_lshlrev_b64 v[14:15], 1, v[8:9]
	v_lshl_add_u64 v[10:11], s[82:83], 0, v[14:15]
	global_load_dwordx4 v[10:13], v[10:11], off
	v_lshl_add_u64 v[14:15], s[92:93], 0, v[14:15]
	global_load_dwordx4 v[14:17], v[14:15], off
	s_and_b64 vcc, exec, s[40:41]
	s_waitcnt vmcnt(0) lgkmcnt(0)
	v_pk_mul_f32 v[18:19], v[18:19], s[0:1] op_sel_hi:[1,0]
	s_nop 0
	v_fma_f32 v20, -v18, v18, v19
	v_fma_f32 v25, -v92, v18, v0
	v_max_f32_e32 v0, 0, v20
	v_add_f32_e32 v20, 0x3727c5ac, v0
	v_rsq_f32_e32 v20, v20
	v_fma_f32 v26, -v93, v18, v1
	v_lshlrev_b32_e32 v0, 16, v10
	v_and_b32_e32 v1, 0xffff0000, v10
	v_fma_f32 v21, -v88, v18, v4
	v_fma_f32 v22, -v89, v18, v5
	v_fma_f32 v23, -v90, v18, v6
	v_fma_f32 v24, -v91, v18, v7
	v_fma_f32 v27, -v94, v18, v2
	v_fma_f32 v28, -v95, v18, v3
	v_lshlrev_b32_e32 v4, 16, v11
	v_and_b32_e32 v5, 0xffff0000, v11
	v_lshlrev_b32_e32 v10, 16, v12
	v_and_b32_e32 v11, 0xffff0000, v12
	v_lshlrev_b32_e32 v12, 16, v13
	v_and_b32_e32 v13, 0xffff0000, v13
	v_pk_add_f32 v[0:1], v[0:1], v[18:19] op_sel_hi:[1,0] neg_lo:[0,1] neg_hi:[0,1]
	v_pk_add_f32 v[4:5], v[4:5], v[18:19] op_sel_hi:[1,0] neg_lo:[0,1] neg_hi:[0,1]
	v_pk_add_f32 v[10:11], v[10:11], v[18:19] op_sel_hi:[1,0] neg_lo:[0,1] neg_hi:[0,1]
	v_pk_add_f32 v[12:13], v[12:13], v[18:19] op_sel_hi:[1,0] neg_lo:[0,1] neg_hi:[0,1]
	v_fma_f32 v18, v21, v20, v72
	v_fma_f32 v19, v22, v20, v73
	v_pk_mul_f32 v[0:1], v[20:21], v[0:1] op_sel_hi:[0,1]
	v_fma_f32 v21, v23, v20, v74
	v_fmac_f32_e32 v75, v24, v20
	v_fma_f32 v22, v25, v20, v76
	v_fma_f32 v23, v26, v20, v77
	v_fma_f32 v24, v27, v20, v78
	v_fmac_f32_e32 v79, v28, v20
	v_pk_mul_f32 v[4:5], v[20:21], v[4:5] op_sel_hi:[0,1]
	v_pk_mul_f32 v[10:11], v[20:21], v[10:11] op_sel_hi:[0,1]
	v_pk_mul_f32 v[12:13], v[20:21], v[12:13] op_sel_hi:[0,1]
	v_mul_f32_e32 v18, 0xbfb8aa3b, v18
	v_mul_f32_e32 v19, 0xbfb8aa3b, v19
	v_mul_f32_e32 v20, 0xbfb8aa3b, v21
	v_mul_f32_e32 v21, 0xbfb8aa3b, v75
	v_mul_f32_e32 v22, 0xbfb8aa3b, v22
	v_mul_f32_e32 v23, 0xbfb8aa3b, v23
	v_mul_f32_e32 v24, 0xbfb8aa3b, v24
	v_mul_f32_e32 v25, 0xbfb8aa3b, v79
	v_exp_f32_e32 v18, v18
	v_exp_f32_e32 v19, v19
	v_exp_f32_e32 v20, v20
	v_exp_f32_e32 v21, v21
	v_exp_f32_e32 v22, v22
	v_exp_f32_e32 v23, v23
	v_exp_f32_e32 v24, v24
	v_exp_f32_e32 v25, v25
	v_add_f32_e32 v18, 1.0, v18
	v_add_f32_e32 v19, 1.0, v19
	v_add_f32_e32 v20, 1.0, v20
	v_add_f32_e32 v21, 1.0, v21
	v_add_f32_e32 v22, 1.0, v22
	v_add_f32_e32 v23, 1.0, v23
	v_add_f32_e32 v24, 1.0, v24
	v_add_f32_e32 v25, 1.0, v25
	v_rcp_f32_e32 v18, v18
	v_rcp_f32_e32 v19, v19
	v_rcp_f32_e32 v20, v20
	v_rcp_f32_e32 v21, v21
	v_rcp_f32_e32 v22, v22
	v_rcp_f32_e32 v23, v23
	v_rcp_f32_e32 v24, v24
	v_rcp_f32_e32 v25, v25
	v_lshlrev_b32_e32 v2, 16, v14
	v_and_b32_e32 v3, 0xffff0000, v14
	v_lshlrev_b32_e32 v6, 16, v15
	v_and_b32_e32 v7, 0xffff0000, v15
	v_lshlrev_b32_e32 v14, 16, v16
	v_and_b32_e32 v15, 0xffff0000, v16
	v_lshlrev_b32_e32 v16, 16, v17
	v_and_b32_e32 v17, 0xffff0000, v17
	v_pk_fma_f32 v[0:1], v[80:81], v[0:1], v[84:85]
	v_pk_fma_f32 v[4:5], v[82:83], v[4:5], v[86:87]
	v_pk_fma_f32 v[10:11], v[64:65], v[10:11], v[68:69]
	v_pk_fma_f32 v[12:13], v[66:67], v[12:13], v[70:71]
	v_pk_fma_f32 v[0:1], v[18:19], v[2:3], v[0:1]
	v_pk_fma_f32 v[2:3], v[20:21], v[6:7], v[4:5]
	v_pk_fma_f32 v[4:5], v[22:23], v[14:15], v[10:11]
	v_pk_fma_f32 v[6:7], v[24:25], v[16:17], v[12:13]
	global_store_dwordx4 v[120:121], v[0:3], off offset:512
	s_nop 1
	v_cvt_pk_bf16_f32 v0, v0, v1
	v_cvt_pk_bf16_f32 v1, v2, v3
	global_store_dwordx4 v[120:121], v[4:7], off offset:528
	v_cvt_pk_bf16_f32 v2, v4, v5
	v_cvt_pk_bf16_f32 v3, v6, v7
	s_cbranch_vccnz .LBB0_1376
	s_nop 0
	v_lshl_add_u64 v[4:5], v[8:9], 1, s[90:91]
	global_store_dwordx4 v[4:5], v[0:3], off

; __device__ __forceinline__ void p0_transpose_item(const float* W, int K, int N, bf16* WT, float* scr, int item, int lane, const float* scale, const float* cb, float* c1, float* c2) {
;     const int nblk = N / 64, kb = item / nblk, nb = item % nblk, k0 = 64 * kb, n0 = 64 * nb;
;     const int lr = lane >> 4, lc = (lane & 15) * 4;
;     f32x4 v[16];
; #pragma unroll
;     for (int i = 0; i < 16; ++i) v[i] = *(const f32x4*)(W + (size_t)(k0 + 4 * i + lr) * N + n0 + lc);
; #pragma unroll
;     for (int i = 0; i < 16; ++i) { const int kk = 4 * i + lr; f32x4 w = v[i]; if (scale) w = w * scale[k0 + kk]; float* d = scr + kk * 65 + lc; d[0] = w[0]; d[1] = w[1]; d[2] = w[2]; d[3] = w[3]; }
.LBB0_1411:
	s_mul_hi_i32 s0, s24, 0xae4c415d
	s_add_i32 s0, s0, s24
	s_lshr_b32 s1, s0, 31
	s_ashr_i32 s0, s0, 12
	s_add_i32 s0, s0, s1
	s_mul_i32 s1, s0, 0x1780
	s_sub_i32 s44, s24, s1
	s_cmpk_gt_i32 s44, 0xeff
	s_mov_b64 s[2:3], -1
	s_cbranch_scc0 .LBB0_1447
	s_cmpk_gt_u32 s44, 0x12ff
	s_cbranch_scc0 .LBB0_1444
	s_ashr_i32 s1, s0, 31
	s_cmpk_gt_u32 s44, 0x16ff
	s_cbranch_scc0 .LBB0_1415
	v_readlane_b32 s48, v253, 18
	s_lshl_b64 s[2:3], s[0:1], 21
	v_readlane_b32 s62, v253, 32
	v_readlane_b32 s63, v253, 33
	s_add_u32 s4, s62, s2
	s_addc_u32 s5, s63, s3
	s_lshl_b64 s[2:3], s[0:1], 20
	s_add_u32 s6, s38, s2
	s_addc_u32 s3, s39, s3
	s_lshl_b32 s2, s44, 1
	s_and_b32 s7, s2, 0x1c0
	s_lshl_b32 s2, s44, 6
	s_and_b32 s2, s2, 0x7c0
	s_lshl_b32 s8, s2, 2
	s_add_u32 s4, s4, s8
	v_or_b32_e32 v2, s7, v69
	s_addc_u32 s5, s5, 0
	v_lshlrev_b32_e32 v168, 2, v68
	v_lshl_add_u64 v[0:1], s[4:5], 0, v[168:169]
	v_lshlrev_b32_e32 v168, 13, v2
	v_lshl_add_u64 v[60:61], v[0:1], 0, v[168:169]
	v_add_co_u32_e32 v4, vcc, s90, v60
	s_mov_b32 s4, 0x20000
	s_nop 0
	v_addc_co_u32_e32 v5, vcc, 0, v61, vcc
	v_add_co_u32_e32 v8, vcc, s88, v60
	global_load_dwordx4 v[0:3], v[60:61], off
	s_nop 0
	global_load_dwordx4 v[4:7], v[4:5], off
	v_addc_co_u32_e32 v9, vcc, 0, v61, vcc
	v_add_co_u32_e32 v12, vcc, s85, v60
	v_lshlrev_b32_e32 v168, 1, v70
	s_nop 0
	v_addc_co_u32_e32 v13, vcc, 0, v61, vcc
	global_load_dwordx4 v[8:11], v[8:9], off
	s_nop 0
	global_load_dwordx4 v[12:15], v[12:13], off
	v_add_co_u32_e32 v16, vcc, s4, v60
	s_mov_b32 s4, 0x28000
	s_nop 0
	v_addc_co_u32_e32 v17, vcc, 0, v61, vcc
	v_add_co_u32_e32 v20, vcc, s4, v60
	s_mov_b32 s4, 0x30000
	s_nop 0
	v_addc_co_u32_e32 v21, vcc, 0, v61, vcc
	global_load_dwordx4 v[16:19], v[16:17], off
	s_nop 0
	global_load_dwordx4 v[20:23], v[20:21], off
	v_add_co_u32_e32 v24, vcc, s4, v60
	s_mov_b32 s4, 0x38000
	s_nop 0
	v_addc_co_u32_e32 v25, vcc, 0, v61, vcc
	v_add_co_u32_e32 v28, vcc, s4, v60
	s_mov_b32 s4, 0x40000
	s_nop 0
	v_addc_co_u32_e32 v29, vcc, 0, v61, vcc
	global_load_dwordx4 v[24:27], v[24:25], off
	s_nop 0
	global_load_dwordx4 v[28:31], v[28:29], off
	v_add_co_u32_e32 v32, vcc, s4, v60
	s_mov_b32 s4, 0x48000
	s_nop 0
	v_addc_co_u32_e32 v33, vcc, 0, v61, vcc
	v_add_co_u32_e32 v36, vcc, s4, v60
	s_mov_b32 s4, 0x50000
	s_nop 0
	v_addc_co_u32_e32 v37, vcc, 0, v61, vcc
	global_load_dwordx4 v[32:35], v[32:33], off
	s_nop 0
	global_load_dwordx4 v[36:39], v[36:37], off
	v_add_co_u32_e32 v40, vcc, s4, v60
	s_mov_b32 s4, 0x58000
	s_nop 0
	v_addc_co_u32_e32 v41, vcc, 0, v61, vcc
	v_add_co_u32_e32 v44, vcc, s4, v60
	s_mov_b32 s4, 0x60000
	s_nop 0
	v_addc_co_u32_e32 v45, vcc, 0, v61, vcc
	global_load_dwordx4 v[40:43], v[40:41], off
	s_nop 0
	global_load_dwordx4 v[44:47], v[44:45], off
	v_add_co_u32_e32 v48, vcc, s4, v60
	s_mov_b32 s4, 0x68000
	s_nop 0
	v_addc_co_u32_e32 v49, vcc, 0, v61, vcc
	global_load_dwordx4 v[48:51], v[48:49], off
	v_add_co_u32_e32 v52, vcc, s4, v60
	s_mov_b32 s4, 0x70000
	s_nop 0
	v_addc_co_u32_e32 v53, vcc, 0, v61, vcc
	global_load_dwordx4 v[52:55], v[52:53], off
	v_add_co_u32_e32 v56, vcc, s4, v60
	s_mov_b32 s4, 0x78000
	s_nop 0
	v_addc_co_u32_e32 v57, vcc, 0, v61, vcc
	global_load_dwordx4 v[56:59], v[56:57], off
	v_add_co_u32_e32 v60, vcc, s4, v60
	s_lshl_b32 s4, s7, 1
	s_nop 0
	v_addc_co_u32_e32 v61, vcc, 0, v61, vcc
	global_load_dwordx4 v[60:63], v[60:61], off
	s_waitcnt vmcnt(0)
	ds_write2_b32 v71, v0, v1 offset1:1
	ds_write2_b32 v71, v2, v3 offset0:2 offset1:3
	v_add_u32_e32 v0, 0x410, v71
	s_waitcnt vmcnt(14)
	ds_write2_b32 v0, v4, v5 offset1:1
	v_add_u32_e32 v0, 0x418, v71
	ds_write2_b32 v0, v6, v7 offset1:1
	v_add_u32_e32 v0, 0x820, v71
	s_add_u32 s4, s6, s4
	s_addc_u32 s5, s3, 0
	s_waitcnt vmcnt(13)
	ds_write2_b32 v0, v8, v9 offset1:1
	v_add_u32_e32 v0, 0x828, v71
	ds_write2_b32 v0, v10, v11 offset1:1
	v_add_u32_e32 v0, 0xc30, v71
	s_waitcnt vmcnt(12)
	ds_write2_b32 v0, v12, v13 offset1:1
	v_add_u32_e32 v0, 0xc38, v71
	ds_write2_b32 v0, v14, v15 offset1:1
	v_add_u32_e32 v0, 0x1040, v71
	v_lshl_add_u64 v[4:5], s[4:5], 0, v[168:169]
	v_readlane_b32 s49, v253, 19
	v_readlane_b32 s50, v253, 20
	s_waitcnt vmcnt(11)
	ds_write2_b32 v0, v16, v17 offset1:1
	v_add_u32_e32 v0, 0x1048, v71
	ds_write2_b32 v0, v18, v19 offset1:1
	v_add_u32_e32 v0, 0x1450, v71
	s_waitcnt vmcnt(10)
	ds_write2_b32 v0, v20, v21 offset1:1
	v_add_u32_e32 v0, 0x1458, v71
	ds_write2_b32 v0, v22, v23 offset1:1
	v_add_u32_e32 v0, 0x1860, v71
	v_readlane_b32 s51, v253, 21
	v_readlane_b32 s52, v253, 22
	v_readlane_b32 s53, v253, 23
	s_waitcnt vmcnt(9)
	ds_write2_b32 v0, v24, v25 offset1:1
	v_add_u32_e32 v0, 0x1868, v71
	ds_write2_b32 v0, v26, v27 offset1:1
	v_add_u32_e32 v0, 0x1c70, v71
	s_waitcnt vmcnt(8)
	ds_write2_b32 v0, v28, v29 offset1:1
	v_add_u32_e32 v0, 0x1c78, v71
	ds_write2_b32 v0, v30, v31 offset1:1
	v_add_u32_e32 v0, 0x2080, v71
	v_readlane_b32 s54, v253, 24
	v_readlane_b32 s55, v253, 25
	v_readlane_b32 s56, v253, 26
	s_waitcnt vmcnt(7)
	ds_write2_b32 v0, v32, v33 offset1:1
	v_add_u32_e32 v0, 0x2088, v71
	ds_write2_b32 v0, v34, v35 offset1:1
	v_add_u32_e32 v0, 0x2490, v71
	s_waitcnt vmcnt(6)
	ds_write2_b32 v0, v36, v37 offset1:1
	v_add_u32_e32 v0, 0x2498, v71
	ds_write2_b32 v0, v38, v39 offset1:1
	v_add_u32_e32 v0, 0x28a0, v71
	v_readlane_b32 s57, v253, 27
	v_readlane_b32 s58, v253, 28
	v_readlane_b32 s59, v253, 29
	s_waitcnt vmcnt(5)
; #define LDS_WAIT() asm volatile("s_waitcnt lgkmcnt(0)" ::: "memory")
; __device__ __forceinline__ unsigned pk2(float lo, float hi) { unsigned r; asm("v_cvt_pk_bf16_f32 %0, %1, %2" : "=v"(r) : "v"(lo), "v"(hi)); return r; }
; __device__ __forceinline__ void p0_transpose_item(const float* W, int K, int N, bf16* WT, float* scr, int item, int lane, const float* scale, const float* cb, float* c1, float* c2) {
;     ...
;     LDS_WAIT(); asm volatile("" ::: "memory");
;     const int c = lane & 7;
; #pragma unroll
;     for (int j = 0; j < 8; ++j) { const int n = (lane >> 3) + 8 * j; const float* sp = scr + (8 * c) * 65 + n;
;         v4u o; o.x = pk2(sp[0 * 65], sp[1 * 65]); o.y = pk2(sp[2 * 65], sp[3 * 65]); o.z = pk2(sp[4 * 65], sp[5 * 65]); o.w = pk2(sp[6 * 65], sp[7 * 65]);
;         *(v4u*)(WT + (size_t)(n0 + n) * K + k0 + 8 * c) = o; }
	ds_write2_b32 v0, v40, v41 offset1:1
	v_add_u32_e32 v0, 0x28a8, v71
	ds_write2_b32 v0, v42, v43 offset1:1
	v_add_u32_e32 v0, 0x2cb0, v71
	s_waitcnt vmcnt(4)
	ds_write2_b32 v0, v44, v45 offset1:1
	v_add_u32_e32 v0, 0x2cb8, v71
	ds_write2_b32 v0, v46, v47 offset1:1
	v_add_u32_e32 v0, 0x30c0, v71
	s_waitcnt vmcnt(3)
	ds_write2_b32 v0, v48, v49 offset1:1
	v_add_u32_e32 v0, 0x30c8, v71
	ds_write2_b32 v0, v50, v51 offset1:1
	v_add_u32_e32 v0, 0x34d0, v71
	v_readlane_b32 s60, v253, 30
	s_waitcnt vmcnt(2)
	ds_write2_b32 v0, v52, v53 offset1:1
	v_add_u32_e32 v0, 0x34d8, v71
	ds_write2_b32 v0, v54, v55 offset1:1
	v_add_u32_e32 v0, 0x38e0, v71
	v_readlane_b32 s61, v253, 31
	s_waitcnt vmcnt(1)
	ds_write2_b32 v0, v56, v57 offset1:1
	v_add_u32_e32 v0, 0x38e8, v71
	ds_write2_b32 v0, v58, v59 offset1:1
	v_add_u32_e32 v0, 0x3cf0, v71
	s_waitcnt vmcnt(0)
	ds_write2_b32 v0, v60, v61 offset1:1
	v_add_u32_e32 v0, 0x3cf8, v71
	ds_write2_b32 v0, v62, v63 offset1:1
	s_waitcnt lgkmcnt(0)
	ds_read_b32 v0, v81
	ds_read_b32 v1, v81 offset:260
	ds_read_b32 v2, v81 offset:520
	ds_read_b32 v3, v81 offset:780
	ds_read_b32 v6, v81 offset:1040
	ds_read_b32 v7, v81 offset:1300
	ds_read_b32 v8, v81 offset:1560
	ds_read_b32 v9, v81 offset:1820
	s_waitcnt lgkmcnt(6)
	v_cvt_pk_bf16_f32 v0, v0, v1
	s_waitcnt lgkmcnt(4)
	v_cvt_pk_bf16_f32 v1, v2, v3
	s_waitcnt lgkmcnt(2)
	v_cvt_pk_bf16_f32 v2, v6, v7
	v_or_b32_e32 v6, s2, v80
	v_lshlrev_b32_e32 v168, 9, v6
	v_lshl_add_u64 v[6:7], v[4:5], 0, v[168:169]
	s_waitcnt lgkmcnt(0)
	v_cvt_pk_bf16_f32 v3, v8, v9
	global_store_dwordx4 v[6:7], v[0:3], off
	ds_read_b32 v0, v81 offset:32
	ds_read_b32 v1, v81 offset:292
	ds_read_b32 v2, v81 offset:552
	ds_read_b32 v3, v81 offset:812
	ds_read_b32 v6, v81 offset:1072
	ds_read_b32 v7, v81 offset:1332
	ds_read_b32 v8, v81 offset:1592
	ds_read_b32 v9, v81 offset:1852
	s_waitcnt lgkmcnt(0)
	v_cvt_pk_bf16_f32 v0, v0, v1
	v_cvt_pk_bf16_f32 v1, v2, v3
	v_cvt_pk_bf16_f32 v2, v6, v7
	v_or_b32_e32 v6, s2, v82
	v_lshlrev_b32_e32 v168, 9, v6
	v_lshl_add_u64 v[6:7], v[4:5], 0, v[168:169]
	v_cvt_pk_bf16_f32 v3, v8, v9
	global_store_dwordx4 v[6:7], v[0:3], off
	ds_read_b32 v0, v81 offset:64
	ds_read_b32 v1, v81 offset:324
	ds_read_b32 v2, v81 offset:584
	ds_read_b32 v3, v81 offset:844
	ds_read_b32 v6, v81 offset:1104
	ds_read_b32 v7, v81 offset:1364
	ds_read_b32 v8, v81 offset:1624
	ds_read_b32 v9, v81 offset:1884
	s_waitcnt lgkmcnt(0)
	v_cvt_pk_bf16_f32 v0, v0, v1
	v_cvt_pk_bf16_f32 v1, v2, v3
	v_cvt_pk_bf16_f32 v2, v6, v7
	v_or_b32_e32 v6, s2, v83
	v_lshlrev_b32_e32 v168, 9, v6
	v_lshl_add_u64 v[6:7], v[4:5], 0, v[168:169]
	v_cvt_pk_bf16_f32 v3, v8, v9
	global_store_dwordx4 v[6:7], v[0:3], off
	ds_read_b32 v0, v81 offset:96
	ds_read_b32 v1, v81 offset:356
	ds_read_b32 v2, v81 offset:616
	ds_read_b32 v3, v81 offset:876
	ds_read_b32 v6, v81 offset:1136
	ds_read_b32 v7, v81 offset:1396
	ds_read_b32 v8, v81 offset:1656
	ds_read_b32 v9, v81 offset:1916
	s_waitcnt lgkmcnt(0)
	v_cvt_pk_bf16_f32 v0, v0, v1
	v_cvt_pk_bf16_f32 v1, v2, v3
	v_cvt_pk_bf16_f32 v2, v6, v7
	v_or_b32_e32 v6, s2, v84
	v_lshlrev_b32_e32 v168, 9, v6
	v_lshl_add_u64 v[6:7], v[4:5], 0, v[168:169]
	v_cvt_pk_bf16_f32 v3, v8, v9
	global_store_dwordx4 v[6:7], v[0:3], off
	ds_read_b32 v0, v81 offset:128
	ds_read_b32 v1, v81 offset:388
	ds_read_b32 v2, v81 offset:648
	ds_read_b32 v3, v81 offset:908
	ds_read_b32 v6, v81 offset:1168
	ds_read_b32 v7, v81 offset:1428
	ds_read_b32 v8, v81 offset:1688
	ds_read_b32 v9, v81 offset:1948
	s_waitcnt lgkmcnt(0)
	v_cvt_pk_bf16_f32 v0, v0, v1
	v_cvt_pk_bf16_f32 v1, v2, v3
	v_cvt_pk_bf16_f32 v2, v6, v7
	v_or_b32_e32 v6, s2, v85
	v_lshlrev_b32_e32 v168, 9, v6
	v_lshl_add_u64 v[6:7], v[4:5], 0, v[168:169]
	v_cvt_pk_bf16_f32 v3, v8, v9
	global_store_dwordx4 v[6:7], v[0:3], off
	ds_read_b32 v0, v81 offset:160
	ds_read_b32 v1, v81 offset:420
	ds_read_b32 v2, v81 offset:680
	ds_read_b32 v3, v81 offset:940
	ds_read_b32 v6, v81 offset:1200
	ds_read_b32 v7, v81 offset:1460
	ds_read_b32 v8, v81 offset:1720
	ds_read_b32 v9, v81 offset:1980
	s_waitcnt lgkmcnt(0)
	v_cvt_pk_bf16_f32 v0, v0, v1
	v_cvt_pk_bf16_f32 v1, v2, v3
	v_cvt_pk_bf16_f32 v2, v6, v7
	v_or_b32_e32 v6, s2, v86
	v_lshlrev_b32_e32 v168, 9, v6
	v_lshl_add_u64 v[6:7], v[4:5], 0, v[168:169]
	v_cvt_pk_bf16_f32 v3, v8, v9
	global_store_dwordx4 v[6:7], v[0:3], off
	ds_read_b32 v0, v81 offset:192
	ds_read_b32 v1, v81 offset:452
	ds_read_b32 v2, v81 offset:712
	ds_read_b32 v3, v81 offset:972
	ds_read_b32 v6, v81 offset:1232
	ds_read_b32 v7, v81 offset:1492
	ds_read_b32 v8, v81 offset:1752
	ds_read_b32 v9, v81 offset:2012
	s_waitcnt lgkmcnt(0)
	v_cvt_pk_bf16_f32 v0, v0, v1
	v_cvt_pk_bf16_f32 v1, v2, v3
	v_cvt_pk_bf16_f32 v2, v6, v7
	v_or_b32_e32 v6, s2, v87
	v_lshlrev_b32_e32 v168, 9, v6
	v_lshl_add_u64 v[6:7], v[4:5], 0, v[168:169]
	v_cvt_pk_bf16_f32 v3, v8, v9
	global_store_dwordx4 v[6:7], v[0:3], off
	ds_read_b32 v0, v81 offset:224
	ds_read_b32 v1, v81 offset:484
	ds_read_b32 v2, v81 offset:744
	ds_read_b32 v3, v81 offset:1004
	ds_read_b32 v6, v81 offset:1264
	ds_read_b32 v7, v81 offset:1524
	ds_read_b32 v8, v81 offset:1784
	ds_read_b32 v9, v81 offset:2044
	s_waitcnt lgkmcnt(0)
	v_cvt_pk_bf16_f32 v0, v0, v1
	v_cvt_pk_bf16_f32 v1, v2, v3
	v_cvt_pk_bf16_f32 v2, v6, v7
	v_or_b32_e32 v6, s2, v88
	v_lshlrev_b32_e32 v168, 9, v6
	v_lshl_add_u64 v[4:5], v[4:5], 0, v[168:169]
	v_cvt_pk_bf16_f32 v3, v8, v9
	global_store_dwordx4 v[4:5], v[0:3], off
	s_waitcnt lgkmcnt(0)
	s_mov_b64 s[2:3], 0

; #define LDS_WAIT() asm volatile("s_waitcnt lgkmcnt(0)" ::: "memory")
; __device__ __forceinline__ unsigned pk2(float lo, float hi) { unsigned r; asm("v_cvt_pk_bf16_f32 %0, %1, %2" : "=v"(r) : "v"(lo), "v"(hi)); return r; }
; __device__ __forceinline__ unsigned f2bf(float f) { return pk2(f, 0.f) & 0xffffu; }
; __device__ __forceinline__ void p0_transpose_item(const float* W, int K, int N, bf16* WT, float* scr, int item, int lane, const float* scale, const float* cb, float* c1, float* c2) {
;     ...
;     LDS_WAIT(); asm volatile("" ::: "memory");
;     const int c = lane & 7;
; #pragma unroll
;     for (int j = 0; j < 8; ++j) { const int n = (lane >> 3) + 8 * j; const float* sp = scr + (8 * c) * 65 + n;
;         v4u o; o.x = pk2(sp[0 * 65], sp[1 * 65]); o.y = pk2(sp[2 * 65], sp[3 * 65]); o.z = pk2(sp[4 * 65], sp[5 * 65]); o.w = pk2(sp[6 * 65], sp[7 * 65]);
;         *(v4u*)(WT + (size_t)(n0 + n) * K + k0 + 8 * c) = o; }
;     if (c1) { float a1 = 0.f, a2 = 0.f;
;         for (int kk = 0; kk < 64; ++kk) { a1 += __uint_as_float(f2bf(scr[kk * 65 + lane]) << 16); a2 += cb[k0 + kk] * W[(size_t)(k0 + kk) * N + n0 + lane]; }
;         atomicAdd(c1 + n0 + lane, a1); atomicAdd(c2 + n0 + lane, a2); }
.LBB0_1440:
	v_add_u32_e32 v0, 0x34d0, v90
	ds_write2_b32 v0, v14, v15 offset1:1
	v_add_u32_e32 v0, 0x34d8, v90
	ds_write2_b32 v0, v12, v13 offset1:1
	v_add_u32_e32 v0, 0x38e0, v90
	ds_write2_b32 v0, v8, v9 offset1:1
	v_add_u32_e32 v0, 0x38e8, v90
	ds_write2_b32 v0, v10, v11 offset1:1
	s_waitcnt lgkmcnt(0)
	ds_read_b32 v2, v81
	ds_read_b32 v3, v81 offset:260
	s_lshl_b64 s[4:5], s[0:1], 22
	s_waitcnt lgkmcnt(0)
	v_cvt_pk_bf16_f32 v2, v2, v3
	ds_read_b32 v3, v81 offset:520
	ds_read_b32 v4, v81 offset:780
	s_waitcnt lgkmcnt(0)
	v_cvt_pk_bf16_f32 v3, v3, v4
	ds_read_b32 v4, v81 offset:1040
	ds_read_b32 v5, v81 offset:1300
	s_waitcnt lgkmcnt(0)
	v_cvt_pk_bf16_f32 v4, v4, v5
	ds_read_b32 v5, v81 offset:1560
	ds_read_b32 v6, v81 offset:1820
	s_lshl_b64 s[4:5], s[4:5], 1
	s_add_u32 s1, s36, s4
	s_addc_u32 s5, s37, s5
	s_lshl_b32 s4, s47, 1
	s_add_u32 s4, s1, s4
	s_addc_u32 s5, s5, 0
	v_lshlrev_b32_e32 v168, 1, v70
	s_waitcnt lgkmcnt(0)
	v_cvt_pk_bf16_f32 v5, v5, v6
	v_or_b32_e32 v6, s48, v80
	v_lshl_add_u64 v[0:1], s[4:5], 0, v[168:169]
	v_lshlrev_b32_e32 v168, 12, v6
	v_lshl_add_u64 v[6:7], v[0:1], 0, v[168:169]
	global_store_dwordx4 v[6:7], v[2:5], off
	ds_read_b32 v2, v81 offset:32
	ds_read_b32 v3, v81 offset:292
	s_waitcnt lgkmcnt(0)
	v_cvt_pk_bf16_f32 v2, v2, v3
	ds_read_b32 v3, v81 offset:552
	ds_read_b32 v4, v81 offset:812
	s_waitcnt lgkmcnt(0)
	v_cvt_pk_bf16_f32 v3, v3, v4
	ds_read_b32 v4, v81 offset:1072
	ds_read_b32 v5, v81 offset:1332
	s_waitcnt lgkmcnt(0)
	v_cvt_pk_bf16_f32 v4, v4, v5
	ds_read_b32 v5, v81 offset:1592
	ds_read_b32 v6, v81 offset:1852
	s_waitcnt lgkmcnt(0)
	v_cvt_pk_bf16_f32 v5, v5, v6
	v_or_b32_e32 v6, s48, v82
	v_lshlrev_b32_e32 v168, 12, v6
	v_lshl_add_u64 v[6:7], v[0:1], 0, v[168:169]
	global_store_dwordx4 v[6:7], v[2:5], off
	ds_read_b32 v2, v81 offset:64
	ds_read_b32 v3, v81 offset:324
	s_waitcnt lgkmcnt(0)
	v_cvt_pk_bf16_f32 v2, v2, v3
	ds_read_b32 v3, v81 offset:584
	ds_read_b32 v4, v81 offset:844
	s_waitcnt lgkmcnt(0)
	v_cvt_pk_bf16_f32 v3, v3, v4
	ds_read_b32 v4, v81 offset:1104
	ds_read_b32 v5, v81 offset:1364
	s_waitcnt lgkmcnt(0)
	v_cvt_pk_bf16_f32 v4, v4, v5
	ds_read_b32 v5, v81 offset:1624
	ds_read_b32 v6, v81 offset:1884
	s_waitcnt lgkmcnt(0)
	v_cvt_pk_bf16_f32 v5, v5, v6
	v_or_b32_e32 v6, s48, v83
	v_lshlrev_b32_e32 v168, 12, v6
	v_lshl_add_u64 v[6:7], v[0:1], 0, v[168:169]
	global_store_dwordx4 v[6:7], v[2:5], off
	ds_read_b32 v2, v81 offset:96
	ds_read_b32 v3, v81 offset:356
	s_waitcnt lgkmcnt(0)
	v_cvt_pk_bf16_f32 v2, v2, v3
	ds_read_b32 v3, v81 offset:616
	ds_read_b32 v4, v81 offset:876
	s_waitcnt lgkmcnt(0)
	v_cvt_pk_bf16_f32 v3, v3, v4
	ds_read_b32 v4, v81 offset:1136
	ds_read_b32 v5, v81 offset:1396
	s_waitcnt lgkmcnt(0)
	v_cvt_pk_bf16_f32 v4, v4, v5
	ds_read_b32 v5, v81 offset:1656
	ds_read_b32 v6, v81 offset:1916
	s_waitcnt lgkmcnt(0)
	v_cvt_pk_bf16_f32 v5, v5, v6
	v_or_b32_e32 v6, s48, v84
	v_lshlrev_b32_e32 v168, 12, v6
	v_lshl_add_u64 v[6:7], v[0:1], 0, v[168:169]
	global_store_dwordx4 v[6:7], v[2:5], off
	ds_read_b32 v2, v81 offset:128
	ds_read_b32 v3, v81 offset:388
	s_waitcnt lgkmcnt(0)
	v_cvt_pk_bf16_f32 v2, v2, v3
	ds_read_b32 v3, v81 offset:648
	ds_read_b32 v4, v81 offset:908
	s_waitcnt lgkmcnt(0)
	v_cvt_pk_bf16_f32 v3, v3, v4
	ds_read_b32 v4, v81 offset:1168
	ds_read_b32 v5, v81 offset:1428
	s_waitcnt lgkmcnt(0)
	v_cvt_pk_bf16_f32 v4, v4, v5
	ds_read_b32 v5, v81 offset:1688
	ds_read_b32 v6, v81 offset:1948
	s_waitcnt lgkmcnt(0)
	v_cvt_pk_bf16_f32 v5, v5, v6
	v_or_b32_e32 v6, s48, v85
	v_lshlrev_b32_e32 v168, 12, v6
	v_lshl_add_u64 v[6:7], v[0:1], 0, v[168:169]
	global_store_dwordx4 v[6:7], v[2:5], off
	ds_read_b32 v2, v81 offset:160
	ds_read_b32 v3, v81 offset:420
	s_waitcnt lgkmcnt(0)
	v_cvt_pk_bf16_f32 v2, v2, v3
	ds_read_b32 v3, v81 offset:680
	ds_read_b32 v4, v81 offset:940
	s_waitcnt lgkmcnt(0)
	v_cvt_pk_bf16_f32 v3, v3, v4
	ds_read_b32 v4, v81 offset:1200
	ds_read_b32 v5, v81 offset:1460
	s_waitcnt lgkmcnt(0)
	v_cvt_pk_bf16_f32 v4, v4, v5
	ds_read_b32 v5, v81 offset:1720
	ds_read_b32 v6, v81 offset:1980
	s_waitcnt lgkmcnt(0)
	v_cvt_pk_bf16_f32 v5, v5, v6
	v_or_b32_e32 v6, s48, v86
	v_lshlrev_b32_e32 v168, 12, v6
	v_lshl_add_u64 v[6:7], v[0:1], 0, v[168:169]
	global_store_dwordx4 v[6:7], v[2:5], off
	ds_read_b32 v2, v81 offset:192
	ds_read_b32 v3, v81 offset:452
	s_waitcnt lgkmcnt(0)
	v_cvt_pk_bf16_f32 v2, v2, v3
	ds_read_b32 v3, v81 offset:712
	ds_read_b32 v4, v81 offset:972
	s_waitcnt lgkmcnt(0)
	v_cvt_pk_bf16_f32 v3, v3, v4
	ds_read_b32 v4, v81 offset:1232
	ds_read_b32 v5, v81 offset:1492
	s_waitcnt lgkmcnt(0)
	v_cvt_pk_bf16_f32 v4, v4, v5
	ds_read_b32 v5, v81 offset:1752
	ds_read_b32 v6, v81 offset:2012
	s_waitcnt lgkmcnt(0)
	v_cvt_pk_bf16_f32 v5, v5, v6
	v_or_b32_e32 v6, s48, v87
	v_lshlrev_b32_e32 v168, 12, v6
	v_lshl_add_u64 v[6:7], v[0:1], 0, v[168:169]
	global_store_dwordx4 v[6:7], v[2:5], off
	ds_read_b32 v2, v81 offset:224
	ds_read_b32 v3, v81 offset:484
	s_waitcnt lgkmcnt(0)
	v_cvt_pk_bf16_f32 v2, v2, v3
	ds_read_b32 v3, v81 offset:744
	ds_read_b32 v4, v81 offset:1004
	s_waitcnt lgkmcnt(0)
	v_cvt_pk_bf16_f32 v3, v3, v4
	ds_read_b32 v4, v81 offset:1264
	ds_read_b32 v5, v81 offset:1524
	s_waitcnt lgkmcnt(0)
	v_cvt_pk_bf16_f32 v4, v4, v5
	ds_read_b32 v5, v81 offset:1784
	ds_read_b32 v6, v81 offset:2044
	s_lshl_b32 s1, s46, 13
	s_and_b32 s1, s1, 0x3ff80000
	s_add_u32 s1, s6, s1
	s_addc_u32 s5, s7, 0
	s_and_b32 s4, s44, 31
	s_waitcnt lgkmcnt(0)
	v_cvt_pk_bf16_f32 v5, v5, v6
	v_or_b32_e32 v6, s48, v88
	s_lshl_b32 s4, s4, 8
	v_readlane_b32 s48, v253, 18
	v_lshlrev_b32_e32 v168, 12, v6
	s_or_b32 s4, s1, s4
	s_lshl_b32 s1, s47, 2
	v_readlane_b32 s60, v253, 30
	v_lshl_add_u64 v[0:1], v[0:1], 0, v[168:169]
	v_readlane_b32 s61, v253, 31
	s_add_u32 s1, s60, s1
	global_store_dwordx4 v[0:1], v[2:5], off
	v_lshl_add_u64 v[0:1], v[72:73], 0, s[4:5]
	s_addc_u32 s8, s61, 0
	s_lshl_b32 s4, s46, 2
	s_and_b32 s4, s4, 0x7ff00
	s_add_u32 s9, s60, s4
	v_mov_b32_e32 v2, 0
	s_addc_u32 s14, s61, 0
	s_mov_b64 s[4:5], 0
	v_mov_b32_e32 v6, v89
	v_mov_b32_e32 v3, v2
	v_readlane_b32 s49, v253, 19
	v_readlane_b32 s50, v253, 20
	v_readlane_b32 s51, v253, 21
	v_readlane_b32 s52, v253, 22
	v_readlane_b32 s53, v253, 23
	v_readlane_b32 s54, v253, 24
	v_readlane_b32 s55, v253, 25
	v_readlane_b32 s56, v253, 26
	v_readlane_b32 s57, v253, 27
	v_readlane_b32 s58, v253, 28
	v_readlane_b32 s59, v253, 29
	v_readlane_b32 s62, v253, 32
	v_readlane_b32 s63, v253, 33
; #define LDS_WAIT() asm volatile("s_waitcnt lgkmcnt(0)" ::: "memory")
; __device__ __forceinline__ unsigned f2bf(float f) { return pk2(f, 0.f) & 0xffffu; }
; __device__ __forceinline__ void p0_transpose_item(const float* W, int K, int N, bf16* WT, float* scr, int item, int lane, const float* scale, const float* cb, float* c1, float* c2) {
;     ...
;     if (c1) { float a1 = 0.f, a2 = 0.f;
;         for (int kk = 0; kk < 64; ++kk) { a1 += __uint_as_float(f2bf(scr[kk * 65 + lane]) << 16); a2 += cb[k0 + kk] * W[(size_t)(k0 + kk) * N + n0 + lane]; }
;         atomicAdd(c1 + n0 + lane, a1); atomicAdd(c2 + n0 + lane, a2); }
;     LDS_WAIT(); asm volatile("" ::: "memory");
.LBB0_1441:
	ds_read2_b32 v[8:9], v6 offset1:65
	s_waitcnt lgkmcnt(0)
	v_cvt_pk_bf16_f32 v4, v8, v169
	s_add_u32 s6, s9, s2
	v_lshlrev_b32_e32 v11, 16, v4
	s_addc_u32 s7, s14, s3
	v_lshl_add_u64 v[4:5], v[0:1], 0, s[4:5]
	global_load_dword v7, v169, s[6:7]
	global_load_dword v8, v[4:5], off
	s_add_u32 s6, s1, s2
	v_add_co_u32_e32 v14, vcc, s69, v4
	s_addc_u32 s7, s8, s3
	s_nop 0
	v_addc_co_u32_e32 v15, vcc, 0, v5, vcc
	v_add_co_u32_e32 v16, vcc, s89, v4
	s_add_u32 s4, s4, 0x10000
	s_nop 0
	v_addc_co_u32_e32 v17, vcc, 0, v5, vcc
	s_addc_u32 s5, s5, 0
	s_add_u32 s1, s1, 32
	s_addc_u32 s8, s8, 0
	s_add_u32 s9, s9, 32
	s_addc_u32 s14, s14, 0
	s_cmp_lg_u32 s4, 0x80000
	s_waitcnt vmcnt(0)
	v_mul_f32_e32 v10, v7, v8
	v_cvt_pk_bf16_f32 v7, v9, v169
	v_pk_add_f32 v[2:3], v[2:3], v[10:11]
	v_lshlrev_b32_e32 v13, 16, v7
	global_load_dwordx4 v[8:11], v169, s[6:7] offset:4
	global_load_dword v7, v[14:15], off
	s_waitcnt vmcnt(0)
	v_mul_f32_e32 v12, v8, v7
	v_pk_add_f32 v[2:3], v[2:3], v[12:13]
	ds_read2_b32 v[12:13], v6 offset0:130 offset1:195
	s_waitcnt lgkmcnt(0)
	v_cvt_pk_bf16_f32 v7, v12, v169
	v_add_co_u32_e32 v12, vcc, s84, v4
	v_lshlrev_b32_e32 v15, 16, v7
	global_load_dword v7, v[16:17], off
	s_waitcnt vmcnt(0)
	v_mul_f32_e32 v14, v9, v7
	v_cvt_pk_bf16_f32 v7, v13, v169
	v_addc_co_u32_e32 v13, vcc, 0, v5, vcc
	v_lshlrev_b32_e32 v9, 16, v7
	global_load_dword v7, v[12:13], off
	v_pk_add_f32 v[2:3], v[2:3], v[14:15]
	v_add_co_u32_e32 v14, vcc, s90, v4
	s_waitcnt vmcnt(0)
	v_mul_f32_e32 v8, v10, v7
	v_add_u32_e32 v7, 0x400, v6
	v_pk_add_f32 v[2:3], v[2:3], v[8:9]
	ds_read2_b32 v[8:9], v7 offset0:4 offset1:69
	s_waitcnt lgkmcnt(0)
	v_cvt_pk_bf16_f32 v8, v8, v169
	v_addc_co_u32_e32 v15, vcc, 0, v5, vcc
	v_lshlrev_b32_e32 v13, 16, v8
	global_load_dword v8, v[14:15], off
	v_add_co_u32_e32 v14, vcc, s70, v4
	v_add_u32_e32 v6, 0x820, v6
	s_nop 0
	v_addc_co_u32_e32 v15, vcc, 0, v5, vcc
	v_add_co_u32_e32 v16, vcc, s91, v4
	s_waitcnt vmcnt(0)
	v_mul_f32_e32 v12, v11, v8
	v_cvt_pk_bf16_f32 v8, v9, v169
	v_pk_add_f32 v[2:3], v[2:3], v[12:13]
	v_lshlrev_b32_e32 v13, 16, v8
	global_load_dwordx3 v[8:10], v169, s[6:7] offset:20
	global_load_dword v11, v[14:15], off
	v_addc_co_u32_e32 v17, vcc, 0, v5, vcc
	v_add_co_u32_e32 v4, vcc, s71, v4
	s_waitcnt vmcnt(0)
	v_mul_f32_e32 v12, v8, v11
	v_pk_add_f32 v[2:3], v[2:3], v[12:13]
	ds_read2_b32 v[12:13], v7 offset0:134 offset1:199
	s_waitcnt lgkmcnt(0)
	v_cvt_pk_bf16_f32 v7, v12, v169
	v_addc_co_u32_e32 v5, vcc, 0, v5, vcc
	v_lshlrev_b32_e32 v15, 16, v7
	global_load_dword v7, v[16:17], off
	s_waitcnt vmcnt(0)
	v_mul_f32_e32 v14, v9, v7
	global_load_dword v4, v[4:5], off
	v_pk_add_f32 v[2:3], v[2:3], v[14:15]
	v_cvt_pk_bf16_f32 v7, v13, v169
	s_waitcnt vmcnt(0)
	v_mul_f32_e32 v8, v10, v4
	v_lshlrev_b32_e32 v9, 16, v7
	v_pk_add_f32 v[2:3], v[2:3], v[8:9]
	s_cbranch_scc1 .LBB0_1441
	s_add_u32 s1, s40, s2
	s_addc_u32 s4, s41, s3
	s_add_u32 s5, s42, s2
	s_addc_u32 s6, s43, s3
	s_add_u32 s2, s1, s45
	s_addc_u32 s3, s4, 0
	v_mov_b32_e32 v75, v169
	v_lshl_add_u64 v[0:1], s[2:3], 0, v[74:75]
	s_add_u32 s2, s5, s45
	s_addc_u32 s3, s6, 0
	global_atomic_add_f32 v[0:1], v3, off
	v_lshl_add_u64 v[0:1], s[2:3], 0, v[74:75]
	global_atomic_add_f32 v[0:1], v2, off
	s_waitcnt lgkmcnt(0)

; #define LDS_WAIT() asm volatile("s_waitcnt lgkmcnt(0)" ::: "memory")
; __device__ __forceinline__ void p0_transpose_item(const float* W, int K, int N, bf16* WT, float* scr, int item, int lane, const float* scale, const float* cb, float* c1, float* c2) {
;     const int nblk = N / 64, kb = item / nblk, nb = item % nblk, k0 = 64 * kb, n0 = 64 * nb;
;     const int lr = lane >> 4, lc = (lane & 15) * 4;
;     f32x4 v[16];
; #pragma unroll
;     for (int i = 0; i < 16; ++i) v[i] = *(const f32x4*)(W + (size_t)(k0 + 4 * i + lr) * N + n0 + lc);
; #pragma unroll
;     for (int i = 0; i < 16; ++i) { const int kk = 4 * i + lr; f32x4 w = v[i]; if (scale) w = w * scale[k0 + kk]; float* d = scr + kk * 65 + lc; d[0] = w[0]; d[1] = w[1]; d[2] = w[2]; d[3] = w[3]; }
;     LDS_WAIT(); asm volatile("" ::: "memory");
.LBB0_1444:
	s_andn2_b64 vcc, exec, s[2:3]
	s_cbranch_vccnz .LBB0_1446
	s_ashr_i32 s1, s0, 31
	v_readlane_b32 s48, v253, 18
	s_lshl_b64 s[2:3], s[0:1], 24
	v_readlane_b32 s56, v253, 26
	v_readlane_b32 s57, v253, 27
	s_add_u32 s4, s56, s2
	s_addc_u32 s5, s57, s3
	s_lshl_b64 s[2:3], s[0:1], 23
	s_add_u32 s6, s27, s2
	s_addc_u32 s7, s28, s3
	s_lshl_b32 s1, s44, 1
	s_add_i32 s1, s1, 0x1e200
	s_and_b32 s8, s1, 0x1ffc0
	s_lshl_b32 s1, s44, 6
	s_and_b32 s1, s1, 0x7c0
	s_lshl_b32 s2, s1, 2
	s_add_u32 s2, s4, s2
	v_or_b32_e32 v2, s8, v69
	s_addc_u32 s3, s5, 0
	v_lshlrev_b32_e32 v168, 2, v68
	v_lshl_add_u64 v[0:1], s[2:3], 0, v[168:169]
	v_lshlrev_b32_e32 v168, 13, v2
	v_lshl_add_u64 v[60:61], v[0:1], 0, v[168:169]
	v_add_co_u32_e32 v4, vcc, s90, v60
	s_mov_b32 s2, 0x20000
	s_nop 0
	v_addc_co_u32_e32 v5, vcc, 0, v61, vcc
	v_add_co_u32_e32 v8, vcc, s88, v60
	global_load_dwordx4 v[0:3], v[60:61], off
	s_nop 0
	global_load_dwordx4 v[4:7], v[4:5], off
	v_addc_co_u32_e32 v9, vcc, 0, v61, vcc
	v_add_co_u32_e32 v12, vcc, s85, v60
	v_lshlrev_b32_e32 v168, 1, v70
	s_nop 0
	v_addc_co_u32_e32 v13, vcc, 0, v61, vcc
	global_load_dwordx4 v[8:11], v[8:9], off
	s_nop 0
	global_load_dwordx4 v[12:15], v[12:13], off
	v_add_co_u32_e32 v16, vcc, s2, v60
	s_mov_b32 s2, 0x28000
	s_nop 0
	v_addc_co_u32_e32 v17, vcc, 0, v61, vcc
	v_add_co_u32_e32 v20, vcc, s2, v60
	s_mov_b32 s2, 0x30000
	s_nop 0
	v_addc_co_u32_e32 v21, vcc, 0, v61, vcc
	global_load_dwordx4 v[16:19], v[16:17], off
	s_nop 0
	global_load_dwordx4 v[20:23], v[20:21], off
	v_add_co_u32_e32 v24, vcc, s2, v60
	s_mov_b32 s2, 0x38000
	s_nop 0
	v_addc_co_u32_e32 v25, vcc, 0, v61, vcc
	v_add_co_u32_e32 v28, vcc, s2, v60
	s_mov_b32 s2, 0x40000
	s_nop 0
	v_addc_co_u32_e32 v29, vcc, 0, v61, vcc
	global_load_dwordx4 v[24:27], v[24:25], off
	s_nop 0
	global_load_dwordx4 v[28:31], v[28:29], off
	v_add_co_u32_e32 v32, vcc, s2, v60
	s_mov_b32 s2, 0x48000
	s_nop 0
	v_addc_co_u32_e32 v33, vcc, 0, v61, vcc
	v_add_co_u32_e32 v36, vcc, s2, v60
	s_mov_b32 s2, 0x50000
	s_nop 0
	v_addc_co_u32_e32 v37, vcc, 0, v61, vcc
	global_load_dwordx4 v[32:35], v[32:33], off
	s_nop 0
	global_load_dwordx4 v[36:39], v[36:37], off
	v_add_co_u32_e32 v40, vcc, s2, v60
	s_mov_b32 s2, 0x58000
	s_nop 0
	v_addc_co_u32_e32 v41, vcc, 0, v61, vcc
	v_add_co_u32_e32 v44, vcc, s2, v60
	s_mov_b32 s2, 0x60000
	s_nop 0
	v_addc_co_u32_e32 v45, vcc, 0, v61, vcc
	global_load_dwordx4 v[40:43], v[40:41], off
	s_nop 0
	global_load_dwordx4 v[44:47], v[44:45], off
	v_add_co_u32_e32 v48, vcc, s2, v60
	s_mov_b32 s2, 0x68000
	s_nop 0
	v_addc_co_u32_e32 v49, vcc, 0, v61, vcc
	global_load_dwordx4 v[48:51], v[48:49], off
	v_add_co_u32_e32 v52, vcc, s2, v60
	s_mov_b32 s2, 0x70000
	s_nop 0
	v_addc_co_u32_e32 v53, vcc, 0, v61, vcc
	global_load_dwordx4 v[52:55], v[52:53], off
	v_add_co_u32_e32 v56, vcc, s2, v60
	s_mov_b32 s2, 0x78000
	s_nop 0
	v_addc_co_u32_e32 v57, vcc, 0, v61, vcc
	global_load_dwordx4 v[56:59], v[56:57], off
	v_add_co_u32_e32 v60, vcc, s2, v60
	s_lshl_b32 s2, s8, 1
	s_nop 0
	v_addc_co_u32_e32 v61, vcc, 0, v61, vcc
	global_load_dwordx4 v[60:63], v[60:61], off
	s_waitcnt vmcnt(0)
	ds_write2_b32 v71, v0, v1 offset1:1
	ds_write2_b32 v71, v2, v3 offset0:2 offset1:3
	v_add_u32_e32 v0, 0x410, v71
	ds_write2_b32 v0, v4, v5 offset1:1
	v_add_u32_e32 v0, 0x418, v71
	ds_write2_b32 v0, v6, v7 offset1:1
	v_add_u32_e32 v0, 0x820, v71
	s_add_u32 s2, s6, s2
	s_addc_u32 s3, s7, 0
	ds_write2_b32 v0, v8, v9 offset1:1
	v_add_u32_e32 v0, 0x828, v71
	ds_write2_b32 v0, v10, v11 offset1:1
	v_add_u32_e32 v0, 0xc30, v71
	ds_write2_b32 v0, v12, v13 offset1:1
	v_add_u32_e32 v0, 0xc38, v71
	ds_write2_b32 v0, v14, v15 offset1:1
	v_add_u32_e32 v0, 0x1040, v71
	v_lshl_add_u64 v[4:5], s[2:3], 0, v[168:169]
	v_readlane_b32 s49, v253, 19
	v_readlane_b32 s50, v253, 20
	ds_write2_b32 v0, v16, v17 offset1:1
	v_add_u32_e32 v0, 0x1048, v71
	ds_write2_b32 v0, v18, v19 offset1:1
	v_add_u32_e32 v0, 0x1450, v71
	ds_write2_b32 v0, v20, v21 offset1:1
	v_add_u32_e32 v0, 0x1458, v71
	ds_write2_b32 v0, v22, v23 offset1:1
	v_add_u32_e32 v0, 0x1860, v71
	v_readlane_b32 s51, v253, 21
	v_readlane_b32 s52, v253, 22
	v_readlane_b32 s53, v253, 23
	ds_write2_b32 v0, v24, v25 offset1:1
	v_add_u32_e32 v0, 0x1868, v71
	ds_write2_b32 v0, v26, v27 offset1:1
	v_add_u32_e32 v0, 0x1c70, v71
	ds_write2_b32 v0, v28, v29 offset1:1
	v_add_u32_e32 v0, 0x1c78, v71
	ds_write2_b32 v0, v30, v31 offset1:1
	v_add_u32_e32 v0, 0x2080, v71
	v_readlane_b32 s54, v253, 24
	v_readlane_b32 s55, v253, 25
	v_readlane_b32 s58, v253, 28
	ds_write2_b32 v0, v32, v33 offset1:1
	v_add_u32_e32 v0, 0x2088, v71
	ds_write2_b32 v0, v34, v35 offset1:1
	v_add_u32_e32 v0, 0x2490, v71
	ds_write2_b32 v0, v36, v37 offset1:1
	v_add_u32_e32 v0, 0x2498, v71
	ds_write2_b32 v0, v38, v39 offset1:1
	v_add_u32_e32 v0, 0x28a0, v71
	v_readlane_b32 s59, v253, 29
	v_readlane_b32 s60, v253, 30
	v_readlane_b32 s61, v253, 31
	ds_write2_b32 v0, v40, v41 offset1:1
	v_add_u32_e32 v0, 0x28a8, v71
	ds_write2_b32 v0, v42, v43 offset1:1
	v_add_u32_e32 v0, 0x2cb0, v71
	ds_write2_b32 v0, v44, v45 offset1:1
	v_add_u32_e32 v0, 0x2cb8, v71
	ds_write2_b32 v0, v46, v47 offset1:1
	v_add_u32_e32 v0, 0x30c0, v71
	ds_write2_b32 v0, v48, v49 offset1:1
	v_add_u32_e32 v0, 0x30c8, v71
	ds_write2_b32 v0, v50, v51 offset1:1
	v_add_u32_e32 v0, 0x34d0, v71
	v_readlane_b32 s62, v253, 32
	ds_write2_b32 v0, v52, v53 offset1:1
	v_add_u32_e32 v0, 0x34d8, v71
	ds_write2_b32 v0, v54, v55 offset1:1
	v_add_u32_e32 v0, 0x38e0, v71
	v_readlane_b32 s63, v253, 33
	ds_write2_b32 v0, v56, v57 offset1:1
	v_add_u32_e32 v0, 0x38e8, v71
	ds_write2_b32 v0, v58, v59 offset1:1
	v_add_u32_e32 v0, 0x3cf0, v71
	ds_write2_b32 v0, v60, v61 offset1:1
	v_add_u32_e32 v0, 0x3cf8, v71
	ds_write2_b32 v0, v62, v63 offset1:1
	s_waitcnt lgkmcnt(0)
; __device__ __forceinline__ unsigned pk2(float lo, float hi) { unsigned r; asm("v_cvt_pk_bf16_f32 %0, %1, %2" : "=v"(r) : "v"(lo), "v"(hi)); return r; }
; __device__ __forceinline__ void p0_transpose_item(const float* W, int K, int N, bf16* WT, float* scr, int item, int lane, const float* scale, const float* cb, float* c1, float* c2) {
;     ...
;     const int c = lane & 7;
; #pragma unroll
;     for (int j = 0; j < 8; ++j) { const int n = (lane >> 3) + 8 * j; const float* sp = scr + (8 * c) * 65 + n;
;         v4u o; o.x = pk2(sp[0 * 65], sp[1 * 65]); o.y = pk2(sp[2 * 65], sp[3 * 65]); o.z = pk2(sp[4 * 65], sp[5 * 65]); o.w = pk2(sp[6 * 65], sp[7 * 65]);
;         *(v4u*)(WT + (size_t)(n0 + n) * K + k0 + 8 * c) = o; }
	ds_read_b32 v0, v81
	ds_read_b32 v1, v81 offset:260
	ds_read_b32 v2, v81 offset:520
	ds_read_b32 v3, v81 offset:780
	ds_read_b32 v6, v81 offset:1040
	ds_read_b32 v7, v81 offset:1300
	ds_read_b32 v8, v81 offset:1560
	ds_read_b32 v9, v81 offset:1820
	s_waitcnt lgkmcnt(0)
	v_cvt_pk_bf16_f32 v0, v0, v1
	v_cvt_pk_bf16_f32 v1, v2, v3
	v_cvt_pk_bf16_f32 v2, v6, v7
	v_or_b32_e32 v6, s1, v80
	v_lshlrev_b32_e32 v168, 12, v6
	v_lshl_add_u64 v[6:7], v[4:5], 0, v[168:169]
	v_cvt_pk_bf16_f32 v3, v8, v9
	global_store_dwordx4 v[6:7], v[0:3], off
	ds_read_b32 v0, v81 offset:32
	ds_read_b32 v1, v81 offset:292
	ds_read_b32 v2, v81 offset:552
	ds_read_b32 v3, v81 offset:812
	ds_read_b32 v6, v81 offset:1072
	ds_read_b32 v7, v81 offset:1332
	ds_read_b32 v8, v81 offset:1592
	ds_read_b32 v9, v81 offset:1852
	s_waitcnt lgkmcnt(0)
	v_cvt_pk_bf16_f32 v0, v0, v1
	v_cvt_pk_bf16_f32 v1, v2, v3
	v_cvt_pk_bf16_f32 v2, v6, v7
	v_or_b32_e32 v6, s1, v82
	v_lshlrev_b32_e32 v168, 12, v6
	v_lshl_add_u64 v[6:7], v[4:5], 0, v[168:169]
	v_cvt_pk_bf16_f32 v3, v8, v9
	global_store_dwordx4 v[6:7], v[0:3], off
	ds_read_b32 v0, v81 offset:64
	ds_read_b32 v1, v81 offset:324
	ds_read_b32 v2, v81 offset:584
	ds_read_b32 v3, v81 offset:844
	ds_read_b32 v6, v81 offset:1104
	ds_read_b32 v7, v81 offset:1364
	ds_read_b32 v8, v81 offset:1624
	ds_read_b32 v9, v81 offset:1884
	s_waitcnt lgkmcnt(0)
	v_cvt_pk_bf16_f32 v0, v0, v1
	v_cvt_pk_bf16_f32 v1, v2, v3
	v_cvt_pk_bf16_f32 v2, v6, v7
	v_or_b32_e32 v6, s1, v83
	v_lshlrev_b32_e32 v168, 12, v6
	v_lshl_add_u64 v[6:7], v[4:5], 0, v[168:169]
	v_cvt_pk_bf16_f32 v3, v8, v9
	global_store_dwordx4 v[6:7], v[0:3], off
	ds_read_b32 v0, v81 offset:96
	ds_read_b32 v1, v81 offset:356
	ds_read_b32 v2, v81 offset:616
	ds_read_b32 v3, v81 offset:876
	ds_read_b32 v6, v81 offset:1136
	ds_read_b32 v7, v81 offset:1396
	ds_read_b32 v8, v81 offset:1656
	ds_read_b32 v9, v81 offset:1916
	s_waitcnt lgkmcnt(0)
	v_cvt_pk_bf16_f32 v0, v0, v1
	v_cvt_pk_bf16_f32 v1, v2, v3
	v_cvt_pk_bf16_f32 v2, v6, v7
	v_or_b32_e32 v6, s1, v84
	v_lshlrev_b32_e32 v168, 12, v6
	v_lshl_add_u64 v[6:7], v[4:5], 0, v[168:169]
	v_cvt_pk_bf16_f32 v3, v8, v9
	global_store_dwordx4 v[6:7], v[0:3], off
	ds_read_b32 v0, v81 offset:128
	ds_read_b32 v1, v81 offset:388
	ds_read_b32 v2, v81 offset:648
	ds_read_b32 v3, v81 offset:908
	ds_read_b32 v6, v81 offset:1168
	ds_read_b32 v7, v81 offset:1428
	ds_read_b32 v8, v81 offset:1688
	ds_read_b32 v9, v81 offset:1948
	s_waitcnt lgkmcnt(0)
	v_cvt_pk_bf16_f32 v0, v0, v1
	v_cvt_pk_bf16_f32 v1, v2, v3
	v_cvt_pk_bf16_f32 v2, v6, v7
	v_or_b32_e32 v6, s1, v85
	v_lshlrev_b32_e32 v168, 12, v6
	v_lshl_add_u64 v[6:7], v[4:5], 0, v[168:169]
	v_cvt_pk_bf16_f32 v3, v8, v9
	global_store_dwordx4 v[6:7], v[0:3], off
	ds_read_b32 v0, v81 offset:160
	ds_read_b32 v1, v81 offset:420
	ds_read_b32 v2, v81 offset:680
	ds_read_b32 v3, v81 offset:940
	ds_read_b32 v6, v81 offset:1200
	ds_read_b32 v7, v81 offset:1460
	ds_read_b32 v8, v81 offset:1720
	ds_read_b32 v9, v81 offset:1980
	s_waitcnt lgkmcnt(0)
	v_cvt_pk_bf16_f32 v0, v0, v1
	v_cvt_pk_bf16_f32 v1, v2, v3
	v_cvt_pk_bf16_f32 v2, v6, v7
	v_or_b32_e32 v6, s1, v86
	v_lshlrev_b32_e32 v168, 12, v6
	v_lshl_add_u64 v[6:7], v[4:5], 0, v[168:169]
	v_cvt_pk_bf16_f32 v3, v8, v9
	global_store_dwordx4 v[6:7], v[0:3], off
	ds_read_b32 v0, v81 offset:192
	ds_read_b32 v1, v81 offset:452
	ds_read_b32 v2, v81 offset:712
	ds_read_b32 v3, v81 offset:972
	ds_read_b32 v6, v81 offset:1232
	ds_read_b32 v7, v81 offset:1492
	ds_read_b32 v8, v81 offset:1752
	ds_read_b32 v9, v81 offset:2012
	s_waitcnt lgkmcnt(0)
	v_cvt_pk_bf16_f32 v0, v0, v1
	v_cvt_pk_bf16_f32 v1, v2, v3
	v_cvt_pk_bf16_f32 v2, v6, v7
	v_or_b32_e32 v6, s1, v87
	v_lshlrev_b32_e32 v168, 12, v6
	v_lshl_add_u64 v[6:7], v[4:5], 0, v[168:169]
	v_cvt_pk_bf16_f32 v3, v8, v9
	global_store_dwordx4 v[6:7], v[0:3], off
	ds_read_b32 v0, v81 offset:224
	ds_read_b32 v1, v81 offset:484
	ds_read_b32 v2, v81 offset:744
	ds_read_b32 v3, v81 offset:1004
	ds_read_b32 v6, v81 offset:1264
	ds_read_b32 v7, v81 offset:1524
	ds_read_b32 v8, v81 offset:1784
	ds_read_b32 v9, v81 offset:2044
	s_waitcnt lgkmcnt(0)
	v_cvt_pk_bf16_f32 v0, v0, v1
	v_cvt_pk_bf16_f32 v1, v2, v3
	v_cvt_pk_bf16_f32 v2, v6, v7
	v_or_b32_e32 v6, s1, v88
	v_lshlrev_b32_e32 v168, 12, v6
	v_lshl_add_u64 v[4:5], v[4:5], 0, v[168:169]
	v_cvt_pk_bf16_f32 v3, v8, v9
	global_store_dwordx4 v[4:5], v[0:3], off
	s_waitcnt lgkmcnt(0)

; #define LDS_WAIT() asm volatile("s_waitcnt lgkmcnt(0)" ::: "memory")
; __device__ __forceinline__ void p0_transpose_item(const float* W, int K, int N, bf16* WT, float* scr, int item, int lane, const float* scale, const float* cb, float* c1, float* c2) {
;     const int nblk = N / 64, kb = item / nblk, nb = item % nblk, k0 = 64 * kb, n0 = 64 * nb;
;     const int lr = lane >> 4, lc = (lane & 15) * 4;
;     f32x4 v[16];
; #pragma unroll
;     for (int i = 0; i < 16; ++i) v[i] = *(const f32x4*)(W + (size_t)(k0 + 4 * i + lr) * N + n0 + lc);
; #pragma unroll
;     for (int i = 0; i < 16; ++i) { const int kk = 4 * i + lr; f32x4 w = v[i]; if (scale) w = w * scale[k0 + kk]; float* d = scr + kk * 65 + lc; d[0] = w[0]; d[1] = w[1]; d[2] = w[2]; d[3] = w[3]; }
;     LDS_WAIT(); asm volatile("" ::: "memory");
.LBB0_1447:
	s_andn2_b64 vcc, exec, s[2:3]
	s_cbranch_vccnz .LBB0_1410
	v_readlane_b32 s48, v253, 2
	s_mul_i32 s2, s0, 0x3c00000
	v_readlane_b32 s52, v253, 6
	s_mul_hi_i32 s1, s0, 0x3c00000
	v_readlane_b32 s53, v253, 7
	s_add_u32 s3, s52, s2
	s_addc_u32 s6, s53, s1
	s_mul_hi_i32 s1, s0, 0x1e00000
	s_mul_i32 s0, s0, 0x1e00000
	s_add_u32 s7, s25, s0
	s_mul_i32 s0, s44, 0xffff8889
	s_addc_u32 s8, s26, s1
	s_lshr_b32 s0, s0, 16
	s_add_i32 s0, s0, s44
	s_sext_i32_i16 s1, s0
	s_ashr_i32 s1, s1, 6
	s_bfe_u32 s0, s0, 0x1000f
	s_add_i32 s0, s1, s0
	s_sext_i32_i16 s1, s0
	s_mulk_i32 s0, 0x78
	s_sub_i32 s0, s44, s0
	s_sext_i32_i16 s0, s0
	s_lshl_b32 s0, s0, 6
	s_lshl_b32 s2, s1, 6
	s_ashr_i32 s1, s0, 31
	s_lshl_b64 s[4:5], s[0:1], 2
	v_or_b32_e32 v2, s2, v69
	s_add_u32 s4, s3, s4
	s_addc_u32 s5, s6, s5
	v_lshlrev_b32_e32 v168, 2, v68
	v_mul_i32_i24_e32 v2, 0x1e00, v2
	v_lshl_add_u64 v[0:1], s[4:5], 0, v[168:169]
	v_ashrrev_i32_e32 v3, 31, v2
	v_lshl_add_u64 v[60:61], v[2:3], 2, v[0:1]
	s_mov_b32 s1, 0x1e000
	v_add_co_u32_e32 v4, vcc, s1, v60
	s_mov_b32 s1, 0x3c000
	s_nop 0
	v_addc_co_u32_e32 v5, vcc, 0, v61, vcc
	v_add_co_u32_e32 v8, vcc, s1, v60
	global_load_dwordx4 v[0:3], v[60:61], off
	s_nop 0
	global_load_dwordx4 v[4:7], v[4:5], off
	v_addc_co_u32_e32 v9, vcc, 0, v61, vcc
	s_mov_b32 s1, 0x5a000
	v_add_co_u32_e32 v12, vcc, s1, v60
	s_mov_b32 s1, 0x78000
	s_nop 0
	v_addc_co_u32_e32 v13, vcc, 0, v61, vcc
	global_load_dwordx4 v[8:11], v[8:9], off
	s_nop 0
	global_load_dwordx4 v[12:15], v[12:13], off
	v_add_co_u32_e32 v16, vcc, s1, v60
	s_mov_b32 s1, 0x96000
	s_nop 0
	v_addc_co_u32_e32 v17, vcc, 0, v61, vcc
	v_add_co_u32_e32 v20, vcc, s1, v60
	s_mov_b32 s1, 0xb4000
	s_nop 0
	v_addc_co_u32_e32 v21, vcc, 0, v61, vcc
	global_load_dwordx4 v[16:19], v[16:17], off
	s_nop 0
	global_load_dwordx4 v[20:23], v[20:21], off
	v_add_co_u32_e32 v24, vcc, s1, v60
	s_mov_b32 s1, 0xd2000
	s_nop 0
	v_addc_co_u32_e32 v25, vcc, 0, v61, vcc
	v_add_co_u32_e32 v28, vcc, s1, v60
	s_mov_b32 s1, 0xf0000
	s_nop 0
	v_addc_co_u32_e32 v29, vcc, 0, v61, vcc
	global_load_dwordx4 v[24:27], v[24:25], off
	s_nop 0
	global_load_dwordx4 v[28:31], v[28:29], off
	v_add_co_u32_e32 v32, vcc, s1, v60
	s_mov_b32 s1, 0x10e000
	s_nop 0
	v_addc_co_u32_e32 v33, vcc, 0, v61, vcc
	v_add_co_u32_e32 v36, vcc, s1, v60
	s_mov_b32 s1, 0x12c000
	s_nop 0
	v_addc_co_u32_e32 v37, vcc, 0, v61, vcc
	global_load_dwordx4 v[32:35], v[32:33], off
	s_nop 0
	global_load_dwordx4 v[36:39], v[36:37], off
	v_add_co_u32_e32 v40, vcc, s1, v60
	s_mov_b32 s1, 0x14a000
	s_nop 0
	v_addc_co_u32_e32 v41, vcc, 0, v61, vcc
	v_add_co_u32_e32 v44, vcc, s1, v60
	s_mov_b32 s1, 0x168000
	s_nop 0
	v_addc_co_u32_e32 v45, vcc, 0, v61, vcc
	global_load_dwordx4 v[40:43], v[40:41], off
	s_nop 0
	global_load_dwordx4 v[44:47], v[44:45], off
	v_add_co_u32_e32 v48, vcc, s1, v60
	s_mov_b32 s1, 0x186000
	s_nop 0
	v_addc_co_u32_e32 v49, vcc, 0, v61, vcc
	global_load_dwordx4 v[48:51], v[48:49], off
	v_add_co_u32_e32 v52, vcc, s1, v60
	s_mov_b32 s1, 0x1a4000
	s_nop 0
	v_addc_co_u32_e32 v53, vcc, 0, v61, vcc
	global_load_dwordx4 v[52:55], v[52:53], off
	v_add_co_u32_e32 v56, vcc, s1, v60
	s_mov_b32 s1, 0x1c2000
	s_nop 0
	v_addc_co_u32_e32 v57, vcc, 0, v61, vcc
	global_load_dwordx4 v[56:59], v[56:57], off
	v_add_co_u32_e32 v60, vcc, s1, v60
	s_ashr_i32 s3, s2, 31
	s_nop 0
	v_addc_co_u32_e32 v61, vcc, 0, v61, vcc
	global_load_dwordx4 v[60:63], v[60:61], off
	s_waitcnt vmcnt(0)
	ds_write2_b32 v71, v0, v1 offset1:1
	ds_write2_b32 v71, v2, v3 offset0:2 offset1:3
	v_add_u32_e32 v0, 0x410, v71
	ds_write2_b32 v0, v4, v5 offset1:1
	v_add_u32_e32 v0, 0x418, v71
	ds_write2_b32 v0, v6, v7 offset1:1
	v_add_u32_e32 v0, 0x820, v71
	s_lshl_b64 s[2:3], s[2:3], 1
	s_add_u32 s2, s7, s2
	s_addc_u32 s3, s8, s3
	ds_write2_b32 v0, v8, v9 offset1:1
	v_add_u32_e32 v0, 0x828, v71
	ds_write2_b32 v0, v10, v11 offset1:1
	v_add_u32_e32 v0, 0xc30, v71
	ds_write2_b32 v0, v12, v13 offset1:1
	v_add_u32_e32 v0, 0xc38, v71
	ds_write2_b32 v0, v14, v15 offset1:1
	v_add_u32_e32 v0, 0x1040, v71
	v_lshlrev_b32_e32 v168, 1, v70
	v_lshl_add_u64 v[4:5], s[2:3], 0, v[168:169]
	v_readlane_b32 s49, v253, 3
	ds_write2_b32 v0, v16, v17 offset1:1
	v_add_u32_e32 v0, 0x1048, v71
	ds_write2_b32 v0, v18, v19 offset1:1
	v_add_u32_e32 v0, 0x1450, v71
	ds_write2_b32 v0, v20, v21 offset1:1
	v_add_u32_e32 v0, 0x1458, v71
	ds_write2_b32 v0, v22, v23 offset1:1
	v_add_u32_e32 v0, 0x1860, v71
	v_readlane_b32 s50, v253, 4
	v_readlane_b32 s51, v253, 5
	v_readlane_b32 s54, v253, 8
	ds_write2_b32 v0, v24, v25 offset1:1
	v_add_u32_e32 v0, 0x1868, v71
	ds_write2_b32 v0, v26, v27 offset1:1
	v_add_u32_e32 v0, 0x1c70, v71
	ds_write2_b32 v0, v28, v29 offset1:1
	v_add_u32_e32 v0, 0x1c78, v71
	ds_write2_b32 v0, v30, v31 offset1:1
	v_add_u32_e32 v0, 0x2080, v71
	v_readlane_b32 s55, v253, 9
	v_readlane_b32 s56, v253, 10
	v_readlane_b32 s57, v253, 11
	ds_write2_b32 v0, v32, v33 offset1:1
	v_add_u32_e32 v0, 0x2088, v71
	ds_write2_b32 v0, v34, v35 offset1:1
	v_add_u32_e32 v0, 0x2490, v71
	ds_write2_b32 v0, v36, v37 offset1:1
	v_add_u32_e32 v0, 0x2498, v71
	ds_write2_b32 v0, v38, v39 offset1:1
	v_add_u32_e32 v0, 0x28a0, v71
	v_readlane_b32 s58, v253, 12
	v_readlane_b32 s59, v253, 13
	v_readlane_b32 s60, v253, 14
	ds_write2_b32 v0, v40, v41 offset1:1
	v_add_u32_e32 v0, 0x28a8, v71
	ds_write2_b32 v0, v42, v43 offset1:1
	v_add_u32_e32 v0, 0x2cb0, v71
	ds_write2_b32 v0, v44, v45 offset1:1
	v_add_u32_e32 v0, 0x2cb8, v71
	ds_write2_b32 v0, v46, v47 offset1:1
	v_add_u32_e32 v0, 0x30c0, v71
	ds_write2_b32 v0, v48, v49 offset1:1
	v_add_u32_e32 v0, 0x30c8, v71
	ds_write2_b32 v0, v50, v51 offset1:1
	v_add_u32_e32 v0, 0x34d0, v71
	v_readlane_b32 s61, v253, 15
	ds_write2_b32 v0, v52, v53 offset1:1
	v_add_u32_e32 v0, 0x34d8, v71
	ds_write2_b32 v0, v54, v55 offset1:1
	v_add_u32_e32 v0, 0x38e0, v71
	v_readlane_b32 s62, v253, 16
	v_readlane_b32 s63, v253, 17
	ds_write2_b32 v0, v56, v57 offset1:1
	v_add_u32_e32 v0, 0x38e8, v71
	ds_write2_b32 v0, v58, v59 offset1:1
	v_add_u32_e32 v0, 0x3cf0, v71
	ds_write2_b32 v0, v60, v61 offset1:1
	v_add_u32_e32 v0, 0x3cf8, v71
	ds_write2_b32 v0, v62, v63 offset1:1
	s_waitcnt lgkmcnt(0)
; __device__ __forceinline__ unsigned pk2(float lo, float hi) { unsigned r; asm("v_cvt_pk_bf16_f32 %0, %1, %2" : "=v"(r) : "v"(lo), "v"(hi)); return r; }
; __device__ __forceinline__ void p0_transpose_item(const float* W, int K, int N, bf16* WT, float* scr, int item, int lane, const float* scale, const float* cb, float* c1, float* c2) {
;     ...
;     const int c = lane & 7;
; #pragma unroll
;     for (int j = 0; j < 8; ++j) { const int n = (lane >> 3) + 8 * j; const float* sp = scr + (8 * c) * 65 + n;
;         v4u o; o.x = pk2(sp[0 * 65], sp[1 * 65]); o.y = pk2(sp[2 * 65], sp[3 * 65]); o.z = pk2(sp[4 * 65], sp[5 * 65]); o.w = pk2(sp[6 * 65], sp[7 * 65]);
;         *(v4u*)(WT + (size_t)(n0 + n) * K + k0 + 8 * c) = o; }
	ds_read_b32 v0, v81
	ds_read_b32 v1, v81 offset:260
	ds_read_b32 v2, v81 offset:520
	ds_read_b32 v3, v81 offset:780
	ds_read_b32 v6, v81 offset:1040
	ds_read_b32 v7, v81 offset:1300
	ds_read_b32 v8, v81 offset:1560
	ds_read_b32 v9, v81 offset:1820
	s_waitcnt lgkmcnt(0)
	v_cvt_pk_bf16_f32 v0, v0, v1
	v_cvt_pk_bf16_f32 v1, v2, v3
	v_cvt_pk_bf16_f32 v2, v6, v7
	v_or_b32_e32 v6, s0, v80
	v_ashrrev_i32_e32 v7, 31, v6
	v_lshlrev_b64 v[6:7], 12, v[6:7]
	v_lshl_add_u64 v[6:7], v[4:5], 0, v[6:7]
	v_cvt_pk_bf16_f32 v3, v8, v9
	global_store_dwordx4 v[6:7], v[0:3], off
	ds_read_b32 v0, v81 offset:32
	ds_read_b32 v1, v81 offset:292
	ds_read_b32 v2, v81 offset:552
	ds_read_b32 v3, v81 offset:812
	ds_read_b32 v6, v81 offset:1072
	ds_read_b32 v7, v81 offset:1332
	ds_read_b32 v8, v81 offset:1592
	ds_read_b32 v9, v81 offset:1852
	s_waitcnt lgkmcnt(0)
	v_cvt_pk_bf16_f32 v0, v0, v1
	v_cvt_pk_bf16_f32 v1, v2, v3
	v_cvt_pk_bf16_f32 v2, v6, v7
	v_or_b32_e32 v6, s0, v82
	v_ashrrev_i32_e32 v7, 31, v6
	v_lshlrev_b64 v[6:7], 12, v[6:7]
	v_lshl_add_u64 v[6:7], v[4:5], 0, v[6:7]
	v_cvt_pk_bf16_f32 v3, v8, v9
	global_store_dwordx4 v[6:7], v[0:3], off
	ds_read_b32 v0, v81 offset:64
	ds_read_b32 v1, v81 offset:324
	ds_read_b32 v2, v81 offset:584
	ds_read_b32 v3, v81 offset:844
	ds_read_b32 v6, v81 offset:1104
	ds_read_b32 v7, v81 offset:1364
	ds_read_b32 v8, v81 offset:1624
	ds_read_b32 v9, v81 offset:1884
	s_waitcnt lgkmcnt(0)
	v_cvt_pk_bf16_f32 v0, v0, v1
	v_cvt_pk_bf16_f32 v1, v2, v3
	v_cvt_pk_bf16_f32 v2, v6, v7
	v_or_b32_e32 v6, s0, v83
	v_ashrrev_i32_e32 v7, 31, v6
	v_lshlrev_b64 v[6:7], 12, v[6:7]
	v_lshl_add_u64 v[6:7], v[4:5], 0, v[6:7]
	v_cvt_pk_bf16_f32 v3, v8, v9
	global_store_dwordx4 v[6:7], v[0:3], off
	ds_read_b32 v0, v81 offset:96
	ds_read_b32 v1, v81 offset:356
	ds_read_b32 v2, v81 offset:616
	ds_read_b32 v3, v81 offset:876
	ds_read_b32 v6, v81 offset:1136
	ds_read_b32 v7, v81 offset:1396
	ds_read_b32 v8, v81 offset:1656
	ds_read_b32 v9, v81 offset:1916
	s_waitcnt lgkmcnt(0)
	v_cvt_pk_bf16_f32 v0, v0, v1
	v_cvt_pk_bf16_f32 v1, v2, v3
	v_cvt_pk_bf16_f32 v2, v6, v7
	v_or_b32_e32 v6, s0, v84
	v_ashrrev_i32_e32 v7, 31, v6
	v_lshlrev_b64 v[6:7], 12, v[6:7]
	v_lshl_add_u64 v[6:7], v[4:5], 0, v[6:7]
	v_cvt_pk_bf16_f32 v3, v8, v9
	global_store_dwordx4 v[6:7], v[0:3], off
	ds_read_b32 v0, v81 offset:128
	ds_read_b32 v1, v81 offset:388
	ds_read_b32 v2, v81 offset:648
	ds_read_b32 v3, v81 offset:908
	ds_read_b32 v6, v81 offset:1168
	ds_read_b32 v7, v81 offset:1428
	ds_read_b32 v8, v81 offset:1688
	ds_read_b32 v9, v81 offset:1948
	s_waitcnt lgkmcnt(0)
	v_cvt_pk_bf16_f32 v0, v0, v1
	v_cvt_pk_bf16_f32 v1, v2, v3
	v_cvt_pk_bf16_f32 v2, v6, v7
	v_or_b32_e32 v6, s0, v85
	v_ashrrev_i32_e32 v7, 31, v6
	v_lshlrev_b64 v[6:7], 12, v[6:7]
	v_lshl_add_u64 v[6:7], v[4:5], 0, v[6:7]
	v_cvt_pk_bf16_f32 v3, v8, v9
	global_store_dwordx4 v[6:7], v[0:3], off
	ds_read_b32 v0, v81 offset:160
	ds_read_b32 v1, v81 offset:420
	ds_read_b32 v2, v81 offset:680
	ds_read_b32 v3, v81 offset:940
	ds_read_b32 v6, v81 offset:1200
	ds_read_b32 v7, v81 offset:1460
	ds_read_b32 v8, v81 offset:1720
	ds_read_b32 v9, v81 offset:1980
	s_waitcnt lgkmcnt(0)
	v_cvt_pk_bf16_f32 v0, v0, v1
	v_cvt_pk_bf16_f32 v1, v2, v3
	v_cvt_pk_bf16_f32 v2, v6, v7
	v_or_b32_e32 v6, s0, v86
	v_ashrrev_i32_e32 v7, 31, v6
	v_lshlrev_b64 v[6:7], 12, v[6:7]
	v_lshl_add_u64 v[6:7], v[4:5], 0, v[6:7]
	v_cvt_pk_bf16_f32 v3, v8, v9
	global_store_dwordx4 v[6:7], v[0:3], off
	ds_read_b32 v0, v81 offset:192
	ds_read_b32 v1, v81 offset:452
	ds_read_b32 v2, v81 offset:712
	ds_read_b32 v3, v81 offset:972
	ds_read_b32 v6, v81 offset:1232
	ds_read_b32 v7, v81 offset:1492
	ds_read_b32 v8, v81 offset:1752
	ds_read_b32 v9, v81 offset:2012
	s_waitcnt lgkmcnt(0)
	v_cvt_pk_bf16_f32 v0, v0, v1
	v_cvt_pk_bf16_f32 v1, v2, v3
	v_cvt_pk_bf16_f32 v2, v6, v7
	v_or_b32_e32 v6, s0, v87
	v_ashrrev_i32_e32 v7, 31, v6
	v_lshlrev_b64 v[6:7], 12, v[6:7]
	v_lshl_add_u64 v[6:7], v[4:5], 0, v[6:7]
	v_cvt_pk_bf16_f32 v3, v8, v9
	global_store_dwordx4 v[6:7], v[0:3], off
	ds_read_b32 v0, v81 offset:224
	ds_read_b32 v1, v81 offset:484
	ds_read_b32 v2, v81 offset:744
	ds_read_b32 v3, v81 offset:1004
	ds_read_b32 v6, v81 offset:1264
	ds_read_b32 v7, v81 offset:1524
	ds_read_b32 v8, v81 offset:1784
	ds_read_b32 v9, v81 offset:2044
	s_waitcnt lgkmcnt(0)
	v_cvt_pk_bf16_f32 v0, v0, v1
	v_cvt_pk_bf16_f32 v1, v2, v3
	v_cvt_pk_bf16_f32 v2, v6, v7
	v_or_b32_e32 v6, s0, v88
	v_ashrrev_i32_e32 v7, 31, v6
	v_lshlrev_b64 v[6:7], 12, v[6:7]
	v_lshl_add_u64 v[4:5], v[4:5], 0, v[6:7]
	v_cvt_pk_bf16_f32 v3, v8, v9
	global_store_dwordx4 v[4:5], v[0:3], off
	s_waitcnt lgkmcnt(0)
	s_branch .LBB0_1410
